# static s_setprio 1 for waves 0-3 in every GEMM stream, all per-segment priority flips removed
# speedup vs baseline: 1.0079x; 1.0013x over previous
.LBB0_231:
	v_and_b32_e32 v1, 15, v2
	s_lshl_b64 s[40:41], s[8:9], 7
	s_lshl_b64 s[22:23], s[22:23], 7
	v_or_b32_e32 v3, s3, v1
	v_lshlrev_b32_e32 v5, 6, v3
	v_and_b32_e32 v6, 48, v2
	s_movk_i32 s2, 0x3c0
	s_add_u32 s8, s6, 0x80
	v_ashrrev_i32_e32 v4, 6, v2
	v_and_or_b32 v5, v5, s2, v6
	v_readlane_b32 s2, v254, 55
	s_addc_u32 s9, s7, 0
	v_lshl_add_u32 v7, v4, 10, s95
	v_add_lshl_u32 v4, v4, s2, 10
	s_sub_u32 s2, 0, s16
	s_subb_u32 s24, 0, s17
	s_add_u32 s2, s10, s2
	s_addc_u32 s25, s11, s24
	s_add_u32 s24, s2, 0x80
	s_addc_u32 s25, s25, 0
	s_add_i32 s63, s53, 0x18000
	s_add_i32 s64, s53, 0x1a000
	s_mov_b32 s98, 0
	s_cselect_b32 s99, 1, 0
	s_cmp_lt_u32 s76, 4
	s_cbranch_scc0 .Lsprio_0
	s_setprio 1
.Lsprio_0:
	s_cmp_lg_u32 s99, 0
	s_waitcnt vmcnt(2)
	s_barrier
	s_mov_b32 m0, s63
	s_nop 0
	global_load_lds_dwordx4 v0, s[8:9]
	s_add_u32 s8, s4, 0x80
	s_mov_b32 m0, s64
	s_nop 0
	global_load_lds_dwordx4 v0, s[24:25]
	s_addc_u32 s9, s5, 0
	s_sub_u32 s2, 0, s38
	s_subb_u32 s24, 0, s39
	s_add_u32 s2, s14, s2
	s_addc_u32 s15, s15, s24
	s_add_u32 s14, s2, 0x80
	s_addc_u32 s15, s15, 0
	s_add_i32 s65, s53, 0x8000
	s_add_i32 s66, s53, 0xa000
	s_mov_b32 m0, s65
	s_nop 0
	global_load_lds_dwordx4 v160, s[8:9]
	s_add_u32 s8, s10, 0x80
	s_addc_u32 s9, s11, 0
	s_mov_b32 m0, s66
	s_nop 0
	global_load_lds_dwordx4 v160, s[14:15]
	s_add_u32 s10, s12, 0x80
	v_lshlrev_b32_e32 v2, 2, v2
	s_addc_u32 s11, s13, 0
	s_add_i32 s67, s53, 0x1c000
	s_mov_b32 m0, s67
	s_nop 0
	global_load_lds_dwordx4 v0, s[8:9]
	v_lshlrev_b32_e32 v3, 2, v3
	v_lshl_or_b32 v1, v1, 6, v6
	v_and_b32_e32 v2, 32, v2
	s_add_i32 s73, s53, 0x1e000
	s_mov_b32 m0, s73
	s_nop 0
	global_load_lds_dwordx4 v0, s[10:11]
	v_and_b32_e32 v3, 32, v3
	v_bitop3_b32 v1, v1, v4, v2 bitop3:0xde
	s_waitcnt vmcnt(6)
	s_add_i32 s78, s53, 0xc000
	s_add_i32 s79, s53, 0xe000
	v_readlane_b32 s2, v254, 0
	v_mov_b32_e32 v161, v0
	v_bitop3_b32 v3, v5, v7, v3 bitop3:0xde
	s_cmpk_lt_u32 s2, 0x100
	v_add_u32_e32 v0, 0, v1
	s_cselect_b64 s[24:25], -1, 0
	s_mov_b32 s27, 0
	v_add_u32_e32 v191, 0x10000, v0
	v_add_u32_e32 v192, 0x14000, v0
	v_add_u32_e32 v193, 0, v3
	v_mov_b32_e32 v194, 0x79797979
	v_mov_b32_e32 v195, 0x7f7f7f7f
	v_add_u32_e32 v196, 0x18000, v0
	v_add_u32_e32 v197, 0x1c000, v0
	s_mov_b32 s82, 0
	s_barrier
	s_branch .LBB0_234

.LBB0_236:
	s_cmp_lt_i32 s18, 3
	s_cbranch_scc1 .Lhz_238
	s_add_i32 s2, s18, -2
	s_add_u32 s26, s4, s40
	s_addc_u32 s31, s5, s41
	s_add_u32 s33, s6, s22
	s_addc_u32 s46, s7, s23
	s_add_u32 s42, s16, s22
	s_addc_u32 s43, s17, s23
	s_add_u32 s47, s6, s42
	s_addc_u32 s48, s7, s43
	s_add_u32 s49, s6, s16
	s_addc_u32 s68, s7, s17
	s_add_u32 s42, s38, s40
	s_addc_u32 s43, s39, s41
	s_add_u32 s69, s4, s42
	s_addc_u32 s70, s5, s43
	s_add_u32 s71, s4, s38
	s_addc_u32 s72, s5, s39
	s_mov_b32 s74, 0
	s_mov_b64 s[42:43], 0
	s_cmp_eq_u32 s98, 0
	s_cbranch_scc1 .Lhf_238
	ds_read_b128 v[24:27], v191
	ds_read_b128 v[28:31], v191 offset:1024
	ds_read_b128 v[16:19], v191 offset:2048
	ds_read_b128 v[20:23], v191 offset:3072
	ds_read_b128 v[8:11], v192
	ds_read_b128 v[12:15], v192 offset:1024
	ds_read_b128 v[0:3], v192 offset:2048
	ds_read_b128 v[4:7], v192 offset:3072
	s_add_i32 s74, s74, 2
	s_add_u32 s75, s4, s42
	s_addc_u32 s77, s5, s43
	s_add_u32 s44, s75, 0x100
	s_addc_u32 s45, s77, 0
	s_add_u32 s80, s26, s42
	ds_read_b128 v[162:165], v193
	ds_read_b128 v[166:169], v193 offset:1024
	ds_read_b128 v[170:173], v193 offset:2048
	ds_read_b128 v[174:177], v193 offset:3072
	ds_read_b128 v[178:181], v193 offset:4096
	ds_read_b128 v[182:185], v193 offset:5120
	ds_read_b128 v[198:201], v193 offset:6144
	ds_read_b128 v[202:205], v193 offset:7168
	s_addc_u32 s81, s31, s43
	s_add_u32 s86, s80, 0x80
	s_addc_u32 s87, s81, 0
	s_add_u32 s83, s69, s42
	s_addc_u32 s84, s70, s43
	s_add_u32 s88, s83, 0x80
	s_mov_b32 m0, s78
	s_nop 0
	global_load_lds_dwordx4 v160, s[86:87]
	s_addc_u32 s89, s84, 0
	s_mov_b32 m0, s79
	s_nop 0
	global_load_lds_dwordx4 v160, s[88:89]
	s_waitcnt vmcnt(24)
	s_waitcnt lgkmcnt(0)
	s_barrier
	s_waitcnt lgkmcnt(6)
	v_mfma_scale_f32_16x16x128_f8f6f4 v[156:159], v[24:31], v[162:169], 0, v195, v194 op_sel_hi:[0,0,0]
	v_mfma_scale_f32_16x16x128_f8f6f4 v[152:155], v[16:23], v[162:169], 0, v195, v194 op_sel_hi:[0,0,0]
	s_waitcnt lgkmcnt(4)
	v_mfma_scale_f32_16x16x128_f8f6f4 v[148:151], v[24:31], v[170:177], 0, v195, v194 op_sel_hi:[0,0,0]
	v_mfma_scale_f32_16x16x128_f8f6f4 v[144:147], v[16:23], v[170:177], 0, v195, v194 op_sel_hi:[0,0,0]
	s_waitcnt lgkmcnt(2)
	v_mfma_scale_f32_16x16x128_f8f6f4 v[140:143], v[24:31], v[178:185], 0, v195, v194 op_sel_hi:[0,0,0]
	v_mfma_scale_f32_16x16x128_f8f6f4 v[136:139], v[16:23], v[178:185], 0, v195, v194 op_sel_hi:[0,0,0]
	s_waitcnt lgkmcnt(0)
	v_mfma_scale_f32_16x16x128_f8f6f4 v[132:135], v[24:31], v[198:205], 0, v195, v194 op_sel_hi:[0,0,0]
	v_mfma_scale_f32_16x16x128_f8f6f4 v[128:131], v[16:23], v[198:205], 0, v195, v194 op_sel_hi:[0,0,0]
	v_mfma_scale_f32_16x16x128_f8f6f4 v[124:127], v[8:15], v[162:169], 0, v195, v194 op_sel_hi:[0,0,0]
	v_mfma_scale_f32_16x16x128_f8f6f4 v[120:123], v[0:7], v[162:169], 0, v195, v194 op_sel_hi:[0,0,0]
	v_mfma_scale_f32_16x16x128_f8f6f4 v[116:119], v[8:15], v[170:177], 0, v195, v194 op_sel_hi:[0,0,0]
	v_mfma_scale_f32_16x16x128_f8f6f4 v[112:115], v[0:7], v[170:177], 0, v195, v194 op_sel_hi:[0,0,0]
	v_mfma_scale_f32_16x16x128_f8f6f4 v[108:111], v[8:15], v[178:185], 0, v195, v194 op_sel_hi:[0,0,0]
	v_mfma_scale_f32_16x16x128_f8f6f4 v[104:107], v[0:7], v[178:185], 0, v195, v194 op_sel_hi:[0,0,0]
	v_mfma_scale_f32_16x16x128_f8f6f4 v[100:103], v[8:15], v[198:205], 0, v195, v194 op_sel_hi:[0,0,0]
	v_mfma_scale_f32_16x16x128_f8f6f4 v[96:99], v[0:7], v[198:205], 0, v195, v194 op_sel_hi:[0,0,0]
	s_barrier
	s_add_u32 s85, s6, s42
	s_addc_u32 s86, s7, s43
	s_add_u32 s90, s85, 0x100
	s_addc_u32 s91, s86, 0
	s_add_u32 s87, s49, s42
	s_addc_u32 s88, s68, s43
	s_add_u32 s92, s87, 0x100
	s_addc_u32 s93, s88, 0
	s_add_u32 s89, s33, s42
	ds_read_b128 v[162:165], v193 offset:16384
	ds_read_b128 v[166:169], v193 offset:17408
	ds_read_b128 v[170:173], v193 offset:18432
	ds_read_b128 v[174:177], v193 offset:19456
	ds_read_b128 v[178:181], v193 offset:20480
	ds_read_b128 v[182:185], v193 offset:21504
	ds_read_b128 v[198:201], v193 offset:22528
	ds_read_b128 v[202:205], v193 offset:23552
	s_mov_b32 m0, s51
	s_nop 0
	global_load_lds_dwordx4 v161, s[90:91]
	s_addc_u32 s90, s46, s43
	s_add_u32 s96, s89, 0x100
	s_addc_u32 s97, s90, 0
	s_mov_b32 m0, s57
	s_nop 0
	global_load_lds_dwordx4 v161, s[92:93]
	s_add_u32 s93, s47, s42
	s_addc_u32 s94, s48, s43
	s_add_u32 s54, s93, 0x100
	s_mov_b32 m0, s58
	s_nop 0
	global_load_lds_dwordx4 v161, s[96:97]
	s_addc_u32 s55, s94, 0
	s_mov_b32 m0, s59
	s_nop 0
	global_load_lds_dwordx4 v161, s[54:55]
	s_add_u32 s91, s71, s42
	s_addc_u32 s92, s72, s43
	s_add_u32 s54, s91, 0x100
	s_mov_b32 m0, s53
	s_nop 0
	global_load_lds_dwordx4 v160, s[44:45]
	s_addc_u32 s55, s92, 0
	s_mov_b32 m0, s60
	s_nop 0
	global_load_lds_dwordx4 v160, s[54:55]
	s_waitcnt vmcnt(24)
	s_waitcnt lgkmcnt(0)
	s_barrier
	s_waitcnt lgkmcnt(6)
	v_mfma_scale_f32_16x16x128_f8f6f4 v[92:95], v[24:31], v[162:169], 0, v195, v194 op_sel_hi:[0,0,0]
	v_mfma_scale_f32_16x16x128_f8f6f4 v[88:91], v[16:23], v[162:169], 0, v195, v194 op_sel_hi:[0,0,0]
	s_waitcnt lgkmcnt(4)
	v_mfma_scale_f32_16x16x128_f8f6f4 v[84:87], v[24:31], v[170:177], 0, v195, v194 op_sel_hi:[0,0,0]
	v_mfma_scale_f32_16x16x128_f8f6f4 v[80:83], v[16:23], v[170:177], 0, v195, v194 op_sel_hi:[0,0,0]
	s_waitcnt lgkmcnt(2)
	v_mfma_scale_f32_16x16x128_f8f6f4 v[76:79], v[24:31], v[178:185], 0, v195, v194 op_sel_hi:[0,0,0]
	v_mfma_scale_f32_16x16x128_f8f6f4 v[72:75], v[16:23], v[178:185], 0, v195, v194 op_sel_hi:[0,0,0]
	s_waitcnt lgkmcnt(0)
	v_mfma_scale_f32_16x16x128_f8f6f4 v[68:71], v[24:31], v[198:205], 0, v195, v194 op_sel_hi:[0,0,0]
	v_mfma_scale_f32_16x16x128_f8f6f4 v[64:67], v[16:23], v[198:205], 0, v195, v194 op_sel_hi:[0,0,0]
	v_mfma_scale_f32_16x16x128_f8f6f4 v[60:63], v[8:15], v[162:169], 0, v195, v194 op_sel_hi:[0,0,0]
	v_mfma_scale_f32_16x16x128_f8f6f4 v[56:59], v[0:7], v[162:169], 0, v195, v194 op_sel_hi:[0,0,0]
	v_mfma_scale_f32_16x16x128_f8f6f4 v[52:55], v[8:15], v[170:177], 0, v195, v194 op_sel_hi:[0,0,0]
	v_mfma_scale_f32_16x16x128_f8f6f4 v[48:51], v[0:7], v[170:177], 0, v195, v194 op_sel_hi:[0,0,0]
	v_mfma_scale_f32_16x16x128_f8f6f4 v[44:47], v[8:15], v[178:185], 0, v195, v194 op_sel_hi:[0,0,0]
	v_mfma_scale_f32_16x16x128_f8f6f4 v[40:43], v[0:7], v[178:185], 0, v195, v194 op_sel_hi:[0,0,0]
	v_mfma_scale_f32_16x16x128_f8f6f4 v[36:39], v[8:15], v[198:205], 0, v195, v194 op_sel_hi:[0,0,0]
	v_mfma_scale_f32_16x16x128_f8f6f4 v[32:35], v[0:7], v[198:205], 0, v195, v194 op_sel_hi:[0,0,0]
	s_barrier
	ds_read_b128 v[24:27], v196
	ds_read_b128 v[28:31], v196 offset:1024
	ds_read_b128 v[16:19], v196 offset:2048
	ds_read_b128 v[20:23], v196 offset:3072
	ds_read_b128 v[8:11], v197
	ds_read_b128 v[12:15], v197 offset:1024
	ds_read_b128 v[0:3], v197 offset:2048
	ds_read_b128 v[4:7], v197 offset:3072
	ds_read_b128 v[162:165], v193 offset:32768
	ds_read_b128 v[166:169], v193 offset:33792
	ds_read_b128 v[170:173], v193 offset:34816
	ds_read_b128 v[174:177], v193 offset:35840
	ds_read_b128 v[178:181], v193 offset:36864
	ds_read_b128 v[182:185], v193 offset:37888
	ds_read_b128 v[198:201], v193 offset:38912
	ds_read_b128 v[202:205], v193 offset:39936
	s_add_u32 s44, s80, 0x100
	s_addc_u32 s45, s81, 0
	s_add_u32 s54, s83, 0x100
	s_mov_b32 m0, s61
	s_nop 0
	global_load_lds_dwordx4 v160, s[44:45]
	s_addc_u32 s55, s84, 0
	s_mov_b32 m0, s62
	s_nop 0
	global_load_lds_dwordx4 v160, s[54:55]
	s_waitcnt vmcnt(8)
	s_waitcnt lgkmcnt(0)
	s_barrier
	s_waitcnt lgkmcnt(6)
	v_mfma_scale_f32_16x16x128_f8f6f4 v[156:159], v[24:31], v[162:169], v[156:159], v195, v194 op_sel_hi:[0,0,0]
	v_mfma_scale_f32_16x16x128_f8f6f4 v[152:155], v[16:23], v[162:169], v[152:155], v195, v194 op_sel_hi:[0,0,0]
	s_waitcnt lgkmcnt(4)
	v_mfma_scale_f32_16x16x128_f8f6f4 v[148:151], v[24:31], v[170:177], v[148:151], v195, v194 op_sel_hi:[0,0,0]
	v_mfma_scale_f32_16x16x128_f8f6f4 v[144:147], v[16:23], v[170:177], v[144:147], v195, v194 op_sel_hi:[0,0,0]
	s_waitcnt lgkmcnt(2)
	v_mfma_scale_f32_16x16x128_f8f6f4 v[140:143], v[24:31], v[178:185], v[140:143], v195, v194 op_sel_hi:[0,0,0]
	v_mfma_scale_f32_16x16x128_f8f6f4 v[136:139], v[16:23], v[178:185], v[136:139], v195, v194 op_sel_hi:[0,0,0]
	s_waitcnt lgkmcnt(0)
	v_mfma_scale_f32_16x16x128_f8f6f4 v[132:135], v[24:31], v[198:205], v[132:135], v195, v194 op_sel_hi:[0,0,0]
	v_mfma_scale_f32_16x16x128_f8f6f4 v[128:131], v[16:23], v[198:205], v[128:131], v195, v194 op_sel_hi:[0,0,0]
	v_mfma_scale_f32_16x16x128_f8f6f4 v[124:127], v[8:15], v[162:169], v[124:127], v195, v194 op_sel_hi:[0,0,0]
	v_mfma_scale_f32_16x16x128_f8f6f4 v[120:123], v[0:7], v[162:169], v[120:123], v195, v194 op_sel_hi:[0,0,0]
	v_mfma_scale_f32_16x16x128_f8f6f4 v[116:119], v[8:15], v[170:177], v[116:119], v195, v194 op_sel_hi:[0,0,0]
	v_mfma_scale_f32_16x16x128_f8f6f4 v[112:115], v[0:7], v[170:177], v[112:115], v195, v194 op_sel_hi:[0,0,0]
	v_mfma_scale_f32_16x16x128_f8f6f4 v[108:111], v[8:15], v[178:185], v[108:111], v195, v194 op_sel_hi:[0,0,0]
	v_mfma_scale_f32_16x16x128_f8f6f4 v[104:107], v[0:7], v[178:185], v[104:107], v195, v194 op_sel_hi:[0,0,0]
	v_mfma_scale_f32_16x16x128_f8f6f4 v[100:103], v[8:15], v[198:205], v[100:103], v195, v194 op_sel_hi:[0,0,0]
	v_mfma_scale_f32_16x16x128_f8f6f4 v[96:99], v[0:7], v[198:205], v[96:99], v195, v194 op_sel_hi:[0,0,0]
	s_barrier
	s_add_u32 s44, s85, 0x180
	s_addc_u32 s45, s86, 0
	ds_read_b128 v[162:165], v193 offset:49152
	ds_read_b128 v[166:169], v193 offset:50176
	ds_read_b128 v[170:173], v193 offset:51200
	ds_read_b128 v[174:177], v193 offset:52224
	ds_read_b128 v[178:181], v193 offset:53248
	ds_read_b128 v[182:185], v193 offset:54272
	ds_read_b128 v[198:201], v193 offset:55296
	ds_read_b128 v[202:205], v193 offset:56320
	s_add_u32 s54, s87, 0x180
	s_mov_b32 m0, s63
	s_nop 0
	global_load_lds_dwordx4 v161, s[44:45]
	s_addc_u32 s55, s88, 0
	s_mov_b32 m0, s64
	s_nop 0
	global_load_lds_dwordx4 v161, s[54:55]
	s_add_u32 s44, s89, 0x180
	s_addc_u32 s45, s90, 0
	s_add_u32 s54, s93, 0x180
	s_mov_b32 m0, s67
	s_nop 0
	global_load_lds_dwordx4 v161, s[44:45]
	s_addc_u32 s55, s94, 0
	s_mov_b32 m0, s73
	s_nop 0
	global_load_lds_dwordx4 v161, s[54:55]
	s_add_u32 s44, s75, 0x180
	s_addc_u32 s45, s77, 0
	s_add_u32 s54, s91, 0x180
	s_mov_b32 m0, s65
	s_nop 0
	global_load_lds_dwordx4 v160, s[44:45]
	s_addc_u32 s55, s92, 0
	s_mov_b32 m0, s66
	s_nop 0
	global_load_lds_dwordx4 v160, s[54:55]
	s_waitcnt vmcnt(8)
	s_waitcnt lgkmcnt(0)
	s_barrier
	s_waitcnt lgkmcnt(6)
	v_mfma_scale_f32_16x16x128_f8f6f4 v[92:95], v[24:31], v[162:169], v[92:95], v195, v194 op_sel_hi:[0,0,0]
	v_mfma_scale_f32_16x16x128_f8f6f4 v[88:91], v[16:23], v[162:169], v[88:91], v195, v194 op_sel_hi:[0,0,0]
	s_waitcnt lgkmcnt(4)
	v_mfma_scale_f32_16x16x128_f8f6f4 v[84:87], v[24:31], v[170:177], v[84:87], v195, v194 op_sel_hi:[0,0,0]
	v_mfma_scale_f32_16x16x128_f8f6f4 v[80:83], v[16:23], v[170:177], v[80:83], v195, v194 op_sel_hi:[0,0,0]
	s_waitcnt lgkmcnt(2)
	v_mfma_scale_f32_16x16x128_f8f6f4 v[76:79], v[24:31], v[178:185], v[76:79], v195, v194 op_sel_hi:[0,0,0]
	v_mfma_scale_f32_16x16x128_f8f6f4 v[72:75], v[16:23], v[178:185], v[72:75], v195, v194 op_sel_hi:[0,0,0]
	s_waitcnt lgkmcnt(0)
	v_mfma_scale_f32_16x16x128_f8f6f4 v[68:71], v[24:31], v[198:205], v[68:71], v195, v194 op_sel_hi:[0,0,0]
	v_mfma_scale_f32_16x16x128_f8f6f4 v[64:67], v[16:23], v[198:205], v[64:67], v195, v194 op_sel_hi:[0,0,0]
	v_mfma_scale_f32_16x16x128_f8f6f4 v[60:63], v[8:15], v[162:169], v[60:63], v195, v194 op_sel_hi:[0,0,0]
	v_mfma_scale_f32_16x16x128_f8f6f4 v[56:59], v[0:7], v[162:169], v[56:59], v195, v194 op_sel_hi:[0,0,0]
	v_mfma_scale_f32_16x16x128_f8f6f4 v[52:55], v[8:15], v[170:177], v[52:55], v195, v194 op_sel_hi:[0,0,0]
	v_mfma_scale_f32_16x16x128_f8f6f4 v[48:51], v[0:7], v[170:177], v[48:51], v195, v194 op_sel_hi:[0,0,0]
	v_mfma_scale_f32_16x16x128_f8f6f4 v[44:47], v[8:15], v[178:185], v[44:47], v195, v194 op_sel_hi:[0,0,0]
	v_mfma_scale_f32_16x16x128_f8f6f4 v[40:43], v[0:7], v[178:185], v[40:43], v195, v194 op_sel_hi:[0,0,0]
	v_mfma_scale_f32_16x16x128_f8f6f4 v[36:39], v[8:15], v[198:205], v[36:39], v195, v194 op_sel_hi:[0,0,0]
	v_mfma_scale_f32_16x16x128_f8f6f4 v[32:35], v[0:7], v[198:205], v[32:35], v195, v194 op_sel_hi:[0,0,0]
	s_barrier
	s_add_u32 s42, s42, 0x100
	s_addc_u32 s43, s43, 0
	s_cmp_ge_i32 s74, s2
	s_cbranch_scc0 .LBB0_238
	s_branch .LBB0_239
.Lhf_238:
	ds_read_b128 v[24:27], v191
	ds_read_b128 v[28:31], v191 offset:1024
	ds_read_b128 v[16:19], v191 offset:2048
	ds_read_b128 v[20:23], v191 offset:3072
	ds_read_b128 v[8:11], v192
	ds_read_b128 v[12:15], v192 offset:1024
	ds_read_b128 v[0:3], v192 offset:2048
	ds_read_b128 v[4:7], v192 offset:3072
	s_add_i32 s74, s74, 2
	s_add_u32 s75, s4, s42
	s_addc_u32 s77, s5, s43
	s_add_u32 s44, s75, 0x100
	s_addc_u32 s45, s77, 0
	s_add_u32 s80, s26, s42
	ds_read_b128 v[162:165], v193
	ds_read_b128 v[166:169], v193 offset:1024
	ds_read_b128 v[170:173], v193 offset:2048
	ds_read_b128 v[174:177], v193 offset:3072
	ds_read_b128 v[178:181], v193 offset:4096
	ds_read_b128 v[182:185], v193 offset:5120
	ds_read_b128 v[198:201], v193 offset:6144
	ds_read_b128 v[202:205], v193 offset:7168
	s_addc_u32 s81, s31, s43
	s_add_u32 s86, s80, 0x80
	s_addc_u32 s87, s81, 0
	s_add_u32 s83, s69, s42
	s_addc_u32 s84, s70, s43
	s_add_u32 s88, s83, 0x80
	s_mov_b32 m0, s78
	s_nop 0
	global_load_lds_dwordx4 v160, s[86:87]
	s_addc_u32 s89, s84, 0
	s_mov_b32 m0, s79
	s_nop 0
	global_load_lds_dwordx4 v160, s[88:89]
	s_waitcnt vmcnt(8)
	s_waitcnt lgkmcnt(0)
	s_barrier
	s_waitcnt lgkmcnt(6)
	v_mfma_scale_f32_16x16x128_f8f6f4 v[156:159], v[24:31], v[162:169], 0, v195, v194 op_sel_hi:[0,0,0]
	v_mfma_scale_f32_16x16x128_f8f6f4 v[152:155], v[16:23], v[162:169], 0, v195, v194 op_sel_hi:[0,0,0]
	s_waitcnt lgkmcnt(4)
	v_mfma_scale_f32_16x16x128_f8f6f4 v[148:151], v[24:31], v[170:177], 0, v195, v194 op_sel_hi:[0,0,0]
	v_mfma_scale_f32_16x16x128_f8f6f4 v[144:147], v[16:23], v[170:177], 0, v195, v194 op_sel_hi:[0,0,0]
	s_waitcnt lgkmcnt(2)
	v_mfma_scale_f32_16x16x128_f8f6f4 v[140:143], v[24:31], v[178:185], 0, v195, v194 op_sel_hi:[0,0,0]
	v_mfma_scale_f32_16x16x128_f8f6f4 v[136:139], v[16:23], v[178:185], 0, v195, v194 op_sel_hi:[0,0,0]
	s_waitcnt lgkmcnt(0)
	v_mfma_scale_f32_16x16x128_f8f6f4 v[132:135], v[24:31], v[198:205], 0, v195, v194 op_sel_hi:[0,0,0]
	v_mfma_scale_f32_16x16x128_f8f6f4 v[128:131], v[16:23], v[198:205], 0, v195, v194 op_sel_hi:[0,0,0]
	v_mfma_scale_f32_16x16x128_f8f6f4 v[124:127], v[8:15], v[162:169], 0, v195, v194 op_sel_hi:[0,0,0]
	v_mfma_scale_f32_16x16x128_f8f6f4 v[120:123], v[0:7], v[162:169], 0, v195, v194 op_sel_hi:[0,0,0]
	v_mfma_scale_f32_16x16x128_f8f6f4 v[116:119], v[8:15], v[170:177], 0, v195, v194 op_sel_hi:[0,0,0]
	v_mfma_scale_f32_16x16x128_f8f6f4 v[112:115], v[0:7], v[170:177], 0, v195, v194 op_sel_hi:[0,0,0]
	v_mfma_scale_f32_16x16x128_f8f6f4 v[108:111], v[8:15], v[178:185], 0, v195, v194 op_sel_hi:[0,0,0]
	v_mfma_scale_f32_16x16x128_f8f6f4 v[104:107], v[0:7], v[178:185], 0, v195, v194 op_sel_hi:[0,0,0]
	v_mfma_scale_f32_16x16x128_f8f6f4 v[100:103], v[8:15], v[198:205], 0, v195, v194 op_sel_hi:[0,0,0]
	v_mfma_scale_f32_16x16x128_f8f6f4 v[96:99], v[0:7], v[198:205], 0, v195, v194 op_sel_hi:[0,0,0]
	s_barrier
	s_add_u32 s85, s6, s42
	s_addc_u32 s86, s7, s43
	s_add_u32 s90, s85, 0x100
	s_addc_u32 s91, s86, 0
	s_add_u32 s87, s49, s42
	s_addc_u32 s88, s68, s43
	s_add_u32 s92, s87, 0x100
	s_addc_u32 s93, s88, 0
	s_add_u32 s89, s33, s42
	ds_read_b128 v[162:165], v193 offset:16384
	ds_read_b128 v[166:169], v193 offset:17408
	ds_read_b128 v[170:173], v193 offset:18432
	ds_read_b128 v[174:177], v193 offset:19456
	ds_read_b128 v[178:181], v193 offset:20480
	ds_read_b128 v[182:185], v193 offset:21504
	ds_read_b128 v[198:201], v193 offset:22528
	ds_read_b128 v[202:205], v193 offset:23552
	s_mov_b32 m0, s51
	s_nop 0
	global_load_lds_dwordx4 v161, s[90:91]
	s_addc_u32 s90, s46, s43
	s_add_u32 s96, s89, 0x100
	s_addc_u32 s97, s90, 0
	s_mov_b32 m0, s57
	s_nop 0
	global_load_lds_dwordx4 v161, s[92:93]
	s_add_u32 s93, s47, s42
	s_addc_u32 s94, s48, s43
	s_add_u32 s54, s93, 0x100
	s_mov_b32 m0, s58
	s_nop 0
	global_load_lds_dwordx4 v161, s[96:97]
	s_addc_u32 s55, s94, 0
	s_mov_b32 m0, s59
	s_nop 0
	global_load_lds_dwordx4 v161, s[54:55]
	s_add_u32 s91, s71, s42
	s_addc_u32 s92, s72, s43
	s_add_u32 s54, s91, 0x100
	s_mov_b32 m0, s53
	s_nop 0
	global_load_lds_dwordx4 v160, s[44:45]
	s_addc_u32 s55, s92, 0
	s_mov_b32 m0, s60
	s_nop 0
	global_load_lds_dwordx4 v160, s[54:55]
	s_waitcnt vmcnt(8)
	s_waitcnt lgkmcnt(0)
	s_barrier
	s_waitcnt lgkmcnt(6)
	v_mfma_scale_f32_16x16x128_f8f6f4 v[92:95], v[24:31], v[162:169], 0, v195, v194 op_sel_hi:[0,0,0]
	v_mfma_scale_f32_16x16x128_f8f6f4 v[88:91], v[16:23], v[162:169], 0, v195, v194 op_sel_hi:[0,0,0]
	s_waitcnt lgkmcnt(4)
	v_mfma_scale_f32_16x16x128_f8f6f4 v[84:87], v[24:31], v[170:177], 0, v195, v194 op_sel_hi:[0,0,0]
	v_mfma_scale_f32_16x16x128_f8f6f4 v[80:83], v[16:23], v[170:177], 0, v195, v194 op_sel_hi:[0,0,0]
	s_waitcnt lgkmcnt(2)
	v_mfma_scale_f32_16x16x128_f8f6f4 v[76:79], v[24:31], v[178:185], 0, v195, v194 op_sel_hi:[0,0,0]
	v_mfma_scale_f32_16x16x128_f8f6f4 v[72:75], v[16:23], v[178:185], 0, v195, v194 op_sel_hi:[0,0,0]
	s_waitcnt lgkmcnt(0)
	v_mfma_scale_f32_16x16x128_f8f6f4 v[68:71], v[24:31], v[198:205], 0, v195, v194 op_sel_hi:[0,0,0]
	v_mfma_scale_f32_16x16x128_f8f6f4 v[64:67], v[16:23], v[198:205], 0, v195, v194 op_sel_hi:[0,0,0]
	v_mfma_scale_f32_16x16x128_f8f6f4 v[60:63], v[8:15], v[162:169], 0, v195, v194 op_sel_hi:[0,0,0]
	v_mfma_scale_f32_16x16x128_f8f6f4 v[56:59], v[0:7], v[162:169], 0, v195, v194 op_sel_hi:[0,0,0]
	v_mfma_scale_f32_16x16x128_f8f6f4 v[52:55], v[8:15], v[170:177], 0, v195, v194 op_sel_hi:[0,0,0]
	v_mfma_scale_f32_16x16x128_f8f6f4 v[48:51], v[0:7], v[170:177], 0, v195, v194 op_sel_hi:[0,0,0]
	v_mfma_scale_f32_16x16x128_f8f6f4 v[44:47], v[8:15], v[178:185], 0, v195, v194 op_sel_hi:[0,0,0]
	v_mfma_scale_f32_16x16x128_f8f6f4 v[40:43], v[0:7], v[178:185], 0, v195, v194 op_sel_hi:[0,0,0]
	v_mfma_scale_f32_16x16x128_f8f6f4 v[36:39], v[8:15], v[198:205], 0, v195, v194 op_sel_hi:[0,0,0]
	v_mfma_scale_f32_16x16x128_f8f6f4 v[32:35], v[0:7], v[198:205], 0, v195, v194 op_sel_hi:[0,0,0]
	s_barrier
	ds_read_b128 v[24:27], v196
	ds_read_b128 v[28:31], v196 offset:1024
	ds_read_b128 v[16:19], v196 offset:2048
	ds_read_b128 v[20:23], v196 offset:3072
	ds_read_b128 v[8:11], v197
	ds_read_b128 v[12:15], v197 offset:1024
	ds_read_b128 v[0:3], v197 offset:2048
	ds_read_b128 v[4:7], v197 offset:3072
	ds_read_b128 v[162:165], v193 offset:32768
	ds_read_b128 v[166:169], v193 offset:33792
	ds_read_b128 v[170:173], v193 offset:34816
	ds_read_b128 v[174:177], v193 offset:35840
	ds_read_b128 v[178:181], v193 offset:36864
	ds_read_b128 v[182:185], v193 offset:37888
	ds_read_b128 v[198:201], v193 offset:38912
	ds_read_b128 v[202:205], v193 offset:39936
	s_add_u32 s44, s80, 0x100
	s_addc_u32 s45, s81, 0
	s_add_u32 s54, s83, 0x100
	s_mov_b32 m0, s61
	s_nop 0
	global_load_lds_dwordx4 v160, s[44:45]
	s_addc_u32 s55, s84, 0
	s_mov_b32 m0, s62
	s_nop 0
	global_load_lds_dwordx4 v160, s[54:55]
	s_waitcnt vmcnt(8)
	s_waitcnt lgkmcnt(0)
	s_barrier
	s_waitcnt lgkmcnt(6)
	v_mfma_scale_f32_16x16x128_f8f6f4 v[156:159], v[24:31], v[162:169], v[156:159], v195, v194 op_sel_hi:[0,0,0]
	v_mfma_scale_f32_16x16x128_f8f6f4 v[152:155], v[16:23], v[162:169], v[152:155], v195, v194 op_sel_hi:[0,0,0]
	s_waitcnt lgkmcnt(4)
	v_mfma_scale_f32_16x16x128_f8f6f4 v[148:151], v[24:31], v[170:177], v[148:151], v195, v194 op_sel_hi:[0,0,0]
	v_mfma_scale_f32_16x16x128_f8f6f4 v[144:147], v[16:23], v[170:177], v[144:147], v195, v194 op_sel_hi:[0,0,0]
	s_waitcnt lgkmcnt(2)
	v_mfma_scale_f32_16x16x128_f8f6f4 v[140:143], v[24:31], v[178:185], v[140:143], v195, v194 op_sel_hi:[0,0,0]
	v_mfma_scale_f32_16x16x128_f8f6f4 v[136:139], v[16:23], v[178:185], v[136:139], v195, v194 op_sel_hi:[0,0,0]
	s_waitcnt lgkmcnt(0)
	v_mfma_scale_f32_16x16x128_f8f6f4 v[132:135], v[24:31], v[198:205], v[132:135], v195, v194 op_sel_hi:[0,0,0]
	v_mfma_scale_f32_16x16x128_f8f6f4 v[128:131], v[16:23], v[198:205], v[128:131], v195, v194 op_sel_hi:[0,0,0]
	v_mfma_scale_f32_16x16x128_f8f6f4 v[124:127], v[8:15], v[162:169], v[124:127], v195, v194 op_sel_hi:[0,0,0]
	v_mfma_scale_f32_16x16x128_f8f6f4 v[120:123], v[0:7], v[162:169], v[120:123], v195, v194 op_sel_hi:[0,0,0]
	v_mfma_scale_f32_16x16x128_f8f6f4 v[116:119], v[8:15], v[170:177], v[116:119], v195, v194 op_sel_hi:[0,0,0]
	v_mfma_scale_f32_16x16x128_f8f6f4 v[112:115], v[0:7], v[170:177], v[112:115], v195, v194 op_sel_hi:[0,0,0]
	v_mfma_scale_f32_16x16x128_f8f6f4 v[108:111], v[8:15], v[178:185], v[108:111], v195, v194 op_sel_hi:[0,0,0]
	v_mfma_scale_f32_16x16x128_f8f6f4 v[104:107], v[0:7], v[178:185], v[104:107], v195, v194 op_sel_hi:[0,0,0]
	v_mfma_scale_f32_16x16x128_f8f6f4 v[100:103], v[8:15], v[198:205], v[100:103], v195, v194 op_sel_hi:[0,0,0]
	v_mfma_scale_f32_16x16x128_f8f6f4 v[96:99], v[0:7], v[198:205], v[96:99], v195, v194 op_sel_hi:[0,0,0]
	s_barrier
	s_add_u32 s44, s85, 0x180
	s_addc_u32 s45, s86, 0
	ds_read_b128 v[162:165], v193 offset:49152
	ds_read_b128 v[166:169], v193 offset:50176
	ds_read_b128 v[170:173], v193 offset:51200
	ds_read_b128 v[174:177], v193 offset:52224
	ds_read_b128 v[178:181], v193 offset:53248
	ds_read_b128 v[182:185], v193 offset:54272
	ds_read_b128 v[198:201], v193 offset:55296
	ds_read_b128 v[202:205], v193 offset:56320
	s_add_u32 s54, s87, 0x180
	s_mov_b32 m0, s63
	s_nop 0
	global_load_lds_dwordx4 v161, s[44:45]
	s_addc_u32 s55, s88, 0
	s_mov_b32 m0, s64
	s_nop 0
	global_load_lds_dwordx4 v161, s[54:55]
	s_add_u32 s44, s89, 0x180
	s_addc_u32 s45, s90, 0
	s_add_u32 s54, s93, 0x180
	s_mov_b32 m0, s67
	s_nop 0
	global_load_lds_dwordx4 v161, s[44:45]
	s_addc_u32 s55, s94, 0
	s_mov_b32 m0, s73
	s_nop 0
	global_load_lds_dwordx4 v161, s[54:55]
	s_add_u32 s44, s75, 0x180
	s_addc_u32 s45, s77, 0
	s_add_u32 s54, s91, 0x180
	s_mov_b32 m0, s65
	s_nop 0
	global_load_lds_dwordx4 v160, s[44:45]
	s_addc_u32 s55, s92, 0
	s_mov_b32 m0, s66
	s_nop 0
	global_load_lds_dwordx4 v160, s[54:55]
	s_waitcnt vmcnt(8)
	s_waitcnt lgkmcnt(0)
	s_barrier
	s_waitcnt lgkmcnt(6)
	v_mfma_scale_f32_16x16x128_f8f6f4 v[92:95], v[24:31], v[162:169], v[92:95], v195, v194 op_sel_hi:[0,0,0]
	v_mfma_scale_f32_16x16x128_f8f6f4 v[88:91], v[16:23], v[162:169], v[88:91], v195, v194 op_sel_hi:[0,0,0]
	s_waitcnt lgkmcnt(4)
	v_mfma_scale_f32_16x16x128_f8f6f4 v[84:87], v[24:31], v[170:177], v[84:87], v195, v194 op_sel_hi:[0,0,0]
	v_mfma_scale_f32_16x16x128_f8f6f4 v[80:83], v[16:23], v[170:177], v[80:83], v195, v194 op_sel_hi:[0,0,0]
	s_waitcnt lgkmcnt(2)
	v_mfma_scale_f32_16x16x128_f8f6f4 v[76:79], v[24:31], v[178:185], v[76:79], v195, v194 op_sel_hi:[0,0,0]
	v_mfma_scale_f32_16x16x128_f8f6f4 v[72:75], v[16:23], v[178:185], v[72:75], v195, v194 op_sel_hi:[0,0,0]
	s_waitcnt lgkmcnt(0)
	v_mfma_scale_f32_16x16x128_f8f6f4 v[68:71], v[24:31], v[198:205], v[68:71], v195, v194 op_sel_hi:[0,0,0]
	v_mfma_scale_f32_16x16x128_f8f6f4 v[64:67], v[16:23], v[198:205], v[64:67], v195, v194 op_sel_hi:[0,0,0]
	v_mfma_scale_f32_16x16x128_f8f6f4 v[60:63], v[8:15], v[162:169], v[60:63], v195, v194 op_sel_hi:[0,0,0]
	v_mfma_scale_f32_16x16x128_f8f6f4 v[56:59], v[0:7], v[162:169], v[56:59], v195, v194 op_sel_hi:[0,0,0]
	v_mfma_scale_f32_16x16x128_f8f6f4 v[52:55], v[8:15], v[170:177], v[52:55], v195, v194 op_sel_hi:[0,0,0]
	v_mfma_scale_f32_16x16x128_f8f6f4 v[48:51], v[0:7], v[170:177], v[48:51], v195, v194 op_sel_hi:[0,0,0]
	v_mfma_scale_f32_16x16x128_f8f6f4 v[44:47], v[8:15], v[178:185], v[44:47], v195, v194 op_sel_hi:[0,0,0]
	v_mfma_scale_f32_16x16x128_f8f6f4 v[40:43], v[0:7], v[178:185], v[40:43], v195, v194 op_sel_hi:[0,0,0]
	v_mfma_scale_f32_16x16x128_f8f6f4 v[36:39], v[8:15], v[198:205], v[36:39], v195, v194 op_sel_hi:[0,0,0]
	v_mfma_scale_f32_16x16x128_f8f6f4 v[32:35], v[0:7], v[198:205], v[32:35], v195, v194 op_sel_hi:[0,0,0]
	s_barrier
	s_add_u32 s42, s42, 0x100
	s_addc_u32 s43, s43, 0
	s_cmp_ge_i32 s74, s2
	s_cbranch_scc0 .LBB0_238
	s_branch .LBB0_239

.LBB0_238:
	ds_read_b128 v[24:27], v191
	ds_read_b128 v[28:31], v191 offset:1024
	ds_read_b128 v[16:19], v191 offset:2048
	ds_read_b128 v[20:23], v191 offset:3072
	ds_read_b128 v[8:11], v192
	ds_read_b128 v[12:15], v192 offset:1024
	ds_read_b128 v[0:3], v192 offset:2048
	ds_read_b128 v[4:7], v192 offset:3072
	s_add_i32 s74, s74, 2
	s_add_u32 s75, s4, s42
	s_addc_u32 s77, s5, s43
	s_add_u32 s44, s75, 0x100
	s_addc_u32 s45, s77, 0
	s_add_u32 s80, s26, s42
	ds_read_b128 v[162:165], v193
	ds_read_b128 v[166:169], v193 offset:1024
	ds_read_b128 v[170:173], v193 offset:2048
	ds_read_b128 v[174:177], v193 offset:3072
	ds_read_b128 v[178:181], v193 offset:4096
	ds_read_b128 v[182:185], v193 offset:5120
	ds_read_b128 v[198:201], v193 offset:6144
	ds_read_b128 v[202:205], v193 offset:7168
	s_addc_u32 s81, s31, s43
	s_add_u32 s86, s80, 0x80
	s_addc_u32 s87, s81, 0
	s_add_u32 s83, s69, s42
	s_addc_u32 s84, s70, s43
	s_add_u32 s88, s83, 0x80
	s_mov_b32 m0, s78
	s_nop 0
	global_load_lds_dwordx4 v160, s[86:87]
	s_addc_u32 s89, s84, 0
	s_mov_b32 m0, s79
	s_nop 0
	global_load_lds_dwordx4 v160, s[88:89]
	s_waitcnt vmcnt(8)
	s_waitcnt lgkmcnt(0)
	s_barrier
	s_waitcnt lgkmcnt(6)
	v_mfma_scale_f32_16x16x128_f8f6f4 v[156:159], v[24:31], v[162:169], v[156:159], v195, v194 op_sel_hi:[0,0,0]
	v_mfma_scale_f32_16x16x128_f8f6f4 v[152:155], v[16:23], v[162:169], v[152:155], v195, v194 op_sel_hi:[0,0,0]
	s_waitcnt lgkmcnt(4)
	v_mfma_scale_f32_16x16x128_f8f6f4 v[148:151], v[24:31], v[170:177], v[148:151], v195, v194 op_sel_hi:[0,0,0]
	v_mfma_scale_f32_16x16x128_f8f6f4 v[144:147], v[16:23], v[170:177], v[144:147], v195, v194 op_sel_hi:[0,0,0]
	s_waitcnt lgkmcnt(2)
	v_mfma_scale_f32_16x16x128_f8f6f4 v[140:143], v[24:31], v[178:185], v[140:143], v195, v194 op_sel_hi:[0,0,0]
	v_mfma_scale_f32_16x16x128_f8f6f4 v[136:139], v[16:23], v[178:185], v[136:139], v195, v194 op_sel_hi:[0,0,0]
	s_waitcnt lgkmcnt(0)
	v_mfma_scale_f32_16x16x128_f8f6f4 v[132:135], v[24:31], v[198:205], v[132:135], v195, v194 op_sel_hi:[0,0,0]
	v_mfma_scale_f32_16x16x128_f8f6f4 v[128:131], v[16:23], v[198:205], v[128:131], v195, v194 op_sel_hi:[0,0,0]
	v_mfma_scale_f32_16x16x128_f8f6f4 v[124:127], v[8:15], v[162:169], v[124:127], v195, v194 op_sel_hi:[0,0,0]
	v_mfma_scale_f32_16x16x128_f8f6f4 v[120:123], v[0:7], v[162:169], v[120:123], v195, v194 op_sel_hi:[0,0,0]
	v_mfma_scale_f32_16x16x128_f8f6f4 v[116:119], v[8:15], v[170:177], v[116:119], v195, v194 op_sel_hi:[0,0,0]
	v_mfma_scale_f32_16x16x128_f8f6f4 v[112:115], v[0:7], v[170:177], v[112:115], v195, v194 op_sel_hi:[0,0,0]
	v_mfma_scale_f32_16x16x128_f8f6f4 v[108:111], v[8:15], v[178:185], v[108:111], v195, v194 op_sel_hi:[0,0,0]
	v_mfma_scale_f32_16x16x128_f8f6f4 v[104:107], v[0:7], v[178:185], v[104:107], v195, v194 op_sel_hi:[0,0,0]
	v_mfma_scale_f32_16x16x128_f8f6f4 v[100:103], v[8:15], v[198:205], v[100:103], v195, v194 op_sel_hi:[0,0,0]
	v_mfma_scale_f32_16x16x128_f8f6f4 v[96:99], v[0:7], v[198:205], v[96:99], v195, v194 op_sel_hi:[0,0,0]
	s_barrier
	s_add_u32 s85, s6, s42
	s_addc_u32 s86, s7, s43
	s_add_u32 s90, s85, 0x100
	s_addc_u32 s91, s86, 0
	s_add_u32 s87, s49, s42
	s_addc_u32 s88, s68, s43
	s_add_u32 s92, s87, 0x100
	s_addc_u32 s93, s88, 0
	s_add_u32 s89, s33, s42
	ds_read_b128 v[162:165], v193 offset:16384
	ds_read_b128 v[166:169], v193 offset:17408
	ds_read_b128 v[170:173], v193 offset:18432
	ds_read_b128 v[174:177], v193 offset:19456
	ds_read_b128 v[178:181], v193 offset:20480
	ds_read_b128 v[182:185], v193 offset:21504
	ds_read_b128 v[198:201], v193 offset:22528
	ds_read_b128 v[202:205], v193 offset:23552
	s_mov_b32 m0, s51
	s_nop 0
	global_load_lds_dwordx4 v161, s[90:91]
	s_addc_u32 s90, s46, s43
	s_add_u32 s96, s89, 0x100
	s_addc_u32 s97, s90, 0
	s_mov_b32 m0, s57
	s_nop 0
	global_load_lds_dwordx4 v161, s[92:93]
	s_add_u32 s93, s47, s42
	s_addc_u32 s94, s48, s43
	s_add_u32 s54, s93, 0x100
	s_mov_b32 m0, s58
	s_nop 0
	global_load_lds_dwordx4 v161, s[96:97]
	s_addc_u32 s55, s94, 0
	s_mov_b32 m0, s59
	s_nop 0
	global_load_lds_dwordx4 v161, s[54:55]
	s_add_u32 s91, s71, s42
	s_addc_u32 s92, s72, s43
	s_add_u32 s54, s91, 0x100
	s_mov_b32 m0, s53
	s_nop 0
	global_load_lds_dwordx4 v160, s[44:45]
	s_addc_u32 s55, s92, 0
	s_mov_b32 m0, s60
	s_nop 0
	global_load_lds_dwordx4 v160, s[54:55]
	s_waitcnt vmcnt(8)
	s_waitcnt lgkmcnt(0)
	s_barrier
	s_waitcnt lgkmcnt(6)
	v_mfma_scale_f32_16x16x128_f8f6f4 v[92:95], v[24:31], v[162:169], v[92:95], v195, v194 op_sel_hi:[0,0,0]
	v_mfma_scale_f32_16x16x128_f8f6f4 v[88:91], v[16:23], v[162:169], v[88:91], v195, v194 op_sel_hi:[0,0,0]
	s_waitcnt lgkmcnt(4)
	v_mfma_scale_f32_16x16x128_f8f6f4 v[84:87], v[24:31], v[170:177], v[84:87], v195, v194 op_sel_hi:[0,0,0]
	v_mfma_scale_f32_16x16x128_f8f6f4 v[80:83], v[16:23], v[170:177], v[80:83], v195, v194 op_sel_hi:[0,0,0]
	s_waitcnt lgkmcnt(2)
	v_mfma_scale_f32_16x16x128_f8f6f4 v[76:79], v[24:31], v[178:185], v[76:79], v195, v194 op_sel_hi:[0,0,0]
	v_mfma_scale_f32_16x16x128_f8f6f4 v[72:75], v[16:23], v[178:185], v[72:75], v195, v194 op_sel_hi:[0,0,0]
	s_waitcnt lgkmcnt(0)
	v_mfma_scale_f32_16x16x128_f8f6f4 v[68:71], v[24:31], v[198:205], v[68:71], v195, v194 op_sel_hi:[0,0,0]
	v_mfma_scale_f32_16x16x128_f8f6f4 v[64:67], v[16:23], v[198:205], v[64:67], v195, v194 op_sel_hi:[0,0,0]
	v_mfma_scale_f32_16x16x128_f8f6f4 v[60:63], v[8:15], v[162:169], v[60:63], v195, v194 op_sel_hi:[0,0,0]
	v_mfma_scale_f32_16x16x128_f8f6f4 v[56:59], v[0:7], v[162:169], v[56:59], v195, v194 op_sel_hi:[0,0,0]
	v_mfma_scale_f32_16x16x128_f8f6f4 v[52:55], v[8:15], v[170:177], v[52:55], v195, v194 op_sel_hi:[0,0,0]
	v_mfma_scale_f32_16x16x128_f8f6f4 v[48:51], v[0:7], v[170:177], v[48:51], v195, v194 op_sel_hi:[0,0,0]
	v_mfma_scale_f32_16x16x128_f8f6f4 v[44:47], v[8:15], v[178:185], v[44:47], v195, v194 op_sel_hi:[0,0,0]
	v_mfma_scale_f32_16x16x128_f8f6f4 v[40:43], v[0:7], v[178:185], v[40:43], v195, v194 op_sel_hi:[0,0,0]
	v_mfma_scale_f32_16x16x128_f8f6f4 v[36:39], v[8:15], v[198:205], v[36:39], v195, v194 op_sel_hi:[0,0,0]
	v_mfma_scale_f32_16x16x128_f8f6f4 v[32:35], v[0:7], v[198:205], v[32:35], v195, v194 op_sel_hi:[0,0,0]
	s_barrier
	ds_read_b128 v[24:27], v196
	ds_read_b128 v[28:31], v196 offset:1024
	ds_read_b128 v[16:19], v196 offset:2048
	ds_read_b128 v[20:23], v196 offset:3072
	ds_read_b128 v[8:11], v197
	ds_read_b128 v[12:15], v197 offset:1024
	ds_read_b128 v[0:3], v197 offset:2048
	ds_read_b128 v[4:7], v197 offset:3072
	ds_read_b128 v[162:165], v193 offset:32768
	ds_read_b128 v[166:169], v193 offset:33792
	ds_read_b128 v[170:173], v193 offset:34816
	ds_read_b128 v[174:177], v193 offset:35840
	ds_read_b128 v[178:181], v193 offset:36864
	ds_read_b128 v[182:185], v193 offset:37888
	ds_read_b128 v[198:201], v193 offset:38912
	ds_read_b128 v[202:205], v193 offset:39936
	s_add_u32 s44, s80, 0x100
	s_addc_u32 s45, s81, 0
	s_add_u32 s54, s83, 0x100
	s_mov_b32 m0, s61
	s_nop 0
	global_load_lds_dwordx4 v160, s[44:45]
	s_addc_u32 s55, s84, 0
	s_mov_b32 m0, s62
	s_nop 0
	global_load_lds_dwordx4 v160, s[54:55]
	s_waitcnt vmcnt(8)
	s_waitcnt lgkmcnt(0)
	s_barrier
	s_waitcnt lgkmcnt(6)
	v_mfma_scale_f32_16x16x128_f8f6f4 v[156:159], v[24:31], v[162:169], v[156:159], v195, v194 op_sel_hi:[0,0,0]
	v_mfma_scale_f32_16x16x128_f8f6f4 v[152:155], v[16:23], v[162:169], v[152:155], v195, v194 op_sel_hi:[0,0,0]
	s_waitcnt lgkmcnt(4)
	v_mfma_scale_f32_16x16x128_f8f6f4 v[148:151], v[24:31], v[170:177], v[148:151], v195, v194 op_sel_hi:[0,0,0]
	v_mfma_scale_f32_16x16x128_f8f6f4 v[144:147], v[16:23], v[170:177], v[144:147], v195, v194 op_sel_hi:[0,0,0]
	s_waitcnt lgkmcnt(2)
	v_mfma_scale_f32_16x16x128_f8f6f4 v[140:143], v[24:31], v[178:185], v[140:143], v195, v194 op_sel_hi:[0,0,0]
	v_mfma_scale_f32_16x16x128_f8f6f4 v[136:139], v[16:23], v[178:185], v[136:139], v195, v194 op_sel_hi:[0,0,0]
	s_waitcnt lgkmcnt(0)
	v_mfma_scale_f32_16x16x128_f8f6f4 v[132:135], v[24:31], v[198:205], v[132:135], v195, v194 op_sel_hi:[0,0,0]
	v_mfma_scale_f32_16x16x128_f8f6f4 v[128:131], v[16:23], v[198:205], v[128:131], v195, v194 op_sel_hi:[0,0,0]
	v_mfma_scale_f32_16x16x128_f8f6f4 v[124:127], v[8:15], v[162:169], v[124:127], v195, v194 op_sel_hi:[0,0,0]
	v_mfma_scale_f32_16x16x128_f8f6f4 v[120:123], v[0:7], v[162:169], v[120:123], v195, v194 op_sel_hi:[0,0,0]
	v_mfma_scale_f32_16x16x128_f8f6f4 v[116:119], v[8:15], v[170:177], v[116:119], v195, v194 op_sel_hi:[0,0,0]
	v_mfma_scale_f32_16x16x128_f8f6f4 v[112:115], v[0:7], v[170:177], v[112:115], v195, v194 op_sel_hi:[0,0,0]
	v_mfma_scale_f32_16x16x128_f8f6f4 v[108:111], v[8:15], v[178:185], v[108:111], v195, v194 op_sel_hi:[0,0,0]
	v_mfma_scale_f32_16x16x128_f8f6f4 v[104:107], v[0:7], v[178:185], v[104:107], v195, v194 op_sel_hi:[0,0,0]
	v_mfma_scale_f32_16x16x128_f8f6f4 v[100:103], v[8:15], v[198:205], v[100:103], v195, v194 op_sel_hi:[0,0,0]
	v_mfma_scale_f32_16x16x128_f8f6f4 v[96:99], v[0:7], v[198:205], v[96:99], v195, v194 op_sel_hi:[0,0,0]
	s_barrier
	s_add_u32 s44, s85, 0x180
	s_addc_u32 s45, s86, 0
	ds_read_b128 v[162:165], v193 offset:49152
	ds_read_b128 v[166:169], v193 offset:50176
	ds_read_b128 v[170:173], v193 offset:51200
	ds_read_b128 v[174:177], v193 offset:52224
	ds_read_b128 v[178:181], v193 offset:53248
	ds_read_b128 v[182:185], v193 offset:54272
	ds_read_b128 v[198:201], v193 offset:55296
	ds_read_b128 v[202:205], v193 offset:56320
	s_add_u32 s54, s87, 0x180
	s_mov_b32 m0, s63
	s_nop 0
	global_load_lds_dwordx4 v161, s[44:45]
	s_addc_u32 s55, s88, 0
	s_mov_b32 m0, s64
	s_nop 0
	global_load_lds_dwordx4 v161, s[54:55]
	s_add_u32 s44, s89, 0x180
	s_addc_u32 s45, s90, 0
	s_add_u32 s54, s93, 0x180
	s_mov_b32 m0, s67
	s_nop 0
	global_load_lds_dwordx4 v161, s[44:45]
	s_addc_u32 s55, s94, 0
	s_mov_b32 m0, s73
	s_nop 0
	global_load_lds_dwordx4 v161, s[54:55]
	s_add_u32 s44, s75, 0x180
	s_addc_u32 s45, s77, 0
	s_add_u32 s54, s91, 0x180
	s_mov_b32 m0, s65
	s_nop 0
	global_load_lds_dwordx4 v160, s[44:45]
	s_addc_u32 s55, s92, 0
	s_mov_b32 m0, s66
	s_nop 0
	global_load_lds_dwordx4 v160, s[54:55]
	s_waitcnt vmcnt(8)
	s_waitcnt lgkmcnt(0)
	s_barrier
	s_waitcnt lgkmcnt(6)
	v_mfma_scale_f32_16x16x128_f8f6f4 v[92:95], v[24:31], v[162:169], v[92:95], v195, v194 op_sel_hi:[0,0,0]
	v_mfma_scale_f32_16x16x128_f8f6f4 v[88:91], v[16:23], v[162:169], v[88:91], v195, v194 op_sel_hi:[0,0,0]
	s_waitcnt lgkmcnt(4)
	v_mfma_scale_f32_16x16x128_f8f6f4 v[84:87], v[24:31], v[170:177], v[84:87], v195, v194 op_sel_hi:[0,0,0]
	v_mfma_scale_f32_16x16x128_f8f6f4 v[80:83], v[16:23], v[170:177], v[80:83], v195, v194 op_sel_hi:[0,0,0]
	s_waitcnt lgkmcnt(2)
	v_mfma_scale_f32_16x16x128_f8f6f4 v[76:79], v[24:31], v[178:185], v[76:79], v195, v194 op_sel_hi:[0,0,0]
	v_mfma_scale_f32_16x16x128_f8f6f4 v[72:75], v[16:23], v[178:185], v[72:75], v195, v194 op_sel_hi:[0,0,0]
	s_waitcnt lgkmcnt(0)
	v_mfma_scale_f32_16x16x128_f8f6f4 v[68:71], v[24:31], v[198:205], v[68:71], v195, v194 op_sel_hi:[0,0,0]
	v_mfma_scale_f32_16x16x128_f8f6f4 v[64:67], v[16:23], v[198:205], v[64:67], v195, v194 op_sel_hi:[0,0,0]
	v_mfma_scale_f32_16x16x128_f8f6f4 v[60:63], v[8:15], v[162:169], v[60:63], v195, v194 op_sel_hi:[0,0,0]
	v_mfma_scale_f32_16x16x128_f8f6f4 v[56:59], v[0:7], v[162:169], v[56:59], v195, v194 op_sel_hi:[0,0,0]
	v_mfma_scale_f32_16x16x128_f8f6f4 v[52:55], v[8:15], v[170:177], v[52:55], v195, v194 op_sel_hi:[0,0,0]
	v_mfma_scale_f32_16x16x128_f8f6f4 v[48:51], v[0:7], v[170:177], v[48:51], v195, v194 op_sel_hi:[0,0,0]
	v_mfma_scale_f32_16x16x128_f8f6f4 v[44:47], v[8:15], v[178:185], v[44:47], v195, v194 op_sel_hi:[0,0,0]
	v_mfma_scale_f32_16x16x128_f8f6f4 v[40:43], v[0:7], v[178:185], v[40:43], v195, v194 op_sel_hi:[0,0,0]
	v_mfma_scale_f32_16x16x128_f8f6f4 v[36:39], v[8:15], v[198:205], v[36:39], v195, v194 op_sel_hi:[0,0,0]
	v_mfma_scale_f32_16x16x128_f8f6f4 v[32:35], v[0:7], v[198:205], v[32:35], v195, v194 op_sel_hi:[0,0,0]
	s_barrier
	s_add_u32 s42, s42, 0x100
	s_addc_u32 s43, s43, 0
	s_cmp_ge_i32 s74, s2
	s_cbranch_scc0 .LBB0_238

.LBB0_241:
	ds_read_b128 v[24:27], v191
	ds_read_b128 v[28:31], v191 offset:1024
	ds_read_b128 v[16:19], v191 offset:2048
	ds_read_b128 v[20:23], v191 offset:3072
	ds_read_b128 v[8:11], v192
	ds_read_b128 v[12:15], v192 offset:1024
	ds_read_b128 v[0:3], v192 offset:2048
	ds_read_b128 v[4:7], v192 offset:3072
	s_ashr_i32 s49, s18, 31
	s_mov_b32 s48, s18
	s_lshl_b64 s[48:49], s[48:49], 7
	s_add_u32 s2, s4, s48
	ds_read_b128 v[162:165], v193
	ds_read_b128 v[166:169], v193 offset:1024
	ds_read_b128 v[170:173], v193 offset:2048
	ds_read_b128 v[174:177], v193 offset:3072
	ds_read_b128 v[178:181], v193 offset:4096
	ds_read_b128 v[182:185], v193 offset:5120
	ds_read_b128 v[198:201], v193 offset:6144
	ds_read_b128 v[202:205], v193 offset:7168
	s_addc_u32 s4, s5, s49
	s_add_u32 s2, s2, s40
	s_addc_u32 s5, s4, s41
	s_add_u32 s4, s2, 0xffffff80
	s_addc_u32 s5, s5, -1
	s_add_u32 s38, s4, s38
	s_mov_b32 m0, s78
	s_nop 0
	global_load_lds_dwordx4 v160, s[4:5]
	s_addc_u32 s39, s5, s39
	s_mov_b32 m0, s79
	s_nop 0
	global_load_lds_dwordx4 v160, s[38:39]
	s_waitcnt vmcnt(8)
	s_waitcnt lgkmcnt(0)
	s_barrier
	s_waitcnt lgkmcnt(6)
	v_mfma_scale_f32_16x16x128_f8f6f4 v[156:159], v[24:31], v[162:169], v[156:159], v195, v194 op_sel_hi:[0,0,0]
	v_mfma_scale_f32_16x16x128_f8f6f4 v[152:155], v[16:23], v[162:169], v[152:155], v195, v194 op_sel_hi:[0,0,0]
	s_waitcnt lgkmcnt(4)
	v_mfma_scale_f32_16x16x128_f8f6f4 v[148:151], v[24:31], v[170:177], v[148:151], v195, v194 op_sel_hi:[0,0,0]
	v_mfma_scale_f32_16x16x128_f8f6f4 v[144:147], v[16:23], v[170:177], v[144:147], v195, v194 op_sel_hi:[0,0,0]
	s_waitcnt lgkmcnt(2)
	v_mfma_scale_f32_16x16x128_f8f6f4 v[140:143], v[24:31], v[178:185], v[140:143], v195, v194 op_sel_hi:[0,0,0]
	v_mfma_scale_f32_16x16x128_f8f6f4 v[136:139], v[16:23], v[178:185], v[136:139], v195, v194 op_sel_hi:[0,0,0]
	s_waitcnt lgkmcnt(0)
	v_mfma_scale_f32_16x16x128_f8f6f4 v[132:135], v[24:31], v[198:205], v[132:135], v195, v194 op_sel_hi:[0,0,0]
	v_mfma_scale_f32_16x16x128_f8f6f4 v[128:131], v[16:23], v[198:205], v[128:131], v195, v194 op_sel_hi:[0,0,0]
	v_mfma_scale_f32_16x16x128_f8f6f4 v[124:127], v[8:15], v[162:169], v[124:127], v195, v194 op_sel_hi:[0,0,0]
	v_mfma_scale_f32_16x16x128_f8f6f4 v[160:163], v[0:7], v[162:169], v[120:123], v195, v194 op_sel_hi:[0,0,0]
	v_mfma_scale_f32_16x16x128_f8f6f4 v[164:167], v[8:15], v[170:177], v[116:119], v195, v194 op_sel_hi:[0,0,0]
	v_mfma_scale_f32_16x16x128_f8f6f4 v[168:171], v[0:7], v[170:177], v[112:115], v195, v194 op_sel_hi:[0,0,0]
	v_mfma_scale_f32_16x16x128_f8f6f4 v[172:175], v[8:15], v[178:185], v[108:111], v195, v194 op_sel_hi:[0,0,0]
	v_mfma_scale_f32_16x16x128_f8f6f4 v[176:179], v[0:7], v[178:185], v[104:107], v195, v194 op_sel_hi:[0,0,0]
	v_mfma_scale_f32_16x16x128_f8f6f4 v[180:183], v[8:15], v[198:205], v[100:103], v195, v194 op_sel_hi:[0,0,0]
	v_mfma_scale_f32_16x16x128_f8f6f4 v[184:187], v[0:7], v[198:205], v[96:99], v195, v194 op_sel_hi:[0,0,0]
	s_barrier
	s_add_u32 s38, s6, s16
	s_nop 3
	ds_read_b128 v[96:99], v193 offset:16384
	ds_read_b128 v[100:103], v193 offset:17408
	ds_read_b128 v[104:107], v193 offset:18432
	ds_read_b128 v[108:111], v193 offset:19456
	ds_read_b128 v[112:115], v193 offset:20480
	ds_read_b128 v[116:119], v193 offset:21504
	ds_read_b128 v[198:201], v193 offset:22528
	ds_read_b128 v[202:205], v193 offset:23552
	s_addc_u32 s39, s7, s17
	s_mov_b32 m0, s51
	s_nop 0
	global_load_lds_dwordx4 v189, s[6:7]
	s_add_u32 s40, s6, s22
	s_mov_b32 m0, s57
	s_nop 0
	global_load_lds_dwordx4 v189, s[38:39]
	s_addc_u32 s41, s7, s23
	s_add_u32 s48, s40, s16
	s_mov_b32 m0, s58
	s_nop 0
	global_load_lds_dwordx4 v189, s[40:41]
	s_addc_u32 s49, s41, s17
	s_mov_b32 m0, s59
	s_nop 0
	global_load_lds_dwordx4 v189, s[48:49]
	s_add_u32 s4, s46, s44
	s_mov_b32 m0, s53
	s_nop 0
	global_load_lds_dwordx4 v188, s[46:47]
	s_addc_u32 s5, s47, s45
	s_mov_b32 m0, s60
	s_nop 0
	global_load_lds_dwordx4 v188, s[4:5]
	s_waitcnt vmcnt(8)
	s_waitcnt lgkmcnt(0)
	s_barrier
	s_waitcnt lgkmcnt(6)
	v_mfma_scale_f32_16x16x128_f8f6f4 v[92:95], v[24:31], v[96:103], v[92:95], v195, v194 op_sel_hi:[0,0,0]
	v_mfma_scale_f32_16x16x128_f8f6f4 v[88:91], v[16:23], v[96:103], v[88:91], v195, v194 op_sel_hi:[0,0,0]
	s_waitcnt lgkmcnt(4)
	v_mfma_scale_f32_16x16x128_f8f6f4 v[84:87], v[24:31], v[104:111], v[84:87], v195, v194 op_sel_hi:[0,0,0]
	v_mfma_scale_f32_16x16x128_f8f6f4 v[80:83], v[16:23], v[104:111], v[80:83], v195, v194 op_sel_hi:[0,0,0]
	s_waitcnt lgkmcnt(2)
	v_mfma_scale_f32_16x16x128_f8f6f4 v[76:79], v[24:31], v[112:119], v[76:79], v195, v194 op_sel_hi:[0,0,0]
	v_mfma_scale_f32_16x16x128_f8f6f4 v[72:75], v[16:23], v[112:119], v[72:75], v195, v194 op_sel_hi:[0,0,0]
	s_waitcnt lgkmcnt(0)
	v_mfma_scale_f32_16x16x128_f8f6f4 v[68:71], v[24:31], v[198:205], v[68:71], v195, v194 op_sel_hi:[0,0,0]
	v_mfma_scale_f32_16x16x128_f8f6f4 v[64:67], v[16:23], v[198:205], v[64:67], v195, v194 op_sel_hi:[0,0,0]
	v_mfma_scale_f32_16x16x128_f8f6f4 v[60:63], v[8:15], v[96:103], v[60:63], v195, v194 op_sel_hi:[0,0,0]
	v_mfma_scale_f32_16x16x128_f8f6f4 v[96:99], v[0:7], v[96:103], v[56:59], v195, v194 op_sel_hi:[0,0,0]
	v_mfma_scale_f32_16x16x128_f8f6f4 v[100:103], v[8:15], v[104:111], v[52:55], v195, v194 op_sel_hi:[0,0,0]
	v_mfma_scale_f32_16x16x128_f8f6f4 v[104:107], v[0:7], v[104:111], v[48:51], v195, v194 op_sel_hi:[0,0,0]
	v_mfma_scale_f32_16x16x128_f8f6f4 v[108:111], v[8:15], v[112:119], v[44:47], v195, v194 op_sel_hi:[0,0,0]
	v_mfma_scale_f32_16x16x128_f8f6f4 v[112:115], v[0:7], v[112:119], v[40:43], v195, v194 op_sel_hi:[0,0,0]
	v_mfma_scale_f32_16x16x128_f8f6f4 v[116:119], v[8:15], v[198:205], v[36:39], v195, v194 op_sel_hi:[0,0,0]
	v_mfma_scale_f32_16x16x128_f8f6f4 v[120:123], v[0:7], v[198:205], v[32:35], v195, v194 op_sel_hi:[0,0,0]
	s_barrier
	ds_read_b128 v[24:27], v196
	ds_read_b128 v[28:31], v196 offset:1024
	ds_read_b128 v[16:19], v196 offset:2048
	ds_read_b128 v[20:23], v196 offset:3072
	ds_read_b128 v[8:11], v197
	ds_read_b128 v[12:15], v197 offset:1024
	ds_read_b128 v[0:3], v197 offset:2048
	ds_read_b128 v[4:7], v197 offset:3072
	ds_read_b128 v[48:51], v193 offset:32768
	ds_read_b128 v[52:55], v193 offset:33792
	ds_read_b128 v[198:201], v193 offset:34816
	ds_read_b128 v[202:205], v193 offset:35840
	ds_read_b128 v[206:209], v193 offset:36864
	ds_read_b128 v[210:213], v193 offset:37888
	ds_read_b128 v[214:217], v193 offset:38912
	ds_read_b128 v[218:221], v193 offset:39936
	s_add_u32 s54, s46, s42
	s_addc_u32 s55, s47, s43
	s_add_u32 s68, s54, s44
	s_mov_b32 m0, s61
	s_nop 0
	global_load_lds_dwordx4 v188, s[54:55]
	s_addc_u32 s69, s55, s45
	s_mov_b32 m0, s62
	s_nop 0
	global_load_lds_dwordx4 v188, s[68:69]
	s_waitcnt vmcnt(8)
	s_waitcnt lgkmcnt(0)
	s_barrier
	s_waitcnt lgkmcnt(6)
	v_mfma_scale_f32_16x16x128_f8f6f4 v[156:159], v[24:31], v[48:55], v[156:159], v195, v194 op_sel_hi:[0,0,0]
	v_mfma_scale_f32_16x16x128_f8f6f4 v[152:155], v[16:23], v[48:55], v[152:155], v195, v194 op_sel_hi:[0,0,0]
	s_waitcnt lgkmcnt(4)
	v_mfma_scale_f32_16x16x128_f8f6f4 v[148:151], v[24:31], v[198:205], v[148:151], v195, v194 op_sel_hi:[0,0,0]
	v_mfma_scale_f32_16x16x128_f8f6f4 v[144:147], v[16:23], v[198:205], v[144:147], v195, v194 op_sel_hi:[0,0,0]
	s_waitcnt lgkmcnt(2)
	v_mfma_scale_f32_16x16x128_f8f6f4 v[44:47], v[24:31], v[206:213], v[140:143], v195, v194 op_sel_hi:[0,0,0]
	v_mfma_scale_f32_16x16x128_f8f6f4 v[40:43], v[16:23], v[206:213], v[136:139], v195, v194 op_sel_hi:[0,0,0]
	s_waitcnt lgkmcnt(0)
	v_mfma_scale_f32_16x16x128_f8f6f4 v[32:35], v[24:31], v[214:221], v[132:135], v195, v194 op_sel_hi:[0,0,0]
	v_mfma_scale_f32_16x16x128_f8f6f4 v[36:39], v[16:23], v[214:221], v[128:131], v195, v194 op_sel_hi:[0,0,0]
	v_mfma_scale_f32_16x16x128_f8f6f4 v[140:143], v[8:15], v[48:55], v[124:127], v195, v194 op_sel_hi:[0,0,0]
	v_mfma_scale_f32_16x16x128_f8f6f4 v[160:163], v[0:7], v[48:55], v[160:163], v195, v194 op_sel_hi:[0,0,0]
	v_mfma_scale_f32_16x16x128_f8f6f4 v[136:139], v[8:15], v[198:205], v[164:167], v195, v194 op_sel_hi:[0,0,0]
	v_mfma_scale_f32_16x16x128_f8f6f4 v[132:135], v[0:7], v[198:205], v[168:171], v195, v194 op_sel_hi:[0,0,0]
	v_mfma_scale_f32_16x16x128_f8f6f4 v[128:131], v[8:15], v[206:213], v[172:175], v195, v194 op_sel_hi:[0,0,0]
	v_mfma_scale_f32_16x16x128_f8f6f4 v[124:127], v[0:7], v[206:213], v[176:179], v195, v194 op_sel_hi:[0,0,0]
	v_mfma_scale_f32_16x16x128_f8f6f4 v[48:51], v[8:15], v[214:221], v[180:183], v195, v194 op_sel_hi:[0,0,0]
	v_mfma_scale_f32_16x16x128_f8f6f4 v[52:55], v[0:7], v[214:221], v[184:187], v195, v194 op_sel_hi:[0,0,0]
	s_barrier
	s_add_u32 s54, s6, 0x80
	s_addc_u32 s55, s7, 0
	s_add_u32 s38, s38, 0x80
	ds_read_b128 v[164:167], v193 offset:49152
	ds_read_b128 v[168:171], v193 offset:50176
	ds_read_b128 v[172:175], v193 offset:51200
	ds_read_b128 v[176:179], v193 offset:52224
	ds_read_b128 v[180:183], v193 offset:53248
	ds_read_b128 v[184:187], v193 offset:54272
	ds_read_b128 v[198:201], v193 offset:55296
	ds_read_b128 v[202:205], v193 offset:56320
	s_addc_u32 s39, s39, 0
	s_mov_b32 m0, s63
	s_nop 0
	global_load_lds_dwordx4 v189, s[54:55]
	s_nop 0
	s_mov_b32 m0, s64
	s_nop 0
	global_load_lds_dwordx4 v189, s[38:39]
	s_add_u32 s38, s40, 0x80
	s_addc_u32 s39, s41, 0
	s_add_u32 s40, s48, 0x80
	s_addc_u32 s41, s49, 0
	s_mov_b32 m0, s67
	s_nop 0
	global_load_lds_dwordx4 v189, s[38:39]
	s_add_u32 s38, s46, 0x80
	s_mov_b32 m0, s73
	s_nop 0
	global_load_lds_dwordx4 v189, s[40:41]
	s_addc_u32 s39, s47, 0
	s_add_u32 s4, s4, 0x80
	s_mov_b32 m0, s65
	s_nop 0
	global_load_lds_dwordx4 v188, s[38:39]
	s_addc_u32 s5, s5, 0
	s_mov_b32 m0, s66
	s_nop 0
	global_load_lds_dwordx4 v188, s[4:5]
	s_waitcnt vmcnt(8)
	s_waitcnt lgkmcnt(0)
	s_barrier
	s_waitcnt lgkmcnt(6)
	v_mfma_scale_f32_16x16x128_f8f6f4 v[92:95], v[24:31], v[164:171], v[92:95], v195, v194 op_sel_hi:[0,0,0]
	v_mfma_scale_f32_16x16x128_f8f6f4 v[88:91], v[16:23], v[164:171], v[88:91], v195, v194 op_sel_hi:[0,0,0]
	s_waitcnt lgkmcnt(4)
	v_mfma_scale_f32_16x16x128_f8f6f4 v[84:87], v[24:31], v[172:179], v[84:87], v195, v194 op_sel_hi:[0,0,0]
	v_mfma_scale_f32_16x16x128_f8f6f4 v[80:83], v[16:23], v[172:179], v[80:83], v195, v194 op_sel_hi:[0,0,0]
	s_waitcnt lgkmcnt(2)
	v_mfma_scale_f32_16x16x128_f8f6f4 v[76:79], v[24:31], v[180:187], v[76:79], v195, v194 op_sel_hi:[0,0,0]
	v_mfma_scale_f32_16x16x128_f8f6f4 v[56:59], v[16:23], v[180:187], v[72:75], v195, v194 op_sel_hi:[0,0,0]
	s_waitcnt lgkmcnt(0)
	v_mfma_scale_f32_16x16x128_f8f6f4 v[24:27], v[24:31], v[198:205], v[68:71], v195, v194 op_sel_hi:[0,0,0]
	v_mfma_scale_f32_16x16x128_f8f6f4 v[16:19], v[16:23], v[198:205], v[64:67], v195, v194 op_sel_hi:[0,0,0]
	v_mfma_scale_f32_16x16x128_f8f6f4 v[72:75], v[8:15], v[164:171], v[60:63], v195, v194 op_sel_hi:[0,0,0]
	v_mfma_scale_f32_16x16x128_f8f6f4 v[68:71], v[0:7], v[164:171], v[96:99], v195, v194 op_sel_hi:[0,0,0]
	v_mfma_scale_f32_16x16x128_f8f6f4 v[64:67], v[8:15], v[172:179], v[100:103], v195, v194 op_sel_hi:[0,0,0]
	v_mfma_scale_f32_16x16x128_f8f6f4 v[60:63], v[0:7], v[172:179], v[104:107], v195, v194 op_sel_hi:[0,0,0]
	v_mfma_scale_f32_16x16x128_f8f6f4 v[28:31], v[8:15], v[180:187], v[108:111], v195, v194 op_sel_hi:[0,0,0]
	v_mfma_scale_f32_16x16x128_f8f6f4 v[20:23], v[0:7], v[180:187], v[112:115], v195, v194 op_sel_hi:[0,0,0]
	v_mfma_scale_f32_16x16x128_f8f6f4 v[8:11], v[8:15], v[198:205], v[116:119], v195, v194 op_sel_hi:[0,0,0]
	v_mfma_scale_f32_16x16x128_f8f6f4 v[0:3], v[0:7], v[198:205], v[120:123], v195, v194 op_sel_hi:[0,0,0]
	s_barrier
	s_andn2_b64 vcc, exec, s[24:25]
	s_cbranch_vccnz .LBB0_243
	s_barrier

.LBB0_250:
	v_and_b32_e32 v1, 15, v2
	v_or_b32_e32 v3, s3, v1
	s_lshl_b64 s[24:25], s[14:15], 7
	v_lshlrev_b32_e32 v5, 6, v3
	v_and_b32_e32 v6, 48, v2
	s_movk_i32 s14, 0x3c0
	s_lshl_b64 s[40:41], s[16:17], 7
	v_ashrrev_i32_e32 v4, 6, v2
	v_and_or_b32 v5, v5, s14, v6
	v_readlane_b32 s14, v254, 55
	v_lshl_add_u32 v7, v4, 10, s95
	s_mov_b32 s98, 0
	s_cselect_b32 s99, 1, 0
	s_cmp_lt_u32 s76, 4
	s_cbranch_scc0 .Lsprio_1
	s_setprio 1
.Lsprio_1:
	s_cmp_lg_u32 s99, 0
	s_waitcnt vmcnt(2)
	s_barrier
	v_add_lshl_u32 v4, v4, s14, 10
	s_add_u32 s14, s6, 0x80
	s_addc_u32 s15, s7, 0
	s_sub_u32 s16, 0, s18
	s_subb_u32 s26, 0, s19
	s_add_u32 s16, s8, s16
	s_addc_u32 s27, s9, s26
	s_add_u32 s26, s16, 0x80
	s_addc_u32 s27, s27, 0
	s_add_i32 s61, s53, 0x18000
	s_mov_b32 m0, s61
	s_nop 0
	global_load_lds_dwordx4 v0, s[14:15]
	s_add_i32 s62, s53, 0x1a000
	s_mov_b32 m0, s62
	s_nop 0
	global_load_lds_dwordx4 v0, s[26:27]
	s_add_u32 s14, s4, 0x80
	s_addc_u32 s15, s5, 0
	s_sub_u32 s16, 0, s38
	s_subb_u32 s26, 0, s39
	s_add_u32 s12, s12, s16
	s_addc_u32 s13, s13, s26
	s_add_u32 s12, s12, 0x80
	s_addc_u32 s13, s13, 0
	s_add_i32 s63, s53, 0x8000
	s_add_i32 s64, s53, 0xa000
	s_add_u32 s8, s8, 0x80
	s_mov_b32 m0, s63
	s_nop 0
	global_load_lds_dwordx4 v128, s[14:15]
	s_addc_u32 s9, s9, 0
	s_mov_b32 m0, s64
	s_nop 0
	global_load_lds_dwordx4 v128, s[12:13]
	s_add_u32 s10, s10, 0x80
	v_lshlrev_b32_e32 v2, 2, v2
	s_addc_u32 s11, s11, 0
	s_add_i32 s65, s53, 0x1c000
	s_mov_b32 m0, s65
	s_nop 0
	global_load_lds_dwordx4 v0, s[8:9]
	v_lshlrev_b32_e32 v3, 2, v3
	v_lshl_or_b32 v1, v1, 6, v6
	v_and_b32_e32 v2, 32, v2
	s_add_i32 s66, s53, 0x1e000
	s_mov_b32 m0, s66
	s_nop 0
	global_load_lds_dwordx4 v0, s[10:11]
	v_and_b32_e32 v3, 32, v3
	v_bitop3_b32 v1, v1, v4, v2 bitop3:0xde
	s_waitcnt vmcnt(6)
	s_add_i32 s67, s53, 0xc000
	s_add_i32 s68, s53, 0xe000
	v_readlane_b32 s8, v254, 0
	v_mov_b32_e32 v129, v0
	v_bitop3_b32 v3, v5, v7, v3 bitop3:0xde
	s_cmpk_lt_u32 s8, 0x100
	v_add_u32_e32 v0, 0, v1
	s_cselect_b64 s[26:27], -1, 0
	v_add_u32_e32 v135, 0x10000, v0
	v_add_u32_e32 v136, 0x14000, v0
	v_add_u32_e32 v137, 0, v3
	v_add_u32_e32 v138, 0x18000, v0
	v_add_u32_e32 v139, 0x1c000, v0
	s_mov_b32 s69, s17
	s_barrier
	s_branch .LBB0_253

.LBB0_255:
	s_cmp_lt_i32 s20, 3
	s_cbranch_scc1 .Lhz_257
	s_add_i32 s16, s20, -2
	s_add_u32 s31, s4, s40
	s_addc_u32 s46, s5, s41
	s_add_u32 s47, s6, s24
	s_addc_u32 s48, s7, s25
	s_add_u32 s42, s18, s24
	s_addc_u32 s43, s19, s25
	s_add_u32 s49, s6, s42
	s_addc_u32 s70, s7, s43
	s_add_u32 s71, s6, s18
	s_addc_u32 s72, s7, s19
	s_add_u32 s42, s38, s40
	s_addc_u32 s43, s39, s41
	s_add_u32 s73, s4, s42
	s_addc_u32 s74, s5, s43
	s_add_u32 s75, s4, s38
	s_addc_u32 s77, s5, s39
	s_mov_b32 s78, 0
	s_mov_b64 s[42:43], 0
	s_cmp_eq_u32 s98, 0
	s_cbranch_scc1 .Lhf_257
	ds_read_b128 v[130:133], v135
	ds_read_b128 v[140:143], v135 offset:1024
	ds_read_b128 v[144:147], v135 offset:2048
	ds_read_b128 v[148:151], v135 offset:3072
	ds_read_b128 v[152:155], v136
	ds_read_b128 v[156:159], v136 offset:1024
	ds_read_b128 v[160:163], v136 offset:2048
	ds_read_b128 v[164:167], v136 offset:3072
	s_add_i32 s78, s78, 2
	s_add_u32 s79, s4, s42
	s_addc_u32 s80, s5, s43
	s_add_u32 s44, s79, 0x100
	s_addc_u32 s45, s80, 0
	s_add_u32 s81, s31, s42
	ds_read_b128 v[168:171], v137
	ds_read_b128 v[172:175], v137 offset:1024
	ds_read_b128 v[176:179], v137 offset:2048
	ds_read_b128 v[180:183], v137 offset:3072
	ds_read_b128 v[184:187], v137 offset:4096
	ds_read_b128 v[188:191], v137 offset:5120
	ds_read_b128 v[192:195], v137 offset:6144
	ds_read_b128 v[196:199], v137 offset:7168
	s_addc_u32 s84, s46, s43
	s_add_u32 s54, s81, 0x80
	s_addc_u32 s55, s84, 0
	s_add_u32 s85, s73, s42
	s_addc_u32 s86, s74, s43
	s_add_u32 s82, s85, 0x80
	s_mov_b32 m0, s67
	s_nop 0
	global_load_lds_dwordx4 v128, s[54:55]
	s_addc_u32 s83, s86, 0
	s_mov_b32 m0, s68
	s_nop 0
	global_load_lds_dwordx4 v128, s[82:83]
	s_waitcnt vmcnt(24)
	s_waitcnt lgkmcnt(0)
	s_barrier
	s_waitcnt lgkmcnt(7)
	v_mfma_f32_16x16x32_bf16 v[124:127], v[130:133], v[168:171], 0
	v_mfma_f32_16x16x32_bf16 v[120:123], v[144:147], v[168:171], 0
	s_waitcnt lgkmcnt(5)
	v_mfma_f32_16x16x32_bf16 v[116:119], v[130:133], v[176:179], 0
	v_mfma_f32_16x16x32_bf16 v[112:115], v[144:147], v[176:179], 0
	s_waitcnt lgkmcnt(3)
	v_mfma_f32_16x16x32_bf16 v[108:111], v[130:133], v[184:187], 0
	v_mfma_f32_16x16x32_bf16 v[104:107], v[144:147], v[184:187], 0
	s_waitcnt lgkmcnt(1)
	v_mfma_f32_16x16x32_bf16 v[100:103], v[130:133], v[192:195], 0
	v_mfma_f32_16x16x32_bf16 v[96:99], v[144:147], v[192:195], 0
	v_mfma_f32_16x16x32_bf16 v[124:127], v[140:143], v[172:175], v[124:127]
	v_mfma_f32_16x16x32_bf16 v[120:123], v[148:151], v[172:175], v[120:123]
	v_mfma_f32_16x16x32_bf16 v[116:119], v[140:143], v[180:183], v[116:119]
	v_mfma_f32_16x16x32_bf16 v[112:115], v[148:151], v[180:183], v[112:115]
	v_mfma_f32_16x16x32_bf16 v[108:111], v[140:143], v[188:191], v[108:111]
	v_mfma_f32_16x16x32_bf16 v[104:107], v[148:151], v[188:191], v[104:107]
	s_waitcnt lgkmcnt(0)
	v_mfma_f32_16x16x32_bf16 v[100:103], v[140:143], v[196:199], v[100:103]
	v_mfma_f32_16x16x32_bf16 v[96:99], v[148:151], v[196:199], v[96:99]
	v_mfma_f32_16x16x32_bf16 v[92:95], v[152:155], v[168:171], 0
	v_mfma_f32_16x16x32_bf16 v[88:91], v[160:163], v[168:171], 0
	v_mfma_f32_16x16x32_bf16 v[84:87], v[152:155], v[176:179], 0
	v_mfma_f32_16x16x32_bf16 v[80:83], v[160:163], v[176:179], 0
	v_mfma_f32_16x16x32_bf16 v[76:79], v[152:155], v[184:187], 0
	v_mfma_f32_16x16x32_bf16 v[72:75], v[160:163], v[184:187], 0
	v_mfma_f32_16x16x32_bf16 v[68:71], v[152:155], v[192:195], 0
	v_mfma_f32_16x16x32_bf16 v[64:67], v[160:163], v[192:195], 0
	v_mfma_f32_16x16x32_bf16 v[92:95], v[156:159], v[172:175], v[92:95]
	v_mfma_f32_16x16x32_bf16 v[88:91], v[164:167], v[172:175], v[88:91]
	v_mfma_f32_16x16x32_bf16 v[84:87], v[156:159], v[180:183], v[84:87]
	v_mfma_f32_16x16x32_bf16 v[80:83], v[164:167], v[180:183], v[80:83]
	v_mfma_f32_16x16x32_bf16 v[76:79], v[156:159], v[188:191], v[76:79]
	v_mfma_f32_16x16x32_bf16 v[72:75], v[164:167], v[188:191], v[72:75]
	v_mfma_f32_16x16x32_bf16 v[68:71], v[156:159], v[196:199], v[68:71]
	v_mfma_f32_16x16x32_bf16 v[64:67], v[164:167], v[196:199], v[64:67]
	s_barrier
	s_add_u32 s87, s6, s42
	s_addc_u32 s88, s7, s43
	s_add_u32 s54, s87, 0x100
	s_addc_u32 s55, s88, 0
	s_add_u32 s89, s71, s42
	s_addc_u32 s90, s72, s43
	s_add_u32 s82, s89, 0x100
	ds_read_b128 v[168:171], v137 offset:16384
	ds_read_b128 v[172:175], v137 offset:17408
	ds_read_b128 v[176:179], v137 offset:18432
	ds_read_b128 v[180:183], v137 offset:19456
	ds_read_b128 v[184:187], v137 offset:20480
	ds_read_b128 v[188:191], v137 offset:21504
	ds_read_b128 v[192:195], v137 offset:22528
	ds_read_b128 v[196:199], v137 offset:23552
	s_addc_u32 s83, s90, 0
	s_mov_b32 m0, s51
	s_nop 0
	global_load_lds_dwordx4 v129, s[54:55]
	s_add_u32 s91, s47, s42
	s_mov_b32 m0, s57
	s_nop 0
	global_load_lds_dwordx4 v129, s[82:83]
	s_addc_u32 s92, s48, s43
	s_add_u32 s54, s91, 0x100
	s_addc_u32 s55, s92, 0
	s_add_u32 s93, s49, s42
	s_addc_u32 s94, s70, s43
	s_add_u32 s82, s93, 0x100
	s_addc_u32 s83, s94, 0
	s_mov_b32 m0, s58
	s_nop 0
	global_load_lds_dwordx4 v129, s[54:55]
	s_mov_b32 m0, s59
	s_nop 0
	global_load_lds_dwordx4 v129, s[82:83]
	s_add_u32 s82, s75, s42
	s_addc_u32 s83, s77, s43
	s_add_u32 s54, s82, 0x100
	s_mov_b32 m0, s53
	s_nop 0
	global_load_lds_dwordx4 v128, s[44:45]
	s_addc_u32 s55, s83, 0
	s_mov_b32 m0, s2
	s_nop 0
	global_load_lds_dwordx4 v128, s[54:55]
	s_waitcnt vmcnt(24)
	s_waitcnt lgkmcnt(0)
	s_barrier
	s_waitcnt lgkmcnt(7)
	v_mfma_f32_16x16x32_bf16 v[60:63], v[130:133], v[168:171], 0
	v_mfma_f32_16x16x32_bf16 v[56:59], v[144:147], v[168:171], 0
	s_waitcnt lgkmcnt(5)
	v_mfma_f32_16x16x32_bf16 v[52:55], v[130:133], v[176:179], 0
	v_mfma_f32_16x16x32_bf16 v[48:51], v[144:147], v[176:179], 0
	s_waitcnt lgkmcnt(3)
	v_mfma_f32_16x16x32_bf16 v[44:47], v[130:133], v[184:187], 0
	v_mfma_f32_16x16x32_bf16 v[40:43], v[144:147], v[184:187], 0
	s_waitcnt lgkmcnt(1)
	v_mfma_f32_16x16x32_bf16 v[36:39], v[130:133], v[192:195], 0
	v_mfma_f32_16x16x32_bf16 v[32:35], v[144:147], v[192:195], 0
	v_mfma_f32_16x16x32_bf16 v[60:63], v[140:143], v[172:175], v[60:63]
	v_mfma_f32_16x16x32_bf16 v[56:59], v[148:151], v[172:175], v[56:59]
	v_mfma_f32_16x16x32_bf16 v[52:55], v[140:143], v[180:183], v[52:55]
	v_mfma_f32_16x16x32_bf16 v[48:51], v[148:151], v[180:183], v[48:51]
	v_mfma_f32_16x16x32_bf16 v[44:47], v[140:143], v[188:191], v[44:47]
	v_mfma_f32_16x16x32_bf16 v[40:43], v[148:151], v[188:191], v[40:43]
	s_waitcnt lgkmcnt(0)
	v_mfma_f32_16x16x32_bf16 v[36:39], v[140:143], v[196:199], v[36:39]
	v_mfma_f32_16x16x32_bf16 v[32:35], v[148:151], v[196:199], v[32:35]
	v_mfma_f32_16x16x32_bf16 v[28:31], v[152:155], v[168:171], 0
	v_mfma_f32_16x16x32_bf16 v[24:27], v[160:163], v[168:171], 0
	v_mfma_f32_16x16x32_bf16 v[20:23], v[152:155], v[176:179], 0
	v_mfma_f32_16x16x32_bf16 v[16:19], v[160:163], v[176:179], 0
	v_mfma_f32_16x16x32_bf16 v[12:15], v[152:155], v[184:187], 0
	v_mfma_f32_16x16x32_bf16 v[8:11], v[160:163], v[184:187], 0
	v_mfma_f32_16x16x32_bf16 v[4:7], v[152:155], v[192:195], 0
	v_mfma_f32_16x16x32_bf16 v[0:3], v[160:163], v[192:195], 0
	v_mfma_f32_16x16x32_bf16 v[28:31], v[156:159], v[172:175], v[28:31]
	v_mfma_f32_16x16x32_bf16 v[24:27], v[164:167], v[172:175], v[24:27]
	v_mfma_f32_16x16x32_bf16 v[20:23], v[156:159], v[180:183], v[20:23]
	v_mfma_f32_16x16x32_bf16 v[16:19], v[164:167], v[180:183], v[16:19]
	v_mfma_f32_16x16x32_bf16 v[12:15], v[156:159], v[188:191], v[12:15]
	v_mfma_f32_16x16x32_bf16 v[8:11], v[164:167], v[188:191], v[8:11]
	v_mfma_f32_16x16x32_bf16 v[4:7], v[156:159], v[196:199], v[4:7]
	v_mfma_f32_16x16x32_bf16 v[0:3], v[164:167], v[196:199], v[0:3]
	s_barrier
	ds_read_b128 v[130:133], v138
	ds_read_b128 v[140:143], v138 offset:1024
	ds_read_b128 v[144:147], v138 offset:2048
	ds_read_b128 v[148:151], v138 offset:3072
	ds_read_b128 v[152:155], v139
	ds_read_b128 v[156:159], v139 offset:1024
	ds_read_b128 v[160:163], v139 offset:2048
	ds_read_b128 v[164:167], v139 offset:3072
	ds_read_b128 v[168:171], v137 offset:32768
	ds_read_b128 v[172:175], v137 offset:33792
	ds_read_b128 v[176:179], v137 offset:34816
	ds_read_b128 v[180:183], v137 offset:35840
	ds_read_b128 v[184:187], v137 offset:36864
	ds_read_b128 v[188:191], v137 offset:37888
	ds_read_b128 v[192:195], v137 offset:38912
	ds_read_b128 v[196:199], v137 offset:39936
	s_add_u32 s44, s81, 0x100
	s_addc_u32 s45, s84, 0
	s_add_u32 s54, s85, 0x100
	s_mov_b32 m0, s33
	s_nop 0
	global_load_lds_dwordx4 v128, s[44:45]
	s_addc_u32 s55, s86, 0
	s_mov_b32 m0, s60
	s_nop 0
	global_load_lds_dwordx4 v128, s[54:55]
	s_waitcnt vmcnt(8)
	s_waitcnt lgkmcnt(0)
	s_barrier
	s_waitcnt lgkmcnt(7)
	v_mfma_f32_16x16x32_bf16 v[124:127], v[130:133], v[168:171], v[124:127]
	v_mfma_f32_16x16x32_bf16 v[120:123], v[144:147], v[168:171], v[120:123]
	s_waitcnt lgkmcnt(5)
	v_mfma_f32_16x16x32_bf16 v[116:119], v[130:133], v[176:179], v[116:119]
	v_mfma_f32_16x16x32_bf16 v[112:115], v[144:147], v[176:179], v[112:115]
	s_waitcnt lgkmcnt(3)
	v_mfma_f32_16x16x32_bf16 v[108:111], v[130:133], v[184:187], v[108:111]
	v_mfma_f32_16x16x32_bf16 v[104:107], v[144:147], v[184:187], v[104:107]
	s_waitcnt lgkmcnt(1)
	v_mfma_f32_16x16x32_bf16 v[100:103], v[130:133], v[192:195], v[100:103]
	v_mfma_f32_16x16x32_bf16 v[96:99], v[144:147], v[192:195], v[96:99]
	v_mfma_f32_16x16x32_bf16 v[124:127], v[140:143], v[172:175], v[124:127]
	v_mfma_f32_16x16x32_bf16 v[120:123], v[148:151], v[172:175], v[120:123]
	v_mfma_f32_16x16x32_bf16 v[116:119], v[140:143], v[180:183], v[116:119]
	v_mfma_f32_16x16x32_bf16 v[112:115], v[148:151], v[180:183], v[112:115]
	v_mfma_f32_16x16x32_bf16 v[108:111], v[140:143], v[188:191], v[108:111]
	v_mfma_f32_16x16x32_bf16 v[104:107], v[148:151], v[188:191], v[104:107]
	s_waitcnt lgkmcnt(0)
	v_mfma_f32_16x16x32_bf16 v[100:103], v[140:143], v[196:199], v[100:103]
	v_mfma_f32_16x16x32_bf16 v[96:99], v[148:151], v[196:199], v[96:99]
	v_mfma_f32_16x16x32_bf16 v[92:95], v[152:155], v[168:171], v[92:95]
	v_mfma_f32_16x16x32_bf16 v[88:91], v[160:163], v[168:171], v[88:91]
	v_mfma_f32_16x16x32_bf16 v[84:87], v[152:155], v[176:179], v[84:87]
	v_mfma_f32_16x16x32_bf16 v[80:83], v[160:163], v[176:179], v[80:83]
	v_mfma_f32_16x16x32_bf16 v[76:79], v[152:155], v[184:187], v[76:79]
	v_mfma_f32_16x16x32_bf16 v[72:75], v[160:163], v[184:187], v[72:75]
	v_mfma_f32_16x16x32_bf16 v[68:71], v[152:155], v[192:195], v[68:71]
	v_mfma_f32_16x16x32_bf16 v[64:67], v[160:163], v[192:195], v[64:67]
	v_mfma_f32_16x16x32_bf16 v[92:95], v[156:159], v[172:175], v[92:95]
	v_mfma_f32_16x16x32_bf16 v[88:91], v[164:167], v[172:175], v[88:91]
	v_mfma_f32_16x16x32_bf16 v[84:87], v[156:159], v[180:183], v[84:87]
	v_mfma_f32_16x16x32_bf16 v[80:83], v[164:167], v[180:183], v[80:83]
	v_mfma_f32_16x16x32_bf16 v[76:79], v[156:159], v[188:191], v[76:79]
	v_mfma_f32_16x16x32_bf16 v[72:75], v[164:167], v[188:191], v[72:75]
	v_mfma_f32_16x16x32_bf16 v[68:71], v[156:159], v[196:199], v[68:71]
	v_mfma_f32_16x16x32_bf16 v[64:67], v[164:167], v[196:199], v[64:67]
	s_barrier
	s_add_u32 s44, s87, 0x180
	s_addc_u32 s45, s88, 0
	ds_read_b128 v[168:171], v137 offset:49152
	ds_read_b128 v[172:175], v137 offset:50176
	ds_read_b128 v[176:179], v137 offset:51200
	ds_read_b128 v[180:183], v137 offset:52224
	ds_read_b128 v[184:187], v137 offset:53248
	ds_read_b128 v[188:191], v137 offset:54272
	ds_read_b128 v[192:195], v137 offset:55296
	ds_read_b128 v[196:199], v137 offset:56320
	s_add_u32 s54, s89, 0x180
	s_mov_b32 m0, s61
	s_nop 0
	global_load_lds_dwordx4 v129, s[44:45]
	s_addc_u32 s55, s90, 0
	s_mov_b32 m0, s62
	s_nop 0
	global_load_lds_dwordx4 v129, s[54:55]
	s_add_u32 s44, s91, 0x180
	s_addc_u32 s45, s92, 0
	s_add_u32 s54, s93, 0x180
	s_mov_b32 m0, s65
	s_nop 0
	global_load_lds_dwordx4 v129, s[44:45]
	s_addc_u32 s55, s94, 0
	s_mov_b32 m0, s66
	s_nop 0
	global_load_lds_dwordx4 v129, s[54:55]
	s_add_u32 s44, s79, 0x180
	s_addc_u32 s45, s80, 0
	s_add_u32 s54, s82, 0x180
	s_mov_b32 m0, s63
	s_nop 0
	global_load_lds_dwordx4 v128, s[44:45]
	s_addc_u32 s55, s83, 0
	s_mov_b32 m0, s64
	s_nop 0
	global_load_lds_dwordx4 v128, s[54:55]
	s_waitcnt vmcnt(8)
	s_waitcnt lgkmcnt(0)
	s_barrier
	s_waitcnt lgkmcnt(7)
	v_mfma_f32_16x16x32_bf16 v[60:63], v[130:133], v[168:171], v[60:63]
	v_mfma_f32_16x16x32_bf16 v[56:59], v[144:147], v[168:171], v[56:59]
	s_waitcnt lgkmcnt(5)
	v_mfma_f32_16x16x32_bf16 v[52:55], v[130:133], v[176:179], v[52:55]
	v_mfma_f32_16x16x32_bf16 v[48:51], v[144:147], v[176:179], v[48:51]
	s_waitcnt lgkmcnt(3)
	v_mfma_f32_16x16x32_bf16 v[44:47], v[130:133], v[184:187], v[44:47]
	v_mfma_f32_16x16x32_bf16 v[40:43], v[144:147], v[184:187], v[40:43]
	s_waitcnt lgkmcnt(1)
	v_mfma_f32_16x16x32_bf16 v[36:39], v[130:133], v[192:195], v[36:39]
	v_mfma_f32_16x16x32_bf16 v[32:35], v[144:147], v[192:195], v[32:35]
	v_mfma_f32_16x16x32_bf16 v[60:63], v[140:143], v[172:175], v[60:63]
	v_mfma_f32_16x16x32_bf16 v[56:59], v[148:151], v[172:175], v[56:59]
	v_mfma_f32_16x16x32_bf16 v[52:55], v[140:143], v[180:183], v[52:55]
	v_mfma_f32_16x16x32_bf16 v[48:51], v[148:151], v[180:183], v[48:51]
	v_mfma_f32_16x16x32_bf16 v[44:47], v[140:143], v[188:191], v[44:47]
	v_mfma_f32_16x16x32_bf16 v[40:43], v[148:151], v[188:191], v[40:43]
	s_waitcnt lgkmcnt(0)
	v_mfma_f32_16x16x32_bf16 v[36:39], v[140:143], v[196:199], v[36:39]
	v_mfma_f32_16x16x32_bf16 v[32:35], v[148:151], v[196:199], v[32:35]
	v_mfma_f32_16x16x32_bf16 v[28:31], v[152:155], v[168:171], v[28:31]
	v_mfma_f32_16x16x32_bf16 v[24:27], v[160:163], v[168:171], v[24:27]
	v_mfma_f32_16x16x32_bf16 v[20:23], v[152:155], v[176:179], v[20:23]
	v_mfma_f32_16x16x32_bf16 v[16:19], v[160:163], v[176:179], v[16:19]
	v_mfma_f32_16x16x32_bf16 v[12:15], v[152:155], v[184:187], v[12:15]
	v_mfma_f32_16x16x32_bf16 v[8:11], v[160:163], v[184:187], v[8:11]
	v_mfma_f32_16x16x32_bf16 v[4:7], v[152:155], v[192:195], v[4:7]
	v_mfma_f32_16x16x32_bf16 v[0:3], v[160:163], v[192:195], v[0:3]
	v_mfma_f32_16x16x32_bf16 v[28:31], v[156:159], v[172:175], v[28:31]
	v_mfma_f32_16x16x32_bf16 v[24:27], v[164:167], v[172:175], v[24:27]
	v_mfma_f32_16x16x32_bf16 v[20:23], v[156:159], v[180:183], v[20:23]
	v_mfma_f32_16x16x32_bf16 v[16:19], v[164:167], v[180:183], v[16:19]
	v_mfma_f32_16x16x32_bf16 v[12:15], v[156:159], v[188:191], v[12:15]
	v_mfma_f32_16x16x32_bf16 v[8:11], v[164:167], v[188:191], v[8:11]
	v_mfma_f32_16x16x32_bf16 v[4:7], v[156:159], v[196:199], v[4:7]
	v_mfma_f32_16x16x32_bf16 v[0:3], v[164:167], v[196:199], v[0:3]
	s_barrier
	s_add_u32 s42, s42, 0x100
	s_addc_u32 s43, s43, 0
	s_cmp_ge_i32 s78, s16
	s_cbranch_scc0 .LBB0_257
	s_branch .LBB0_258
.Lhf_257:
	ds_read_b128 v[130:133], v135
	ds_read_b128 v[140:143], v135 offset:1024
	ds_read_b128 v[144:147], v135 offset:2048
	ds_read_b128 v[148:151], v135 offset:3072
	ds_read_b128 v[152:155], v136
	ds_read_b128 v[156:159], v136 offset:1024
	ds_read_b128 v[160:163], v136 offset:2048
	ds_read_b128 v[164:167], v136 offset:3072
	s_add_i32 s78, s78, 2
	s_add_u32 s79, s4, s42
	s_addc_u32 s80, s5, s43
	s_add_u32 s44, s79, 0x100
	s_addc_u32 s45, s80, 0
	s_add_u32 s81, s31, s42
	ds_read_b128 v[168:171], v137
	ds_read_b128 v[172:175], v137 offset:1024
	ds_read_b128 v[176:179], v137 offset:2048
	ds_read_b128 v[180:183], v137 offset:3072
	ds_read_b128 v[184:187], v137 offset:4096
	ds_read_b128 v[188:191], v137 offset:5120
	ds_read_b128 v[192:195], v137 offset:6144
	ds_read_b128 v[196:199], v137 offset:7168
	s_addc_u32 s84, s46, s43
	s_add_u32 s54, s81, 0x80
	s_addc_u32 s55, s84, 0
	s_add_u32 s85, s73, s42
	s_addc_u32 s86, s74, s43
	s_add_u32 s82, s85, 0x80
	s_mov_b32 m0, s67
	s_nop 0
	global_load_lds_dwordx4 v128, s[54:55]
	s_addc_u32 s83, s86, 0
	s_mov_b32 m0, s68
	s_nop 0
	global_load_lds_dwordx4 v128, s[82:83]
	s_waitcnt vmcnt(8)
	s_waitcnt lgkmcnt(0)
	s_barrier
	s_waitcnt lgkmcnt(7)
	v_mfma_f32_16x16x32_bf16 v[124:127], v[130:133], v[168:171], 0
	v_mfma_f32_16x16x32_bf16 v[120:123], v[144:147], v[168:171], 0
	s_waitcnt lgkmcnt(5)
	v_mfma_f32_16x16x32_bf16 v[116:119], v[130:133], v[176:179], 0
	v_mfma_f32_16x16x32_bf16 v[112:115], v[144:147], v[176:179], 0
	s_waitcnt lgkmcnt(3)
	v_mfma_f32_16x16x32_bf16 v[108:111], v[130:133], v[184:187], 0
	v_mfma_f32_16x16x32_bf16 v[104:107], v[144:147], v[184:187], 0
	s_waitcnt lgkmcnt(1)
	v_mfma_f32_16x16x32_bf16 v[100:103], v[130:133], v[192:195], 0
	v_mfma_f32_16x16x32_bf16 v[96:99], v[144:147], v[192:195], 0
	v_mfma_f32_16x16x32_bf16 v[124:127], v[140:143], v[172:175], v[124:127]
	v_mfma_f32_16x16x32_bf16 v[120:123], v[148:151], v[172:175], v[120:123]
	v_mfma_f32_16x16x32_bf16 v[116:119], v[140:143], v[180:183], v[116:119]
	v_mfma_f32_16x16x32_bf16 v[112:115], v[148:151], v[180:183], v[112:115]
	v_mfma_f32_16x16x32_bf16 v[108:111], v[140:143], v[188:191], v[108:111]
	v_mfma_f32_16x16x32_bf16 v[104:107], v[148:151], v[188:191], v[104:107]
	s_waitcnt lgkmcnt(0)
	v_mfma_f32_16x16x32_bf16 v[100:103], v[140:143], v[196:199], v[100:103]
	v_mfma_f32_16x16x32_bf16 v[96:99], v[148:151], v[196:199], v[96:99]
	v_mfma_f32_16x16x32_bf16 v[92:95], v[152:155], v[168:171], 0
	v_mfma_f32_16x16x32_bf16 v[88:91], v[160:163], v[168:171], 0
	v_mfma_f32_16x16x32_bf16 v[84:87], v[152:155], v[176:179], 0
	v_mfma_f32_16x16x32_bf16 v[80:83], v[160:163], v[176:179], 0
	v_mfma_f32_16x16x32_bf16 v[76:79], v[152:155], v[184:187], 0
	v_mfma_f32_16x16x32_bf16 v[72:75], v[160:163], v[184:187], 0
	v_mfma_f32_16x16x32_bf16 v[68:71], v[152:155], v[192:195], 0
	v_mfma_f32_16x16x32_bf16 v[64:67], v[160:163], v[192:195], 0
	v_mfma_f32_16x16x32_bf16 v[92:95], v[156:159], v[172:175], v[92:95]
	v_mfma_f32_16x16x32_bf16 v[88:91], v[164:167], v[172:175], v[88:91]
	v_mfma_f32_16x16x32_bf16 v[84:87], v[156:159], v[180:183], v[84:87]
	v_mfma_f32_16x16x32_bf16 v[80:83], v[164:167], v[180:183], v[80:83]
	v_mfma_f32_16x16x32_bf16 v[76:79], v[156:159], v[188:191], v[76:79]
	v_mfma_f32_16x16x32_bf16 v[72:75], v[164:167], v[188:191], v[72:75]
	v_mfma_f32_16x16x32_bf16 v[68:71], v[156:159], v[196:199], v[68:71]
	v_mfma_f32_16x16x32_bf16 v[64:67], v[164:167], v[196:199], v[64:67]
	s_barrier
	s_add_u32 s87, s6, s42
	s_addc_u32 s88, s7, s43
	s_add_u32 s54, s87, 0x100
	s_addc_u32 s55, s88, 0
	s_add_u32 s89, s71, s42
	s_addc_u32 s90, s72, s43
	s_add_u32 s82, s89, 0x100
	ds_read_b128 v[168:171], v137 offset:16384
	ds_read_b128 v[172:175], v137 offset:17408
	ds_read_b128 v[176:179], v137 offset:18432
	ds_read_b128 v[180:183], v137 offset:19456
	ds_read_b128 v[184:187], v137 offset:20480
	ds_read_b128 v[188:191], v137 offset:21504
	ds_read_b128 v[192:195], v137 offset:22528
	ds_read_b128 v[196:199], v137 offset:23552
	s_addc_u32 s83, s90, 0
	s_mov_b32 m0, s51
	s_nop 0
	global_load_lds_dwordx4 v129, s[54:55]
	s_add_u32 s91, s47, s42
	s_mov_b32 m0, s57
	s_nop 0
	global_load_lds_dwordx4 v129, s[82:83]
	s_addc_u32 s92, s48, s43
	s_add_u32 s54, s91, 0x100
	s_addc_u32 s55, s92, 0
	s_add_u32 s93, s49, s42
	s_addc_u32 s94, s70, s43
	s_add_u32 s82, s93, 0x100
	s_addc_u32 s83, s94, 0
	s_mov_b32 m0, s58
	s_nop 0
	global_load_lds_dwordx4 v129, s[54:55]
	s_mov_b32 m0, s59
	s_nop 0
	global_load_lds_dwordx4 v129, s[82:83]
	s_add_u32 s82, s75, s42
	s_addc_u32 s83, s77, s43
	s_add_u32 s54, s82, 0x100
	s_mov_b32 m0, s53
	s_nop 0
	global_load_lds_dwordx4 v128, s[44:45]
	s_addc_u32 s55, s83, 0
	s_mov_b32 m0, s2
	s_nop 0
	global_load_lds_dwordx4 v128, s[54:55]
	s_waitcnt vmcnt(8)
	s_waitcnt lgkmcnt(0)
	s_barrier
	s_waitcnt lgkmcnt(7)
	v_mfma_f32_16x16x32_bf16 v[60:63], v[130:133], v[168:171], 0
	v_mfma_f32_16x16x32_bf16 v[56:59], v[144:147], v[168:171], 0
	s_waitcnt lgkmcnt(5)
	v_mfma_f32_16x16x32_bf16 v[52:55], v[130:133], v[176:179], 0
	v_mfma_f32_16x16x32_bf16 v[48:51], v[144:147], v[176:179], 0
	s_waitcnt lgkmcnt(3)
	v_mfma_f32_16x16x32_bf16 v[44:47], v[130:133], v[184:187], 0
	v_mfma_f32_16x16x32_bf16 v[40:43], v[144:147], v[184:187], 0
	s_waitcnt lgkmcnt(1)
	v_mfma_f32_16x16x32_bf16 v[36:39], v[130:133], v[192:195], 0
	v_mfma_f32_16x16x32_bf16 v[32:35], v[144:147], v[192:195], 0
	v_mfma_f32_16x16x32_bf16 v[60:63], v[140:143], v[172:175], v[60:63]
	v_mfma_f32_16x16x32_bf16 v[56:59], v[148:151], v[172:175], v[56:59]
	v_mfma_f32_16x16x32_bf16 v[52:55], v[140:143], v[180:183], v[52:55]
	v_mfma_f32_16x16x32_bf16 v[48:51], v[148:151], v[180:183], v[48:51]
	v_mfma_f32_16x16x32_bf16 v[44:47], v[140:143], v[188:191], v[44:47]
	v_mfma_f32_16x16x32_bf16 v[40:43], v[148:151], v[188:191], v[40:43]
	s_waitcnt lgkmcnt(0)
	v_mfma_f32_16x16x32_bf16 v[36:39], v[140:143], v[196:199], v[36:39]
	v_mfma_f32_16x16x32_bf16 v[32:35], v[148:151], v[196:199], v[32:35]
	v_mfma_f32_16x16x32_bf16 v[28:31], v[152:155], v[168:171], 0
	v_mfma_f32_16x16x32_bf16 v[24:27], v[160:163], v[168:171], 0
	v_mfma_f32_16x16x32_bf16 v[20:23], v[152:155], v[176:179], 0
	v_mfma_f32_16x16x32_bf16 v[16:19], v[160:163], v[176:179], 0
	v_mfma_f32_16x16x32_bf16 v[12:15], v[152:155], v[184:187], 0
	v_mfma_f32_16x16x32_bf16 v[8:11], v[160:163], v[184:187], 0
	v_mfma_f32_16x16x32_bf16 v[4:7], v[152:155], v[192:195], 0
	v_mfma_f32_16x16x32_bf16 v[0:3], v[160:163], v[192:195], 0
	v_mfma_f32_16x16x32_bf16 v[28:31], v[156:159], v[172:175], v[28:31]
	v_mfma_f32_16x16x32_bf16 v[24:27], v[164:167], v[172:175], v[24:27]
	v_mfma_f32_16x16x32_bf16 v[20:23], v[156:159], v[180:183], v[20:23]
	v_mfma_f32_16x16x32_bf16 v[16:19], v[164:167], v[180:183], v[16:19]
	v_mfma_f32_16x16x32_bf16 v[12:15], v[156:159], v[188:191], v[12:15]
	v_mfma_f32_16x16x32_bf16 v[8:11], v[164:167], v[188:191], v[8:11]
	v_mfma_f32_16x16x32_bf16 v[4:7], v[156:159], v[196:199], v[4:7]
	v_mfma_f32_16x16x32_bf16 v[0:3], v[164:167], v[196:199], v[0:3]
	s_barrier
	ds_read_b128 v[130:133], v138
	ds_read_b128 v[140:143], v138 offset:1024
	ds_read_b128 v[144:147], v138 offset:2048
	ds_read_b128 v[148:151], v138 offset:3072
	ds_read_b128 v[152:155], v139
	ds_read_b128 v[156:159], v139 offset:1024
	ds_read_b128 v[160:163], v139 offset:2048
	ds_read_b128 v[164:167], v139 offset:3072
	ds_read_b128 v[168:171], v137 offset:32768
	ds_read_b128 v[172:175], v137 offset:33792
	ds_read_b128 v[176:179], v137 offset:34816
	ds_read_b128 v[180:183], v137 offset:35840
	ds_read_b128 v[184:187], v137 offset:36864
	ds_read_b128 v[188:191], v137 offset:37888
	ds_read_b128 v[192:195], v137 offset:38912
	ds_read_b128 v[196:199], v137 offset:39936
	s_add_u32 s44, s81, 0x100
	s_addc_u32 s45, s84, 0
	s_add_u32 s54, s85, 0x100
	s_mov_b32 m0, s33
	s_nop 0
	global_load_lds_dwordx4 v128, s[44:45]
	s_addc_u32 s55, s86, 0
	s_mov_b32 m0, s60
	s_nop 0
	global_load_lds_dwordx4 v128, s[54:55]
	s_waitcnt vmcnt(8)
	s_waitcnt lgkmcnt(0)
	s_barrier
	s_waitcnt lgkmcnt(7)
	v_mfma_f32_16x16x32_bf16 v[124:127], v[130:133], v[168:171], v[124:127]
	v_mfma_f32_16x16x32_bf16 v[120:123], v[144:147], v[168:171], v[120:123]
	s_waitcnt lgkmcnt(5)
	v_mfma_f32_16x16x32_bf16 v[116:119], v[130:133], v[176:179], v[116:119]
	v_mfma_f32_16x16x32_bf16 v[112:115], v[144:147], v[176:179], v[112:115]
	s_waitcnt lgkmcnt(3)
	v_mfma_f32_16x16x32_bf16 v[108:111], v[130:133], v[184:187], v[108:111]
	v_mfma_f32_16x16x32_bf16 v[104:107], v[144:147], v[184:187], v[104:107]
	s_waitcnt lgkmcnt(1)
	v_mfma_f32_16x16x32_bf16 v[100:103], v[130:133], v[192:195], v[100:103]
	v_mfma_f32_16x16x32_bf16 v[96:99], v[144:147], v[192:195], v[96:99]
	v_mfma_f32_16x16x32_bf16 v[124:127], v[140:143], v[172:175], v[124:127]
	v_mfma_f32_16x16x32_bf16 v[120:123], v[148:151], v[172:175], v[120:123]
	v_mfma_f32_16x16x32_bf16 v[116:119], v[140:143], v[180:183], v[116:119]
	v_mfma_f32_16x16x32_bf16 v[112:115], v[148:151], v[180:183], v[112:115]
	v_mfma_f32_16x16x32_bf16 v[108:111], v[140:143], v[188:191], v[108:111]
	v_mfma_f32_16x16x32_bf16 v[104:107], v[148:151], v[188:191], v[104:107]
	s_waitcnt lgkmcnt(0)
	v_mfma_f32_16x16x32_bf16 v[100:103], v[140:143], v[196:199], v[100:103]
	v_mfma_f32_16x16x32_bf16 v[96:99], v[148:151], v[196:199], v[96:99]
	v_mfma_f32_16x16x32_bf16 v[92:95], v[152:155], v[168:171], v[92:95]
	v_mfma_f32_16x16x32_bf16 v[88:91], v[160:163], v[168:171], v[88:91]
	v_mfma_f32_16x16x32_bf16 v[84:87], v[152:155], v[176:179], v[84:87]
	v_mfma_f32_16x16x32_bf16 v[80:83], v[160:163], v[176:179], v[80:83]
	v_mfma_f32_16x16x32_bf16 v[76:79], v[152:155], v[184:187], v[76:79]
	v_mfma_f32_16x16x32_bf16 v[72:75], v[160:163], v[184:187], v[72:75]
	v_mfma_f32_16x16x32_bf16 v[68:71], v[152:155], v[192:195], v[68:71]
	v_mfma_f32_16x16x32_bf16 v[64:67], v[160:163], v[192:195], v[64:67]
	v_mfma_f32_16x16x32_bf16 v[92:95], v[156:159], v[172:175], v[92:95]
	v_mfma_f32_16x16x32_bf16 v[88:91], v[164:167], v[172:175], v[88:91]
	v_mfma_f32_16x16x32_bf16 v[84:87], v[156:159], v[180:183], v[84:87]
	v_mfma_f32_16x16x32_bf16 v[80:83], v[164:167], v[180:183], v[80:83]
	v_mfma_f32_16x16x32_bf16 v[76:79], v[156:159], v[188:191], v[76:79]
	v_mfma_f32_16x16x32_bf16 v[72:75], v[164:167], v[188:191], v[72:75]
	v_mfma_f32_16x16x32_bf16 v[68:71], v[156:159], v[196:199], v[68:71]
	v_mfma_f32_16x16x32_bf16 v[64:67], v[164:167], v[196:199], v[64:67]
	s_barrier
	s_add_u32 s44, s87, 0x180
	s_addc_u32 s45, s88, 0
	ds_read_b128 v[168:171], v137 offset:49152
	ds_read_b128 v[172:175], v137 offset:50176
	ds_read_b128 v[176:179], v137 offset:51200
	ds_read_b128 v[180:183], v137 offset:52224
	ds_read_b128 v[184:187], v137 offset:53248
	ds_read_b128 v[188:191], v137 offset:54272
	ds_read_b128 v[192:195], v137 offset:55296
	ds_read_b128 v[196:199], v137 offset:56320
	s_add_u32 s54, s89, 0x180
	s_mov_b32 m0, s61
	s_nop 0
	global_load_lds_dwordx4 v129, s[44:45]
	s_addc_u32 s55, s90, 0
	s_mov_b32 m0, s62
	s_nop 0
	global_load_lds_dwordx4 v129, s[54:55]
	s_add_u32 s44, s91, 0x180
	s_addc_u32 s45, s92, 0
	s_add_u32 s54, s93, 0x180
	s_mov_b32 m0, s65
	s_nop 0
	global_load_lds_dwordx4 v129, s[44:45]
	s_addc_u32 s55, s94, 0
	s_mov_b32 m0, s66
	s_nop 0
	global_load_lds_dwordx4 v129, s[54:55]
	s_add_u32 s44, s79, 0x180
	s_addc_u32 s45, s80, 0
	s_add_u32 s54, s82, 0x180
	s_mov_b32 m0, s63
	s_nop 0
	global_load_lds_dwordx4 v128, s[44:45]
	s_addc_u32 s55, s83, 0
	s_mov_b32 m0, s64
	s_nop 0
	global_load_lds_dwordx4 v128, s[54:55]
	s_waitcnt vmcnt(8)
	s_waitcnt lgkmcnt(0)
	s_barrier
	s_waitcnt lgkmcnt(7)
	v_mfma_f32_16x16x32_bf16 v[60:63], v[130:133], v[168:171], v[60:63]
	v_mfma_f32_16x16x32_bf16 v[56:59], v[144:147], v[168:171], v[56:59]
	s_waitcnt lgkmcnt(5)
	v_mfma_f32_16x16x32_bf16 v[52:55], v[130:133], v[176:179], v[52:55]
	v_mfma_f32_16x16x32_bf16 v[48:51], v[144:147], v[176:179], v[48:51]
	s_waitcnt lgkmcnt(3)
	v_mfma_f32_16x16x32_bf16 v[44:47], v[130:133], v[184:187], v[44:47]
	v_mfma_f32_16x16x32_bf16 v[40:43], v[144:147], v[184:187], v[40:43]
	s_waitcnt lgkmcnt(1)
	v_mfma_f32_16x16x32_bf16 v[36:39], v[130:133], v[192:195], v[36:39]
	v_mfma_f32_16x16x32_bf16 v[32:35], v[144:147], v[192:195], v[32:35]
	v_mfma_f32_16x16x32_bf16 v[60:63], v[140:143], v[172:175], v[60:63]
	v_mfma_f32_16x16x32_bf16 v[56:59], v[148:151], v[172:175], v[56:59]
	v_mfma_f32_16x16x32_bf16 v[52:55], v[140:143], v[180:183], v[52:55]
	v_mfma_f32_16x16x32_bf16 v[48:51], v[148:151], v[180:183], v[48:51]
	v_mfma_f32_16x16x32_bf16 v[44:47], v[140:143], v[188:191], v[44:47]
	v_mfma_f32_16x16x32_bf16 v[40:43], v[148:151], v[188:191], v[40:43]
	s_waitcnt lgkmcnt(0)
	v_mfma_f32_16x16x32_bf16 v[36:39], v[140:143], v[196:199], v[36:39]
	v_mfma_f32_16x16x32_bf16 v[32:35], v[148:151], v[196:199], v[32:35]
	v_mfma_f32_16x16x32_bf16 v[28:31], v[152:155], v[168:171], v[28:31]
	v_mfma_f32_16x16x32_bf16 v[24:27], v[160:163], v[168:171], v[24:27]
	v_mfma_f32_16x16x32_bf16 v[20:23], v[152:155], v[176:179], v[20:23]
	v_mfma_f32_16x16x32_bf16 v[16:19], v[160:163], v[176:179], v[16:19]
	v_mfma_f32_16x16x32_bf16 v[12:15], v[152:155], v[184:187], v[12:15]
	v_mfma_f32_16x16x32_bf16 v[8:11], v[160:163], v[184:187], v[8:11]
	v_mfma_f32_16x16x32_bf16 v[4:7], v[152:155], v[192:195], v[4:7]
	v_mfma_f32_16x16x32_bf16 v[0:3], v[160:163], v[192:195], v[0:3]
	v_mfma_f32_16x16x32_bf16 v[28:31], v[156:159], v[172:175], v[28:31]
	v_mfma_f32_16x16x32_bf16 v[24:27], v[164:167], v[172:175], v[24:27]
	v_mfma_f32_16x16x32_bf16 v[20:23], v[156:159], v[180:183], v[20:23]
	v_mfma_f32_16x16x32_bf16 v[16:19], v[164:167], v[180:183], v[16:19]
	v_mfma_f32_16x16x32_bf16 v[12:15], v[156:159], v[188:191], v[12:15]
	v_mfma_f32_16x16x32_bf16 v[8:11], v[164:167], v[188:191], v[8:11]
	v_mfma_f32_16x16x32_bf16 v[4:7], v[156:159], v[196:199], v[4:7]
	v_mfma_f32_16x16x32_bf16 v[0:3], v[164:167], v[196:199], v[0:3]
	s_barrier
	s_add_u32 s42, s42, 0x100
	s_addc_u32 s43, s43, 0
	s_cmp_ge_i32 s78, s16
	s_cbranch_scc0 .LBB0_257
	s_branch .LBB0_258

.LBB0_257:
	ds_read_b128 v[130:133], v135
	ds_read_b128 v[140:143], v135 offset:1024
	ds_read_b128 v[144:147], v135 offset:2048
	ds_read_b128 v[148:151], v135 offset:3072
	ds_read_b128 v[152:155], v136
	ds_read_b128 v[156:159], v136 offset:1024
	ds_read_b128 v[160:163], v136 offset:2048
	ds_read_b128 v[164:167], v136 offset:3072
	s_add_i32 s78, s78, 2
	s_add_u32 s79, s4, s42
	s_addc_u32 s80, s5, s43
	s_add_u32 s44, s79, 0x100
	s_addc_u32 s45, s80, 0
	s_add_u32 s81, s31, s42
	ds_read_b128 v[168:171], v137
	ds_read_b128 v[172:175], v137 offset:1024
	ds_read_b128 v[176:179], v137 offset:2048
	ds_read_b128 v[180:183], v137 offset:3072
	ds_read_b128 v[184:187], v137 offset:4096
	ds_read_b128 v[188:191], v137 offset:5120
	ds_read_b128 v[192:195], v137 offset:6144
	ds_read_b128 v[196:199], v137 offset:7168
	s_addc_u32 s84, s46, s43
	s_add_u32 s54, s81, 0x80
	s_addc_u32 s55, s84, 0
	s_add_u32 s85, s73, s42
	s_addc_u32 s86, s74, s43
	s_add_u32 s82, s85, 0x80
	s_mov_b32 m0, s67
	s_nop 0
	global_load_lds_dwordx4 v128, s[54:55]
	s_addc_u32 s83, s86, 0
	s_mov_b32 m0, s68
	s_nop 0
	global_load_lds_dwordx4 v128, s[82:83]
	s_waitcnt vmcnt(8)
	s_waitcnt lgkmcnt(0)
	s_barrier
	s_waitcnt lgkmcnt(7)
	v_mfma_f32_16x16x32_bf16 v[124:127], v[130:133], v[168:171], v[124:127]
	v_mfma_f32_16x16x32_bf16 v[120:123], v[144:147], v[168:171], v[120:123]
	s_waitcnt lgkmcnt(5)
	v_mfma_f32_16x16x32_bf16 v[116:119], v[130:133], v[176:179], v[116:119]
	v_mfma_f32_16x16x32_bf16 v[112:115], v[144:147], v[176:179], v[112:115]
	s_waitcnt lgkmcnt(3)
	v_mfma_f32_16x16x32_bf16 v[108:111], v[130:133], v[184:187], v[108:111]
	v_mfma_f32_16x16x32_bf16 v[104:107], v[144:147], v[184:187], v[104:107]
	s_waitcnt lgkmcnt(1)
	v_mfma_f32_16x16x32_bf16 v[100:103], v[130:133], v[192:195], v[100:103]
	v_mfma_f32_16x16x32_bf16 v[96:99], v[144:147], v[192:195], v[96:99]
	v_mfma_f32_16x16x32_bf16 v[124:127], v[140:143], v[172:175], v[124:127]
	v_mfma_f32_16x16x32_bf16 v[120:123], v[148:151], v[172:175], v[120:123]
	v_mfma_f32_16x16x32_bf16 v[116:119], v[140:143], v[180:183], v[116:119]
	v_mfma_f32_16x16x32_bf16 v[112:115], v[148:151], v[180:183], v[112:115]
	v_mfma_f32_16x16x32_bf16 v[108:111], v[140:143], v[188:191], v[108:111]
	v_mfma_f32_16x16x32_bf16 v[104:107], v[148:151], v[188:191], v[104:107]
	s_waitcnt lgkmcnt(0)
	v_mfma_f32_16x16x32_bf16 v[100:103], v[140:143], v[196:199], v[100:103]
	v_mfma_f32_16x16x32_bf16 v[96:99], v[148:151], v[196:199], v[96:99]
	v_mfma_f32_16x16x32_bf16 v[92:95], v[152:155], v[168:171], v[92:95]
	v_mfma_f32_16x16x32_bf16 v[88:91], v[160:163], v[168:171], v[88:91]
	v_mfma_f32_16x16x32_bf16 v[84:87], v[152:155], v[176:179], v[84:87]
	v_mfma_f32_16x16x32_bf16 v[80:83], v[160:163], v[176:179], v[80:83]
	v_mfma_f32_16x16x32_bf16 v[76:79], v[152:155], v[184:187], v[76:79]
	v_mfma_f32_16x16x32_bf16 v[72:75], v[160:163], v[184:187], v[72:75]
	v_mfma_f32_16x16x32_bf16 v[68:71], v[152:155], v[192:195], v[68:71]
	v_mfma_f32_16x16x32_bf16 v[64:67], v[160:163], v[192:195], v[64:67]
	v_mfma_f32_16x16x32_bf16 v[92:95], v[156:159], v[172:175], v[92:95]
	v_mfma_f32_16x16x32_bf16 v[88:91], v[164:167], v[172:175], v[88:91]
	v_mfma_f32_16x16x32_bf16 v[84:87], v[156:159], v[180:183], v[84:87]
	v_mfma_f32_16x16x32_bf16 v[80:83], v[164:167], v[180:183], v[80:83]
	v_mfma_f32_16x16x32_bf16 v[76:79], v[156:159], v[188:191], v[76:79]
	v_mfma_f32_16x16x32_bf16 v[72:75], v[164:167], v[188:191], v[72:75]
	v_mfma_f32_16x16x32_bf16 v[68:71], v[156:159], v[196:199], v[68:71]
	v_mfma_f32_16x16x32_bf16 v[64:67], v[164:167], v[196:199], v[64:67]
	s_barrier
	s_add_u32 s87, s6, s42
	s_addc_u32 s88, s7, s43
	s_add_u32 s54, s87, 0x100
	s_addc_u32 s55, s88, 0
	s_add_u32 s89, s71, s42
	s_addc_u32 s90, s72, s43
	s_add_u32 s82, s89, 0x100
	ds_read_b128 v[168:171], v137 offset:16384
	ds_read_b128 v[172:175], v137 offset:17408
	ds_read_b128 v[176:179], v137 offset:18432
	ds_read_b128 v[180:183], v137 offset:19456
	ds_read_b128 v[184:187], v137 offset:20480
	ds_read_b128 v[188:191], v137 offset:21504
	ds_read_b128 v[192:195], v137 offset:22528
	ds_read_b128 v[196:199], v137 offset:23552
	s_addc_u32 s83, s90, 0
	s_mov_b32 m0, s51
	s_nop 0
	global_load_lds_dwordx4 v129, s[54:55]
	s_add_u32 s91, s47, s42
	s_mov_b32 m0, s57
	s_nop 0
	global_load_lds_dwordx4 v129, s[82:83]
	s_addc_u32 s92, s48, s43
	s_add_u32 s54, s91, 0x100
	s_addc_u32 s55, s92, 0
	s_add_u32 s93, s49, s42
	s_addc_u32 s94, s70, s43
	s_add_u32 s82, s93, 0x100
	s_addc_u32 s83, s94, 0
	s_mov_b32 m0, s58
	s_nop 0
	global_load_lds_dwordx4 v129, s[54:55]
	s_mov_b32 m0, s59
	s_nop 0
	global_load_lds_dwordx4 v129, s[82:83]
	s_add_u32 s82, s75, s42
	s_addc_u32 s83, s77, s43
	s_add_u32 s54, s82, 0x100
	s_mov_b32 m0, s53
	s_nop 0
	global_load_lds_dwordx4 v128, s[44:45]
	s_addc_u32 s55, s83, 0
	s_mov_b32 m0, s2
	s_nop 0
	global_load_lds_dwordx4 v128, s[54:55]
	s_waitcnt vmcnt(8)
	s_waitcnt lgkmcnt(0)
	s_barrier
	s_waitcnt lgkmcnt(7)
	v_mfma_f32_16x16x32_bf16 v[60:63], v[130:133], v[168:171], v[60:63]
	v_mfma_f32_16x16x32_bf16 v[56:59], v[144:147], v[168:171], v[56:59]
	s_waitcnt lgkmcnt(5)
	v_mfma_f32_16x16x32_bf16 v[52:55], v[130:133], v[176:179], v[52:55]
	v_mfma_f32_16x16x32_bf16 v[48:51], v[144:147], v[176:179], v[48:51]
	s_waitcnt lgkmcnt(3)
	v_mfma_f32_16x16x32_bf16 v[44:47], v[130:133], v[184:187], v[44:47]
	v_mfma_f32_16x16x32_bf16 v[40:43], v[144:147], v[184:187], v[40:43]
	s_waitcnt lgkmcnt(1)
	v_mfma_f32_16x16x32_bf16 v[36:39], v[130:133], v[192:195], v[36:39]
	v_mfma_f32_16x16x32_bf16 v[32:35], v[144:147], v[192:195], v[32:35]
	v_mfma_f32_16x16x32_bf16 v[60:63], v[140:143], v[172:175], v[60:63]
	v_mfma_f32_16x16x32_bf16 v[56:59], v[148:151], v[172:175], v[56:59]
	v_mfma_f32_16x16x32_bf16 v[52:55], v[140:143], v[180:183], v[52:55]
	v_mfma_f32_16x16x32_bf16 v[48:51], v[148:151], v[180:183], v[48:51]
	v_mfma_f32_16x16x32_bf16 v[44:47], v[140:143], v[188:191], v[44:47]
	v_mfma_f32_16x16x32_bf16 v[40:43], v[148:151], v[188:191], v[40:43]
	s_waitcnt lgkmcnt(0)
	v_mfma_f32_16x16x32_bf16 v[36:39], v[140:143], v[196:199], v[36:39]
	v_mfma_f32_16x16x32_bf16 v[32:35], v[148:151], v[196:199], v[32:35]
	v_mfma_f32_16x16x32_bf16 v[28:31], v[152:155], v[168:171], v[28:31]
	v_mfma_f32_16x16x32_bf16 v[24:27], v[160:163], v[168:171], v[24:27]
	v_mfma_f32_16x16x32_bf16 v[20:23], v[152:155], v[176:179], v[20:23]
	v_mfma_f32_16x16x32_bf16 v[16:19], v[160:163], v[176:179], v[16:19]
	v_mfma_f32_16x16x32_bf16 v[12:15], v[152:155], v[184:187], v[12:15]
	v_mfma_f32_16x16x32_bf16 v[8:11], v[160:163], v[184:187], v[8:11]
	v_mfma_f32_16x16x32_bf16 v[4:7], v[152:155], v[192:195], v[4:7]
	v_mfma_f32_16x16x32_bf16 v[0:3], v[160:163], v[192:195], v[0:3]
	v_mfma_f32_16x16x32_bf16 v[28:31], v[156:159], v[172:175], v[28:31]
	v_mfma_f32_16x16x32_bf16 v[24:27], v[164:167], v[172:175], v[24:27]
	v_mfma_f32_16x16x32_bf16 v[20:23], v[156:159], v[180:183], v[20:23]
	v_mfma_f32_16x16x32_bf16 v[16:19], v[164:167], v[180:183], v[16:19]
	v_mfma_f32_16x16x32_bf16 v[12:15], v[156:159], v[188:191], v[12:15]
	v_mfma_f32_16x16x32_bf16 v[8:11], v[164:167], v[188:191], v[8:11]
	v_mfma_f32_16x16x32_bf16 v[4:7], v[156:159], v[196:199], v[4:7]
	v_mfma_f32_16x16x32_bf16 v[0:3], v[164:167], v[196:199], v[0:3]
	s_barrier
	ds_read_b128 v[130:133], v138
	ds_read_b128 v[140:143], v138 offset:1024
	ds_read_b128 v[144:147], v138 offset:2048
	ds_read_b128 v[148:151], v138 offset:3072
	ds_read_b128 v[152:155], v139
	ds_read_b128 v[156:159], v139 offset:1024
	ds_read_b128 v[160:163], v139 offset:2048
	ds_read_b128 v[164:167], v139 offset:3072
	ds_read_b128 v[168:171], v137 offset:32768
	ds_read_b128 v[172:175], v137 offset:33792
	ds_read_b128 v[176:179], v137 offset:34816
	ds_read_b128 v[180:183], v137 offset:35840
	ds_read_b128 v[184:187], v137 offset:36864
	ds_read_b128 v[188:191], v137 offset:37888
	ds_read_b128 v[192:195], v137 offset:38912
	ds_read_b128 v[196:199], v137 offset:39936
	s_add_u32 s44, s81, 0x100
	s_addc_u32 s45, s84, 0
	s_add_u32 s54, s85, 0x100
	s_mov_b32 m0, s33
	s_nop 0
	global_load_lds_dwordx4 v128, s[44:45]
	s_addc_u32 s55, s86, 0
	s_mov_b32 m0, s60
	s_nop 0
	global_load_lds_dwordx4 v128, s[54:55]
	s_waitcnt vmcnt(8)
	s_waitcnt lgkmcnt(0)
	s_barrier
	s_waitcnt lgkmcnt(7)
	v_mfma_f32_16x16x32_bf16 v[124:127], v[130:133], v[168:171], v[124:127]
	v_mfma_f32_16x16x32_bf16 v[120:123], v[144:147], v[168:171], v[120:123]
	s_waitcnt lgkmcnt(5)
	v_mfma_f32_16x16x32_bf16 v[116:119], v[130:133], v[176:179], v[116:119]
	v_mfma_f32_16x16x32_bf16 v[112:115], v[144:147], v[176:179], v[112:115]
	s_waitcnt lgkmcnt(3)
	v_mfma_f32_16x16x32_bf16 v[108:111], v[130:133], v[184:187], v[108:111]
	v_mfma_f32_16x16x32_bf16 v[104:107], v[144:147], v[184:187], v[104:107]
	s_waitcnt lgkmcnt(1)
	v_mfma_f32_16x16x32_bf16 v[100:103], v[130:133], v[192:195], v[100:103]
	v_mfma_f32_16x16x32_bf16 v[96:99], v[144:147], v[192:195], v[96:99]
	v_mfma_f32_16x16x32_bf16 v[124:127], v[140:143], v[172:175], v[124:127]
	v_mfma_f32_16x16x32_bf16 v[120:123], v[148:151], v[172:175], v[120:123]
	v_mfma_f32_16x16x32_bf16 v[116:119], v[140:143], v[180:183], v[116:119]
	v_mfma_f32_16x16x32_bf16 v[112:115], v[148:151], v[180:183], v[112:115]
	v_mfma_f32_16x16x32_bf16 v[108:111], v[140:143], v[188:191], v[108:111]
	v_mfma_f32_16x16x32_bf16 v[104:107], v[148:151], v[188:191], v[104:107]
	s_waitcnt lgkmcnt(0)
	v_mfma_f32_16x16x32_bf16 v[100:103], v[140:143], v[196:199], v[100:103]
	v_mfma_f32_16x16x32_bf16 v[96:99], v[148:151], v[196:199], v[96:99]
	v_mfma_f32_16x16x32_bf16 v[92:95], v[152:155], v[168:171], v[92:95]
	v_mfma_f32_16x16x32_bf16 v[88:91], v[160:163], v[168:171], v[88:91]
	v_mfma_f32_16x16x32_bf16 v[84:87], v[152:155], v[176:179], v[84:87]
	v_mfma_f32_16x16x32_bf16 v[80:83], v[160:163], v[176:179], v[80:83]
	v_mfma_f32_16x16x32_bf16 v[76:79], v[152:155], v[184:187], v[76:79]
	v_mfma_f32_16x16x32_bf16 v[72:75], v[160:163], v[184:187], v[72:75]
	v_mfma_f32_16x16x32_bf16 v[68:71], v[152:155], v[192:195], v[68:71]
	v_mfma_f32_16x16x32_bf16 v[64:67], v[160:163], v[192:195], v[64:67]
	v_mfma_f32_16x16x32_bf16 v[92:95], v[156:159], v[172:175], v[92:95]
	v_mfma_f32_16x16x32_bf16 v[88:91], v[164:167], v[172:175], v[88:91]
	v_mfma_f32_16x16x32_bf16 v[84:87], v[156:159], v[180:183], v[84:87]
	v_mfma_f32_16x16x32_bf16 v[80:83], v[164:167], v[180:183], v[80:83]
	v_mfma_f32_16x16x32_bf16 v[76:79], v[156:159], v[188:191], v[76:79]
	v_mfma_f32_16x16x32_bf16 v[72:75], v[164:167], v[188:191], v[72:75]
	v_mfma_f32_16x16x32_bf16 v[68:71], v[156:159], v[196:199], v[68:71]
	v_mfma_f32_16x16x32_bf16 v[64:67], v[164:167], v[196:199], v[64:67]
	s_barrier
	s_add_u32 s44, s87, 0x180
	s_addc_u32 s45, s88, 0
	ds_read_b128 v[168:171], v137 offset:49152
	ds_read_b128 v[172:175], v137 offset:50176
	ds_read_b128 v[176:179], v137 offset:51200
	ds_read_b128 v[180:183], v137 offset:52224
	ds_read_b128 v[184:187], v137 offset:53248
	ds_read_b128 v[188:191], v137 offset:54272
	ds_read_b128 v[192:195], v137 offset:55296
	ds_read_b128 v[196:199], v137 offset:56320
	s_add_u32 s54, s89, 0x180
	s_mov_b32 m0, s61
	s_nop 0
	global_load_lds_dwordx4 v129, s[44:45]
	s_addc_u32 s55, s90, 0
	s_mov_b32 m0, s62
	s_nop 0
	global_load_lds_dwordx4 v129, s[54:55]
	s_add_u32 s44, s91, 0x180
	s_addc_u32 s45, s92, 0
	s_add_u32 s54, s93, 0x180
	s_mov_b32 m0, s65
	s_nop 0
	global_load_lds_dwordx4 v129, s[44:45]
	s_addc_u32 s55, s94, 0
	s_mov_b32 m0, s66
	s_nop 0
	global_load_lds_dwordx4 v129, s[54:55]
	s_add_u32 s44, s79, 0x180
	s_addc_u32 s45, s80, 0
	s_add_u32 s54, s82, 0x180
	s_mov_b32 m0, s63
	s_nop 0
	global_load_lds_dwordx4 v128, s[44:45]
	s_addc_u32 s55, s83, 0
	s_mov_b32 m0, s64
	s_nop 0
	global_load_lds_dwordx4 v128, s[54:55]
	s_waitcnt vmcnt(8)
	s_waitcnt lgkmcnt(0)
	s_barrier
	s_waitcnt lgkmcnt(7)
	v_mfma_f32_16x16x32_bf16 v[60:63], v[130:133], v[168:171], v[60:63]
	v_mfma_f32_16x16x32_bf16 v[56:59], v[144:147], v[168:171], v[56:59]
	s_waitcnt lgkmcnt(5)
	v_mfma_f32_16x16x32_bf16 v[52:55], v[130:133], v[176:179], v[52:55]
	v_mfma_f32_16x16x32_bf16 v[48:51], v[144:147], v[176:179], v[48:51]
	s_waitcnt lgkmcnt(3)
	v_mfma_f32_16x16x32_bf16 v[44:47], v[130:133], v[184:187], v[44:47]
	v_mfma_f32_16x16x32_bf16 v[40:43], v[144:147], v[184:187], v[40:43]
	s_waitcnt lgkmcnt(1)
	v_mfma_f32_16x16x32_bf16 v[36:39], v[130:133], v[192:195], v[36:39]
	v_mfma_f32_16x16x32_bf16 v[32:35], v[144:147], v[192:195], v[32:35]
	v_mfma_f32_16x16x32_bf16 v[60:63], v[140:143], v[172:175], v[60:63]
	v_mfma_f32_16x16x32_bf16 v[56:59], v[148:151], v[172:175], v[56:59]
	v_mfma_f32_16x16x32_bf16 v[52:55], v[140:143], v[180:183], v[52:55]
	v_mfma_f32_16x16x32_bf16 v[48:51], v[148:151], v[180:183], v[48:51]
	v_mfma_f32_16x16x32_bf16 v[44:47], v[140:143], v[188:191], v[44:47]
	v_mfma_f32_16x16x32_bf16 v[40:43], v[148:151], v[188:191], v[40:43]
	s_waitcnt lgkmcnt(0)
	v_mfma_f32_16x16x32_bf16 v[36:39], v[140:143], v[196:199], v[36:39]
	v_mfma_f32_16x16x32_bf16 v[32:35], v[148:151], v[196:199], v[32:35]
	v_mfma_f32_16x16x32_bf16 v[28:31], v[152:155], v[168:171], v[28:31]
	v_mfma_f32_16x16x32_bf16 v[24:27], v[160:163], v[168:171], v[24:27]
	v_mfma_f32_16x16x32_bf16 v[20:23], v[152:155], v[176:179], v[20:23]
	v_mfma_f32_16x16x32_bf16 v[16:19], v[160:163], v[176:179], v[16:19]
	v_mfma_f32_16x16x32_bf16 v[12:15], v[152:155], v[184:187], v[12:15]
	v_mfma_f32_16x16x32_bf16 v[8:11], v[160:163], v[184:187], v[8:11]
	v_mfma_f32_16x16x32_bf16 v[4:7], v[152:155], v[192:195], v[4:7]
	v_mfma_f32_16x16x32_bf16 v[0:3], v[160:163], v[192:195], v[0:3]
	v_mfma_f32_16x16x32_bf16 v[28:31], v[156:159], v[172:175], v[28:31]
	v_mfma_f32_16x16x32_bf16 v[24:27], v[164:167], v[172:175], v[24:27]
	v_mfma_f32_16x16x32_bf16 v[20:23], v[156:159], v[180:183], v[20:23]
	v_mfma_f32_16x16x32_bf16 v[16:19], v[164:167], v[180:183], v[16:19]
	v_mfma_f32_16x16x32_bf16 v[12:15], v[156:159], v[188:191], v[12:15]
	v_mfma_f32_16x16x32_bf16 v[8:11], v[164:167], v[188:191], v[8:11]
	v_mfma_f32_16x16x32_bf16 v[4:7], v[156:159], v[196:199], v[4:7]
	v_mfma_f32_16x16x32_bf16 v[0:3], v[164:167], v[196:199], v[0:3]
	s_barrier
	s_add_u32 s42, s42, 0x100
	s_addc_u32 s43, s43, 0
	s_cmp_ge_i32 s78, s16
	s_cbranch_scc0 .LBB0_257

.LBB0_260:
	ds_read_b128 v[140:143], v135
	ds_read_b128 v[144:147], v135 offset:1024
	ds_read_b128 v[148:151], v135 offset:2048
	ds_read_b128 v[152:155], v135 offset:3072
	ds_read_b128 v[156:159], v136
	ds_read_b128 v[160:163], v136 offset:1024
	ds_read_b128 v[164:167], v136 offset:2048
	ds_read_b128 v[168:171], v136 offset:3072
	s_ashr_i32 s49, s20, 31
	s_mov_b32 s48, s20
	s_lshl_b64 s[48:49], s[48:49], 7
	s_add_u32 s4, s4, s48
	ds_read_b128 v[172:175], v137
	ds_read_b128 v[176:179], v137 offset:1024
	ds_read_b128 v[180:183], v137 offset:2048
	ds_read_b128 v[184:187], v137 offset:3072
	ds_read_b128 v[188:191], v137 offset:4096
	ds_read_b128 v[192:195], v137 offset:5120
	ds_read_b128 v[196:199], v137 offset:6144
	ds_read_b128 v[200:203], v137 offset:7168
	s_addc_u32 s5, s5, s49
	s_add_u32 s4, s4, s40
	s_addc_u32 s5, s5, s41
	s_add_u32 s4, s4, 0xffffff80
	s_addc_u32 s5, s5, -1
	s_add_u32 s38, s4, s38
	s_mov_b32 m0, s67
	s_nop 0
	global_load_lds_dwordx4 v128, s[4:5]
	s_addc_u32 s39, s5, s39
	s_mov_b32 m0, s68
	s_nop 0
	global_load_lds_dwordx4 v128, s[38:39]
	s_waitcnt vmcnt(8)
	s_waitcnt lgkmcnt(0)
	s_barrier
	s_waitcnt lgkmcnt(7)
	v_mfma_f32_16x16x32_bf16 v[124:127], v[140:143], v[172:175], v[124:127]
	s_waitcnt lgkmcnt(5)
	v_mfma_f32_16x16x32_bf16 v[116:119], v[140:143], v[180:183], v[116:119]
	s_waitcnt lgkmcnt(3)
	v_mfma_f32_16x16x32_bf16 v[108:111], v[140:143], v[188:191], v[108:111]
	s_waitcnt lgkmcnt(1)
	v_mfma_f32_16x16x32_bf16 v[100:103], v[140:143], v[196:199], v[100:103]
	v_mfma_f32_16x16x32_bf16 v[124:127], v[144:147], v[176:179], v[124:127]
	v_mfma_f32_16x16x32_bf16 v[120:123], v[148:151], v[172:175], v[120:123]
	v_mfma_f32_16x16x32_bf16 v[116:119], v[144:147], v[184:187], v[116:119]
	v_mfma_f32_16x16x32_bf16 v[112:115], v[148:151], v[180:183], v[112:115]
	v_mfma_f32_16x16x32_bf16 v[108:111], v[144:147], v[192:195], v[108:111]
	v_mfma_f32_16x16x32_bf16 v[104:107], v[148:151], v[188:191], v[104:107]
	s_waitcnt lgkmcnt(0)
	v_mfma_f32_16x16x32_bf16 v[100:103], v[144:147], v[200:203], v[100:103]
	v_mfma_f32_16x16x32_bf16 v[96:99], v[148:151], v[196:199], v[96:99]
	v_mfma_f32_16x16x32_bf16 v[204:207], v[152:155], v[176:179], v[120:123]
	v_mfma_f32_16x16x32_bf16 v[208:211], v[152:155], v[184:187], v[112:115]
	v_mfma_f32_16x16x32_bf16 v[212:215], v[152:155], v[192:195], v[104:107]
	v_mfma_f32_16x16x32_bf16 v[216:219], v[152:155], v[200:203], v[96:99]
	v_mfma_f32_16x16x32_bf16 v[92:95], v[156:159], v[172:175], v[92:95]
	v_mfma_f32_16x16x32_bf16 v[88:91], v[164:167], v[172:175], v[88:91]
	v_mfma_f32_16x16x32_bf16 v[84:87], v[156:159], v[180:183], v[84:87]
	v_mfma_f32_16x16x32_bf16 v[80:83], v[164:167], v[180:183], v[80:83]
	v_mfma_f32_16x16x32_bf16 v[76:79], v[156:159], v[188:191], v[76:79]
	v_mfma_f32_16x16x32_bf16 v[92:95], v[160:163], v[176:179], v[92:95]
	v_mfma_f32_16x16x32_bf16 v[88:91], v[168:171], v[176:179], v[88:91]
	v_mfma_f32_16x16x32_bf16 v[84:87], v[160:163], v[184:187], v[84:87]
	v_mfma_f32_16x16x32_bf16 v[80:83], v[168:171], v[184:187], v[80:83]
	v_mfma_f32_16x16x32_bf16 v[76:79], v[160:163], v[192:195], v[76:79]
	v_mfma_f32_16x16x32_bf16 v[72:75], v[164:167], v[188:191], v[72:75]
	v_mfma_f32_16x16x32_bf16 v[68:71], v[156:159], v[196:199], v[68:71]
	v_mfma_f32_16x16x32_bf16 v[64:67], v[164:167], v[196:199], v[64:67]
	v_mfma_f32_16x16x32_bf16 v[172:175], v[168:171], v[192:195], v[72:75]
	v_mfma_f32_16x16x32_bf16 v[176:179], v[160:163], v[200:203], v[68:71]
	v_mfma_f32_16x16x32_bf16 v[180:183], v[168:171], v[200:203], v[64:67]
	s_barrier
	s_add_u32 s38, s6, s18
	s_nop 1
	ds_read_b128 v[64:67], v137 offset:16384
	ds_read_b128 v[68:71], v137 offset:17408
	ds_read_b128 v[72:75], v137 offset:18432
	ds_read_b128 v[96:99], v137 offset:19456
	ds_read_b128 v[104:107], v137 offset:20480
	ds_read_b128 v[112:115], v137 offset:21504
	ds_read_b128 v[120:123], v137 offset:22528
	ds_read_b128 v[184:187], v137 offset:23552
	s_addc_u32 s39, s7, s19
	s_mov_b32 m0, s51
	s_nop 0
	global_load_lds_dwordx4 v131, s[6:7]
	s_add_u32 s40, s6, s24
	s_mov_b32 m0, s57
	s_nop 0
	global_load_lds_dwordx4 v131, s[38:39]
	s_addc_u32 s41, s7, s25
	s_add_u32 s48, s40, s18
	s_mov_b32 m0, s58
	s_nop 0
	global_load_lds_dwordx4 v131, s[40:41]
	s_addc_u32 s49, s41, s19
	s_mov_b32 m0, s59
	s_nop 0
	global_load_lds_dwordx4 v131, s[48:49]
	s_add_u32 s4, s46, s44
	s_mov_b32 m0, s53
	s_nop 0
	global_load_lds_dwordx4 v130, s[46:47]
	s_addc_u32 s5, s47, s45
	s_mov_b32 m0, s2
	s_nop 0
	global_load_lds_dwordx4 v130, s[4:5]
	s_waitcnt vmcnt(8)
	s_waitcnt lgkmcnt(0)
	s_barrier
	s_waitcnt lgkmcnt(7)
	v_mfma_f32_16x16x32_bf16 v[60:63], v[140:143], v[64:67], v[60:63]
	v_mfma_f32_16x16x32_bf16 v[56:59], v[148:151], v[64:67], v[56:59]
	s_waitcnt lgkmcnt(5)
	v_mfma_f32_16x16x32_bf16 v[52:55], v[140:143], v[72:75], v[52:55]
	v_mfma_f32_16x16x32_bf16 v[48:51], v[148:151], v[72:75], v[48:51]
	v_mfma_f32_16x16x32_bf16 v[60:63], v[144:147], v[68:71], v[60:63]
	v_mfma_f32_16x16x32_bf16 v[56:59], v[152:155], v[68:71], v[56:59]
	s_waitcnt lgkmcnt(4)
	v_mfma_f32_16x16x32_bf16 v[52:55], v[144:147], v[96:99], v[52:55]
	v_mfma_f32_16x16x32_bf16 v[48:51], v[152:155], v[96:99], v[48:51]
	s_waitcnt lgkmcnt(3)
	v_mfma_f32_16x16x32_bf16 v[44:47], v[140:143], v[104:107], v[44:47]
	v_mfma_f32_16x16x32_bf16 v[40:43], v[148:151], v[104:107], v[40:43]
	s_waitcnt lgkmcnt(1)
	v_mfma_f32_16x16x32_bf16 v[36:39], v[140:143], v[120:123], v[36:39]
	v_mfma_f32_16x16x32_bf16 v[32:35], v[148:151], v[120:123], v[32:35]
	v_mfma_f32_16x16x32_bf16 v[188:191], v[144:147], v[112:115], v[44:47]
	v_mfma_f32_16x16x32_bf16 v[192:195], v[152:155], v[112:115], v[40:43]
	s_waitcnt lgkmcnt(0)
	v_mfma_f32_16x16x32_bf16 v[140:143], v[144:147], v[184:187], v[36:39]
	v_mfma_f32_16x16x32_bf16 v[144:147], v[152:155], v[184:187], v[32:35]
	v_mfma_f32_16x16x32_bf16 v[28:31], v[156:159], v[64:67], v[28:31]
	v_mfma_f32_16x16x32_bf16 v[20:23], v[156:159], v[72:75], v[20:23]
	v_mfma_f32_16x16x32_bf16 v[12:15], v[156:159], v[104:107], v[12:15]
	v_mfma_f32_16x16x32_bf16 v[4:7], v[156:159], v[120:123], v[4:7]
	v_mfma_f32_16x16x32_bf16 v[28:31], v[160:163], v[68:71], v[28:31]
	v_mfma_f32_16x16x32_bf16 v[24:27], v[164:167], v[64:67], v[24:27]
	v_mfma_f32_16x16x32_bf16 v[20:23], v[160:163], v[96:99], v[20:23]
	v_mfma_f32_16x16x32_bf16 v[16:19], v[164:167], v[72:75], v[16:19]
	v_mfma_f32_16x16x32_bf16 v[12:15], v[160:163], v[112:115], v[12:15]
	v_mfma_f32_16x16x32_bf16 v[8:11], v[164:167], v[104:107], v[8:11]
	v_mfma_f32_16x16x32_bf16 v[4:7], v[160:163], v[184:187], v[4:7]
	v_mfma_f32_16x16x32_bf16 v[0:3], v[164:167], v[120:123], v[0:3]
	v_mfma_f32_16x16x32_bf16 v[148:151], v[168:171], v[68:71], v[24:27]
	v_mfma_f32_16x16x32_bf16 v[152:155], v[168:171], v[96:99], v[16:19]
	v_mfma_f32_16x16x32_bf16 v[196:199], v[168:171], v[112:115], v[8:11]
	v_mfma_f32_16x16x32_bf16 v[156:159], v[168:171], v[184:187], v[0:3]
	s_barrier
	s_nop 1
	ds_read_b128 v[0:3], v138
	ds_read_b128 v[8:11], v138 offset:1024
	ds_read_b128 v[160:163], v138 offset:2048
	ds_read_b128 v[164:167], v138 offset:3072
	ds_read_b128 v[168:171], v139
	ds_read_b128 v[184:187], v139 offset:1024
	ds_read_b128 v[200:203], v139 offset:2048
	ds_read_b128 v[220:223], v139 offset:3072
	ds_read_b128 v[16:19], v137 offset:32768
	ds_read_b128 v[24:27], v137 offset:33792
	ds_read_b128 v[36:39], v137 offset:34816
	ds_read_b128 v[44:47], v137 offset:35840
	ds_read_b128 v[68:71], v137 offset:36864
	ds_read_b128 v[224:227], v137 offset:37888
	ds_read_b128 v[228:231], v137 offset:38912
	ds_read_b128 v[232:235], v137 offset:39936
	s_add_u32 s54, s46, s42
	s_addc_u32 s55, s47, s43
	s_add_u32 s70, s54, s44
	s_mov_b32 m0, s33
	s_nop 0
	global_load_lds_dwordx4 v130, s[54:55]
	s_addc_u32 s71, s55, s45
	s_mov_b32 m0, s60
	s_nop 0
	global_load_lds_dwordx4 v130, s[70:71]
	s_waitcnt vmcnt(8)
	s_waitcnt lgkmcnt(0)
	s_barrier
	s_waitcnt lgkmcnt(7)
	v_mfma_f32_16x16x32_bf16 v[32:35], v[0:3], v[16:19], v[124:127]
	s_waitcnt lgkmcnt(6)
	v_mfma_f32_16x16x32_bf16 v[120:123], v[8:11], v[24:27], v[32:35]
	v_mfma_f32_16x16x32_bf16 v[32:35], v[160:163], v[16:19], v[204:207]
	v_mfma_f32_16x16x32_bf16 v[112:115], v[164:167], v[24:27], v[32:35]
	s_waitcnt lgkmcnt(5)
	v_mfma_f32_16x16x32_bf16 v[32:35], v[0:3], v[36:39], v[116:119]
	s_waitcnt lgkmcnt(4)
	v_mfma_f32_16x16x32_bf16 v[104:107], v[8:11], v[44:47], v[32:35]
	v_mfma_f32_16x16x32_bf16 v[32:35], v[160:163], v[36:39], v[208:211]
	v_mfma_f32_16x16x32_bf16 v[96:99], v[164:167], v[44:47], v[32:35]
	s_waitcnt lgkmcnt(3)
	v_mfma_f32_16x16x32_bf16 v[32:35], v[0:3], v[68:71], v[108:111]
	s_waitcnt lgkmcnt(2)
	v_mfma_f32_16x16x32_bf16 v[72:75], v[8:11], v[224:227], v[32:35]
	v_mfma_f32_16x16x32_bf16 v[32:35], v[160:163], v[68:71], v[212:215]
	v_mfma_f32_16x16x32_bf16 v[64:67], v[164:167], v[224:227], v[32:35]
	s_waitcnt lgkmcnt(1)
	v_mfma_f32_16x16x32_bf16 v[32:35], v[0:3], v[228:231], v[100:103]
	s_waitcnt lgkmcnt(0)
	v_mfma_f32_16x16x32_bf16 v[40:43], v[8:11], v[232:235], v[32:35]
	v_mfma_f32_16x16x32_bf16 v[32:35], v[160:163], v[228:231], v[216:219]
	v_mfma_f32_16x16x32_bf16 v[32:35], v[164:167], v[232:235], v[32:35]
	v_mfma_f32_16x16x32_bf16 v[92:95], v[168:171], v[16:19], v[92:95]
	v_mfma_f32_16x16x32_bf16 v[16:19], v[200:203], v[16:19], v[88:91]
	v_mfma_f32_16x16x32_bf16 v[116:119], v[220:223], v[24:27], v[16:19]
	v_mfma_f32_16x16x32_bf16 v[16:19], v[168:171], v[36:39], v[84:87]
	v_mfma_f32_16x16x32_bf16 v[108:111], v[184:187], v[44:47], v[16:19]
	v_mfma_f32_16x16x32_bf16 v[16:19], v[200:203], v[36:39], v[80:83]
	v_mfma_f32_16x16x32_bf16 v[100:103], v[220:223], v[44:47], v[16:19]
	v_mfma_f32_16x16x32_bf16 v[16:19], v[168:171], v[68:71], v[76:79]
	v_mfma_f32_16x16x32_bf16 v[76:79], v[184:187], v[224:227], v[16:19]
	v_mfma_f32_16x16x32_bf16 v[16:19], v[200:203], v[68:71], v[172:175]
	v_mfma_f32_16x16x32_bf16 v[68:71], v[220:223], v[224:227], v[16:19]
	v_mfma_f32_16x16x32_bf16 v[16:19], v[168:171], v[228:231], v[176:179]
	v_mfma_f32_16x16x32_bf16 v[44:47], v[184:187], v[232:235], v[16:19]
	v_mfma_f32_16x16x32_bf16 v[16:19], v[200:203], v[228:231], v[180:183]
	v_mfma_f32_16x16x32_bf16 v[124:127], v[184:187], v[24:27], v[92:95]
	v_mfma_f32_16x16x32_bf16 v[36:39], v[220:223], v[232:235], v[16:19]
	s_barrier
	s_add_u32 s54, s6, 0x80
	s_addc_u32 s55, s7, 0
	s_add_u32 s38, s38, 0x80
	ds_read_b128 v[84:87], v137 offset:49152
	ds_read_b128 v[172:175], v137 offset:50176
	ds_read_b128 v[176:179], v137 offset:51200
	ds_read_b128 v[180:183], v137 offset:52224
	ds_read_b128 v[204:207], v137 offset:53248
	ds_read_b128 v[208:211], v137 offset:54272
	ds_read_b128 v[212:215], v137 offset:55296
	ds_read_b128 v[216:219], v137 offset:56320
	s_addc_u32 s39, s39, 0
	s_mov_b32 m0, s61
	s_nop 0
	global_load_lds_dwordx4 v131, s[54:55]
	s_nop 0
	s_mov_b32 m0, s62
	s_nop 0
	global_load_lds_dwordx4 v131, s[38:39]
	s_add_u32 s38, s40, 0x80
	s_addc_u32 s39, s41, 0
	s_add_u32 s40, s48, 0x80
	s_addc_u32 s41, s49, 0
	s_mov_b32 m0, s65
	s_nop 0
	global_load_lds_dwordx4 v131, s[38:39]
	s_add_u32 s38, s46, 0x80
	s_mov_b32 m0, s66
	s_nop 0
	global_load_lds_dwordx4 v131, s[40:41]
	s_addc_u32 s39, s47, 0
	s_add_u32 s4, s4, 0x80
	s_mov_b32 m0, s63
	s_nop 0
	global_load_lds_dwordx4 v130, s[38:39]
	s_addc_u32 s5, s5, 0
	s_mov_b32 m0, s64
	s_nop 0
	global_load_lds_dwordx4 v130, s[4:5]
	s_waitcnt vmcnt(8)
	s_waitcnt lgkmcnt(0)
	s_barrier
	s_waitcnt lgkmcnt(7)
	v_mfma_f32_16x16x32_bf16 v[16:19], v[0:3], v[84:87], v[60:63]
	s_waitcnt lgkmcnt(6)
	v_mfma_f32_16x16x32_bf16 v[88:91], v[8:11], v[172:175], v[16:19]
	v_mfma_f32_16x16x32_bf16 v[16:19], v[160:163], v[84:87], v[56:59]
	v_mfma_f32_16x16x32_bf16 v[80:83], v[164:167], v[172:175], v[16:19]
	s_waitcnt lgkmcnt(5)
	v_mfma_f32_16x16x32_bf16 v[16:19], v[0:3], v[176:179], v[52:55]
	s_waitcnt lgkmcnt(4)
	v_mfma_f32_16x16x32_bf16 v[56:59], v[8:11], v[180:183], v[16:19]
	v_mfma_f32_16x16x32_bf16 v[16:19], v[160:163], v[176:179], v[48:51]
	v_mfma_f32_16x16x32_bf16 v[48:51], v[164:167], v[180:183], v[16:19]
	s_waitcnt lgkmcnt(3)
	v_mfma_f32_16x16x32_bf16 v[16:19], v[0:3], v[204:207], v[188:191]
	s_waitcnt lgkmcnt(1)
	v_mfma_f32_16x16x32_bf16 v[0:3], v[0:3], v[212:215], v[140:143]
	v_mfma_f32_16x16x32_bf16 v[24:27], v[8:11], v[208:211], v[16:19]
	v_mfma_f32_16x16x32_bf16 v[16:19], v[160:163], v[204:207], v[192:195]
	s_waitcnt lgkmcnt(0)
	v_mfma_f32_16x16x32_bf16 v[8:11], v[8:11], v[216:219], v[0:3]
	v_mfma_f32_16x16x32_bf16 v[0:3], v[160:163], v[212:215], v[144:147]
	v_mfma_f32_16x16x32_bf16 v[16:19], v[164:167], v[208:211], v[16:19]
	v_mfma_f32_16x16x32_bf16 v[0:3], v[164:167], v[216:219], v[0:3]
	v_mfma_f32_16x16x32_bf16 v[28:31], v[168:171], v[84:87], v[28:31]
	v_mfma_f32_16x16x32_bf16 v[92:95], v[184:187], v[172:175], v[28:31]
	v_mfma_f32_16x16x32_bf16 v[28:31], v[200:203], v[84:87], v[148:151]
	v_mfma_f32_16x16x32_bf16 v[20:23], v[168:171], v[176:179], v[20:23]
	v_mfma_f32_16x16x32_bf16 v[12:15], v[168:171], v[204:207], v[12:15]
	v_mfma_f32_16x16x32_bf16 v[84:87], v[220:223], v[172:175], v[28:31]
	v_mfma_f32_16x16x32_bf16 v[60:63], v[184:187], v[180:183], v[20:23]
	v_mfma_f32_16x16x32_bf16 v[20:23], v[200:203], v[176:179], v[152:155]
	v_mfma_f32_16x16x32_bf16 v[28:31], v[184:187], v[208:211], v[12:15]
	v_mfma_f32_16x16x32_bf16 v[12:15], v[200:203], v[204:207], v[196:199]
	v_mfma_f32_16x16x32_bf16 v[4:7], v[168:171], v[212:215], v[4:7]
	v_mfma_f32_16x16x32_bf16 v[52:55], v[220:223], v[180:183], v[20:23]
	v_mfma_f32_16x16x32_bf16 v[20:23], v[220:223], v[208:211], v[12:15]
	v_mfma_f32_16x16x32_bf16 v[12:15], v[184:187], v[216:219], v[4:7]
	v_mfma_f32_16x16x32_bf16 v[4:7], v[200:203], v[212:215], v[156:159]
	v_mfma_f32_16x16x32_bf16 v[4:7], v[220:223], v[216:219], v[4:7]
	s_barrier
	s_andn2_b64 vcc, exec, s[26:27]
	s_cbranch_vccnz .LBB0_262
	s_barrier

.LBB0_269:
	v_and_b32_e32 v1, 15, v2
	s_lshl_b64 s[48:49], s[8:9], 7
	s_lshl_b64 s[18:19], s[18:19], 7
	v_or_b32_e32 v3, s3, v1
	v_lshlrev_b32_e32 v5, 6, v3
	v_and_b32_e32 v6, 48, v2
	s_movk_i32 s2, 0x3c0
	s_add_u32 s8, s6, 0x80
	v_ashrrev_i32_e32 v4, 6, v2
	v_and_or_b32 v5, v5, s2, v6
	v_readlane_b32 s2, v254, 55
	s_addc_u32 s9, s7, 0
	v_lshl_add_u32 v7, v4, 10, s95
	v_add_lshl_u32 v4, v4, s2, 10
	s_sub_u32 s2, 0, s0
	s_subb_u32 s20, 0, s1
	s_add_u32 s2, s10, s2
	s_addc_u32 s21, s11, s20
	s_add_u32 s20, s2, 0x80
	s_addc_u32 s21, s21, 0
	s_add_i32 s65, s53, 0x18000
	s_add_i32 s66, s53, 0x1a000
	s_mov_b32 s98, 0
	s_cselect_b32 s99, 1, 0
	s_cmp_lt_u32 s76, 4
	s_cbranch_scc0 .Lsprio_2
	s_setprio 1
.Lsprio_2:
	s_cmp_lg_u32 s99, 0
	s_waitcnt vmcnt(2)
	s_barrier
	s_mov_b32 m0, s65
	s_nop 0
	global_load_lds_dwordx4 v0, s[8:9]
	s_add_u32 s8, s4, 0x80
	s_mov_b32 m0, s66
	s_nop 0
	global_load_lds_dwordx4 v0, s[20:21]
	s_addc_u32 s9, s5, 0
	s_sub_u32 s2, 0, s46
	s_subb_u32 s20, 0, s47
	s_add_u32 s2, s14, s2
	s_addc_u32 s15, s15, s20
	s_add_u32 s14, s2, 0x80
	s_addc_u32 s15, s15, 0
	s_add_i32 s67, s53, 0x8000
	s_add_i32 s73, s53, 0xa000
	s_mov_b32 m0, s67
	s_nop 0
	global_load_lds_dwordx4 v128, s[8:9]
	s_add_u32 s8, s10, 0x80
	s_addc_u32 s9, s11, 0
	s_mov_b32 m0, s73
	s_nop 0
	global_load_lds_dwordx4 v128, s[14:15]
	s_add_u32 s10, s12, 0x80
	v_lshlrev_b32_e32 v2, 2, v2
	s_addc_u32 s11, s13, 0
	s_add_i32 s78, s53, 0x1c000
	s_mov_b32 m0, s78
	s_nop 0
	global_load_lds_dwordx4 v0, s[8:9]
	v_lshlrev_b32_e32 v3, 2, v3
	v_lshl_or_b32 v1, v1, 6, v6
	v_and_b32_e32 v2, 32, v2
	s_add_i32 s79, s53, 0x1e000
	s_mov_b32 m0, s79
	s_nop 0
	global_load_lds_dwordx4 v0, s[10:11]
	v_and_b32_e32 v3, 32, v3
	v_bitop3_b32 v1, v1, v4, v2 bitop3:0xde
	s_waitcnt vmcnt(6)
	s_add_i32 s82, s53, 0xc000
	s_add_i32 s83, s53, 0xe000
	v_readlane_b32 s2, v254, 0
	v_mov_b32_e32 v129, v0
	v_bitop3_b32 v3, v5, v7, v3 bitop3:0xde
	s_cmpk_lt_u32 s2, 0x100
	v_add_u32_e32 v0, 0, v1
	s_mov_b32 s21, 0
	s_cselect_b64 s[22:23], -1, 0
	v_add_u32_e32 v143, 0x10000, v0
	v_add_u32_e32 v144, 0x14000, v0
	v_add_u32_e32 v145, 0, v3
	v_add_u32_e32 v146, 0x18000, v0
	v_add_u32_e32 v147, 0x1c000, v0
	s_mov_b32 s34, s31
	s_mov_b32 s31, 0
	s_barrier
	s_branch .LBB0_272

.LBB0_274:
	s_cmp_lt_i32 s28, 3
	s_cbranch_scc1 .Lhz_276
	s_add_i32 s2, s28, -2
	s_add_u32 s20, s4, s48
	s_addc_u32 s33, s5, s49
	s_add_u32 s42, s6, s18
	s_addc_u32 s43, s7, s19
	s_add_u32 s38, s0, s18
	s_addc_u32 s39, s1, s19
	s_add_u32 s50, s6, s38
	s_addc_u32 s51, s7, s39
	s_add_u32 s68, s6, s0
	s_addc_u32 s69, s7, s1
	s_add_u32 s38, s46, s48
	s_addc_u32 s39, s47, s49
	s_add_u32 s70, s4, s38
	s_addc_u32 s71, s5, s39
	s_add_u32 s72, s4, s46
	s_addc_u32 s74, s5, s47
	s_mov_b32 s75, 0
	s_mov_b64 s[38:39], 0
	s_cmp_eq_u32 s98, 0
	s_cbranch_scc1 .Lhf_276
	ds_read_b128 v[130:133], v143
	ds_read_b128 v[134:137], v143 offset:1024
	ds_read_b128 v[138:141], v143 offset:2048
	ds_read_b128 v[148:151], v143 offset:3072
	ds_read_b128 v[152:155], v144
	ds_read_b128 v[156:159], v144 offset:1024
	ds_read_b128 v[160:163], v144 offset:2048
	ds_read_b128 v[164:167], v144 offset:3072
	s_add_i32 s75, s75, 2
	s_add_u32 s77, s4, s38
	s_addc_u32 s80, s5, s39
	s_add_u32 s40, s77, 0x100
	s_addc_u32 s41, s80, 0
	s_add_u32 s81, s20, s38
	ds_read_b128 v[168:171], v145
	ds_read_b128 v[172:175], v145 offset:1024
	ds_read_b128 v[176:179], v145 offset:2048
	ds_read_b128 v[180:183], v145 offset:3072
	ds_read_b128 v[184:187], v145 offset:4096
	ds_read_b128 v[188:191], v145 offset:5120
	ds_read_b128 v[192:195], v145 offset:6144
	ds_read_b128 v[196:199], v145 offset:7168
	s_addc_u32 s86, s33, s39
	s_add_u32 s54, s81, 0x80
	s_addc_u32 s55, s86, 0
	s_add_u32 s87, s70, s38
	s_addc_u32 s88, s71, s39
	s_add_u32 s84, s87, 0x80
	s_mov_b32 m0, s82
	s_nop 0
	global_load_lds_dwordx4 v128, s[54:55]
	s_addc_u32 s85, s88, 0
	s_mov_b32 m0, s83
	s_nop 0
	global_load_lds_dwordx4 v128, s[84:85]
	s_waitcnt vmcnt(24)
	s_waitcnt lgkmcnt(0)
	s_barrier
	s_waitcnt lgkmcnt(7)
	v_mfma_f32_16x16x32_bf16 v[124:127], v[130:133], v[168:171], 0
	v_mfma_f32_16x16x32_bf16 v[120:123], v[138:141], v[168:171], 0
	s_waitcnt lgkmcnt(5)
	v_mfma_f32_16x16x32_bf16 v[116:119], v[130:133], v[176:179], 0
	v_mfma_f32_16x16x32_bf16 v[112:115], v[138:141], v[176:179], 0
	s_waitcnt lgkmcnt(3)
	v_mfma_f32_16x16x32_bf16 v[108:111], v[130:133], v[184:187], 0
	v_mfma_f32_16x16x32_bf16 v[104:107], v[138:141], v[184:187], 0
	s_waitcnt lgkmcnt(1)
	v_mfma_f32_16x16x32_bf16 v[100:103], v[130:133], v[192:195], 0
	v_mfma_f32_16x16x32_bf16 v[96:99], v[138:141], v[192:195], 0
	v_mfma_f32_16x16x32_bf16 v[124:127], v[134:137], v[172:175], v[124:127]
	v_mfma_f32_16x16x32_bf16 v[120:123], v[148:151], v[172:175], v[120:123]
	v_mfma_f32_16x16x32_bf16 v[116:119], v[134:137], v[180:183], v[116:119]
	v_mfma_f32_16x16x32_bf16 v[112:115], v[148:151], v[180:183], v[112:115]
	v_mfma_f32_16x16x32_bf16 v[108:111], v[134:137], v[188:191], v[108:111]
	v_mfma_f32_16x16x32_bf16 v[104:107], v[148:151], v[188:191], v[104:107]
	s_waitcnt lgkmcnt(0)
	v_mfma_f32_16x16x32_bf16 v[100:103], v[134:137], v[196:199], v[100:103]
	v_mfma_f32_16x16x32_bf16 v[96:99], v[148:151], v[196:199], v[96:99]
	v_mfma_f32_16x16x32_bf16 v[92:95], v[152:155], v[168:171], 0
	v_mfma_f32_16x16x32_bf16 v[88:91], v[160:163], v[168:171], 0
	v_mfma_f32_16x16x32_bf16 v[84:87], v[152:155], v[176:179], 0
	v_mfma_f32_16x16x32_bf16 v[80:83], v[160:163], v[176:179], 0
	v_mfma_f32_16x16x32_bf16 v[76:79], v[152:155], v[184:187], 0
	v_mfma_f32_16x16x32_bf16 v[72:75], v[160:163], v[184:187], 0
	v_mfma_f32_16x16x32_bf16 v[68:71], v[152:155], v[192:195], 0
	v_mfma_f32_16x16x32_bf16 v[64:67], v[160:163], v[192:195], 0
	v_mfma_f32_16x16x32_bf16 v[92:95], v[156:159], v[172:175], v[92:95]
	v_mfma_f32_16x16x32_bf16 v[88:91], v[164:167], v[172:175], v[88:91]
	v_mfma_f32_16x16x32_bf16 v[84:87], v[156:159], v[180:183], v[84:87]
	v_mfma_f32_16x16x32_bf16 v[80:83], v[164:167], v[180:183], v[80:83]
	v_mfma_f32_16x16x32_bf16 v[76:79], v[156:159], v[188:191], v[76:79]
	v_mfma_f32_16x16x32_bf16 v[72:75], v[164:167], v[188:191], v[72:75]
	v_mfma_f32_16x16x32_bf16 v[68:71], v[156:159], v[196:199], v[68:71]
	v_mfma_f32_16x16x32_bf16 v[64:67], v[164:167], v[196:199], v[64:67]
	s_barrier
	s_add_u32 s89, s6, s38
	s_addc_u32 s90, s7, s39
	s_add_u32 s54, s89, 0x100
	s_addc_u32 s55, s90, 0
	s_add_u32 s91, s68, s38
	s_addc_u32 s92, s69, s39
	s_add_u32 s84, s91, 0x100
	ds_read_b128 v[168:171], v145 offset:16384
	ds_read_b128 v[172:175], v145 offset:17408
	ds_read_b128 v[176:179], v145 offset:18432
	ds_read_b128 v[180:183], v145 offset:19456
	ds_read_b128 v[184:187], v145 offset:20480
	ds_read_b128 v[188:191], v145 offset:21504
	ds_read_b128 v[192:195], v145 offset:22528
	ds_read_b128 v[196:199], v145 offset:23552
	s_addc_u32 s85, s92, 0
	s_mov_b32 m0, s58
	s_nop 0
	global_load_lds_dwordx4 v129, s[54:55]
	s_add_u32 s93, s42, s38
	s_mov_b32 m0, s59
	s_nop 0
	global_load_lds_dwordx4 v129, s[84:85]
	s_addc_u32 s94, s43, s39
	s_add_u32 s54, s93, 0x100
	s_addc_u32 s55, s94, 0
	s_add_u32 s96, s50, s38
	s_addc_u32 s97, s51, s39
	s_add_u32 s84, s96, 0x100
	s_addc_u32 s85, s97, 0
	s_mov_b32 m0, s60
	s_nop 0
	global_load_lds_dwordx4 v129, s[54:55]
	s_mov_b32 m0, s61
	s_nop 0
	global_load_lds_dwordx4 v129, s[84:85]
	s_add_u32 s84, s72, s38
	s_addc_u32 s85, s74, s39
	s_add_u32 s54, s84, 0x100
	s_mov_b32 m0, s53
	s_nop 0
	global_load_lds_dwordx4 v128, s[40:41]
	s_addc_u32 s55, s85, 0
	s_mov_b32 m0, s62
	s_nop 0
	global_load_lds_dwordx4 v128, s[54:55]
	s_waitcnt vmcnt(24)
	s_waitcnt lgkmcnt(0)
	s_barrier
	s_waitcnt lgkmcnt(7)
	v_mfma_f32_16x16x32_bf16 v[60:63], v[130:133], v[168:171], 0
	v_mfma_f32_16x16x32_bf16 v[56:59], v[138:141], v[168:171], 0
	s_waitcnt lgkmcnt(5)
	v_mfma_f32_16x16x32_bf16 v[52:55], v[130:133], v[176:179], 0
	v_mfma_f32_16x16x32_bf16 v[48:51], v[138:141], v[176:179], 0
	s_waitcnt lgkmcnt(3)
	v_mfma_f32_16x16x32_bf16 v[44:47], v[130:133], v[184:187], 0
	v_mfma_f32_16x16x32_bf16 v[40:43], v[138:141], v[184:187], 0
	s_waitcnt lgkmcnt(1)
	v_mfma_f32_16x16x32_bf16 v[36:39], v[130:133], v[192:195], 0
	v_mfma_f32_16x16x32_bf16 v[32:35], v[138:141], v[192:195], 0
	v_mfma_f32_16x16x32_bf16 v[60:63], v[134:137], v[172:175], v[60:63]
	v_mfma_f32_16x16x32_bf16 v[56:59], v[148:151], v[172:175], v[56:59]
	v_mfma_f32_16x16x32_bf16 v[52:55], v[134:137], v[180:183], v[52:55]
	v_mfma_f32_16x16x32_bf16 v[48:51], v[148:151], v[180:183], v[48:51]
	v_mfma_f32_16x16x32_bf16 v[44:47], v[134:137], v[188:191], v[44:47]
	v_mfma_f32_16x16x32_bf16 v[40:43], v[148:151], v[188:191], v[40:43]
	s_waitcnt lgkmcnt(0)
	v_mfma_f32_16x16x32_bf16 v[36:39], v[134:137], v[196:199], v[36:39]
	v_mfma_f32_16x16x32_bf16 v[32:35], v[148:151], v[196:199], v[32:35]
	v_mfma_f32_16x16x32_bf16 v[28:31], v[152:155], v[168:171], 0
	v_mfma_f32_16x16x32_bf16 v[24:27], v[160:163], v[168:171], 0
	v_mfma_f32_16x16x32_bf16 v[20:23], v[152:155], v[176:179], 0
	v_mfma_f32_16x16x32_bf16 v[16:19], v[160:163], v[176:179], 0
	v_mfma_f32_16x16x32_bf16 v[12:15], v[152:155], v[184:187], 0
	v_mfma_f32_16x16x32_bf16 v[8:11], v[160:163], v[184:187], 0
	v_mfma_f32_16x16x32_bf16 v[4:7], v[152:155], v[192:195], 0
	v_mfma_f32_16x16x32_bf16 v[0:3], v[160:163], v[192:195], 0
	v_mfma_f32_16x16x32_bf16 v[28:31], v[156:159], v[172:175], v[28:31]
	v_mfma_f32_16x16x32_bf16 v[24:27], v[164:167], v[172:175], v[24:27]
	v_mfma_f32_16x16x32_bf16 v[20:23], v[156:159], v[180:183], v[20:23]
	v_mfma_f32_16x16x32_bf16 v[16:19], v[164:167], v[180:183], v[16:19]
	v_mfma_f32_16x16x32_bf16 v[12:15], v[156:159], v[188:191], v[12:15]
	v_mfma_f32_16x16x32_bf16 v[8:11], v[164:167], v[188:191], v[8:11]
	v_mfma_f32_16x16x32_bf16 v[4:7], v[156:159], v[196:199], v[4:7]
	v_mfma_f32_16x16x32_bf16 v[0:3], v[164:167], v[196:199], v[0:3]
	s_barrier
	ds_read_b128 v[130:133], v146
	ds_read_b128 v[134:137], v146 offset:1024
	ds_read_b128 v[138:141], v146 offset:2048
	ds_read_b128 v[148:151], v146 offset:3072
	ds_read_b128 v[152:155], v147
	ds_read_b128 v[156:159], v147 offset:1024
	ds_read_b128 v[160:163], v147 offset:2048
	ds_read_b128 v[164:167], v147 offset:3072
	ds_read_b128 v[168:171], v145 offset:32768
	ds_read_b128 v[172:175], v145 offset:33792
	ds_read_b128 v[176:179], v145 offset:34816
	ds_read_b128 v[180:183], v145 offset:35840
	ds_read_b128 v[184:187], v145 offset:36864
	ds_read_b128 v[188:191], v145 offset:37888
	ds_read_b128 v[192:195], v145 offset:38912
	ds_read_b128 v[196:199], v145 offset:39936
	s_add_u32 s40, s81, 0x100
	s_addc_u32 s41, s86, 0
	s_add_u32 s54, s87, 0x100
	s_mov_b32 m0, s63
	s_nop 0
	global_load_lds_dwordx4 v128, s[40:41]
	s_addc_u32 s55, s88, 0
	s_mov_b32 m0, s64
	s_nop 0
	global_load_lds_dwordx4 v128, s[54:55]
	s_waitcnt vmcnt(8)
	s_waitcnt lgkmcnt(0)
	s_barrier
	s_waitcnt lgkmcnt(7)
	v_mfma_f32_16x16x32_bf16 v[124:127], v[130:133], v[168:171], v[124:127]
	v_mfma_f32_16x16x32_bf16 v[120:123], v[138:141], v[168:171], v[120:123]
	s_waitcnt lgkmcnt(5)
	v_mfma_f32_16x16x32_bf16 v[116:119], v[130:133], v[176:179], v[116:119]
	v_mfma_f32_16x16x32_bf16 v[112:115], v[138:141], v[176:179], v[112:115]
	s_waitcnt lgkmcnt(3)
	v_mfma_f32_16x16x32_bf16 v[108:111], v[130:133], v[184:187], v[108:111]
	v_mfma_f32_16x16x32_bf16 v[104:107], v[138:141], v[184:187], v[104:107]
	s_waitcnt lgkmcnt(1)
	v_mfma_f32_16x16x32_bf16 v[100:103], v[130:133], v[192:195], v[100:103]
	v_mfma_f32_16x16x32_bf16 v[96:99], v[138:141], v[192:195], v[96:99]
	v_mfma_f32_16x16x32_bf16 v[124:127], v[134:137], v[172:175], v[124:127]
	v_mfma_f32_16x16x32_bf16 v[120:123], v[148:151], v[172:175], v[120:123]
	v_mfma_f32_16x16x32_bf16 v[116:119], v[134:137], v[180:183], v[116:119]
	v_mfma_f32_16x16x32_bf16 v[112:115], v[148:151], v[180:183], v[112:115]
	v_mfma_f32_16x16x32_bf16 v[108:111], v[134:137], v[188:191], v[108:111]
	v_mfma_f32_16x16x32_bf16 v[104:107], v[148:151], v[188:191], v[104:107]
	s_waitcnt lgkmcnt(0)
	v_mfma_f32_16x16x32_bf16 v[100:103], v[134:137], v[196:199], v[100:103]
	v_mfma_f32_16x16x32_bf16 v[96:99], v[148:151], v[196:199], v[96:99]
	v_mfma_f32_16x16x32_bf16 v[92:95], v[152:155], v[168:171], v[92:95]
	v_mfma_f32_16x16x32_bf16 v[88:91], v[160:163], v[168:171], v[88:91]
	v_mfma_f32_16x16x32_bf16 v[84:87], v[152:155], v[176:179], v[84:87]
	v_mfma_f32_16x16x32_bf16 v[80:83], v[160:163], v[176:179], v[80:83]
	v_mfma_f32_16x16x32_bf16 v[76:79], v[152:155], v[184:187], v[76:79]
	v_mfma_f32_16x16x32_bf16 v[72:75], v[160:163], v[184:187], v[72:75]
	v_mfma_f32_16x16x32_bf16 v[68:71], v[152:155], v[192:195], v[68:71]
	v_mfma_f32_16x16x32_bf16 v[64:67], v[160:163], v[192:195], v[64:67]
	v_mfma_f32_16x16x32_bf16 v[92:95], v[156:159], v[172:175], v[92:95]
	v_mfma_f32_16x16x32_bf16 v[88:91], v[164:167], v[172:175], v[88:91]
	v_mfma_f32_16x16x32_bf16 v[84:87], v[156:159], v[180:183], v[84:87]
	v_mfma_f32_16x16x32_bf16 v[80:83], v[164:167], v[180:183], v[80:83]
	v_mfma_f32_16x16x32_bf16 v[76:79], v[156:159], v[188:191], v[76:79]
	v_mfma_f32_16x16x32_bf16 v[72:75], v[164:167], v[188:191], v[72:75]
	v_mfma_f32_16x16x32_bf16 v[68:71], v[156:159], v[196:199], v[68:71]
	v_mfma_f32_16x16x32_bf16 v[64:67], v[164:167], v[196:199], v[64:67]
	s_barrier
	s_add_u32 s40, s89, 0x180
	s_addc_u32 s41, s90, 0
	ds_read_b128 v[168:171], v145 offset:49152
	ds_read_b128 v[172:175], v145 offset:50176
	ds_read_b128 v[176:179], v145 offset:51200
	ds_read_b128 v[180:183], v145 offset:52224
	ds_read_b128 v[184:187], v145 offset:53248
	ds_read_b128 v[188:191], v145 offset:54272
	ds_read_b128 v[192:195], v145 offset:55296
	ds_read_b128 v[196:199], v145 offset:56320
	s_add_u32 s54, s91, 0x180
	s_mov_b32 m0, s65
	s_nop 0
	global_load_lds_dwordx4 v129, s[40:41]
	s_addc_u32 s55, s92, 0
	s_mov_b32 m0, s66
	s_nop 0
	global_load_lds_dwordx4 v129, s[54:55]
	s_add_u32 s40, s93, 0x180
	s_addc_u32 s41, s94, 0
	s_add_u32 s54, s96, 0x180
	s_mov_b32 m0, s78
	s_nop 0
	global_load_lds_dwordx4 v129, s[40:41]
	s_addc_u32 s55, s97, 0
	s_mov_b32 m0, s79
	s_nop 0
	global_load_lds_dwordx4 v129, s[54:55]
	s_add_u32 s40, s77, 0x180
	s_addc_u32 s41, s80, 0
	s_add_u32 s54, s84, 0x180
	s_mov_b32 m0, s67
	s_nop 0
	global_load_lds_dwordx4 v128, s[40:41]
	s_addc_u32 s55, s85, 0
	s_mov_b32 m0, s73
	s_nop 0
	global_load_lds_dwordx4 v128, s[54:55]
	s_waitcnt vmcnt(8)
	s_waitcnt lgkmcnt(0)
	s_barrier
	s_waitcnt lgkmcnt(7)
	v_mfma_f32_16x16x32_bf16 v[60:63], v[130:133], v[168:171], v[60:63]
	v_mfma_f32_16x16x32_bf16 v[56:59], v[138:141], v[168:171], v[56:59]
	s_waitcnt lgkmcnt(5)
	v_mfma_f32_16x16x32_bf16 v[52:55], v[130:133], v[176:179], v[52:55]
	v_mfma_f32_16x16x32_bf16 v[48:51], v[138:141], v[176:179], v[48:51]
	s_waitcnt lgkmcnt(3)
	v_mfma_f32_16x16x32_bf16 v[44:47], v[130:133], v[184:187], v[44:47]
	v_mfma_f32_16x16x32_bf16 v[40:43], v[138:141], v[184:187], v[40:43]
	s_waitcnt lgkmcnt(1)
	v_mfma_f32_16x16x32_bf16 v[36:39], v[130:133], v[192:195], v[36:39]
	v_mfma_f32_16x16x32_bf16 v[32:35], v[138:141], v[192:195], v[32:35]
	v_mfma_f32_16x16x32_bf16 v[60:63], v[134:137], v[172:175], v[60:63]
	v_mfma_f32_16x16x32_bf16 v[56:59], v[148:151], v[172:175], v[56:59]
	v_mfma_f32_16x16x32_bf16 v[52:55], v[134:137], v[180:183], v[52:55]
	v_mfma_f32_16x16x32_bf16 v[48:51], v[148:151], v[180:183], v[48:51]
	v_mfma_f32_16x16x32_bf16 v[44:47], v[134:137], v[188:191], v[44:47]
	v_mfma_f32_16x16x32_bf16 v[40:43], v[148:151], v[188:191], v[40:43]
	s_waitcnt lgkmcnt(0)
	v_mfma_f32_16x16x32_bf16 v[36:39], v[134:137], v[196:199], v[36:39]
	v_mfma_f32_16x16x32_bf16 v[32:35], v[148:151], v[196:199], v[32:35]
	v_mfma_f32_16x16x32_bf16 v[28:31], v[152:155], v[168:171], v[28:31]
	v_mfma_f32_16x16x32_bf16 v[24:27], v[160:163], v[168:171], v[24:27]
	v_mfma_f32_16x16x32_bf16 v[20:23], v[152:155], v[176:179], v[20:23]
	v_mfma_f32_16x16x32_bf16 v[16:19], v[160:163], v[176:179], v[16:19]
	v_mfma_f32_16x16x32_bf16 v[12:15], v[152:155], v[184:187], v[12:15]
	v_mfma_f32_16x16x32_bf16 v[8:11], v[160:163], v[184:187], v[8:11]
	v_mfma_f32_16x16x32_bf16 v[4:7], v[152:155], v[192:195], v[4:7]
	v_mfma_f32_16x16x32_bf16 v[0:3], v[160:163], v[192:195], v[0:3]
	v_mfma_f32_16x16x32_bf16 v[28:31], v[156:159], v[172:175], v[28:31]
	v_mfma_f32_16x16x32_bf16 v[24:27], v[164:167], v[172:175], v[24:27]
	v_mfma_f32_16x16x32_bf16 v[20:23], v[156:159], v[180:183], v[20:23]
	v_mfma_f32_16x16x32_bf16 v[16:19], v[164:167], v[180:183], v[16:19]
	v_mfma_f32_16x16x32_bf16 v[12:15], v[156:159], v[188:191], v[12:15]
	v_mfma_f32_16x16x32_bf16 v[8:11], v[164:167], v[188:191], v[8:11]
	v_mfma_f32_16x16x32_bf16 v[4:7], v[156:159], v[196:199], v[4:7]
	v_mfma_f32_16x16x32_bf16 v[0:3], v[164:167], v[196:199], v[0:3]
	s_barrier
	s_add_u32 s38, s38, 0x100
	s_addc_u32 s39, s39, 0
	s_cmp_ge_i32 s75, s2
	s_cbranch_scc0 .LBB0_276
	s_branch .LBB0_277
.Lhf_276:
	ds_read_b128 v[130:133], v143
	ds_read_b128 v[134:137], v143 offset:1024
	ds_read_b128 v[138:141], v143 offset:2048
	ds_read_b128 v[148:151], v143 offset:3072
	ds_read_b128 v[152:155], v144
	ds_read_b128 v[156:159], v144 offset:1024
	ds_read_b128 v[160:163], v144 offset:2048
	ds_read_b128 v[164:167], v144 offset:3072
	s_add_i32 s75, s75, 2
	s_add_u32 s77, s4, s38
	s_addc_u32 s80, s5, s39
	s_add_u32 s40, s77, 0x100
	s_addc_u32 s41, s80, 0
	s_add_u32 s81, s20, s38
	ds_read_b128 v[168:171], v145
	ds_read_b128 v[172:175], v145 offset:1024
	ds_read_b128 v[176:179], v145 offset:2048
	ds_read_b128 v[180:183], v145 offset:3072
	ds_read_b128 v[184:187], v145 offset:4096
	ds_read_b128 v[188:191], v145 offset:5120
	ds_read_b128 v[192:195], v145 offset:6144
	ds_read_b128 v[196:199], v145 offset:7168
	s_addc_u32 s86, s33, s39
	s_add_u32 s54, s81, 0x80
	s_addc_u32 s55, s86, 0
	s_add_u32 s87, s70, s38
	s_addc_u32 s88, s71, s39
	s_add_u32 s84, s87, 0x80
	s_mov_b32 m0, s82
	s_nop 0
	global_load_lds_dwordx4 v128, s[54:55]
	s_addc_u32 s85, s88, 0
	s_mov_b32 m0, s83
	s_nop 0
	global_load_lds_dwordx4 v128, s[84:85]
	s_waitcnt vmcnt(8)
	s_waitcnt lgkmcnt(0)
	s_barrier
	s_waitcnt lgkmcnt(7)
	v_mfma_f32_16x16x32_bf16 v[124:127], v[130:133], v[168:171], 0
	v_mfma_f32_16x16x32_bf16 v[120:123], v[138:141], v[168:171], 0
	s_waitcnt lgkmcnt(5)
	v_mfma_f32_16x16x32_bf16 v[116:119], v[130:133], v[176:179], 0
	v_mfma_f32_16x16x32_bf16 v[112:115], v[138:141], v[176:179], 0
	s_waitcnt lgkmcnt(3)
	v_mfma_f32_16x16x32_bf16 v[108:111], v[130:133], v[184:187], 0
	v_mfma_f32_16x16x32_bf16 v[104:107], v[138:141], v[184:187], 0
	s_waitcnt lgkmcnt(1)
	v_mfma_f32_16x16x32_bf16 v[100:103], v[130:133], v[192:195], 0
	v_mfma_f32_16x16x32_bf16 v[96:99], v[138:141], v[192:195], 0
	v_mfma_f32_16x16x32_bf16 v[124:127], v[134:137], v[172:175], v[124:127]
	v_mfma_f32_16x16x32_bf16 v[120:123], v[148:151], v[172:175], v[120:123]
	v_mfma_f32_16x16x32_bf16 v[116:119], v[134:137], v[180:183], v[116:119]
	v_mfma_f32_16x16x32_bf16 v[112:115], v[148:151], v[180:183], v[112:115]
	v_mfma_f32_16x16x32_bf16 v[108:111], v[134:137], v[188:191], v[108:111]
	v_mfma_f32_16x16x32_bf16 v[104:107], v[148:151], v[188:191], v[104:107]
	s_waitcnt lgkmcnt(0)
	v_mfma_f32_16x16x32_bf16 v[100:103], v[134:137], v[196:199], v[100:103]
	v_mfma_f32_16x16x32_bf16 v[96:99], v[148:151], v[196:199], v[96:99]
	v_mfma_f32_16x16x32_bf16 v[92:95], v[152:155], v[168:171], 0
	v_mfma_f32_16x16x32_bf16 v[88:91], v[160:163], v[168:171], 0
	v_mfma_f32_16x16x32_bf16 v[84:87], v[152:155], v[176:179], 0
	v_mfma_f32_16x16x32_bf16 v[80:83], v[160:163], v[176:179], 0
	v_mfma_f32_16x16x32_bf16 v[76:79], v[152:155], v[184:187], 0
	v_mfma_f32_16x16x32_bf16 v[72:75], v[160:163], v[184:187], 0
	v_mfma_f32_16x16x32_bf16 v[68:71], v[152:155], v[192:195], 0
	v_mfma_f32_16x16x32_bf16 v[64:67], v[160:163], v[192:195], 0
	v_mfma_f32_16x16x32_bf16 v[92:95], v[156:159], v[172:175], v[92:95]
	v_mfma_f32_16x16x32_bf16 v[88:91], v[164:167], v[172:175], v[88:91]
	v_mfma_f32_16x16x32_bf16 v[84:87], v[156:159], v[180:183], v[84:87]
	v_mfma_f32_16x16x32_bf16 v[80:83], v[164:167], v[180:183], v[80:83]
	v_mfma_f32_16x16x32_bf16 v[76:79], v[156:159], v[188:191], v[76:79]
	v_mfma_f32_16x16x32_bf16 v[72:75], v[164:167], v[188:191], v[72:75]
	v_mfma_f32_16x16x32_bf16 v[68:71], v[156:159], v[196:199], v[68:71]
	v_mfma_f32_16x16x32_bf16 v[64:67], v[164:167], v[196:199], v[64:67]
	s_barrier
	s_add_u32 s89, s6, s38
	s_addc_u32 s90, s7, s39
	s_add_u32 s54, s89, 0x100
	s_addc_u32 s55, s90, 0
	s_add_u32 s91, s68, s38
	s_addc_u32 s92, s69, s39
	s_add_u32 s84, s91, 0x100
	ds_read_b128 v[168:171], v145 offset:16384
	ds_read_b128 v[172:175], v145 offset:17408
	ds_read_b128 v[176:179], v145 offset:18432
	ds_read_b128 v[180:183], v145 offset:19456
	ds_read_b128 v[184:187], v145 offset:20480
	ds_read_b128 v[188:191], v145 offset:21504
	ds_read_b128 v[192:195], v145 offset:22528
	ds_read_b128 v[196:199], v145 offset:23552
	s_addc_u32 s85, s92, 0
	s_mov_b32 m0, s58
	s_nop 0
	global_load_lds_dwordx4 v129, s[54:55]
	s_add_u32 s93, s42, s38
	s_mov_b32 m0, s59
	s_nop 0
	global_load_lds_dwordx4 v129, s[84:85]
	s_addc_u32 s94, s43, s39
	s_add_u32 s54, s93, 0x100
	s_addc_u32 s55, s94, 0
	s_add_u32 s96, s50, s38
	s_addc_u32 s97, s51, s39
	s_add_u32 s84, s96, 0x100
	s_addc_u32 s85, s97, 0
	s_mov_b32 m0, s60
	s_nop 0
	global_load_lds_dwordx4 v129, s[54:55]
	s_mov_b32 m0, s61
	s_nop 0
	global_load_lds_dwordx4 v129, s[84:85]
	s_add_u32 s84, s72, s38
	s_addc_u32 s85, s74, s39
	s_add_u32 s54, s84, 0x100
	s_mov_b32 m0, s53
	s_nop 0
	global_load_lds_dwordx4 v128, s[40:41]
	s_addc_u32 s55, s85, 0
	s_mov_b32 m0, s62
	s_nop 0
	global_load_lds_dwordx4 v128, s[54:55]
	s_waitcnt vmcnt(8)
	s_waitcnt lgkmcnt(0)
	s_barrier
	s_waitcnt lgkmcnt(7)
	v_mfma_f32_16x16x32_bf16 v[60:63], v[130:133], v[168:171], 0
	v_mfma_f32_16x16x32_bf16 v[56:59], v[138:141], v[168:171], 0
	s_waitcnt lgkmcnt(5)
	v_mfma_f32_16x16x32_bf16 v[52:55], v[130:133], v[176:179], 0
	v_mfma_f32_16x16x32_bf16 v[48:51], v[138:141], v[176:179], 0
	s_waitcnt lgkmcnt(3)
	v_mfma_f32_16x16x32_bf16 v[44:47], v[130:133], v[184:187], 0
	v_mfma_f32_16x16x32_bf16 v[40:43], v[138:141], v[184:187], 0
	s_waitcnt lgkmcnt(1)
	v_mfma_f32_16x16x32_bf16 v[36:39], v[130:133], v[192:195], 0
	v_mfma_f32_16x16x32_bf16 v[32:35], v[138:141], v[192:195], 0
	v_mfma_f32_16x16x32_bf16 v[60:63], v[134:137], v[172:175], v[60:63]
	v_mfma_f32_16x16x32_bf16 v[56:59], v[148:151], v[172:175], v[56:59]
	v_mfma_f32_16x16x32_bf16 v[52:55], v[134:137], v[180:183], v[52:55]
	v_mfma_f32_16x16x32_bf16 v[48:51], v[148:151], v[180:183], v[48:51]
	v_mfma_f32_16x16x32_bf16 v[44:47], v[134:137], v[188:191], v[44:47]
	v_mfma_f32_16x16x32_bf16 v[40:43], v[148:151], v[188:191], v[40:43]
	s_waitcnt lgkmcnt(0)
	v_mfma_f32_16x16x32_bf16 v[36:39], v[134:137], v[196:199], v[36:39]
	v_mfma_f32_16x16x32_bf16 v[32:35], v[148:151], v[196:199], v[32:35]
	v_mfma_f32_16x16x32_bf16 v[28:31], v[152:155], v[168:171], 0
	v_mfma_f32_16x16x32_bf16 v[24:27], v[160:163], v[168:171], 0
	v_mfma_f32_16x16x32_bf16 v[20:23], v[152:155], v[176:179], 0
	v_mfma_f32_16x16x32_bf16 v[16:19], v[160:163], v[176:179], 0
	v_mfma_f32_16x16x32_bf16 v[12:15], v[152:155], v[184:187], 0
	v_mfma_f32_16x16x32_bf16 v[8:11], v[160:163], v[184:187], 0
	v_mfma_f32_16x16x32_bf16 v[4:7], v[152:155], v[192:195], 0
	v_mfma_f32_16x16x32_bf16 v[0:3], v[160:163], v[192:195], 0
	v_mfma_f32_16x16x32_bf16 v[28:31], v[156:159], v[172:175], v[28:31]
	v_mfma_f32_16x16x32_bf16 v[24:27], v[164:167], v[172:175], v[24:27]
	v_mfma_f32_16x16x32_bf16 v[20:23], v[156:159], v[180:183], v[20:23]
	v_mfma_f32_16x16x32_bf16 v[16:19], v[164:167], v[180:183], v[16:19]
	v_mfma_f32_16x16x32_bf16 v[12:15], v[156:159], v[188:191], v[12:15]
	v_mfma_f32_16x16x32_bf16 v[8:11], v[164:167], v[188:191], v[8:11]
	v_mfma_f32_16x16x32_bf16 v[4:7], v[156:159], v[196:199], v[4:7]
	v_mfma_f32_16x16x32_bf16 v[0:3], v[164:167], v[196:199], v[0:3]
	s_barrier
	ds_read_b128 v[130:133], v146
	ds_read_b128 v[134:137], v146 offset:1024
	ds_read_b128 v[138:141], v146 offset:2048
	ds_read_b128 v[148:151], v146 offset:3072
	ds_read_b128 v[152:155], v147
	ds_read_b128 v[156:159], v147 offset:1024
	ds_read_b128 v[160:163], v147 offset:2048
	ds_read_b128 v[164:167], v147 offset:3072
	ds_read_b128 v[168:171], v145 offset:32768
	ds_read_b128 v[172:175], v145 offset:33792
	ds_read_b128 v[176:179], v145 offset:34816
	ds_read_b128 v[180:183], v145 offset:35840
	ds_read_b128 v[184:187], v145 offset:36864
	ds_read_b128 v[188:191], v145 offset:37888
	ds_read_b128 v[192:195], v145 offset:38912
	ds_read_b128 v[196:199], v145 offset:39936
	s_add_u32 s40, s81, 0x100
	s_addc_u32 s41, s86, 0
	s_add_u32 s54, s87, 0x100
	s_mov_b32 m0, s63
	s_nop 0
	global_load_lds_dwordx4 v128, s[40:41]
	s_addc_u32 s55, s88, 0
	s_mov_b32 m0, s64
	s_nop 0
	global_load_lds_dwordx4 v128, s[54:55]
	s_waitcnt vmcnt(8)
	s_waitcnt lgkmcnt(0)
	s_barrier
	s_waitcnt lgkmcnt(7)
	v_mfma_f32_16x16x32_bf16 v[124:127], v[130:133], v[168:171], v[124:127]
	v_mfma_f32_16x16x32_bf16 v[120:123], v[138:141], v[168:171], v[120:123]
	s_waitcnt lgkmcnt(5)
	v_mfma_f32_16x16x32_bf16 v[116:119], v[130:133], v[176:179], v[116:119]
	v_mfma_f32_16x16x32_bf16 v[112:115], v[138:141], v[176:179], v[112:115]
	s_waitcnt lgkmcnt(3)
	v_mfma_f32_16x16x32_bf16 v[108:111], v[130:133], v[184:187], v[108:111]
	v_mfma_f32_16x16x32_bf16 v[104:107], v[138:141], v[184:187], v[104:107]
	s_waitcnt lgkmcnt(1)
	v_mfma_f32_16x16x32_bf16 v[100:103], v[130:133], v[192:195], v[100:103]
	v_mfma_f32_16x16x32_bf16 v[96:99], v[138:141], v[192:195], v[96:99]
	v_mfma_f32_16x16x32_bf16 v[124:127], v[134:137], v[172:175], v[124:127]
	v_mfma_f32_16x16x32_bf16 v[120:123], v[148:151], v[172:175], v[120:123]
	v_mfma_f32_16x16x32_bf16 v[116:119], v[134:137], v[180:183], v[116:119]
	v_mfma_f32_16x16x32_bf16 v[112:115], v[148:151], v[180:183], v[112:115]
	v_mfma_f32_16x16x32_bf16 v[108:111], v[134:137], v[188:191], v[108:111]
	v_mfma_f32_16x16x32_bf16 v[104:107], v[148:151], v[188:191], v[104:107]
	s_waitcnt lgkmcnt(0)
	v_mfma_f32_16x16x32_bf16 v[100:103], v[134:137], v[196:199], v[100:103]
	v_mfma_f32_16x16x32_bf16 v[96:99], v[148:151], v[196:199], v[96:99]
	v_mfma_f32_16x16x32_bf16 v[92:95], v[152:155], v[168:171], v[92:95]
	v_mfma_f32_16x16x32_bf16 v[88:91], v[160:163], v[168:171], v[88:91]
	v_mfma_f32_16x16x32_bf16 v[84:87], v[152:155], v[176:179], v[84:87]
	v_mfma_f32_16x16x32_bf16 v[80:83], v[160:163], v[176:179], v[80:83]
	v_mfma_f32_16x16x32_bf16 v[76:79], v[152:155], v[184:187], v[76:79]
	v_mfma_f32_16x16x32_bf16 v[72:75], v[160:163], v[184:187], v[72:75]
	v_mfma_f32_16x16x32_bf16 v[68:71], v[152:155], v[192:195], v[68:71]
	v_mfma_f32_16x16x32_bf16 v[64:67], v[160:163], v[192:195], v[64:67]
	v_mfma_f32_16x16x32_bf16 v[92:95], v[156:159], v[172:175], v[92:95]
	v_mfma_f32_16x16x32_bf16 v[88:91], v[164:167], v[172:175], v[88:91]
	v_mfma_f32_16x16x32_bf16 v[84:87], v[156:159], v[180:183], v[84:87]
	v_mfma_f32_16x16x32_bf16 v[80:83], v[164:167], v[180:183], v[80:83]
	v_mfma_f32_16x16x32_bf16 v[76:79], v[156:159], v[188:191], v[76:79]
	v_mfma_f32_16x16x32_bf16 v[72:75], v[164:167], v[188:191], v[72:75]
	v_mfma_f32_16x16x32_bf16 v[68:71], v[156:159], v[196:199], v[68:71]
	v_mfma_f32_16x16x32_bf16 v[64:67], v[164:167], v[196:199], v[64:67]
	s_barrier
	s_add_u32 s40, s89, 0x180
	s_addc_u32 s41, s90, 0
	ds_read_b128 v[168:171], v145 offset:49152
	ds_read_b128 v[172:175], v145 offset:50176
	ds_read_b128 v[176:179], v145 offset:51200
	ds_read_b128 v[180:183], v145 offset:52224
	ds_read_b128 v[184:187], v145 offset:53248
	ds_read_b128 v[188:191], v145 offset:54272
	ds_read_b128 v[192:195], v145 offset:55296
	ds_read_b128 v[196:199], v145 offset:56320
	s_add_u32 s54, s91, 0x180
	s_mov_b32 m0, s65
	s_nop 0
	global_load_lds_dwordx4 v129, s[40:41]
	s_addc_u32 s55, s92, 0
	s_mov_b32 m0, s66
	s_nop 0
	global_load_lds_dwordx4 v129, s[54:55]
	s_add_u32 s40, s93, 0x180
	s_addc_u32 s41, s94, 0
	s_add_u32 s54, s96, 0x180
	s_mov_b32 m0, s78
	s_nop 0
	global_load_lds_dwordx4 v129, s[40:41]
	s_addc_u32 s55, s97, 0
	s_mov_b32 m0, s79
	s_nop 0
	global_load_lds_dwordx4 v129, s[54:55]
	s_add_u32 s40, s77, 0x180
	s_addc_u32 s41, s80, 0
	s_add_u32 s54, s84, 0x180
	s_mov_b32 m0, s67
	s_nop 0
	global_load_lds_dwordx4 v128, s[40:41]
	s_addc_u32 s55, s85, 0
	s_mov_b32 m0, s73
	s_nop 0
	global_load_lds_dwordx4 v128, s[54:55]
	s_waitcnt vmcnt(8)
	s_waitcnt lgkmcnt(0)
	s_barrier
	s_waitcnt lgkmcnt(7)
	v_mfma_f32_16x16x32_bf16 v[60:63], v[130:133], v[168:171], v[60:63]
	v_mfma_f32_16x16x32_bf16 v[56:59], v[138:141], v[168:171], v[56:59]
	s_waitcnt lgkmcnt(5)
	v_mfma_f32_16x16x32_bf16 v[52:55], v[130:133], v[176:179], v[52:55]
	v_mfma_f32_16x16x32_bf16 v[48:51], v[138:141], v[176:179], v[48:51]
	s_waitcnt lgkmcnt(3)
	v_mfma_f32_16x16x32_bf16 v[44:47], v[130:133], v[184:187], v[44:47]
	v_mfma_f32_16x16x32_bf16 v[40:43], v[138:141], v[184:187], v[40:43]
	s_waitcnt lgkmcnt(1)
	v_mfma_f32_16x16x32_bf16 v[36:39], v[130:133], v[192:195], v[36:39]
	v_mfma_f32_16x16x32_bf16 v[32:35], v[138:141], v[192:195], v[32:35]
	v_mfma_f32_16x16x32_bf16 v[60:63], v[134:137], v[172:175], v[60:63]
	v_mfma_f32_16x16x32_bf16 v[56:59], v[148:151], v[172:175], v[56:59]
	v_mfma_f32_16x16x32_bf16 v[52:55], v[134:137], v[180:183], v[52:55]
	v_mfma_f32_16x16x32_bf16 v[48:51], v[148:151], v[180:183], v[48:51]
	v_mfma_f32_16x16x32_bf16 v[44:47], v[134:137], v[188:191], v[44:47]
	v_mfma_f32_16x16x32_bf16 v[40:43], v[148:151], v[188:191], v[40:43]
	s_waitcnt lgkmcnt(0)
	v_mfma_f32_16x16x32_bf16 v[36:39], v[134:137], v[196:199], v[36:39]
	v_mfma_f32_16x16x32_bf16 v[32:35], v[148:151], v[196:199], v[32:35]
	v_mfma_f32_16x16x32_bf16 v[28:31], v[152:155], v[168:171], v[28:31]
	v_mfma_f32_16x16x32_bf16 v[24:27], v[160:163], v[168:171], v[24:27]
	v_mfma_f32_16x16x32_bf16 v[20:23], v[152:155], v[176:179], v[20:23]
	v_mfma_f32_16x16x32_bf16 v[16:19], v[160:163], v[176:179], v[16:19]
	v_mfma_f32_16x16x32_bf16 v[12:15], v[152:155], v[184:187], v[12:15]
	v_mfma_f32_16x16x32_bf16 v[8:11], v[160:163], v[184:187], v[8:11]
	v_mfma_f32_16x16x32_bf16 v[4:7], v[152:155], v[192:195], v[4:7]
	v_mfma_f32_16x16x32_bf16 v[0:3], v[160:163], v[192:195], v[0:3]
	v_mfma_f32_16x16x32_bf16 v[28:31], v[156:159], v[172:175], v[28:31]
	v_mfma_f32_16x16x32_bf16 v[24:27], v[164:167], v[172:175], v[24:27]
	v_mfma_f32_16x16x32_bf16 v[20:23], v[156:159], v[180:183], v[20:23]
	v_mfma_f32_16x16x32_bf16 v[16:19], v[164:167], v[180:183], v[16:19]
	v_mfma_f32_16x16x32_bf16 v[12:15], v[156:159], v[188:191], v[12:15]
	v_mfma_f32_16x16x32_bf16 v[8:11], v[164:167], v[188:191], v[8:11]
	v_mfma_f32_16x16x32_bf16 v[4:7], v[156:159], v[196:199], v[4:7]
	v_mfma_f32_16x16x32_bf16 v[0:3], v[164:167], v[196:199], v[0:3]
	s_barrier
	s_add_u32 s38, s38, 0x100
	s_addc_u32 s39, s39, 0
	s_cmp_ge_i32 s75, s2
	s_cbranch_scc0 .LBB0_276
	s_branch .LBB0_277

.LBB0_276:
	ds_read_b128 v[130:133], v143
	ds_read_b128 v[134:137], v143 offset:1024
	ds_read_b128 v[138:141], v143 offset:2048
	ds_read_b128 v[148:151], v143 offset:3072
	ds_read_b128 v[152:155], v144
	ds_read_b128 v[156:159], v144 offset:1024
	ds_read_b128 v[160:163], v144 offset:2048
	ds_read_b128 v[164:167], v144 offset:3072
	s_add_i32 s75, s75, 2
	s_add_u32 s77, s4, s38
	s_addc_u32 s80, s5, s39
	s_add_u32 s40, s77, 0x100
	s_addc_u32 s41, s80, 0
	s_add_u32 s81, s20, s38
	ds_read_b128 v[168:171], v145
	ds_read_b128 v[172:175], v145 offset:1024
	ds_read_b128 v[176:179], v145 offset:2048
	ds_read_b128 v[180:183], v145 offset:3072
	ds_read_b128 v[184:187], v145 offset:4096
	ds_read_b128 v[188:191], v145 offset:5120
	ds_read_b128 v[192:195], v145 offset:6144
	ds_read_b128 v[196:199], v145 offset:7168
	s_addc_u32 s86, s33, s39
	s_add_u32 s54, s81, 0x80
	s_addc_u32 s55, s86, 0
	s_add_u32 s87, s70, s38
	s_addc_u32 s88, s71, s39
	s_add_u32 s84, s87, 0x80
	s_mov_b32 m0, s82
	s_nop 0
	global_load_lds_dwordx4 v128, s[54:55]
	s_addc_u32 s85, s88, 0
	s_mov_b32 m0, s83
	s_nop 0
	global_load_lds_dwordx4 v128, s[84:85]
	s_waitcnt vmcnt(8)
	s_waitcnt lgkmcnt(0)
	s_barrier
	s_waitcnt lgkmcnt(7)
	v_mfma_f32_16x16x32_bf16 v[124:127], v[130:133], v[168:171], v[124:127]
	v_mfma_f32_16x16x32_bf16 v[120:123], v[138:141], v[168:171], v[120:123]
	s_waitcnt lgkmcnt(5)
	v_mfma_f32_16x16x32_bf16 v[116:119], v[130:133], v[176:179], v[116:119]
	v_mfma_f32_16x16x32_bf16 v[112:115], v[138:141], v[176:179], v[112:115]
	s_waitcnt lgkmcnt(3)
	v_mfma_f32_16x16x32_bf16 v[108:111], v[130:133], v[184:187], v[108:111]
	v_mfma_f32_16x16x32_bf16 v[104:107], v[138:141], v[184:187], v[104:107]
	s_waitcnt lgkmcnt(1)
	v_mfma_f32_16x16x32_bf16 v[100:103], v[130:133], v[192:195], v[100:103]
	v_mfma_f32_16x16x32_bf16 v[96:99], v[138:141], v[192:195], v[96:99]
	v_mfma_f32_16x16x32_bf16 v[124:127], v[134:137], v[172:175], v[124:127]
	v_mfma_f32_16x16x32_bf16 v[120:123], v[148:151], v[172:175], v[120:123]
	v_mfma_f32_16x16x32_bf16 v[116:119], v[134:137], v[180:183], v[116:119]
	v_mfma_f32_16x16x32_bf16 v[112:115], v[148:151], v[180:183], v[112:115]
	v_mfma_f32_16x16x32_bf16 v[108:111], v[134:137], v[188:191], v[108:111]
	v_mfma_f32_16x16x32_bf16 v[104:107], v[148:151], v[188:191], v[104:107]
	s_waitcnt lgkmcnt(0)
	v_mfma_f32_16x16x32_bf16 v[100:103], v[134:137], v[196:199], v[100:103]
	v_mfma_f32_16x16x32_bf16 v[96:99], v[148:151], v[196:199], v[96:99]
	v_mfma_f32_16x16x32_bf16 v[92:95], v[152:155], v[168:171], v[92:95]
	v_mfma_f32_16x16x32_bf16 v[88:91], v[160:163], v[168:171], v[88:91]
	v_mfma_f32_16x16x32_bf16 v[84:87], v[152:155], v[176:179], v[84:87]
	v_mfma_f32_16x16x32_bf16 v[80:83], v[160:163], v[176:179], v[80:83]
	v_mfma_f32_16x16x32_bf16 v[76:79], v[152:155], v[184:187], v[76:79]
	v_mfma_f32_16x16x32_bf16 v[72:75], v[160:163], v[184:187], v[72:75]
	v_mfma_f32_16x16x32_bf16 v[68:71], v[152:155], v[192:195], v[68:71]
	v_mfma_f32_16x16x32_bf16 v[64:67], v[160:163], v[192:195], v[64:67]
	v_mfma_f32_16x16x32_bf16 v[92:95], v[156:159], v[172:175], v[92:95]
	v_mfma_f32_16x16x32_bf16 v[88:91], v[164:167], v[172:175], v[88:91]
	v_mfma_f32_16x16x32_bf16 v[84:87], v[156:159], v[180:183], v[84:87]
	v_mfma_f32_16x16x32_bf16 v[80:83], v[164:167], v[180:183], v[80:83]
	v_mfma_f32_16x16x32_bf16 v[76:79], v[156:159], v[188:191], v[76:79]
	v_mfma_f32_16x16x32_bf16 v[72:75], v[164:167], v[188:191], v[72:75]
	v_mfma_f32_16x16x32_bf16 v[68:71], v[156:159], v[196:199], v[68:71]
	v_mfma_f32_16x16x32_bf16 v[64:67], v[164:167], v[196:199], v[64:67]
	s_barrier
	s_add_u32 s89, s6, s38
	s_addc_u32 s90, s7, s39
	s_add_u32 s54, s89, 0x100
	s_addc_u32 s55, s90, 0
	s_add_u32 s91, s68, s38
	s_addc_u32 s92, s69, s39
	s_add_u32 s84, s91, 0x100
	ds_read_b128 v[168:171], v145 offset:16384
	ds_read_b128 v[172:175], v145 offset:17408
	ds_read_b128 v[176:179], v145 offset:18432
	ds_read_b128 v[180:183], v145 offset:19456
	ds_read_b128 v[184:187], v145 offset:20480
	ds_read_b128 v[188:191], v145 offset:21504
	ds_read_b128 v[192:195], v145 offset:22528
	ds_read_b128 v[196:199], v145 offset:23552
	s_addc_u32 s85, s92, 0
	s_mov_b32 m0, s58
	s_nop 0
	global_load_lds_dwordx4 v129, s[54:55]
	s_add_u32 s93, s42, s38
	s_mov_b32 m0, s59
	s_nop 0
	global_load_lds_dwordx4 v129, s[84:85]
	s_addc_u32 s94, s43, s39
	s_add_u32 s54, s93, 0x100
	s_addc_u32 s55, s94, 0
	s_add_u32 s96, s50, s38
	s_addc_u32 s97, s51, s39
	s_add_u32 s84, s96, 0x100
	s_addc_u32 s85, s97, 0
	s_mov_b32 m0, s60
	s_nop 0
	global_load_lds_dwordx4 v129, s[54:55]
	s_mov_b32 m0, s61
	s_nop 0
	global_load_lds_dwordx4 v129, s[84:85]
	s_add_u32 s84, s72, s38
	s_addc_u32 s85, s74, s39
	s_add_u32 s54, s84, 0x100
	s_mov_b32 m0, s53
	s_nop 0
	global_load_lds_dwordx4 v128, s[40:41]
	s_addc_u32 s55, s85, 0
	s_mov_b32 m0, s62
	s_nop 0
	global_load_lds_dwordx4 v128, s[54:55]
	s_waitcnt vmcnt(8)
	s_waitcnt lgkmcnt(0)
	s_barrier
	s_waitcnt lgkmcnt(7)
	v_mfma_f32_16x16x32_bf16 v[60:63], v[130:133], v[168:171], v[60:63]
	v_mfma_f32_16x16x32_bf16 v[56:59], v[138:141], v[168:171], v[56:59]
	s_waitcnt lgkmcnt(5)
	v_mfma_f32_16x16x32_bf16 v[52:55], v[130:133], v[176:179], v[52:55]
	v_mfma_f32_16x16x32_bf16 v[48:51], v[138:141], v[176:179], v[48:51]
	s_waitcnt lgkmcnt(3)
	v_mfma_f32_16x16x32_bf16 v[44:47], v[130:133], v[184:187], v[44:47]
	v_mfma_f32_16x16x32_bf16 v[40:43], v[138:141], v[184:187], v[40:43]
	s_waitcnt lgkmcnt(1)
	v_mfma_f32_16x16x32_bf16 v[36:39], v[130:133], v[192:195], v[36:39]
	v_mfma_f32_16x16x32_bf16 v[32:35], v[138:141], v[192:195], v[32:35]
	v_mfma_f32_16x16x32_bf16 v[60:63], v[134:137], v[172:175], v[60:63]
	v_mfma_f32_16x16x32_bf16 v[56:59], v[148:151], v[172:175], v[56:59]
	v_mfma_f32_16x16x32_bf16 v[52:55], v[134:137], v[180:183], v[52:55]
	v_mfma_f32_16x16x32_bf16 v[48:51], v[148:151], v[180:183], v[48:51]
	v_mfma_f32_16x16x32_bf16 v[44:47], v[134:137], v[188:191], v[44:47]
	v_mfma_f32_16x16x32_bf16 v[40:43], v[148:151], v[188:191], v[40:43]
	s_waitcnt lgkmcnt(0)
	v_mfma_f32_16x16x32_bf16 v[36:39], v[134:137], v[196:199], v[36:39]
	v_mfma_f32_16x16x32_bf16 v[32:35], v[148:151], v[196:199], v[32:35]
	v_mfma_f32_16x16x32_bf16 v[28:31], v[152:155], v[168:171], v[28:31]
	v_mfma_f32_16x16x32_bf16 v[24:27], v[160:163], v[168:171], v[24:27]
	v_mfma_f32_16x16x32_bf16 v[20:23], v[152:155], v[176:179], v[20:23]
	v_mfma_f32_16x16x32_bf16 v[16:19], v[160:163], v[176:179], v[16:19]
	v_mfma_f32_16x16x32_bf16 v[12:15], v[152:155], v[184:187], v[12:15]
	v_mfma_f32_16x16x32_bf16 v[8:11], v[160:163], v[184:187], v[8:11]
	v_mfma_f32_16x16x32_bf16 v[4:7], v[152:155], v[192:195], v[4:7]
	v_mfma_f32_16x16x32_bf16 v[0:3], v[160:163], v[192:195], v[0:3]
	v_mfma_f32_16x16x32_bf16 v[28:31], v[156:159], v[172:175], v[28:31]
	v_mfma_f32_16x16x32_bf16 v[24:27], v[164:167], v[172:175], v[24:27]
	v_mfma_f32_16x16x32_bf16 v[20:23], v[156:159], v[180:183], v[20:23]
	v_mfma_f32_16x16x32_bf16 v[16:19], v[164:167], v[180:183], v[16:19]
	v_mfma_f32_16x16x32_bf16 v[12:15], v[156:159], v[188:191], v[12:15]
	v_mfma_f32_16x16x32_bf16 v[8:11], v[164:167], v[188:191], v[8:11]
	v_mfma_f32_16x16x32_bf16 v[4:7], v[156:159], v[196:199], v[4:7]
	v_mfma_f32_16x16x32_bf16 v[0:3], v[164:167], v[196:199], v[0:3]
	s_barrier
	ds_read_b128 v[130:133], v146
	ds_read_b128 v[134:137], v146 offset:1024
	ds_read_b128 v[138:141], v146 offset:2048
	ds_read_b128 v[148:151], v146 offset:3072
	ds_read_b128 v[152:155], v147
	ds_read_b128 v[156:159], v147 offset:1024
	ds_read_b128 v[160:163], v147 offset:2048
	ds_read_b128 v[164:167], v147 offset:3072
	ds_read_b128 v[168:171], v145 offset:32768
	ds_read_b128 v[172:175], v145 offset:33792
	ds_read_b128 v[176:179], v145 offset:34816
	ds_read_b128 v[180:183], v145 offset:35840
	ds_read_b128 v[184:187], v145 offset:36864
	ds_read_b128 v[188:191], v145 offset:37888
	ds_read_b128 v[192:195], v145 offset:38912
	ds_read_b128 v[196:199], v145 offset:39936
	s_add_u32 s40, s81, 0x100
	s_addc_u32 s41, s86, 0
	s_add_u32 s54, s87, 0x100
	s_mov_b32 m0, s63
	s_nop 0
	global_load_lds_dwordx4 v128, s[40:41]
	s_addc_u32 s55, s88, 0
	s_mov_b32 m0, s64
	s_nop 0
	global_load_lds_dwordx4 v128, s[54:55]
	s_waitcnt vmcnt(8)
	s_waitcnt lgkmcnt(0)
	s_barrier
	s_waitcnt lgkmcnt(7)
	v_mfma_f32_16x16x32_bf16 v[124:127], v[130:133], v[168:171], v[124:127]
	v_mfma_f32_16x16x32_bf16 v[120:123], v[138:141], v[168:171], v[120:123]
	s_waitcnt lgkmcnt(5)
	v_mfma_f32_16x16x32_bf16 v[116:119], v[130:133], v[176:179], v[116:119]
	v_mfma_f32_16x16x32_bf16 v[112:115], v[138:141], v[176:179], v[112:115]
	s_waitcnt lgkmcnt(3)
	v_mfma_f32_16x16x32_bf16 v[108:111], v[130:133], v[184:187], v[108:111]
	v_mfma_f32_16x16x32_bf16 v[104:107], v[138:141], v[184:187], v[104:107]
	s_waitcnt lgkmcnt(1)
	v_mfma_f32_16x16x32_bf16 v[100:103], v[130:133], v[192:195], v[100:103]
	v_mfma_f32_16x16x32_bf16 v[96:99], v[138:141], v[192:195], v[96:99]
	v_mfma_f32_16x16x32_bf16 v[124:127], v[134:137], v[172:175], v[124:127]
	v_mfma_f32_16x16x32_bf16 v[120:123], v[148:151], v[172:175], v[120:123]
	v_mfma_f32_16x16x32_bf16 v[116:119], v[134:137], v[180:183], v[116:119]
	v_mfma_f32_16x16x32_bf16 v[112:115], v[148:151], v[180:183], v[112:115]
	v_mfma_f32_16x16x32_bf16 v[108:111], v[134:137], v[188:191], v[108:111]
	v_mfma_f32_16x16x32_bf16 v[104:107], v[148:151], v[188:191], v[104:107]
	s_waitcnt lgkmcnt(0)
	v_mfma_f32_16x16x32_bf16 v[100:103], v[134:137], v[196:199], v[100:103]
	v_mfma_f32_16x16x32_bf16 v[96:99], v[148:151], v[196:199], v[96:99]
	v_mfma_f32_16x16x32_bf16 v[92:95], v[152:155], v[168:171], v[92:95]
	v_mfma_f32_16x16x32_bf16 v[88:91], v[160:163], v[168:171], v[88:91]
	v_mfma_f32_16x16x32_bf16 v[84:87], v[152:155], v[176:179], v[84:87]
	v_mfma_f32_16x16x32_bf16 v[80:83], v[160:163], v[176:179], v[80:83]
	v_mfma_f32_16x16x32_bf16 v[76:79], v[152:155], v[184:187], v[76:79]
	v_mfma_f32_16x16x32_bf16 v[72:75], v[160:163], v[184:187], v[72:75]
	v_mfma_f32_16x16x32_bf16 v[68:71], v[152:155], v[192:195], v[68:71]
	v_mfma_f32_16x16x32_bf16 v[64:67], v[160:163], v[192:195], v[64:67]
	v_mfma_f32_16x16x32_bf16 v[92:95], v[156:159], v[172:175], v[92:95]
	v_mfma_f32_16x16x32_bf16 v[88:91], v[164:167], v[172:175], v[88:91]
	v_mfma_f32_16x16x32_bf16 v[84:87], v[156:159], v[180:183], v[84:87]
	v_mfma_f32_16x16x32_bf16 v[80:83], v[164:167], v[180:183], v[80:83]
	v_mfma_f32_16x16x32_bf16 v[76:79], v[156:159], v[188:191], v[76:79]
	v_mfma_f32_16x16x32_bf16 v[72:75], v[164:167], v[188:191], v[72:75]
	v_mfma_f32_16x16x32_bf16 v[68:71], v[156:159], v[196:199], v[68:71]
	v_mfma_f32_16x16x32_bf16 v[64:67], v[164:167], v[196:199], v[64:67]
	s_barrier
	s_add_u32 s40, s89, 0x180
	s_addc_u32 s41, s90, 0
	ds_read_b128 v[168:171], v145 offset:49152
	ds_read_b128 v[172:175], v145 offset:50176
	ds_read_b128 v[176:179], v145 offset:51200
	ds_read_b128 v[180:183], v145 offset:52224
	ds_read_b128 v[184:187], v145 offset:53248
	ds_read_b128 v[188:191], v145 offset:54272
	ds_read_b128 v[192:195], v145 offset:55296
	ds_read_b128 v[196:199], v145 offset:56320
	s_add_u32 s54, s91, 0x180
	s_mov_b32 m0, s65
	s_nop 0
	global_load_lds_dwordx4 v129, s[40:41]
	s_addc_u32 s55, s92, 0
	s_mov_b32 m0, s66
	s_nop 0
	global_load_lds_dwordx4 v129, s[54:55]
	s_add_u32 s40, s93, 0x180
	s_addc_u32 s41, s94, 0
	s_add_u32 s54, s96, 0x180
	s_mov_b32 m0, s78
	s_nop 0
	global_load_lds_dwordx4 v129, s[40:41]
	s_addc_u32 s55, s97, 0
	s_mov_b32 m0, s79
	s_nop 0
	global_load_lds_dwordx4 v129, s[54:55]
	s_add_u32 s40, s77, 0x180
	s_addc_u32 s41, s80, 0
	s_add_u32 s54, s84, 0x180
	s_mov_b32 m0, s67
	s_nop 0
	global_load_lds_dwordx4 v128, s[40:41]
	s_addc_u32 s55, s85, 0
	s_mov_b32 m0, s73
	s_nop 0
	global_load_lds_dwordx4 v128, s[54:55]
	s_waitcnt vmcnt(8)
	s_waitcnt lgkmcnt(0)
	s_barrier
	s_waitcnt lgkmcnt(7)
	v_mfma_f32_16x16x32_bf16 v[60:63], v[130:133], v[168:171], v[60:63]
	v_mfma_f32_16x16x32_bf16 v[56:59], v[138:141], v[168:171], v[56:59]
	s_waitcnt lgkmcnt(5)
	v_mfma_f32_16x16x32_bf16 v[52:55], v[130:133], v[176:179], v[52:55]
	v_mfma_f32_16x16x32_bf16 v[48:51], v[138:141], v[176:179], v[48:51]
	s_waitcnt lgkmcnt(3)
	v_mfma_f32_16x16x32_bf16 v[44:47], v[130:133], v[184:187], v[44:47]
	v_mfma_f32_16x16x32_bf16 v[40:43], v[138:141], v[184:187], v[40:43]
	s_waitcnt lgkmcnt(1)
	v_mfma_f32_16x16x32_bf16 v[36:39], v[130:133], v[192:195], v[36:39]
	v_mfma_f32_16x16x32_bf16 v[32:35], v[138:141], v[192:195], v[32:35]
	v_mfma_f32_16x16x32_bf16 v[60:63], v[134:137], v[172:175], v[60:63]
	v_mfma_f32_16x16x32_bf16 v[56:59], v[148:151], v[172:175], v[56:59]
	v_mfma_f32_16x16x32_bf16 v[52:55], v[134:137], v[180:183], v[52:55]
	v_mfma_f32_16x16x32_bf16 v[48:51], v[148:151], v[180:183], v[48:51]
	v_mfma_f32_16x16x32_bf16 v[44:47], v[134:137], v[188:191], v[44:47]
	v_mfma_f32_16x16x32_bf16 v[40:43], v[148:151], v[188:191], v[40:43]
	s_waitcnt lgkmcnt(0)
	v_mfma_f32_16x16x32_bf16 v[36:39], v[134:137], v[196:199], v[36:39]
	v_mfma_f32_16x16x32_bf16 v[32:35], v[148:151], v[196:199], v[32:35]
	v_mfma_f32_16x16x32_bf16 v[28:31], v[152:155], v[168:171], v[28:31]
	v_mfma_f32_16x16x32_bf16 v[24:27], v[160:163], v[168:171], v[24:27]
	v_mfma_f32_16x16x32_bf16 v[20:23], v[152:155], v[176:179], v[20:23]
	v_mfma_f32_16x16x32_bf16 v[16:19], v[160:163], v[176:179], v[16:19]
	v_mfma_f32_16x16x32_bf16 v[12:15], v[152:155], v[184:187], v[12:15]
	v_mfma_f32_16x16x32_bf16 v[8:11], v[160:163], v[184:187], v[8:11]
	v_mfma_f32_16x16x32_bf16 v[4:7], v[152:155], v[192:195], v[4:7]
	v_mfma_f32_16x16x32_bf16 v[0:3], v[160:163], v[192:195], v[0:3]
	v_mfma_f32_16x16x32_bf16 v[28:31], v[156:159], v[172:175], v[28:31]
	v_mfma_f32_16x16x32_bf16 v[24:27], v[164:167], v[172:175], v[24:27]
	v_mfma_f32_16x16x32_bf16 v[20:23], v[156:159], v[180:183], v[20:23]
	v_mfma_f32_16x16x32_bf16 v[16:19], v[164:167], v[180:183], v[16:19]
	v_mfma_f32_16x16x32_bf16 v[12:15], v[156:159], v[188:191], v[12:15]
	v_mfma_f32_16x16x32_bf16 v[8:11], v[164:167], v[188:191], v[8:11]
	v_mfma_f32_16x16x32_bf16 v[4:7], v[156:159], v[196:199], v[4:7]
	v_mfma_f32_16x16x32_bf16 v[0:3], v[164:167], v[196:199], v[0:3]
	s_barrier
	s_add_u32 s38, s38, 0x100
	s_addc_u32 s39, s39, 0
	s_cmp_ge_i32 s75, s2
	s_cbranch_scc0 .LBB0_276

.LBB0_279:
	ds_read_b128 v[130:133], v143
	ds_read_b128 v[138:141], v143 offset:1024
	ds_read_b128 v[148:151], v143 offset:2048
	ds_read_b128 v[152:155], v143 offset:3072
	ds_read_b128 v[156:159], v144
	ds_read_b128 v[160:163], v144 offset:1024
	ds_read_b128 v[164:167], v144 offset:2048
	ds_read_b128 v[168:171], v144 offset:3072
	s_ashr_i32 s51, s28, 31
	s_mov_b32 s50, s28
	s_lshl_b64 s[50:51], s[50:51], 7
	s_add_u32 s2, s4, s50
	ds_read_b128 v[172:175], v145
	ds_read_b128 v[176:179], v145 offset:1024
	ds_read_b128 v[180:183], v145 offset:2048
	ds_read_b128 v[184:187], v145 offset:3072
	ds_read_b128 v[188:191], v145 offset:4096
	ds_read_b128 v[192:195], v145 offset:5120
	ds_read_b128 v[196:199], v145 offset:6144
	ds_read_b128 v[200:203], v145 offset:7168
	s_addc_u32 s4, s5, s51
	s_add_u32 s2, s2, s48
	s_addc_u32 s5, s4, s49
	s_add_u32 s4, s2, 0xffffff80
	s_addc_u32 s5, s5, -1
	s_add_u32 s46, s4, s46
	s_mov_b32 m0, s82
	s_nop 0
	global_load_lds_dwordx4 v128, s[4:5]
	s_addc_u32 s47, s5, s47
	s_mov_b32 m0, s83
	s_nop 0
	global_load_lds_dwordx4 v128, s[46:47]
	s_waitcnt vmcnt(8)
	s_waitcnt lgkmcnt(0)
	s_barrier
	s_waitcnt lgkmcnt(7)
	v_mfma_f32_16x16x32_bf16 v[124:127], v[130:133], v[172:175], v[124:127]
	v_mfma_f32_16x16x32_bf16 v[120:123], v[148:151], v[172:175], v[120:123]
	s_waitcnt lgkmcnt(5)
	v_mfma_f32_16x16x32_bf16 v[116:119], v[130:133], v[180:183], v[116:119]
	s_waitcnt lgkmcnt(3)
	v_mfma_f32_16x16x32_bf16 v[108:111], v[130:133], v[188:191], v[108:111]
	s_waitcnt lgkmcnt(1)
	v_mfma_f32_16x16x32_bf16 v[100:103], v[130:133], v[196:199], v[100:103]
	v_mfma_f32_16x16x32_bf16 v[124:127], v[138:141], v[176:179], v[124:127]
	v_mfma_f32_16x16x32_bf16 v[120:123], v[152:155], v[176:179], v[120:123]
	v_mfma_f32_16x16x32_bf16 v[116:119], v[138:141], v[184:187], v[116:119]
	v_mfma_f32_16x16x32_bf16 v[112:115], v[148:151], v[180:183], v[112:115]
	v_mfma_f32_16x16x32_bf16 v[108:111], v[138:141], v[192:195], v[108:111]
	v_mfma_f32_16x16x32_bf16 v[104:107], v[148:151], v[188:191], v[104:107]
	s_waitcnt lgkmcnt(0)
	v_mfma_f32_16x16x32_bf16 v[100:103], v[138:141], v[200:203], v[100:103]
	v_mfma_f32_16x16x32_bf16 v[96:99], v[148:151], v[196:199], v[96:99]
	v_mfma_f32_16x16x32_bf16 v[204:207], v[152:155], v[184:187], v[112:115]
	v_mfma_f32_16x16x32_bf16 v[208:211], v[152:155], v[192:195], v[104:107]
	v_mfma_f32_16x16x32_bf16 v[212:215], v[152:155], v[200:203], v[96:99]
	v_mfma_f32_16x16x32_bf16 v[92:95], v[156:159], v[172:175], v[92:95]
	v_mfma_f32_16x16x32_bf16 v[84:87], v[156:159], v[180:183], v[84:87]
	v_mfma_f32_16x16x32_bf16 v[76:79], v[156:159], v[188:191], v[76:79]
	v_mfma_f32_16x16x32_bf16 v[68:71], v[156:159], v[196:199], v[68:71]
	v_mfma_f32_16x16x32_bf16 v[64:67], v[164:167], v[196:199], v[64:67]
	v_mfma_f32_16x16x32_bf16 v[92:95], v[160:163], v[176:179], v[92:95]
	v_mfma_f32_16x16x32_bf16 v[88:91], v[164:167], v[172:175], v[88:91]
	v_mfma_f32_16x16x32_bf16 v[84:87], v[160:163], v[184:187], v[84:87]
	v_mfma_f32_16x16x32_bf16 v[80:83], v[164:167], v[180:183], v[80:83]
	v_mfma_f32_16x16x32_bf16 v[76:79], v[160:163], v[192:195], v[76:79]
	v_mfma_f32_16x16x32_bf16 v[72:75], v[164:167], v[188:191], v[72:75]
	v_mfma_f32_16x16x32_bf16 v[68:71], v[160:163], v[200:203], v[68:71]
	v_mfma_f32_16x16x32_bf16 v[64:67], v[168:171], v[200:203], v[64:67]
	v_mfma_f32_16x16x32_bf16 v[172:175], v[168:171], v[176:179], v[88:91]
	v_mfma_f32_16x16x32_bf16 v[176:179], v[168:171], v[184:187], v[80:83]
	v_mfma_f32_16x16x32_bf16 v[180:183], v[168:171], v[192:195], v[72:75]
	s_barrier
	s_add_u32 s46, s6, s0
	ds_read_b128 v[72:75], v145 offset:16384
	ds_read_b128 v[80:83], v145 offset:17408
	ds_read_b128 v[88:91], v145 offset:18432
	ds_read_b128 v[96:99], v145 offset:19456
	ds_read_b128 v[104:107], v145 offset:20480
	ds_read_b128 v[112:115], v145 offset:21504
	ds_read_b128 v[184:187], v145 offset:22528
	ds_read_b128 v[188:191], v145 offset:23552
	s_addc_u32 s47, s7, s1
	s_mov_b32 m0, s58
	s_nop 0
	global_load_lds_dwordx4 v137, s[6:7]
	s_add_u32 s48, s6, s18
	s_mov_b32 m0, s59
	s_nop 0
	global_load_lds_dwordx4 v137, s[46:47]
	s_addc_u32 s49, s7, s19
	s_add_u32 s50, s48, s0
	s_mov_b32 m0, s60
	s_nop 0
	global_load_lds_dwordx4 v137, s[48:49]
	s_addc_u32 s51, s49, s1
	s_mov_b32 m0, s61
	s_nop 0
	global_load_lds_dwordx4 v137, s[50:51]
	s_add_u32 s4, s42, s40
	s_mov_b32 m0, s53
	s_nop 0
	global_load_lds_dwordx4 v136, s[42:43]
	s_addc_u32 s5, s43, s41
	s_mov_b32 m0, s62
	s_nop 0
	global_load_lds_dwordx4 v136, s[4:5]
	s_waitcnt vmcnt(8)
	s_waitcnt lgkmcnt(0)
	s_barrier
	s_waitcnt lgkmcnt(7)
	v_mfma_f32_16x16x32_bf16 v[60:63], v[130:133], v[72:75], v[60:63]
	v_mfma_f32_16x16x32_bf16 v[56:59], v[148:151], v[72:75], v[56:59]
	s_waitcnt lgkmcnt(5)
	v_mfma_f32_16x16x32_bf16 v[52:55], v[130:133], v[88:91], v[52:55]
	s_waitcnt lgkmcnt(3)
	v_mfma_f32_16x16x32_bf16 v[44:47], v[130:133], v[104:107], v[44:47]
	s_waitcnt lgkmcnt(1)
	v_mfma_f32_16x16x32_bf16 v[36:39], v[130:133], v[184:187], v[36:39]
	v_mfma_f32_16x16x32_bf16 v[60:63], v[138:141], v[80:83], v[60:63]
	v_mfma_f32_16x16x32_bf16 v[56:59], v[152:155], v[80:83], v[56:59]
	v_mfma_f32_16x16x32_bf16 v[52:55], v[138:141], v[96:99], v[52:55]
	v_mfma_f32_16x16x32_bf16 v[48:51], v[148:151], v[88:91], v[48:51]
	v_mfma_f32_16x16x32_bf16 v[44:47], v[138:141], v[112:115], v[44:47]
	v_mfma_f32_16x16x32_bf16 v[40:43], v[148:151], v[104:107], v[40:43]
	s_waitcnt lgkmcnt(0)
	v_mfma_f32_16x16x32_bf16 v[36:39], v[138:141], v[188:191], v[36:39]
	v_mfma_f32_16x16x32_bf16 v[32:35], v[148:151], v[184:187], v[32:35]
	v_mfma_f32_16x16x32_bf16 v[192:195], v[152:155], v[96:99], v[48:51]
	v_mfma_f32_16x16x32_bf16 v[196:199], v[152:155], v[112:115], v[40:43]
	v_mfma_f32_16x16x32_bf16 v[138:141], v[152:155], v[188:191], v[32:35]
	v_mfma_f32_16x16x32_bf16 v[28:31], v[156:159], v[72:75], v[28:31]
	v_mfma_f32_16x16x32_bf16 v[16:19], v[164:167], v[88:91], v[16:19]
	v_mfma_f32_16x16x32_bf16 v[4:7], v[156:159], v[184:187], v[4:7]
	v_mfma_f32_16x16x32_bf16 v[28:31], v[160:163], v[80:83], v[28:31]
	v_mfma_f32_16x16x32_bf16 v[24:27], v[164:167], v[72:75], v[24:27]
	v_mfma_f32_16x16x32_bf16 v[20:23], v[156:159], v[88:91], v[20:23]
	v_mfma_f32_16x16x32_bf16 v[16:19], v[168:171], v[96:99], v[16:19]
	v_mfma_f32_16x16x32_bf16 v[12:15], v[156:159], v[104:107], v[12:15]
	v_mfma_f32_16x16x32_bf16 v[8:11], v[164:167], v[104:107], v[8:11]
	v_mfma_f32_16x16x32_bf16 v[4:7], v[160:163], v[188:191], v[4:7]
	v_mfma_f32_16x16x32_bf16 v[0:3], v[164:167], v[184:187], v[0:3]
	v_mfma_f32_16x16x32_bf16 v[148:151], v[168:171], v[80:83], v[24:27]
	v_mfma_f32_16x16x32_bf16 v[20:23], v[160:163], v[96:99], v[20:23]
	v_mfma_f32_16x16x32_bf16 v[152:155], v[160:163], v[112:115], v[12:15]
	v_mfma_f32_16x16x32_bf16 v[8:11], v[168:171], v[112:115], v[8:11]
	v_mfma_f32_16x16x32_bf16 v[156:159], v[168:171], v[188:191], v[0:3]
	s_barrier
	s_nop 0
	ds_read_b128 v[0:3], v146
	ds_read_b128 v[12:15], v146 offset:1024
	ds_read_b128 v[160:163], v146 offset:2048
	ds_read_b128 v[164:167], v146 offset:3072
	ds_read_b128 v[168:171], v147
	ds_read_b128 v[184:187], v147 offset:1024
	ds_read_b128 v[188:191], v147 offset:2048
	ds_read_b128 v[200:203], v147 offset:3072
	ds_read_b128 v[24:27], v145 offset:32768
	ds_read_b128 v[32:35], v145 offset:33792
	ds_read_b128 v[40:43], v145 offset:34816
	ds_read_b128 v[48:51], v145 offset:35840
	ds_read_b128 v[216:219], v145 offset:36864
	ds_read_b128 v[220:223], v145 offset:37888
	ds_read_b128 v[224:227], v145 offset:38912
	ds_read_b128 v[228:231], v145 offset:39936
	s_add_u32 s54, s42, s38
	s_addc_u32 s55, s43, s39
	s_add_u32 s68, s54, s40
	s_mov_b32 m0, s63
	s_nop 0
	global_load_lds_dwordx4 v136, s[54:55]
	s_addc_u32 s69, s55, s41
	s_mov_b32 m0, s64
	s_nop 0
	global_load_lds_dwordx4 v136, s[68:69]
	s_waitcnt vmcnt(8)
	s_waitcnt lgkmcnt(0)
	s_barrier
	s_waitcnt lgkmcnt(7)
	v_mfma_f32_16x16x32_bf16 v[72:75], v[0:3], v[24:27], v[124:127]
	s_waitcnt lgkmcnt(6)
	v_mfma_f32_16x16x32_bf16 v[128:131], v[12:15], v[32:35], v[72:75]
	v_mfma_f32_16x16x32_bf16 v[72:75], v[160:163], v[24:27], v[120:123]
	v_mfma_f32_16x16x32_bf16 v[120:123], v[164:167], v[32:35], v[72:75]
	s_waitcnt lgkmcnt(5)
	v_mfma_f32_16x16x32_bf16 v[72:75], v[0:3], v[40:43], v[116:119]
	s_waitcnt lgkmcnt(4)
	v_mfma_f32_16x16x32_bf16 v[112:115], v[12:15], v[48:51], v[72:75]
	v_mfma_f32_16x16x32_bf16 v[72:75], v[160:163], v[40:43], v[204:207]
	v_mfma_f32_16x16x32_bf16 v[104:107], v[164:167], v[48:51], v[72:75]
	s_waitcnt lgkmcnt(3)
	v_mfma_f32_16x16x32_bf16 v[72:75], v[0:3], v[216:219], v[108:111]
	s_waitcnt lgkmcnt(2)
	v_mfma_f32_16x16x32_bf16 v[96:99], v[12:15], v[220:223], v[72:75]
	v_mfma_f32_16x16x32_bf16 v[72:75], v[160:163], v[216:219], v[208:211]
	v_mfma_f32_16x16x32_bf16 v[88:91], v[164:167], v[220:223], v[72:75]
	s_waitcnt lgkmcnt(1)
	v_mfma_f32_16x16x32_bf16 v[72:75], v[0:3], v[224:227], v[100:103]
	s_waitcnt lgkmcnt(0)
	v_mfma_f32_16x16x32_bf16 v[80:83], v[12:15], v[228:231], v[72:75]
	v_mfma_f32_16x16x32_bf16 v[72:75], v[160:163], v[224:227], v[212:215]
	v_mfma_f32_16x16x32_bf16 v[72:75], v[164:167], v[228:231], v[72:75]
	v_mfma_f32_16x16x32_bf16 v[92:95], v[168:171], v[24:27], v[92:95]
	v_mfma_f32_16x16x32_bf16 v[24:27], v[188:191], v[24:27], v[172:175]
	v_mfma_f32_16x16x32_bf16 v[124:127], v[200:203], v[32:35], v[24:27]
	v_mfma_f32_16x16x32_bf16 v[24:27], v[168:171], v[40:43], v[84:87]
	v_mfma_f32_16x16x32_bf16 v[116:119], v[184:187], v[48:51], v[24:27]
	v_mfma_f32_16x16x32_bf16 v[24:27], v[188:191], v[40:43], v[176:179]
	v_mfma_f32_16x16x32_bf16 v[108:111], v[200:203], v[48:51], v[24:27]
	v_mfma_f32_16x16x32_bf16 v[24:27], v[168:171], v[216:219], v[76:79]
	v_mfma_f32_16x16x32_bf16 v[100:103], v[184:187], v[220:223], v[24:27]
	v_mfma_f32_16x16x32_bf16 v[24:27], v[188:191], v[216:219], v[180:183]
	v_mfma_f32_16x16x32_bf16 v[132:135], v[184:187], v[32:35], v[92:95]
	v_mfma_f32_16x16x32_bf16 v[92:95], v[200:203], v[220:223], v[24:27]
	v_mfma_f32_16x16x32_bf16 v[24:27], v[168:171], v[224:227], v[68:71]
	v_mfma_f32_16x16x32_bf16 v[84:87], v[184:187], v[228:231], v[24:27]
	v_mfma_f32_16x16x32_bf16 v[24:27], v[188:191], v[224:227], v[64:67]
	v_mfma_f32_16x16x32_bf16 v[76:79], v[200:203], v[228:231], v[24:27]
	s_barrier
	s_add_u32 s54, s6, 0x80
	s_addc_u32 s55, s7, 0
	s_add_u32 s46, s46, 0x80
	ds_read_b128 v[172:175], v145 offset:49152
	ds_read_b128 v[176:179], v145 offset:50176
	ds_read_b128 v[180:183], v145 offset:51200
	ds_read_b128 v[204:207], v145 offset:52224
	ds_read_b128 v[208:211], v145 offset:53248
	ds_read_b128 v[212:215], v145 offset:54272
	ds_read_b128 v[216:219], v145 offset:55296
	ds_read_b128 v[220:223], v145 offset:56320
	s_addc_u32 s47, s47, 0
	s_mov_b32 m0, s65
	s_nop 0
	global_load_lds_dwordx4 v137, s[54:55]
	s_nop 0
	s_mov_b32 m0, s66
	s_nop 0
	global_load_lds_dwordx4 v137, s[46:47]
	s_add_u32 s46, s48, 0x80
	s_addc_u32 s47, s49, 0
	s_add_u32 s48, s50, 0x80
	s_addc_u32 s49, s51, 0
	s_mov_b32 m0, s78
	s_nop 0
	global_load_lds_dwordx4 v137, s[46:47]
	s_add_u32 s46, s42, 0x80
	s_mov_b32 m0, s79
	s_nop 0
	global_load_lds_dwordx4 v137, s[48:49]
	s_addc_u32 s47, s43, 0
	s_add_u32 s4, s4, 0x80
	s_mov_b32 m0, s67
	s_nop 0
	global_load_lds_dwordx4 v136, s[46:47]
	s_addc_u32 s5, s5, 0
	s_mov_b32 m0, s73
	s_nop 0
	global_load_lds_dwordx4 v136, s[4:5]
	s_waitcnt vmcnt(8)
	s_waitcnt lgkmcnt(0)
	s_barrier
	s_waitcnt lgkmcnt(7)
	v_mfma_f32_16x16x32_bf16 v[24:27], v[0:3], v[172:175], v[60:63]
	s_waitcnt lgkmcnt(6)
	v_mfma_f32_16x16x32_bf16 v[64:67], v[12:15], v[176:179], v[24:27]
	v_mfma_f32_16x16x32_bf16 v[24:27], v[160:163], v[172:175], v[56:59]
	v_mfma_f32_16x16x32_bf16 v[56:59], v[164:167], v[176:179], v[24:27]
	s_waitcnt lgkmcnt(5)
	v_mfma_f32_16x16x32_bf16 v[24:27], v[0:3], v[180:183], v[52:55]
	s_waitcnt lgkmcnt(4)
	v_mfma_f32_16x16x32_bf16 v[48:51], v[12:15], v[204:207], v[24:27]
	v_mfma_f32_16x16x32_bf16 v[24:27], v[160:163], v[180:183], v[192:195]
	v_mfma_f32_16x16x32_bf16 v[40:43], v[164:167], v[204:207], v[24:27]
	s_waitcnt lgkmcnt(3)
	v_mfma_f32_16x16x32_bf16 v[24:27], v[0:3], v[208:211], v[44:47]
	s_waitcnt lgkmcnt(1)
	v_mfma_f32_16x16x32_bf16 v[0:3], v[0:3], v[216:219], v[36:39]
	v_mfma_f32_16x16x32_bf16 v[32:35], v[12:15], v[212:215], v[24:27]
	v_mfma_f32_16x16x32_bf16 v[24:27], v[160:163], v[208:211], v[196:199]
	s_waitcnt lgkmcnt(0)
	v_mfma_f32_16x16x32_bf16 v[12:15], v[12:15], v[220:223], v[0:3]
	v_mfma_f32_16x16x32_bf16 v[0:3], v[160:163], v[216:219], v[138:141]
	v_mfma_f32_16x16x32_bf16 v[24:27], v[164:167], v[212:215], v[24:27]
	v_mfma_f32_16x16x32_bf16 v[0:3], v[164:167], v[220:223], v[0:3]
	v_mfma_f32_16x16x32_bf16 v[16:19], v[188:191], v[180:183], v[16:19]
	v_mfma_f32_16x16x32_bf16 v[28:31], v[168:171], v[172:175], v[28:31]
	v_mfma_f32_16x16x32_bf16 v[44:47], v[200:203], v[204:207], v[16:19]
	v_mfma_f32_16x16x32_bf16 v[16:19], v[168:171], v[208:211], v[152:155]
	v_mfma_f32_16x16x32_bf16 v[4:7], v[168:171], v[216:219], v[4:7]
	v_mfma_f32_16x16x32_bf16 v[68:71], v[184:187], v[176:179], v[28:31]
	v_mfma_f32_16x16x32_bf16 v[28:31], v[188:191], v[172:175], v[148:151]
	v_mfma_f32_16x16x32_bf16 v[20:23], v[168:171], v[180:183], v[20:23]
	v_mfma_f32_16x16x32_bf16 v[36:39], v[184:187], v[212:215], v[16:19]
	v_mfma_f32_16x16x32_bf16 v[8:11], v[188:191], v[208:211], v[8:11]
	v_mfma_f32_16x16x32_bf16 v[16:19], v[184:187], v[220:223], v[4:7]
	v_mfma_f32_16x16x32_bf16 v[4:7], v[188:191], v[216:219], v[156:159]
	v_mfma_f32_16x16x32_bf16 v[60:63], v[200:203], v[176:179], v[28:31]
	v_mfma_f32_16x16x32_bf16 v[52:55], v[184:187], v[204:207], v[20:23]
	v_mfma_f32_16x16x32_bf16 v[28:31], v[200:203], v[212:215], v[8:11]
	v_mfma_f32_16x16x32_bf16 v[4:7], v[200:203], v[220:223], v[4:7]
	s_barrier
	s_andn2_b64 vcc, exec, s[22:23]
	s_cbranch_vccnz .LBB0_281
	s_barrier

.LBB0_288:
	v_and_b32_e32 v1, 15, v2
	s_lshl_b64 s[44:45], s[0:1], 7
	s_lshl_b64 s[22:23], s[14:15], 7
	v_or_b32_e32 v3, s3, v1
	v_lshlrev_b32_e32 v5, 6, v3
	v_and_b32_e32 v6, 48, v2
	s_movk_i32 s0, 0x3c0
	s_add_u32 s14, s6, 0x80
	v_ashrrev_i32_e32 v4, 6, v2
	v_and_or_b32 v5, v5, s0, v6
	v_readlane_b32 s0, v254, 55
	s_addc_u32 s15, s7, 0
	v_lshl_add_u32 v7, v4, 10, s95
	v_add_lshl_u32 v4, v4, s0, 10
	s_sub_u32 s0, 0, s16
	s_subb_u32 s2, 0, s17
	s_add_u32 s0, s8, s0
	s_addc_u32 s2, s9, s2
	s_add_u32 s24, s0, 0x80
	s_addc_u32 s25, s2, 0
	s_add_i32 s61, s53, 0x18000
	s_add_i32 s62, s53, 0x1a000
	s_mov_b32 s98, 0
	s_cselect_b32 s99, 1, 0
	s_cmp_lt_u32 s76, 4
	s_cbranch_scc0 .Lsprio_3
	s_setprio 1
.Lsprio_3:
	s_cmp_lg_u32 s99, 0
	s_waitcnt vmcnt(2)
	s_barrier
	s_mov_b32 m0, s61
	s_nop 0
	global_load_lds_dwordx4 v0, s[14:15]
	s_add_u32 s14, s4, 0x80
	s_mov_b32 m0, s62
	s_nop 0
	global_load_lds_dwordx4 v0, s[24:25]
	s_addc_u32 s15, s5, 0
	s_sub_u32 s0, 0, s42
	s_subb_u32 s2, 0, s43
	s_add_u32 s0, s12, s0
	s_addc_u32 s2, s13, s2
	s_add_u32 s12, s0, 0x80
	s_addc_u32 s13, s2, 0
	s_add_i32 s63, s53, 0x8000
	s_add_i32 s64, s53, 0xa000
	s_add_u32 s8, s8, 0x80
	s_mov_b32 m0, s63
	s_nop 0
	global_load_lds_dwordx4 v130, s[14:15]
	s_addc_u32 s9, s9, 0
	s_mov_b32 m0, s64
	s_nop 0
	global_load_lds_dwordx4 v130, s[12:13]
	s_add_u32 s10, s10, 0x80
	v_lshlrev_b32_e32 v2, 2, v2
	s_addc_u32 s11, s11, 0
	s_add_i32 s65, s53, 0x1c000
	s_mov_b32 m0, s65
	s_nop 0
	global_load_lds_dwordx4 v0, s[8:9]
	v_lshlrev_b32_e32 v3, 2, v3
	v_lshl_or_b32 v1, v1, 6, v6
	v_and_b32_e32 v2, 32, v2
	s_add_i32 s66, s53, 0x1e000
	s_mov_b32 m0, s66
	s_nop 0
	global_load_lds_dwordx4 v0, s[10:11]
	v_and_b32_e32 v3, 32, v3
	v_bitop3_b32 v1, v1, v4, v2 bitop3:0xde
	s_waitcnt vmcnt(6)
	s_add_i32 s67, s53, 0xc000
	s_add_i32 s73, s53, 0xe000
	v_readlane_b32 s0, v254, 0
	v_mov_b32_e32 v131, v0
	v_bitop3_b32 v3, v5, v7, v3 bitop3:0xde
	s_cmpk_lt_u32 s0, 0x100
	v_add_u32_e32 v0, 0, v1
	s_cselect_b64 s[24:25], -1, 0
	v_add_u32_e32 v137, 0x10000, v0
	v_add_u32_e32 v138, 0x14000, v0
	v_add_u32_e32 v139, 0, v3
	v_add_u32_e32 v140, 0x18000, v0
	v_add_u32_e32 v141, 0x1c000, v0
	s_mov_b32 s79, s1
	s_barrier
	s_branch .LBB0_291

.LBB0_293:
	s_cmp_lt_i32 s30, 3
	s_cbranch_scc1 .Lhz_295
	s_add_i32 s0, s30, -2
	s_add_u32 s2, s4, s44
	s_addc_u32 s33, s5, s45
	s_add_u32 s38, s6, s22
	s_addc_u32 s39, s7, s23
	s_add_u32 s34, s16, s22
	s_addc_u32 s35, s17, s23
	s_add_u32 s46, s6, s34
	s_addc_u32 s47, s7, s35
	s_add_u32 s68, s6, s16
	s_addc_u32 s69, s7, s17
	s_add_u32 s34, s42, s44
	s_addc_u32 s35, s43, s45
	s_add_u32 s70, s4, s34
	s_addc_u32 s71, s5, s35
	s_add_u32 s72, s4, s42
	s_addc_u32 s74, s5, s43
	s_mov_b32 s75, 0
	s_mov_b64 s[34:35], 0
	s_cmp_eq_u32 s98, 0
	s_cbranch_scc1 .Lhf_295
	ds_read_b128 v[132:135], v137
	ds_read_b128 v[142:145], v137 offset:1024
	ds_read_b128 v[146:149], v137 offset:2048
	ds_read_b128 v[150:153], v137 offset:3072
	ds_read_b128 v[154:157], v138
	ds_read_b128 v[158:161], v138 offset:1024
	ds_read_b128 v[162:165], v138 offset:2048
	ds_read_b128 v[166:169], v138 offset:3072
	s_add_i32 s75, s75, 2
	s_add_u32 s77, s4, s34
	s_addc_u32 s80, s5, s35
	s_add_u32 s36, s77, 0x100
	s_addc_u32 s37, s80, 0
	s_add_u32 s81, s2, s34
	ds_read_b128 v[170:173], v139
	ds_read_b128 v[174:177], v139 offset:1024
	ds_read_b128 v[178:181], v139 offset:2048
	ds_read_b128 v[182:185], v139 offset:3072
	ds_read_b128 v[186:189], v139 offset:4096
	ds_read_b128 v[190:193], v139 offset:5120
	ds_read_b128 v[194:197], v139 offset:6144
	ds_read_b128 v[198:201], v139 offset:7168
	s_addc_u32 s84, s33, s35
	s_add_u32 s54, s81, 0x80
	s_addc_u32 s55, s84, 0
	s_add_u32 s85, s70, s34
	s_addc_u32 s86, s71, s35
	s_add_u32 s82, s85, 0x80
	s_mov_b32 m0, s67
	s_nop 0
	global_load_lds_dwordx4 v130, s[54:55]
	s_addc_u32 s83, s86, 0
	s_mov_b32 m0, s73
	s_nop 0
	global_load_lds_dwordx4 v130, s[82:83]
	s_waitcnt vmcnt(24)
	s_waitcnt lgkmcnt(0)
	s_barrier
	s_waitcnt lgkmcnt(7)
	v_mfma_f32_16x16x32_bf16 v[124:127], v[132:135], v[170:173], 0
	v_mfma_f32_16x16x32_bf16 v[120:123], v[146:149], v[170:173], 0
	s_waitcnt lgkmcnt(5)
	v_mfma_f32_16x16x32_bf16 v[116:119], v[132:135], v[178:181], 0
	v_mfma_f32_16x16x32_bf16 v[112:115], v[146:149], v[178:181], 0
	s_waitcnt lgkmcnt(3)
	v_mfma_f32_16x16x32_bf16 v[108:111], v[132:135], v[186:189], 0
	v_mfma_f32_16x16x32_bf16 v[104:107], v[146:149], v[186:189], 0
	s_waitcnt lgkmcnt(1)
	v_mfma_f32_16x16x32_bf16 v[100:103], v[132:135], v[194:197], 0
	v_mfma_f32_16x16x32_bf16 v[96:99], v[146:149], v[194:197], 0
	v_mfma_f32_16x16x32_bf16 v[124:127], v[142:145], v[174:177], v[124:127]
	v_mfma_f32_16x16x32_bf16 v[120:123], v[150:153], v[174:177], v[120:123]
	v_mfma_f32_16x16x32_bf16 v[116:119], v[142:145], v[182:185], v[116:119]
	v_mfma_f32_16x16x32_bf16 v[112:115], v[150:153], v[182:185], v[112:115]
	v_mfma_f32_16x16x32_bf16 v[108:111], v[142:145], v[190:193], v[108:111]
	v_mfma_f32_16x16x32_bf16 v[104:107], v[150:153], v[190:193], v[104:107]
	s_waitcnt lgkmcnt(0)
	v_mfma_f32_16x16x32_bf16 v[100:103], v[142:145], v[198:201], v[100:103]
	v_mfma_f32_16x16x32_bf16 v[96:99], v[150:153], v[198:201], v[96:99]
	v_mfma_f32_16x16x32_bf16 v[92:95], v[154:157], v[170:173], 0
	v_mfma_f32_16x16x32_bf16 v[88:91], v[162:165], v[170:173], 0
	v_mfma_f32_16x16x32_bf16 v[84:87], v[154:157], v[178:181], 0
	v_mfma_f32_16x16x32_bf16 v[80:83], v[162:165], v[178:181], 0
	v_mfma_f32_16x16x32_bf16 v[76:79], v[154:157], v[186:189], 0
	v_mfma_f32_16x16x32_bf16 v[72:75], v[162:165], v[186:189], 0
	v_mfma_f32_16x16x32_bf16 v[68:71], v[154:157], v[194:197], 0
	v_mfma_f32_16x16x32_bf16 v[64:67], v[162:165], v[194:197], 0
	v_mfma_f32_16x16x32_bf16 v[92:95], v[158:161], v[174:177], v[92:95]
	v_mfma_f32_16x16x32_bf16 v[88:91], v[166:169], v[174:177], v[88:91]
	v_mfma_f32_16x16x32_bf16 v[84:87], v[158:161], v[182:185], v[84:87]
	v_mfma_f32_16x16x32_bf16 v[80:83], v[166:169], v[182:185], v[80:83]
	v_mfma_f32_16x16x32_bf16 v[76:79], v[158:161], v[190:193], v[76:79]
	v_mfma_f32_16x16x32_bf16 v[72:75], v[166:169], v[190:193], v[72:75]
	v_mfma_f32_16x16x32_bf16 v[68:71], v[158:161], v[198:201], v[68:71]
	v_mfma_f32_16x16x32_bf16 v[64:67], v[166:169], v[198:201], v[64:67]
	s_barrier
	s_add_u32 s87, s6, s34
	s_addc_u32 s88, s7, s35
	s_add_u32 s54, s87, 0x100
	s_addc_u32 s55, s88, 0
	s_add_u32 s89, s68, s34
	s_addc_u32 s90, s69, s35
	s_add_u32 s82, s89, 0x100
	ds_read_b128 v[170:173], v139 offset:16384
	ds_read_b128 v[174:177], v139 offset:17408
	ds_read_b128 v[178:181], v139 offset:18432
	ds_read_b128 v[182:185], v139 offset:19456
	ds_read_b128 v[186:189], v139 offset:20480
	ds_read_b128 v[190:193], v139 offset:21504
	ds_read_b128 v[194:197], v139 offset:22528
	ds_read_b128 v[198:201], v139 offset:23552
	s_addc_u32 s83, s90, 0
	s_mov_b32 m0, s49
	s_nop 0
	global_load_lds_dwordx4 v131, s[54:55]
	s_add_u32 s91, s38, s34
	s_mov_b32 m0, s50
	s_nop 0
	global_load_lds_dwordx4 v131, s[82:83]
	s_addc_u32 s92, s39, s35
	s_add_u32 s54, s91, 0x100
	s_addc_u32 s55, s92, 0
	s_add_u32 s93, s46, s34
	s_addc_u32 s94, s47, s35
	s_add_u32 s82, s93, 0x100
	s_addc_u32 s83, s94, 0
	s_mov_b32 m0, s51
	s_nop 0
	global_load_lds_dwordx4 v131, s[54:55]
	s_mov_b32 m0, s57
	s_nop 0
	global_load_lds_dwordx4 v131, s[82:83]
	s_add_u32 s82, s72, s34
	s_addc_u32 s83, s74, s35
	s_add_u32 s54, s82, 0x100
	s_mov_b32 m0, s53
	s_nop 0
	global_load_lds_dwordx4 v130, s[36:37]
	s_addc_u32 s55, s83, 0
	s_mov_b32 m0, s58
	s_nop 0
	global_load_lds_dwordx4 v130, s[54:55]
	s_waitcnt vmcnt(24)
	s_waitcnt lgkmcnt(0)
	s_barrier
	s_waitcnt lgkmcnt(7)
	v_mfma_f32_16x16x32_bf16 v[60:63], v[132:135], v[170:173], 0
	v_mfma_f32_16x16x32_bf16 v[56:59], v[146:149], v[170:173], 0
	s_waitcnt lgkmcnt(5)
	v_mfma_f32_16x16x32_bf16 v[52:55], v[132:135], v[178:181], 0
	v_mfma_f32_16x16x32_bf16 v[48:51], v[146:149], v[178:181], 0
	s_waitcnt lgkmcnt(3)
	v_mfma_f32_16x16x32_bf16 v[44:47], v[132:135], v[186:189], 0
	v_mfma_f32_16x16x32_bf16 v[40:43], v[146:149], v[186:189], 0
	s_waitcnt lgkmcnt(1)
	v_mfma_f32_16x16x32_bf16 v[36:39], v[132:135], v[194:197], 0
	v_mfma_f32_16x16x32_bf16 v[32:35], v[146:149], v[194:197], 0
	v_mfma_f32_16x16x32_bf16 v[60:63], v[142:145], v[174:177], v[60:63]
	v_mfma_f32_16x16x32_bf16 v[56:59], v[150:153], v[174:177], v[56:59]
	v_mfma_f32_16x16x32_bf16 v[52:55], v[142:145], v[182:185], v[52:55]
	v_mfma_f32_16x16x32_bf16 v[48:51], v[150:153], v[182:185], v[48:51]
	v_mfma_f32_16x16x32_bf16 v[44:47], v[142:145], v[190:193], v[44:47]
	v_mfma_f32_16x16x32_bf16 v[40:43], v[150:153], v[190:193], v[40:43]
	s_waitcnt lgkmcnt(0)
	v_mfma_f32_16x16x32_bf16 v[36:39], v[142:145], v[198:201], v[36:39]
	v_mfma_f32_16x16x32_bf16 v[32:35], v[150:153], v[198:201], v[32:35]
	v_mfma_f32_16x16x32_bf16 v[28:31], v[154:157], v[170:173], 0
	v_mfma_f32_16x16x32_bf16 v[24:27], v[162:165], v[170:173], 0
	v_mfma_f32_16x16x32_bf16 v[20:23], v[154:157], v[178:181], 0
	v_mfma_f32_16x16x32_bf16 v[16:19], v[162:165], v[178:181], 0
	v_mfma_f32_16x16x32_bf16 v[12:15], v[154:157], v[186:189], 0
	v_mfma_f32_16x16x32_bf16 v[8:11], v[162:165], v[186:189], 0
	v_mfma_f32_16x16x32_bf16 v[4:7], v[154:157], v[194:197], 0
	v_mfma_f32_16x16x32_bf16 v[0:3], v[162:165], v[194:197], 0
	v_mfma_f32_16x16x32_bf16 v[28:31], v[158:161], v[174:177], v[28:31]
	v_mfma_f32_16x16x32_bf16 v[24:27], v[166:169], v[174:177], v[24:27]
	v_mfma_f32_16x16x32_bf16 v[20:23], v[158:161], v[182:185], v[20:23]
	v_mfma_f32_16x16x32_bf16 v[16:19], v[166:169], v[182:185], v[16:19]
	v_mfma_f32_16x16x32_bf16 v[12:15], v[158:161], v[190:193], v[12:15]
	v_mfma_f32_16x16x32_bf16 v[8:11], v[166:169], v[190:193], v[8:11]
	v_mfma_f32_16x16x32_bf16 v[4:7], v[158:161], v[198:201], v[4:7]
	v_mfma_f32_16x16x32_bf16 v[0:3], v[166:169], v[198:201], v[0:3]
	s_barrier
	ds_read_b128 v[132:135], v140
	ds_read_b128 v[142:145], v140 offset:1024
	ds_read_b128 v[146:149], v140 offset:2048
	ds_read_b128 v[150:153], v140 offset:3072
	ds_read_b128 v[154:157], v141
	ds_read_b128 v[158:161], v141 offset:1024
	ds_read_b128 v[162:165], v141 offset:2048
	ds_read_b128 v[166:169], v141 offset:3072
	ds_read_b128 v[170:173], v139 offset:32768
	ds_read_b128 v[174:177], v139 offset:33792
	ds_read_b128 v[178:181], v139 offset:34816
	ds_read_b128 v[182:185], v139 offset:35840
	ds_read_b128 v[186:189], v139 offset:36864
	ds_read_b128 v[190:193], v139 offset:37888
	ds_read_b128 v[194:197], v139 offset:38912
	ds_read_b128 v[198:201], v139 offset:39936
	s_add_u32 s36, s81, 0x100
	s_addc_u32 s37, s84, 0
	s_add_u32 s54, s85, 0x100
	s_mov_b32 m0, s59
	s_nop 0
	global_load_lds_dwordx4 v130, s[36:37]
	s_addc_u32 s55, s86, 0
	s_mov_b32 m0, s60
	s_nop 0
	global_load_lds_dwordx4 v130, s[54:55]
	s_waitcnt vmcnt(8)
	s_waitcnt lgkmcnt(0)
	s_barrier
	s_waitcnt lgkmcnt(7)
	v_mfma_f32_16x16x32_bf16 v[124:127], v[132:135], v[170:173], v[124:127]
	v_mfma_f32_16x16x32_bf16 v[120:123], v[146:149], v[170:173], v[120:123]
	s_waitcnt lgkmcnt(5)
	v_mfma_f32_16x16x32_bf16 v[116:119], v[132:135], v[178:181], v[116:119]
	v_mfma_f32_16x16x32_bf16 v[112:115], v[146:149], v[178:181], v[112:115]
	s_waitcnt lgkmcnt(3)
	v_mfma_f32_16x16x32_bf16 v[108:111], v[132:135], v[186:189], v[108:111]
	v_mfma_f32_16x16x32_bf16 v[104:107], v[146:149], v[186:189], v[104:107]
	s_waitcnt lgkmcnt(1)
	v_mfma_f32_16x16x32_bf16 v[100:103], v[132:135], v[194:197], v[100:103]
	v_mfma_f32_16x16x32_bf16 v[96:99], v[146:149], v[194:197], v[96:99]
	v_mfma_f32_16x16x32_bf16 v[124:127], v[142:145], v[174:177], v[124:127]
	v_mfma_f32_16x16x32_bf16 v[120:123], v[150:153], v[174:177], v[120:123]
	v_mfma_f32_16x16x32_bf16 v[116:119], v[142:145], v[182:185], v[116:119]
	v_mfma_f32_16x16x32_bf16 v[112:115], v[150:153], v[182:185], v[112:115]
	v_mfma_f32_16x16x32_bf16 v[108:111], v[142:145], v[190:193], v[108:111]
	v_mfma_f32_16x16x32_bf16 v[104:107], v[150:153], v[190:193], v[104:107]
	s_waitcnt lgkmcnt(0)
	v_mfma_f32_16x16x32_bf16 v[100:103], v[142:145], v[198:201], v[100:103]
	v_mfma_f32_16x16x32_bf16 v[96:99], v[150:153], v[198:201], v[96:99]
	v_mfma_f32_16x16x32_bf16 v[92:95], v[154:157], v[170:173], v[92:95]
	v_mfma_f32_16x16x32_bf16 v[88:91], v[162:165], v[170:173], v[88:91]
	v_mfma_f32_16x16x32_bf16 v[84:87], v[154:157], v[178:181], v[84:87]
	v_mfma_f32_16x16x32_bf16 v[80:83], v[162:165], v[178:181], v[80:83]
	v_mfma_f32_16x16x32_bf16 v[76:79], v[154:157], v[186:189], v[76:79]
	v_mfma_f32_16x16x32_bf16 v[72:75], v[162:165], v[186:189], v[72:75]
	v_mfma_f32_16x16x32_bf16 v[68:71], v[154:157], v[194:197], v[68:71]
	v_mfma_f32_16x16x32_bf16 v[64:67], v[162:165], v[194:197], v[64:67]
	v_mfma_f32_16x16x32_bf16 v[92:95], v[158:161], v[174:177], v[92:95]
	v_mfma_f32_16x16x32_bf16 v[88:91], v[166:169], v[174:177], v[88:91]
	v_mfma_f32_16x16x32_bf16 v[84:87], v[158:161], v[182:185], v[84:87]
	v_mfma_f32_16x16x32_bf16 v[80:83], v[166:169], v[182:185], v[80:83]
	v_mfma_f32_16x16x32_bf16 v[76:79], v[158:161], v[190:193], v[76:79]
	v_mfma_f32_16x16x32_bf16 v[72:75], v[166:169], v[190:193], v[72:75]
	v_mfma_f32_16x16x32_bf16 v[68:71], v[158:161], v[198:201], v[68:71]
	v_mfma_f32_16x16x32_bf16 v[64:67], v[166:169], v[198:201], v[64:67]
	s_barrier
	s_add_u32 s36, s87, 0x180
	s_addc_u32 s37, s88, 0
	ds_read_b128 v[170:173], v139 offset:49152
	ds_read_b128 v[174:177], v139 offset:50176
	ds_read_b128 v[178:181], v139 offset:51200
	ds_read_b128 v[182:185], v139 offset:52224
	ds_read_b128 v[186:189], v139 offset:53248
	ds_read_b128 v[190:193], v139 offset:54272
	ds_read_b128 v[194:197], v139 offset:55296
	ds_read_b128 v[198:201], v139 offset:56320
	s_add_u32 s54, s89, 0x180
	s_mov_b32 m0, s61
	s_nop 0
	global_load_lds_dwordx4 v131, s[36:37]
	s_addc_u32 s55, s90, 0
	s_mov_b32 m0, s62
	s_nop 0
	global_load_lds_dwordx4 v131, s[54:55]
	s_add_u32 s36, s91, 0x180
	s_addc_u32 s37, s92, 0
	s_add_u32 s54, s93, 0x180
	s_mov_b32 m0, s65
	s_nop 0
	global_load_lds_dwordx4 v131, s[36:37]
	s_addc_u32 s55, s94, 0
	s_mov_b32 m0, s66
	s_nop 0
	global_load_lds_dwordx4 v131, s[54:55]
	s_add_u32 s36, s77, 0x180
	s_addc_u32 s37, s80, 0
	s_add_u32 s54, s82, 0x180
	s_mov_b32 m0, s63
	s_nop 0
	global_load_lds_dwordx4 v130, s[36:37]
	s_addc_u32 s55, s83, 0
	s_mov_b32 m0, s64
	s_nop 0
	global_load_lds_dwordx4 v130, s[54:55]
	s_waitcnt vmcnt(8)
	s_waitcnt lgkmcnt(0)
	s_barrier
	s_waitcnt lgkmcnt(7)
	v_mfma_f32_16x16x32_bf16 v[60:63], v[132:135], v[170:173], v[60:63]
	v_mfma_f32_16x16x32_bf16 v[56:59], v[146:149], v[170:173], v[56:59]
	s_waitcnt lgkmcnt(5)
	v_mfma_f32_16x16x32_bf16 v[52:55], v[132:135], v[178:181], v[52:55]
	v_mfma_f32_16x16x32_bf16 v[48:51], v[146:149], v[178:181], v[48:51]
	s_waitcnt lgkmcnt(3)
	v_mfma_f32_16x16x32_bf16 v[44:47], v[132:135], v[186:189], v[44:47]
	v_mfma_f32_16x16x32_bf16 v[40:43], v[146:149], v[186:189], v[40:43]
	s_waitcnt lgkmcnt(1)
	v_mfma_f32_16x16x32_bf16 v[36:39], v[132:135], v[194:197], v[36:39]
	v_mfma_f32_16x16x32_bf16 v[32:35], v[146:149], v[194:197], v[32:35]
	v_mfma_f32_16x16x32_bf16 v[60:63], v[142:145], v[174:177], v[60:63]
	v_mfma_f32_16x16x32_bf16 v[56:59], v[150:153], v[174:177], v[56:59]
	v_mfma_f32_16x16x32_bf16 v[52:55], v[142:145], v[182:185], v[52:55]
	v_mfma_f32_16x16x32_bf16 v[48:51], v[150:153], v[182:185], v[48:51]
	v_mfma_f32_16x16x32_bf16 v[44:47], v[142:145], v[190:193], v[44:47]
	v_mfma_f32_16x16x32_bf16 v[40:43], v[150:153], v[190:193], v[40:43]
	s_waitcnt lgkmcnt(0)
	v_mfma_f32_16x16x32_bf16 v[36:39], v[142:145], v[198:201], v[36:39]
	v_mfma_f32_16x16x32_bf16 v[32:35], v[150:153], v[198:201], v[32:35]
	v_mfma_f32_16x16x32_bf16 v[28:31], v[154:157], v[170:173], v[28:31]
	v_mfma_f32_16x16x32_bf16 v[24:27], v[162:165], v[170:173], v[24:27]
	v_mfma_f32_16x16x32_bf16 v[20:23], v[154:157], v[178:181], v[20:23]
	v_mfma_f32_16x16x32_bf16 v[16:19], v[162:165], v[178:181], v[16:19]
	v_mfma_f32_16x16x32_bf16 v[12:15], v[154:157], v[186:189], v[12:15]
	v_mfma_f32_16x16x32_bf16 v[8:11], v[162:165], v[186:189], v[8:11]
	v_mfma_f32_16x16x32_bf16 v[4:7], v[154:157], v[194:197], v[4:7]
	v_mfma_f32_16x16x32_bf16 v[0:3], v[162:165], v[194:197], v[0:3]
	v_mfma_f32_16x16x32_bf16 v[28:31], v[158:161], v[174:177], v[28:31]
	v_mfma_f32_16x16x32_bf16 v[24:27], v[166:169], v[174:177], v[24:27]
	v_mfma_f32_16x16x32_bf16 v[20:23], v[158:161], v[182:185], v[20:23]
	v_mfma_f32_16x16x32_bf16 v[16:19], v[166:169], v[182:185], v[16:19]
	v_mfma_f32_16x16x32_bf16 v[12:15], v[158:161], v[190:193], v[12:15]
	v_mfma_f32_16x16x32_bf16 v[8:11], v[166:169], v[190:193], v[8:11]
	v_mfma_f32_16x16x32_bf16 v[4:7], v[158:161], v[198:201], v[4:7]
	v_mfma_f32_16x16x32_bf16 v[0:3], v[166:169], v[198:201], v[0:3]
	s_barrier
	s_add_u32 s34, s34, 0x100
	s_addc_u32 s35, s35, 0
	s_cmp_ge_i32 s75, s0
	s_cbranch_scc0 .LBB0_295
	s_branch .LBB0_296
.Lhf_295:
	ds_read_b128 v[132:135], v137
	ds_read_b128 v[142:145], v137 offset:1024
	ds_read_b128 v[146:149], v137 offset:2048
	ds_read_b128 v[150:153], v137 offset:3072
	ds_read_b128 v[154:157], v138
	ds_read_b128 v[158:161], v138 offset:1024
	ds_read_b128 v[162:165], v138 offset:2048
	ds_read_b128 v[166:169], v138 offset:3072
	s_add_i32 s75, s75, 2
	s_add_u32 s77, s4, s34
	s_addc_u32 s80, s5, s35
	s_add_u32 s36, s77, 0x100
	s_addc_u32 s37, s80, 0
	s_add_u32 s81, s2, s34
	ds_read_b128 v[170:173], v139
	ds_read_b128 v[174:177], v139 offset:1024
	ds_read_b128 v[178:181], v139 offset:2048
	ds_read_b128 v[182:185], v139 offset:3072
	ds_read_b128 v[186:189], v139 offset:4096
	ds_read_b128 v[190:193], v139 offset:5120
	ds_read_b128 v[194:197], v139 offset:6144
	ds_read_b128 v[198:201], v139 offset:7168
	s_addc_u32 s84, s33, s35
	s_add_u32 s54, s81, 0x80
	s_addc_u32 s55, s84, 0
	s_add_u32 s85, s70, s34
	s_addc_u32 s86, s71, s35
	s_add_u32 s82, s85, 0x80
	s_mov_b32 m0, s67
	s_nop 0
	global_load_lds_dwordx4 v130, s[54:55]
	s_addc_u32 s83, s86, 0
	s_mov_b32 m0, s73
	s_nop 0
	global_load_lds_dwordx4 v130, s[82:83]
	s_waitcnt vmcnt(8)
	s_waitcnt lgkmcnt(0)
	s_barrier
	s_waitcnt lgkmcnt(7)
	v_mfma_f32_16x16x32_bf16 v[124:127], v[132:135], v[170:173], 0
	v_mfma_f32_16x16x32_bf16 v[120:123], v[146:149], v[170:173], 0
	s_waitcnt lgkmcnt(5)
	v_mfma_f32_16x16x32_bf16 v[116:119], v[132:135], v[178:181], 0
	v_mfma_f32_16x16x32_bf16 v[112:115], v[146:149], v[178:181], 0
	s_waitcnt lgkmcnt(3)
	v_mfma_f32_16x16x32_bf16 v[108:111], v[132:135], v[186:189], 0
	v_mfma_f32_16x16x32_bf16 v[104:107], v[146:149], v[186:189], 0
	s_waitcnt lgkmcnt(1)
	v_mfma_f32_16x16x32_bf16 v[100:103], v[132:135], v[194:197], 0
	v_mfma_f32_16x16x32_bf16 v[96:99], v[146:149], v[194:197], 0
	v_mfma_f32_16x16x32_bf16 v[124:127], v[142:145], v[174:177], v[124:127]
	v_mfma_f32_16x16x32_bf16 v[120:123], v[150:153], v[174:177], v[120:123]
	v_mfma_f32_16x16x32_bf16 v[116:119], v[142:145], v[182:185], v[116:119]
	v_mfma_f32_16x16x32_bf16 v[112:115], v[150:153], v[182:185], v[112:115]
	v_mfma_f32_16x16x32_bf16 v[108:111], v[142:145], v[190:193], v[108:111]
	v_mfma_f32_16x16x32_bf16 v[104:107], v[150:153], v[190:193], v[104:107]
	s_waitcnt lgkmcnt(0)
	v_mfma_f32_16x16x32_bf16 v[100:103], v[142:145], v[198:201], v[100:103]
	v_mfma_f32_16x16x32_bf16 v[96:99], v[150:153], v[198:201], v[96:99]
	v_mfma_f32_16x16x32_bf16 v[92:95], v[154:157], v[170:173], 0
	v_mfma_f32_16x16x32_bf16 v[88:91], v[162:165], v[170:173], 0
	v_mfma_f32_16x16x32_bf16 v[84:87], v[154:157], v[178:181], 0
	v_mfma_f32_16x16x32_bf16 v[80:83], v[162:165], v[178:181], 0
	v_mfma_f32_16x16x32_bf16 v[76:79], v[154:157], v[186:189], 0
	v_mfma_f32_16x16x32_bf16 v[72:75], v[162:165], v[186:189], 0
	v_mfma_f32_16x16x32_bf16 v[68:71], v[154:157], v[194:197], 0
	v_mfma_f32_16x16x32_bf16 v[64:67], v[162:165], v[194:197], 0
	v_mfma_f32_16x16x32_bf16 v[92:95], v[158:161], v[174:177], v[92:95]
	v_mfma_f32_16x16x32_bf16 v[88:91], v[166:169], v[174:177], v[88:91]
	v_mfma_f32_16x16x32_bf16 v[84:87], v[158:161], v[182:185], v[84:87]
	v_mfma_f32_16x16x32_bf16 v[80:83], v[166:169], v[182:185], v[80:83]
	v_mfma_f32_16x16x32_bf16 v[76:79], v[158:161], v[190:193], v[76:79]
	v_mfma_f32_16x16x32_bf16 v[72:75], v[166:169], v[190:193], v[72:75]
	v_mfma_f32_16x16x32_bf16 v[68:71], v[158:161], v[198:201], v[68:71]
	v_mfma_f32_16x16x32_bf16 v[64:67], v[166:169], v[198:201], v[64:67]
	s_barrier
	s_add_u32 s87, s6, s34
	s_addc_u32 s88, s7, s35
	s_add_u32 s54, s87, 0x100
	s_addc_u32 s55, s88, 0
	s_add_u32 s89, s68, s34
	s_addc_u32 s90, s69, s35
	s_add_u32 s82, s89, 0x100
	ds_read_b128 v[170:173], v139 offset:16384
	ds_read_b128 v[174:177], v139 offset:17408
	ds_read_b128 v[178:181], v139 offset:18432
	ds_read_b128 v[182:185], v139 offset:19456
	ds_read_b128 v[186:189], v139 offset:20480
	ds_read_b128 v[190:193], v139 offset:21504
	ds_read_b128 v[194:197], v139 offset:22528
	ds_read_b128 v[198:201], v139 offset:23552
	s_addc_u32 s83, s90, 0
	s_mov_b32 m0, s49
	s_nop 0
	global_load_lds_dwordx4 v131, s[54:55]
	s_add_u32 s91, s38, s34
	s_mov_b32 m0, s50
	s_nop 0
	global_load_lds_dwordx4 v131, s[82:83]
	s_addc_u32 s92, s39, s35
	s_add_u32 s54, s91, 0x100
	s_addc_u32 s55, s92, 0
	s_add_u32 s93, s46, s34
	s_addc_u32 s94, s47, s35
	s_add_u32 s82, s93, 0x100
	s_addc_u32 s83, s94, 0
	s_mov_b32 m0, s51
	s_nop 0
	global_load_lds_dwordx4 v131, s[54:55]
	s_mov_b32 m0, s57
	s_nop 0
	global_load_lds_dwordx4 v131, s[82:83]
	s_add_u32 s82, s72, s34
	s_addc_u32 s83, s74, s35
	s_add_u32 s54, s82, 0x100
	s_mov_b32 m0, s53
	s_nop 0
	global_load_lds_dwordx4 v130, s[36:37]
	s_addc_u32 s55, s83, 0
	s_mov_b32 m0, s58
	s_nop 0
	global_load_lds_dwordx4 v130, s[54:55]
	s_waitcnt vmcnt(8)
	s_waitcnt lgkmcnt(0)
	s_barrier
	s_waitcnt lgkmcnt(7)
	v_mfma_f32_16x16x32_bf16 v[60:63], v[132:135], v[170:173], 0
	v_mfma_f32_16x16x32_bf16 v[56:59], v[146:149], v[170:173], 0
	s_waitcnt lgkmcnt(5)
	v_mfma_f32_16x16x32_bf16 v[52:55], v[132:135], v[178:181], 0
	v_mfma_f32_16x16x32_bf16 v[48:51], v[146:149], v[178:181], 0
	s_waitcnt lgkmcnt(3)
	v_mfma_f32_16x16x32_bf16 v[44:47], v[132:135], v[186:189], 0
	v_mfma_f32_16x16x32_bf16 v[40:43], v[146:149], v[186:189], 0
	s_waitcnt lgkmcnt(1)
	v_mfma_f32_16x16x32_bf16 v[36:39], v[132:135], v[194:197], 0
	v_mfma_f32_16x16x32_bf16 v[32:35], v[146:149], v[194:197], 0
	v_mfma_f32_16x16x32_bf16 v[60:63], v[142:145], v[174:177], v[60:63]
	v_mfma_f32_16x16x32_bf16 v[56:59], v[150:153], v[174:177], v[56:59]
	v_mfma_f32_16x16x32_bf16 v[52:55], v[142:145], v[182:185], v[52:55]
	v_mfma_f32_16x16x32_bf16 v[48:51], v[150:153], v[182:185], v[48:51]
	v_mfma_f32_16x16x32_bf16 v[44:47], v[142:145], v[190:193], v[44:47]
	v_mfma_f32_16x16x32_bf16 v[40:43], v[150:153], v[190:193], v[40:43]
	s_waitcnt lgkmcnt(0)
	v_mfma_f32_16x16x32_bf16 v[36:39], v[142:145], v[198:201], v[36:39]
	v_mfma_f32_16x16x32_bf16 v[32:35], v[150:153], v[198:201], v[32:35]
	v_mfma_f32_16x16x32_bf16 v[28:31], v[154:157], v[170:173], 0
	v_mfma_f32_16x16x32_bf16 v[24:27], v[162:165], v[170:173], 0
	v_mfma_f32_16x16x32_bf16 v[20:23], v[154:157], v[178:181], 0
	v_mfma_f32_16x16x32_bf16 v[16:19], v[162:165], v[178:181], 0
	v_mfma_f32_16x16x32_bf16 v[12:15], v[154:157], v[186:189], 0
	v_mfma_f32_16x16x32_bf16 v[8:11], v[162:165], v[186:189], 0
	v_mfma_f32_16x16x32_bf16 v[4:7], v[154:157], v[194:197], 0
	v_mfma_f32_16x16x32_bf16 v[0:3], v[162:165], v[194:197], 0
	v_mfma_f32_16x16x32_bf16 v[28:31], v[158:161], v[174:177], v[28:31]
	v_mfma_f32_16x16x32_bf16 v[24:27], v[166:169], v[174:177], v[24:27]
	v_mfma_f32_16x16x32_bf16 v[20:23], v[158:161], v[182:185], v[20:23]
	v_mfma_f32_16x16x32_bf16 v[16:19], v[166:169], v[182:185], v[16:19]
	v_mfma_f32_16x16x32_bf16 v[12:15], v[158:161], v[190:193], v[12:15]
	v_mfma_f32_16x16x32_bf16 v[8:11], v[166:169], v[190:193], v[8:11]
	v_mfma_f32_16x16x32_bf16 v[4:7], v[158:161], v[198:201], v[4:7]
	v_mfma_f32_16x16x32_bf16 v[0:3], v[166:169], v[198:201], v[0:3]
	s_barrier
	ds_read_b128 v[132:135], v140
	ds_read_b128 v[142:145], v140 offset:1024
	ds_read_b128 v[146:149], v140 offset:2048
	ds_read_b128 v[150:153], v140 offset:3072
	ds_read_b128 v[154:157], v141
	ds_read_b128 v[158:161], v141 offset:1024
	ds_read_b128 v[162:165], v141 offset:2048
	ds_read_b128 v[166:169], v141 offset:3072
	ds_read_b128 v[170:173], v139 offset:32768
	ds_read_b128 v[174:177], v139 offset:33792
	ds_read_b128 v[178:181], v139 offset:34816
	ds_read_b128 v[182:185], v139 offset:35840
	ds_read_b128 v[186:189], v139 offset:36864
	ds_read_b128 v[190:193], v139 offset:37888
	ds_read_b128 v[194:197], v139 offset:38912
	ds_read_b128 v[198:201], v139 offset:39936
	s_add_u32 s36, s81, 0x100
	s_addc_u32 s37, s84, 0
	s_add_u32 s54, s85, 0x100
	s_mov_b32 m0, s59
	s_nop 0
	global_load_lds_dwordx4 v130, s[36:37]
	s_addc_u32 s55, s86, 0
	s_mov_b32 m0, s60
	s_nop 0
	global_load_lds_dwordx4 v130, s[54:55]
	s_waitcnt vmcnt(8)
	s_waitcnt lgkmcnt(0)
	s_barrier
	s_waitcnt lgkmcnt(7)
	v_mfma_f32_16x16x32_bf16 v[124:127], v[132:135], v[170:173], v[124:127]
	v_mfma_f32_16x16x32_bf16 v[120:123], v[146:149], v[170:173], v[120:123]
	s_waitcnt lgkmcnt(5)
	v_mfma_f32_16x16x32_bf16 v[116:119], v[132:135], v[178:181], v[116:119]
	v_mfma_f32_16x16x32_bf16 v[112:115], v[146:149], v[178:181], v[112:115]
	s_waitcnt lgkmcnt(3)
	v_mfma_f32_16x16x32_bf16 v[108:111], v[132:135], v[186:189], v[108:111]
	v_mfma_f32_16x16x32_bf16 v[104:107], v[146:149], v[186:189], v[104:107]
	s_waitcnt lgkmcnt(1)
	v_mfma_f32_16x16x32_bf16 v[100:103], v[132:135], v[194:197], v[100:103]
	v_mfma_f32_16x16x32_bf16 v[96:99], v[146:149], v[194:197], v[96:99]
	v_mfma_f32_16x16x32_bf16 v[124:127], v[142:145], v[174:177], v[124:127]
	v_mfma_f32_16x16x32_bf16 v[120:123], v[150:153], v[174:177], v[120:123]
	v_mfma_f32_16x16x32_bf16 v[116:119], v[142:145], v[182:185], v[116:119]
	v_mfma_f32_16x16x32_bf16 v[112:115], v[150:153], v[182:185], v[112:115]
	v_mfma_f32_16x16x32_bf16 v[108:111], v[142:145], v[190:193], v[108:111]
	v_mfma_f32_16x16x32_bf16 v[104:107], v[150:153], v[190:193], v[104:107]
	s_waitcnt lgkmcnt(0)
	v_mfma_f32_16x16x32_bf16 v[100:103], v[142:145], v[198:201], v[100:103]
	v_mfma_f32_16x16x32_bf16 v[96:99], v[150:153], v[198:201], v[96:99]
	v_mfma_f32_16x16x32_bf16 v[92:95], v[154:157], v[170:173], v[92:95]
	v_mfma_f32_16x16x32_bf16 v[88:91], v[162:165], v[170:173], v[88:91]
	v_mfma_f32_16x16x32_bf16 v[84:87], v[154:157], v[178:181], v[84:87]
	v_mfma_f32_16x16x32_bf16 v[80:83], v[162:165], v[178:181], v[80:83]
	v_mfma_f32_16x16x32_bf16 v[76:79], v[154:157], v[186:189], v[76:79]
	v_mfma_f32_16x16x32_bf16 v[72:75], v[162:165], v[186:189], v[72:75]
	v_mfma_f32_16x16x32_bf16 v[68:71], v[154:157], v[194:197], v[68:71]
	v_mfma_f32_16x16x32_bf16 v[64:67], v[162:165], v[194:197], v[64:67]
	v_mfma_f32_16x16x32_bf16 v[92:95], v[158:161], v[174:177], v[92:95]
	v_mfma_f32_16x16x32_bf16 v[88:91], v[166:169], v[174:177], v[88:91]
	v_mfma_f32_16x16x32_bf16 v[84:87], v[158:161], v[182:185], v[84:87]
	v_mfma_f32_16x16x32_bf16 v[80:83], v[166:169], v[182:185], v[80:83]
	v_mfma_f32_16x16x32_bf16 v[76:79], v[158:161], v[190:193], v[76:79]
	v_mfma_f32_16x16x32_bf16 v[72:75], v[166:169], v[190:193], v[72:75]
	v_mfma_f32_16x16x32_bf16 v[68:71], v[158:161], v[198:201], v[68:71]
	v_mfma_f32_16x16x32_bf16 v[64:67], v[166:169], v[198:201], v[64:67]
	s_barrier
	s_add_u32 s36, s87, 0x180
	s_addc_u32 s37, s88, 0
	ds_read_b128 v[170:173], v139 offset:49152
	ds_read_b128 v[174:177], v139 offset:50176
	ds_read_b128 v[178:181], v139 offset:51200
	ds_read_b128 v[182:185], v139 offset:52224
	ds_read_b128 v[186:189], v139 offset:53248
	ds_read_b128 v[190:193], v139 offset:54272
	ds_read_b128 v[194:197], v139 offset:55296
	ds_read_b128 v[198:201], v139 offset:56320
	s_add_u32 s54, s89, 0x180
	s_mov_b32 m0, s61
	s_nop 0
	global_load_lds_dwordx4 v131, s[36:37]
	s_addc_u32 s55, s90, 0
	s_mov_b32 m0, s62
	s_nop 0
	global_load_lds_dwordx4 v131, s[54:55]
	s_add_u32 s36, s91, 0x180
	s_addc_u32 s37, s92, 0
	s_add_u32 s54, s93, 0x180
	s_mov_b32 m0, s65
	s_nop 0
	global_load_lds_dwordx4 v131, s[36:37]
	s_addc_u32 s55, s94, 0
	s_mov_b32 m0, s66
	s_nop 0
	global_load_lds_dwordx4 v131, s[54:55]
	s_add_u32 s36, s77, 0x180
	s_addc_u32 s37, s80, 0
	s_add_u32 s54, s82, 0x180
	s_mov_b32 m0, s63
	s_nop 0
	global_load_lds_dwordx4 v130, s[36:37]
	s_addc_u32 s55, s83, 0
	s_mov_b32 m0, s64
	s_nop 0
	global_load_lds_dwordx4 v130, s[54:55]
	s_waitcnt vmcnt(8)
	s_waitcnt lgkmcnt(0)
	s_barrier
	s_waitcnt lgkmcnt(7)
	v_mfma_f32_16x16x32_bf16 v[60:63], v[132:135], v[170:173], v[60:63]
	v_mfma_f32_16x16x32_bf16 v[56:59], v[146:149], v[170:173], v[56:59]
	s_waitcnt lgkmcnt(5)
	v_mfma_f32_16x16x32_bf16 v[52:55], v[132:135], v[178:181], v[52:55]
	v_mfma_f32_16x16x32_bf16 v[48:51], v[146:149], v[178:181], v[48:51]
	s_waitcnt lgkmcnt(3)
	v_mfma_f32_16x16x32_bf16 v[44:47], v[132:135], v[186:189], v[44:47]
	v_mfma_f32_16x16x32_bf16 v[40:43], v[146:149], v[186:189], v[40:43]
	s_waitcnt lgkmcnt(1)
	v_mfma_f32_16x16x32_bf16 v[36:39], v[132:135], v[194:197], v[36:39]
	v_mfma_f32_16x16x32_bf16 v[32:35], v[146:149], v[194:197], v[32:35]
	v_mfma_f32_16x16x32_bf16 v[60:63], v[142:145], v[174:177], v[60:63]
	v_mfma_f32_16x16x32_bf16 v[56:59], v[150:153], v[174:177], v[56:59]
	v_mfma_f32_16x16x32_bf16 v[52:55], v[142:145], v[182:185], v[52:55]
	v_mfma_f32_16x16x32_bf16 v[48:51], v[150:153], v[182:185], v[48:51]
	v_mfma_f32_16x16x32_bf16 v[44:47], v[142:145], v[190:193], v[44:47]
	v_mfma_f32_16x16x32_bf16 v[40:43], v[150:153], v[190:193], v[40:43]
	s_waitcnt lgkmcnt(0)
	v_mfma_f32_16x16x32_bf16 v[36:39], v[142:145], v[198:201], v[36:39]
	v_mfma_f32_16x16x32_bf16 v[32:35], v[150:153], v[198:201], v[32:35]
	v_mfma_f32_16x16x32_bf16 v[28:31], v[154:157], v[170:173], v[28:31]
	v_mfma_f32_16x16x32_bf16 v[24:27], v[162:165], v[170:173], v[24:27]
	v_mfma_f32_16x16x32_bf16 v[20:23], v[154:157], v[178:181], v[20:23]
	v_mfma_f32_16x16x32_bf16 v[16:19], v[162:165], v[178:181], v[16:19]
	v_mfma_f32_16x16x32_bf16 v[12:15], v[154:157], v[186:189], v[12:15]
	v_mfma_f32_16x16x32_bf16 v[8:11], v[162:165], v[186:189], v[8:11]
	v_mfma_f32_16x16x32_bf16 v[4:7], v[154:157], v[194:197], v[4:7]
	v_mfma_f32_16x16x32_bf16 v[0:3], v[162:165], v[194:197], v[0:3]
	v_mfma_f32_16x16x32_bf16 v[28:31], v[158:161], v[174:177], v[28:31]
	v_mfma_f32_16x16x32_bf16 v[24:27], v[166:169], v[174:177], v[24:27]
	v_mfma_f32_16x16x32_bf16 v[20:23], v[158:161], v[182:185], v[20:23]
	v_mfma_f32_16x16x32_bf16 v[16:19], v[166:169], v[182:185], v[16:19]
	v_mfma_f32_16x16x32_bf16 v[12:15], v[158:161], v[190:193], v[12:15]
	v_mfma_f32_16x16x32_bf16 v[8:11], v[166:169], v[190:193], v[8:11]
	v_mfma_f32_16x16x32_bf16 v[4:7], v[158:161], v[198:201], v[4:7]
	v_mfma_f32_16x16x32_bf16 v[0:3], v[166:169], v[198:201], v[0:3]
	s_barrier
	s_add_u32 s34, s34, 0x100
	s_addc_u32 s35, s35, 0
	s_cmp_ge_i32 s75, s0
	s_cbranch_scc0 .LBB0_295
	s_branch .LBB0_296

.LBB0_295:
	ds_read_b128 v[132:135], v137
	ds_read_b128 v[142:145], v137 offset:1024
	ds_read_b128 v[146:149], v137 offset:2048
	ds_read_b128 v[150:153], v137 offset:3072
	ds_read_b128 v[154:157], v138
	ds_read_b128 v[158:161], v138 offset:1024
	ds_read_b128 v[162:165], v138 offset:2048
	ds_read_b128 v[166:169], v138 offset:3072
	s_add_i32 s75, s75, 2
	s_add_u32 s77, s4, s34
	s_addc_u32 s80, s5, s35
	s_add_u32 s36, s77, 0x100
	s_addc_u32 s37, s80, 0
	s_add_u32 s81, s2, s34
	ds_read_b128 v[170:173], v139
	ds_read_b128 v[174:177], v139 offset:1024
	ds_read_b128 v[178:181], v139 offset:2048
	ds_read_b128 v[182:185], v139 offset:3072
	ds_read_b128 v[186:189], v139 offset:4096
	ds_read_b128 v[190:193], v139 offset:5120
	ds_read_b128 v[194:197], v139 offset:6144
	ds_read_b128 v[198:201], v139 offset:7168
	s_addc_u32 s84, s33, s35
	s_add_u32 s54, s81, 0x80
	s_addc_u32 s55, s84, 0
	s_add_u32 s85, s70, s34
	s_addc_u32 s86, s71, s35
	s_add_u32 s82, s85, 0x80
	s_mov_b32 m0, s67
	s_nop 0
	global_load_lds_dwordx4 v130, s[54:55]
	s_addc_u32 s83, s86, 0
	s_mov_b32 m0, s73
	s_nop 0
	global_load_lds_dwordx4 v130, s[82:83]
	s_waitcnt vmcnt(8)
	s_waitcnt lgkmcnt(0)
	s_barrier
	s_waitcnt lgkmcnt(7)
	v_mfma_f32_16x16x32_bf16 v[124:127], v[132:135], v[170:173], v[124:127]
	v_mfma_f32_16x16x32_bf16 v[120:123], v[146:149], v[170:173], v[120:123]
	s_waitcnt lgkmcnt(5)
	v_mfma_f32_16x16x32_bf16 v[116:119], v[132:135], v[178:181], v[116:119]
	v_mfma_f32_16x16x32_bf16 v[112:115], v[146:149], v[178:181], v[112:115]
	s_waitcnt lgkmcnt(3)
	v_mfma_f32_16x16x32_bf16 v[108:111], v[132:135], v[186:189], v[108:111]
	v_mfma_f32_16x16x32_bf16 v[104:107], v[146:149], v[186:189], v[104:107]
	s_waitcnt lgkmcnt(1)
	v_mfma_f32_16x16x32_bf16 v[100:103], v[132:135], v[194:197], v[100:103]
	v_mfma_f32_16x16x32_bf16 v[96:99], v[146:149], v[194:197], v[96:99]
	v_mfma_f32_16x16x32_bf16 v[124:127], v[142:145], v[174:177], v[124:127]
	v_mfma_f32_16x16x32_bf16 v[120:123], v[150:153], v[174:177], v[120:123]
	v_mfma_f32_16x16x32_bf16 v[116:119], v[142:145], v[182:185], v[116:119]
	v_mfma_f32_16x16x32_bf16 v[112:115], v[150:153], v[182:185], v[112:115]
	v_mfma_f32_16x16x32_bf16 v[108:111], v[142:145], v[190:193], v[108:111]
	v_mfma_f32_16x16x32_bf16 v[104:107], v[150:153], v[190:193], v[104:107]
	s_waitcnt lgkmcnt(0)
	v_mfma_f32_16x16x32_bf16 v[100:103], v[142:145], v[198:201], v[100:103]
	v_mfma_f32_16x16x32_bf16 v[96:99], v[150:153], v[198:201], v[96:99]
	v_mfma_f32_16x16x32_bf16 v[92:95], v[154:157], v[170:173], v[92:95]
	v_mfma_f32_16x16x32_bf16 v[88:91], v[162:165], v[170:173], v[88:91]
	v_mfma_f32_16x16x32_bf16 v[84:87], v[154:157], v[178:181], v[84:87]
	v_mfma_f32_16x16x32_bf16 v[80:83], v[162:165], v[178:181], v[80:83]
	v_mfma_f32_16x16x32_bf16 v[76:79], v[154:157], v[186:189], v[76:79]
	v_mfma_f32_16x16x32_bf16 v[72:75], v[162:165], v[186:189], v[72:75]
	v_mfma_f32_16x16x32_bf16 v[68:71], v[154:157], v[194:197], v[68:71]
	v_mfma_f32_16x16x32_bf16 v[64:67], v[162:165], v[194:197], v[64:67]
	v_mfma_f32_16x16x32_bf16 v[92:95], v[158:161], v[174:177], v[92:95]
	v_mfma_f32_16x16x32_bf16 v[88:91], v[166:169], v[174:177], v[88:91]
	v_mfma_f32_16x16x32_bf16 v[84:87], v[158:161], v[182:185], v[84:87]
	v_mfma_f32_16x16x32_bf16 v[80:83], v[166:169], v[182:185], v[80:83]
	v_mfma_f32_16x16x32_bf16 v[76:79], v[158:161], v[190:193], v[76:79]
	v_mfma_f32_16x16x32_bf16 v[72:75], v[166:169], v[190:193], v[72:75]
	v_mfma_f32_16x16x32_bf16 v[68:71], v[158:161], v[198:201], v[68:71]
	v_mfma_f32_16x16x32_bf16 v[64:67], v[166:169], v[198:201], v[64:67]
	s_barrier
	s_add_u32 s87, s6, s34
	s_addc_u32 s88, s7, s35
	s_add_u32 s54, s87, 0x100
	s_addc_u32 s55, s88, 0
	s_add_u32 s89, s68, s34
	s_addc_u32 s90, s69, s35
	s_add_u32 s82, s89, 0x100
	ds_read_b128 v[170:173], v139 offset:16384
	ds_read_b128 v[174:177], v139 offset:17408
	ds_read_b128 v[178:181], v139 offset:18432
	ds_read_b128 v[182:185], v139 offset:19456
	ds_read_b128 v[186:189], v139 offset:20480
	ds_read_b128 v[190:193], v139 offset:21504
	ds_read_b128 v[194:197], v139 offset:22528
	ds_read_b128 v[198:201], v139 offset:23552
	s_addc_u32 s83, s90, 0
	s_mov_b32 m0, s49
	s_nop 0
	global_load_lds_dwordx4 v131, s[54:55]
	s_add_u32 s91, s38, s34
	s_mov_b32 m0, s50
	s_nop 0
	global_load_lds_dwordx4 v131, s[82:83]
	s_addc_u32 s92, s39, s35
	s_add_u32 s54, s91, 0x100
	s_addc_u32 s55, s92, 0
	s_add_u32 s93, s46, s34
	s_addc_u32 s94, s47, s35
	s_add_u32 s82, s93, 0x100
	s_addc_u32 s83, s94, 0
	s_mov_b32 m0, s51
	s_nop 0
	global_load_lds_dwordx4 v131, s[54:55]
	s_mov_b32 m0, s57
	s_nop 0
	global_load_lds_dwordx4 v131, s[82:83]
	s_add_u32 s82, s72, s34
	s_addc_u32 s83, s74, s35
	s_add_u32 s54, s82, 0x100
	s_mov_b32 m0, s53
	s_nop 0
	global_load_lds_dwordx4 v130, s[36:37]
	s_addc_u32 s55, s83, 0
	s_mov_b32 m0, s58
	s_nop 0
	global_load_lds_dwordx4 v130, s[54:55]
	s_waitcnt vmcnt(8)
	s_waitcnt lgkmcnt(0)
	s_barrier
	s_waitcnt lgkmcnt(7)
	v_mfma_f32_16x16x32_bf16 v[60:63], v[132:135], v[170:173], v[60:63]
	v_mfma_f32_16x16x32_bf16 v[56:59], v[146:149], v[170:173], v[56:59]
	s_waitcnt lgkmcnt(5)
	v_mfma_f32_16x16x32_bf16 v[52:55], v[132:135], v[178:181], v[52:55]
	v_mfma_f32_16x16x32_bf16 v[48:51], v[146:149], v[178:181], v[48:51]
	s_waitcnt lgkmcnt(3)
	v_mfma_f32_16x16x32_bf16 v[44:47], v[132:135], v[186:189], v[44:47]
	v_mfma_f32_16x16x32_bf16 v[40:43], v[146:149], v[186:189], v[40:43]
	s_waitcnt lgkmcnt(1)
	v_mfma_f32_16x16x32_bf16 v[36:39], v[132:135], v[194:197], v[36:39]
	v_mfma_f32_16x16x32_bf16 v[32:35], v[146:149], v[194:197], v[32:35]
	v_mfma_f32_16x16x32_bf16 v[60:63], v[142:145], v[174:177], v[60:63]
	v_mfma_f32_16x16x32_bf16 v[56:59], v[150:153], v[174:177], v[56:59]
	v_mfma_f32_16x16x32_bf16 v[52:55], v[142:145], v[182:185], v[52:55]
	v_mfma_f32_16x16x32_bf16 v[48:51], v[150:153], v[182:185], v[48:51]
	v_mfma_f32_16x16x32_bf16 v[44:47], v[142:145], v[190:193], v[44:47]
	v_mfma_f32_16x16x32_bf16 v[40:43], v[150:153], v[190:193], v[40:43]
	s_waitcnt lgkmcnt(0)
	v_mfma_f32_16x16x32_bf16 v[36:39], v[142:145], v[198:201], v[36:39]
	v_mfma_f32_16x16x32_bf16 v[32:35], v[150:153], v[198:201], v[32:35]
	v_mfma_f32_16x16x32_bf16 v[28:31], v[154:157], v[170:173], v[28:31]
	v_mfma_f32_16x16x32_bf16 v[24:27], v[162:165], v[170:173], v[24:27]
	v_mfma_f32_16x16x32_bf16 v[20:23], v[154:157], v[178:181], v[20:23]
	v_mfma_f32_16x16x32_bf16 v[16:19], v[162:165], v[178:181], v[16:19]
	v_mfma_f32_16x16x32_bf16 v[12:15], v[154:157], v[186:189], v[12:15]
	v_mfma_f32_16x16x32_bf16 v[8:11], v[162:165], v[186:189], v[8:11]
	v_mfma_f32_16x16x32_bf16 v[4:7], v[154:157], v[194:197], v[4:7]
	v_mfma_f32_16x16x32_bf16 v[0:3], v[162:165], v[194:197], v[0:3]
	v_mfma_f32_16x16x32_bf16 v[28:31], v[158:161], v[174:177], v[28:31]
	v_mfma_f32_16x16x32_bf16 v[24:27], v[166:169], v[174:177], v[24:27]
	v_mfma_f32_16x16x32_bf16 v[20:23], v[158:161], v[182:185], v[20:23]
	v_mfma_f32_16x16x32_bf16 v[16:19], v[166:169], v[182:185], v[16:19]
	v_mfma_f32_16x16x32_bf16 v[12:15], v[158:161], v[190:193], v[12:15]
	v_mfma_f32_16x16x32_bf16 v[8:11], v[166:169], v[190:193], v[8:11]
	v_mfma_f32_16x16x32_bf16 v[4:7], v[158:161], v[198:201], v[4:7]
	v_mfma_f32_16x16x32_bf16 v[0:3], v[166:169], v[198:201], v[0:3]
	s_barrier
	ds_read_b128 v[132:135], v140
	ds_read_b128 v[142:145], v140 offset:1024
	ds_read_b128 v[146:149], v140 offset:2048
	ds_read_b128 v[150:153], v140 offset:3072
	ds_read_b128 v[154:157], v141
	ds_read_b128 v[158:161], v141 offset:1024
	ds_read_b128 v[162:165], v141 offset:2048
	ds_read_b128 v[166:169], v141 offset:3072
	ds_read_b128 v[170:173], v139 offset:32768
	ds_read_b128 v[174:177], v139 offset:33792
	ds_read_b128 v[178:181], v139 offset:34816
	ds_read_b128 v[182:185], v139 offset:35840
	ds_read_b128 v[186:189], v139 offset:36864
	ds_read_b128 v[190:193], v139 offset:37888
	ds_read_b128 v[194:197], v139 offset:38912
	ds_read_b128 v[198:201], v139 offset:39936
	s_add_u32 s36, s81, 0x100
	s_addc_u32 s37, s84, 0
	s_add_u32 s54, s85, 0x100
	s_mov_b32 m0, s59
	s_nop 0
	global_load_lds_dwordx4 v130, s[36:37]
	s_addc_u32 s55, s86, 0
	s_mov_b32 m0, s60
	s_nop 0
	global_load_lds_dwordx4 v130, s[54:55]
	s_waitcnt vmcnt(8)
	s_waitcnt lgkmcnt(0)
	s_barrier
	s_waitcnt lgkmcnt(7)
	v_mfma_f32_16x16x32_bf16 v[124:127], v[132:135], v[170:173], v[124:127]
	v_mfma_f32_16x16x32_bf16 v[120:123], v[146:149], v[170:173], v[120:123]
	s_waitcnt lgkmcnt(5)
	v_mfma_f32_16x16x32_bf16 v[116:119], v[132:135], v[178:181], v[116:119]
	v_mfma_f32_16x16x32_bf16 v[112:115], v[146:149], v[178:181], v[112:115]
	s_waitcnt lgkmcnt(3)
	v_mfma_f32_16x16x32_bf16 v[108:111], v[132:135], v[186:189], v[108:111]
	v_mfma_f32_16x16x32_bf16 v[104:107], v[146:149], v[186:189], v[104:107]
	s_waitcnt lgkmcnt(1)
	v_mfma_f32_16x16x32_bf16 v[100:103], v[132:135], v[194:197], v[100:103]
	v_mfma_f32_16x16x32_bf16 v[96:99], v[146:149], v[194:197], v[96:99]
	v_mfma_f32_16x16x32_bf16 v[124:127], v[142:145], v[174:177], v[124:127]
	v_mfma_f32_16x16x32_bf16 v[120:123], v[150:153], v[174:177], v[120:123]
	v_mfma_f32_16x16x32_bf16 v[116:119], v[142:145], v[182:185], v[116:119]
	v_mfma_f32_16x16x32_bf16 v[112:115], v[150:153], v[182:185], v[112:115]
	v_mfma_f32_16x16x32_bf16 v[108:111], v[142:145], v[190:193], v[108:111]
	v_mfma_f32_16x16x32_bf16 v[104:107], v[150:153], v[190:193], v[104:107]
	s_waitcnt lgkmcnt(0)
	v_mfma_f32_16x16x32_bf16 v[100:103], v[142:145], v[198:201], v[100:103]
	v_mfma_f32_16x16x32_bf16 v[96:99], v[150:153], v[198:201], v[96:99]
	v_mfma_f32_16x16x32_bf16 v[92:95], v[154:157], v[170:173], v[92:95]
	v_mfma_f32_16x16x32_bf16 v[88:91], v[162:165], v[170:173], v[88:91]
	v_mfma_f32_16x16x32_bf16 v[84:87], v[154:157], v[178:181], v[84:87]
	v_mfma_f32_16x16x32_bf16 v[80:83], v[162:165], v[178:181], v[80:83]
	v_mfma_f32_16x16x32_bf16 v[76:79], v[154:157], v[186:189], v[76:79]
	v_mfma_f32_16x16x32_bf16 v[72:75], v[162:165], v[186:189], v[72:75]
	v_mfma_f32_16x16x32_bf16 v[68:71], v[154:157], v[194:197], v[68:71]
	v_mfma_f32_16x16x32_bf16 v[64:67], v[162:165], v[194:197], v[64:67]
	v_mfma_f32_16x16x32_bf16 v[92:95], v[158:161], v[174:177], v[92:95]
	v_mfma_f32_16x16x32_bf16 v[88:91], v[166:169], v[174:177], v[88:91]
	v_mfma_f32_16x16x32_bf16 v[84:87], v[158:161], v[182:185], v[84:87]
	v_mfma_f32_16x16x32_bf16 v[80:83], v[166:169], v[182:185], v[80:83]
	v_mfma_f32_16x16x32_bf16 v[76:79], v[158:161], v[190:193], v[76:79]
	v_mfma_f32_16x16x32_bf16 v[72:75], v[166:169], v[190:193], v[72:75]
	v_mfma_f32_16x16x32_bf16 v[68:71], v[158:161], v[198:201], v[68:71]
	v_mfma_f32_16x16x32_bf16 v[64:67], v[166:169], v[198:201], v[64:67]
	s_barrier
	s_add_u32 s36, s87, 0x180
	s_addc_u32 s37, s88, 0
	ds_read_b128 v[170:173], v139 offset:49152
	ds_read_b128 v[174:177], v139 offset:50176
	ds_read_b128 v[178:181], v139 offset:51200
	ds_read_b128 v[182:185], v139 offset:52224
	ds_read_b128 v[186:189], v139 offset:53248
	ds_read_b128 v[190:193], v139 offset:54272
	ds_read_b128 v[194:197], v139 offset:55296
	ds_read_b128 v[198:201], v139 offset:56320
	s_add_u32 s54, s89, 0x180
	s_mov_b32 m0, s61
	s_nop 0
	global_load_lds_dwordx4 v131, s[36:37]
	s_addc_u32 s55, s90, 0
	s_mov_b32 m0, s62
	s_nop 0
	global_load_lds_dwordx4 v131, s[54:55]
	s_add_u32 s36, s91, 0x180
	s_addc_u32 s37, s92, 0
	s_add_u32 s54, s93, 0x180
	s_mov_b32 m0, s65
	s_nop 0
	global_load_lds_dwordx4 v131, s[36:37]
	s_addc_u32 s55, s94, 0
	s_mov_b32 m0, s66
	s_nop 0
	global_load_lds_dwordx4 v131, s[54:55]
	s_add_u32 s36, s77, 0x180
	s_addc_u32 s37, s80, 0
	s_add_u32 s54, s82, 0x180
	s_mov_b32 m0, s63
	s_nop 0
	global_load_lds_dwordx4 v130, s[36:37]
	s_addc_u32 s55, s83, 0
	s_mov_b32 m0, s64
	s_nop 0
	global_load_lds_dwordx4 v130, s[54:55]
	s_waitcnt vmcnt(8)
	s_waitcnt lgkmcnt(0)
	s_barrier
	s_waitcnt lgkmcnt(7)
	v_mfma_f32_16x16x32_bf16 v[60:63], v[132:135], v[170:173], v[60:63]
	v_mfma_f32_16x16x32_bf16 v[56:59], v[146:149], v[170:173], v[56:59]
	s_waitcnt lgkmcnt(5)
	v_mfma_f32_16x16x32_bf16 v[52:55], v[132:135], v[178:181], v[52:55]
	v_mfma_f32_16x16x32_bf16 v[48:51], v[146:149], v[178:181], v[48:51]
	s_waitcnt lgkmcnt(3)
	v_mfma_f32_16x16x32_bf16 v[44:47], v[132:135], v[186:189], v[44:47]
	v_mfma_f32_16x16x32_bf16 v[40:43], v[146:149], v[186:189], v[40:43]
	s_waitcnt lgkmcnt(1)
	v_mfma_f32_16x16x32_bf16 v[36:39], v[132:135], v[194:197], v[36:39]
	v_mfma_f32_16x16x32_bf16 v[32:35], v[146:149], v[194:197], v[32:35]
	v_mfma_f32_16x16x32_bf16 v[60:63], v[142:145], v[174:177], v[60:63]
	v_mfma_f32_16x16x32_bf16 v[56:59], v[150:153], v[174:177], v[56:59]
	v_mfma_f32_16x16x32_bf16 v[52:55], v[142:145], v[182:185], v[52:55]
	v_mfma_f32_16x16x32_bf16 v[48:51], v[150:153], v[182:185], v[48:51]
	v_mfma_f32_16x16x32_bf16 v[44:47], v[142:145], v[190:193], v[44:47]
	v_mfma_f32_16x16x32_bf16 v[40:43], v[150:153], v[190:193], v[40:43]
	s_waitcnt lgkmcnt(0)
	v_mfma_f32_16x16x32_bf16 v[36:39], v[142:145], v[198:201], v[36:39]
	v_mfma_f32_16x16x32_bf16 v[32:35], v[150:153], v[198:201], v[32:35]
	v_mfma_f32_16x16x32_bf16 v[28:31], v[154:157], v[170:173], v[28:31]
	v_mfma_f32_16x16x32_bf16 v[24:27], v[162:165], v[170:173], v[24:27]
	v_mfma_f32_16x16x32_bf16 v[20:23], v[154:157], v[178:181], v[20:23]
	v_mfma_f32_16x16x32_bf16 v[16:19], v[162:165], v[178:181], v[16:19]
	v_mfma_f32_16x16x32_bf16 v[12:15], v[154:157], v[186:189], v[12:15]
	v_mfma_f32_16x16x32_bf16 v[8:11], v[162:165], v[186:189], v[8:11]
	v_mfma_f32_16x16x32_bf16 v[4:7], v[154:157], v[194:197], v[4:7]
	v_mfma_f32_16x16x32_bf16 v[0:3], v[162:165], v[194:197], v[0:3]
	v_mfma_f32_16x16x32_bf16 v[28:31], v[158:161], v[174:177], v[28:31]
	v_mfma_f32_16x16x32_bf16 v[24:27], v[166:169], v[174:177], v[24:27]
	v_mfma_f32_16x16x32_bf16 v[20:23], v[158:161], v[182:185], v[20:23]
	v_mfma_f32_16x16x32_bf16 v[16:19], v[166:169], v[182:185], v[16:19]
	v_mfma_f32_16x16x32_bf16 v[12:15], v[158:161], v[190:193], v[12:15]
	v_mfma_f32_16x16x32_bf16 v[8:11], v[166:169], v[190:193], v[8:11]
	v_mfma_f32_16x16x32_bf16 v[4:7], v[158:161], v[198:201], v[4:7]
	v_mfma_f32_16x16x32_bf16 v[0:3], v[166:169], v[198:201], v[0:3]
	s_barrier
	s_add_u32 s34, s34, 0x100
	s_addc_u32 s35, s35, 0
	s_cmp_ge_i32 s75, s0
	s_cbranch_scc0 .LBB0_295

.LBB0_298:
	ds_read_b128 v[132:135], v137
	ds_read_b128 v[142:145], v137 offset:1024
	ds_read_b128 v[146:149], v137 offset:2048
	ds_read_b128 v[150:153], v137 offset:3072
	ds_read_b128 v[154:157], v138
	ds_read_b128 v[158:161], v138 offset:1024
	ds_read_b128 v[162:165], v138 offset:2048
	ds_read_b128 v[166:169], v138 offset:3072
	s_ashr_i32 s47, s30, 31
	s_mov_b32 s46, s30
	s_lshl_b64 s[46:47], s[46:47], 7
	s_add_u32 s0, s4, s46
	ds_read_b128 v[170:173], v139
	ds_read_b128 v[174:177], v139 offset:1024
	ds_read_b128 v[178:181], v139 offset:2048
	ds_read_b128 v[182:185], v139 offset:3072
	ds_read_b128 v[186:189], v139 offset:4096
	ds_read_b128 v[190:193], v139 offset:5120
	ds_read_b128 v[194:197], v139 offset:6144
	ds_read_b128 v[198:201], v139 offset:7168
	s_addc_u32 s2, s5, s47
	s_add_u32 s0, s0, s44
	s_addc_u32 s2, s2, s45
	s_add_u32 s4, s0, 0xffffff80
	s_addc_u32 s5, s2, -1
	s_add_u32 s42, s4, s42
	s_mov_b32 m0, s67
	s_nop 0
	global_load_lds_dwordx4 v130, s[4:5]
	s_addc_u32 s43, s5, s43
	s_mov_b32 m0, s73
	s_nop 0
	global_load_lds_dwordx4 v130, s[42:43]
	s_waitcnt vmcnt(8)
	s_waitcnt lgkmcnt(0)
	s_barrier
	s_waitcnt lgkmcnt(7)
	v_mfma_f32_16x16x32_bf16 v[124:127], v[132:135], v[170:173], v[124:127]
	v_mfma_f32_16x16x32_bf16 v[120:123], v[146:149], v[170:173], v[120:123]
	s_waitcnt lgkmcnt(5)
	v_mfma_f32_16x16x32_bf16 v[116:119], v[132:135], v[178:181], v[116:119]
	v_mfma_f32_16x16x32_bf16 v[112:115], v[146:149], v[178:181], v[112:115]
	s_waitcnt lgkmcnt(1)
	v_mfma_f32_16x16x32_bf16 v[100:103], v[132:135], v[194:197], v[100:103]
	v_mfma_f32_16x16x32_bf16 v[96:99], v[146:149], v[194:197], v[96:99]
	v_mfma_f32_16x16x32_bf16 v[124:127], v[142:145], v[174:177], v[124:127]
	v_mfma_f32_16x16x32_bf16 v[120:123], v[150:153], v[174:177], v[120:123]
	v_mfma_f32_16x16x32_bf16 v[116:119], v[142:145], v[182:185], v[116:119]
	v_mfma_f32_16x16x32_bf16 v[112:115], v[150:153], v[182:185], v[112:115]
	v_mfma_f32_16x16x32_bf16 v[108:111], v[132:135], v[186:189], v[108:111]
	v_mfma_f32_16x16x32_bf16 v[104:107], v[146:149], v[186:189], v[104:107]
	s_waitcnt lgkmcnt(0)
	v_mfma_f32_16x16x32_bf16 v[100:103], v[142:145], v[198:201], v[100:103]
	v_mfma_f32_16x16x32_bf16 v[96:99], v[150:153], v[198:201], v[96:99]
	v_mfma_f32_16x16x32_bf16 v[202:205], v[142:145], v[190:193], v[108:111]
	v_mfma_f32_16x16x32_bf16 v[206:209], v[150:153], v[190:193], v[104:107]
	v_mfma_f32_16x16x32_bf16 v[84:87], v[154:157], v[178:181], v[84:87]
	v_mfma_f32_16x16x32_bf16 v[80:83], v[162:165], v[178:181], v[80:83]
	v_mfma_f32_16x16x32_bf16 v[68:71], v[154:157], v[194:197], v[68:71]
	v_mfma_f32_16x16x32_bf16 v[64:67], v[162:165], v[194:197], v[64:67]
	v_mfma_f32_16x16x32_bf16 v[92:95], v[154:157], v[170:173], v[92:95]
	v_mfma_f32_16x16x32_bf16 v[88:91], v[162:165], v[170:173], v[88:91]
	v_mfma_f32_16x16x32_bf16 v[84:87], v[158:161], v[182:185], v[84:87]
	v_mfma_f32_16x16x32_bf16 v[80:83], v[166:169], v[182:185], v[80:83]
	v_mfma_f32_16x16x32_bf16 v[76:79], v[154:157], v[186:189], v[76:79]
	v_mfma_f32_16x16x32_bf16 v[72:75], v[162:165], v[186:189], v[72:75]
	v_mfma_f32_16x16x32_bf16 v[68:71], v[158:161], v[198:201], v[68:71]
	v_mfma_f32_16x16x32_bf16 v[64:67], v[166:169], v[198:201], v[64:67]
	v_mfma_f32_16x16x32_bf16 v[210:213], v[158:161], v[174:177], v[92:95]
	v_mfma_f32_16x16x32_bf16 v[170:173], v[166:169], v[174:177], v[88:91]
	v_mfma_f32_16x16x32_bf16 v[174:177], v[158:161], v[190:193], v[76:79]
	v_mfma_f32_16x16x32_bf16 v[178:181], v[166:169], v[190:193], v[72:75]
	s_barrier
	s_add_u32 s42, s6, s16
	ds_read_b128 v[72:75], v139 offset:16384
	ds_read_b128 v[76:79], v139 offset:17408
	ds_read_b128 v[88:91], v139 offset:18432
	ds_read_b128 v[92:95], v139 offset:19456
	ds_read_b128 v[104:107], v139 offset:20480
	ds_read_b128 v[108:111], v139 offset:21504
	ds_read_b128 v[182:185], v139 offset:22528
	ds_read_b128 v[186:189], v139 offset:23552
	s_addc_u32 s43, s7, s17
	s_mov_b32 m0, s49
	s_nop 0
	global_load_lds_dwordx4 v129, s[6:7]
	s_add_u32 s44, s6, s22
	s_mov_b32 m0, s50
	s_nop 0
	global_load_lds_dwordx4 v129, s[42:43]
	s_addc_u32 s45, s7, s23
	s_add_u32 s46, s44, s16
	s_mov_b32 m0, s51
	s_nop 0
	global_load_lds_dwordx4 v129, s[44:45]
	s_addc_u32 s47, s45, s17
	s_mov_b32 m0, s57
	s_nop 0
	global_load_lds_dwordx4 v129, s[46:47]
	s_add_u32 s4, s38, s36
	s_mov_b32 m0, s53
	s_nop 0
	global_load_lds_dwordx4 v128, s[38:39]
	s_addc_u32 s5, s39, s37
	s_mov_b32 m0, s58
	s_nop 0
	global_load_lds_dwordx4 v128, s[4:5]
	s_waitcnt vmcnt(8)
	s_waitcnt lgkmcnt(0)
	s_barrier
	s_waitcnt lgkmcnt(7)
	v_mfma_f32_16x16x32_bf16 v[60:63], v[132:135], v[72:75], v[60:63]
	v_mfma_f32_16x16x32_bf16 v[56:59], v[146:149], v[72:75], v[56:59]
	s_waitcnt lgkmcnt(5)
	v_mfma_f32_16x16x32_bf16 v[52:55], v[132:135], v[88:91], v[52:55]
	v_mfma_f32_16x16x32_bf16 v[48:51], v[146:149], v[88:91], v[48:51]
	s_waitcnt lgkmcnt(1)
	v_mfma_f32_16x16x32_bf16 v[36:39], v[132:135], v[182:185], v[36:39]
	v_mfma_f32_16x16x32_bf16 v[32:35], v[146:149], v[182:185], v[32:35]
	v_mfma_f32_16x16x32_bf16 v[60:63], v[142:145], v[76:79], v[60:63]
	v_mfma_f32_16x16x32_bf16 v[56:59], v[150:153], v[76:79], v[56:59]
	v_mfma_f32_16x16x32_bf16 v[52:55], v[142:145], v[92:95], v[52:55]
	v_mfma_f32_16x16x32_bf16 v[48:51], v[150:153], v[92:95], v[48:51]
	v_mfma_f32_16x16x32_bf16 v[44:47], v[132:135], v[104:107], v[44:47]
	v_mfma_f32_16x16x32_bf16 v[40:43], v[146:149], v[104:107], v[40:43]
	s_waitcnt lgkmcnt(0)
	v_mfma_f32_16x16x32_bf16 v[36:39], v[142:145], v[186:189], v[36:39]
	v_mfma_f32_16x16x32_bf16 v[32:35], v[150:153], v[186:189], v[32:35]
	v_mfma_f32_16x16x32_bf16 v[190:193], v[142:145], v[108:111], v[44:47]
	v_mfma_f32_16x16x32_bf16 v[194:197], v[150:153], v[108:111], v[40:43]
	v_mfma_f32_16x16x32_bf16 v[20:23], v[154:157], v[88:91], v[20:23]
	v_mfma_f32_16x16x32_bf16 v[16:19], v[162:165], v[88:91], v[16:19]
	v_mfma_f32_16x16x32_bf16 v[4:7], v[154:157], v[182:185], v[4:7]
	v_mfma_f32_16x16x32_bf16 v[0:3], v[162:165], v[182:185], v[0:3]
	v_mfma_f32_16x16x32_bf16 v[28:31], v[154:157], v[72:75], v[28:31]
	v_mfma_f32_16x16x32_bf16 v[24:27], v[162:165], v[72:75], v[24:27]
	v_mfma_f32_16x16x32_bf16 v[20:23], v[158:161], v[92:95], v[20:23]
	v_mfma_f32_16x16x32_bf16 v[16:19], v[166:169], v[92:95], v[16:19]
	v_mfma_f32_16x16x32_bf16 v[12:15], v[154:157], v[104:107], v[12:15]
	v_mfma_f32_16x16x32_bf16 v[8:11], v[162:165], v[104:107], v[8:11]
	v_mfma_f32_16x16x32_bf16 v[4:7], v[158:161], v[186:189], v[4:7]
	v_mfma_f32_16x16x32_bf16 v[0:3], v[166:169], v[186:189], v[0:3]
	v_mfma_f32_16x16x32_bf16 v[130:133], v[158:161], v[76:79], v[28:31]
	v_mfma_f32_16x16x32_bf16 v[142:145], v[166:169], v[76:79], v[24:27]
	v_mfma_f32_16x16x32_bf16 v[146:149], v[158:161], v[108:111], v[12:15]
	v_mfma_f32_16x16x32_bf16 v[150:153], v[166:169], v[108:111], v[8:11]
	s_barrier
	s_nop 0
	ds_read_b128 v[8:11], v140
	ds_read_b128 v[12:15], v140 offset:1024
	ds_read_b128 v[154:157], v140 offset:2048
	ds_read_b128 v[158:161], v140 offset:3072
	ds_read_b128 v[162:165], v141
	ds_read_b128 v[166:169], v141 offset:1024
	ds_read_b128 v[182:185], v141 offset:2048
	ds_read_b128 v[186:189], v141 offset:3072
	ds_read_b128 v[24:27], v139 offset:32768
	ds_read_b128 v[28:31], v139 offset:33792
	ds_read_b128 v[40:43], v139 offset:34816
	ds_read_b128 v[44:47], v139 offset:35840
	ds_read_b128 v[198:201], v139 offset:36864
	ds_read_b128 v[214:217], v139 offset:37888
	ds_read_b128 v[218:221], v139 offset:38912
	ds_read_b128 v[222:225], v139 offset:39936
	s_add_u32 s54, s38, s34
	s_addc_u32 s55, s39, s35
	s_add_u32 s68, s54, s36
	s_mov_b32 m0, s59
	s_nop 0
	global_load_lds_dwordx4 v128, s[54:55]
	s_addc_u32 s69, s55, s37
	s_mov_b32 m0, s60
	s_nop 0
	global_load_lds_dwordx4 v128, s[68:69]
	s_waitcnt vmcnt(8)
	s_waitcnt lgkmcnt(0)
	s_barrier
	s_waitcnt lgkmcnt(7)
	v_mfma_f32_16x16x32_bf16 v[72:75], v[8:11], v[24:27], v[124:127]
	s_waitcnt lgkmcnt(6)
	v_mfma_f32_16x16x32_bf16 v[124:127], v[12:15], v[28:31], v[72:75]
	v_mfma_f32_16x16x32_bf16 v[72:75], v[154:157], v[24:27], v[120:123]
	v_mfma_f32_16x16x32_bf16 v[120:123], v[158:161], v[28:31], v[72:75]
	s_waitcnt lgkmcnt(5)
	v_mfma_f32_16x16x32_bf16 v[72:75], v[8:11], v[40:43], v[116:119]
	s_waitcnt lgkmcnt(4)
	v_mfma_f32_16x16x32_bf16 v[108:111], v[12:15], v[44:47], v[72:75]
	v_mfma_f32_16x16x32_bf16 v[72:75], v[154:157], v[40:43], v[112:115]
	v_mfma_f32_16x16x32_bf16 v[104:107], v[158:161], v[44:47], v[72:75]
	s_waitcnt lgkmcnt(3)
	v_mfma_f32_16x16x32_bf16 v[72:75], v[8:11], v[198:201], v[202:205]
	s_waitcnt lgkmcnt(2)
	v_mfma_f32_16x16x32_bf16 v[92:95], v[12:15], v[214:217], v[72:75]
	v_mfma_f32_16x16x32_bf16 v[72:75], v[154:157], v[198:201], v[206:209]
	v_mfma_f32_16x16x32_bf16 v[88:91], v[158:161], v[214:217], v[72:75]
	s_waitcnt lgkmcnt(1)
	v_mfma_f32_16x16x32_bf16 v[72:75], v[8:11], v[218:221], v[100:103]
	s_waitcnt lgkmcnt(0)
	v_mfma_f32_16x16x32_bf16 v[76:79], v[12:15], v[222:225], v[72:75]
	v_mfma_f32_16x16x32_bf16 v[72:75], v[154:157], v[218:221], v[96:99]
	v_mfma_f32_16x16x32_bf16 v[72:75], v[158:161], v[222:225], v[72:75]
	v_mfma_f32_16x16x32_bf16 v[96:99], v[162:165], v[24:27], v[210:213]
	v_mfma_f32_16x16x32_bf16 v[24:27], v[182:185], v[24:27], v[170:173]
	v_mfma_f32_16x16x32_bf16 v[112:115], v[186:189], v[28:31], v[24:27]
	v_mfma_f32_16x16x32_bf16 v[24:27], v[162:165], v[40:43], v[84:87]
	v_mfma_f32_16x16x32_bf16 v[100:103], v[166:169], v[44:47], v[24:27]
	v_mfma_f32_16x16x32_bf16 v[24:27], v[182:185], v[40:43], v[80:83]
	v_mfma_f32_16x16x32_bf16 v[116:119], v[166:169], v[28:31], v[96:99]
	v_mfma_f32_16x16x32_bf16 v[96:99], v[186:189], v[44:47], v[24:27]
	v_mfma_f32_16x16x32_bf16 v[24:27], v[162:165], v[198:201], v[174:177]
	v_mfma_f32_16x16x32_bf16 v[84:87], v[166:169], v[214:217], v[24:27]
	v_mfma_f32_16x16x32_bf16 v[24:27], v[182:185], v[198:201], v[178:181]
	v_mfma_f32_16x16x32_bf16 v[80:83], v[186:189], v[214:217], v[24:27]
	v_mfma_f32_16x16x32_bf16 v[24:27], v[162:165], v[218:221], v[68:71]
	v_mfma_f32_16x16x32_bf16 v[68:71], v[166:169], v[222:225], v[24:27]
	v_mfma_f32_16x16x32_bf16 v[24:27], v[182:185], v[218:221], v[64:67]
	v_mfma_f32_16x16x32_bf16 v[64:67], v[186:189], v[222:225], v[24:27]
	s_barrier
	s_add_u32 s54, s6, 0x80
	s_addc_u32 s55, s7, 0
	s_add_u32 s42, s42, 0x80
	ds_read_b128 v[170:173], v139 offset:49152
	ds_read_b128 v[174:177], v139 offset:50176
	ds_read_b128 v[178:181], v139 offset:51200
	ds_read_b128 v[198:201], v139 offset:52224
	ds_read_b128 v[202:205], v139 offset:53248
	ds_read_b128 v[206:209], v139 offset:54272
	ds_read_b128 v[210:213], v139 offset:55296
	ds_read_b128 v[214:217], v139 offset:56320
	s_addc_u32 s43, s43, 0
	s_mov_b32 m0, s61
	s_nop 0
	global_load_lds_dwordx4 v129, s[54:55]
	s_nop 0
	s_mov_b32 m0, s62
	s_nop 0
	global_load_lds_dwordx4 v129, s[42:43]
	s_add_u32 s42, s44, 0x80
	s_addc_u32 s43, s45, 0
	s_add_u32 s44, s46, 0x80
	s_addc_u32 s45, s47, 0
	s_mov_b32 m0, s65
	s_nop 0
	global_load_lds_dwordx4 v129, s[42:43]
	s_add_u32 s42, s38, 0x80
	s_mov_b32 m0, s66
	s_nop 0
	global_load_lds_dwordx4 v129, s[44:45]
	s_addc_u32 s43, s39, 0
	s_add_u32 s4, s4, 0x80
	s_mov_b32 m0, s63
	s_nop 0
	global_load_lds_dwordx4 v128, s[42:43]
	s_addc_u32 s5, s5, 0
	s_mov_b32 m0, s64
	s_nop 0
	global_load_lds_dwordx4 v128, s[4:5]
	s_waitcnt vmcnt(8)
	s_waitcnt lgkmcnt(0)
	s_barrier
	s_waitcnt lgkmcnt(7)
	v_mfma_f32_16x16x32_bf16 v[24:27], v[8:11], v[170:173], v[60:63]
	s_waitcnt lgkmcnt(6)
	v_mfma_f32_16x16x32_bf16 v[60:63], v[12:15], v[174:177], v[24:27]
	v_mfma_f32_16x16x32_bf16 v[24:27], v[154:157], v[170:173], v[56:59]
	v_mfma_f32_16x16x32_bf16 v[56:59], v[158:161], v[174:177], v[24:27]
	s_waitcnt lgkmcnt(5)
	v_mfma_f32_16x16x32_bf16 v[24:27], v[8:11], v[178:181], v[52:55]
	s_waitcnt lgkmcnt(4)
	v_mfma_f32_16x16x32_bf16 v[44:47], v[12:15], v[198:201], v[24:27]
	v_mfma_f32_16x16x32_bf16 v[24:27], v[154:157], v[178:181], v[48:51]
	v_mfma_f32_16x16x32_bf16 v[40:43], v[158:161], v[198:201], v[24:27]
	s_waitcnt lgkmcnt(3)
	v_mfma_f32_16x16x32_bf16 v[24:27], v[8:11], v[202:205], v[190:193]
	s_waitcnt lgkmcnt(1)
	v_mfma_f32_16x16x32_bf16 v[8:11], v[8:11], v[210:213], v[36:39]
	v_mfma_f32_16x16x32_bf16 v[28:31], v[12:15], v[206:209], v[24:27]
	v_mfma_f32_16x16x32_bf16 v[24:27], v[154:157], v[202:205], v[194:197]
	s_waitcnt lgkmcnt(0)
	v_mfma_f32_16x16x32_bf16 v[12:15], v[12:15], v[214:217], v[8:11]
	v_mfma_f32_16x16x32_bf16 v[8:11], v[154:157], v[210:213], v[32:35]
	v_mfma_f32_16x16x32_bf16 v[24:27], v[158:161], v[206:209], v[24:27]
	v_mfma_f32_16x16x32_bf16 v[8:11], v[158:161], v[214:217], v[8:11]
	v_mfma_f32_16x16x32_bf16 v[32:35], v[162:165], v[170:173], v[130:133]
	v_mfma_f32_16x16x32_bf16 v[52:55], v[166:169], v[174:177], v[32:35]
	v_mfma_f32_16x16x32_bf16 v[32:35], v[182:185], v[170:173], v[142:145]
	v_mfma_f32_16x16x32_bf16 v[16:19], v[182:185], v[178:181], v[16:19]
	v_mfma_f32_16x16x32_bf16 v[48:51], v[186:189], v[174:177], v[32:35]
	v_mfma_f32_16x16x32_bf16 v[20:23], v[162:165], v[178:181], v[20:23]
	v_mfma_f32_16x16x32_bf16 v[32:35], v[186:189], v[198:201], v[16:19]
	v_mfma_f32_16x16x32_bf16 v[16:19], v[162:165], v[202:205], v[146:149]
	v_mfma_f32_16x16x32_bf16 v[36:39], v[166:169], v[198:201], v[20:23]
	v_mfma_f32_16x16x32_bf16 v[20:23], v[166:169], v[206:209], v[16:19]
	v_mfma_f32_16x16x32_bf16 v[16:19], v[182:185], v[202:205], v[150:153]
	v_mfma_f32_16x16x32_bf16 v[4:7], v[162:165], v[210:213], v[4:7]
	v_mfma_f32_16x16x32_bf16 v[0:3], v[182:185], v[210:213], v[0:3]
	v_mfma_f32_16x16x32_bf16 v[16:19], v[186:189], v[206:209], v[16:19]
	v_mfma_f32_16x16x32_bf16 v[4:7], v[166:169], v[214:217], v[4:7]
	v_mfma_f32_16x16x32_bf16 v[0:3], v[186:189], v[214:217], v[0:3]
	s_barrier
	s_andn2_b64 vcc, exec, s[24:25]
	s_cbranch_vccnz .LBB0_300
	s_barrier

.LBB0_307:
	v_and_b32_e32 v1, 15, v2
	s_lshl_b64 s[36:37], s[8:9], 7
	s_lshl_b64 s[18:19], s[18:19], 7
	v_or_b32_e32 v3, s3, v1
	v_lshlrev_b32_e32 v5, 6, v3
	v_and_b32_e32 v6, 48, v2
	s_movk_i32 s2, 0x3c0
	s_add_u32 s8, s6, 0x80
	v_ashrrev_i32_e32 v4, 6, v2
	v_and_or_b32 v5, v5, s2, v6
	v_readlane_b32 s2, v254, 55
	s_addc_u32 s9, s7, 0
	v_lshl_add_u32 v7, v4, 10, s95
	v_add_lshl_u32 v4, v4, s2, 10
	s_sub_u32 s2, 0, s0
	s_subb_u32 s22, 0, s1
	s_add_u32 s2, s10, s2
	s_addc_u32 s23, s11, s22
	s_add_u32 s22, s2, 0x80
	s_addc_u32 s23, s23, 0
	s_add_i32 s54, s53, 0x18000
	s_add_i32 s55, s53, 0x1a000
	s_mov_b32 s98, 0
	s_cselect_b32 s99, 1, 0
	s_cmp_lt_u32 s76, 4
	s_cbranch_scc0 .Lsprio_4
	s_setprio 1
.Lsprio_4:
	s_cmp_lg_u32 s99, 0
	s_waitcnt vmcnt(2)
	s_barrier
	s_mov_b32 m0, s54
	s_nop 0
	global_load_lds_dwordx4 v0, s[8:9]
	s_add_u32 s8, s4, 0x80
	s_mov_b32 m0, s55
	s_nop 0
	global_load_lds_dwordx4 v0, s[22:23]
	s_addc_u32 s9, s5, 0
	s_sub_u32 s2, 0, s34
	s_subb_u32 s22, 0, s35
	s_add_u32 s2, s14, s2
	s_addc_u32 s15, s15, s22
	s_add_u32 s14, s2, 0x80
	s_addc_u32 s15, s15, 0
	s_add_i32 s56, s53, 0x8000
	s_add_i32 s61, s53, 0xa000
	s_mov_b32 m0, s56
	s_nop 0
	global_load_lds_dwordx4 v160, s[8:9]
	s_add_u32 s8, s10, 0x80
	s_addc_u32 s9, s11, 0
	s_mov_b32 m0, s61
	s_nop 0
	global_load_lds_dwordx4 v160, s[14:15]
	s_add_u32 s10, s12, 0x80
	v_lshlrev_b32_e32 v2, 2, v2
	s_addc_u32 s11, s13, 0
	s_add_i32 s62, s53, 0x1c000
	s_mov_b32 m0, s62
	s_nop 0
	global_load_lds_dwordx4 v0, s[8:9]
	v_lshlrev_b32_e32 v3, 2, v3
	v_lshl_or_b32 v1, v1, 6, v6
	v_and_b32_e32 v2, 32, v2
	s_add_i32 s63, s53, 0x1e000
	s_mov_b32 m0, s63
	s_nop 0
	global_load_lds_dwordx4 v0, s[10:11]
	v_and_b32_e32 v3, 32, v3
	v_bitop3_b32 v1, v1, v4, v2 bitop3:0xde
	s_waitcnt vmcnt(6)
	s_add_i32 s64, s53, 0xc000
	s_add_i32 s65, s53, 0xe000
	v_readlane_b32 s2, v254, 0
	v_mov_b32_e32 v161, v0
	v_bitop3_b32 v3, v5, v7, v3 bitop3:0xde
	s_cmpk_lt_u32 s2, 0x100
	v_add_u32_e32 v0, 0, v1
	s_mov_b32 s23, 0
	s_cselect_b64 s[24:25], -1, 0
	v_add_u32_e32 v194, 0x10000, v0
	v_add_u32_e32 v248, 0x14000, v0
	v_add_u32_e32 v249, 0, v3
	v_mov_b32_e32 v250, 0x79797979
	v_mov_b32_e32 v251, 0x7f7f7f7f
	v_add_u32_e32 v252, 0x18000, v0
	v_add_u32_e32 v253, 0x1c000, v0
	s_mov_b32 s67, 0
	s_barrier
	s_branch .LBB0_310

.LBB0_312:
	s_cmp_lt_i32 s20, 3
	s_cbranch_scc1 .Lhz_314
	s_add_i32 s2, s20, -2
	s_add_u32 s22, s4, s36
	s_addc_u32 s33, s5, s37
	s_add_u32 s42, s6, s18
	s_addc_u32 s43, s7, s19
	s_add_u32 s38, s0, s18
	s_addc_u32 s39, s1, s19
	s_add_u32 s44, s6, s38
	s_addc_u32 s45, s7, s39
	s_add_u32 s68, s6, s0
	s_addc_u32 s69, s7, s1
	s_add_u32 s38, s34, s36
	s_addc_u32 s39, s35, s37
	s_add_u32 s70, s4, s38
	s_addc_u32 s71, s5, s39
	s_add_u32 s72, s4, s34
	s_addc_u32 s73, s5, s35
	s_mov_b32 s74, 0
	s_mov_b64 s[38:39], 0
	s_cmp_eq_u32 s98, 0
	s_cbranch_scc1 .Lhf_314
	ds_read_b128 v[24:27], v194
	ds_read_b128 v[28:31], v194 offset:1024
	ds_read_b128 v[16:19], v194 offset:2048
	ds_read_b128 v[20:23], v194 offset:3072
	ds_read_b128 v[8:11], v248
	ds_read_b128 v[12:15], v248 offset:1024
	ds_read_b128 v[0:3], v248 offset:2048
	ds_read_b128 v[4:7], v248 offset:3072
	s_add_i32 s74, s74, 2
	s_add_u32 s75, s4, s38
	s_addc_u32 s77, s5, s39
	s_add_u32 s40, s75, 0x100
	s_addc_u32 s41, s77, 0
	s_add_u32 s78, s22, s38
	ds_read_b128 v[162:165], v249
	ds_read_b128 v[166:169], v249 offset:1024
	ds_read_b128 v[170:173], v249 offset:2048
	ds_read_b128 v[174:177], v249 offset:3072
	ds_read_b128 v[178:181], v249 offset:4096
	ds_read_b128 v[182:185], v249 offset:5120
	ds_read_b128 v[186:189], v249 offset:6144
	ds_read_b128 v[190:193], v249 offset:7168
	s_addc_u32 s79, s33, s39
	s_add_u32 s82, s78, 0x80
	s_addc_u32 s83, s79, 0
	s_add_u32 s80, s70, s38
	s_addc_u32 s81, s71, s39
	s_add_u32 s84, s80, 0x80
	s_mov_b32 m0, s64
	s_nop 0
	global_load_lds_dwordx4 v160, s[82:83]
	s_addc_u32 s85, s81, 0
	s_mov_b32 m0, s65
	s_nop 0
	global_load_lds_dwordx4 v160, s[84:85]
	s_waitcnt vmcnt(24)
	s_waitcnt lgkmcnt(0)
	s_barrier
	s_waitcnt lgkmcnt(6)
	v_mfma_scale_f32_16x16x128_f8f6f4 v[156:159], v[24:31], v[162:169], 0, v251, v250 op_sel_hi:[0,0,0]
	v_mfma_scale_f32_16x16x128_f8f6f4 v[152:155], v[16:23], v[162:169], 0, v251, v250 op_sel_hi:[0,0,0]
	s_waitcnt lgkmcnt(4)
	v_mfma_scale_f32_16x16x128_f8f6f4 v[148:151], v[24:31], v[170:177], 0, v251, v250 op_sel_hi:[0,0,0]
	v_mfma_scale_f32_16x16x128_f8f6f4 v[144:147], v[16:23], v[170:177], 0, v251, v250 op_sel_hi:[0,0,0]
	s_waitcnt lgkmcnt(2)
	v_mfma_scale_f32_16x16x128_f8f6f4 v[140:143], v[24:31], v[178:185], 0, v251, v250 op_sel_hi:[0,0,0]
	v_mfma_scale_f32_16x16x128_f8f6f4 v[136:139], v[16:23], v[178:185], 0, v251, v250 op_sel_hi:[0,0,0]
	s_waitcnt lgkmcnt(0)
	v_mfma_scale_f32_16x16x128_f8f6f4 v[132:135], v[24:31], v[186:193], 0, v251, v250 op_sel_hi:[0,0,0]
	v_mfma_scale_f32_16x16x128_f8f6f4 v[128:131], v[16:23], v[186:193], 0, v251, v250 op_sel_hi:[0,0,0]
	v_mfma_scale_f32_16x16x128_f8f6f4 v[124:127], v[8:15], v[162:169], 0, v251, v250 op_sel_hi:[0,0,0]
	v_mfma_scale_f32_16x16x128_f8f6f4 v[120:123], v[0:7], v[162:169], 0, v251, v250 op_sel_hi:[0,0,0]
	v_mfma_scale_f32_16x16x128_f8f6f4 v[116:119], v[8:15], v[170:177], 0, v251, v250 op_sel_hi:[0,0,0]
	v_mfma_scale_f32_16x16x128_f8f6f4 v[112:115], v[0:7], v[170:177], 0, v251, v250 op_sel_hi:[0,0,0]
	v_mfma_scale_f32_16x16x128_f8f6f4 v[108:111], v[8:15], v[178:185], 0, v251, v250 op_sel_hi:[0,0,0]
	v_mfma_scale_f32_16x16x128_f8f6f4 v[104:107], v[0:7], v[178:185], 0, v251, v250 op_sel_hi:[0,0,0]
	v_mfma_scale_f32_16x16x128_f8f6f4 v[100:103], v[8:15], v[186:193], 0, v251, v250 op_sel_hi:[0,0,0]
	v_mfma_scale_f32_16x16x128_f8f6f4 v[96:99], v[0:7], v[186:193], 0, v251, v250 op_sel_hi:[0,0,0]
	s_barrier
	s_add_u32 s82, s6, s38
	s_addc_u32 s83, s7, s39
	s_add_u32 s86, s82, 0x100
	s_addc_u32 s87, s83, 0
	s_add_u32 s84, s68, s38
	s_addc_u32 s85, s69, s39
	ds_read_b128 v[162:165], v249 offset:16384
	ds_read_b128 v[166:169], v249 offset:17408
	ds_read_b128 v[170:173], v249 offset:18432
	ds_read_b128 v[174:177], v249 offset:19456
	ds_read_b128 v[178:181], v249 offset:20480
	ds_read_b128 v[182:185], v249 offset:21504
	ds_read_b128 v[186:189], v249 offset:22528
	ds_read_b128 v[190:193], v249 offset:23552
	s_add_u32 s88, s84, 0x100
	s_mov_b32 m0, s49
	s_nop 0
	global_load_lds_dwordx4 v161, s[86:87]
	s_addc_u32 s89, s85, 0
	s_mov_b32 m0, s50
	s_nop 0
	global_load_lds_dwordx4 v161, s[88:89]
	s_add_u32 s86, s42, s38
	s_addc_u32 s87, s43, s39
	s_add_u32 s88, s86, 0x100
	s_addc_u32 s89, s87, 0
	s_add_u32 s90, s44, s38
	s_addc_u32 s91, s45, s39
	s_add_u32 s92, s90, 0x100
	s_mov_b32 m0, s51
	s_nop 0
	global_load_lds_dwordx4 v161, s[88:89]
	s_addc_u32 s93, s91, 0
	s_mov_b32 m0, s57
	s_nop 0
	global_load_lds_dwordx4 v161, s[92:93]
	s_add_u32 s88, s72, s38
	s_addc_u32 s89, s73, s39
	s_add_u32 s92, s88, 0x100
	s_mov_b32 m0, s53
	s_nop 0
	global_load_lds_dwordx4 v160, s[40:41]
	s_addc_u32 s93, s89, 0
	s_mov_b32 m0, s58
	s_nop 0
	global_load_lds_dwordx4 v160, s[92:93]
	s_waitcnt vmcnt(24)
	s_waitcnt lgkmcnt(0)
	s_barrier
	s_waitcnt lgkmcnt(6)
	v_mfma_scale_f32_16x16x128_f8f6f4 v[92:95], v[24:31], v[162:169], 0, v251, v250 op_sel_hi:[0,0,0]
	v_mfma_scale_f32_16x16x128_f8f6f4 v[88:91], v[16:23], v[162:169], 0, v251, v250 op_sel_hi:[0,0,0]
	s_waitcnt lgkmcnt(4)
	v_mfma_scale_f32_16x16x128_f8f6f4 v[84:87], v[24:31], v[170:177], 0, v251, v250 op_sel_hi:[0,0,0]
	v_mfma_scale_f32_16x16x128_f8f6f4 v[80:83], v[16:23], v[170:177], 0, v251, v250 op_sel_hi:[0,0,0]
	s_waitcnt lgkmcnt(2)
	v_mfma_scale_f32_16x16x128_f8f6f4 v[76:79], v[24:31], v[178:185], 0, v251, v250 op_sel_hi:[0,0,0]
	v_mfma_scale_f32_16x16x128_f8f6f4 v[72:75], v[16:23], v[178:185], 0, v251, v250 op_sel_hi:[0,0,0]
	s_waitcnt lgkmcnt(0)
	v_mfma_scale_f32_16x16x128_f8f6f4 v[68:71], v[24:31], v[186:193], 0, v251, v250 op_sel_hi:[0,0,0]
	v_mfma_scale_f32_16x16x128_f8f6f4 v[64:67], v[16:23], v[186:193], 0, v251, v250 op_sel_hi:[0,0,0]
	v_mfma_scale_f32_16x16x128_f8f6f4 v[60:63], v[8:15], v[162:169], 0, v251, v250 op_sel_hi:[0,0,0]
	v_mfma_scale_f32_16x16x128_f8f6f4 v[56:59], v[0:7], v[162:169], 0, v251, v250 op_sel_hi:[0,0,0]
	v_mfma_scale_f32_16x16x128_f8f6f4 v[52:55], v[8:15], v[170:177], 0, v251, v250 op_sel_hi:[0,0,0]
	v_mfma_scale_f32_16x16x128_f8f6f4 v[48:51], v[0:7], v[170:177], 0, v251, v250 op_sel_hi:[0,0,0]
	v_mfma_scale_f32_16x16x128_f8f6f4 v[44:47], v[8:15], v[178:185], 0, v251, v250 op_sel_hi:[0,0,0]
	v_mfma_scale_f32_16x16x128_f8f6f4 v[40:43], v[0:7], v[178:185], 0, v251, v250 op_sel_hi:[0,0,0]
	v_mfma_scale_f32_16x16x128_f8f6f4 v[36:39], v[8:15], v[186:193], 0, v251, v250 op_sel_hi:[0,0,0]
	v_mfma_scale_f32_16x16x128_f8f6f4 v[32:35], v[0:7], v[186:193], 0, v251, v250 op_sel_hi:[0,0,0]
	s_barrier
	ds_read_b128 v[24:27], v252
	ds_read_b128 v[28:31], v252 offset:1024
	ds_read_b128 v[16:19], v252 offset:2048
	ds_read_b128 v[20:23], v252 offset:3072
	ds_read_b128 v[8:11], v253
	ds_read_b128 v[12:15], v253 offset:1024
	ds_read_b128 v[0:3], v253 offset:2048
	ds_read_b128 v[4:7], v253 offset:3072
	ds_read_b128 v[162:165], v249 offset:32768
	ds_read_b128 v[166:169], v249 offset:33792
	ds_read_b128 v[170:173], v249 offset:34816
	ds_read_b128 v[174:177], v249 offset:35840
	ds_read_b128 v[178:181], v249 offset:36864
	ds_read_b128 v[182:185], v249 offset:37888
	ds_read_b128 v[186:189], v249 offset:38912
	ds_read_b128 v[190:193], v249 offset:39936
	s_add_u32 s40, s78, 0x100
	s_addc_u32 s41, s79, 0
	s_add_u32 s78, s80, 0x100
	s_mov_b32 m0, s59
	s_nop 0
	global_load_lds_dwordx4 v160, s[40:41]
	s_addc_u32 s79, s81, 0
	s_mov_b32 m0, s60
	s_nop 0
	global_load_lds_dwordx4 v160, s[78:79]
	s_waitcnt vmcnt(8)
	s_waitcnt lgkmcnt(0)
	s_barrier
	s_waitcnt lgkmcnt(6)
	v_mfma_scale_f32_16x16x128_f8f6f4 v[156:159], v[24:31], v[162:169], v[156:159], v251, v250 op_sel_hi:[0,0,0]
	v_mfma_scale_f32_16x16x128_f8f6f4 v[152:155], v[16:23], v[162:169], v[152:155], v251, v250 op_sel_hi:[0,0,0]
	s_waitcnt lgkmcnt(4)
	v_mfma_scale_f32_16x16x128_f8f6f4 v[148:151], v[24:31], v[170:177], v[148:151], v251, v250 op_sel_hi:[0,0,0]
	v_mfma_scale_f32_16x16x128_f8f6f4 v[144:147], v[16:23], v[170:177], v[144:147], v251, v250 op_sel_hi:[0,0,0]
	s_waitcnt lgkmcnt(2)
	v_mfma_scale_f32_16x16x128_f8f6f4 v[140:143], v[24:31], v[178:185], v[140:143], v251, v250 op_sel_hi:[0,0,0]
	v_mfma_scale_f32_16x16x128_f8f6f4 v[136:139], v[16:23], v[178:185], v[136:139], v251, v250 op_sel_hi:[0,0,0]
	s_waitcnt lgkmcnt(0)
	v_mfma_scale_f32_16x16x128_f8f6f4 v[132:135], v[24:31], v[186:193], v[132:135], v251, v250 op_sel_hi:[0,0,0]
	v_mfma_scale_f32_16x16x128_f8f6f4 v[128:131], v[16:23], v[186:193], v[128:131], v251, v250 op_sel_hi:[0,0,0]
	v_mfma_scale_f32_16x16x128_f8f6f4 v[124:127], v[8:15], v[162:169], v[124:127], v251, v250 op_sel_hi:[0,0,0]
	v_mfma_scale_f32_16x16x128_f8f6f4 v[120:123], v[0:7], v[162:169], v[120:123], v251, v250 op_sel_hi:[0,0,0]
	v_mfma_scale_f32_16x16x128_f8f6f4 v[116:119], v[8:15], v[170:177], v[116:119], v251, v250 op_sel_hi:[0,0,0]
	v_mfma_scale_f32_16x16x128_f8f6f4 v[112:115], v[0:7], v[170:177], v[112:115], v251, v250 op_sel_hi:[0,0,0]
	v_mfma_scale_f32_16x16x128_f8f6f4 v[108:111], v[8:15], v[178:185], v[108:111], v251, v250 op_sel_hi:[0,0,0]
	v_mfma_scale_f32_16x16x128_f8f6f4 v[104:107], v[0:7], v[178:185], v[104:107], v251, v250 op_sel_hi:[0,0,0]
	v_mfma_scale_f32_16x16x128_f8f6f4 v[100:103], v[8:15], v[186:193], v[100:103], v251, v250 op_sel_hi:[0,0,0]
	v_mfma_scale_f32_16x16x128_f8f6f4 v[96:99], v[0:7], v[186:193], v[96:99], v251, v250 op_sel_hi:[0,0,0]
	s_barrier
	s_add_u32 s40, s82, 0x180
	s_addc_u32 s41, s83, 0
	ds_read_b128 v[162:165], v249 offset:49152
	ds_read_b128 v[166:169], v249 offset:50176
	ds_read_b128 v[170:173], v249 offset:51200
	ds_read_b128 v[174:177], v249 offset:52224
	ds_read_b128 v[178:181], v249 offset:53248
	ds_read_b128 v[182:185], v249 offset:54272
	ds_read_b128 v[186:189], v249 offset:55296
	ds_read_b128 v[190:193], v249 offset:56320
	s_add_u32 s78, s84, 0x180
	s_mov_b32 m0, s54
	s_nop 0
	global_load_lds_dwordx4 v161, s[40:41]
	s_addc_u32 s79, s85, 0
	s_mov_b32 m0, s55
	s_nop 0
	global_load_lds_dwordx4 v161, s[78:79]
	s_add_u32 s40, s86, 0x180
	s_addc_u32 s41, s87, 0
	s_add_u32 s78, s90, 0x180
	s_mov_b32 m0, s62
	s_nop 0
	global_load_lds_dwordx4 v161, s[40:41]
	s_addc_u32 s79, s91, 0
	s_mov_b32 m0, s63
	s_nop 0
	global_load_lds_dwordx4 v161, s[78:79]
	s_add_u32 s40, s75, 0x180
	s_addc_u32 s41, s77, 0
	s_add_u32 s78, s88, 0x180
	s_mov_b32 m0, s56
	s_nop 0
	global_load_lds_dwordx4 v160, s[40:41]
	s_addc_u32 s79, s89, 0
	s_mov_b32 m0, s61
	s_nop 0
	global_load_lds_dwordx4 v160, s[78:79]
	s_waitcnt vmcnt(8)
	s_waitcnt lgkmcnt(0)
	s_barrier
	s_waitcnt lgkmcnt(6)
	v_mfma_scale_f32_16x16x128_f8f6f4 v[92:95], v[24:31], v[162:169], v[92:95], v251, v250 op_sel_hi:[0,0,0]
	v_mfma_scale_f32_16x16x128_f8f6f4 v[88:91], v[16:23], v[162:169], v[88:91], v251, v250 op_sel_hi:[0,0,0]
	s_waitcnt lgkmcnt(4)
	v_mfma_scale_f32_16x16x128_f8f6f4 v[84:87], v[24:31], v[170:177], v[84:87], v251, v250 op_sel_hi:[0,0,0]
	v_mfma_scale_f32_16x16x128_f8f6f4 v[80:83], v[16:23], v[170:177], v[80:83], v251, v250 op_sel_hi:[0,0,0]
	s_waitcnt lgkmcnt(2)
	v_mfma_scale_f32_16x16x128_f8f6f4 v[76:79], v[24:31], v[178:185], v[76:79], v251, v250 op_sel_hi:[0,0,0]
	v_mfma_scale_f32_16x16x128_f8f6f4 v[72:75], v[16:23], v[178:185], v[72:75], v251, v250 op_sel_hi:[0,0,0]
	s_waitcnt lgkmcnt(0)
	v_mfma_scale_f32_16x16x128_f8f6f4 v[68:71], v[24:31], v[186:193], v[68:71], v251, v250 op_sel_hi:[0,0,0]
	v_mfma_scale_f32_16x16x128_f8f6f4 v[64:67], v[16:23], v[186:193], v[64:67], v251, v250 op_sel_hi:[0,0,0]
	v_mfma_scale_f32_16x16x128_f8f6f4 v[60:63], v[8:15], v[162:169], v[60:63], v251, v250 op_sel_hi:[0,0,0]
	v_mfma_scale_f32_16x16x128_f8f6f4 v[56:59], v[0:7], v[162:169], v[56:59], v251, v250 op_sel_hi:[0,0,0]
	v_mfma_scale_f32_16x16x128_f8f6f4 v[52:55], v[8:15], v[170:177], v[52:55], v251, v250 op_sel_hi:[0,0,0]
	v_mfma_scale_f32_16x16x128_f8f6f4 v[48:51], v[0:7], v[170:177], v[48:51], v251, v250 op_sel_hi:[0,0,0]
	v_mfma_scale_f32_16x16x128_f8f6f4 v[44:47], v[8:15], v[178:185], v[44:47], v251, v250 op_sel_hi:[0,0,0]
	v_mfma_scale_f32_16x16x128_f8f6f4 v[40:43], v[0:7], v[178:185], v[40:43], v251, v250 op_sel_hi:[0,0,0]
	v_mfma_scale_f32_16x16x128_f8f6f4 v[36:39], v[8:15], v[186:193], v[36:39], v251, v250 op_sel_hi:[0,0,0]
	v_mfma_scale_f32_16x16x128_f8f6f4 v[32:35], v[0:7], v[186:193], v[32:35], v251, v250 op_sel_hi:[0,0,0]
	s_barrier
	s_add_u32 s38, s38, 0x100
	s_addc_u32 s39, s39, 0
	s_cmp_ge_i32 s74, s2
	s_cbranch_scc0 .LBB0_314
	s_branch .LBB0_315
.Lhf_314:
	ds_read_b128 v[24:27], v194
	ds_read_b128 v[28:31], v194 offset:1024
	ds_read_b128 v[16:19], v194 offset:2048
	ds_read_b128 v[20:23], v194 offset:3072
	ds_read_b128 v[8:11], v248
	ds_read_b128 v[12:15], v248 offset:1024
	ds_read_b128 v[0:3], v248 offset:2048
	ds_read_b128 v[4:7], v248 offset:3072
	s_add_i32 s74, s74, 2
	s_add_u32 s75, s4, s38
	s_addc_u32 s77, s5, s39
	s_add_u32 s40, s75, 0x100
	s_addc_u32 s41, s77, 0
	s_add_u32 s78, s22, s38
	ds_read_b128 v[162:165], v249
	ds_read_b128 v[166:169], v249 offset:1024
	ds_read_b128 v[170:173], v249 offset:2048
	ds_read_b128 v[174:177], v249 offset:3072
	ds_read_b128 v[178:181], v249 offset:4096
	ds_read_b128 v[182:185], v249 offset:5120
	ds_read_b128 v[186:189], v249 offset:6144
	ds_read_b128 v[190:193], v249 offset:7168
	s_addc_u32 s79, s33, s39
	s_add_u32 s82, s78, 0x80
	s_addc_u32 s83, s79, 0
	s_add_u32 s80, s70, s38
	s_addc_u32 s81, s71, s39
	s_add_u32 s84, s80, 0x80
	s_mov_b32 m0, s64
	s_nop 0
	global_load_lds_dwordx4 v160, s[82:83]
	s_addc_u32 s85, s81, 0
	s_mov_b32 m0, s65
	s_nop 0
	global_load_lds_dwordx4 v160, s[84:85]
	s_waitcnt vmcnt(8)
	s_waitcnt lgkmcnt(0)
	s_barrier
	s_waitcnt lgkmcnt(6)
	v_mfma_scale_f32_16x16x128_f8f6f4 v[156:159], v[24:31], v[162:169], 0, v251, v250 op_sel_hi:[0,0,0]
	v_mfma_scale_f32_16x16x128_f8f6f4 v[152:155], v[16:23], v[162:169], 0, v251, v250 op_sel_hi:[0,0,0]
	s_waitcnt lgkmcnt(4)
	v_mfma_scale_f32_16x16x128_f8f6f4 v[148:151], v[24:31], v[170:177], 0, v251, v250 op_sel_hi:[0,0,0]
	v_mfma_scale_f32_16x16x128_f8f6f4 v[144:147], v[16:23], v[170:177], 0, v251, v250 op_sel_hi:[0,0,0]
	s_waitcnt lgkmcnt(2)
	v_mfma_scale_f32_16x16x128_f8f6f4 v[140:143], v[24:31], v[178:185], 0, v251, v250 op_sel_hi:[0,0,0]
	v_mfma_scale_f32_16x16x128_f8f6f4 v[136:139], v[16:23], v[178:185], 0, v251, v250 op_sel_hi:[0,0,0]
	s_waitcnt lgkmcnt(0)
	v_mfma_scale_f32_16x16x128_f8f6f4 v[132:135], v[24:31], v[186:193], 0, v251, v250 op_sel_hi:[0,0,0]
	v_mfma_scale_f32_16x16x128_f8f6f4 v[128:131], v[16:23], v[186:193], 0, v251, v250 op_sel_hi:[0,0,0]
	v_mfma_scale_f32_16x16x128_f8f6f4 v[124:127], v[8:15], v[162:169], 0, v251, v250 op_sel_hi:[0,0,0]
	v_mfma_scale_f32_16x16x128_f8f6f4 v[120:123], v[0:7], v[162:169], 0, v251, v250 op_sel_hi:[0,0,0]
	v_mfma_scale_f32_16x16x128_f8f6f4 v[116:119], v[8:15], v[170:177], 0, v251, v250 op_sel_hi:[0,0,0]
	v_mfma_scale_f32_16x16x128_f8f6f4 v[112:115], v[0:7], v[170:177], 0, v251, v250 op_sel_hi:[0,0,0]
	v_mfma_scale_f32_16x16x128_f8f6f4 v[108:111], v[8:15], v[178:185], 0, v251, v250 op_sel_hi:[0,0,0]
	v_mfma_scale_f32_16x16x128_f8f6f4 v[104:107], v[0:7], v[178:185], 0, v251, v250 op_sel_hi:[0,0,0]
	v_mfma_scale_f32_16x16x128_f8f6f4 v[100:103], v[8:15], v[186:193], 0, v251, v250 op_sel_hi:[0,0,0]
	v_mfma_scale_f32_16x16x128_f8f6f4 v[96:99], v[0:7], v[186:193], 0, v251, v250 op_sel_hi:[0,0,0]
	s_barrier
	s_add_u32 s82, s6, s38
	s_addc_u32 s83, s7, s39
	s_add_u32 s86, s82, 0x100
	s_addc_u32 s87, s83, 0
	s_add_u32 s84, s68, s38
	s_addc_u32 s85, s69, s39
	ds_read_b128 v[162:165], v249 offset:16384
	ds_read_b128 v[166:169], v249 offset:17408
	ds_read_b128 v[170:173], v249 offset:18432
	ds_read_b128 v[174:177], v249 offset:19456
	ds_read_b128 v[178:181], v249 offset:20480
	ds_read_b128 v[182:185], v249 offset:21504
	ds_read_b128 v[186:189], v249 offset:22528
	ds_read_b128 v[190:193], v249 offset:23552
	s_add_u32 s88, s84, 0x100
	s_mov_b32 m0, s49
	s_nop 0
	global_load_lds_dwordx4 v161, s[86:87]
	s_addc_u32 s89, s85, 0
	s_mov_b32 m0, s50
	s_nop 0
	global_load_lds_dwordx4 v161, s[88:89]
	s_add_u32 s86, s42, s38
	s_addc_u32 s87, s43, s39
	s_add_u32 s88, s86, 0x100
	s_addc_u32 s89, s87, 0
	s_add_u32 s90, s44, s38
	s_addc_u32 s91, s45, s39
	s_add_u32 s92, s90, 0x100
	s_mov_b32 m0, s51
	s_nop 0
	global_load_lds_dwordx4 v161, s[88:89]
	s_addc_u32 s93, s91, 0
	s_mov_b32 m0, s57
	s_nop 0
	global_load_lds_dwordx4 v161, s[92:93]
	s_add_u32 s88, s72, s38
	s_addc_u32 s89, s73, s39
	s_add_u32 s92, s88, 0x100
	s_mov_b32 m0, s53
	s_nop 0
	global_load_lds_dwordx4 v160, s[40:41]
	s_addc_u32 s93, s89, 0
	s_mov_b32 m0, s58
	s_nop 0
	global_load_lds_dwordx4 v160, s[92:93]
	s_waitcnt vmcnt(8)
	s_waitcnt lgkmcnt(0)
	s_barrier
	s_waitcnt lgkmcnt(6)
	v_mfma_scale_f32_16x16x128_f8f6f4 v[92:95], v[24:31], v[162:169], 0, v251, v250 op_sel_hi:[0,0,0]
	v_mfma_scale_f32_16x16x128_f8f6f4 v[88:91], v[16:23], v[162:169], 0, v251, v250 op_sel_hi:[0,0,0]
	s_waitcnt lgkmcnt(4)
	v_mfma_scale_f32_16x16x128_f8f6f4 v[84:87], v[24:31], v[170:177], 0, v251, v250 op_sel_hi:[0,0,0]
	v_mfma_scale_f32_16x16x128_f8f6f4 v[80:83], v[16:23], v[170:177], 0, v251, v250 op_sel_hi:[0,0,0]
	s_waitcnt lgkmcnt(2)
	v_mfma_scale_f32_16x16x128_f8f6f4 v[76:79], v[24:31], v[178:185], 0, v251, v250 op_sel_hi:[0,0,0]
	v_mfma_scale_f32_16x16x128_f8f6f4 v[72:75], v[16:23], v[178:185], 0, v251, v250 op_sel_hi:[0,0,0]
	s_waitcnt lgkmcnt(0)
	v_mfma_scale_f32_16x16x128_f8f6f4 v[68:71], v[24:31], v[186:193], 0, v251, v250 op_sel_hi:[0,0,0]
	v_mfma_scale_f32_16x16x128_f8f6f4 v[64:67], v[16:23], v[186:193], 0, v251, v250 op_sel_hi:[0,0,0]
	v_mfma_scale_f32_16x16x128_f8f6f4 v[60:63], v[8:15], v[162:169], 0, v251, v250 op_sel_hi:[0,0,0]
	v_mfma_scale_f32_16x16x128_f8f6f4 v[56:59], v[0:7], v[162:169], 0, v251, v250 op_sel_hi:[0,0,0]
	v_mfma_scale_f32_16x16x128_f8f6f4 v[52:55], v[8:15], v[170:177], 0, v251, v250 op_sel_hi:[0,0,0]
	v_mfma_scale_f32_16x16x128_f8f6f4 v[48:51], v[0:7], v[170:177], 0, v251, v250 op_sel_hi:[0,0,0]
	v_mfma_scale_f32_16x16x128_f8f6f4 v[44:47], v[8:15], v[178:185], 0, v251, v250 op_sel_hi:[0,0,0]
	v_mfma_scale_f32_16x16x128_f8f6f4 v[40:43], v[0:7], v[178:185], 0, v251, v250 op_sel_hi:[0,0,0]
	v_mfma_scale_f32_16x16x128_f8f6f4 v[36:39], v[8:15], v[186:193], 0, v251, v250 op_sel_hi:[0,0,0]
	v_mfma_scale_f32_16x16x128_f8f6f4 v[32:35], v[0:7], v[186:193], 0, v251, v250 op_sel_hi:[0,0,0]
	s_barrier
	ds_read_b128 v[24:27], v252
	ds_read_b128 v[28:31], v252 offset:1024
	ds_read_b128 v[16:19], v252 offset:2048
	ds_read_b128 v[20:23], v252 offset:3072
	ds_read_b128 v[8:11], v253
	ds_read_b128 v[12:15], v253 offset:1024
	ds_read_b128 v[0:3], v253 offset:2048
	ds_read_b128 v[4:7], v253 offset:3072
	ds_read_b128 v[162:165], v249 offset:32768
	ds_read_b128 v[166:169], v249 offset:33792
	ds_read_b128 v[170:173], v249 offset:34816
	ds_read_b128 v[174:177], v249 offset:35840
	ds_read_b128 v[178:181], v249 offset:36864
	ds_read_b128 v[182:185], v249 offset:37888
	ds_read_b128 v[186:189], v249 offset:38912
	ds_read_b128 v[190:193], v249 offset:39936
	s_add_u32 s40, s78, 0x100
	s_addc_u32 s41, s79, 0
	s_add_u32 s78, s80, 0x100
	s_mov_b32 m0, s59
	s_nop 0
	global_load_lds_dwordx4 v160, s[40:41]
	s_addc_u32 s79, s81, 0
	s_mov_b32 m0, s60
	s_nop 0
	global_load_lds_dwordx4 v160, s[78:79]
	s_waitcnt vmcnt(8)
	s_waitcnt lgkmcnt(0)
	s_barrier
	s_waitcnt lgkmcnt(6)
	v_mfma_scale_f32_16x16x128_f8f6f4 v[156:159], v[24:31], v[162:169], v[156:159], v251, v250 op_sel_hi:[0,0,0]
	v_mfma_scale_f32_16x16x128_f8f6f4 v[152:155], v[16:23], v[162:169], v[152:155], v251, v250 op_sel_hi:[0,0,0]
	s_waitcnt lgkmcnt(4)
	v_mfma_scale_f32_16x16x128_f8f6f4 v[148:151], v[24:31], v[170:177], v[148:151], v251, v250 op_sel_hi:[0,0,0]
	v_mfma_scale_f32_16x16x128_f8f6f4 v[144:147], v[16:23], v[170:177], v[144:147], v251, v250 op_sel_hi:[0,0,0]
	s_waitcnt lgkmcnt(2)
	v_mfma_scale_f32_16x16x128_f8f6f4 v[140:143], v[24:31], v[178:185], v[140:143], v251, v250 op_sel_hi:[0,0,0]
	v_mfma_scale_f32_16x16x128_f8f6f4 v[136:139], v[16:23], v[178:185], v[136:139], v251, v250 op_sel_hi:[0,0,0]
	s_waitcnt lgkmcnt(0)
	v_mfma_scale_f32_16x16x128_f8f6f4 v[132:135], v[24:31], v[186:193], v[132:135], v251, v250 op_sel_hi:[0,0,0]
	v_mfma_scale_f32_16x16x128_f8f6f4 v[128:131], v[16:23], v[186:193], v[128:131], v251, v250 op_sel_hi:[0,0,0]
	v_mfma_scale_f32_16x16x128_f8f6f4 v[124:127], v[8:15], v[162:169], v[124:127], v251, v250 op_sel_hi:[0,0,0]
	v_mfma_scale_f32_16x16x128_f8f6f4 v[120:123], v[0:7], v[162:169], v[120:123], v251, v250 op_sel_hi:[0,0,0]
	v_mfma_scale_f32_16x16x128_f8f6f4 v[116:119], v[8:15], v[170:177], v[116:119], v251, v250 op_sel_hi:[0,0,0]
	v_mfma_scale_f32_16x16x128_f8f6f4 v[112:115], v[0:7], v[170:177], v[112:115], v251, v250 op_sel_hi:[0,0,0]
	v_mfma_scale_f32_16x16x128_f8f6f4 v[108:111], v[8:15], v[178:185], v[108:111], v251, v250 op_sel_hi:[0,0,0]
	v_mfma_scale_f32_16x16x128_f8f6f4 v[104:107], v[0:7], v[178:185], v[104:107], v251, v250 op_sel_hi:[0,0,0]
	v_mfma_scale_f32_16x16x128_f8f6f4 v[100:103], v[8:15], v[186:193], v[100:103], v251, v250 op_sel_hi:[0,0,0]
	v_mfma_scale_f32_16x16x128_f8f6f4 v[96:99], v[0:7], v[186:193], v[96:99], v251, v250 op_sel_hi:[0,0,0]
	s_barrier
	s_add_u32 s40, s82, 0x180
	s_addc_u32 s41, s83, 0
	ds_read_b128 v[162:165], v249 offset:49152
	ds_read_b128 v[166:169], v249 offset:50176
	ds_read_b128 v[170:173], v249 offset:51200
	ds_read_b128 v[174:177], v249 offset:52224
	ds_read_b128 v[178:181], v249 offset:53248
	ds_read_b128 v[182:185], v249 offset:54272
	ds_read_b128 v[186:189], v249 offset:55296
	ds_read_b128 v[190:193], v249 offset:56320
	s_add_u32 s78, s84, 0x180
	s_mov_b32 m0, s54
	s_nop 0
	global_load_lds_dwordx4 v161, s[40:41]
	s_addc_u32 s79, s85, 0
	s_mov_b32 m0, s55
	s_nop 0
	global_load_lds_dwordx4 v161, s[78:79]
	s_add_u32 s40, s86, 0x180
	s_addc_u32 s41, s87, 0
	s_add_u32 s78, s90, 0x180
	s_mov_b32 m0, s62
	s_nop 0
	global_load_lds_dwordx4 v161, s[40:41]
	s_addc_u32 s79, s91, 0
	s_mov_b32 m0, s63
	s_nop 0
	global_load_lds_dwordx4 v161, s[78:79]
	s_add_u32 s40, s75, 0x180
	s_addc_u32 s41, s77, 0
	s_add_u32 s78, s88, 0x180
	s_mov_b32 m0, s56
	s_nop 0
	global_load_lds_dwordx4 v160, s[40:41]
	s_addc_u32 s79, s89, 0
	s_mov_b32 m0, s61
	s_nop 0
	global_load_lds_dwordx4 v160, s[78:79]
	s_waitcnt vmcnt(8)
	s_waitcnt lgkmcnt(0)
	s_barrier
	s_waitcnt lgkmcnt(6)
	v_mfma_scale_f32_16x16x128_f8f6f4 v[92:95], v[24:31], v[162:169], v[92:95], v251, v250 op_sel_hi:[0,0,0]
	v_mfma_scale_f32_16x16x128_f8f6f4 v[88:91], v[16:23], v[162:169], v[88:91], v251, v250 op_sel_hi:[0,0,0]
	s_waitcnt lgkmcnt(4)
	v_mfma_scale_f32_16x16x128_f8f6f4 v[84:87], v[24:31], v[170:177], v[84:87], v251, v250 op_sel_hi:[0,0,0]
	v_mfma_scale_f32_16x16x128_f8f6f4 v[80:83], v[16:23], v[170:177], v[80:83], v251, v250 op_sel_hi:[0,0,0]
	s_waitcnt lgkmcnt(2)
	v_mfma_scale_f32_16x16x128_f8f6f4 v[76:79], v[24:31], v[178:185], v[76:79], v251, v250 op_sel_hi:[0,0,0]
	v_mfma_scale_f32_16x16x128_f8f6f4 v[72:75], v[16:23], v[178:185], v[72:75], v251, v250 op_sel_hi:[0,0,0]
	s_waitcnt lgkmcnt(0)
	v_mfma_scale_f32_16x16x128_f8f6f4 v[68:71], v[24:31], v[186:193], v[68:71], v251, v250 op_sel_hi:[0,0,0]
	v_mfma_scale_f32_16x16x128_f8f6f4 v[64:67], v[16:23], v[186:193], v[64:67], v251, v250 op_sel_hi:[0,0,0]
	v_mfma_scale_f32_16x16x128_f8f6f4 v[60:63], v[8:15], v[162:169], v[60:63], v251, v250 op_sel_hi:[0,0,0]
	v_mfma_scale_f32_16x16x128_f8f6f4 v[56:59], v[0:7], v[162:169], v[56:59], v251, v250 op_sel_hi:[0,0,0]
	v_mfma_scale_f32_16x16x128_f8f6f4 v[52:55], v[8:15], v[170:177], v[52:55], v251, v250 op_sel_hi:[0,0,0]
	v_mfma_scale_f32_16x16x128_f8f6f4 v[48:51], v[0:7], v[170:177], v[48:51], v251, v250 op_sel_hi:[0,0,0]
	v_mfma_scale_f32_16x16x128_f8f6f4 v[44:47], v[8:15], v[178:185], v[44:47], v251, v250 op_sel_hi:[0,0,0]
	v_mfma_scale_f32_16x16x128_f8f6f4 v[40:43], v[0:7], v[178:185], v[40:43], v251, v250 op_sel_hi:[0,0,0]
	v_mfma_scale_f32_16x16x128_f8f6f4 v[36:39], v[8:15], v[186:193], v[36:39], v251, v250 op_sel_hi:[0,0,0]
	v_mfma_scale_f32_16x16x128_f8f6f4 v[32:35], v[0:7], v[186:193], v[32:35], v251, v250 op_sel_hi:[0,0,0]
	s_barrier
	s_add_u32 s38, s38, 0x100
	s_addc_u32 s39, s39, 0
	s_cmp_ge_i32 s74, s2
	s_cbranch_scc0 .LBB0_314
	s_branch .LBB0_315

.LBB0_314:
	ds_read_b128 v[24:27], v194
	ds_read_b128 v[28:31], v194 offset:1024
	ds_read_b128 v[16:19], v194 offset:2048
	ds_read_b128 v[20:23], v194 offset:3072
	ds_read_b128 v[8:11], v248
	ds_read_b128 v[12:15], v248 offset:1024
	ds_read_b128 v[0:3], v248 offset:2048
	ds_read_b128 v[4:7], v248 offset:3072
	s_add_i32 s74, s74, 2
	s_add_u32 s75, s4, s38
	s_addc_u32 s77, s5, s39
	s_add_u32 s40, s75, 0x100
	s_addc_u32 s41, s77, 0
	s_add_u32 s78, s22, s38
	ds_read_b128 v[162:165], v249
	ds_read_b128 v[166:169], v249 offset:1024
	ds_read_b128 v[170:173], v249 offset:2048
	ds_read_b128 v[174:177], v249 offset:3072
	ds_read_b128 v[178:181], v249 offset:4096
	ds_read_b128 v[182:185], v249 offset:5120
	ds_read_b128 v[186:189], v249 offset:6144
	ds_read_b128 v[190:193], v249 offset:7168
	s_addc_u32 s79, s33, s39
	s_add_u32 s82, s78, 0x80
	s_addc_u32 s83, s79, 0
	s_add_u32 s80, s70, s38
	s_addc_u32 s81, s71, s39
	s_add_u32 s84, s80, 0x80
	s_mov_b32 m0, s64
	s_nop 0
	global_load_lds_dwordx4 v160, s[82:83]
	s_addc_u32 s85, s81, 0
	s_mov_b32 m0, s65
	s_nop 0
	global_load_lds_dwordx4 v160, s[84:85]
	s_waitcnt vmcnt(8)
	s_waitcnt lgkmcnt(0)
	s_barrier
	s_waitcnt lgkmcnt(6)
	v_mfma_scale_f32_16x16x128_f8f6f4 v[156:159], v[24:31], v[162:169], v[156:159], v251, v250 op_sel_hi:[0,0,0]
	v_mfma_scale_f32_16x16x128_f8f6f4 v[152:155], v[16:23], v[162:169], v[152:155], v251, v250 op_sel_hi:[0,0,0]
	s_waitcnt lgkmcnt(4)
	v_mfma_scale_f32_16x16x128_f8f6f4 v[148:151], v[24:31], v[170:177], v[148:151], v251, v250 op_sel_hi:[0,0,0]
	v_mfma_scale_f32_16x16x128_f8f6f4 v[144:147], v[16:23], v[170:177], v[144:147], v251, v250 op_sel_hi:[0,0,0]
	s_waitcnt lgkmcnt(2)
	v_mfma_scale_f32_16x16x128_f8f6f4 v[140:143], v[24:31], v[178:185], v[140:143], v251, v250 op_sel_hi:[0,0,0]
	v_mfma_scale_f32_16x16x128_f8f6f4 v[136:139], v[16:23], v[178:185], v[136:139], v251, v250 op_sel_hi:[0,0,0]
	s_waitcnt lgkmcnt(0)
	v_mfma_scale_f32_16x16x128_f8f6f4 v[132:135], v[24:31], v[186:193], v[132:135], v251, v250 op_sel_hi:[0,0,0]
	v_mfma_scale_f32_16x16x128_f8f6f4 v[128:131], v[16:23], v[186:193], v[128:131], v251, v250 op_sel_hi:[0,0,0]
	v_mfma_scale_f32_16x16x128_f8f6f4 v[124:127], v[8:15], v[162:169], v[124:127], v251, v250 op_sel_hi:[0,0,0]
	v_mfma_scale_f32_16x16x128_f8f6f4 v[120:123], v[0:7], v[162:169], v[120:123], v251, v250 op_sel_hi:[0,0,0]
	v_mfma_scale_f32_16x16x128_f8f6f4 v[116:119], v[8:15], v[170:177], v[116:119], v251, v250 op_sel_hi:[0,0,0]
	v_mfma_scale_f32_16x16x128_f8f6f4 v[112:115], v[0:7], v[170:177], v[112:115], v251, v250 op_sel_hi:[0,0,0]
	v_mfma_scale_f32_16x16x128_f8f6f4 v[108:111], v[8:15], v[178:185], v[108:111], v251, v250 op_sel_hi:[0,0,0]
	v_mfma_scale_f32_16x16x128_f8f6f4 v[104:107], v[0:7], v[178:185], v[104:107], v251, v250 op_sel_hi:[0,0,0]
	v_mfma_scale_f32_16x16x128_f8f6f4 v[100:103], v[8:15], v[186:193], v[100:103], v251, v250 op_sel_hi:[0,0,0]
	v_mfma_scale_f32_16x16x128_f8f6f4 v[96:99], v[0:7], v[186:193], v[96:99], v251, v250 op_sel_hi:[0,0,0]
	s_barrier
	s_add_u32 s82, s6, s38
	s_addc_u32 s83, s7, s39
	s_add_u32 s86, s82, 0x100
	s_addc_u32 s87, s83, 0
	s_add_u32 s84, s68, s38
	s_addc_u32 s85, s69, s39
	ds_read_b128 v[162:165], v249 offset:16384
	ds_read_b128 v[166:169], v249 offset:17408
	ds_read_b128 v[170:173], v249 offset:18432
	ds_read_b128 v[174:177], v249 offset:19456
	ds_read_b128 v[178:181], v249 offset:20480
	ds_read_b128 v[182:185], v249 offset:21504
	ds_read_b128 v[186:189], v249 offset:22528
	ds_read_b128 v[190:193], v249 offset:23552
	s_add_u32 s88, s84, 0x100
	s_mov_b32 m0, s49
	s_nop 0
	global_load_lds_dwordx4 v161, s[86:87]
	s_addc_u32 s89, s85, 0
	s_mov_b32 m0, s50
	s_nop 0
	global_load_lds_dwordx4 v161, s[88:89]
	s_add_u32 s86, s42, s38
	s_addc_u32 s87, s43, s39
	s_add_u32 s88, s86, 0x100
	s_addc_u32 s89, s87, 0
	s_add_u32 s90, s44, s38
	s_addc_u32 s91, s45, s39
	s_add_u32 s92, s90, 0x100
	s_mov_b32 m0, s51
	s_nop 0
	global_load_lds_dwordx4 v161, s[88:89]
	s_addc_u32 s93, s91, 0
	s_mov_b32 m0, s57
	s_nop 0
	global_load_lds_dwordx4 v161, s[92:93]
	s_add_u32 s88, s72, s38
	s_addc_u32 s89, s73, s39
	s_add_u32 s92, s88, 0x100
	s_mov_b32 m0, s53
	s_nop 0
	global_load_lds_dwordx4 v160, s[40:41]
	s_addc_u32 s93, s89, 0
	s_mov_b32 m0, s58
	s_nop 0
	global_load_lds_dwordx4 v160, s[92:93]
	s_waitcnt vmcnt(8)
	s_waitcnt lgkmcnt(0)
	s_barrier
	s_waitcnt lgkmcnt(6)
	v_mfma_scale_f32_16x16x128_f8f6f4 v[92:95], v[24:31], v[162:169], v[92:95], v251, v250 op_sel_hi:[0,0,0]
	v_mfma_scale_f32_16x16x128_f8f6f4 v[88:91], v[16:23], v[162:169], v[88:91], v251, v250 op_sel_hi:[0,0,0]
	s_waitcnt lgkmcnt(4)
	v_mfma_scale_f32_16x16x128_f8f6f4 v[84:87], v[24:31], v[170:177], v[84:87], v251, v250 op_sel_hi:[0,0,0]
	v_mfma_scale_f32_16x16x128_f8f6f4 v[80:83], v[16:23], v[170:177], v[80:83], v251, v250 op_sel_hi:[0,0,0]
	s_waitcnt lgkmcnt(2)
	v_mfma_scale_f32_16x16x128_f8f6f4 v[76:79], v[24:31], v[178:185], v[76:79], v251, v250 op_sel_hi:[0,0,0]
	v_mfma_scale_f32_16x16x128_f8f6f4 v[72:75], v[16:23], v[178:185], v[72:75], v251, v250 op_sel_hi:[0,0,0]
	s_waitcnt lgkmcnt(0)
	v_mfma_scale_f32_16x16x128_f8f6f4 v[68:71], v[24:31], v[186:193], v[68:71], v251, v250 op_sel_hi:[0,0,0]
	v_mfma_scale_f32_16x16x128_f8f6f4 v[64:67], v[16:23], v[186:193], v[64:67], v251, v250 op_sel_hi:[0,0,0]
	v_mfma_scale_f32_16x16x128_f8f6f4 v[60:63], v[8:15], v[162:169], v[60:63], v251, v250 op_sel_hi:[0,0,0]
	v_mfma_scale_f32_16x16x128_f8f6f4 v[56:59], v[0:7], v[162:169], v[56:59], v251, v250 op_sel_hi:[0,0,0]
	v_mfma_scale_f32_16x16x128_f8f6f4 v[52:55], v[8:15], v[170:177], v[52:55], v251, v250 op_sel_hi:[0,0,0]
	v_mfma_scale_f32_16x16x128_f8f6f4 v[48:51], v[0:7], v[170:177], v[48:51], v251, v250 op_sel_hi:[0,0,0]
	v_mfma_scale_f32_16x16x128_f8f6f4 v[44:47], v[8:15], v[178:185], v[44:47], v251, v250 op_sel_hi:[0,0,0]
	v_mfma_scale_f32_16x16x128_f8f6f4 v[40:43], v[0:7], v[178:185], v[40:43], v251, v250 op_sel_hi:[0,0,0]
	v_mfma_scale_f32_16x16x128_f8f6f4 v[36:39], v[8:15], v[186:193], v[36:39], v251, v250 op_sel_hi:[0,0,0]
	v_mfma_scale_f32_16x16x128_f8f6f4 v[32:35], v[0:7], v[186:193], v[32:35], v251, v250 op_sel_hi:[0,0,0]
	s_barrier
	ds_read_b128 v[24:27], v252
	ds_read_b128 v[28:31], v252 offset:1024
	ds_read_b128 v[16:19], v252 offset:2048
	ds_read_b128 v[20:23], v252 offset:3072
	ds_read_b128 v[8:11], v253
	ds_read_b128 v[12:15], v253 offset:1024
	ds_read_b128 v[0:3], v253 offset:2048
	ds_read_b128 v[4:7], v253 offset:3072
	ds_read_b128 v[162:165], v249 offset:32768
	ds_read_b128 v[166:169], v249 offset:33792
	ds_read_b128 v[170:173], v249 offset:34816
	ds_read_b128 v[174:177], v249 offset:35840
	ds_read_b128 v[178:181], v249 offset:36864
	ds_read_b128 v[182:185], v249 offset:37888
	ds_read_b128 v[186:189], v249 offset:38912
	ds_read_b128 v[190:193], v249 offset:39936
	s_add_u32 s40, s78, 0x100
	s_addc_u32 s41, s79, 0
	s_add_u32 s78, s80, 0x100
	s_mov_b32 m0, s59
	s_nop 0
	global_load_lds_dwordx4 v160, s[40:41]
	s_addc_u32 s79, s81, 0
	s_mov_b32 m0, s60
	s_nop 0
	global_load_lds_dwordx4 v160, s[78:79]
	s_waitcnt vmcnt(8)
	s_waitcnt lgkmcnt(0)
	s_barrier
	s_waitcnt lgkmcnt(6)
	v_mfma_scale_f32_16x16x128_f8f6f4 v[156:159], v[24:31], v[162:169], v[156:159], v251, v250 op_sel_hi:[0,0,0]
	v_mfma_scale_f32_16x16x128_f8f6f4 v[152:155], v[16:23], v[162:169], v[152:155], v251, v250 op_sel_hi:[0,0,0]
	s_waitcnt lgkmcnt(4)
	v_mfma_scale_f32_16x16x128_f8f6f4 v[148:151], v[24:31], v[170:177], v[148:151], v251, v250 op_sel_hi:[0,0,0]
	v_mfma_scale_f32_16x16x128_f8f6f4 v[144:147], v[16:23], v[170:177], v[144:147], v251, v250 op_sel_hi:[0,0,0]
	s_waitcnt lgkmcnt(2)
	v_mfma_scale_f32_16x16x128_f8f6f4 v[140:143], v[24:31], v[178:185], v[140:143], v251, v250 op_sel_hi:[0,0,0]
	v_mfma_scale_f32_16x16x128_f8f6f4 v[136:139], v[16:23], v[178:185], v[136:139], v251, v250 op_sel_hi:[0,0,0]
	s_waitcnt lgkmcnt(0)
	v_mfma_scale_f32_16x16x128_f8f6f4 v[132:135], v[24:31], v[186:193], v[132:135], v251, v250 op_sel_hi:[0,0,0]
	v_mfma_scale_f32_16x16x128_f8f6f4 v[128:131], v[16:23], v[186:193], v[128:131], v251, v250 op_sel_hi:[0,0,0]
	v_mfma_scale_f32_16x16x128_f8f6f4 v[124:127], v[8:15], v[162:169], v[124:127], v251, v250 op_sel_hi:[0,0,0]
	v_mfma_scale_f32_16x16x128_f8f6f4 v[120:123], v[0:7], v[162:169], v[120:123], v251, v250 op_sel_hi:[0,0,0]
	v_mfma_scale_f32_16x16x128_f8f6f4 v[116:119], v[8:15], v[170:177], v[116:119], v251, v250 op_sel_hi:[0,0,0]
	v_mfma_scale_f32_16x16x128_f8f6f4 v[112:115], v[0:7], v[170:177], v[112:115], v251, v250 op_sel_hi:[0,0,0]
	v_mfma_scale_f32_16x16x128_f8f6f4 v[108:111], v[8:15], v[178:185], v[108:111], v251, v250 op_sel_hi:[0,0,0]
	v_mfma_scale_f32_16x16x128_f8f6f4 v[104:107], v[0:7], v[178:185], v[104:107], v251, v250 op_sel_hi:[0,0,0]
	v_mfma_scale_f32_16x16x128_f8f6f4 v[100:103], v[8:15], v[186:193], v[100:103], v251, v250 op_sel_hi:[0,0,0]
	v_mfma_scale_f32_16x16x128_f8f6f4 v[96:99], v[0:7], v[186:193], v[96:99], v251, v250 op_sel_hi:[0,0,0]
	s_barrier
	s_add_u32 s40, s82, 0x180
	s_addc_u32 s41, s83, 0
	ds_read_b128 v[162:165], v249 offset:49152
	ds_read_b128 v[166:169], v249 offset:50176
	ds_read_b128 v[170:173], v249 offset:51200
	ds_read_b128 v[174:177], v249 offset:52224
	ds_read_b128 v[178:181], v249 offset:53248
	ds_read_b128 v[182:185], v249 offset:54272
	ds_read_b128 v[186:189], v249 offset:55296
	ds_read_b128 v[190:193], v249 offset:56320
	s_add_u32 s78, s84, 0x180
	s_mov_b32 m0, s54
	s_nop 0
	global_load_lds_dwordx4 v161, s[40:41]
	s_addc_u32 s79, s85, 0
	s_mov_b32 m0, s55
	s_nop 0
	global_load_lds_dwordx4 v161, s[78:79]
	s_add_u32 s40, s86, 0x180
	s_addc_u32 s41, s87, 0
	s_add_u32 s78, s90, 0x180
	s_mov_b32 m0, s62
	s_nop 0
	global_load_lds_dwordx4 v161, s[40:41]
	s_addc_u32 s79, s91, 0
	s_mov_b32 m0, s63
	s_nop 0
	global_load_lds_dwordx4 v161, s[78:79]
	s_add_u32 s40, s75, 0x180
	s_addc_u32 s41, s77, 0
	s_add_u32 s78, s88, 0x180
	s_mov_b32 m0, s56
	s_nop 0
	global_load_lds_dwordx4 v160, s[40:41]
	s_addc_u32 s79, s89, 0
	s_mov_b32 m0, s61
	s_nop 0
	global_load_lds_dwordx4 v160, s[78:79]
	s_waitcnt vmcnt(8)
	s_waitcnt lgkmcnt(0)
	s_barrier
	s_waitcnt lgkmcnt(6)
	v_mfma_scale_f32_16x16x128_f8f6f4 v[92:95], v[24:31], v[162:169], v[92:95], v251, v250 op_sel_hi:[0,0,0]
	v_mfma_scale_f32_16x16x128_f8f6f4 v[88:91], v[16:23], v[162:169], v[88:91], v251, v250 op_sel_hi:[0,0,0]
	s_waitcnt lgkmcnt(4)
	v_mfma_scale_f32_16x16x128_f8f6f4 v[84:87], v[24:31], v[170:177], v[84:87], v251, v250 op_sel_hi:[0,0,0]
	v_mfma_scale_f32_16x16x128_f8f6f4 v[80:83], v[16:23], v[170:177], v[80:83], v251, v250 op_sel_hi:[0,0,0]
	s_waitcnt lgkmcnt(2)
	v_mfma_scale_f32_16x16x128_f8f6f4 v[76:79], v[24:31], v[178:185], v[76:79], v251, v250 op_sel_hi:[0,0,0]
	v_mfma_scale_f32_16x16x128_f8f6f4 v[72:75], v[16:23], v[178:185], v[72:75], v251, v250 op_sel_hi:[0,0,0]
	s_waitcnt lgkmcnt(0)
	v_mfma_scale_f32_16x16x128_f8f6f4 v[68:71], v[24:31], v[186:193], v[68:71], v251, v250 op_sel_hi:[0,0,0]
	v_mfma_scale_f32_16x16x128_f8f6f4 v[64:67], v[16:23], v[186:193], v[64:67], v251, v250 op_sel_hi:[0,0,0]
	v_mfma_scale_f32_16x16x128_f8f6f4 v[60:63], v[8:15], v[162:169], v[60:63], v251, v250 op_sel_hi:[0,0,0]
	v_mfma_scale_f32_16x16x128_f8f6f4 v[56:59], v[0:7], v[162:169], v[56:59], v251, v250 op_sel_hi:[0,0,0]
	v_mfma_scale_f32_16x16x128_f8f6f4 v[52:55], v[8:15], v[170:177], v[52:55], v251, v250 op_sel_hi:[0,0,0]
	v_mfma_scale_f32_16x16x128_f8f6f4 v[48:51], v[0:7], v[170:177], v[48:51], v251, v250 op_sel_hi:[0,0,0]
	v_mfma_scale_f32_16x16x128_f8f6f4 v[44:47], v[8:15], v[178:185], v[44:47], v251, v250 op_sel_hi:[0,0,0]
	v_mfma_scale_f32_16x16x128_f8f6f4 v[40:43], v[0:7], v[178:185], v[40:43], v251, v250 op_sel_hi:[0,0,0]
	v_mfma_scale_f32_16x16x128_f8f6f4 v[36:39], v[8:15], v[186:193], v[36:39], v251, v250 op_sel_hi:[0,0,0]
	v_mfma_scale_f32_16x16x128_f8f6f4 v[32:35], v[0:7], v[186:193], v[32:35], v251, v250 op_sel_hi:[0,0,0]
	s_barrier
	s_add_u32 s38, s38, 0x100
	s_addc_u32 s39, s39, 0
	s_cmp_ge_i32 s74, s2
	s_cbranch_scc0 .LBB0_314

.LBB0_317:
	ds_read_b128 v[24:27], v194
	ds_read_b128 v[28:31], v194 offset:1024
	ds_read_b128 v[16:19], v194 offset:2048
	ds_read_b128 v[20:23], v194 offset:3072
	ds_read_b128 v[8:11], v248
	ds_read_b128 v[12:15], v248 offset:1024
	ds_read_b128 v[0:3], v248 offset:2048
	ds_read_b128 v[4:7], v248 offset:3072
	s_ashr_i32 s45, s20, 31
	s_mov_b32 s44, s20
	s_lshl_b64 s[44:45], s[44:45], 7
	s_add_u32 s2, s4, s44
	ds_read_b128 v[162:165], v249
	ds_read_b128 v[166:169], v249 offset:1024
	ds_read_b128 v[170:173], v249 offset:2048
	ds_read_b128 v[174:177], v249 offset:3072
	ds_read_b128 v[228:231], v249 offset:4096
	ds_read_b128 v[232:235], v249 offset:5120
	ds_read_b128 v[236:239], v249 offset:6144
	ds_read_b128 v[240:243], v249 offset:7168
	s_addc_u32 s4, s5, s45
	s_add_u32 s2, s2, s36
	s_addc_u32 s5, s4, s37
	s_add_u32 s4, s2, 0xffffff80
	s_addc_u32 s5, s5, -1
	s_add_u32 s34, s4, s34
	s_mov_b32 m0, s64
	s_nop 0
	global_load_lds_dwordx4 v160, s[4:5]
	s_addc_u32 s35, s5, s35
	s_mov_b32 m0, s65
	s_nop 0
	global_load_lds_dwordx4 v160, s[34:35]
	s_waitcnt vmcnt(8)
	s_waitcnt lgkmcnt(0)
	s_barrier
	s_waitcnt lgkmcnt(6)
	v_mfma_scale_f32_16x16x128_f8f6f4 v[180:183], v[24:31], v[162:169], v[156:159], v251, v250 op_sel_hi:[0,0,0]
	v_mfma_scale_f32_16x16x128_f8f6f4 v[184:187], v[16:23], v[162:169], v[152:155], v251, v250 op_sel_hi:[0,0,0]
	s_waitcnt lgkmcnt(4)
	v_mfma_scale_f32_16x16x128_f8f6f4 v[188:191], v[24:31], v[170:177], v[148:151], v251, v250 op_sel_hi:[0,0,0]
	v_mfma_scale_f32_16x16x128_f8f6f4 v[144:147], v[16:23], v[170:177], v[144:147], v251, v250 op_sel_hi:[0,0,0]
	s_waitcnt lgkmcnt(2)
	v_mfma_scale_f32_16x16x128_f8f6f4 v[196:199], v[24:31], v[228:235], v[140:143], v251, v250 op_sel_hi:[0,0,0]
	v_mfma_scale_f32_16x16x128_f8f6f4 v[200:203], v[16:23], v[228:235], v[136:139], v251, v250 op_sel_hi:[0,0,0]
	s_waitcnt lgkmcnt(0)
	v_mfma_scale_f32_16x16x128_f8f6f4 v[204:207], v[24:31], v[236:243], v[132:135], v251, v250 op_sel_hi:[0,0,0]
	v_mfma_scale_f32_16x16x128_f8f6f4 v[208:211], v[16:23], v[236:243], v[128:131], v251, v250 op_sel_hi:[0,0,0]
	v_mfma_scale_f32_16x16x128_f8f6f4 v[212:215], v[8:15], v[162:169], v[124:127], v251, v250 op_sel_hi:[0,0,0]
	v_mfma_scale_f32_16x16x128_f8f6f4 v[216:219], v[0:7], v[162:169], v[120:123], v251, v250 op_sel_hi:[0,0,0]
	v_mfma_scale_f32_16x16x128_f8f6f4 v[116:119], v[8:15], v[170:177], v[116:119], v251, v250 op_sel_hi:[0,0,0]
	v_mfma_scale_f32_16x16x128_f8f6f4 v[220:223], v[0:7], v[170:177], v[112:115], v251, v250 op_sel_hi:[0,0,0]
	v_mfma_scale_f32_16x16x128_f8f6f4 v[224:227], v[8:15], v[228:235], v[108:111], v251, v250 op_sel_hi:[0,0,0]
	v_mfma_scale_f32_16x16x128_f8f6f4 v[228:231], v[0:7], v[228:235], v[104:107], v251, v250 op_sel_hi:[0,0,0]
	v_mfma_scale_f32_16x16x128_f8f6f4 v[232:235], v[8:15], v[236:243], v[100:103], v251, v250 op_sel_hi:[0,0,0]
	v_mfma_scale_f32_16x16x128_f8f6f4 v[236:239], v[0:7], v[236:243], v[96:99], v251, v250 op_sel_hi:[0,0,0]
	s_barrier
	s_add_u32 s34, s6, s0
	s_nop 3
	ds_read_b128 v[96:99], v249 offset:16384
	ds_read_b128 v[100:103], v249 offset:17408
	ds_read_b128 v[104:107], v249 offset:18432
	ds_read_b128 v[108:111], v249 offset:19456
	ds_read_b128 v[168:171], v249 offset:20480
	ds_read_b128 v[172:175], v249 offset:21504
	ds_read_b128 v[240:243], v249 offset:22528
	ds_read_b128 v[244:247], v249 offset:23552
	s_addc_u32 s35, s7, s1
	s_mov_b32 m0, s49
	s_nop 0
	global_load_lds_dwordx4 v193, s[6:7]
	s_add_u32 s36, s6, s18
	s_mov_b32 m0, s50
	s_nop 0
	global_load_lds_dwordx4 v193, s[34:35]
	s_addc_u32 s37, s7, s19
	s_add_u32 s44, s36, s0
	s_mov_b32 m0, s51
	s_nop 0
	global_load_lds_dwordx4 v193, s[36:37]
	s_addc_u32 s45, s37, s1
	s_mov_b32 m0, s57
	s_nop 0
	global_load_lds_dwordx4 v193, s[44:45]
	s_add_u32 s4, s42, s40
	s_mov_b32 m0, s53
	s_nop 0
	global_load_lds_dwordx4 v192, s[42:43]
	s_addc_u32 s5, s43, s41
	s_mov_b32 m0, s58
	s_nop 0
	global_load_lds_dwordx4 v192, s[4:5]
	s_waitcnt vmcnt(8)
	s_waitcnt lgkmcnt(0)
	s_barrier
	s_waitcnt lgkmcnt(6)
	v_mfma_scale_f32_16x16x128_f8f6f4 v[124:127], v[24:31], v[96:103], v[92:95], v251, v250 op_sel_hi:[0,0,0]
	v_mfma_scale_f32_16x16x128_f8f6f4 v[128:131], v[16:23], v[96:103], v[88:91], v251, v250 op_sel_hi:[0,0,0]
	s_waitcnt lgkmcnt(4)
	v_mfma_scale_f32_16x16x128_f8f6f4 v[132:135], v[24:31], v[104:111], v[84:87], v251, v250 op_sel_hi:[0,0,0]
	v_mfma_scale_f32_16x16x128_f8f6f4 v[136:139], v[16:23], v[104:111], v[80:83], v251, v250 op_sel_hi:[0,0,0]
	s_waitcnt lgkmcnt(2)
	v_mfma_scale_f32_16x16x128_f8f6f4 v[76:79], v[24:31], v[168:175], v[76:79], v251, v250 op_sel_hi:[0,0,0]
	v_mfma_scale_f32_16x16x128_f8f6f4 v[140:143], v[16:23], v[168:175], v[72:75], v251, v250 op_sel_hi:[0,0,0]
	s_waitcnt lgkmcnt(0)
	v_mfma_scale_f32_16x16x128_f8f6f4 v[68:71], v[24:31], v[240:247], v[68:71], v251, v250 op_sel_hi:[0,0,0]
	v_mfma_scale_f32_16x16x128_f8f6f4 v[148:151], v[16:23], v[240:247], v[64:67], v251, v250 op_sel_hi:[0,0,0]
	v_mfma_scale_f32_16x16x128_f8f6f4 v[60:63], v[8:15], v[96:103], v[60:63], v251, v250 op_sel_hi:[0,0,0]
	v_mfma_scale_f32_16x16x128_f8f6f4 v[152:155], v[0:7], v[96:103], v[56:59], v251, v250 op_sel_hi:[0,0,0]
	v_mfma_scale_f32_16x16x128_f8f6f4 v[156:159], v[8:15], v[104:111], v[52:55], v251, v250 op_sel_hi:[0,0,0]
	v_mfma_scale_f32_16x16x128_f8f6f4 v[160:163], v[0:7], v[104:111], v[48:51], v251, v250 op_sel_hi:[0,0,0]
	v_mfma_scale_f32_16x16x128_f8f6f4 v[164:167], v[8:15], v[168:175], v[44:47], v251, v250 op_sel_hi:[0,0,0]
	v_mfma_scale_f32_16x16x128_f8f6f4 v[168:171], v[0:7], v[168:175], v[40:43], v251, v250 op_sel_hi:[0,0,0]
	v_mfma_scale_f32_16x16x128_f8f6f4 v[172:175], v[8:15], v[240:247], v[36:39], v251, v250 op_sel_hi:[0,0,0]
	v_mfma_scale_f32_16x16x128_f8f6f4 v[176:179], v[0:7], v[240:247], v[32:35], v251, v250 op_sel_hi:[0,0,0]
	s_barrier
	ds_read_b128 v[24:27], v252
	ds_read_b128 v[28:31], v252 offset:1024
	ds_read_b128 v[16:19], v252 offset:2048
	ds_read_b128 v[20:23], v252 offset:3072
	ds_read_b128 v[8:11], v253
	ds_read_b128 v[12:15], v253 offset:1024
	ds_read_b128 v[0:3], v253 offset:2048
	ds_read_b128 v[4:7], v253 offset:3072
	ds_read_b128 v[32:35], v249 offset:32768
	ds_read_b128 v[36:39], v249 offset:33792
	ds_read_b128 v[40:43], v249 offset:34816
	ds_read_b128 v[44:47], v249 offset:35840
	ds_read_b128 v[48:51], v249 offset:36864
	ds_read_b128 v[52:55], v249 offset:37888
	ds_read_b128 v[80:83], v249 offset:38912
	ds_read_b128 v[84:87], v249 offset:39936
	s_add_u32 s68, s42, s38
	s_addc_u32 s69, s43, s39
	s_add_u32 s70, s68, s40
	s_mov_b32 m0, s59
	s_nop 0
	global_load_lds_dwordx4 v192, s[68:69]
	s_addc_u32 s71, s69, s41
	s_mov_b32 m0, s60
	s_nop 0
	global_load_lds_dwordx4 v192, s[70:71]
	s_waitcnt vmcnt(8)
	s_waitcnt lgkmcnt(0)
	s_barrier
	s_waitcnt lgkmcnt(6)
	v_mfma_scale_f32_16x16x128_f8f6f4 v[240:243], v[24:31], v[32:39], v[180:183], v251, v250 op_sel_hi:[0,0,0]
	v_mfma_scale_f32_16x16x128_f8f6f4 v[120:123], v[16:23], v[32:39], v[184:187], v251, v250 op_sel_hi:[0,0,0]
	s_waitcnt lgkmcnt(4)
	v_mfma_scale_f32_16x16x128_f8f6f4 v[112:115], v[24:31], v[40:47], v[188:191], v251, v250 op_sel_hi:[0,0,0]
	v_mfma_scale_f32_16x16x128_f8f6f4 v[104:107], v[16:23], v[40:47], v[144:147], v251, v250 op_sel_hi:[0,0,0]
	s_waitcnt lgkmcnt(2)
	v_mfma_scale_f32_16x16x128_f8f6f4 v[100:103], v[24:31], v[48:55], v[196:199], v251, v250 op_sel_hi:[0,0,0]
	v_mfma_scale_f32_16x16x128_f8f6f4 v[92:95], v[16:23], v[48:55], v[200:203], v251, v250 op_sel_hi:[0,0,0]
	s_waitcnt lgkmcnt(0)
	v_mfma_scale_f32_16x16x128_f8f6f4 v[188:191], v[24:31], v[80:87], v[204:207], v251, v250 op_sel_hi:[0,0,0]
	v_mfma_scale_f32_16x16x128_f8f6f4 v[144:147], v[16:23], v[80:87], v[208:211], v251, v250 op_sel_hi:[0,0,0]
	v_mfma_scale_f32_16x16x128_f8f6f4 v[184:187], v[8:15], v[32:39], v[212:215], v251, v250 op_sel_hi:[0,0,0]
	v_mfma_scale_f32_16x16x128_f8f6f4 v[180:183], v[0:7], v[32:39], v[216:219], v251, v250 op_sel_hi:[0,0,0]
	v_mfma_scale_f32_16x16x128_f8f6f4 v[116:119], v[8:15], v[40:47], v[116:119], v251, v250 op_sel_hi:[0,0,0]
	v_mfma_scale_f32_16x16x128_f8f6f4 v[108:111], v[0:7], v[40:47], v[220:223], v251, v250 op_sel_hi:[0,0,0]
	v_mfma_scale_f32_16x16x128_f8f6f4 v[96:99], v[8:15], v[48:55], v[224:227], v251, v250 op_sel_hi:[0,0,0]
	v_mfma_scale_f32_16x16x128_f8f6f4 v[88:91], v[0:7], v[48:55], v[228:231], v251, v250 op_sel_hi:[0,0,0]
	v_mfma_scale_f32_16x16x128_f8f6f4 v[72:75], v[8:15], v[80:87], v[232:235], v251, v250 op_sel_hi:[0,0,0]
	v_mfma_scale_f32_16x16x128_f8f6f4 v[56:59], v[0:7], v[80:87], v[236:239], v251, v250 op_sel_hi:[0,0,0]
	s_barrier
	s_add_u32 s68, s6, 0x80
	s_addc_u32 s69, s7, 0
	s_add_u32 s34, s34, 0x80
	ds_read_b128 v[196:199], v249 offset:49152
	ds_read_b128 v[200:203], v249 offset:50176
	ds_read_b128 v[204:207], v249 offset:51200
	ds_read_b128 v[208:211], v249 offset:52224
	ds_read_b128 v[212:215], v249 offset:53248
	ds_read_b128 v[216:219], v249 offset:54272
	ds_read_b128 v[220:223], v249 offset:55296
	ds_read_b128 v[224:227], v249 offset:56320
	s_addc_u32 s35, s35, 0
	s_mov_b32 m0, s54
	s_nop 0
	global_load_lds_dwordx4 v193, s[68:69]
	s_nop 0
	s_mov_b32 m0, s55
	s_nop 0
	global_load_lds_dwordx4 v193, s[34:35]
	s_add_u32 s34, s36, 0x80
	s_addc_u32 s35, s37, 0
	s_add_u32 s36, s44, 0x80
	s_addc_u32 s37, s45, 0
	s_mov_b32 m0, s62
	s_nop 0
	global_load_lds_dwordx4 v193, s[34:35]
	s_add_u32 s34, s42, 0x80
	s_mov_b32 m0, s63
	s_nop 0
	global_load_lds_dwordx4 v193, s[36:37]
	s_addc_u32 s35, s43, 0
	s_add_u32 s4, s4, 0x80
	s_mov_b32 m0, s56
	s_nop 0
	global_load_lds_dwordx4 v192, s[34:35]
	s_addc_u32 s5, s5, 0
	s_mov_b32 m0, s61
	s_nop 0
	global_load_lds_dwordx4 v192, s[4:5]
	s_waitcnt vmcnt(8)
	s_waitcnt lgkmcnt(0)
	s_barrier
	s_waitcnt lgkmcnt(6)
	v_mfma_scale_f32_16x16x128_f8f6f4 v[84:87], v[24:31], v[196:203], v[124:127], v251, v250 op_sel_hi:[0,0,0]
	v_mfma_scale_f32_16x16x128_f8f6f4 v[64:67], v[16:23], v[196:203], v[128:131], v251, v250 op_sel_hi:[0,0,0]
	s_waitcnt lgkmcnt(4)
	v_mfma_scale_f32_16x16x128_f8f6f4 v[52:55], v[24:31], v[204:211], v[132:135], v251, v250 op_sel_hi:[0,0,0]
	v_mfma_scale_f32_16x16x128_f8f6f4 v[44:47], v[16:23], v[204:211], v[136:139], v251, v250 op_sel_hi:[0,0,0]
	s_waitcnt lgkmcnt(2)
	v_mfma_scale_f32_16x16x128_f8f6f4 v[36:39], v[24:31], v[212:219], v[76:79], v251, v250 op_sel_hi:[0,0,0]
	v_mfma_scale_f32_16x16x128_f8f6f4 v[32:35], v[16:23], v[212:219], v[140:143], v251, v250 op_sel_hi:[0,0,0]
	s_waitcnt lgkmcnt(0)
	v_mfma_scale_f32_16x16x128_f8f6f4 v[24:27], v[24:31], v[220:227], v[68:71], v251, v250 op_sel_hi:[0,0,0]
	v_mfma_scale_f32_16x16x128_f8f6f4 v[16:19], v[16:23], v[220:227], v[148:151], v251, v250 op_sel_hi:[0,0,0]
	v_mfma_scale_f32_16x16x128_f8f6f4 v[76:79], v[8:15], v[196:203], v[60:63], v251, v250 op_sel_hi:[0,0,0]
	v_mfma_scale_f32_16x16x128_f8f6f4 v[60:63], v[0:7], v[196:203], v[152:155], v251, v250 op_sel_hi:[0,0,0]
	v_mfma_scale_f32_16x16x128_f8f6f4 v[48:51], v[8:15], v[204:211], v[156:159], v251, v250 op_sel_hi:[0,0,0]
	v_mfma_scale_f32_16x16x128_f8f6f4 v[40:43], v[0:7], v[204:211], v[160:163], v251, v250 op_sel_hi:[0,0,0]
	v_mfma_scale_f32_16x16x128_f8f6f4 v[28:31], v[8:15], v[212:219], v[164:167], v251, v250 op_sel_hi:[0,0,0]
	v_mfma_scale_f32_16x16x128_f8f6f4 v[20:23], v[0:7], v[212:219], v[168:171], v251, v250 op_sel_hi:[0,0,0]
	v_mfma_scale_f32_16x16x128_f8f6f4 v[8:11], v[8:15], v[220:227], v[172:175], v251, v250 op_sel_hi:[0,0,0]
	v_mfma_scale_f32_16x16x128_f8f6f4 v[0:3], v[0:7], v[220:227], v[176:179], v251, v250 op_sel_hi:[0,0,0]
	s_barrier
	s_andn2_b64 vcc, exec, s[24:25]
	s_cbranch_vccnz .LBB0_319
	s_barrier

.LBB0_443:
	v_and_b32_e32 v1, 15, v2
	v_or_b32_e32 v3, s52, v1
	s_lshl_b64 s[50:51], s[8:9], 7
	s_lshl_b64 s[20:21], s[20:21], 7
	v_lshlrev_b32_e32 v5, 6, v3
	v_and_b32_e32 v6, 48, v2
	s_movk_i32 s8, 0x3c0
	v_and_or_b32 v5, v5, s8, v6
	s_add_u32 s8, s6, 0x80
	s_addc_u32 s9, s7, 0
	s_sub_u32 s22, 0, s16
	s_subb_u32 s23, 0, s17
	s_add_u32 s22, s10, s22
	s_addc_u32 s23, s11, s23
	s_add_u32 s22, s22, 0x80
	s_mov_b32 s98, 0
	s_cselect_b32 s99, 1, 0
	s_cmp_lt_u32 s76, 4
	s_cbranch_scc0 .Lsprio_5
	s_setprio 1
.Lsprio_5:
	s_cmp_lg_u32 s99, 0
	s_waitcnt vmcnt(2)
	s_barrier
	s_addc_u32 s23, s23, 0
	s_add_i32 s63, s54, 0x18000
	s_mov_b32 m0, s63
	s_nop 0
	global_load_lds_dwordx4 v0, s[8:9]
	s_add_i32 s64, s54, 0x1a000
	s_mov_b32 m0, s64
	s_nop 0
	global_load_lds_dwordx4 v0, s[22:23]
	s_add_u32 s8, s4, 0x80
	s_addc_u32 s9, s5, 0
	s_sub_u32 s22, 0, s48
	s_subb_u32 s23, 0, s49
	s_add_u32 s14, s14, s22
	s_addc_u32 s15, s15, s23
	s_add_u32 s14, s14, 0x80
	s_addc_u32 s15, s15, 0
	s_add_i32 s65, s54, 0x8000
	s_mov_b32 m0, s65
	s_nop 0
	global_load_lds_dwordx4 v128, s[8:9]
	s_add_i32 s66, s54, 0xa000
	s_mov_b32 m0, s66
	s_nop 0
	global_load_lds_dwordx4 v128, s[14:15]
	s_add_u32 s8, s10, 0x80
	s_addc_u32 s9, s11, 0
	s_add_u32 s10, s12, 0x80
	v_ashrrev_i32_e32 v4, 6, v2
	v_writelane_b32 v254, s3, 55
	v_lshlrev_b32_e32 v3, 2, v3
	s_addc_u32 s11, s13, 0
	s_add_i32 s67, s54, 0x1c000
	s_mov_b32 m0, s67
	s_nop 0
	global_load_lds_dwordx4 v0, s[8:9]
	v_lshl_add_u32 v7, v4, 10, s3
	v_and_b32_e32 v3, 32, v3
	v_writelane_b32 v254, s26, 61
	v_lshlrev_b32_e32 v2, 2, v2
	s_add_i32 s68, s54, 0x1e000
	s_mov_b32 m0, s68
	s_nop 0
	global_load_lds_dwordx4 v0, s[10:11]
	v_mov_b32_e32 v120, 0
	v_bitop3_b32 v151, v5, v7, v3 bitop3:0xde
	v_lshl_or_b32 v1, v1, 6, v6
	v_add_lshl_u32 v3, v4, s26, 10
	v_and_b32_e32 v2, 32, v2
	s_waitcnt vmcnt(6)
	s_add_i32 s69, s54, 0xc000
	s_add_i32 s70, s54, 0xe000
	v_readlane_b32 s2, v254, 0
	v_mov_b32_e32 v121, v120
	v_mov_b32_e32 v122, v120
	v_mov_b32_e32 v123, v120
	v_mov_b32_e32 v129, v0
	v_bitop3_b32 v152, v1, v3, v2 bitop3:0xde
	s_cmpk_lt_u32 s2, 0x100
	v_mov_b64_e32 v[126:127], v[122:123]
	v_mov_b64_e32 v[116:117], v[120:121]
	v_mov_b64_e32 v[108:109], v[120:121]
	v_mov_b64_e32 v[100:101], v[120:121]
	v_mov_b64_e32 v[92:93], v[120:121]
	v_mov_b64_e32 v[84:85], v[120:121]
	v_mov_b64_e32 v[76:77], v[120:121]
	v_mov_b64_e32 v[72:73], v[120:121]
	v_mov_b64_e32 v[64:65], v[120:121]
	v_mov_b64_e32 v[56:57], v[120:121]
	v_mov_b64_e32 v[44:45], v[120:121]
	v_mov_b64_e32 v[36:37], v[120:121]
	v_mov_b64_e32 v[28:29], v[120:121]
	v_mov_b64_e32 v[20:21], v[120:121]
	v_mov_b64_e32 v[12:13], v[120:121]
	v_mov_b64_e32 v[112:113], v[120:121]
	v_mov_b64_e32 v[104:105], v[120:121]
	v_mov_b64_e32 v[96:97], v[120:121]
	v_mov_b64_e32 v[88:89], v[120:121]
	v_mov_b64_e32 v[80:81], v[120:121]
	v_mov_b64_e32 v[68:69], v[120:121]
	v_mov_b64_e32 v[60:61], v[120:121]
	v_mov_b64_e32 v[52:53], v[120:121]
	v_mov_b64_e32 v[48:49], v[120:121]
	v_mov_b64_e32 v[40:41], v[120:121]
	v_mov_b64_e32 v[32:33], v[120:121]
	v_mov_b64_e32 v[24:25], v[120:121]
	v_mov_b64_e32 v[16:17], v[120:121]
	v_mov_b64_e32 v[8:9], v[120:121]
	v_mov_b64_e32 v[4:5], v[120:121]
	v_mov_b64_e32 v[0:1], v[120:121]
	s_cselect_b64 s[22:23], -1, 0
	s_add_i32 s71, s52, 0x80
	s_add_i32 s72, s52, 0xa0
	s_mov_b32 s25, 0
	v_mov_b64_e32 v[124:125], v[120:121]
	v_mov_b64_e32 v[118:119], v[122:123]
	v_mov_b64_e32 v[110:111], v[122:123]
	v_mov_b64_e32 v[102:103], v[122:123]
	v_mov_b64_e32 v[94:95], v[122:123]
	v_mov_b64_e32 v[86:87], v[122:123]
	v_mov_b64_e32 v[78:79], v[122:123]
	v_mov_b64_e32 v[74:75], v[122:123]
	v_mov_b64_e32 v[66:67], v[122:123]
	v_mov_b64_e32 v[58:59], v[122:123]
	v_mov_b64_e32 v[46:47], v[122:123]
	v_mov_b64_e32 v[38:39], v[122:123]
	v_mov_b64_e32 v[30:31], v[122:123]
	v_mov_b64_e32 v[22:23], v[122:123]
	v_mov_b64_e32 v[14:15], v[122:123]
	v_mov_b64_e32 v[114:115], v[122:123]
	v_mov_b64_e32 v[106:107], v[122:123]
	v_mov_b64_e32 v[98:99], v[122:123]
	v_mov_b64_e32 v[90:91], v[122:123]
	v_mov_b64_e32 v[82:83], v[122:123]
	v_mov_b64_e32 v[70:71], v[122:123]
	v_mov_b64_e32 v[62:63], v[122:123]
	v_mov_b64_e32 v[54:55], v[122:123]
	v_mov_b64_e32 v[50:51], v[122:123]
	v_mov_b64_e32 v[42:43], v[122:123]
	v_mov_b64_e32 v[34:35], v[122:123]
	v_mov_b64_e32 v[26:27], v[122:123]
	v_mov_b64_e32 v[18:19], v[122:123]
	v_mov_b64_e32 v[10:11], v[122:123]
	v_mov_b64_e32 v[6:7], v[122:123]
	v_mov_b64_e32 v[2:3], v[122:123]
	s_mov_b32 s36, s31
	s_mov_b32 s31, 0
	s_barrier
	s_branch .LBB0_446

.LBB0_450:
	v_add_u32_e32 v153, 0, v152
	v_add_u32_e32 v142, 0x10000, v153
	v_add_u32_e32 v162, 0x14000, v153
	ds_read_b128 v[130:133], v142
	ds_read_b128 v[134:137], v142 offset:1024
	ds_read_b128 v[138:141], v142 offset:2048
	ds_read_b128 v[142:145], v142 offset:3072
	ds_read_b128 v[146:149], v162
	ds_read_b128 v[154:157], v162 offset:1024
	ds_read_b128 v[158:161], v162 offset:2048
	ds_read_b128 v[162:165], v162 offset:3072
	s_add_i32 s82, s82, 2
	s_add_u32 s83, s4, s40
	s_addc_u32 s84, s5, s41
	s_add_u32 s42, s83, 0x100
	s_addc_u32 s43, s84, 0
	v_add_u32_e32 v198, 0, v151
	s_add_u32 s85, s24, s40
	ds_read_b128 v[166:169], v198
	ds_read_b128 v[170:173], v198 offset:1024
	ds_read_b128 v[174:177], v198 offset:2048
	ds_read_b128 v[178:181], v198 offset:3072
	ds_read_b128 v[182:185], v198 offset:4096
	ds_read_b128 v[186:189], v198 offset:5120
	ds_read_b128 v[190:193], v198 offset:6144
	ds_read_b128 v[194:197], v198 offset:7168
	s_addc_u32 s90, s45, s41
	s_add_u32 s86, s85, 0x80
	s_addc_u32 s87, s90, 0
	s_add_u32 s91, s78, s40
	s_addc_u32 s92, s79, s41
	s_add_u32 s88, s91, 0x80
	s_mov_b32 m0, s69
	s_nop 0
	global_load_lds_dwordx4 v128, s[86:87]
	s_addc_u32 s89, s92, 0
	s_mov_b32 m0, s70
	s_nop 0
	global_load_lds_dwordx4 v128, s[88:89]
	s_waitcnt vmcnt(8)
	s_waitcnt lgkmcnt(0)
	s_barrier
	s_waitcnt lgkmcnt(7)
	v_mfma_f32_16x16x32_bf16 v[0:3], v[130:133], v[166:169], v[0:3]
	v_mfma_f32_16x16x32_bf16 v[4:7], v[138:141], v[166:169], v[4:7]
	s_waitcnt lgkmcnt(5)
	v_mfma_f32_16x16x32_bf16 v[8:11], v[130:133], v[174:177], v[8:11]
	v_mfma_f32_16x16x32_bf16 v[16:19], v[138:141], v[174:177], v[16:19]
	s_waitcnt lgkmcnt(3)
	v_mfma_f32_16x16x32_bf16 v[24:27], v[130:133], v[182:185], v[24:27]
	v_mfma_f32_16x16x32_bf16 v[32:35], v[138:141], v[182:185], v[32:35]
	s_waitcnt lgkmcnt(1)
	v_mfma_f32_16x16x32_bf16 v[40:43], v[130:133], v[190:193], v[40:43]
	v_mfma_f32_16x16x32_bf16 v[48:51], v[138:141], v[190:193], v[48:51]
	v_mfma_f32_16x16x32_bf16 v[0:3], v[134:137], v[170:173], v[0:3]
	v_mfma_f32_16x16x32_bf16 v[4:7], v[142:145], v[170:173], v[4:7]
	v_mfma_f32_16x16x32_bf16 v[8:11], v[134:137], v[178:181], v[8:11]
	v_mfma_f32_16x16x32_bf16 v[16:19], v[142:145], v[178:181], v[16:19]
	v_mfma_f32_16x16x32_bf16 v[24:27], v[134:137], v[186:189], v[24:27]
	v_mfma_f32_16x16x32_bf16 v[32:35], v[142:145], v[186:189], v[32:35]
	s_waitcnt lgkmcnt(0)
	v_mfma_f32_16x16x32_bf16 v[40:43], v[134:137], v[194:197], v[40:43]
	v_mfma_f32_16x16x32_bf16 v[48:51], v[142:145], v[194:197], v[48:51]
	v_mfma_f32_16x16x32_bf16 v[52:55], v[146:149], v[166:169], v[52:55]
	v_mfma_f32_16x16x32_bf16 v[60:63], v[158:161], v[166:169], v[60:63]
	v_mfma_f32_16x16x32_bf16 v[68:71], v[146:149], v[174:177], v[68:71]
	v_mfma_f32_16x16x32_bf16 v[80:83], v[158:161], v[174:177], v[80:83]
	v_mfma_f32_16x16x32_bf16 v[88:91], v[146:149], v[182:185], v[88:91]
	v_mfma_f32_16x16x32_bf16 v[96:99], v[158:161], v[182:185], v[96:99]
	v_mfma_f32_16x16x32_bf16 v[104:107], v[146:149], v[190:193], v[104:107]
	v_mfma_f32_16x16x32_bf16 v[112:115], v[158:161], v[190:193], v[112:115]
	v_mfma_f32_16x16x32_bf16 v[52:55], v[154:157], v[170:173], v[52:55]
	v_mfma_f32_16x16x32_bf16 v[60:63], v[162:165], v[170:173], v[60:63]
	v_mfma_f32_16x16x32_bf16 v[68:71], v[154:157], v[178:181], v[68:71]
	v_mfma_f32_16x16x32_bf16 v[80:83], v[162:165], v[178:181], v[80:83]
	v_mfma_f32_16x16x32_bf16 v[88:91], v[154:157], v[186:189], v[88:91]
	v_mfma_f32_16x16x32_bf16 v[96:99], v[162:165], v[186:189], v[96:99]
	v_mfma_f32_16x16x32_bf16 v[104:107], v[154:157], v[194:197], v[104:107]
	v_mfma_f32_16x16x32_bf16 v[112:115], v[162:165], v[194:197], v[112:115]
	s_barrier
	s_add_u32 s93, s6, s40
	s_addc_u32 s94, s7, s41
	s_add_u32 s86, s93, 0x100
	s_addc_u32 s87, s94, 0
	s_add_u32 s95, s75, s40
	s_addc_u32 s96, s77, s41
	s_add_u32 s88, s95, 0x100
	ds_read_b128 v[166:169], v198 offset:16384
	ds_read_b128 v[170:173], v198 offset:17408
	ds_read_b128 v[174:177], v198 offset:18432
	ds_read_b128 v[178:181], v198 offset:19456
	ds_read_b128 v[182:185], v198 offset:20480
	ds_read_b128 v[186:189], v198 offset:21504
	ds_read_b128 v[190:193], v198 offset:22528
	ds_read_b128 v[194:197], v198 offset:23552
	s_addc_u32 s89, s96, 0
	s_mov_b32 m0, s56
	s_nop 0
	global_load_lds_dwordx4 v129, s[86:87]
	s_add_u32 s97, s46, s40
	s_mov_b32 m0, s57
	s_nop 0
	global_load_lds_dwordx4 v129, s[88:89]
	s_addc_u32 vcc_lo, s47, s41
	s_add_u32 s86, s97, 0x100
	s_addc_u32 s87, vcc_lo, 0
	s_add_u32 vcc_hi, s73, s40
	s_addc_u32 s2, s74, s41
	s_add_u32 s88, vcc_hi, 0x100
	s_mov_b32 m0, s58
	s_nop 0
	global_load_lds_dwordx4 v129, s[86:87]
	s_addc_u32 s89, s2, 0
	s_mov_b32 m0, s59
	s_nop 0
	global_load_lds_dwordx4 v129, s[88:89]
	s_add_u32 s3, s80, s40
	s_addc_u32 s88, s81, s41
	s_add_u32 s86, s3, 0x100
	s_mov_b32 m0, s54
	s_nop 0
	global_load_lds_dwordx4 v128, s[42:43]
	s_addc_u32 s87, s88, 0
	s_mov_b32 m0, s60
	s_nop 0
	global_load_lds_dwordx4 v128, s[86:87]
	s_waitcnt vmcnt(8)
	s_waitcnt lgkmcnt(0)
	s_barrier
	s_waitcnt lgkmcnt(7)
	v_mfma_f32_16x16x32_bf16 v[12:15], v[130:133], v[166:169], v[12:15]
	v_mfma_f32_16x16x32_bf16 v[20:23], v[138:141], v[166:169], v[20:23]
	s_waitcnt lgkmcnt(5)
	v_mfma_f32_16x16x32_bf16 v[28:31], v[130:133], v[174:177], v[28:31]
	v_mfma_f32_16x16x32_bf16 v[36:39], v[138:141], v[174:177], v[36:39]
	s_waitcnt lgkmcnt(3)
	v_mfma_f32_16x16x32_bf16 v[44:47], v[130:133], v[182:185], v[44:47]
	v_mfma_f32_16x16x32_bf16 v[56:59], v[138:141], v[182:185], v[56:59]
	s_waitcnt lgkmcnt(1)
	v_mfma_f32_16x16x32_bf16 v[64:67], v[130:133], v[190:193], v[64:67]
	v_mfma_f32_16x16x32_bf16 v[72:75], v[138:141], v[190:193], v[72:75]
	v_mfma_f32_16x16x32_bf16 v[12:15], v[134:137], v[170:173], v[12:15]
	v_mfma_f32_16x16x32_bf16 v[20:23], v[142:145], v[170:173], v[20:23]
	v_mfma_f32_16x16x32_bf16 v[28:31], v[134:137], v[178:181], v[28:31]
	v_mfma_f32_16x16x32_bf16 v[36:39], v[142:145], v[178:181], v[36:39]
	v_mfma_f32_16x16x32_bf16 v[44:47], v[134:137], v[186:189], v[44:47]
	v_mfma_f32_16x16x32_bf16 v[56:59], v[142:145], v[186:189], v[56:59]
	s_waitcnt lgkmcnt(0)
	v_mfma_f32_16x16x32_bf16 v[64:67], v[134:137], v[194:197], v[64:67]
	v_mfma_f32_16x16x32_bf16 v[72:75], v[142:145], v[194:197], v[72:75]
	v_mfma_f32_16x16x32_bf16 v[76:79], v[146:149], v[166:169], v[76:79]
	v_mfma_f32_16x16x32_bf16 v[84:87], v[158:161], v[166:169], v[84:87]
	v_mfma_f32_16x16x32_bf16 v[92:95], v[146:149], v[174:177], v[92:95]
	v_mfma_f32_16x16x32_bf16 v[100:103], v[158:161], v[174:177], v[100:103]
	v_mfma_f32_16x16x32_bf16 v[108:111], v[146:149], v[182:185], v[108:111]
	v_mfma_f32_16x16x32_bf16 v[116:119], v[158:161], v[182:185], v[116:119]
	v_mfma_f32_16x16x32_bf16 v[124:127], v[146:149], v[190:193], v[124:127]
	v_mfma_f32_16x16x32_bf16 v[120:123], v[158:161], v[190:193], v[120:123]
	v_mfma_f32_16x16x32_bf16 v[76:79], v[154:157], v[170:173], v[76:79]
	v_mfma_f32_16x16x32_bf16 v[84:87], v[162:165], v[170:173], v[84:87]
	v_mfma_f32_16x16x32_bf16 v[92:95], v[154:157], v[178:181], v[92:95]
	v_mfma_f32_16x16x32_bf16 v[100:103], v[162:165], v[178:181], v[100:103]
	v_mfma_f32_16x16x32_bf16 v[108:111], v[154:157], v[186:189], v[108:111]
	v_mfma_f32_16x16x32_bf16 v[116:119], v[162:165], v[186:189], v[116:119]
	v_mfma_f32_16x16x32_bf16 v[124:127], v[154:157], v[194:197], v[124:127]
	v_mfma_f32_16x16x32_bf16 v[120:123], v[162:165], v[194:197], v[120:123]
	s_barrier
	v_add_u32_e32 v142, 0x18000, v153
	v_add_u32_e32 v153, 0x1c000, v153
	ds_read_b128 v[130:133], v142
	ds_read_b128 v[134:137], v142 offset:1024
	ds_read_b128 v[138:141], v142 offset:2048
	ds_read_b128 v[142:145], v142 offset:3072
	ds_read_b128 v[146:149], v153
	ds_read_b128 v[154:157], v153 offset:1024
	ds_read_b128 v[158:161], v153 offset:2048
	ds_read_b128 v[162:165], v153 offset:3072
	ds_read_b128 v[166:169], v198 offset:32768
	ds_read_b128 v[170:173], v198 offset:33792
	ds_read_b128 v[174:177], v198 offset:34816
	ds_read_b128 v[178:181], v198 offset:35840
	ds_read_b128 v[182:185], v198 offset:36864
	ds_read_b128 v[186:189], v198 offset:37888
	ds_read_b128 v[190:193], v198 offset:38912
	ds_read_b128 v[194:197], v198 offset:39936
	s_add_u32 s42, s85, 0x100
	s_addc_u32 s43, s90, 0
	s_add_u32 s86, s91, 0x100
	s_mov_b32 m0, s61
	s_nop 0
	global_load_lds_dwordx4 v128, s[42:43]
	s_addc_u32 s87, s92, 0
	s_mov_b32 m0, s62
	s_nop 0
	global_load_lds_dwordx4 v128, s[86:87]
	s_waitcnt vmcnt(8)
	s_waitcnt lgkmcnt(0)
	s_barrier
	s_waitcnt lgkmcnt(7)
	v_mfma_f32_16x16x32_bf16 v[0:3], v[130:133], v[166:169], v[0:3]
	v_mfma_f32_16x16x32_bf16 v[4:7], v[138:141], v[166:169], v[4:7]
	s_waitcnt lgkmcnt(5)
	v_mfma_f32_16x16x32_bf16 v[8:11], v[130:133], v[174:177], v[8:11]
	v_mfma_f32_16x16x32_bf16 v[16:19], v[138:141], v[174:177], v[16:19]
	s_waitcnt lgkmcnt(3)
	v_mfma_f32_16x16x32_bf16 v[24:27], v[130:133], v[182:185], v[24:27]
	v_mfma_f32_16x16x32_bf16 v[32:35], v[138:141], v[182:185], v[32:35]
	s_waitcnt lgkmcnt(1)
	v_mfma_f32_16x16x32_bf16 v[40:43], v[130:133], v[190:193], v[40:43]
	v_mfma_f32_16x16x32_bf16 v[48:51], v[138:141], v[190:193], v[48:51]
	v_mfma_f32_16x16x32_bf16 v[0:3], v[134:137], v[170:173], v[0:3]
	v_mfma_f32_16x16x32_bf16 v[4:7], v[142:145], v[170:173], v[4:7]
	v_mfma_f32_16x16x32_bf16 v[8:11], v[134:137], v[178:181], v[8:11]
	v_mfma_f32_16x16x32_bf16 v[16:19], v[142:145], v[178:181], v[16:19]
	v_mfma_f32_16x16x32_bf16 v[24:27], v[134:137], v[186:189], v[24:27]
	v_mfma_f32_16x16x32_bf16 v[32:35], v[142:145], v[186:189], v[32:35]
	s_waitcnt lgkmcnt(0)
	v_mfma_f32_16x16x32_bf16 v[40:43], v[134:137], v[194:197], v[40:43]
	v_mfma_f32_16x16x32_bf16 v[48:51], v[142:145], v[194:197], v[48:51]
	v_mfma_f32_16x16x32_bf16 v[52:55], v[146:149], v[166:169], v[52:55]
	v_mfma_f32_16x16x32_bf16 v[60:63], v[158:161], v[166:169], v[60:63]
	v_mfma_f32_16x16x32_bf16 v[68:71], v[146:149], v[174:177], v[68:71]
	v_mfma_f32_16x16x32_bf16 v[80:83], v[158:161], v[174:177], v[80:83]
	v_mfma_f32_16x16x32_bf16 v[88:91], v[146:149], v[182:185], v[88:91]
	v_mfma_f32_16x16x32_bf16 v[96:99], v[158:161], v[182:185], v[96:99]
	v_mfma_f32_16x16x32_bf16 v[104:107], v[146:149], v[190:193], v[104:107]
	v_mfma_f32_16x16x32_bf16 v[112:115], v[158:161], v[190:193], v[112:115]
	v_mfma_f32_16x16x32_bf16 v[52:55], v[154:157], v[170:173], v[52:55]
	v_mfma_f32_16x16x32_bf16 v[60:63], v[162:165], v[170:173], v[60:63]
	v_mfma_f32_16x16x32_bf16 v[68:71], v[154:157], v[178:181], v[68:71]
	v_mfma_f32_16x16x32_bf16 v[80:83], v[162:165], v[178:181], v[80:83]
	v_mfma_f32_16x16x32_bf16 v[88:91], v[154:157], v[186:189], v[88:91]
	v_mfma_f32_16x16x32_bf16 v[96:99], v[162:165], v[186:189], v[96:99]
	v_mfma_f32_16x16x32_bf16 v[104:107], v[154:157], v[194:197], v[104:107]
	v_mfma_f32_16x16x32_bf16 v[112:115], v[162:165], v[194:197], v[112:115]
	s_barrier
	s_add_u32 s42, s93, 0x180
	s_addc_u32 s43, s94, 0
	ds_read_b128 v[166:169], v198 offset:49152
	ds_read_b128 v[170:173], v198 offset:50176
	ds_read_b128 v[174:177], v198 offset:51200
	ds_read_b128 v[178:181], v198 offset:52224
	ds_read_b128 v[182:185], v198 offset:53248
	ds_read_b128 v[186:189], v198 offset:54272
	ds_read_b128 v[190:193], v198 offset:55296
	ds_read_b128 v[194:197], v198 offset:56320
	s_add_u32 s86, s95, 0x180
	s_mov_b32 m0, s63
	s_nop 0
	global_load_lds_dwordx4 v129, s[42:43]
	s_addc_u32 s87, s96, 0
	s_mov_b32 m0, s64
	s_nop 0
	global_load_lds_dwordx4 v129, s[86:87]
	s_add_u32 s42, s97, 0x180
	s_addc_u32 s43, vcc_lo, 0
	s_add_u32 s86, vcc_hi, 0x180
	s_addc_u32 s87, s2, 0
	s_mov_b32 m0, s67
	s_nop 0
	global_load_lds_dwordx4 v129, s[42:43]
	s_add_u32 s42, s83, 0x180
	s_mov_b32 m0, s68
	s_nop 0
	global_load_lds_dwordx4 v129, s[86:87]
	s_addc_u32 s43, s84, 0
	s_add_u32 s84, s3, 0x180
	s_mov_b32 m0, s65
	s_nop 0
	global_load_lds_dwordx4 v128, s[42:43]
	s_addc_u32 s85, s88, 0
	s_mov_b32 m0, s66
	s_nop 0
	global_load_lds_dwordx4 v128, s[84:85]
	s_waitcnt vmcnt(8)
	s_waitcnt lgkmcnt(0)
	s_barrier
	s_waitcnt lgkmcnt(7)
	v_mfma_f32_16x16x32_bf16 v[12:15], v[130:133], v[166:169], v[12:15]
	v_mfma_f32_16x16x32_bf16 v[20:23], v[138:141], v[166:169], v[20:23]
	s_waitcnt lgkmcnt(5)
	v_mfma_f32_16x16x32_bf16 v[28:31], v[130:133], v[174:177], v[28:31]
	v_mfma_f32_16x16x32_bf16 v[36:39], v[138:141], v[174:177], v[36:39]
	s_waitcnt lgkmcnt(3)
	v_mfma_f32_16x16x32_bf16 v[44:47], v[130:133], v[182:185], v[44:47]
	v_mfma_f32_16x16x32_bf16 v[56:59], v[138:141], v[182:185], v[56:59]
	s_waitcnt lgkmcnt(1)
	v_mfma_f32_16x16x32_bf16 v[64:67], v[130:133], v[190:193], v[64:67]
	v_mfma_f32_16x16x32_bf16 v[72:75], v[138:141], v[190:193], v[72:75]
	v_mfma_f32_16x16x32_bf16 v[12:15], v[134:137], v[170:173], v[12:15]
	v_mfma_f32_16x16x32_bf16 v[20:23], v[142:145], v[170:173], v[20:23]
	v_mfma_f32_16x16x32_bf16 v[28:31], v[134:137], v[178:181], v[28:31]
	v_mfma_f32_16x16x32_bf16 v[36:39], v[142:145], v[178:181], v[36:39]
	v_mfma_f32_16x16x32_bf16 v[44:47], v[134:137], v[186:189], v[44:47]
	v_mfma_f32_16x16x32_bf16 v[56:59], v[142:145], v[186:189], v[56:59]
	s_waitcnt lgkmcnt(0)
	v_mfma_f32_16x16x32_bf16 v[64:67], v[134:137], v[194:197], v[64:67]
	v_mfma_f32_16x16x32_bf16 v[72:75], v[142:145], v[194:197], v[72:75]
	v_mfma_f32_16x16x32_bf16 v[76:79], v[146:149], v[166:169], v[76:79]
	v_mfma_f32_16x16x32_bf16 v[84:87], v[158:161], v[166:169], v[84:87]
	v_mfma_f32_16x16x32_bf16 v[92:95], v[146:149], v[174:177], v[92:95]
	v_mfma_f32_16x16x32_bf16 v[100:103], v[158:161], v[174:177], v[100:103]
	v_mfma_f32_16x16x32_bf16 v[108:111], v[146:149], v[182:185], v[108:111]
	v_mfma_f32_16x16x32_bf16 v[116:119], v[158:161], v[182:185], v[116:119]
	v_mfma_f32_16x16x32_bf16 v[124:127], v[146:149], v[190:193], v[124:127]
	v_mfma_f32_16x16x32_bf16 v[120:123], v[158:161], v[190:193], v[120:123]
	v_mfma_f32_16x16x32_bf16 v[76:79], v[154:157], v[170:173], v[76:79]
	v_mfma_f32_16x16x32_bf16 v[84:87], v[162:165], v[170:173], v[84:87]
	v_mfma_f32_16x16x32_bf16 v[92:95], v[154:157], v[178:181], v[92:95]
	v_mfma_f32_16x16x32_bf16 v[100:103], v[162:165], v[178:181], v[100:103]
	v_mfma_f32_16x16x32_bf16 v[108:111], v[154:157], v[186:189], v[108:111]
	v_mfma_f32_16x16x32_bf16 v[116:119], v[162:165], v[186:189], v[116:119]
	v_mfma_f32_16x16x32_bf16 v[124:127], v[154:157], v[194:197], v[124:127]
	v_mfma_f32_16x16x32_bf16 v[120:123], v[162:165], v[194:197], v[120:123]
	s_barrier
	s_add_u32 s40, s40, 0x100
	s_addc_u32 s41, s41, 0
	s_cmp_ge_i32 s82, s11
	s_cbranch_scc0 .LBB0_450

.LBB0_453:
	v_add_u32_e32 v129, 0, v152
	v_add_u32_e32 v142, 0x10000, v129
	v_add_u32_e32 v146, 0x14000, v129
	ds_read_b128 v[130:133], v142
	ds_read_b128 v[134:137], v142 offset:1024
	ds_read_b128 v[138:141], v142 offset:2048
	ds_read_b128 v[142:145], v142 offset:3072
	ds_read_b128 v[154:157], v146
	ds_read_b128 v[158:161], v146 offset:1024
	ds_read_b128 v[162:165], v146 offset:2048
	ds_read_b128 v[166:169], v146 offset:3072
	s_ashr_i32 s45, s44, 31
	s_lshl_b64 s[44:45], s[44:45], 7
	v_add_u32_e32 v146, 0, v151
	s_add_u32 s2, s4, s44
	ds_read_b128 v[170:173], v146
	ds_read_b128 v[174:177], v146 offset:1024
	ds_read_b128 v[178:181], v146 offset:2048
	ds_read_b128 v[182:185], v146 offset:3072
	ds_read_b128 v[186:189], v146 offset:4096
	ds_read_b128 v[190:193], v146 offset:5120
	ds_read_b128 v[194:197], v146 offset:6144
	ds_read_b128 v[198:201], v146 offset:7168
	s_addc_u32 s3, s5, s45
	s_add_u32 s2, s2, s50
	s_addc_u32 s3, s3, s51
	s_add_u32 s4, s2, 0xffffff80
	s_addc_u32 s5, s3, -1
	s_add_u32 s44, s4, s48
	s_mov_b32 m0, s69
	s_nop 0
	global_load_lds_dwordx4 v128, s[4:5]
	s_addc_u32 s45, s5, s49
	s_mov_b32 m0, s70
	s_nop 0
	global_load_lds_dwordx4 v128, s[44:45]
	s_waitcnt vmcnt(8)
	s_waitcnt lgkmcnt(0)
	s_barrier
	s_waitcnt lgkmcnt(7)
	v_mfma_f32_16x16x32_bf16 v[0:3], v[130:133], v[170:173], v[0:3]
	v_mfma_f32_16x16x32_bf16 v[4:7], v[138:141], v[170:173], v[4:7]
	s_waitcnt lgkmcnt(5)
	v_mfma_f32_16x16x32_bf16 v[8:11], v[130:133], v[178:181], v[8:11]
	v_mfma_f32_16x16x32_bf16 v[16:19], v[138:141], v[178:181], v[16:19]
	s_waitcnt lgkmcnt(3)
	v_mfma_f32_16x16x32_bf16 v[24:27], v[130:133], v[186:189], v[24:27]
	v_mfma_f32_16x16x32_bf16 v[32:35], v[138:141], v[186:189], v[32:35]
	s_waitcnt lgkmcnt(1)
	v_mfma_f32_16x16x32_bf16 v[40:43], v[130:133], v[194:197], v[40:43]
	v_mfma_f32_16x16x32_bf16 v[48:51], v[138:141], v[194:197], v[48:51]
	v_mfma_f32_16x16x32_bf16 v[0:3], v[134:137], v[174:177], v[0:3]
	v_mfma_f32_16x16x32_bf16 v[4:7], v[142:145], v[174:177], v[4:7]
	v_mfma_f32_16x16x32_bf16 v[8:11], v[134:137], v[182:185], v[8:11]
	v_mfma_f32_16x16x32_bf16 v[16:19], v[142:145], v[182:185], v[16:19]
	v_mfma_f32_16x16x32_bf16 v[24:27], v[134:137], v[190:193], v[24:27]
	v_mfma_f32_16x16x32_bf16 v[32:35], v[142:145], v[190:193], v[32:35]
	s_waitcnt lgkmcnt(0)
	v_mfma_f32_16x16x32_bf16 v[40:43], v[134:137], v[198:201], v[40:43]
	v_mfma_f32_16x16x32_bf16 v[48:51], v[142:145], v[198:201], v[48:51]
	v_mfma_f32_16x16x32_bf16 v[52:55], v[154:157], v[170:173], v[52:55]
	v_mfma_f32_16x16x32_bf16 v[60:63], v[162:165], v[170:173], v[60:63]
	v_mfma_f32_16x16x32_bf16 v[68:71], v[154:157], v[178:181], v[68:71]
	v_mfma_f32_16x16x32_bf16 v[52:55], v[158:161], v[174:177], v[52:55]
	v_mfma_f32_16x16x32_bf16 v[60:63], v[166:169], v[174:177], v[60:63]
	v_mfma_f32_16x16x32_bf16 v[68:71], v[158:161], v[182:185], v[68:71]
	v_mfma_f32_16x16x32_bf16 v[80:83], v[162:165], v[178:181], v[80:83]
	v_mfma_f32_16x16x32_bf16 v[88:91], v[154:157], v[186:189], v[88:91]
	v_mfma_f32_16x16x32_bf16 v[96:99], v[162:165], v[186:189], v[96:99]
	v_mfma_f32_16x16x32_bf16 v[104:107], v[154:157], v[194:197], v[104:107]
	v_mfma_f32_16x16x32_bf16 v[112:115], v[162:165], v[194:197], v[112:115]
	v_mfma_f32_16x16x32_bf16 v[80:83], v[166:169], v[182:185], v[80:83]
	v_mfma_f32_16x16x32_bf16 v[88:91], v[158:161], v[190:193], v[88:91]
	v_mfma_f32_16x16x32_bf16 v[96:99], v[166:169], v[190:193], v[96:99]
	v_mfma_f32_16x16x32_bf16 v[104:107], v[158:161], v[198:201], v[104:107]
	v_mfma_f32_16x16x32_bf16 v[112:115], v[166:169], v[198:201], v[112:115]
	s_barrier
	s_add_u32 s44, s6, s16
	ds_read_b128 v[170:173], v146 offset:16384
	ds_read_b128 v[174:177], v146 offset:17408
	ds_read_b128 v[178:181], v146 offset:18432
	ds_read_b128 v[182:185], v146 offset:19456
	ds_read_b128 v[186:189], v146 offset:20480
	ds_read_b128 v[190:193], v146 offset:21504
	ds_read_b128 v[194:197], v146 offset:22528
	ds_read_b128 v[198:201], v146 offset:23552
	s_addc_u32 s45, s7, s17
	s_mov_b32 m0, s56
	s_nop 0
	global_load_lds_dwordx4 v149, s[6:7]
	s_add_u32 s48, s6, s20
	s_mov_b32 m0, s57
	s_nop 0
	global_load_lds_dwordx4 v149, s[44:45]
	s_addc_u32 s49, s7, s21
	s_add_u32 s50, s48, s16
	s_mov_b32 m0, s58
	s_nop 0
	global_load_lds_dwordx4 v149, s[48:49]
	s_addc_u32 s51, s49, s17
	s_mov_b32 m0, s59
	s_nop 0
	global_load_lds_dwordx4 v149, s[50:51]
	s_add_u32 s4, s46, s42
	s_mov_b32 m0, s54
	s_nop 0
	global_load_lds_dwordx4 v148, s[46:47]
	s_addc_u32 s5, s47, s43
	s_mov_b32 m0, s60
	s_nop 0
	global_load_lds_dwordx4 v148, s[4:5]
	s_waitcnt vmcnt(8)
	s_waitcnt lgkmcnt(0)
	s_barrier
	s_waitcnt lgkmcnt(7)
	v_mfma_f32_16x16x32_bf16 v[12:15], v[130:133], v[170:173], v[12:15]
	s_waitcnt lgkmcnt(6)
	v_mfma_f32_16x16x32_bf16 v[202:205], v[134:137], v[174:177], v[12:15]
	v_mfma_f32_16x16x32_bf16 v[12:15], v[138:141], v[170:173], v[20:23]
	v_mfma_f32_16x16x32_bf16 v[206:209], v[142:145], v[174:177], v[12:15]
	s_waitcnt lgkmcnt(5)
	v_mfma_f32_16x16x32_bf16 v[12:15], v[130:133], v[178:181], v[28:31]
	s_waitcnt lgkmcnt(4)
	v_mfma_f32_16x16x32_bf16 v[210:213], v[134:137], v[182:185], v[12:15]
	v_mfma_f32_16x16x32_bf16 v[12:15], v[138:141], v[178:181], v[36:39]
	v_mfma_f32_16x16x32_bf16 v[214:217], v[142:145], v[182:185], v[12:15]
	s_waitcnt lgkmcnt(3)
	v_mfma_f32_16x16x32_bf16 v[12:15], v[130:133], v[186:189], v[44:47]
	s_waitcnt lgkmcnt(2)
	v_mfma_f32_16x16x32_bf16 v[218:221], v[134:137], v[190:193], v[12:15]
	v_mfma_f32_16x16x32_bf16 v[12:15], v[138:141], v[186:189], v[56:59]
	v_mfma_f32_16x16x32_bf16 v[56:59], v[142:145], v[190:193], v[12:15]
	s_waitcnt lgkmcnt(1)
	v_mfma_f32_16x16x32_bf16 v[12:15], v[130:133], v[194:197], v[64:67]
	s_waitcnt lgkmcnt(0)
	v_mfma_f32_16x16x32_bf16 v[64:67], v[134:137], v[198:201], v[12:15]
	v_mfma_f32_16x16x32_bf16 v[12:15], v[138:141], v[194:197], v[72:75]
	v_mfma_f32_16x16x32_bf16 v[72:75], v[142:145], v[198:201], v[12:15]
	v_mfma_f32_16x16x32_bf16 v[12:15], v[154:157], v[170:173], v[76:79]
	v_mfma_f32_16x16x32_bf16 v[76:79], v[158:161], v[174:177], v[12:15]
	v_mfma_f32_16x16x32_bf16 v[12:15], v[162:165], v[170:173], v[84:87]
	v_mfma_f32_16x16x32_bf16 v[84:87], v[166:169], v[174:177], v[12:15]
	v_mfma_f32_16x16x32_bf16 v[12:15], v[154:157], v[178:181], v[92:95]
	v_mfma_f32_16x16x32_bf16 v[92:95], v[158:161], v[182:185], v[12:15]
	v_mfma_f32_16x16x32_bf16 v[12:15], v[162:165], v[178:181], v[100:103]
	v_mfma_f32_16x16x32_bf16 v[100:103], v[166:169], v[182:185], v[12:15]
	v_mfma_f32_16x16x32_bf16 v[12:15], v[154:157], v[186:189], v[108:111]
	v_mfma_f32_16x16x32_bf16 v[108:111], v[158:161], v[190:193], v[12:15]
	v_mfma_f32_16x16x32_bf16 v[12:15], v[162:165], v[186:189], v[116:119]
	v_mfma_f32_16x16x32_bf16 v[116:119], v[166:169], v[190:193], v[12:15]
	v_mfma_f32_16x16x32_bf16 v[12:15], v[154:157], v[194:197], v[124:127]
	v_mfma_f32_16x16x32_bf16 v[124:127], v[158:161], v[198:201], v[12:15]
	v_mfma_f32_16x16x32_bf16 v[12:15], v[162:165], v[194:197], v[120:123]
	v_mfma_f32_16x16x32_bf16 v[120:123], v[166:169], v[198:201], v[12:15]
	s_barrier
	s_nop 4
	v_add_u32_e32 v12, 0x18000, v129
	ds_read_b128 v[154:157], v12
	ds_read_b128 v[158:161], v12 offset:1024
	ds_read_b128 v[162:165], v12 offset:2048
	ds_read_b128 v[166:169], v12 offset:3072
	v_add_u32_e32 v12, 0x1c000, v129
	ds_read_b128 v[170:173], v12
	ds_read_b128 v[174:177], v12 offset:1024
	ds_read_b128 v[178:181], v12 offset:2048
	ds_read_b128 v[182:185], v12 offset:3072
	ds_read_b128 v[12:15], v146 offset:32768
	ds_read_b128 v[20:23], v146 offset:33792
	ds_read_b128 v[28:31], v146 offset:34816
	ds_read_b128 v[36:39], v146 offset:35840
	ds_read_b128 v[128:131], v146 offset:36864
	ds_read_b128 v[132:135], v146 offset:37888
	ds_read_b128 v[136:139], v146 offset:38912
	ds_read_b128 v[140:143], v146 offset:39936
	s_add_u32 s74, s46, s40
	s_addc_u32 s75, s47, s41
	s_add_u32 s78, s74, s42
	s_mov_b32 m0, s61
	s_nop 0
	global_load_lds_dwordx4 v148, s[74:75]
	s_addc_u32 s79, s75, s43
	s_mov_b32 m0, s62
	s_nop 0
	global_load_lds_dwordx4 v148, s[78:79]
	s_waitcnt vmcnt(8)
	s_waitcnt lgkmcnt(0)
	s_barrier
	s_waitcnt lgkmcnt(7)
	v_mfma_f32_16x16x32_bf16 v[0:3], v[154:157], v[12:15], v[0:3]
	v_mfma_f32_16x16x32_bf16 v[4:7], v[162:165], v[12:15], v[4:7]
	s_waitcnt lgkmcnt(5)
	v_mfma_f32_16x16x32_bf16 v[8:11], v[154:157], v[28:31], v[8:11]
	v_mfma_f32_16x16x32_bf16 v[16:19], v[162:165], v[28:31], v[16:19]
	s_waitcnt lgkmcnt(3)
	v_mfma_f32_16x16x32_bf16 v[24:27], v[154:157], v[128:131], v[24:27]
	v_mfma_f32_16x16x32_bf16 v[32:35], v[162:165], v[128:131], v[32:35]
	s_waitcnt lgkmcnt(1)
	v_mfma_f32_16x16x32_bf16 v[40:43], v[154:157], v[136:139], v[40:43]
	v_mfma_f32_16x16x32_bf16 v[44:47], v[162:165], v[136:139], v[48:51]
	v_mfma_f32_16x16x32_bf16 v[0:3], v[158:161], v[20:23], v[0:3]
	v_mfma_f32_16x16x32_bf16 v[4:7], v[166:169], v[20:23], v[4:7]
	v_mfma_f32_16x16x32_bf16 v[8:11], v[158:161], v[36:39], v[8:11]
	v_mfma_f32_16x16x32_bf16 v[16:19], v[166:169], v[36:39], v[16:19]
	v_mfma_f32_16x16x32_bf16 v[24:27], v[158:161], v[132:135], v[24:27]
	v_mfma_f32_16x16x32_bf16 v[32:35], v[166:169], v[132:135], v[32:35]
	s_waitcnt lgkmcnt(0)
	v_mfma_f32_16x16x32_bf16 v[40:43], v[158:161], v[140:143], v[40:43]
	v_mfma_f32_16x16x32_bf16 v[48:51], v[166:169], v[140:143], v[44:47]
	v_mfma_f32_16x16x32_bf16 v[44:47], v[170:173], v[12:15], v[52:55]
	v_mfma_f32_16x16x32_bf16 v[12:15], v[178:181], v[12:15], v[60:63]
	v_mfma_f32_16x16x32_bf16 v[60:63], v[182:185], v[20:23], v[12:15]
	v_mfma_f32_16x16x32_bf16 v[12:15], v[170:173], v[28:31], v[68:71]
	v_mfma_f32_16x16x32_bf16 v[68:71], v[174:177], v[36:39], v[12:15]
	v_mfma_f32_16x16x32_bf16 v[12:15], v[178:181], v[28:31], v[80:83]
	v_mfma_f32_16x16x32_bf16 v[52:55], v[174:177], v[20:23], v[44:47]
	v_mfma_f32_16x16x32_bf16 v[44:47], v[182:185], v[36:39], v[12:15]
	v_mfma_f32_16x16x32_bf16 v[12:15], v[170:173], v[128:131], v[88:91]
	v_mfma_f32_16x16x32_bf16 v[36:39], v[174:177], v[132:135], v[12:15]
	v_mfma_f32_16x16x32_bf16 v[12:15], v[178:181], v[128:131], v[96:99]
	v_mfma_f32_16x16x32_bf16 v[28:31], v[182:185], v[132:135], v[12:15]
	v_mfma_f32_16x16x32_bf16 v[12:15], v[170:173], v[136:139], v[104:107]
	v_mfma_f32_16x16x32_bf16 v[20:23], v[174:177], v[140:143], v[12:15]
	v_mfma_f32_16x16x32_bf16 v[12:15], v[178:181], v[136:139], v[112:115]
	v_mfma_f32_16x16x32_bf16 v[12:15], v[182:185], v[140:143], v[12:15]
	s_barrier
	s_add_u32 s74, s6, 0x80
	s_addc_u32 s75, s7, 0
	s_add_u32 s44, s44, 0x80
	ds_read_b128 v[80:83], v146 offset:49152
	ds_read_b128 v[88:91], v146 offset:50176
	ds_read_b128 v[96:99], v146 offset:51200
	ds_read_b128 v[104:107], v146 offset:52224
	ds_read_b128 v[112:115], v146 offset:53248
	ds_read_b128 v[186:189], v146 offset:54272
	ds_read_b128 v[190:193], v146 offset:55296
	ds_read_b128 v[194:197], v146 offset:56320
	s_addc_u32 s45, s45, 0
	s_mov_b32 m0, s63
	s_nop 0
	global_load_lds_dwordx4 v149, s[74:75]
	s_nop 0
	s_mov_b32 m0, s64
	s_nop 0
	global_load_lds_dwordx4 v149, s[44:45]
	s_add_u32 s44, s48, 0x80
	s_addc_u32 s45, s49, 0
	s_add_u32 s48, s50, 0x80
	s_addc_u32 s49, s51, 0
	s_mov_b32 m0, s67
	s_nop 0
	global_load_lds_dwordx4 v149, s[44:45]
	s_add_u32 s44, s46, 0x80
	s_mov_b32 m0, s68
	s_nop 0
	global_load_lds_dwordx4 v149, s[48:49]
	s_addc_u32 s45, s47, 0
	s_add_u32 s4, s4, 0x80
	s_mov_b32 m0, s65
	s_nop 0
	global_load_lds_dwordx4 v148, s[44:45]
	s_addc_u32 s5, s5, 0
	s_mov_b32 m0, s66
	s_nop 0
	global_load_lds_dwordx4 v148, s[4:5]
	s_waitcnt vmcnt(8)
	s_waitcnt lgkmcnt(0)
	s_barrier
	s_waitcnt lgkmcnt(7)
	v_mfma_f32_16x16x32_bf16 v[128:131], v[154:157], v[80:83], v[202:205]
	s_waitcnt lgkmcnt(6)
	v_mfma_f32_16x16x32_bf16 v[144:147], v[158:161], v[88:91], v[128:131]
	v_mfma_f32_16x16x32_bf16 v[128:131], v[162:165], v[80:83], v[206:209]
	v_mfma_f32_16x16x32_bf16 v[140:143], v[166:169], v[88:91], v[128:131]
	s_waitcnt lgkmcnt(5)
	v_mfma_f32_16x16x32_bf16 v[128:131], v[154:157], v[96:99], v[210:213]
	s_waitcnt lgkmcnt(4)
	v_mfma_f32_16x16x32_bf16 v[136:139], v[158:161], v[104:107], v[128:131]
	v_mfma_f32_16x16x32_bf16 v[128:131], v[162:165], v[96:99], v[214:217]
	v_mfma_f32_16x16x32_bf16 v[132:135], v[166:169], v[104:107], v[128:131]
	s_waitcnt lgkmcnt(3)
	v_mfma_f32_16x16x32_bf16 v[128:131], v[154:157], v[112:115], v[218:221]
	v_mfma_f32_16x16x32_bf16 v[56:59], v[162:165], v[112:115], v[56:59]
	s_waitcnt lgkmcnt(1)
	v_mfma_f32_16x16x32_bf16 v[64:67], v[154:157], v[190:193], v[64:67]
	v_mfma_f32_16x16x32_bf16 v[72:75], v[162:165], v[190:193], v[72:75]
	v_mfma_f32_16x16x32_bf16 v[128:131], v[158:161], v[186:189], v[128:131]
	v_mfma_f32_16x16x32_bf16 v[56:59], v[166:169], v[186:189], v[56:59]
	s_waitcnt lgkmcnt(0)
	v_mfma_f32_16x16x32_bf16 v[64:67], v[158:161], v[194:197], v[64:67]
	v_mfma_f32_16x16x32_bf16 v[72:75], v[166:169], v[194:197], v[72:75]
	v_mfma_f32_16x16x32_bf16 v[76:79], v[170:173], v[80:83], v[76:79]
	v_mfma_f32_16x16x32_bf16 v[80:83], v[178:181], v[80:83], v[84:87]
	v_mfma_f32_16x16x32_bf16 v[84:87], v[182:185], v[88:91], v[80:83]
	v_mfma_f32_16x16x32_bf16 v[80:83], v[170:173], v[96:99], v[92:95]
	v_mfma_f32_16x16x32_bf16 v[92:95], v[174:177], v[104:107], v[80:83]
	v_mfma_f32_16x16x32_bf16 v[80:83], v[178:181], v[96:99], v[100:103]
	v_mfma_f32_16x16x32_bf16 v[100:103], v[182:185], v[104:107], v[80:83]
	v_mfma_f32_16x16x32_bf16 v[80:83], v[170:173], v[112:115], v[108:111]
	v_mfma_f32_16x16x32_bf16 v[108:111], v[174:177], v[186:189], v[80:83]
	v_mfma_f32_16x16x32_bf16 v[80:83], v[178:181], v[112:115], v[116:119]
	v_mfma_f32_16x16x32_bf16 v[116:119], v[182:185], v[186:189], v[80:83]
	v_mfma_f32_16x16x32_bf16 v[80:83], v[170:173], v[190:193], v[124:127]
	v_mfma_f32_16x16x32_bf16 v[124:127], v[174:177], v[194:197], v[80:83]
	v_mfma_f32_16x16x32_bf16 v[80:83], v[178:181], v[190:193], v[120:123]
	v_mfma_f32_16x16x32_bf16 v[76:79], v[174:177], v[88:91], v[76:79]
	v_mfma_f32_16x16x32_bf16 v[120:123], v[182:185], v[194:197], v[80:83]
	s_barrier
	s_andn2_b64 vcc, exec, s[22:23]
	s_cbranch_vccnz .LBB0_455
	s_barrier

.LBB0_462:
	v_and_b32_e32 v1, 15, v2
	v_or_b32_e32 v3, s52, v1
	s_lshl_b64 s[38:39], s[16:17], 7
	s_lshl_b64 s[22:23], s[14:15], 7
	v_lshlrev_b32_e32 v5, 6, v3
	v_and_b32_e32 v6, 48, v2
	s_movk_i32 s2, 0x3c0
	v_ashrrev_i32_e32 v4, 6, v2
	v_and_or_b32 v5, v5, s2, v6
	s_add_u32 s2, s6, 0x80
	v_lshl_add_u32 v7, v4, 10, s3
	s_addc_u32 s3, s7, 0
	s_sub_u32 s14, 0, s18
	s_subb_u32 s15, 0, s19
	s_add_u32 s14, s8, s14
	s_addc_u32 s15, s9, s15
	s_add_u32 s14, s14, 0x80
	s_mov_b32 s98, 0
	s_cselect_b32 s99, 1, 0
	s_cmp_lt_u32 s76, 4
	s_cbranch_scc0 .Lsprio_6
	s_setprio 1
.Lsprio_6:
	s_cmp_lg_u32 s99, 0
	s_waitcnt vmcnt(2)
	s_barrier
	s_addc_u32 s15, s15, 0
	s_add_i32 s61, s54, 0x18000
	s_mov_b32 m0, s61
	s_nop 0
	global_load_lds_dwordx4 v0, s[2:3]
	s_add_i32 s62, s54, 0x1a000
	s_mov_b32 m0, s62
	s_nop 0
	global_load_lds_dwordx4 v0, s[14:15]
	s_add_u32 s2, s4, 0x80
	s_addc_u32 s3, s5, 0
	s_sub_u32 s14, 0, s36
	s_subb_u32 s15, 0, s37
	s_add_u32 s12, s12, s14
	s_addc_u32 s13, s13, s15
	s_add_u32 s12, s12, 0x80
	s_addc_u32 s13, s13, 0
	s_add_i32 s63, s54, 0x8000
	s_mov_b32 m0, s63
	s_nop 0
	global_load_lds_dwordx4 v160, s[2:3]
	s_add_i32 s64, s54, 0xa000
	s_mov_b32 m0, s64
	s_nop 0
	global_load_lds_dwordx4 v160, s[12:13]
	s_add_u32 s2, s8, 0x80
	s_addc_u32 s3, s9, 0
	s_add_u32 s8, s10, 0x80
	v_lshlrev_b32_e32 v2, 2, v2
	s_addc_u32 s9, s11, 0
	s_add_i32 s65, s54, 0x1c000
	s_mov_b32 m0, s65
	s_nop 0
	global_load_lds_dwordx4 v0, s[2:3]
	v_lshlrev_b32_e32 v3, 2, v3
	v_lshl_or_b32 v1, v1, 6, v6
	v_add_lshl_u32 v4, v4, s26, 10
	v_and_b32_e32 v2, 32, v2
	s_add_i32 s66, s54, 0x1e000
	s_mov_b32 m0, s66
	s_nop 0
	global_load_lds_dwordx4 v0, s[8:9]
	v_and_b32_e32 v3, 32, v3
	v_bitop3_b32 v1, v1, v4, v2 bitop3:0xde
	s_waitcnt vmcnt(6)
	s_add_i32 s67, s54, 0xc000
	s_add_i32 s73, s54, 0xe000
	v_readlane_b32 s2, v254, 0
	v_mov_b32_e32 v161, v0
	v_bitop3_b32 v3, v5, v7, v3 bitop3:0xde
	s_cmpk_lt_u32 s2, 0x100
	v_add_u32_e32 v0, 0, v1
	s_cselect_b64 s[26:27], -1, 0
	v_add_u32_e32 v194, 0x10000, v0
	v_add_u32_e32 v248, 0x14000, v0
	v_add_u32_e32 v249, 0, v3
	v_mov_b32_e32 v250, 0x79797979
	v_mov_b32_e32 v251, 0x7f7f7f7f
	v_add_u32_e32 v252, 0x18000, v0
	v_add_u32_e32 v253, 0x1c000, v0
	s_mov_b32 s79, s17
	s_barrier
	s_branch .LBB0_465

.LBB0_467:
	s_cmp_lt_i32 s24, 3
	s_cbranch_scc1 .Lhz_469
	s_add_i32 s2, s24, -2
	s_add_u32 s3, s4, s38
	s_addc_u32 s16, s5, s39
	s_add_u32 s33, s6, s22
	s_addc_u32 s44, s7, s23
	s_add_u32 s40, s18, s22
	s_addc_u32 s41, s19, s23
	s_add_u32 s45, s6, s40
	s_addc_u32 s46, s7, s41
	s_add_u32 s47, s6, s18
	s_addc_u32 s68, s7, s19
	s_add_u32 s40, s36, s38
	s_addc_u32 s41, s37, s39
	s_add_u32 s69, s4, s40
	s_addc_u32 s70, s5, s41
	s_add_u32 s71, s4, s36
	s_addc_u32 s72, s5, s37
	s_mov_b32 s74, 0
	s_mov_b64 s[40:41], 0
	s_cmp_eq_u32 s98, 0
	s_cbranch_scc1 .Lhf_469
	ds_read_b128 v[24:27], v194
	ds_read_b128 v[28:31], v194 offset:1024
	ds_read_b128 v[16:19], v194 offset:2048
	ds_read_b128 v[20:23], v194 offset:3072
	ds_read_b128 v[8:11], v248
	ds_read_b128 v[12:15], v248 offset:1024
	ds_read_b128 v[0:3], v248 offset:2048
	ds_read_b128 v[4:7], v248 offset:3072
	s_add_i32 s74, s74, 2
	s_add_u32 s75, s4, s40
	s_addc_u32 s77, s5, s41
	s_add_u32 s42, s75, 0x100
	s_addc_u32 s43, s77, 0
	s_add_u32 s80, s3, s40
	ds_read_b128 v[162:165], v249
	ds_read_b128 v[166:169], v249 offset:1024
	ds_read_b128 v[170:173], v249 offset:2048
	ds_read_b128 v[174:177], v249 offset:3072
	ds_read_b128 v[178:181], v249 offset:4096
	ds_read_b128 v[182:185], v249 offset:5120
	ds_read_b128 v[186:189], v249 offset:6144
	ds_read_b128 v[190:193], v249 offset:7168
	s_addc_u32 s81, s16, s41
	s_add_u32 s84, s80, 0x80
	s_addc_u32 s85, s81, 0
	s_add_u32 s82, s69, s40
	s_addc_u32 s83, s70, s41
	s_add_u32 s86, s82, 0x80
	s_mov_b32 m0, s67
	s_nop 0
	global_load_lds_dwordx4 v160, s[84:85]
	s_addc_u32 s87, s83, 0
	s_mov_b32 m0, s73
	s_nop 0
	global_load_lds_dwordx4 v160, s[86:87]
	s_waitcnt vmcnt(24)
	s_waitcnt lgkmcnt(0)
	s_barrier
	s_waitcnt lgkmcnt(6)
	v_mfma_scale_f32_16x16x128_f8f6f4 v[156:159], v[24:31], v[162:169], 0, v251, v250 op_sel_hi:[0,0,0]
	v_mfma_scale_f32_16x16x128_f8f6f4 v[152:155], v[16:23], v[162:169], 0, v251, v250 op_sel_hi:[0,0,0]
	s_waitcnt lgkmcnt(4)
	v_mfma_scale_f32_16x16x128_f8f6f4 v[148:151], v[24:31], v[170:177], 0, v251, v250 op_sel_hi:[0,0,0]
	v_mfma_scale_f32_16x16x128_f8f6f4 v[144:147], v[16:23], v[170:177], 0, v251, v250 op_sel_hi:[0,0,0]
	s_waitcnt lgkmcnt(2)
	v_mfma_scale_f32_16x16x128_f8f6f4 v[140:143], v[24:31], v[178:185], 0, v251, v250 op_sel_hi:[0,0,0]
	v_mfma_scale_f32_16x16x128_f8f6f4 v[136:139], v[16:23], v[178:185], 0, v251, v250 op_sel_hi:[0,0,0]
	s_waitcnt lgkmcnt(0)
	v_mfma_scale_f32_16x16x128_f8f6f4 v[132:135], v[24:31], v[186:193], 0, v251, v250 op_sel_hi:[0,0,0]
	v_mfma_scale_f32_16x16x128_f8f6f4 v[128:131], v[16:23], v[186:193], 0, v251, v250 op_sel_hi:[0,0,0]
	v_mfma_scale_f32_16x16x128_f8f6f4 v[124:127], v[8:15], v[162:169], 0, v251, v250 op_sel_hi:[0,0,0]
	v_mfma_scale_f32_16x16x128_f8f6f4 v[120:123], v[0:7], v[162:169], 0, v251, v250 op_sel_hi:[0,0,0]
	v_mfma_scale_f32_16x16x128_f8f6f4 v[116:119], v[8:15], v[170:177], 0, v251, v250 op_sel_hi:[0,0,0]
	v_mfma_scale_f32_16x16x128_f8f6f4 v[112:115], v[0:7], v[170:177], 0, v251, v250 op_sel_hi:[0,0,0]
	v_mfma_scale_f32_16x16x128_f8f6f4 v[108:111], v[8:15], v[178:185], 0, v251, v250 op_sel_hi:[0,0,0]
	v_mfma_scale_f32_16x16x128_f8f6f4 v[104:107], v[0:7], v[178:185], 0, v251, v250 op_sel_hi:[0,0,0]
	v_mfma_scale_f32_16x16x128_f8f6f4 v[100:103], v[8:15], v[186:193], 0, v251, v250 op_sel_hi:[0,0,0]
	v_mfma_scale_f32_16x16x128_f8f6f4 v[96:99], v[0:7], v[186:193], 0, v251, v250 op_sel_hi:[0,0,0]
	s_barrier
	s_add_u32 s84, s6, s40
	s_addc_u32 s85, s7, s41
	s_add_u32 s88, s84, 0x100
	s_addc_u32 s89, s85, 0
	s_add_u32 s86, s47, s40
	s_addc_u32 s87, s68, s41
	ds_read_b128 v[162:165], v249 offset:16384
	ds_read_b128 v[166:169], v249 offset:17408
	ds_read_b128 v[170:173], v249 offset:18432
	ds_read_b128 v[174:177], v249 offset:19456
	ds_read_b128 v[178:181], v249 offset:20480
	ds_read_b128 v[182:185], v249 offset:21504
	ds_read_b128 v[186:189], v249 offset:22528
	ds_read_b128 v[190:193], v249 offset:23552
	s_add_u32 s90, s86, 0x100
	s_mov_b32 m0, s51
	s_nop 0
	global_load_lds_dwordx4 v161, s[88:89]
	s_addc_u32 s91, s87, 0
	s_mov_b32 m0, s55
	s_nop 0
	global_load_lds_dwordx4 v161, s[90:91]
	s_add_u32 s88, s33, s40
	s_addc_u32 s89, s44, s41
	s_add_u32 s90, s88, 0x100
	s_addc_u32 s91, s89, 0
	s_add_u32 s92, s45, s40
	s_addc_u32 s93, s46, s41
	s_add_u32 s94, s92, 0x100
	s_mov_b32 m0, s56
	s_nop 0
	global_load_lds_dwordx4 v161, s[90:91]
	s_addc_u32 s95, s93, 0
	s_mov_b32 m0, s57
	s_nop 0
	global_load_lds_dwordx4 v161, s[94:95]
	s_add_u32 s90, s71, s40
	s_addc_u32 s91, s72, s41
	s_add_u32 s94, s90, 0x100
	s_mov_b32 m0, s54
	s_nop 0
	global_load_lds_dwordx4 v160, s[42:43]
	s_addc_u32 s95, s91, 0
	s_mov_b32 m0, s58
	s_nop 0
	global_load_lds_dwordx4 v160, s[94:95]
	s_waitcnt vmcnt(24)
	s_waitcnt lgkmcnt(0)
	s_barrier
	s_waitcnt lgkmcnt(6)
	v_mfma_scale_f32_16x16x128_f8f6f4 v[92:95], v[24:31], v[162:169], 0, v251, v250 op_sel_hi:[0,0,0]
	v_mfma_scale_f32_16x16x128_f8f6f4 v[88:91], v[16:23], v[162:169], 0, v251, v250 op_sel_hi:[0,0,0]
	s_waitcnt lgkmcnt(4)
	v_mfma_scale_f32_16x16x128_f8f6f4 v[84:87], v[24:31], v[170:177], 0, v251, v250 op_sel_hi:[0,0,0]
	v_mfma_scale_f32_16x16x128_f8f6f4 v[80:83], v[16:23], v[170:177], 0, v251, v250 op_sel_hi:[0,0,0]
	s_waitcnt lgkmcnt(2)
	v_mfma_scale_f32_16x16x128_f8f6f4 v[76:79], v[24:31], v[178:185], 0, v251, v250 op_sel_hi:[0,0,0]
	v_mfma_scale_f32_16x16x128_f8f6f4 v[72:75], v[16:23], v[178:185], 0, v251, v250 op_sel_hi:[0,0,0]
	s_waitcnt lgkmcnt(0)
	v_mfma_scale_f32_16x16x128_f8f6f4 v[68:71], v[24:31], v[186:193], 0, v251, v250 op_sel_hi:[0,0,0]
	v_mfma_scale_f32_16x16x128_f8f6f4 v[64:67], v[16:23], v[186:193], 0, v251, v250 op_sel_hi:[0,0,0]
	v_mfma_scale_f32_16x16x128_f8f6f4 v[60:63], v[8:15], v[162:169], 0, v251, v250 op_sel_hi:[0,0,0]
	v_mfma_scale_f32_16x16x128_f8f6f4 v[56:59], v[0:7], v[162:169], 0, v251, v250 op_sel_hi:[0,0,0]
	v_mfma_scale_f32_16x16x128_f8f6f4 v[52:55], v[8:15], v[170:177], 0, v251, v250 op_sel_hi:[0,0,0]
	v_mfma_scale_f32_16x16x128_f8f6f4 v[48:51], v[0:7], v[170:177], 0, v251, v250 op_sel_hi:[0,0,0]
	v_mfma_scale_f32_16x16x128_f8f6f4 v[44:47], v[8:15], v[178:185], 0, v251, v250 op_sel_hi:[0,0,0]
	v_mfma_scale_f32_16x16x128_f8f6f4 v[40:43], v[0:7], v[178:185], 0, v251, v250 op_sel_hi:[0,0,0]
	v_mfma_scale_f32_16x16x128_f8f6f4 v[36:39], v[8:15], v[186:193], 0, v251, v250 op_sel_hi:[0,0,0]
	v_mfma_scale_f32_16x16x128_f8f6f4 v[32:35], v[0:7], v[186:193], 0, v251, v250 op_sel_hi:[0,0,0]
	s_barrier
	ds_read_b128 v[24:27], v252
	ds_read_b128 v[28:31], v252 offset:1024
	ds_read_b128 v[16:19], v252 offset:2048
	ds_read_b128 v[20:23], v252 offset:3072
	ds_read_b128 v[8:11], v253
	ds_read_b128 v[12:15], v253 offset:1024
	ds_read_b128 v[0:3], v253 offset:2048
	ds_read_b128 v[4:7], v253 offset:3072
	ds_read_b128 v[162:165], v249 offset:32768
	ds_read_b128 v[166:169], v249 offset:33792
	ds_read_b128 v[170:173], v249 offset:34816
	ds_read_b128 v[174:177], v249 offset:35840
	ds_read_b128 v[178:181], v249 offset:36864
	ds_read_b128 v[182:185], v249 offset:37888
	ds_read_b128 v[186:189], v249 offset:38912
	ds_read_b128 v[190:193], v249 offset:39936
	s_add_u32 s42, s80, 0x100
	s_addc_u32 s43, s81, 0
	s_add_u32 s80, s82, 0x100
	s_mov_b32 m0, s59
	s_nop 0
	global_load_lds_dwordx4 v160, s[42:43]
	s_addc_u32 s81, s83, 0
	s_mov_b32 m0, s60
	s_nop 0
	global_load_lds_dwordx4 v160, s[80:81]
	s_waitcnt vmcnt(8)
	s_waitcnt lgkmcnt(0)
	s_barrier
	s_waitcnt lgkmcnt(6)
	v_mfma_scale_f32_16x16x128_f8f6f4 v[156:159], v[24:31], v[162:169], v[156:159], v251, v250 op_sel_hi:[0,0,0]
	v_mfma_scale_f32_16x16x128_f8f6f4 v[152:155], v[16:23], v[162:169], v[152:155], v251, v250 op_sel_hi:[0,0,0]
	s_waitcnt lgkmcnt(4)
	v_mfma_scale_f32_16x16x128_f8f6f4 v[148:151], v[24:31], v[170:177], v[148:151], v251, v250 op_sel_hi:[0,0,0]
	v_mfma_scale_f32_16x16x128_f8f6f4 v[144:147], v[16:23], v[170:177], v[144:147], v251, v250 op_sel_hi:[0,0,0]
	s_waitcnt lgkmcnt(2)
	v_mfma_scale_f32_16x16x128_f8f6f4 v[140:143], v[24:31], v[178:185], v[140:143], v251, v250 op_sel_hi:[0,0,0]
	v_mfma_scale_f32_16x16x128_f8f6f4 v[136:139], v[16:23], v[178:185], v[136:139], v251, v250 op_sel_hi:[0,0,0]
	s_waitcnt lgkmcnt(0)
	v_mfma_scale_f32_16x16x128_f8f6f4 v[132:135], v[24:31], v[186:193], v[132:135], v251, v250 op_sel_hi:[0,0,0]
	v_mfma_scale_f32_16x16x128_f8f6f4 v[128:131], v[16:23], v[186:193], v[128:131], v251, v250 op_sel_hi:[0,0,0]
	v_mfma_scale_f32_16x16x128_f8f6f4 v[124:127], v[8:15], v[162:169], v[124:127], v251, v250 op_sel_hi:[0,0,0]
	v_mfma_scale_f32_16x16x128_f8f6f4 v[120:123], v[0:7], v[162:169], v[120:123], v251, v250 op_sel_hi:[0,0,0]
	v_mfma_scale_f32_16x16x128_f8f6f4 v[116:119], v[8:15], v[170:177], v[116:119], v251, v250 op_sel_hi:[0,0,0]
	v_mfma_scale_f32_16x16x128_f8f6f4 v[112:115], v[0:7], v[170:177], v[112:115], v251, v250 op_sel_hi:[0,0,0]
	v_mfma_scale_f32_16x16x128_f8f6f4 v[108:111], v[8:15], v[178:185], v[108:111], v251, v250 op_sel_hi:[0,0,0]
	v_mfma_scale_f32_16x16x128_f8f6f4 v[104:107], v[0:7], v[178:185], v[104:107], v251, v250 op_sel_hi:[0,0,0]
	v_mfma_scale_f32_16x16x128_f8f6f4 v[100:103], v[8:15], v[186:193], v[100:103], v251, v250 op_sel_hi:[0,0,0]
	v_mfma_scale_f32_16x16x128_f8f6f4 v[96:99], v[0:7], v[186:193], v[96:99], v251, v250 op_sel_hi:[0,0,0]
	s_barrier
	s_add_u32 s42, s84, 0x180
	s_addc_u32 s43, s85, 0
	ds_read_b128 v[162:165], v249 offset:49152
	ds_read_b128 v[166:169], v249 offset:50176
	ds_read_b128 v[170:173], v249 offset:51200
	ds_read_b128 v[174:177], v249 offset:52224
	ds_read_b128 v[178:181], v249 offset:53248
	ds_read_b128 v[182:185], v249 offset:54272
	ds_read_b128 v[186:189], v249 offset:55296
	ds_read_b128 v[190:193], v249 offset:56320
	s_add_u32 s80, s86, 0x180
	s_mov_b32 m0, s61
	s_nop 0
	global_load_lds_dwordx4 v161, s[42:43]
	s_addc_u32 s81, s87, 0
	s_mov_b32 m0, s62
	s_nop 0
	global_load_lds_dwordx4 v161, s[80:81]
	s_add_u32 s42, s88, 0x180
	s_addc_u32 s43, s89, 0
	s_add_u32 s80, s92, 0x180
	s_mov_b32 m0, s65
	s_nop 0
	global_load_lds_dwordx4 v161, s[42:43]
	s_addc_u32 s81, s93, 0
	s_mov_b32 m0, s66
	s_nop 0
	global_load_lds_dwordx4 v161, s[80:81]
	s_add_u32 s42, s75, 0x180
	s_addc_u32 s43, s77, 0
	s_add_u32 s80, s90, 0x180
	s_mov_b32 m0, s63
	s_nop 0
	global_load_lds_dwordx4 v160, s[42:43]
	s_addc_u32 s81, s91, 0
	s_mov_b32 m0, s64
	s_nop 0
	global_load_lds_dwordx4 v160, s[80:81]
	s_waitcnt vmcnt(8)
	s_waitcnt lgkmcnt(0)
	s_barrier
	s_waitcnt lgkmcnt(6)
	v_mfma_scale_f32_16x16x128_f8f6f4 v[92:95], v[24:31], v[162:169], v[92:95], v251, v250 op_sel_hi:[0,0,0]
	v_mfma_scale_f32_16x16x128_f8f6f4 v[88:91], v[16:23], v[162:169], v[88:91], v251, v250 op_sel_hi:[0,0,0]
	s_waitcnt lgkmcnt(4)
	v_mfma_scale_f32_16x16x128_f8f6f4 v[84:87], v[24:31], v[170:177], v[84:87], v251, v250 op_sel_hi:[0,0,0]
	v_mfma_scale_f32_16x16x128_f8f6f4 v[80:83], v[16:23], v[170:177], v[80:83], v251, v250 op_sel_hi:[0,0,0]
	s_waitcnt lgkmcnt(2)
	v_mfma_scale_f32_16x16x128_f8f6f4 v[76:79], v[24:31], v[178:185], v[76:79], v251, v250 op_sel_hi:[0,0,0]
	v_mfma_scale_f32_16x16x128_f8f6f4 v[72:75], v[16:23], v[178:185], v[72:75], v251, v250 op_sel_hi:[0,0,0]
	s_waitcnt lgkmcnt(0)
	v_mfma_scale_f32_16x16x128_f8f6f4 v[68:71], v[24:31], v[186:193], v[68:71], v251, v250 op_sel_hi:[0,0,0]
	v_mfma_scale_f32_16x16x128_f8f6f4 v[64:67], v[16:23], v[186:193], v[64:67], v251, v250 op_sel_hi:[0,0,0]
	v_mfma_scale_f32_16x16x128_f8f6f4 v[60:63], v[8:15], v[162:169], v[60:63], v251, v250 op_sel_hi:[0,0,0]
	v_mfma_scale_f32_16x16x128_f8f6f4 v[56:59], v[0:7], v[162:169], v[56:59], v251, v250 op_sel_hi:[0,0,0]
	v_mfma_scale_f32_16x16x128_f8f6f4 v[52:55], v[8:15], v[170:177], v[52:55], v251, v250 op_sel_hi:[0,0,0]
	v_mfma_scale_f32_16x16x128_f8f6f4 v[48:51], v[0:7], v[170:177], v[48:51], v251, v250 op_sel_hi:[0,0,0]
	v_mfma_scale_f32_16x16x128_f8f6f4 v[44:47], v[8:15], v[178:185], v[44:47], v251, v250 op_sel_hi:[0,0,0]
	v_mfma_scale_f32_16x16x128_f8f6f4 v[40:43], v[0:7], v[178:185], v[40:43], v251, v250 op_sel_hi:[0,0,0]
	v_mfma_scale_f32_16x16x128_f8f6f4 v[36:39], v[8:15], v[186:193], v[36:39], v251, v250 op_sel_hi:[0,0,0]
	v_mfma_scale_f32_16x16x128_f8f6f4 v[32:35], v[0:7], v[186:193], v[32:35], v251, v250 op_sel_hi:[0,0,0]
	s_barrier
	s_add_u32 s40, s40, 0x100
	s_addc_u32 s41, s41, 0
	s_cmp_ge_i32 s74, s2
	s_cbranch_scc0 .LBB0_469
	s_branch .LBB0_470
.Lhf_469:
	ds_read_b128 v[24:27], v194
	ds_read_b128 v[28:31], v194 offset:1024
	ds_read_b128 v[16:19], v194 offset:2048
	ds_read_b128 v[20:23], v194 offset:3072
	ds_read_b128 v[8:11], v248
	ds_read_b128 v[12:15], v248 offset:1024
	ds_read_b128 v[0:3], v248 offset:2048
	ds_read_b128 v[4:7], v248 offset:3072
	s_add_i32 s74, s74, 2
	s_add_u32 s75, s4, s40
	s_addc_u32 s77, s5, s41
	s_add_u32 s42, s75, 0x100
	s_addc_u32 s43, s77, 0
	s_add_u32 s80, s3, s40
	ds_read_b128 v[162:165], v249
	ds_read_b128 v[166:169], v249 offset:1024
	ds_read_b128 v[170:173], v249 offset:2048
	ds_read_b128 v[174:177], v249 offset:3072
	ds_read_b128 v[178:181], v249 offset:4096
	ds_read_b128 v[182:185], v249 offset:5120
	ds_read_b128 v[186:189], v249 offset:6144
	ds_read_b128 v[190:193], v249 offset:7168
	s_addc_u32 s81, s16, s41
	s_add_u32 s84, s80, 0x80
	s_addc_u32 s85, s81, 0
	s_add_u32 s82, s69, s40
	s_addc_u32 s83, s70, s41
	s_add_u32 s86, s82, 0x80
	s_mov_b32 m0, s67
	s_nop 0
	global_load_lds_dwordx4 v160, s[84:85]
	s_addc_u32 s87, s83, 0
	s_mov_b32 m0, s73
	s_nop 0
	global_load_lds_dwordx4 v160, s[86:87]
	s_waitcnt vmcnt(8)
	s_waitcnt lgkmcnt(0)
	s_barrier
	s_waitcnt lgkmcnt(6)
	v_mfma_scale_f32_16x16x128_f8f6f4 v[156:159], v[24:31], v[162:169], 0, v251, v250 op_sel_hi:[0,0,0]
	v_mfma_scale_f32_16x16x128_f8f6f4 v[152:155], v[16:23], v[162:169], 0, v251, v250 op_sel_hi:[0,0,0]
	s_waitcnt lgkmcnt(4)
	v_mfma_scale_f32_16x16x128_f8f6f4 v[148:151], v[24:31], v[170:177], 0, v251, v250 op_sel_hi:[0,0,0]
	v_mfma_scale_f32_16x16x128_f8f6f4 v[144:147], v[16:23], v[170:177], 0, v251, v250 op_sel_hi:[0,0,0]
	s_waitcnt lgkmcnt(2)
	v_mfma_scale_f32_16x16x128_f8f6f4 v[140:143], v[24:31], v[178:185], 0, v251, v250 op_sel_hi:[0,0,0]
	v_mfma_scale_f32_16x16x128_f8f6f4 v[136:139], v[16:23], v[178:185], 0, v251, v250 op_sel_hi:[0,0,0]
	s_waitcnt lgkmcnt(0)
	v_mfma_scale_f32_16x16x128_f8f6f4 v[132:135], v[24:31], v[186:193], 0, v251, v250 op_sel_hi:[0,0,0]
	v_mfma_scale_f32_16x16x128_f8f6f4 v[128:131], v[16:23], v[186:193], 0, v251, v250 op_sel_hi:[0,0,0]
	v_mfma_scale_f32_16x16x128_f8f6f4 v[124:127], v[8:15], v[162:169], 0, v251, v250 op_sel_hi:[0,0,0]
	v_mfma_scale_f32_16x16x128_f8f6f4 v[120:123], v[0:7], v[162:169], 0, v251, v250 op_sel_hi:[0,0,0]
	v_mfma_scale_f32_16x16x128_f8f6f4 v[116:119], v[8:15], v[170:177], 0, v251, v250 op_sel_hi:[0,0,0]
	v_mfma_scale_f32_16x16x128_f8f6f4 v[112:115], v[0:7], v[170:177], 0, v251, v250 op_sel_hi:[0,0,0]
	v_mfma_scale_f32_16x16x128_f8f6f4 v[108:111], v[8:15], v[178:185], 0, v251, v250 op_sel_hi:[0,0,0]
	v_mfma_scale_f32_16x16x128_f8f6f4 v[104:107], v[0:7], v[178:185], 0, v251, v250 op_sel_hi:[0,0,0]
	v_mfma_scale_f32_16x16x128_f8f6f4 v[100:103], v[8:15], v[186:193], 0, v251, v250 op_sel_hi:[0,0,0]
	v_mfma_scale_f32_16x16x128_f8f6f4 v[96:99], v[0:7], v[186:193], 0, v251, v250 op_sel_hi:[0,0,0]
	s_barrier
	s_add_u32 s84, s6, s40
	s_addc_u32 s85, s7, s41
	s_add_u32 s88, s84, 0x100
	s_addc_u32 s89, s85, 0
	s_add_u32 s86, s47, s40
	s_addc_u32 s87, s68, s41
	ds_read_b128 v[162:165], v249 offset:16384
	ds_read_b128 v[166:169], v249 offset:17408
	ds_read_b128 v[170:173], v249 offset:18432
	ds_read_b128 v[174:177], v249 offset:19456
	ds_read_b128 v[178:181], v249 offset:20480
	ds_read_b128 v[182:185], v249 offset:21504
	ds_read_b128 v[186:189], v249 offset:22528
	ds_read_b128 v[190:193], v249 offset:23552
	s_add_u32 s90, s86, 0x100
	s_mov_b32 m0, s51
	s_nop 0
	global_load_lds_dwordx4 v161, s[88:89]
	s_addc_u32 s91, s87, 0
	s_mov_b32 m0, s55
	s_nop 0
	global_load_lds_dwordx4 v161, s[90:91]
	s_add_u32 s88, s33, s40
	s_addc_u32 s89, s44, s41
	s_add_u32 s90, s88, 0x100
	s_addc_u32 s91, s89, 0
	s_add_u32 s92, s45, s40
	s_addc_u32 s93, s46, s41
	s_add_u32 s94, s92, 0x100
	s_mov_b32 m0, s56
	s_nop 0
	global_load_lds_dwordx4 v161, s[90:91]
	s_addc_u32 s95, s93, 0
	s_mov_b32 m0, s57
	s_nop 0
	global_load_lds_dwordx4 v161, s[94:95]
	s_add_u32 s90, s71, s40
	s_addc_u32 s91, s72, s41
	s_add_u32 s94, s90, 0x100
	s_mov_b32 m0, s54
	s_nop 0
	global_load_lds_dwordx4 v160, s[42:43]
	s_addc_u32 s95, s91, 0
	s_mov_b32 m0, s58
	s_nop 0
	global_load_lds_dwordx4 v160, s[94:95]
	s_waitcnt vmcnt(8)
	s_waitcnt lgkmcnt(0)
	s_barrier
	s_waitcnt lgkmcnt(6)
	v_mfma_scale_f32_16x16x128_f8f6f4 v[92:95], v[24:31], v[162:169], 0, v251, v250 op_sel_hi:[0,0,0]
	v_mfma_scale_f32_16x16x128_f8f6f4 v[88:91], v[16:23], v[162:169], 0, v251, v250 op_sel_hi:[0,0,0]
	s_waitcnt lgkmcnt(4)
	v_mfma_scale_f32_16x16x128_f8f6f4 v[84:87], v[24:31], v[170:177], 0, v251, v250 op_sel_hi:[0,0,0]
	v_mfma_scale_f32_16x16x128_f8f6f4 v[80:83], v[16:23], v[170:177], 0, v251, v250 op_sel_hi:[0,0,0]
	s_waitcnt lgkmcnt(2)
	v_mfma_scale_f32_16x16x128_f8f6f4 v[76:79], v[24:31], v[178:185], 0, v251, v250 op_sel_hi:[0,0,0]
	v_mfma_scale_f32_16x16x128_f8f6f4 v[72:75], v[16:23], v[178:185], 0, v251, v250 op_sel_hi:[0,0,0]
	s_waitcnt lgkmcnt(0)
	v_mfma_scale_f32_16x16x128_f8f6f4 v[68:71], v[24:31], v[186:193], 0, v251, v250 op_sel_hi:[0,0,0]
	v_mfma_scale_f32_16x16x128_f8f6f4 v[64:67], v[16:23], v[186:193], 0, v251, v250 op_sel_hi:[0,0,0]
	v_mfma_scale_f32_16x16x128_f8f6f4 v[60:63], v[8:15], v[162:169], 0, v251, v250 op_sel_hi:[0,0,0]
	v_mfma_scale_f32_16x16x128_f8f6f4 v[56:59], v[0:7], v[162:169], 0, v251, v250 op_sel_hi:[0,0,0]
	v_mfma_scale_f32_16x16x128_f8f6f4 v[52:55], v[8:15], v[170:177], 0, v251, v250 op_sel_hi:[0,0,0]
	v_mfma_scale_f32_16x16x128_f8f6f4 v[48:51], v[0:7], v[170:177], 0, v251, v250 op_sel_hi:[0,0,0]
	v_mfma_scale_f32_16x16x128_f8f6f4 v[44:47], v[8:15], v[178:185], 0, v251, v250 op_sel_hi:[0,0,0]
	v_mfma_scale_f32_16x16x128_f8f6f4 v[40:43], v[0:7], v[178:185], 0, v251, v250 op_sel_hi:[0,0,0]
	v_mfma_scale_f32_16x16x128_f8f6f4 v[36:39], v[8:15], v[186:193], 0, v251, v250 op_sel_hi:[0,0,0]
	v_mfma_scale_f32_16x16x128_f8f6f4 v[32:35], v[0:7], v[186:193], 0, v251, v250 op_sel_hi:[0,0,0]
	s_barrier
	ds_read_b128 v[24:27], v252
	ds_read_b128 v[28:31], v252 offset:1024
	ds_read_b128 v[16:19], v252 offset:2048
	ds_read_b128 v[20:23], v252 offset:3072
	ds_read_b128 v[8:11], v253
	ds_read_b128 v[12:15], v253 offset:1024
	ds_read_b128 v[0:3], v253 offset:2048
	ds_read_b128 v[4:7], v253 offset:3072
	ds_read_b128 v[162:165], v249 offset:32768
	ds_read_b128 v[166:169], v249 offset:33792
	ds_read_b128 v[170:173], v249 offset:34816
	ds_read_b128 v[174:177], v249 offset:35840
	ds_read_b128 v[178:181], v249 offset:36864
	ds_read_b128 v[182:185], v249 offset:37888
	ds_read_b128 v[186:189], v249 offset:38912
	ds_read_b128 v[190:193], v249 offset:39936
	s_add_u32 s42, s80, 0x100
	s_addc_u32 s43, s81, 0
	s_add_u32 s80, s82, 0x100
	s_mov_b32 m0, s59
	s_nop 0
	global_load_lds_dwordx4 v160, s[42:43]
	s_addc_u32 s81, s83, 0
	s_mov_b32 m0, s60
	s_nop 0
	global_load_lds_dwordx4 v160, s[80:81]
	s_waitcnt vmcnt(8)
	s_waitcnt lgkmcnt(0)
	s_barrier
	s_waitcnt lgkmcnt(6)
	v_mfma_scale_f32_16x16x128_f8f6f4 v[156:159], v[24:31], v[162:169], v[156:159], v251, v250 op_sel_hi:[0,0,0]
	v_mfma_scale_f32_16x16x128_f8f6f4 v[152:155], v[16:23], v[162:169], v[152:155], v251, v250 op_sel_hi:[0,0,0]
	s_waitcnt lgkmcnt(4)
	v_mfma_scale_f32_16x16x128_f8f6f4 v[148:151], v[24:31], v[170:177], v[148:151], v251, v250 op_sel_hi:[0,0,0]
	v_mfma_scale_f32_16x16x128_f8f6f4 v[144:147], v[16:23], v[170:177], v[144:147], v251, v250 op_sel_hi:[0,0,0]
	s_waitcnt lgkmcnt(2)
	v_mfma_scale_f32_16x16x128_f8f6f4 v[140:143], v[24:31], v[178:185], v[140:143], v251, v250 op_sel_hi:[0,0,0]
	v_mfma_scale_f32_16x16x128_f8f6f4 v[136:139], v[16:23], v[178:185], v[136:139], v251, v250 op_sel_hi:[0,0,0]
	s_waitcnt lgkmcnt(0)
	v_mfma_scale_f32_16x16x128_f8f6f4 v[132:135], v[24:31], v[186:193], v[132:135], v251, v250 op_sel_hi:[0,0,0]
	v_mfma_scale_f32_16x16x128_f8f6f4 v[128:131], v[16:23], v[186:193], v[128:131], v251, v250 op_sel_hi:[0,0,0]
	v_mfma_scale_f32_16x16x128_f8f6f4 v[124:127], v[8:15], v[162:169], v[124:127], v251, v250 op_sel_hi:[0,0,0]
	v_mfma_scale_f32_16x16x128_f8f6f4 v[120:123], v[0:7], v[162:169], v[120:123], v251, v250 op_sel_hi:[0,0,0]
	v_mfma_scale_f32_16x16x128_f8f6f4 v[116:119], v[8:15], v[170:177], v[116:119], v251, v250 op_sel_hi:[0,0,0]
	v_mfma_scale_f32_16x16x128_f8f6f4 v[112:115], v[0:7], v[170:177], v[112:115], v251, v250 op_sel_hi:[0,0,0]
	v_mfma_scale_f32_16x16x128_f8f6f4 v[108:111], v[8:15], v[178:185], v[108:111], v251, v250 op_sel_hi:[0,0,0]
	v_mfma_scale_f32_16x16x128_f8f6f4 v[104:107], v[0:7], v[178:185], v[104:107], v251, v250 op_sel_hi:[0,0,0]
	v_mfma_scale_f32_16x16x128_f8f6f4 v[100:103], v[8:15], v[186:193], v[100:103], v251, v250 op_sel_hi:[0,0,0]
	v_mfma_scale_f32_16x16x128_f8f6f4 v[96:99], v[0:7], v[186:193], v[96:99], v251, v250 op_sel_hi:[0,0,0]
	s_barrier
	s_add_u32 s42, s84, 0x180
	s_addc_u32 s43, s85, 0
	ds_read_b128 v[162:165], v249 offset:49152
	ds_read_b128 v[166:169], v249 offset:50176
	ds_read_b128 v[170:173], v249 offset:51200
	ds_read_b128 v[174:177], v249 offset:52224
	ds_read_b128 v[178:181], v249 offset:53248
	ds_read_b128 v[182:185], v249 offset:54272
	ds_read_b128 v[186:189], v249 offset:55296
	ds_read_b128 v[190:193], v249 offset:56320
	s_add_u32 s80, s86, 0x180
	s_mov_b32 m0, s61
	s_nop 0
	global_load_lds_dwordx4 v161, s[42:43]
	s_addc_u32 s81, s87, 0
	s_mov_b32 m0, s62
	s_nop 0
	global_load_lds_dwordx4 v161, s[80:81]
	s_add_u32 s42, s88, 0x180
	s_addc_u32 s43, s89, 0
	s_add_u32 s80, s92, 0x180
	s_mov_b32 m0, s65
	s_nop 0
	global_load_lds_dwordx4 v161, s[42:43]
	s_addc_u32 s81, s93, 0
	s_mov_b32 m0, s66
	s_nop 0
	global_load_lds_dwordx4 v161, s[80:81]
	s_add_u32 s42, s75, 0x180
	s_addc_u32 s43, s77, 0
	s_add_u32 s80, s90, 0x180
	s_mov_b32 m0, s63
	s_nop 0
	global_load_lds_dwordx4 v160, s[42:43]
	s_addc_u32 s81, s91, 0
	s_mov_b32 m0, s64
	s_nop 0
	global_load_lds_dwordx4 v160, s[80:81]
	s_waitcnt vmcnt(8)
	s_waitcnt lgkmcnt(0)
	s_barrier
	s_waitcnt lgkmcnt(6)
	v_mfma_scale_f32_16x16x128_f8f6f4 v[92:95], v[24:31], v[162:169], v[92:95], v251, v250 op_sel_hi:[0,0,0]
	v_mfma_scale_f32_16x16x128_f8f6f4 v[88:91], v[16:23], v[162:169], v[88:91], v251, v250 op_sel_hi:[0,0,0]
	s_waitcnt lgkmcnt(4)
	v_mfma_scale_f32_16x16x128_f8f6f4 v[84:87], v[24:31], v[170:177], v[84:87], v251, v250 op_sel_hi:[0,0,0]
	v_mfma_scale_f32_16x16x128_f8f6f4 v[80:83], v[16:23], v[170:177], v[80:83], v251, v250 op_sel_hi:[0,0,0]
	s_waitcnt lgkmcnt(2)
	v_mfma_scale_f32_16x16x128_f8f6f4 v[76:79], v[24:31], v[178:185], v[76:79], v251, v250 op_sel_hi:[0,0,0]
	v_mfma_scale_f32_16x16x128_f8f6f4 v[72:75], v[16:23], v[178:185], v[72:75], v251, v250 op_sel_hi:[0,0,0]
	s_waitcnt lgkmcnt(0)
	v_mfma_scale_f32_16x16x128_f8f6f4 v[68:71], v[24:31], v[186:193], v[68:71], v251, v250 op_sel_hi:[0,0,0]
	v_mfma_scale_f32_16x16x128_f8f6f4 v[64:67], v[16:23], v[186:193], v[64:67], v251, v250 op_sel_hi:[0,0,0]
	v_mfma_scale_f32_16x16x128_f8f6f4 v[60:63], v[8:15], v[162:169], v[60:63], v251, v250 op_sel_hi:[0,0,0]
	v_mfma_scale_f32_16x16x128_f8f6f4 v[56:59], v[0:7], v[162:169], v[56:59], v251, v250 op_sel_hi:[0,0,0]
	v_mfma_scale_f32_16x16x128_f8f6f4 v[52:55], v[8:15], v[170:177], v[52:55], v251, v250 op_sel_hi:[0,0,0]
	v_mfma_scale_f32_16x16x128_f8f6f4 v[48:51], v[0:7], v[170:177], v[48:51], v251, v250 op_sel_hi:[0,0,0]
	v_mfma_scale_f32_16x16x128_f8f6f4 v[44:47], v[8:15], v[178:185], v[44:47], v251, v250 op_sel_hi:[0,0,0]
	v_mfma_scale_f32_16x16x128_f8f6f4 v[40:43], v[0:7], v[178:185], v[40:43], v251, v250 op_sel_hi:[0,0,0]
	v_mfma_scale_f32_16x16x128_f8f6f4 v[36:39], v[8:15], v[186:193], v[36:39], v251, v250 op_sel_hi:[0,0,0]
	v_mfma_scale_f32_16x16x128_f8f6f4 v[32:35], v[0:7], v[186:193], v[32:35], v251, v250 op_sel_hi:[0,0,0]
	s_barrier
	s_add_u32 s40, s40, 0x100
	s_addc_u32 s41, s41, 0
	s_cmp_ge_i32 s74, s2
	s_cbranch_scc0 .LBB0_469
	s_branch .LBB0_470

.LBB0_469:
	ds_read_b128 v[24:27], v194
	ds_read_b128 v[28:31], v194 offset:1024
	ds_read_b128 v[16:19], v194 offset:2048
	ds_read_b128 v[20:23], v194 offset:3072
	ds_read_b128 v[8:11], v248
	ds_read_b128 v[12:15], v248 offset:1024
	ds_read_b128 v[0:3], v248 offset:2048
	ds_read_b128 v[4:7], v248 offset:3072
	s_add_i32 s74, s74, 2
	s_add_u32 s75, s4, s40
	s_addc_u32 s77, s5, s41
	s_add_u32 s42, s75, 0x100
	s_addc_u32 s43, s77, 0
	s_add_u32 s80, s3, s40
	ds_read_b128 v[162:165], v249
	ds_read_b128 v[166:169], v249 offset:1024
	ds_read_b128 v[170:173], v249 offset:2048
	ds_read_b128 v[174:177], v249 offset:3072
	ds_read_b128 v[178:181], v249 offset:4096
	ds_read_b128 v[182:185], v249 offset:5120
	ds_read_b128 v[186:189], v249 offset:6144
	ds_read_b128 v[190:193], v249 offset:7168
	s_addc_u32 s81, s16, s41
	s_add_u32 s84, s80, 0x80
	s_addc_u32 s85, s81, 0
	s_add_u32 s82, s69, s40
	s_addc_u32 s83, s70, s41
	s_add_u32 s86, s82, 0x80
	s_mov_b32 m0, s67
	s_nop 0
	global_load_lds_dwordx4 v160, s[84:85]
	s_addc_u32 s87, s83, 0
	s_mov_b32 m0, s73
	s_nop 0
	global_load_lds_dwordx4 v160, s[86:87]
	s_waitcnt vmcnt(8)
	s_waitcnt lgkmcnt(0)
	s_barrier
	s_waitcnt lgkmcnt(6)
	v_mfma_scale_f32_16x16x128_f8f6f4 v[156:159], v[24:31], v[162:169], v[156:159], v251, v250 op_sel_hi:[0,0,0]
	v_mfma_scale_f32_16x16x128_f8f6f4 v[152:155], v[16:23], v[162:169], v[152:155], v251, v250 op_sel_hi:[0,0,0]
	s_waitcnt lgkmcnt(4)
	v_mfma_scale_f32_16x16x128_f8f6f4 v[148:151], v[24:31], v[170:177], v[148:151], v251, v250 op_sel_hi:[0,0,0]
	v_mfma_scale_f32_16x16x128_f8f6f4 v[144:147], v[16:23], v[170:177], v[144:147], v251, v250 op_sel_hi:[0,0,0]
	s_waitcnt lgkmcnt(2)
	v_mfma_scale_f32_16x16x128_f8f6f4 v[140:143], v[24:31], v[178:185], v[140:143], v251, v250 op_sel_hi:[0,0,0]
	v_mfma_scale_f32_16x16x128_f8f6f4 v[136:139], v[16:23], v[178:185], v[136:139], v251, v250 op_sel_hi:[0,0,0]
	s_waitcnt lgkmcnt(0)
	v_mfma_scale_f32_16x16x128_f8f6f4 v[132:135], v[24:31], v[186:193], v[132:135], v251, v250 op_sel_hi:[0,0,0]
	v_mfma_scale_f32_16x16x128_f8f6f4 v[128:131], v[16:23], v[186:193], v[128:131], v251, v250 op_sel_hi:[0,0,0]
	v_mfma_scale_f32_16x16x128_f8f6f4 v[124:127], v[8:15], v[162:169], v[124:127], v251, v250 op_sel_hi:[0,0,0]
	v_mfma_scale_f32_16x16x128_f8f6f4 v[120:123], v[0:7], v[162:169], v[120:123], v251, v250 op_sel_hi:[0,0,0]
	v_mfma_scale_f32_16x16x128_f8f6f4 v[116:119], v[8:15], v[170:177], v[116:119], v251, v250 op_sel_hi:[0,0,0]
	v_mfma_scale_f32_16x16x128_f8f6f4 v[112:115], v[0:7], v[170:177], v[112:115], v251, v250 op_sel_hi:[0,0,0]
	v_mfma_scale_f32_16x16x128_f8f6f4 v[108:111], v[8:15], v[178:185], v[108:111], v251, v250 op_sel_hi:[0,0,0]
	v_mfma_scale_f32_16x16x128_f8f6f4 v[104:107], v[0:7], v[178:185], v[104:107], v251, v250 op_sel_hi:[0,0,0]
	v_mfma_scale_f32_16x16x128_f8f6f4 v[100:103], v[8:15], v[186:193], v[100:103], v251, v250 op_sel_hi:[0,0,0]
	v_mfma_scale_f32_16x16x128_f8f6f4 v[96:99], v[0:7], v[186:193], v[96:99], v251, v250 op_sel_hi:[0,0,0]
	s_barrier
	s_add_u32 s84, s6, s40
	s_addc_u32 s85, s7, s41
	s_add_u32 s88, s84, 0x100
	s_addc_u32 s89, s85, 0
	s_add_u32 s86, s47, s40
	s_addc_u32 s87, s68, s41
	ds_read_b128 v[162:165], v249 offset:16384
	ds_read_b128 v[166:169], v249 offset:17408
	ds_read_b128 v[170:173], v249 offset:18432
	ds_read_b128 v[174:177], v249 offset:19456
	ds_read_b128 v[178:181], v249 offset:20480
	ds_read_b128 v[182:185], v249 offset:21504
	ds_read_b128 v[186:189], v249 offset:22528
	ds_read_b128 v[190:193], v249 offset:23552
	s_add_u32 s90, s86, 0x100
	s_mov_b32 m0, s51
	s_nop 0
	global_load_lds_dwordx4 v161, s[88:89]
	s_addc_u32 s91, s87, 0
	s_mov_b32 m0, s55
	s_nop 0
	global_load_lds_dwordx4 v161, s[90:91]
	s_add_u32 s88, s33, s40
	s_addc_u32 s89, s44, s41
	s_add_u32 s90, s88, 0x100
	s_addc_u32 s91, s89, 0
	s_add_u32 s92, s45, s40
	s_addc_u32 s93, s46, s41
	s_add_u32 s94, s92, 0x100
	s_mov_b32 m0, s56
	s_nop 0
	global_load_lds_dwordx4 v161, s[90:91]
	s_addc_u32 s95, s93, 0
	s_mov_b32 m0, s57
	s_nop 0
	global_load_lds_dwordx4 v161, s[94:95]
	s_add_u32 s90, s71, s40
	s_addc_u32 s91, s72, s41
	s_add_u32 s94, s90, 0x100
	s_mov_b32 m0, s54
	s_nop 0
	global_load_lds_dwordx4 v160, s[42:43]
	s_addc_u32 s95, s91, 0
	s_mov_b32 m0, s58
	s_nop 0
	global_load_lds_dwordx4 v160, s[94:95]
	s_waitcnt vmcnt(8)
	s_waitcnt lgkmcnt(0)
	s_barrier
	s_waitcnt lgkmcnt(6)
	v_mfma_scale_f32_16x16x128_f8f6f4 v[92:95], v[24:31], v[162:169], v[92:95], v251, v250 op_sel_hi:[0,0,0]
	v_mfma_scale_f32_16x16x128_f8f6f4 v[88:91], v[16:23], v[162:169], v[88:91], v251, v250 op_sel_hi:[0,0,0]
	s_waitcnt lgkmcnt(4)
	v_mfma_scale_f32_16x16x128_f8f6f4 v[84:87], v[24:31], v[170:177], v[84:87], v251, v250 op_sel_hi:[0,0,0]
	v_mfma_scale_f32_16x16x128_f8f6f4 v[80:83], v[16:23], v[170:177], v[80:83], v251, v250 op_sel_hi:[0,0,0]
	s_waitcnt lgkmcnt(2)
	v_mfma_scale_f32_16x16x128_f8f6f4 v[76:79], v[24:31], v[178:185], v[76:79], v251, v250 op_sel_hi:[0,0,0]
	v_mfma_scale_f32_16x16x128_f8f6f4 v[72:75], v[16:23], v[178:185], v[72:75], v251, v250 op_sel_hi:[0,0,0]
	s_waitcnt lgkmcnt(0)
	v_mfma_scale_f32_16x16x128_f8f6f4 v[68:71], v[24:31], v[186:193], v[68:71], v251, v250 op_sel_hi:[0,0,0]
	v_mfma_scale_f32_16x16x128_f8f6f4 v[64:67], v[16:23], v[186:193], v[64:67], v251, v250 op_sel_hi:[0,0,0]
	v_mfma_scale_f32_16x16x128_f8f6f4 v[60:63], v[8:15], v[162:169], v[60:63], v251, v250 op_sel_hi:[0,0,0]
	v_mfma_scale_f32_16x16x128_f8f6f4 v[56:59], v[0:7], v[162:169], v[56:59], v251, v250 op_sel_hi:[0,0,0]
	v_mfma_scale_f32_16x16x128_f8f6f4 v[52:55], v[8:15], v[170:177], v[52:55], v251, v250 op_sel_hi:[0,0,0]
	v_mfma_scale_f32_16x16x128_f8f6f4 v[48:51], v[0:7], v[170:177], v[48:51], v251, v250 op_sel_hi:[0,0,0]
	v_mfma_scale_f32_16x16x128_f8f6f4 v[44:47], v[8:15], v[178:185], v[44:47], v251, v250 op_sel_hi:[0,0,0]
	v_mfma_scale_f32_16x16x128_f8f6f4 v[40:43], v[0:7], v[178:185], v[40:43], v251, v250 op_sel_hi:[0,0,0]
	v_mfma_scale_f32_16x16x128_f8f6f4 v[36:39], v[8:15], v[186:193], v[36:39], v251, v250 op_sel_hi:[0,0,0]
	v_mfma_scale_f32_16x16x128_f8f6f4 v[32:35], v[0:7], v[186:193], v[32:35], v251, v250 op_sel_hi:[0,0,0]
	s_barrier
	ds_read_b128 v[24:27], v252
	ds_read_b128 v[28:31], v252 offset:1024
	ds_read_b128 v[16:19], v252 offset:2048
	ds_read_b128 v[20:23], v252 offset:3072
	ds_read_b128 v[8:11], v253
	ds_read_b128 v[12:15], v253 offset:1024
	ds_read_b128 v[0:3], v253 offset:2048
	ds_read_b128 v[4:7], v253 offset:3072
	ds_read_b128 v[162:165], v249 offset:32768
	ds_read_b128 v[166:169], v249 offset:33792
	ds_read_b128 v[170:173], v249 offset:34816
	ds_read_b128 v[174:177], v249 offset:35840
	ds_read_b128 v[178:181], v249 offset:36864
	ds_read_b128 v[182:185], v249 offset:37888
	ds_read_b128 v[186:189], v249 offset:38912
	ds_read_b128 v[190:193], v249 offset:39936
	s_add_u32 s42, s80, 0x100
	s_addc_u32 s43, s81, 0
	s_add_u32 s80, s82, 0x100
	s_mov_b32 m0, s59
	s_nop 0
	global_load_lds_dwordx4 v160, s[42:43]
	s_addc_u32 s81, s83, 0
	s_mov_b32 m0, s60
	s_nop 0
	global_load_lds_dwordx4 v160, s[80:81]
	s_waitcnt vmcnt(8)
	s_waitcnt lgkmcnt(0)
	s_barrier
	s_waitcnt lgkmcnt(6)
	v_mfma_scale_f32_16x16x128_f8f6f4 v[156:159], v[24:31], v[162:169], v[156:159], v251, v250 op_sel_hi:[0,0,0]
	v_mfma_scale_f32_16x16x128_f8f6f4 v[152:155], v[16:23], v[162:169], v[152:155], v251, v250 op_sel_hi:[0,0,0]
	s_waitcnt lgkmcnt(4)
	v_mfma_scale_f32_16x16x128_f8f6f4 v[148:151], v[24:31], v[170:177], v[148:151], v251, v250 op_sel_hi:[0,0,0]
	v_mfma_scale_f32_16x16x128_f8f6f4 v[144:147], v[16:23], v[170:177], v[144:147], v251, v250 op_sel_hi:[0,0,0]
	s_waitcnt lgkmcnt(2)
	v_mfma_scale_f32_16x16x128_f8f6f4 v[140:143], v[24:31], v[178:185], v[140:143], v251, v250 op_sel_hi:[0,0,0]
	v_mfma_scale_f32_16x16x128_f8f6f4 v[136:139], v[16:23], v[178:185], v[136:139], v251, v250 op_sel_hi:[0,0,0]
	s_waitcnt lgkmcnt(0)
	v_mfma_scale_f32_16x16x128_f8f6f4 v[132:135], v[24:31], v[186:193], v[132:135], v251, v250 op_sel_hi:[0,0,0]
	v_mfma_scale_f32_16x16x128_f8f6f4 v[128:131], v[16:23], v[186:193], v[128:131], v251, v250 op_sel_hi:[0,0,0]
	v_mfma_scale_f32_16x16x128_f8f6f4 v[124:127], v[8:15], v[162:169], v[124:127], v251, v250 op_sel_hi:[0,0,0]
	v_mfma_scale_f32_16x16x128_f8f6f4 v[120:123], v[0:7], v[162:169], v[120:123], v251, v250 op_sel_hi:[0,0,0]
	v_mfma_scale_f32_16x16x128_f8f6f4 v[116:119], v[8:15], v[170:177], v[116:119], v251, v250 op_sel_hi:[0,0,0]
	v_mfma_scale_f32_16x16x128_f8f6f4 v[112:115], v[0:7], v[170:177], v[112:115], v251, v250 op_sel_hi:[0,0,0]
	v_mfma_scale_f32_16x16x128_f8f6f4 v[108:111], v[8:15], v[178:185], v[108:111], v251, v250 op_sel_hi:[0,0,0]
	v_mfma_scale_f32_16x16x128_f8f6f4 v[104:107], v[0:7], v[178:185], v[104:107], v251, v250 op_sel_hi:[0,0,0]
	v_mfma_scale_f32_16x16x128_f8f6f4 v[100:103], v[8:15], v[186:193], v[100:103], v251, v250 op_sel_hi:[0,0,0]
	v_mfma_scale_f32_16x16x128_f8f6f4 v[96:99], v[0:7], v[186:193], v[96:99], v251, v250 op_sel_hi:[0,0,0]
	s_barrier
	s_add_u32 s42, s84, 0x180
	s_addc_u32 s43, s85, 0
	ds_read_b128 v[162:165], v249 offset:49152
	ds_read_b128 v[166:169], v249 offset:50176
	ds_read_b128 v[170:173], v249 offset:51200
	ds_read_b128 v[174:177], v249 offset:52224
	ds_read_b128 v[178:181], v249 offset:53248
	ds_read_b128 v[182:185], v249 offset:54272
	ds_read_b128 v[186:189], v249 offset:55296
	ds_read_b128 v[190:193], v249 offset:56320
	s_add_u32 s80, s86, 0x180
	s_mov_b32 m0, s61
	s_nop 0
	global_load_lds_dwordx4 v161, s[42:43]
	s_addc_u32 s81, s87, 0
	s_mov_b32 m0, s62
	s_nop 0
	global_load_lds_dwordx4 v161, s[80:81]
	s_add_u32 s42, s88, 0x180
	s_addc_u32 s43, s89, 0
	s_add_u32 s80, s92, 0x180
	s_mov_b32 m0, s65
	s_nop 0
	global_load_lds_dwordx4 v161, s[42:43]
	s_addc_u32 s81, s93, 0
	s_mov_b32 m0, s66
	s_nop 0
	global_load_lds_dwordx4 v161, s[80:81]
	s_add_u32 s42, s75, 0x180
	s_addc_u32 s43, s77, 0
	s_add_u32 s80, s90, 0x180
	s_mov_b32 m0, s63
	s_nop 0
	global_load_lds_dwordx4 v160, s[42:43]
	s_addc_u32 s81, s91, 0
	s_mov_b32 m0, s64
	s_nop 0
	global_load_lds_dwordx4 v160, s[80:81]
	s_waitcnt vmcnt(8)
	s_waitcnt lgkmcnt(0)
	s_barrier
	s_waitcnt lgkmcnt(6)
	v_mfma_scale_f32_16x16x128_f8f6f4 v[92:95], v[24:31], v[162:169], v[92:95], v251, v250 op_sel_hi:[0,0,0]
	v_mfma_scale_f32_16x16x128_f8f6f4 v[88:91], v[16:23], v[162:169], v[88:91], v251, v250 op_sel_hi:[0,0,0]
	s_waitcnt lgkmcnt(4)
	v_mfma_scale_f32_16x16x128_f8f6f4 v[84:87], v[24:31], v[170:177], v[84:87], v251, v250 op_sel_hi:[0,0,0]
	v_mfma_scale_f32_16x16x128_f8f6f4 v[80:83], v[16:23], v[170:177], v[80:83], v251, v250 op_sel_hi:[0,0,0]
	s_waitcnt lgkmcnt(2)
	v_mfma_scale_f32_16x16x128_f8f6f4 v[76:79], v[24:31], v[178:185], v[76:79], v251, v250 op_sel_hi:[0,0,0]
	v_mfma_scale_f32_16x16x128_f8f6f4 v[72:75], v[16:23], v[178:185], v[72:75], v251, v250 op_sel_hi:[0,0,0]
	s_waitcnt lgkmcnt(0)
	v_mfma_scale_f32_16x16x128_f8f6f4 v[68:71], v[24:31], v[186:193], v[68:71], v251, v250 op_sel_hi:[0,0,0]
	v_mfma_scale_f32_16x16x128_f8f6f4 v[64:67], v[16:23], v[186:193], v[64:67], v251, v250 op_sel_hi:[0,0,0]
	v_mfma_scale_f32_16x16x128_f8f6f4 v[60:63], v[8:15], v[162:169], v[60:63], v251, v250 op_sel_hi:[0,0,0]
	v_mfma_scale_f32_16x16x128_f8f6f4 v[56:59], v[0:7], v[162:169], v[56:59], v251, v250 op_sel_hi:[0,0,0]
	v_mfma_scale_f32_16x16x128_f8f6f4 v[52:55], v[8:15], v[170:177], v[52:55], v251, v250 op_sel_hi:[0,0,0]
	v_mfma_scale_f32_16x16x128_f8f6f4 v[48:51], v[0:7], v[170:177], v[48:51], v251, v250 op_sel_hi:[0,0,0]
	v_mfma_scale_f32_16x16x128_f8f6f4 v[44:47], v[8:15], v[178:185], v[44:47], v251, v250 op_sel_hi:[0,0,0]
	v_mfma_scale_f32_16x16x128_f8f6f4 v[40:43], v[0:7], v[178:185], v[40:43], v251, v250 op_sel_hi:[0,0,0]
	v_mfma_scale_f32_16x16x128_f8f6f4 v[36:39], v[8:15], v[186:193], v[36:39], v251, v250 op_sel_hi:[0,0,0]
	v_mfma_scale_f32_16x16x128_f8f6f4 v[32:35], v[0:7], v[186:193], v[32:35], v251, v250 op_sel_hi:[0,0,0]
	s_barrier
	s_add_u32 s40, s40, 0x100
	s_addc_u32 s41, s41, 0
	s_cmp_ge_i32 s74, s2
	s_cbranch_scc0 .LBB0_469

.LBB0_472:
	ds_read_b128 v[24:27], v194
	ds_read_b128 v[28:31], v194 offset:1024
	ds_read_b128 v[16:19], v194 offset:2048
	ds_read_b128 v[20:23], v194 offset:3072
	ds_read_b128 v[8:11], v248
	ds_read_b128 v[12:15], v248 offset:1024
	ds_read_b128 v[0:3], v248 offset:2048
	ds_read_b128 v[4:7], v248 offset:3072
	s_ashr_i32 s3, s24, 31
	s_mov_b32 s2, s24
	s_lshl_b64 s[2:3], s[2:3], 7
	s_add_u32 s2, s4, s2
	ds_read_b128 v[162:165], v249
	ds_read_b128 v[166:169], v249 offset:1024
	ds_read_b128 v[170:173], v249 offset:2048
	ds_read_b128 v[174:177], v249 offset:3072
	ds_read_b128 v[228:231], v249 offset:4096
	ds_read_b128 v[232:235], v249 offset:5120
	ds_read_b128 v[236:239], v249 offset:6144
	ds_read_b128 v[240:243], v249 offset:7168
	s_addc_u32 s3, s5, s3
	s_add_u32 s2, s2, s38
	s_addc_u32 s3, s3, s39
	s_add_u32 s2, s2, 0xffffff80
	s_addc_u32 s3, s3, -1
	s_add_u32 s4, s2, s36
	s_mov_b32 m0, s67
	s_nop 0
	global_load_lds_dwordx4 v160, s[2:3]
	s_addc_u32 s5, s3, s37
	s_mov_b32 m0, s73
	s_nop 0
	global_load_lds_dwordx4 v160, s[4:5]
	s_waitcnt vmcnt(8)
	s_waitcnt lgkmcnt(0)
	s_barrier
	s_waitcnt lgkmcnt(6)
	v_mfma_scale_f32_16x16x128_f8f6f4 v[180:183], v[24:31], v[162:169], v[156:159], v251, v250 op_sel_hi:[0,0,0]
	v_mfma_scale_f32_16x16x128_f8f6f4 v[184:187], v[16:23], v[162:169], v[152:155], v251, v250 op_sel_hi:[0,0,0]
	s_waitcnt lgkmcnt(4)
	v_mfma_scale_f32_16x16x128_f8f6f4 v[188:191], v[24:31], v[170:177], v[148:151], v251, v250 op_sel_hi:[0,0,0]
	v_mfma_scale_f32_16x16x128_f8f6f4 v[144:147], v[16:23], v[170:177], v[144:147], v251, v250 op_sel_hi:[0,0,0]
	s_waitcnt lgkmcnt(2)
	v_mfma_scale_f32_16x16x128_f8f6f4 v[196:199], v[24:31], v[228:235], v[140:143], v251, v250 op_sel_hi:[0,0,0]
	v_mfma_scale_f32_16x16x128_f8f6f4 v[200:203], v[16:23], v[228:235], v[136:139], v251, v250 op_sel_hi:[0,0,0]
	s_waitcnt lgkmcnt(0)
	v_mfma_scale_f32_16x16x128_f8f6f4 v[204:207], v[24:31], v[236:243], v[132:135], v251, v250 op_sel_hi:[0,0,0]
	v_mfma_scale_f32_16x16x128_f8f6f4 v[208:211], v[16:23], v[236:243], v[128:131], v251, v250 op_sel_hi:[0,0,0]
	v_mfma_scale_f32_16x16x128_f8f6f4 v[212:215], v[8:15], v[162:169], v[124:127], v251, v250 op_sel_hi:[0,0,0]
	v_mfma_scale_f32_16x16x128_f8f6f4 v[216:219], v[0:7], v[162:169], v[120:123], v251, v250 op_sel_hi:[0,0,0]
	v_mfma_scale_f32_16x16x128_f8f6f4 v[116:119], v[8:15], v[170:177], v[116:119], v251, v250 op_sel_hi:[0,0,0]
	v_mfma_scale_f32_16x16x128_f8f6f4 v[220:223], v[0:7], v[170:177], v[112:115], v251, v250 op_sel_hi:[0,0,0]
	v_mfma_scale_f32_16x16x128_f8f6f4 v[224:227], v[8:15], v[228:235], v[108:111], v251, v250 op_sel_hi:[0,0,0]
	v_mfma_scale_f32_16x16x128_f8f6f4 v[228:231], v[0:7], v[228:235], v[104:107], v251, v250 op_sel_hi:[0,0,0]
	v_mfma_scale_f32_16x16x128_f8f6f4 v[232:235], v[8:15], v[236:243], v[100:103], v251, v250 op_sel_hi:[0,0,0]
	v_mfma_scale_f32_16x16x128_f8f6f4 v[236:239], v[0:7], v[236:243], v[96:99], v251, v250 op_sel_hi:[0,0,0]
	s_barrier
	s_add_u32 s36, s6, s18
	s_nop 3
	ds_read_b128 v[96:99], v249 offset:16384
	ds_read_b128 v[100:103], v249 offset:17408
	ds_read_b128 v[104:107], v249 offset:18432
	ds_read_b128 v[108:111], v249 offset:19456
	ds_read_b128 v[168:171], v249 offset:20480
	ds_read_b128 v[172:175], v249 offset:21504
	ds_read_b128 v[240:243], v249 offset:22528
	ds_read_b128 v[244:247], v249 offset:23552
	s_addc_u32 s37, s7, s19
	s_mov_b32 m0, s51
	s_nop 0
	global_load_lds_dwordx4 v193, s[6:7]
	s_add_u32 s38, s6, s22
	s_mov_b32 m0, s55
	s_nop 0
	global_load_lds_dwordx4 v193, s[36:37]
	s_addc_u32 s39, s7, s23
	s_add_u32 s46, s38, s18
	s_mov_b32 m0, s56
	s_nop 0
	global_load_lds_dwordx4 v193, s[38:39]
	s_addc_u32 s47, s39, s19
	s_mov_b32 m0, s57
	s_nop 0
	global_load_lds_dwordx4 v193, s[46:47]
	s_add_u32 s4, s44, s42
	s_mov_b32 m0, s54
	s_nop 0
	global_load_lds_dwordx4 v192, s[44:45]
	s_addc_u32 s5, s45, s43
	s_mov_b32 m0, s58
	s_nop 0
	global_load_lds_dwordx4 v192, s[4:5]
	s_waitcnt vmcnt(8)
	s_waitcnt lgkmcnt(0)
	s_barrier
	s_waitcnt lgkmcnt(6)
	v_mfma_scale_f32_16x16x128_f8f6f4 v[124:127], v[24:31], v[96:103], v[92:95], v251, v250 op_sel_hi:[0,0,0]
	v_mfma_scale_f32_16x16x128_f8f6f4 v[128:131], v[16:23], v[96:103], v[88:91], v251, v250 op_sel_hi:[0,0,0]
	s_waitcnt lgkmcnt(4)
	v_mfma_scale_f32_16x16x128_f8f6f4 v[132:135], v[24:31], v[104:111], v[84:87], v251, v250 op_sel_hi:[0,0,0]
	v_mfma_scale_f32_16x16x128_f8f6f4 v[136:139], v[16:23], v[104:111], v[80:83], v251, v250 op_sel_hi:[0,0,0]
	s_waitcnt lgkmcnt(2)
	v_mfma_scale_f32_16x16x128_f8f6f4 v[76:79], v[24:31], v[168:175], v[76:79], v251, v250 op_sel_hi:[0,0,0]
	v_mfma_scale_f32_16x16x128_f8f6f4 v[140:143], v[16:23], v[168:175], v[72:75], v251, v250 op_sel_hi:[0,0,0]
	s_waitcnt lgkmcnt(0)
	v_mfma_scale_f32_16x16x128_f8f6f4 v[68:71], v[24:31], v[240:247], v[68:71], v251, v250 op_sel_hi:[0,0,0]
	v_mfma_scale_f32_16x16x128_f8f6f4 v[148:151], v[16:23], v[240:247], v[64:67], v251, v250 op_sel_hi:[0,0,0]
	v_mfma_scale_f32_16x16x128_f8f6f4 v[60:63], v[8:15], v[96:103], v[60:63], v251, v250 op_sel_hi:[0,0,0]
	v_mfma_scale_f32_16x16x128_f8f6f4 v[152:155], v[0:7], v[96:103], v[56:59], v251, v250 op_sel_hi:[0,0,0]
	v_mfma_scale_f32_16x16x128_f8f6f4 v[156:159], v[8:15], v[104:111], v[52:55], v251, v250 op_sel_hi:[0,0,0]
	v_mfma_scale_f32_16x16x128_f8f6f4 v[160:163], v[0:7], v[104:111], v[48:51], v251, v250 op_sel_hi:[0,0,0]
	v_mfma_scale_f32_16x16x128_f8f6f4 v[164:167], v[8:15], v[168:175], v[44:47], v251, v250 op_sel_hi:[0,0,0]
	v_mfma_scale_f32_16x16x128_f8f6f4 v[168:171], v[0:7], v[168:175], v[40:43], v251, v250 op_sel_hi:[0,0,0]
	v_mfma_scale_f32_16x16x128_f8f6f4 v[172:175], v[8:15], v[240:247], v[36:39], v251, v250 op_sel_hi:[0,0,0]
	v_mfma_scale_f32_16x16x128_f8f6f4 v[176:179], v[0:7], v[240:247], v[32:35], v251, v250 op_sel_hi:[0,0,0]
	s_barrier
	ds_read_b128 v[24:27], v252
	ds_read_b128 v[28:31], v252 offset:1024
	ds_read_b128 v[16:19], v252 offset:2048
	ds_read_b128 v[20:23], v252 offset:3072
	ds_read_b128 v[8:11], v253
	ds_read_b128 v[12:15], v253 offset:1024
	ds_read_b128 v[0:3], v253 offset:2048
	ds_read_b128 v[4:7], v253 offset:3072
	ds_read_b128 v[32:35], v249 offset:32768
	ds_read_b128 v[36:39], v249 offset:33792
	ds_read_b128 v[40:43], v249 offset:34816
	ds_read_b128 v[44:47], v249 offset:35840
	ds_read_b128 v[48:51], v249 offset:36864
	ds_read_b128 v[52:55], v249 offset:37888
	ds_read_b128 v[80:83], v249 offset:38912
	ds_read_b128 v[84:87], v249 offset:39936
	s_add_u32 s2, s44, s40
	s_addc_u32 s3, s45, s41
	s_add_u32 s68, s2, s42
	s_mov_b32 m0, s59
	s_nop 0
	global_load_lds_dwordx4 v192, s[2:3]
	s_addc_u32 s69, s3, s43
	s_mov_b32 m0, s60
	s_nop 0
	global_load_lds_dwordx4 v192, s[68:69]
	s_waitcnt vmcnt(8)
	s_waitcnt lgkmcnt(0)
	s_barrier
	s_waitcnt lgkmcnt(6)
	v_mfma_scale_f32_16x16x128_f8f6f4 v[240:243], v[24:31], v[32:39], v[180:183], v251, v250 op_sel_hi:[0,0,0]
	v_mfma_scale_f32_16x16x128_f8f6f4 v[120:123], v[16:23], v[32:39], v[184:187], v251, v250 op_sel_hi:[0,0,0]
	s_waitcnt lgkmcnt(4)
	v_mfma_scale_f32_16x16x128_f8f6f4 v[112:115], v[24:31], v[40:47], v[188:191], v251, v250 op_sel_hi:[0,0,0]
	v_mfma_scale_f32_16x16x128_f8f6f4 v[104:107], v[16:23], v[40:47], v[144:147], v251, v250 op_sel_hi:[0,0,0]
	s_waitcnt lgkmcnt(2)
	v_mfma_scale_f32_16x16x128_f8f6f4 v[100:103], v[24:31], v[48:55], v[196:199], v251, v250 op_sel_hi:[0,0,0]
	v_mfma_scale_f32_16x16x128_f8f6f4 v[92:95], v[16:23], v[48:55], v[200:203], v251, v250 op_sel_hi:[0,0,0]
	s_waitcnt lgkmcnt(0)
	v_mfma_scale_f32_16x16x128_f8f6f4 v[188:191], v[24:31], v[80:87], v[204:207], v251, v250 op_sel_hi:[0,0,0]
	v_mfma_scale_f32_16x16x128_f8f6f4 v[144:147], v[16:23], v[80:87], v[208:211], v251, v250 op_sel_hi:[0,0,0]
	v_mfma_scale_f32_16x16x128_f8f6f4 v[184:187], v[8:15], v[32:39], v[212:215], v251, v250 op_sel_hi:[0,0,0]
	v_mfma_scale_f32_16x16x128_f8f6f4 v[180:183], v[0:7], v[32:39], v[216:219], v251, v250 op_sel_hi:[0,0,0]
	v_mfma_scale_f32_16x16x128_f8f6f4 v[116:119], v[8:15], v[40:47], v[116:119], v251, v250 op_sel_hi:[0,0,0]
	v_mfma_scale_f32_16x16x128_f8f6f4 v[108:111], v[0:7], v[40:47], v[220:223], v251, v250 op_sel_hi:[0,0,0]
	v_mfma_scale_f32_16x16x128_f8f6f4 v[96:99], v[8:15], v[48:55], v[224:227], v251, v250 op_sel_hi:[0,0,0]
	v_mfma_scale_f32_16x16x128_f8f6f4 v[88:91], v[0:7], v[48:55], v[228:231], v251, v250 op_sel_hi:[0,0,0]
	v_mfma_scale_f32_16x16x128_f8f6f4 v[72:75], v[8:15], v[80:87], v[232:235], v251, v250 op_sel_hi:[0,0,0]
	v_mfma_scale_f32_16x16x128_f8f6f4 v[56:59], v[0:7], v[80:87], v[236:239], v251, v250 op_sel_hi:[0,0,0]
	s_barrier
	s_add_u32 s2, s6, 0x80
	s_addc_u32 s3, s7, 0
	ds_read_b128 v[196:199], v249 offset:49152
	ds_read_b128 v[200:203], v249 offset:50176
	ds_read_b128 v[204:207], v249 offset:51200
	ds_read_b128 v[208:211], v249 offset:52224
	ds_read_b128 v[212:215], v249 offset:53248
	ds_read_b128 v[216:219], v249 offset:54272
	ds_read_b128 v[220:223], v249 offset:55296
	ds_read_b128 v[224:227], v249 offset:56320
	s_add_u32 s36, s36, 0x80
	s_mov_b32 m0, s61
	s_nop 0
	global_load_lds_dwordx4 v193, s[2:3]
	s_addc_u32 s37, s37, 0
	s_mov_b32 m0, s62
	s_nop 0
	global_load_lds_dwordx4 v193, s[36:37]
	s_add_u32 s2, s38, 0x80
	s_addc_u32 s3, s39, 0
	s_add_u32 s36, s46, 0x80
	s_mov_b32 m0, s65
	s_nop 0
	global_load_lds_dwordx4 v193, s[2:3]
	s_addc_u32 s37, s47, 0
	s_mov_b32 m0, s66
	s_nop 0
	global_load_lds_dwordx4 v193, s[36:37]
	s_add_u32 s2, s44, 0x80
	s_addc_u32 s3, s45, 0
	s_add_u32 s4, s4, 0x80
	s_mov_b32 m0, s63
	s_nop 0
	global_load_lds_dwordx4 v192, s[2:3]
	s_addc_u32 s5, s5, 0
	s_mov_b32 m0, s64
	s_nop 0
	global_load_lds_dwordx4 v192, s[4:5]
	s_waitcnt vmcnt(8)
	s_waitcnt lgkmcnt(0)
	s_barrier
	s_waitcnt lgkmcnt(6)
	v_mfma_scale_f32_16x16x128_f8f6f4 v[84:87], v[24:31], v[196:203], v[124:127], v251, v250 op_sel_hi:[0,0,0]
	v_mfma_scale_f32_16x16x128_f8f6f4 v[64:67], v[16:23], v[196:203], v[128:131], v251, v250 op_sel_hi:[0,0,0]
	s_waitcnt lgkmcnt(4)
	v_mfma_scale_f32_16x16x128_f8f6f4 v[52:55], v[24:31], v[204:211], v[132:135], v251, v250 op_sel_hi:[0,0,0]
	v_mfma_scale_f32_16x16x128_f8f6f4 v[44:47], v[16:23], v[204:211], v[136:139], v251, v250 op_sel_hi:[0,0,0]
	s_waitcnt lgkmcnt(2)
	v_mfma_scale_f32_16x16x128_f8f6f4 v[36:39], v[24:31], v[212:219], v[76:79], v251, v250 op_sel_hi:[0,0,0]
	v_mfma_scale_f32_16x16x128_f8f6f4 v[32:35], v[16:23], v[212:219], v[140:143], v251, v250 op_sel_hi:[0,0,0]
	s_waitcnt lgkmcnt(0)
	v_mfma_scale_f32_16x16x128_f8f6f4 v[24:27], v[24:31], v[220:227], v[68:71], v251, v250 op_sel_hi:[0,0,0]
	v_mfma_scale_f32_16x16x128_f8f6f4 v[16:19], v[16:23], v[220:227], v[148:151], v251, v250 op_sel_hi:[0,0,0]
	v_mfma_scale_f32_16x16x128_f8f6f4 v[76:79], v[8:15], v[196:203], v[60:63], v251, v250 op_sel_hi:[0,0,0]
	v_mfma_scale_f32_16x16x128_f8f6f4 v[60:63], v[0:7], v[196:203], v[152:155], v251, v250 op_sel_hi:[0,0,0]
	v_mfma_scale_f32_16x16x128_f8f6f4 v[48:51], v[8:15], v[204:211], v[156:159], v251, v250 op_sel_hi:[0,0,0]
	v_mfma_scale_f32_16x16x128_f8f6f4 v[40:43], v[0:7], v[204:211], v[160:163], v251, v250 op_sel_hi:[0,0,0]
	v_mfma_scale_f32_16x16x128_f8f6f4 v[28:31], v[8:15], v[212:219], v[164:167], v251, v250 op_sel_hi:[0,0,0]
	v_mfma_scale_f32_16x16x128_f8f6f4 v[20:23], v[0:7], v[212:219], v[168:171], v251, v250 op_sel_hi:[0,0,0]
	v_mfma_scale_f32_16x16x128_f8f6f4 v[8:11], v[8:15], v[220:227], v[172:175], v251, v250 op_sel_hi:[0,0,0]
	v_mfma_scale_f32_16x16x128_f8f6f4 v[0:3], v[0:7], v[220:227], v[176:179], v251, v250 op_sel_hi:[0,0,0]
	s_barrier
	s_andn2_b64 vcc, exec, s[26:27]
	s_cbranch_vccnz .LBB0_474
	s_barrier

.LBB0_676:
	v_and_b32_e32 v1, 15, v2
	v_or_b32_e32 v3, s3, v1
	s_lshl_b64 s[40:41], s[8:9], 7
	s_lshl_b64 s[22:23], s[22:23], 7
	v_lshlrev_b32_e32 v5, 6, v3
	v_and_b32_e32 v6, 48, v2
	s_movk_i32 s8, 0x3c0
	v_and_or_b32 v5, v5, s8, v6
	s_add_u32 s8, s6, 0x80
	s_addc_u32 s9, s7, 0
	s_sub_u32 s24, 0, s16
	s_subb_u32 s25, 0, s17
	s_add_u32 s24, s10, s24
	s_addc_u32 s25, s11, s25
	s_add_u32 s24, s24, 0x80
	s_mov_b32 s98, 0
	s_cselect_b32 s99, 1, 0
	s_cmp_lt_u32 s76, 4
	s_cbranch_scc0 .Lsprio_7
	s_setprio 1
.Lsprio_7:
	s_cmp_lg_u32 s99, 0
	s_waitcnt vmcnt(2)
	s_barrier
	s_addc_u32 s25, s25, 0
	s_add_i32 s62, s57, 0x18000
	s_mov_b32 m0, s62
	s_nop 0
	global_load_lds_dwordx4 v0, s[8:9]
	s_add_i32 s63, s57, 0x1a000
	s_mov_b32 m0, s63
	s_nop 0
	global_load_lds_dwordx4 v0, s[24:25]
	s_add_u32 s8, s4, 0x80
	s_addc_u32 s9, s5, 0
	s_sub_u32 s24, 0, s38
	s_subb_u32 s25, 0, s39
	s_add_u32 s14, s14, s24
	s_addc_u32 s15, s15, s25
	s_add_u32 s14, s14, 0x80
	s_addc_u32 s15, s15, 0
	s_add_i32 s64, s57, 0x8000
	s_mov_b32 m0, s64
	s_nop 0
	global_load_lds_dwordx4 v128, s[8:9]
	s_add_i32 s65, s57, 0xa000
	s_mov_b32 m0, s65
	s_nop 0
	global_load_lds_dwordx4 v128, s[14:15]
	s_add_u32 s8, s10, 0x80
	s_addc_u32 s9, s11, 0
	s_add_u32 s10, s12, 0x80
	v_ashrrev_i32_e32 v4, 6, v2
	v_lshlrev_b32_e32 v2, 2, v2
	s_addc_u32 s11, s13, 0
	s_add_i32 s66, s57, 0x1c000
	s_mov_b32 m0, s66
	s_nop 0
	global_load_lds_dwordx4 v0, s[8:9]
	v_lshl_add_u32 v7, v4, 10, s50
	v_lshlrev_b32_e32 v3, 2, v3
	v_lshl_or_b32 v1, v1, 6, v6
	v_add_lshl_u32 v4, v4, s51, 10
	v_and_b32_e32 v2, 32, v2
	s_add_i32 s67, s57, 0x1e000
	s_mov_b32 m0, s67
	s_nop 0
	global_load_lds_dwordx4 v0, s[10:11]
	v_and_b32_e32 v3, 32, v3
	v_bitop3_b32 v1, v1, v4, v2 bitop3:0xde
	s_waitcnt vmcnt(6)
	s_add_i32 s68, s57, 0xc000
	s_add_i32 s69, s57, 0xe000
	v_readlane_b32 s8, v254, 0
	v_mov_b32_e32 v129, v0
	v_bitop3_b32 v3, v5, v7, v3 bitop3:0xde
	s_cmpk_lt_u32 s8, 0x100
	v_add_u32_e32 v0, 0, v1
	s_cselect_b64 s[24:25], -1, 0
	s_mov_b32 s27, 0
	v_add_u32_e32 v135, 0x10000, v0
	v_add_u32_e32 v136, 0x14000, v0
	v_add_u32_e32 v137, 0, v3
	v_add_u32_e32 v138, 0x18000, v0
	v_add_u32_e32 v139, 0x1c000, v0
	s_mov_b32 s70, 0
	s_barrier
	s_branch .LBB0_679

.LBB0_681:
	s_cmp_lt_i32 s18, 3
	s_cbranch_scc1 .Lhz_683
	s_add_i32 s26, s18, -2
	s_add_u32 s31, s4, s40
	s_addc_u32 s46, s5, s41
	s_add_u32 s47, s6, s22
	s_addc_u32 s48, s7, s23
	s_add_u32 s42, s16, s22
	s_addc_u32 s43, s17, s23
	s_add_u32 s49, s6, s42
	s_addc_u32 s71, s7, s43
	s_add_u32 s72, s6, s16
	s_addc_u32 s73, s7, s17
	s_add_u32 s42, s38, s40
	s_addc_u32 s43, s39, s41
	s_add_u32 s74, s4, s42
	s_addc_u32 s75, s5, s43
	s_add_u32 s77, s4, s38
	s_addc_u32 s78, s5, s39
	s_mov_b32 s79, 0
	s_mov_b64 s[42:43], 0
	s_cmp_eq_u32 s98, 0
	s_cbranch_scc1 .Lhf_683
	ds_read_b128 v[130:133], v135
	ds_read_b128 v[140:143], v135 offset:1024
	ds_read_b128 v[144:147], v135 offset:2048
	ds_read_b128 v[148:151], v135 offset:3072
	ds_read_b128 v[152:155], v136
	ds_read_b128 v[156:159], v136 offset:1024
	ds_read_b128 v[160:163], v136 offset:2048
	ds_read_b128 v[164:167], v136 offset:3072
	s_add_i32 s79, s79, 2
	s_add_u32 s80, s4, s42
	s_addc_u32 s81, s5, s43
	s_add_u32 s44, s80, 0x100
	s_addc_u32 s45, s81, 0
	s_add_u32 s86, s31, s42
	ds_read_b128 v[168:171], v137
	ds_read_b128 v[172:175], v137 offset:1024
	ds_read_b128 v[176:179], v137 offset:2048
	ds_read_b128 v[180:183], v137 offset:3072
	ds_read_b128 v[184:187], v137 offset:4096
	ds_read_b128 v[188:191], v137 offset:5120
	ds_read_b128 v[192:195], v137 offset:6144
	ds_read_b128 v[196:199], v137 offset:7168
	s_addc_u32 s87, s46, s43
	s_add_u32 s82, s86, 0x80
	s_addc_u32 s83, s87, 0
	s_add_u32 s88, s74, s42
	s_addc_u32 s89, s75, s43
	s_add_u32 s84, s88, 0x80
	s_mov_b32 m0, s68
	s_nop 0
	global_load_lds_dwordx4 v128, s[82:83]
	s_addc_u32 s85, s89, 0
	s_mov_b32 m0, s69
	s_nop 0
	global_load_lds_dwordx4 v128, s[84:85]
	s_waitcnt vmcnt(24)
	s_waitcnt lgkmcnt(0)
	s_barrier
	s_waitcnt lgkmcnt(7)
	v_mfma_f32_16x16x32_bf16 v[124:127], v[130:133], v[168:171], 0
	v_mfma_f32_16x16x32_bf16 v[120:123], v[144:147], v[168:171], 0
	s_waitcnt lgkmcnt(5)
	v_mfma_f32_16x16x32_bf16 v[116:119], v[130:133], v[176:179], 0
	v_mfma_f32_16x16x32_bf16 v[112:115], v[144:147], v[176:179], 0
	s_waitcnt lgkmcnt(3)
	v_mfma_f32_16x16x32_bf16 v[108:111], v[130:133], v[184:187], 0
	v_mfma_f32_16x16x32_bf16 v[104:107], v[144:147], v[184:187], 0
	s_waitcnt lgkmcnt(1)
	v_mfma_f32_16x16x32_bf16 v[100:103], v[130:133], v[192:195], 0
	v_mfma_f32_16x16x32_bf16 v[96:99], v[144:147], v[192:195], 0
	v_mfma_f32_16x16x32_bf16 v[124:127], v[140:143], v[172:175], v[124:127]
	v_mfma_f32_16x16x32_bf16 v[120:123], v[148:151], v[172:175], v[120:123]
	v_mfma_f32_16x16x32_bf16 v[116:119], v[140:143], v[180:183], v[116:119]
	v_mfma_f32_16x16x32_bf16 v[112:115], v[148:151], v[180:183], v[112:115]
	v_mfma_f32_16x16x32_bf16 v[108:111], v[140:143], v[188:191], v[108:111]
	v_mfma_f32_16x16x32_bf16 v[104:107], v[148:151], v[188:191], v[104:107]
	s_waitcnt lgkmcnt(0)
	v_mfma_f32_16x16x32_bf16 v[100:103], v[140:143], v[196:199], v[100:103]
	v_mfma_f32_16x16x32_bf16 v[96:99], v[148:151], v[196:199], v[96:99]
	v_mfma_f32_16x16x32_bf16 v[92:95], v[152:155], v[168:171], 0
	v_mfma_f32_16x16x32_bf16 v[88:91], v[160:163], v[168:171], 0
	v_mfma_f32_16x16x32_bf16 v[84:87], v[152:155], v[176:179], 0
	v_mfma_f32_16x16x32_bf16 v[80:83], v[160:163], v[176:179], 0
	v_mfma_f32_16x16x32_bf16 v[76:79], v[152:155], v[184:187], 0
	v_mfma_f32_16x16x32_bf16 v[72:75], v[160:163], v[184:187], 0
	v_mfma_f32_16x16x32_bf16 v[68:71], v[152:155], v[192:195], 0
	v_mfma_f32_16x16x32_bf16 v[64:67], v[160:163], v[192:195], 0
	v_mfma_f32_16x16x32_bf16 v[92:95], v[156:159], v[172:175], v[92:95]
	v_mfma_f32_16x16x32_bf16 v[88:91], v[164:167], v[172:175], v[88:91]
	v_mfma_f32_16x16x32_bf16 v[84:87], v[156:159], v[180:183], v[84:87]
	v_mfma_f32_16x16x32_bf16 v[80:83], v[164:167], v[180:183], v[80:83]
	v_mfma_f32_16x16x32_bf16 v[76:79], v[156:159], v[188:191], v[76:79]
	v_mfma_f32_16x16x32_bf16 v[72:75], v[164:167], v[188:191], v[72:75]
	v_mfma_f32_16x16x32_bf16 v[68:71], v[156:159], v[196:199], v[68:71]
	v_mfma_f32_16x16x32_bf16 v[64:67], v[164:167], v[196:199], v[64:67]
	s_barrier
	s_add_u32 s90, s6, s42
	s_addc_u32 s91, s7, s43
	s_add_u32 s82, s90, 0x100
	s_addc_u32 s83, s91, 0
	s_add_u32 s92, s72, s42
	s_addc_u32 s93, s73, s43
	s_add_u32 s84, s92, 0x100
	ds_read_b128 v[168:171], v137 offset:16384
	ds_read_b128 v[172:175], v137 offset:17408
	ds_read_b128 v[176:179], v137 offset:18432
	ds_read_b128 v[180:183], v137 offset:19456
	ds_read_b128 v[184:187], v137 offset:20480
	ds_read_b128 v[188:191], v137 offset:21504
	ds_read_b128 v[192:195], v137 offset:22528
	ds_read_b128 v[196:199], v137 offset:23552
	s_addc_u32 s85, s93, 0
	s_mov_b32 m0, s55
	s_nop 0
	global_load_lds_dwordx4 v129, s[82:83]
	s_add_u32 s94, s47, s42
	s_mov_b32 m0, s58
	s_nop 0
	global_load_lds_dwordx4 v129, s[84:85]
	s_addc_u32 s95, s48, s43
	s_add_u32 s82, s94, 0x100
	s_addc_u32 s83, s95, 0
	s_add_u32 s96, s49, s42
	s_addc_u32 s97, s71, s43
	s_add_u32 s84, s96, 0x100
	s_addc_u32 s85, s97, 0
	s_mov_b32 m0, s2
	s_nop 0
	global_load_lds_dwordx4 v129, s[82:83]
	s_mov_b32 m0, s59
	s_nop 0
	global_load_lds_dwordx4 v129, s[84:85]
	s_add_u32 s84, s77, s42
	s_addc_u32 s85, s78, s43
	s_add_u32 s82, s84, 0x100
	s_mov_b32 m0, s57
	s_nop 0
	global_load_lds_dwordx4 v128, s[44:45]
	s_addc_u32 s83, s85, 0
	s_mov_b32 m0, s60
	s_nop 0
	global_load_lds_dwordx4 v128, s[82:83]
	s_waitcnt vmcnt(24)
	s_waitcnt lgkmcnt(0)
	s_barrier
	s_waitcnt lgkmcnt(7)
	v_mfma_f32_16x16x32_bf16 v[60:63], v[130:133], v[168:171], 0
	v_mfma_f32_16x16x32_bf16 v[56:59], v[144:147], v[168:171], 0
	s_waitcnt lgkmcnt(5)
	v_mfma_f32_16x16x32_bf16 v[52:55], v[130:133], v[176:179], 0
	v_mfma_f32_16x16x32_bf16 v[48:51], v[144:147], v[176:179], 0
	s_waitcnt lgkmcnt(3)
	v_mfma_f32_16x16x32_bf16 v[44:47], v[130:133], v[184:187], 0
	v_mfma_f32_16x16x32_bf16 v[40:43], v[144:147], v[184:187], 0
	s_waitcnt lgkmcnt(1)
	v_mfma_f32_16x16x32_bf16 v[36:39], v[130:133], v[192:195], 0
	v_mfma_f32_16x16x32_bf16 v[32:35], v[144:147], v[192:195], 0
	v_mfma_f32_16x16x32_bf16 v[60:63], v[140:143], v[172:175], v[60:63]
	v_mfma_f32_16x16x32_bf16 v[56:59], v[148:151], v[172:175], v[56:59]
	v_mfma_f32_16x16x32_bf16 v[52:55], v[140:143], v[180:183], v[52:55]
	v_mfma_f32_16x16x32_bf16 v[48:51], v[148:151], v[180:183], v[48:51]
	v_mfma_f32_16x16x32_bf16 v[44:47], v[140:143], v[188:191], v[44:47]
	v_mfma_f32_16x16x32_bf16 v[40:43], v[148:151], v[188:191], v[40:43]
	s_waitcnt lgkmcnt(0)
	v_mfma_f32_16x16x32_bf16 v[36:39], v[140:143], v[196:199], v[36:39]
	v_mfma_f32_16x16x32_bf16 v[32:35], v[148:151], v[196:199], v[32:35]
	v_mfma_f32_16x16x32_bf16 v[28:31], v[152:155], v[168:171], 0
	v_mfma_f32_16x16x32_bf16 v[24:27], v[160:163], v[168:171], 0
	v_mfma_f32_16x16x32_bf16 v[20:23], v[152:155], v[176:179], 0
	v_mfma_f32_16x16x32_bf16 v[16:19], v[160:163], v[176:179], 0
	v_mfma_f32_16x16x32_bf16 v[12:15], v[152:155], v[184:187], 0
	v_mfma_f32_16x16x32_bf16 v[8:11], v[160:163], v[184:187], 0
	v_mfma_f32_16x16x32_bf16 v[4:7], v[152:155], v[192:195], 0
	v_mfma_f32_16x16x32_bf16 v[0:3], v[160:163], v[192:195], 0
	v_mfma_f32_16x16x32_bf16 v[28:31], v[156:159], v[172:175], v[28:31]
	v_mfma_f32_16x16x32_bf16 v[24:27], v[164:167], v[172:175], v[24:27]
	v_mfma_f32_16x16x32_bf16 v[20:23], v[156:159], v[180:183], v[20:23]
	v_mfma_f32_16x16x32_bf16 v[16:19], v[164:167], v[180:183], v[16:19]
	v_mfma_f32_16x16x32_bf16 v[12:15], v[156:159], v[188:191], v[12:15]
	v_mfma_f32_16x16x32_bf16 v[8:11], v[164:167], v[188:191], v[8:11]
	v_mfma_f32_16x16x32_bf16 v[4:7], v[156:159], v[196:199], v[4:7]
	v_mfma_f32_16x16x32_bf16 v[0:3], v[164:167], v[196:199], v[0:3]
	s_barrier
	ds_read_b128 v[130:133], v138
	ds_read_b128 v[140:143], v138 offset:1024
	ds_read_b128 v[144:147], v138 offset:2048
	ds_read_b128 v[148:151], v138 offset:3072
	ds_read_b128 v[152:155], v139
	ds_read_b128 v[156:159], v139 offset:1024
	ds_read_b128 v[160:163], v139 offset:2048
	ds_read_b128 v[164:167], v139 offset:3072
	ds_read_b128 v[168:171], v137 offset:32768
	ds_read_b128 v[172:175], v137 offset:33792
	ds_read_b128 v[176:179], v137 offset:34816
	ds_read_b128 v[180:183], v137 offset:35840
	ds_read_b128 v[184:187], v137 offset:36864
	ds_read_b128 v[188:191], v137 offset:37888
	ds_read_b128 v[192:195], v137 offset:38912
	ds_read_b128 v[196:199], v137 offset:39936
	s_add_u32 s44, s86, 0x100
	s_addc_u32 s45, s87, 0
	s_add_u32 s82, s88, 0x100
	s_mov_b32 m0, s33
	s_nop 0
	global_load_lds_dwordx4 v128, s[44:45]
	s_addc_u32 s83, s89, 0
	s_mov_b32 m0, s61
	s_nop 0
	global_load_lds_dwordx4 v128, s[82:83]
	s_waitcnt vmcnt(8)
	s_waitcnt lgkmcnt(0)
	s_barrier
	s_waitcnt lgkmcnt(7)
	v_mfma_f32_16x16x32_bf16 v[124:127], v[130:133], v[168:171], v[124:127]
	v_mfma_f32_16x16x32_bf16 v[120:123], v[144:147], v[168:171], v[120:123]
	s_waitcnt lgkmcnt(5)
	v_mfma_f32_16x16x32_bf16 v[116:119], v[130:133], v[176:179], v[116:119]
	v_mfma_f32_16x16x32_bf16 v[112:115], v[144:147], v[176:179], v[112:115]
	s_waitcnt lgkmcnt(3)
	v_mfma_f32_16x16x32_bf16 v[108:111], v[130:133], v[184:187], v[108:111]
	v_mfma_f32_16x16x32_bf16 v[104:107], v[144:147], v[184:187], v[104:107]
	s_waitcnt lgkmcnt(1)
	v_mfma_f32_16x16x32_bf16 v[100:103], v[130:133], v[192:195], v[100:103]
	v_mfma_f32_16x16x32_bf16 v[96:99], v[144:147], v[192:195], v[96:99]
	v_mfma_f32_16x16x32_bf16 v[124:127], v[140:143], v[172:175], v[124:127]
	v_mfma_f32_16x16x32_bf16 v[120:123], v[148:151], v[172:175], v[120:123]
	v_mfma_f32_16x16x32_bf16 v[116:119], v[140:143], v[180:183], v[116:119]
	v_mfma_f32_16x16x32_bf16 v[112:115], v[148:151], v[180:183], v[112:115]
	v_mfma_f32_16x16x32_bf16 v[108:111], v[140:143], v[188:191], v[108:111]
	v_mfma_f32_16x16x32_bf16 v[104:107], v[148:151], v[188:191], v[104:107]
	s_waitcnt lgkmcnt(0)
	v_mfma_f32_16x16x32_bf16 v[100:103], v[140:143], v[196:199], v[100:103]
	v_mfma_f32_16x16x32_bf16 v[96:99], v[148:151], v[196:199], v[96:99]
	v_mfma_f32_16x16x32_bf16 v[92:95], v[152:155], v[168:171], v[92:95]
	v_mfma_f32_16x16x32_bf16 v[88:91], v[160:163], v[168:171], v[88:91]
	v_mfma_f32_16x16x32_bf16 v[84:87], v[152:155], v[176:179], v[84:87]
	v_mfma_f32_16x16x32_bf16 v[80:83], v[160:163], v[176:179], v[80:83]
	v_mfma_f32_16x16x32_bf16 v[76:79], v[152:155], v[184:187], v[76:79]
	v_mfma_f32_16x16x32_bf16 v[72:75], v[160:163], v[184:187], v[72:75]
	v_mfma_f32_16x16x32_bf16 v[68:71], v[152:155], v[192:195], v[68:71]
	v_mfma_f32_16x16x32_bf16 v[64:67], v[160:163], v[192:195], v[64:67]
	v_mfma_f32_16x16x32_bf16 v[92:95], v[156:159], v[172:175], v[92:95]
	v_mfma_f32_16x16x32_bf16 v[88:91], v[164:167], v[172:175], v[88:91]
	v_mfma_f32_16x16x32_bf16 v[84:87], v[156:159], v[180:183], v[84:87]
	v_mfma_f32_16x16x32_bf16 v[80:83], v[164:167], v[180:183], v[80:83]
	v_mfma_f32_16x16x32_bf16 v[76:79], v[156:159], v[188:191], v[76:79]
	v_mfma_f32_16x16x32_bf16 v[72:75], v[164:167], v[188:191], v[72:75]
	v_mfma_f32_16x16x32_bf16 v[68:71], v[156:159], v[196:199], v[68:71]
	v_mfma_f32_16x16x32_bf16 v[64:67], v[164:167], v[196:199], v[64:67]
	s_barrier
	s_add_u32 s44, s90, 0x180
	s_addc_u32 s45, s91, 0
	ds_read_b128 v[168:171], v137 offset:49152
	ds_read_b128 v[172:175], v137 offset:50176
	ds_read_b128 v[176:179], v137 offset:51200
	ds_read_b128 v[180:183], v137 offset:52224
	ds_read_b128 v[184:187], v137 offset:53248
	ds_read_b128 v[188:191], v137 offset:54272
	ds_read_b128 v[192:195], v137 offset:55296
	ds_read_b128 v[196:199], v137 offset:56320
	s_add_u32 s82, s92, 0x180
	s_mov_b32 m0, s62
	s_nop 0
	global_load_lds_dwordx4 v129, s[44:45]
	s_addc_u32 s83, s93, 0
	s_mov_b32 m0, s63
	s_nop 0
	global_load_lds_dwordx4 v129, s[82:83]
	s_add_u32 s44, s94, 0x180
	s_addc_u32 s45, s95, 0
	s_add_u32 s82, s96, 0x180
	s_mov_b32 m0, s66
	s_nop 0
	global_load_lds_dwordx4 v129, s[44:45]
	s_addc_u32 s83, s97, 0
	s_mov_b32 m0, s67
	s_nop 0
	global_load_lds_dwordx4 v129, s[82:83]
	s_add_u32 s44, s80, 0x180
	s_addc_u32 s45, s81, 0
	s_add_u32 s80, s84, 0x180
	s_mov_b32 m0, s64
	s_nop 0
	global_load_lds_dwordx4 v128, s[44:45]
	s_addc_u32 s81, s85, 0
	s_mov_b32 m0, s65
	s_nop 0
	global_load_lds_dwordx4 v128, s[80:81]
	s_waitcnt vmcnt(8)
	s_waitcnt lgkmcnt(0)
	s_barrier
	s_waitcnt lgkmcnt(7)
	v_mfma_f32_16x16x32_bf16 v[60:63], v[130:133], v[168:171], v[60:63]
	v_mfma_f32_16x16x32_bf16 v[56:59], v[144:147], v[168:171], v[56:59]
	s_waitcnt lgkmcnt(5)
	v_mfma_f32_16x16x32_bf16 v[52:55], v[130:133], v[176:179], v[52:55]
	v_mfma_f32_16x16x32_bf16 v[48:51], v[144:147], v[176:179], v[48:51]
	s_waitcnt lgkmcnt(3)
	v_mfma_f32_16x16x32_bf16 v[44:47], v[130:133], v[184:187], v[44:47]
	v_mfma_f32_16x16x32_bf16 v[40:43], v[144:147], v[184:187], v[40:43]
	s_waitcnt lgkmcnt(1)
	v_mfma_f32_16x16x32_bf16 v[36:39], v[130:133], v[192:195], v[36:39]
	v_mfma_f32_16x16x32_bf16 v[32:35], v[144:147], v[192:195], v[32:35]
	v_mfma_f32_16x16x32_bf16 v[60:63], v[140:143], v[172:175], v[60:63]
	v_mfma_f32_16x16x32_bf16 v[56:59], v[148:151], v[172:175], v[56:59]
	v_mfma_f32_16x16x32_bf16 v[52:55], v[140:143], v[180:183], v[52:55]
	v_mfma_f32_16x16x32_bf16 v[48:51], v[148:151], v[180:183], v[48:51]
	v_mfma_f32_16x16x32_bf16 v[44:47], v[140:143], v[188:191], v[44:47]
	v_mfma_f32_16x16x32_bf16 v[40:43], v[148:151], v[188:191], v[40:43]
	s_waitcnt lgkmcnt(0)
	v_mfma_f32_16x16x32_bf16 v[36:39], v[140:143], v[196:199], v[36:39]
	v_mfma_f32_16x16x32_bf16 v[32:35], v[148:151], v[196:199], v[32:35]
	v_mfma_f32_16x16x32_bf16 v[28:31], v[152:155], v[168:171], v[28:31]
	v_mfma_f32_16x16x32_bf16 v[24:27], v[160:163], v[168:171], v[24:27]
	v_mfma_f32_16x16x32_bf16 v[20:23], v[152:155], v[176:179], v[20:23]
	v_mfma_f32_16x16x32_bf16 v[16:19], v[160:163], v[176:179], v[16:19]
	v_mfma_f32_16x16x32_bf16 v[12:15], v[152:155], v[184:187], v[12:15]
	v_mfma_f32_16x16x32_bf16 v[8:11], v[160:163], v[184:187], v[8:11]
	v_mfma_f32_16x16x32_bf16 v[4:7], v[152:155], v[192:195], v[4:7]
	v_mfma_f32_16x16x32_bf16 v[0:3], v[160:163], v[192:195], v[0:3]
	v_mfma_f32_16x16x32_bf16 v[28:31], v[156:159], v[172:175], v[28:31]
	v_mfma_f32_16x16x32_bf16 v[24:27], v[164:167], v[172:175], v[24:27]
	v_mfma_f32_16x16x32_bf16 v[20:23], v[156:159], v[180:183], v[20:23]
	v_mfma_f32_16x16x32_bf16 v[16:19], v[164:167], v[180:183], v[16:19]
	v_mfma_f32_16x16x32_bf16 v[12:15], v[156:159], v[188:191], v[12:15]
	v_mfma_f32_16x16x32_bf16 v[8:11], v[164:167], v[188:191], v[8:11]
	v_mfma_f32_16x16x32_bf16 v[4:7], v[156:159], v[196:199], v[4:7]
	v_mfma_f32_16x16x32_bf16 v[0:3], v[164:167], v[196:199], v[0:3]
	s_barrier
	s_add_u32 s42, s42, 0x100
	s_addc_u32 s43, s43, 0
	s_cmp_ge_i32 s79, s26
	s_cbranch_scc0 .LBB0_683
	s_branch .LBB0_684
.Lhf_683:
	ds_read_b128 v[130:133], v135
	ds_read_b128 v[140:143], v135 offset:1024
	ds_read_b128 v[144:147], v135 offset:2048
	ds_read_b128 v[148:151], v135 offset:3072
	ds_read_b128 v[152:155], v136
	ds_read_b128 v[156:159], v136 offset:1024
	ds_read_b128 v[160:163], v136 offset:2048
	ds_read_b128 v[164:167], v136 offset:3072
	s_add_i32 s79, s79, 2
	s_add_u32 s80, s4, s42
	s_addc_u32 s81, s5, s43
	s_add_u32 s44, s80, 0x100
	s_addc_u32 s45, s81, 0
	s_add_u32 s86, s31, s42
	ds_read_b128 v[168:171], v137
	ds_read_b128 v[172:175], v137 offset:1024
	ds_read_b128 v[176:179], v137 offset:2048
	ds_read_b128 v[180:183], v137 offset:3072
	ds_read_b128 v[184:187], v137 offset:4096
	ds_read_b128 v[188:191], v137 offset:5120
	ds_read_b128 v[192:195], v137 offset:6144
	ds_read_b128 v[196:199], v137 offset:7168
	s_addc_u32 s87, s46, s43
	s_add_u32 s82, s86, 0x80
	s_addc_u32 s83, s87, 0
	s_add_u32 s88, s74, s42
	s_addc_u32 s89, s75, s43
	s_add_u32 s84, s88, 0x80
	s_mov_b32 m0, s68
	s_nop 0
	global_load_lds_dwordx4 v128, s[82:83]
	s_addc_u32 s85, s89, 0
	s_mov_b32 m0, s69
	s_nop 0
	global_load_lds_dwordx4 v128, s[84:85]
	s_waitcnt vmcnt(8)
	s_waitcnt lgkmcnt(0)
	s_barrier
	s_waitcnt lgkmcnt(7)
	v_mfma_f32_16x16x32_bf16 v[124:127], v[130:133], v[168:171], 0
	v_mfma_f32_16x16x32_bf16 v[120:123], v[144:147], v[168:171], 0
	s_waitcnt lgkmcnt(5)
	v_mfma_f32_16x16x32_bf16 v[116:119], v[130:133], v[176:179], 0
	v_mfma_f32_16x16x32_bf16 v[112:115], v[144:147], v[176:179], 0
	s_waitcnt lgkmcnt(3)
	v_mfma_f32_16x16x32_bf16 v[108:111], v[130:133], v[184:187], 0
	v_mfma_f32_16x16x32_bf16 v[104:107], v[144:147], v[184:187], 0
	s_waitcnt lgkmcnt(1)
	v_mfma_f32_16x16x32_bf16 v[100:103], v[130:133], v[192:195], 0
	v_mfma_f32_16x16x32_bf16 v[96:99], v[144:147], v[192:195], 0
	v_mfma_f32_16x16x32_bf16 v[124:127], v[140:143], v[172:175], v[124:127]
	v_mfma_f32_16x16x32_bf16 v[120:123], v[148:151], v[172:175], v[120:123]
	v_mfma_f32_16x16x32_bf16 v[116:119], v[140:143], v[180:183], v[116:119]
	v_mfma_f32_16x16x32_bf16 v[112:115], v[148:151], v[180:183], v[112:115]
	v_mfma_f32_16x16x32_bf16 v[108:111], v[140:143], v[188:191], v[108:111]
	v_mfma_f32_16x16x32_bf16 v[104:107], v[148:151], v[188:191], v[104:107]
	s_waitcnt lgkmcnt(0)
	v_mfma_f32_16x16x32_bf16 v[100:103], v[140:143], v[196:199], v[100:103]
	v_mfma_f32_16x16x32_bf16 v[96:99], v[148:151], v[196:199], v[96:99]
	v_mfma_f32_16x16x32_bf16 v[92:95], v[152:155], v[168:171], 0
	v_mfma_f32_16x16x32_bf16 v[88:91], v[160:163], v[168:171], 0
	v_mfma_f32_16x16x32_bf16 v[84:87], v[152:155], v[176:179], 0
	v_mfma_f32_16x16x32_bf16 v[80:83], v[160:163], v[176:179], 0
	v_mfma_f32_16x16x32_bf16 v[76:79], v[152:155], v[184:187], 0
	v_mfma_f32_16x16x32_bf16 v[72:75], v[160:163], v[184:187], 0
	v_mfma_f32_16x16x32_bf16 v[68:71], v[152:155], v[192:195], 0
	v_mfma_f32_16x16x32_bf16 v[64:67], v[160:163], v[192:195], 0
	v_mfma_f32_16x16x32_bf16 v[92:95], v[156:159], v[172:175], v[92:95]
	v_mfma_f32_16x16x32_bf16 v[88:91], v[164:167], v[172:175], v[88:91]
	v_mfma_f32_16x16x32_bf16 v[84:87], v[156:159], v[180:183], v[84:87]
	v_mfma_f32_16x16x32_bf16 v[80:83], v[164:167], v[180:183], v[80:83]
	v_mfma_f32_16x16x32_bf16 v[76:79], v[156:159], v[188:191], v[76:79]
	v_mfma_f32_16x16x32_bf16 v[72:75], v[164:167], v[188:191], v[72:75]
	v_mfma_f32_16x16x32_bf16 v[68:71], v[156:159], v[196:199], v[68:71]
	v_mfma_f32_16x16x32_bf16 v[64:67], v[164:167], v[196:199], v[64:67]
	s_barrier
	s_add_u32 s90, s6, s42
	s_addc_u32 s91, s7, s43
	s_add_u32 s82, s90, 0x100
	s_addc_u32 s83, s91, 0
	s_add_u32 s92, s72, s42
	s_addc_u32 s93, s73, s43
	s_add_u32 s84, s92, 0x100
	ds_read_b128 v[168:171], v137 offset:16384
	ds_read_b128 v[172:175], v137 offset:17408
	ds_read_b128 v[176:179], v137 offset:18432
	ds_read_b128 v[180:183], v137 offset:19456
	ds_read_b128 v[184:187], v137 offset:20480
	ds_read_b128 v[188:191], v137 offset:21504
	ds_read_b128 v[192:195], v137 offset:22528
	ds_read_b128 v[196:199], v137 offset:23552
	s_addc_u32 s85, s93, 0
	s_mov_b32 m0, s55
	s_nop 0
	global_load_lds_dwordx4 v129, s[82:83]
	s_add_u32 s94, s47, s42
	s_mov_b32 m0, s58
	s_nop 0
	global_load_lds_dwordx4 v129, s[84:85]
	s_addc_u32 s95, s48, s43
	s_add_u32 s82, s94, 0x100
	s_addc_u32 s83, s95, 0
	s_add_u32 s96, s49, s42
	s_addc_u32 s97, s71, s43
	s_add_u32 s84, s96, 0x100
	s_addc_u32 s85, s97, 0
	s_mov_b32 m0, s2
	s_nop 0
	global_load_lds_dwordx4 v129, s[82:83]
	s_mov_b32 m0, s59
	s_nop 0
	global_load_lds_dwordx4 v129, s[84:85]
	s_add_u32 s84, s77, s42
	s_addc_u32 s85, s78, s43
	s_add_u32 s82, s84, 0x100
	s_mov_b32 m0, s57
	s_nop 0
	global_load_lds_dwordx4 v128, s[44:45]
	s_addc_u32 s83, s85, 0
	s_mov_b32 m0, s60
	s_nop 0
	global_load_lds_dwordx4 v128, s[82:83]
	s_waitcnt vmcnt(8)
	s_waitcnt lgkmcnt(0)
	s_barrier
	s_waitcnt lgkmcnt(7)
	v_mfma_f32_16x16x32_bf16 v[60:63], v[130:133], v[168:171], 0
	v_mfma_f32_16x16x32_bf16 v[56:59], v[144:147], v[168:171], 0
	s_waitcnt lgkmcnt(5)
	v_mfma_f32_16x16x32_bf16 v[52:55], v[130:133], v[176:179], 0
	v_mfma_f32_16x16x32_bf16 v[48:51], v[144:147], v[176:179], 0
	s_waitcnt lgkmcnt(3)
	v_mfma_f32_16x16x32_bf16 v[44:47], v[130:133], v[184:187], 0
	v_mfma_f32_16x16x32_bf16 v[40:43], v[144:147], v[184:187], 0
	s_waitcnt lgkmcnt(1)
	v_mfma_f32_16x16x32_bf16 v[36:39], v[130:133], v[192:195], 0
	v_mfma_f32_16x16x32_bf16 v[32:35], v[144:147], v[192:195], 0
	v_mfma_f32_16x16x32_bf16 v[60:63], v[140:143], v[172:175], v[60:63]
	v_mfma_f32_16x16x32_bf16 v[56:59], v[148:151], v[172:175], v[56:59]
	v_mfma_f32_16x16x32_bf16 v[52:55], v[140:143], v[180:183], v[52:55]
	v_mfma_f32_16x16x32_bf16 v[48:51], v[148:151], v[180:183], v[48:51]
	v_mfma_f32_16x16x32_bf16 v[44:47], v[140:143], v[188:191], v[44:47]
	v_mfma_f32_16x16x32_bf16 v[40:43], v[148:151], v[188:191], v[40:43]
	s_waitcnt lgkmcnt(0)
	v_mfma_f32_16x16x32_bf16 v[36:39], v[140:143], v[196:199], v[36:39]
	v_mfma_f32_16x16x32_bf16 v[32:35], v[148:151], v[196:199], v[32:35]
	v_mfma_f32_16x16x32_bf16 v[28:31], v[152:155], v[168:171], 0
	v_mfma_f32_16x16x32_bf16 v[24:27], v[160:163], v[168:171], 0
	v_mfma_f32_16x16x32_bf16 v[20:23], v[152:155], v[176:179], 0
	v_mfma_f32_16x16x32_bf16 v[16:19], v[160:163], v[176:179], 0
	v_mfma_f32_16x16x32_bf16 v[12:15], v[152:155], v[184:187], 0
	v_mfma_f32_16x16x32_bf16 v[8:11], v[160:163], v[184:187], 0
	v_mfma_f32_16x16x32_bf16 v[4:7], v[152:155], v[192:195], 0
	v_mfma_f32_16x16x32_bf16 v[0:3], v[160:163], v[192:195], 0
	v_mfma_f32_16x16x32_bf16 v[28:31], v[156:159], v[172:175], v[28:31]
	v_mfma_f32_16x16x32_bf16 v[24:27], v[164:167], v[172:175], v[24:27]
	v_mfma_f32_16x16x32_bf16 v[20:23], v[156:159], v[180:183], v[20:23]
	v_mfma_f32_16x16x32_bf16 v[16:19], v[164:167], v[180:183], v[16:19]
	v_mfma_f32_16x16x32_bf16 v[12:15], v[156:159], v[188:191], v[12:15]
	v_mfma_f32_16x16x32_bf16 v[8:11], v[164:167], v[188:191], v[8:11]
	v_mfma_f32_16x16x32_bf16 v[4:7], v[156:159], v[196:199], v[4:7]
	v_mfma_f32_16x16x32_bf16 v[0:3], v[164:167], v[196:199], v[0:3]
	s_barrier
	ds_read_b128 v[130:133], v138
	ds_read_b128 v[140:143], v138 offset:1024
	ds_read_b128 v[144:147], v138 offset:2048
	ds_read_b128 v[148:151], v138 offset:3072
	ds_read_b128 v[152:155], v139
	ds_read_b128 v[156:159], v139 offset:1024
	ds_read_b128 v[160:163], v139 offset:2048
	ds_read_b128 v[164:167], v139 offset:3072
	ds_read_b128 v[168:171], v137 offset:32768
	ds_read_b128 v[172:175], v137 offset:33792
	ds_read_b128 v[176:179], v137 offset:34816
	ds_read_b128 v[180:183], v137 offset:35840
	ds_read_b128 v[184:187], v137 offset:36864
	ds_read_b128 v[188:191], v137 offset:37888
	ds_read_b128 v[192:195], v137 offset:38912
	ds_read_b128 v[196:199], v137 offset:39936
	s_add_u32 s44, s86, 0x100
	s_addc_u32 s45, s87, 0
	s_add_u32 s82, s88, 0x100
	s_mov_b32 m0, s33
	s_nop 0
	global_load_lds_dwordx4 v128, s[44:45]
	s_addc_u32 s83, s89, 0
	s_mov_b32 m0, s61
	s_nop 0
	global_load_lds_dwordx4 v128, s[82:83]
	s_waitcnt vmcnt(8)
	s_waitcnt lgkmcnt(0)
	s_barrier
	s_waitcnt lgkmcnt(7)
	v_mfma_f32_16x16x32_bf16 v[124:127], v[130:133], v[168:171], v[124:127]
	v_mfma_f32_16x16x32_bf16 v[120:123], v[144:147], v[168:171], v[120:123]
	s_waitcnt lgkmcnt(5)
	v_mfma_f32_16x16x32_bf16 v[116:119], v[130:133], v[176:179], v[116:119]
	v_mfma_f32_16x16x32_bf16 v[112:115], v[144:147], v[176:179], v[112:115]
	s_waitcnt lgkmcnt(3)
	v_mfma_f32_16x16x32_bf16 v[108:111], v[130:133], v[184:187], v[108:111]
	v_mfma_f32_16x16x32_bf16 v[104:107], v[144:147], v[184:187], v[104:107]
	s_waitcnt lgkmcnt(1)
	v_mfma_f32_16x16x32_bf16 v[100:103], v[130:133], v[192:195], v[100:103]
	v_mfma_f32_16x16x32_bf16 v[96:99], v[144:147], v[192:195], v[96:99]
	v_mfma_f32_16x16x32_bf16 v[124:127], v[140:143], v[172:175], v[124:127]
	v_mfma_f32_16x16x32_bf16 v[120:123], v[148:151], v[172:175], v[120:123]
	v_mfma_f32_16x16x32_bf16 v[116:119], v[140:143], v[180:183], v[116:119]
	v_mfma_f32_16x16x32_bf16 v[112:115], v[148:151], v[180:183], v[112:115]
	v_mfma_f32_16x16x32_bf16 v[108:111], v[140:143], v[188:191], v[108:111]
	v_mfma_f32_16x16x32_bf16 v[104:107], v[148:151], v[188:191], v[104:107]
	s_waitcnt lgkmcnt(0)
	v_mfma_f32_16x16x32_bf16 v[100:103], v[140:143], v[196:199], v[100:103]
	v_mfma_f32_16x16x32_bf16 v[96:99], v[148:151], v[196:199], v[96:99]
	v_mfma_f32_16x16x32_bf16 v[92:95], v[152:155], v[168:171], v[92:95]
	v_mfma_f32_16x16x32_bf16 v[88:91], v[160:163], v[168:171], v[88:91]
	v_mfma_f32_16x16x32_bf16 v[84:87], v[152:155], v[176:179], v[84:87]
	v_mfma_f32_16x16x32_bf16 v[80:83], v[160:163], v[176:179], v[80:83]
	v_mfma_f32_16x16x32_bf16 v[76:79], v[152:155], v[184:187], v[76:79]
	v_mfma_f32_16x16x32_bf16 v[72:75], v[160:163], v[184:187], v[72:75]
	v_mfma_f32_16x16x32_bf16 v[68:71], v[152:155], v[192:195], v[68:71]
	v_mfma_f32_16x16x32_bf16 v[64:67], v[160:163], v[192:195], v[64:67]
	v_mfma_f32_16x16x32_bf16 v[92:95], v[156:159], v[172:175], v[92:95]
	v_mfma_f32_16x16x32_bf16 v[88:91], v[164:167], v[172:175], v[88:91]
	v_mfma_f32_16x16x32_bf16 v[84:87], v[156:159], v[180:183], v[84:87]
	v_mfma_f32_16x16x32_bf16 v[80:83], v[164:167], v[180:183], v[80:83]
	v_mfma_f32_16x16x32_bf16 v[76:79], v[156:159], v[188:191], v[76:79]
	v_mfma_f32_16x16x32_bf16 v[72:75], v[164:167], v[188:191], v[72:75]
	v_mfma_f32_16x16x32_bf16 v[68:71], v[156:159], v[196:199], v[68:71]
	v_mfma_f32_16x16x32_bf16 v[64:67], v[164:167], v[196:199], v[64:67]
	s_barrier
	s_add_u32 s44, s90, 0x180
	s_addc_u32 s45, s91, 0
	ds_read_b128 v[168:171], v137 offset:49152
	ds_read_b128 v[172:175], v137 offset:50176
	ds_read_b128 v[176:179], v137 offset:51200
	ds_read_b128 v[180:183], v137 offset:52224
	ds_read_b128 v[184:187], v137 offset:53248
	ds_read_b128 v[188:191], v137 offset:54272
	ds_read_b128 v[192:195], v137 offset:55296
	ds_read_b128 v[196:199], v137 offset:56320
	s_add_u32 s82, s92, 0x180
	s_mov_b32 m0, s62
	s_nop 0
	global_load_lds_dwordx4 v129, s[44:45]
	s_addc_u32 s83, s93, 0
	s_mov_b32 m0, s63
	s_nop 0
	global_load_lds_dwordx4 v129, s[82:83]
	s_add_u32 s44, s94, 0x180
	s_addc_u32 s45, s95, 0
	s_add_u32 s82, s96, 0x180
	s_mov_b32 m0, s66
	s_nop 0
	global_load_lds_dwordx4 v129, s[44:45]
	s_addc_u32 s83, s97, 0
	s_mov_b32 m0, s67
	s_nop 0
	global_load_lds_dwordx4 v129, s[82:83]
	s_add_u32 s44, s80, 0x180
	s_addc_u32 s45, s81, 0
	s_add_u32 s80, s84, 0x180
	s_mov_b32 m0, s64
	s_nop 0
	global_load_lds_dwordx4 v128, s[44:45]
	s_addc_u32 s81, s85, 0
	s_mov_b32 m0, s65
	s_nop 0
	global_load_lds_dwordx4 v128, s[80:81]
	s_waitcnt vmcnt(8)
	s_waitcnt lgkmcnt(0)
	s_barrier
	s_waitcnt lgkmcnt(7)
	v_mfma_f32_16x16x32_bf16 v[60:63], v[130:133], v[168:171], v[60:63]
	v_mfma_f32_16x16x32_bf16 v[56:59], v[144:147], v[168:171], v[56:59]
	s_waitcnt lgkmcnt(5)
	v_mfma_f32_16x16x32_bf16 v[52:55], v[130:133], v[176:179], v[52:55]
	v_mfma_f32_16x16x32_bf16 v[48:51], v[144:147], v[176:179], v[48:51]
	s_waitcnt lgkmcnt(3)
	v_mfma_f32_16x16x32_bf16 v[44:47], v[130:133], v[184:187], v[44:47]
	v_mfma_f32_16x16x32_bf16 v[40:43], v[144:147], v[184:187], v[40:43]
	s_waitcnt lgkmcnt(1)
	v_mfma_f32_16x16x32_bf16 v[36:39], v[130:133], v[192:195], v[36:39]
	v_mfma_f32_16x16x32_bf16 v[32:35], v[144:147], v[192:195], v[32:35]
	v_mfma_f32_16x16x32_bf16 v[60:63], v[140:143], v[172:175], v[60:63]
	v_mfma_f32_16x16x32_bf16 v[56:59], v[148:151], v[172:175], v[56:59]
	v_mfma_f32_16x16x32_bf16 v[52:55], v[140:143], v[180:183], v[52:55]
	v_mfma_f32_16x16x32_bf16 v[48:51], v[148:151], v[180:183], v[48:51]
	v_mfma_f32_16x16x32_bf16 v[44:47], v[140:143], v[188:191], v[44:47]
	v_mfma_f32_16x16x32_bf16 v[40:43], v[148:151], v[188:191], v[40:43]
	s_waitcnt lgkmcnt(0)
	v_mfma_f32_16x16x32_bf16 v[36:39], v[140:143], v[196:199], v[36:39]
	v_mfma_f32_16x16x32_bf16 v[32:35], v[148:151], v[196:199], v[32:35]
	v_mfma_f32_16x16x32_bf16 v[28:31], v[152:155], v[168:171], v[28:31]
	v_mfma_f32_16x16x32_bf16 v[24:27], v[160:163], v[168:171], v[24:27]
	v_mfma_f32_16x16x32_bf16 v[20:23], v[152:155], v[176:179], v[20:23]
	v_mfma_f32_16x16x32_bf16 v[16:19], v[160:163], v[176:179], v[16:19]
	v_mfma_f32_16x16x32_bf16 v[12:15], v[152:155], v[184:187], v[12:15]
	v_mfma_f32_16x16x32_bf16 v[8:11], v[160:163], v[184:187], v[8:11]
	v_mfma_f32_16x16x32_bf16 v[4:7], v[152:155], v[192:195], v[4:7]
	v_mfma_f32_16x16x32_bf16 v[0:3], v[160:163], v[192:195], v[0:3]
	v_mfma_f32_16x16x32_bf16 v[28:31], v[156:159], v[172:175], v[28:31]
	v_mfma_f32_16x16x32_bf16 v[24:27], v[164:167], v[172:175], v[24:27]
	v_mfma_f32_16x16x32_bf16 v[20:23], v[156:159], v[180:183], v[20:23]
	v_mfma_f32_16x16x32_bf16 v[16:19], v[164:167], v[180:183], v[16:19]
	v_mfma_f32_16x16x32_bf16 v[12:15], v[156:159], v[188:191], v[12:15]
	v_mfma_f32_16x16x32_bf16 v[8:11], v[164:167], v[188:191], v[8:11]
	v_mfma_f32_16x16x32_bf16 v[4:7], v[156:159], v[196:199], v[4:7]
	v_mfma_f32_16x16x32_bf16 v[0:3], v[164:167], v[196:199], v[0:3]
	s_barrier
	s_add_u32 s42, s42, 0x100
	s_addc_u32 s43, s43, 0
	s_cmp_ge_i32 s79, s26
	s_cbranch_scc0 .LBB0_683
	s_branch .LBB0_684

.LBB0_683:
	ds_read_b128 v[130:133], v135
	ds_read_b128 v[140:143], v135 offset:1024
	ds_read_b128 v[144:147], v135 offset:2048
	ds_read_b128 v[148:151], v135 offset:3072
	ds_read_b128 v[152:155], v136
	ds_read_b128 v[156:159], v136 offset:1024
	ds_read_b128 v[160:163], v136 offset:2048
	ds_read_b128 v[164:167], v136 offset:3072
	s_add_i32 s79, s79, 2
	s_add_u32 s80, s4, s42
	s_addc_u32 s81, s5, s43
	s_add_u32 s44, s80, 0x100
	s_addc_u32 s45, s81, 0
	s_add_u32 s86, s31, s42
	ds_read_b128 v[168:171], v137
	ds_read_b128 v[172:175], v137 offset:1024
	ds_read_b128 v[176:179], v137 offset:2048
	ds_read_b128 v[180:183], v137 offset:3072
	ds_read_b128 v[184:187], v137 offset:4096
	ds_read_b128 v[188:191], v137 offset:5120
	ds_read_b128 v[192:195], v137 offset:6144
	ds_read_b128 v[196:199], v137 offset:7168
	s_addc_u32 s87, s46, s43
	s_add_u32 s82, s86, 0x80
	s_addc_u32 s83, s87, 0
	s_add_u32 s88, s74, s42
	s_addc_u32 s89, s75, s43
	s_add_u32 s84, s88, 0x80
	s_mov_b32 m0, s68
	s_nop 0
	global_load_lds_dwordx4 v128, s[82:83]
	s_addc_u32 s85, s89, 0
	s_mov_b32 m0, s69
	s_nop 0
	global_load_lds_dwordx4 v128, s[84:85]
	s_waitcnt vmcnt(8)
	s_waitcnt lgkmcnt(0)
	s_barrier
	s_waitcnt lgkmcnt(7)
	v_mfma_f32_16x16x32_bf16 v[124:127], v[130:133], v[168:171], v[124:127]
	v_mfma_f32_16x16x32_bf16 v[120:123], v[144:147], v[168:171], v[120:123]
	s_waitcnt lgkmcnt(5)
	v_mfma_f32_16x16x32_bf16 v[116:119], v[130:133], v[176:179], v[116:119]
	v_mfma_f32_16x16x32_bf16 v[112:115], v[144:147], v[176:179], v[112:115]
	s_waitcnt lgkmcnt(3)
	v_mfma_f32_16x16x32_bf16 v[108:111], v[130:133], v[184:187], v[108:111]
	v_mfma_f32_16x16x32_bf16 v[104:107], v[144:147], v[184:187], v[104:107]
	s_waitcnt lgkmcnt(1)
	v_mfma_f32_16x16x32_bf16 v[100:103], v[130:133], v[192:195], v[100:103]
	v_mfma_f32_16x16x32_bf16 v[96:99], v[144:147], v[192:195], v[96:99]
	v_mfma_f32_16x16x32_bf16 v[124:127], v[140:143], v[172:175], v[124:127]
	v_mfma_f32_16x16x32_bf16 v[120:123], v[148:151], v[172:175], v[120:123]
	v_mfma_f32_16x16x32_bf16 v[116:119], v[140:143], v[180:183], v[116:119]
	v_mfma_f32_16x16x32_bf16 v[112:115], v[148:151], v[180:183], v[112:115]
	v_mfma_f32_16x16x32_bf16 v[108:111], v[140:143], v[188:191], v[108:111]
	v_mfma_f32_16x16x32_bf16 v[104:107], v[148:151], v[188:191], v[104:107]
	s_waitcnt lgkmcnt(0)
	v_mfma_f32_16x16x32_bf16 v[100:103], v[140:143], v[196:199], v[100:103]
	v_mfma_f32_16x16x32_bf16 v[96:99], v[148:151], v[196:199], v[96:99]
	v_mfma_f32_16x16x32_bf16 v[92:95], v[152:155], v[168:171], v[92:95]
	v_mfma_f32_16x16x32_bf16 v[88:91], v[160:163], v[168:171], v[88:91]
	v_mfma_f32_16x16x32_bf16 v[84:87], v[152:155], v[176:179], v[84:87]
	v_mfma_f32_16x16x32_bf16 v[80:83], v[160:163], v[176:179], v[80:83]
	v_mfma_f32_16x16x32_bf16 v[76:79], v[152:155], v[184:187], v[76:79]
	v_mfma_f32_16x16x32_bf16 v[72:75], v[160:163], v[184:187], v[72:75]
	v_mfma_f32_16x16x32_bf16 v[68:71], v[152:155], v[192:195], v[68:71]
	v_mfma_f32_16x16x32_bf16 v[64:67], v[160:163], v[192:195], v[64:67]
	v_mfma_f32_16x16x32_bf16 v[92:95], v[156:159], v[172:175], v[92:95]
	v_mfma_f32_16x16x32_bf16 v[88:91], v[164:167], v[172:175], v[88:91]
	v_mfma_f32_16x16x32_bf16 v[84:87], v[156:159], v[180:183], v[84:87]
	v_mfma_f32_16x16x32_bf16 v[80:83], v[164:167], v[180:183], v[80:83]
	v_mfma_f32_16x16x32_bf16 v[76:79], v[156:159], v[188:191], v[76:79]
	v_mfma_f32_16x16x32_bf16 v[72:75], v[164:167], v[188:191], v[72:75]
	v_mfma_f32_16x16x32_bf16 v[68:71], v[156:159], v[196:199], v[68:71]
	v_mfma_f32_16x16x32_bf16 v[64:67], v[164:167], v[196:199], v[64:67]
	s_barrier
	s_add_u32 s90, s6, s42
	s_addc_u32 s91, s7, s43
	s_add_u32 s82, s90, 0x100
	s_addc_u32 s83, s91, 0
	s_add_u32 s92, s72, s42
	s_addc_u32 s93, s73, s43
	s_add_u32 s84, s92, 0x100
	ds_read_b128 v[168:171], v137 offset:16384
	ds_read_b128 v[172:175], v137 offset:17408
	ds_read_b128 v[176:179], v137 offset:18432
	ds_read_b128 v[180:183], v137 offset:19456
	ds_read_b128 v[184:187], v137 offset:20480
	ds_read_b128 v[188:191], v137 offset:21504
	ds_read_b128 v[192:195], v137 offset:22528
	ds_read_b128 v[196:199], v137 offset:23552
	s_addc_u32 s85, s93, 0
	s_mov_b32 m0, s55
	s_nop 0
	global_load_lds_dwordx4 v129, s[82:83]
	s_add_u32 s94, s47, s42
	s_mov_b32 m0, s58
	s_nop 0
	global_load_lds_dwordx4 v129, s[84:85]
	s_addc_u32 s95, s48, s43
	s_add_u32 s82, s94, 0x100
	s_addc_u32 s83, s95, 0
	s_add_u32 s96, s49, s42
	s_addc_u32 s97, s71, s43
	s_add_u32 s84, s96, 0x100
	s_addc_u32 s85, s97, 0
	s_mov_b32 m0, s2
	s_nop 0
	global_load_lds_dwordx4 v129, s[82:83]
	s_mov_b32 m0, s59
	s_nop 0
	global_load_lds_dwordx4 v129, s[84:85]
	s_add_u32 s84, s77, s42
	s_addc_u32 s85, s78, s43
	s_add_u32 s82, s84, 0x100
	s_mov_b32 m0, s57
	s_nop 0
	global_load_lds_dwordx4 v128, s[44:45]
	s_addc_u32 s83, s85, 0
	s_mov_b32 m0, s60
	s_nop 0
	global_load_lds_dwordx4 v128, s[82:83]
	s_waitcnt vmcnt(8)
	s_waitcnt lgkmcnt(0)
	s_barrier
	s_waitcnt lgkmcnt(7)
	v_mfma_f32_16x16x32_bf16 v[60:63], v[130:133], v[168:171], v[60:63]
	v_mfma_f32_16x16x32_bf16 v[56:59], v[144:147], v[168:171], v[56:59]
	s_waitcnt lgkmcnt(5)
	v_mfma_f32_16x16x32_bf16 v[52:55], v[130:133], v[176:179], v[52:55]
	v_mfma_f32_16x16x32_bf16 v[48:51], v[144:147], v[176:179], v[48:51]
	s_waitcnt lgkmcnt(3)
	v_mfma_f32_16x16x32_bf16 v[44:47], v[130:133], v[184:187], v[44:47]
	v_mfma_f32_16x16x32_bf16 v[40:43], v[144:147], v[184:187], v[40:43]
	s_waitcnt lgkmcnt(1)
	v_mfma_f32_16x16x32_bf16 v[36:39], v[130:133], v[192:195], v[36:39]
	v_mfma_f32_16x16x32_bf16 v[32:35], v[144:147], v[192:195], v[32:35]
	v_mfma_f32_16x16x32_bf16 v[60:63], v[140:143], v[172:175], v[60:63]
	v_mfma_f32_16x16x32_bf16 v[56:59], v[148:151], v[172:175], v[56:59]
	v_mfma_f32_16x16x32_bf16 v[52:55], v[140:143], v[180:183], v[52:55]
	v_mfma_f32_16x16x32_bf16 v[48:51], v[148:151], v[180:183], v[48:51]
	v_mfma_f32_16x16x32_bf16 v[44:47], v[140:143], v[188:191], v[44:47]
	v_mfma_f32_16x16x32_bf16 v[40:43], v[148:151], v[188:191], v[40:43]
	s_waitcnt lgkmcnt(0)
	v_mfma_f32_16x16x32_bf16 v[36:39], v[140:143], v[196:199], v[36:39]
	v_mfma_f32_16x16x32_bf16 v[32:35], v[148:151], v[196:199], v[32:35]
	v_mfma_f32_16x16x32_bf16 v[28:31], v[152:155], v[168:171], v[28:31]
	v_mfma_f32_16x16x32_bf16 v[24:27], v[160:163], v[168:171], v[24:27]
	v_mfma_f32_16x16x32_bf16 v[20:23], v[152:155], v[176:179], v[20:23]
	v_mfma_f32_16x16x32_bf16 v[16:19], v[160:163], v[176:179], v[16:19]
	v_mfma_f32_16x16x32_bf16 v[12:15], v[152:155], v[184:187], v[12:15]
	v_mfma_f32_16x16x32_bf16 v[8:11], v[160:163], v[184:187], v[8:11]
	v_mfma_f32_16x16x32_bf16 v[4:7], v[152:155], v[192:195], v[4:7]
	v_mfma_f32_16x16x32_bf16 v[0:3], v[160:163], v[192:195], v[0:3]
	v_mfma_f32_16x16x32_bf16 v[28:31], v[156:159], v[172:175], v[28:31]
	v_mfma_f32_16x16x32_bf16 v[24:27], v[164:167], v[172:175], v[24:27]
	v_mfma_f32_16x16x32_bf16 v[20:23], v[156:159], v[180:183], v[20:23]
	v_mfma_f32_16x16x32_bf16 v[16:19], v[164:167], v[180:183], v[16:19]
	v_mfma_f32_16x16x32_bf16 v[12:15], v[156:159], v[188:191], v[12:15]
	v_mfma_f32_16x16x32_bf16 v[8:11], v[164:167], v[188:191], v[8:11]
	v_mfma_f32_16x16x32_bf16 v[4:7], v[156:159], v[196:199], v[4:7]
	v_mfma_f32_16x16x32_bf16 v[0:3], v[164:167], v[196:199], v[0:3]
	s_barrier
	ds_read_b128 v[130:133], v138
	ds_read_b128 v[140:143], v138 offset:1024
	ds_read_b128 v[144:147], v138 offset:2048
	ds_read_b128 v[148:151], v138 offset:3072
	ds_read_b128 v[152:155], v139
	ds_read_b128 v[156:159], v139 offset:1024
	ds_read_b128 v[160:163], v139 offset:2048
	ds_read_b128 v[164:167], v139 offset:3072
	ds_read_b128 v[168:171], v137 offset:32768
	ds_read_b128 v[172:175], v137 offset:33792
	ds_read_b128 v[176:179], v137 offset:34816
	ds_read_b128 v[180:183], v137 offset:35840
	ds_read_b128 v[184:187], v137 offset:36864
	ds_read_b128 v[188:191], v137 offset:37888
	ds_read_b128 v[192:195], v137 offset:38912
	ds_read_b128 v[196:199], v137 offset:39936
	s_add_u32 s44, s86, 0x100
	s_addc_u32 s45, s87, 0
	s_add_u32 s82, s88, 0x100
	s_mov_b32 m0, s33
	s_nop 0
	global_load_lds_dwordx4 v128, s[44:45]
	s_addc_u32 s83, s89, 0
	s_mov_b32 m0, s61
	s_nop 0
	global_load_lds_dwordx4 v128, s[82:83]
	s_waitcnt vmcnt(8)
	s_waitcnt lgkmcnt(0)
	s_barrier
	s_waitcnt lgkmcnt(7)
	v_mfma_f32_16x16x32_bf16 v[124:127], v[130:133], v[168:171], v[124:127]
	v_mfma_f32_16x16x32_bf16 v[120:123], v[144:147], v[168:171], v[120:123]
	s_waitcnt lgkmcnt(5)
	v_mfma_f32_16x16x32_bf16 v[116:119], v[130:133], v[176:179], v[116:119]
	v_mfma_f32_16x16x32_bf16 v[112:115], v[144:147], v[176:179], v[112:115]
	s_waitcnt lgkmcnt(3)
	v_mfma_f32_16x16x32_bf16 v[108:111], v[130:133], v[184:187], v[108:111]
	v_mfma_f32_16x16x32_bf16 v[104:107], v[144:147], v[184:187], v[104:107]
	s_waitcnt lgkmcnt(1)
	v_mfma_f32_16x16x32_bf16 v[100:103], v[130:133], v[192:195], v[100:103]
	v_mfma_f32_16x16x32_bf16 v[96:99], v[144:147], v[192:195], v[96:99]
	v_mfma_f32_16x16x32_bf16 v[124:127], v[140:143], v[172:175], v[124:127]
	v_mfma_f32_16x16x32_bf16 v[120:123], v[148:151], v[172:175], v[120:123]
	v_mfma_f32_16x16x32_bf16 v[116:119], v[140:143], v[180:183], v[116:119]
	v_mfma_f32_16x16x32_bf16 v[112:115], v[148:151], v[180:183], v[112:115]
	v_mfma_f32_16x16x32_bf16 v[108:111], v[140:143], v[188:191], v[108:111]
	v_mfma_f32_16x16x32_bf16 v[104:107], v[148:151], v[188:191], v[104:107]
	s_waitcnt lgkmcnt(0)
	v_mfma_f32_16x16x32_bf16 v[100:103], v[140:143], v[196:199], v[100:103]
	v_mfma_f32_16x16x32_bf16 v[96:99], v[148:151], v[196:199], v[96:99]
	v_mfma_f32_16x16x32_bf16 v[92:95], v[152:155], v[168:171], v[92:95]
	v_mfma_f32_16x16x32_bf16 v[88:91], v[160:163], v[168:171], v[88:91]
	v_mfma_f32_16x16x32_bf16 v[84:87], v[152:155], v[176:179], v[84:87]
	v_mfma_f32_16x16x32_bf16 v[80:83], v[160:163], v[176:179], v[80:83]
	v_mfma_f32_16x16x32_bf16 v[76:79], v[152:155], v[184:187], v[76:79]
	v_mfma_f32_16x16x32_bf16 v[72:75], v[160:163], v[184:187], v[72:75]
	v_mfma_f32_16x16x32_bf16 v[68:71], v[152:155], v[192:195], v[68:71]
	v_mfma_f32_16x16x32_bf16 v[64:67], v[160:163], v[192:195], v[64:67]
	v_mfma_f32_16x16x32_bf16 v[92:95], v[156:159], v[172:175], v[92:95]
	v_mfma_f32_16x16x32_bf16 v[88:91], v[164:167], v[172:175], v[88:91]
	v_mfma_f32_16x16x32_bf16 v[84:87], v[156:159], v[180:183], v[84:87]
	v_mfma_f32_16x16x32_bf16 v[80:83], v[164:167], v[180:183], v[80:83]
	v_mfma_f32_16x16x32_bf16 v[76:79], v[156:159], v[188:191], v[76:79]
	v_mfma_f32_16x16x32_bf16 v[72:75], v[164:167], v[188:191], v[72:75]
	v_mfma_f32_16x16x32_bf16 v[68:71], v[156:159], v[196:199], v[68:71]
	v_mfma_f32_16x16x32_bf16 v[64:67], v[164:167], v[196:199], v[64:67]
	s_barrier
	s_add_u32 s44, s90, 0x180
	s_addc_u32 s45, s91, 0
	ds_read_b128 v[168:171], v137 offset:49152
	ds_read_b128 v[172:175], v137 offset:50176
	ds_read_b128 v[176:179], v137 offset:51200
	ds_read_b128 v[180:183], v137 offset:52224
	ds_read_b128 v[184:187], v137 offset:53248
	ds_read_b128 v[188:191], v137 offset:54272
	ds_read_b128 v[192:195], v137 offset:55296
	ds_read_b128 v[196:199], v137 offset:56320
	s_add_u32 s82, s92, 0x180
	s_mov_b32 m0, s62
	s_nop 0
	global_load_lds_dwordx4 v129, s[44:45]
	s_addc_u32 s83, s93, 0
	s_mov_b32 m0, s63
	s_nop 0
	global_load_lds_dwordx4 v129, s[82:83]
	s_add_u32 s44, s94, 0x180
	s_addc_u32 s45, s95, 0
	s_add_u32 s82, s96, 0x180
	s_mov_b32 m0, s66
	s_nop 0
	global_load_lds_dwordx4 v129, s[44:45]
	s_addc_u32 s83, s97, 0
	s_mov_b32 m0, s67
	s_nop 0
	global_load_lds_dwordx4 v129, s[82:83]
	s_add_u32 s44, s80, 0x180
	s_addc_u32 s45, s81, 0
	s_add_u32 s80, s84, 0x180
	s_mov_b32 m0, s64
	s_nop 0
	global_load_lds_dwordx4 v128, s[44:45]
	s_addc_u32 s81, s85, 0
	s_mov_b32 m0, s65
	s_nop 0
	global_load_lds_dwordx4 v128, s[80:81]
	s_waitcnt vmcnt(8)
	s_waitcnt lgkmcnt(0)
	s_barrier
	s_waitcnt lgkmcnt(7)
	v_mfma_f32_16x16x32_bf16 v[60:63], v[130:133], v[168:171], v[60:63]
	v_mfma_f32_16x16x32_bf16 v[56:59], v[144:147], v[168:171], v[56:59]
	s_waitcnt lgkmcnt(5)
	v_mfma_f32_16x16x32_bf16 v[52:55], v[130:133], v[176:179], v[52:55]
	v_mfma_f32_16x16x32_bf16 v[48:51], v[144:147], v[176:179], v[48:51]
	s_waitcnt lgkmcnt(3)
	v_mfma_f32_16x16x32_bf16 v[44:47], v[130:133], v[184:187], v[44:47]
	v_mfma_f32_16x16x32_bf16 v[40:43], v[144:147], v[184:187], v[40:43]
	s_waitcnt lgkmcnt(1)
	v_mfma_f32_16x16x32_bf16 v[36:39], v[130:133], v[192:195], v[36:39]
	v_mfma_f32_16x16x32_bf16 v[32:35], v[144:147], v[192:195], v[32:35]
	v_mfma_f32_16x16x32_bf16 v[60:63], v[140:143], v[172:175], v[60:63]
	v_mfma_f32_16x16x32_bf16 v[56:59], v[148:151], v[172:175], v[56:59]
	v_mfma_f32_16x16x32_bf16 v[52:55], v[140:143], v[180:183], v[52:55]
	v_mfma_f32_16x16x32_bf16 v[48:51], v[148:151], v[180:183], v[48:51]
	v_mfma_f32_16x16x32_bf16 v[44:47], v[140:143], v[188:191], v[44:47]
	v_mfma_f32_16x16x32_bf16 v[40:43], v[148:151], v[188:191], v[40:43]
	s_waitcnt lgkmcnt(0)
	v_mfma_f32_16x16x32_bf16 v[36:39], v[140:143], v[196:199], v[36:39]
	v_mfma_f32_16x16x32_bf16 v[32:35], v[148:151], v[196:199], v[32:35]
	v_mfma_f32_16x16x32_bf16 v[28:31], v[152:155], v[168:171], v[28:31]
	v_mfma_f32_16x16x32_bf16 v[24:27], v[160:163], v[168:171], v[24:27]
	v_mfma_f32_16x16x32_bf16 v[20:23], v[152:155], v[176:179], v[20:23]
	v_mfma_f32_16x16x32_bf16 v[16:19], v[160:163], v[176:179], v[16:19]
	v_mfma_f32_16x16x32_bf16 v[12:15], v[152:155], v[184:187], v[12:15]
	v_mfma_f32_16x16x32_bf16 v[8:11], v[160:163], v[184:187], v[8:11]
	v_mfma_f32_16x16x32_bf16 v[4:7], v[152:155], v[192:195], v[4:7]
	v_mfma_f32_16x16x32_bf16 v[0:3], v[160:163], v[192:195], v[0:3]
	v_mfma_f32_16x16x32_bf16 v[28:31], v[156:159], v[172:175], v[28:31]
	v_mfma_f32_16x16x32_bf16 v[24:27], v[164:167], v[172:175], v[24:27]
	v_mfma_f32_16x16x32_bf16 v[20:23], v[156:159], v[180:183], v[20:23]
	v_mfma_f32_16x16x32_bf16 v[16:19], v[164:167], v[180:183], v[16:19]
	v_mfma_f32_16x16x32_bf16 v[12:15], v[156:159], v[188:191], v[12:15]
	v_mfma_f32_16x16x32_bf16 v[8:11], v[164:167], v[188:191], v[8:11]
	v_mfma_f32_16x16x32_bf16 v[4:7], v[156:159], v[196:199], v[4:7]
	v_mfma_f32_16x16x32_bf16 v[0:3], v[164:167], v[196:199], v[0:3]
	s_barrier
	s_add_u32 s42, s42, 0x100
	s_addc_u32 s43, s43, 0
	s_cmp_ge_i32 s79, s26
	s_cbranch_scc0 .LBB0_683

.LBB0_686:
	ds_read_b128 v[140:143], v135
	ds_read_b128 v[144:147], v135 offset:1024
	ds_read_b128 v[148:151], v135 offset:2048
	ds_read_b128 v[152:155], v135 offset:3072
	ds_read_b128 v[156:159], v136
	ds_read_b128 v[160:163], v136 offset:1024
	ds_read_b128 v[164:167], v136 offset:2048
	ds_read_b128 v[168:171], v136 offset:3072
	s_ashr_i32 s49, s18, 31
	s_mov_b32 s48, s18
	s_lshl_b64 s[48:49], s[48:49], 7
	s_add_u32 s4, s4, s48
	ds_read_b128 v[172:175], v137
	ds_read_b128 v[176:179], v137 offset:1024
	ds_read_b128 v[180:183], v137 offset:2048
	ds_read_b128 v[184:187], v137 offset:3072
	ds_read_b128 v[188:191], v137 offset:4096
	ds_read_b128 v[192:195], v137 offset:5120
	ds_read_b128 v[196:199], v137 offset:6144
	ds_read_b128 v[200:203], v137 offset:7168
	s_addc_u32 s5, s5, s49
	s_add_u32 s4, s4, s40
	s_addc_u32 s5, s5, s41
	s_add_u32 s4, s4, 0xffffff80
	s_addc_u32 s5, s5, -1
	s_add_u32 s38, s4, s38
	s_mov_b32 m0, s68
	s_nop 0
	global_load_lds_dwordx4 v128, s[4:5]
	s_addc_u32 s39, s5, s39
	s_mov_b32 m0, s69
	s_nop 0
	global_load_lds_dwordx4 v128, s[38:39]
	s_waitcnt vmcnt(8)
	s_waitcnt lgkmcnt(0)
	s_barrier
	s_waitcnt lgkmcnt(7)
	v_mfma_f32_16x16x32_bf16 v[124:127], v[140:143], v[172:175], v[124:127]
	s_waitcnt lgkmcnt(5)
	v_mfma_f32_16x16x32_bf16 v[116:119], v[140:143], v[180:183], v[116:119]
	s_waitcnt lgkmcnt(3)
	v_mfma_f32_16x16x32_bf16 v[108:111], v[140:143], v[188:191], v[108:111]
	s_waitcnt lgkmcnt(1)
	v_mfma_f32_16x16x32_bf16 v[100:103], v[140:143], v[196:199], v[100:103]
	v_mfma_f32_16x16x32_bf16 v[124:127], v[144:147], v[176:179], v[124:127]
	v_mfma_f32_16x16x32_bf16 v[120:123], v[148:151], v[172:175], v[120:123]
	v_mfma_f32_16x16x32_bf16 v[116:119], v[144:147], v[184:187], v[116:119]
	v_mfma_f32_16x16x32_bf16 v[112:115], v[148:151], v[180:183], v[112:115]
	v_mfma_f32_16x16x32_bf16 v[108:111], v[144:147], v[192:195], v[108:111]
	v_mfma_f32_16x16x32_bf16 v[104:107], v[148:151], v[188:191], v[104:107]
	s_waitcnt lgkmcnt(0)
	v_mfma_f32_16x16x32_bf16 v[100:103], v[144:147], v[200:203], v[100:103]
	v_mfma_f32_16x16x32_bf16 v[96:99], v[148:151], v[196:199], v[96:99]
	v_mfma_f32_16x16x32_bf16 v[204:207], v[152:155], v[176:179], v[120:123]
	v_mfma_f32_16x16x32_bf16 v[208:211], v[152:155], v[184:187], v[112:115]
	v_mfma_f32_16x16x32_bf16 v[212:215], v[152:155], v[192:195], v[104:107]
	v_mfma_f32_16x16x32_bf16 v[216:219], v[152:155], v[200:203], v[96:99]
	v_mfma_f32_16x16x32_bf16 v[92:95], v[156:159], v[172:175], v[92:95]
	v_mfma_f32_16x16x32_bf16 v[88:91], v[164:167], v[172:175], v[88:91]
	v_mfma_f32_16x16x32_bf16 v[84:87], v[156:159], v[180:183], v[84:87]
	v_mfma_f32_16x16x32_bf16 v[80:83], v[164:167], v[180:183], v[80:83]
	v_mfma_f32_16x16x32_bf16 v[76:79], v[156:159], v[188:191], v[76:79]
	v_mfma_f32_16x16x32_bf16 v[92:95], v[160:163], v[176:179], v[92:95]
	v_mfma_f32_16x16x32_bf16 v[88:91], v[168:171], v[176:179], v[88:91]
	v_mfma_f32_16x16x32_bf16 v[84:87], v[160:163], v[184:187], v[84:87]
	v_mfma_f32_16x16x32_bf16 v[80:83], v[168:171], v[184:187], v[80:83]
	v_mfma_f32_16x16x32_bf16 v[76:79], v[160:163], v[192:195], v[76:79]
	v_mfma_f32_16x16x32_bf16 v[72:75], v[164:167], v[188:191], v[72:75]
	v_mfma_f32_16x16x32_bf16 v[68:71], v[156:159], v[196:199], v[68:71]
	v_mfma_f32_16x16x32_bf16 v[64:67], v[164:167], v[196:199], v[64:67]
	v_mfma_f32_16x16x32_bf16 v[172:175], v[168:171], v[192:195], v[72:75]
	v_mfma_f32_16x16x32_bf16 v[176:179], v[160:163], v[200:203], v[68:71]
	v_mfma_f32_16x16x32_bf16 v[180:183], v[168:171], v[200:203], v[64:67]
	s_barrier
	s_add_u32 s38, s6, s16
	s_nop 1
	ds_read_b128 v[64:67], v137 offset:16384
	ds_read_b128 v[68:71], v137 offset:17408
	ds_read_b128 v[72:75], v137 offset:18432
	ds_read_b128 v[96:99], v137 offset:19456
	ds_read_b128 v[104:107], v137 offset:20480
	ds_read_b128 v[112:115], v137 offset:21504
	ds_read_b128 v[120:123], v137 offset:22528
	ds_read_b128 v[184:187], v137 offset:23552
	s_addc_u32 s39, s7, s17
	s_mov_b32 m0, s55
	s_nop 0
	global_load_lds_dwordx4 v131, s[6:7]
	s_add_u32 s40, s6, s22
	s_mov_b32 m0, s58
	s_nop 0
	global_load_lds_dwordx4 v131, s[38:39]
	s_addc_u32 s41, s7, s23
	s_add_u32 s48, s40, s16
	s_mov_b32 m0, s2
	s_nop 0
	global_load_lds_dwordx4 v131, s[40:41]
	s_addc_u32 s49, s41, s17
	s_mov_b32 m0, s59
	s_nop 0
	global_load_lds_dwordx4 v131, s[48:49]
	s_add_u32 s4, s46, s44
	s_mov_b32 m0, s57
	s_nop 0
	global_load_lds_dwordx4 v130, s[46:47]
	s_addc_u32 s5, s47, s45
	s_mov_b32 m0, s60
	s_nop 0
	global_load_lds_dwordx4 v130, s[4:5]
	s_waitcnt vmcnt(8)
	s_waitcnt lgkmcnt(0)
	s_barrier
	s_waitcnt lgkmcnt(7)
	v_mfma_f32_16x16x32_bf16 v[60:63], v[140:143], v[64:67], v[60:63]
	v_mfma_f32_16x16x32_bf16 v[56:59], v[148:151], v[64:67], v[56:59]
	s_waitcnt lgkmcnt(5)
	v_mfma_f32_16x16x32_bf16 v[52:55], v[140:143], v[72:75], v[52:55]
	v_mfma_f32_16x16x32_bf16 v[48:51], v[148:151], v[72:75], v[48:51]
	v_mfma_f32_16x16x32_bf16 v[60:63], v[144:147], v[68:71], v[60:63]
	v_mfma_f32_16x16x32_bf16 v[56:59], v[152:155], v[68:71], v[56:59]
	s_waitcnt lgkmcnt(4)
	v_mfma_f32_16x16x32_bf16 v[52:55], v[144:147], v[96:99], v[52:55]
	v_mfma_f32_16x16x32_bf16 v[48:51], v[152:155], v[96:99], v[48:51]
	s_waitcnt lgkmcnt(3)
	v_mfma_f32_16x16x32_bf16 v[44:47], v[140:143], v[104:107], v[44:47]
	v_mfma_f32_16x16x32_bf16 v[40:43], v[148:151], v[104:107], v[40:43]
	s_waitcnt lgkmcnt(1)
	v_mfma_f32_16x16x32_bf16 v[36:39], v[140:143], v[120:123], v[36:39]
	v_mfma_f32_16x16x32_bf16 v[32:35], v[148:151], v[120:123], v[32:35]
	v_mfma_f32_16x16x32_bf16 v[188:191], v[144:147], v[112:115], v[44:47]
	v_mfma_f32_16x16x32_bf16 v[192:195], v[152:155], v[112:115], v[40:43]
	s_waitcnt lgkmcnt(0)
	v_mfma_f32_16x16x32_bf16 v[140:143], v[144:147], v[184:187], v[36:39]
	v_mfma_f32_16x16x32_bf16 v[144:147], v[152:155], v[184:187], v[32:35]
	v_mfma_f32_16x16x32_bf16 v[28:31], v[156:159], v[64:67], v[28:31]
	v_mfma_f32_16x16x32_bf16 v[20:23], v[156:159], v[72:75], v[20:23]
	v_mfma_f32_16x16x32_bf16 v[12:15], v[156:159], v[104:107], v[12:15]
	v_mfma_f32_16x16x32_bf16 v[4:7], v[156:159], v[120:123], v[4:7]
	v_mfma_f32_16x16x32_bf16 v[28:31], v[160:163], v[68:71], v[28:31]
	v_mfma_f32_16x16x32_bf16 v[24:27], v[164:167], v[64:67], v[24:27]
	v_mfma_f32_16x16x32_bf16 v[20:23], v[160:163], v[96:99], v[20:23]
	v_mfma_f32_16x16x32_bf16 v[16:19], v[164:167], v[72:75], v[16:19]
	v_mfma_f32_16x16x32_bf16 v[12:15], v[160:163], v[112:115], v[12:15]
	v_mfma_f32_16x16x32_bf16 v[8:11], v[164:167], v[104:107], v[8:11]
	v_mfma_f32_16x16x32_bf16 v[4:7], v[160:163], v[184:187], v[4:7]
	v_mfma_f32_16x16x32_bf16 v[0:3], v[164:167], v[120:123], v[0:3]
	v_mfma_f32_16x16x32_bf16 v[148:151], v[168:171], v[68:71], v[24:27]
	v_mfma_f32_16x16x32_bf16 v[152:155], v[168:171], v[96:99], v[16:19]
	v_mfma_f32_16x16x32_bf16 v[196:199], v[168:171], v[112:115], v[8:11]
	v_mfma_f32_16x16x32_bf16 v[156:159], v[168:171], v[184:187], v[0:3]
	s_barrier
	s_nop 1
	ds_read_b128 v[0:3], v138
	ds_read_b128 v[8:11], v138 offset:1024
	ds_read_b128 v[160:163], v138 offset:2048
	ds_read_b128 v[164:167], v138 offset:3072
	ds_read_b128 v[168:171], v139
	ds_read_b128 v[184:187], v139 offset:1024
	ds_read_b128 v[200:203], v139 offset:2048
	ds_read_b128 v[220:223], v139 offset:3072
	ds_read_b128 v[16:19], v137 offset:32768
	ds_read_b128 v[24:27], v137 offset:33792
	ds_read_b128 v[36:39], v137 offset:34816
	ds_read_b128 v[44:47], v137 offset:35840
	ds_read_b128 v[68:71], v137 offset:36864
	ds_read_b128 v[224:227], v137 offset:37888
	ds_read_b128 v[228:231], v137 offset:38912
	ds_read_b128 v[232:235], v137 offset:39936
	s_add_u32 s72, s46, s42
	s_addc_u32 s73, s47, s43
	s_add_u32 s74, s72, s44
	s_mov_b32 m0, s33
	s_nop 0
	global_load_lds_dwordx4 v130, s[72:73]
	s_addc_u32 s75, s73, s45
	s_mov_b32 m0, s61
	s_nop 0
	global_load_lds_dwordx4 v130, s[74:75]
	s_waitcnt vmcnt(8)
	s_waitcnt lgkmcnt(0)
	s_barrier
	s_waitcnt lgkmcnt(7)
	v_mfma_f32_16x16x32_bf16 v[32:35], v[0:3], v[16:19], v[124:127]
	s_waitcnt lgkmcnt(6)
	v_mfma_f32_16x16x32_bf16 v[120:123], v[8:11], v[24:27], v[32:35]
	v_mfma_f32_16x16x32_bf16 v[32:35], v[160:163], v[16:19], v[204:207]
	v_mfma_f32_16x16x32_bf16 v[112:115], v[164:167], v[24:27], v[32:35]
	s_waitcnt lgkmcnt(5)
	v_mfma_f32_16x16x32_bf16 v[32:35], v[0:3], v[36:39], v[116:119]
	s_waitcnt lgkmcnt(4)
	v_mfma_f32_16x16x32_bf16 v[104:107], v[8:11], v[44:47], v[32:35]
	v_mfma_f32_16x16x32_bf16 v[32:35], v[160:163], v[36:39], v[208:211]
	v_mfma_f32_16x16x32_bf16 v[96:99], v[164:167], v[44:47], v[32:35]
	s_waitcnt lgkmcnt(3)
	v_mfma_f32_16x16x32_bf16 v[32:35], v[0:3], v[68:71], v[108:111]
	s_waitcnt lgkmcnt(2)
	v_mfma_f32_16x16x32_bf16 v[72:75], v[8:11], v[224:227], v[32:35]
	v_mfma_f32_16x16x32_bf16 v[32:35], v[160:163], v[68:71], v[212:215]
	v_mfma_f32_16x16x32_bf16 v[64:67], v[164:167], v[224:227], v[32:35]
	s_waitcnt lgkmcnt(1)
	v_mfma_f32_16x16x32_bf16 v[32:35], v[0:3], v[228:231], v[100:103]
	s_waitcnt lgkmcnt(0)
	v_mfma_f32_16x16x32_bf16 v[40:43], v[8:11], v[232:235], v[32:35]
	v_mfma_f32_16x16x32_bf16 v[32:35], v[160:163], v[228:231], v[216:219]
	v_mfma_f32_16x16x32_bf16 v[32:35], v[164:167], v[232:235], v[32:35]
	v_mfma_f32_16x16x32_bf16 v[92:95], v[168:171], v[16:19], v[92:95]
	v_mfma_f32_16x16x32_bf16 v[16:19], v[200:203], v[16:19], v[88:91]
	v_mfma_f32_16x16x32_bf16 v[116:119], v[220:223], v[24:27], v[16:19]
	v_mfma_f32_16x16x32_bf16 v[16:19], v[168:171], v[36:39], v[84:87]
	v_mfma_f32_16x16x32_bf16 v[108:111], v[184:187], v[44:47], v[16:19]
	v_mfma_f32_16x16x32_bf16 v[16:19], v[200:203], v[36:39], v[80:83]
	v_mfma_f32_16x16x32_bf16 v[100:103], v[220:223], v[44:47], v[16:19]
	v_mfma_f32_16x16x32_bf16 v[16:19], v[168:171], v[68:71], v[76:79]
	v_mfma_f32_16x16x32_bf16 v[76:79], v[184:187], v[224:227], v[16:19]
	v_mfma_f32_16x16x32_bf16 v[16:19], v[200:203], v[68:71], v[172:175]
	v_mfma_f32_16x16x32_bf16 v[68:71], v[220:223], v[224:227], v[16:19]
	v_mfma_f32_16x16x32_bf16 v[16:19], v[168:171], v[228:231], v[176:179]
	v_mfma_f32_16x16x32_bf16 v[44:47], v[184:187], v[232:235], v[16:19]
	v_mfma_f32_16x16x32_bf16 v[16:19], v[200:203], v[228:231], v[180:183]
	v_mfma_f32_16x16x32_bf16 v[124:127], v[184:187], v[24:27], v[92:95]
	v_mfma_f32_16x16x32_bf16 v[36:39], v[220:223], v[232:235], v[16:19]
	s_barrier
	s_add_u32 s72, s6, 0x80
	s_addc_u32 s73, s7, 0
	s_add_u32 s38, s38, 0x80
	ds_read_b128 v[84:87], v137 offset:49152
	ds_read_b128 v[172:175], v137 offset:50176
	ds_read_b128 v[176:179], v137 offset:51200
	ds_read_b128 v[180:183], v137 offset:52224
	ds_read_b128 v[204:207], v137 offset:53248
	ds_read_b128 v[208:211], v137 offset:54272
	ds_read_b128 v[212:215], v137 offset:55296
	ds_read_b128 v[216:219], v137 offset:56320
	s_addc_u32 s39, s39, 0
	s_mov_b32 m0, s62
	s_nop 0
	global_load_lds_dwordx4 v131, s[72:73]
	s_nop 0
	s_mov_b32 m0, s63
	s_nop 0
	global_load_lds_dwordx4 v131, s[38:39]
	s_add_u32 s38, s40, 0x80
	s_addc_u32 s39, s41, 0
	s_add_u32 s40, s48, 0x80
	s_addc_u32 s41, s49, 0
	s_mov_b32 m0, s66
	s_nop 0
	global_load_lds_dwordx4 v131, s[38:39]
	s_add_u32 s38, s46, 0x80
	s_mov_b32 m0, s67
	s_nop 0
	global_load_lds_dwordx4 v131, s[40:41]
	s_addc_u32 s39, s47, 0
	s_add_u32 s4, s4, 0x80
	s_mov_b32 m0, s64
	s_nop 0
	global_load_lds_dwordx4 v130, s[38:39]
	s_addc_u32 s5, s5, 0
	s_mov_b32 m0, s65
	s_nop 0
	global_load_lds_dwordx4 v130, s[4:5]
	s_waitcnt vmcnt(8)
	s_waitcnt lgkmcnt(0)
	s_barrier
	s_waitcnt lgkmcnt(7)
	v_mfma_f32_16x16x32_bf16 v[16:19], v[0:3], v[84:87], v[60:63]
	s_waitcnt lgkmcnt(6)
	v_mfma_f32_16x16x32_bf16 v[88:91], v[8:11], v[172:175], v[16:19]
	v_mfma_f32_16x16x32_bf16 v[16:19], v[160:163], v[84:87], v[56:59]
	v_mfma_f32_16x16x32_bf16 v[80:83], v[164:167], v[172:175], v[16:19]
	s_waitcnt lgkmcnt(5)
	v_mfma_f32_16x16x32_bf16 v[16:19], v[0:3], v[176:179], v[52:55]
	s_waitcnt lgkmcnt(4)
	v_mfma_f32_16x16x32_bf16 v[56:59], v[8:11], v[180:183], v[16:19]
	v_mfma_f32_16x16x32_bf16 v[16:19], v[160:163], v[176:179], v[48:51]
	v_mfma_f32_16x16x32_bf16 v[48:51], v[164:167], v[180:183], v[16:19]
	s_waitcnt lgkmcnt(3)
	v_mfma_f32_16x16x32_bf16 v[16:19], v[0:3], v[204:207], v[188:191]
	s_waitcnt lgkmcnt(1)
	v_mfma_f32_16x16x32_bf16 v[0:3], v[0:3], v[212:215], v[140:143]
	v_mfma_f32_16x16x32_bf16 v[24:27], v[8:11], v[208:211], v[16:19]
	v_mfma_f32_16x16x32_bf16 v[16:19], v[160:163], v[204:207], v[192:195]
	s_waitcnt lgkmcnt(0)
	v_mfma_f32_16x16x32_bf16 v[8:11], v[8:11], v[216:219], v[0:3]
	v_mfma_f32_16x16x32_bf16 v[0:3], v[160:163], v[212:215], v[144:147]
	v_mfma_f32_16x16x32_bf16 v[16:19], v[164:167], v[208:211], v[16:19]
	v_mfma_f32_16x16x32_bf16 v[0:3], v[164:167], v[216:219], v[0:3]
	v_mfma_f32_16x16x32_bf16 v[28:31], v[168:171], v[84:87], v[28:31]
	v_mfma_f32_16x16x32_bf16 v[92:95], v[184:187], v[172:175], v[28:31]
	v_mfma_f32_16x16x32_bf16 v[28:31], v[200:203], v[84:87], v[148:151]
	v_mfma_f32_16x16x32_bf16 v[20:23], v[168:171], v[176:179], v[20:23]
	v_mfma_f32_16x16x32_bf16 v[12:15], v[168:171], v[204:207], v[12:15]
	v_mfma_f32_16x16x32_bf16 v[84:87], v[220:223], v[172:175], v[28:31]
	v_mfma_f32_16x16x32_bf16 v[60:63], v[184:187], v[180:183], v[20:23]
	v_mfma_f32_16x16x32_bf16 v[20:23], v[200:203], v[176:179], v[152:155]
	v_mfma_f32_16x16x32_bf16 v[28:31], v[184:187], v[208:211], v[12:15]
	v_mfma_f32_16x16x32_bf16 v[12:15], v[200:203], v[204:207], v[196:199]
	v_mfma_f32_16x16x32_bf16 v[4:7], v[168:171], v[212:215], v[4:7]
	v_mfma_f32_16x16x32_bf16 v[52:55], v[220:223], v[180:183], v[20:23]
	v_mfma_f32_16x16x32_bf16 v[20:23], v[220:223], v[208:211], v[12:15]
	v_mfma_f32_16x16x32_bf16 v[12:15], v[184:187], v[216:219], v[4:7]
	v_mfma_f32_16x16x32_bf16 v[4:7], v[200:203], v[212:215], v[156:159]
	v_mfma_f32_16x16x32_bf16 v[4:7], v[220:223], v[216:219], v[4:7]
	s_barrier
	s_andn2_b64 vcc, exec, s[24:25]
	s_cbranch_vccnz .LBB0_688
	s_barrier

.LBB0_695:
	s_lshl_b64 s[54:55], s[0:1], 7
	s_lshl_b64 s[34:35], s[18:19], 7
	v_and_b32_e32 v1, 15, v2
	v_or_b32_e32 v3, s3, v1
	s_add_u32 s18, s6, 0x80
	v_lshlrev_b32_e32 v5, 6, v3
	v_and_b32_e32 v6, 48, v2
	s_movk_i32 s0, 0x3c0
	s_addc_u32 s19, s7, 0
	v_and_or_b32 v5, v5, s0, v6
	s_sub_u32 s0, 0, s28
	s_subb_u32 s2, 0, s29
	s_add_u32 s0, s12, s0
	s_addc_u32 s2, s13, s2
	s_add_u32 s20, s0, 0x80
	s_addc_u32 s21, s2, 0
	s_add_i32 s67, s57, 0x18000
	s_add_i32 s73, s57, 0x1a000
	s_mov_b32 s98, 0
	s_cselect_b32 s99, 1, 0
	s_cmp_lt_u32 s76, 4
	s_cbranch_scc0 .Lsprio_8
	s_setprio 1
.Lsprio_8:
	s_cmp_lg_u32 s99, 0
	s_waitcnt vmcnt(2)
	s_barrier
	s_mov_b32 m0, s67
	s_nop 0
	global_load_lds_dwordx4 v0, s[18:19]
	s_add_u32 s18, s4, 0x80
	s_mov_b32 m0, s73
	s_nop 0
	global_load_lds_dwordx4 v0, s[20:21]
	s_addc_u32 s19, s5, 0
	s_sub_u32 s0, 0, s52
	s_subb_u32 s2, 0, s53
	s_add_u32 s0, s16, s0
	s_addc_u32 s2, s17, s2
	s_add_u32 s16, s0, 0x80
	s_addc_u32 s17, s2, 0
	s_add_i32 s78, s57, 0x8000
	s_add_i32 s79, s57, 0xa000
	s_add_u32 s12, s12, 0x80
	s_mov_b32 m0, s78
	s_nop 0
	global_load_lds_dwordx4 v60, s[18:19]
	s_addc_u32 s13, s13, 0
	v_ashrrev_i32_e32 v4, 6, v2
	v_lshlrev_b32_e32 v3, 2, v3
	s_mov_b32 m0, s79
	s_nop 0
	global_load_lds_dwordx4 v60, s[16:17]
	s_add_u32 s14, s14, 0x80
	v_lshl_add_u32 v7, v4, 10, s50
	v_and_b32_e32 v3, 32, v3
	v_lshlrev_b32_e32 v2, 2, v2
	s_addc_u32 s15, s15, 0
	s_add_i32 s82, s57, 0x1c000
	s_mov_b32 m0, s82
	s_nop 0
	global_load_lds_dwordx4 v0, s[12:13]
	v_mov_b32_e32 v61, v0
	v_bitop3_b32 v149, v5, v7, v3 bitop3:0xde
	v_lshl_or_b32 v1, v1, 6, v6
	v_add_lshl_u32 v3, v4, s51, 10
	v_and_b32_e32 v2, 32, v2
	s_add_i32 s83, s57, 0x1e000
	s_mov_b32 m0, s83
	s_nop 0
	global_load_lds_dwordx4 v0, s[14:15]
	v_mov_b32_e32 v0, 0
	v_bitop3_b32 v150, v1, v3, v2 bitop3:0xde
	s_waitcnt vmcnt(6)
	s_add_i32 s84, s57, 0xc000
	s_add_i32 s85, s57, 0xe000
	v_mov_b32_e32 v2, v0
	v_mov_b32_e32 v3, v0
	v_readlane_b32 s0, v254, 0
	v_mov_b32_e32 v1, v0
	s_cmpk_lt_u32 s0, 0x100
	v_mov_b64_e32 v[14:15], v[2:3]
	v_mov_b64_e32 v[22:23], v[2:3]
	v_mov_b64_e32 v[54:55], v[2:3]
	v_mov_b64_e32 v[58:59], v[2:3]
	v_mov_b64_e32 v[78:79], v[2:3]
	v_mov_b64_e32 v[86:87], v[2:3]
	v_mov_b64_e32 v[118:119], v[2:3]
	v_mov_b64_e32 v[122:123], v[2:3]
	v_mov_b64_e32 v[38:39], v[2:3]
	v_mov_b64_e32 v[42:43], v[2:3]
	v_mov_b64_e32 v[126:127], v[2:3]
	v_mov_b64_e32 v[130:131], v[2:3]
	v_mov_b64_e32 v[102:103], v[2:3]
	v_mov_b64_e32 v[106:107], v[2:3]
	v_mov_b64_e32 v[134:135], v[2:3]
	v_mov_b64_e32 v[138:139], v[2:3]
	v_mov_b64_e32 v[114:115], v[2:3]
	v_mov_b64_e32 v[110:111], v[2:3]
	v_mov_b64_e32 v[70:71], v[2:3]
	v_mov_b64_e32 v[74:75], v[2:3]
	v_mov_b64_e32 v[50:51], v[2:3]
	v_mov_b64_e32 v[46:47], v[2:3]
	v_mov_b64_e32 v[6:7], v[2:3]
	v_mov_b64_e32 v[10:11], v[2:3]
	v_mov_b64_e32 v[98:99], v[2:3]
	v_mov_b64_e32 v[94:95], v[2:3]
	v_mov_b64_e32 v[82:83], v[2:3]
	v_mov_b64_e32 v[90:91], v[2:3]
	v_mov_b64_e32 v[34:35], v[2:3]
	v_mov_b64_e32 v[30:31], v[2:3]
	v_mov_b64_e32 v[18:19], v[2:3]
	v_mov_b64_e32 v[26:27], v[2:3]
	s_mov_b32 s44, s25
	s_mov_b32 s45, s26
	s_cselect_b64 s[26:27], -1, 0
	v_mov_b64_e32 v[12:13], v[0:1]
	v_mov_b64_e32 v[20:21], v[0:1]
	v_mov_b64_e32 v[52:53], v[0:1]
	v_mov_b64_e32 v[56:57], v[0:1]
	v_mov_b64_e32 v[76:77], v[0:1]
	v_mov_b64_e32 v[84:85], v[0:1]
	v_mov_b64_e32 v[116:117], v[0:1]
	v_mov_b64_e32 v[120:121], v[0:1]
	v_mov_b64_e32 v[36:37], v[0:1]
	v_mov_b64_e32 v[40:41], v[0:1]
	v_mov_b64_e32 v[124:125], v[0:1]
	v_mov_b64_e32 v[128:129], v[0:1]
	v_mov_b64_e32 v[100:101], v[0:1]
	v_mov_b64_e32 v[104:105], v[0:1]
	v_mov_b64_e32 v[132:133], v[0:1]
	v_mov_b64_e32 v[136:137], v[0:1]
	v_mov_b64_e32 v[112:113], v[0:1]
	v_mov_b64_e32 v[108:109], v[0:1]
	v_mov_b64_e32 v[68:69], v[0:1]
	v_mov_b64_e32 v[72:73], v[0:1]
	v_mov_b64_e32 v[48:49], v[0:1]
	v_mov_b64_e32 v[44:45], v[0:1]
	v_mov_b64_e32 v[4:5], v[0:1]
	v_mov_b64_e32 v[8:9], v[0:1]
	v_mov_b64_e32 v[96:97], v[0:1]
	v_mov_b64_e32 v[92:93], v[0:1]
	v_mov_b64_e32 v[80:81], v[0:1]
	v_mov_b64_e32 v[88:89], v[0:1]
	v_mov_b64_e32 v[32:33], v[0:1]
	v_mov_b64_e32 v[28:29], v[0:1]
	v_mov_b64_e32 v[16:17], v[0:1]
	v_mov_b64_e32 v[24:25], v[0:1]
	s_mov_b32 s2, s1
	s_barrier
	s_branch .LBB0_698

.LBB0_702:
	v_add_u32_e32 v1, 0, v150
	v_add_u32_e32 v2, 0x10000, v1
	ds_read_b128 v[62:65], v2
	ds_read_b128 v[140:143], v2 offset:1024
	ds_read_b128 v[144:147], v2 offset:2048
	ds_read_b128 v[152:155], v2 offset:3072
	v_add_u32_e32 v2, 0x14000, v1
	ds_read_b128 v[156:159], v2
	ds_read_b128 v[160:163], v2 offset:1024
	ds_read_b128 v[164:167], v2 offset:2048
	ds_read_b128 v[168:171], v2 offset:3072
	s_add_i32 s77, s77, 2
	s_add_u32 s80, s4, s46
	s_addc_u32 s81, s5, s47
	s_add_u32 s48, s80, 0x100
	s_addc_u32 s49, s81, 0
	v_add_u32_e32 v151, 0, v149
	s_add_u32 s87, s23, s46
	ds_read_b128 v[172:175], v151
	ds_read_b128 v[176:179], v151 offset:1024
	ds_read_b128 v[180:183], v151 offset:2048
	ds_read_b128 v[184:187], v151 offset:3072
	ds_read_b128 v[188:191], v151 offset:4096
	ds_read_b128 v[192:195], v151 offset:5120
	ds_read_b128 v[196:199], v151 offset:6144
	ds_read_b128 v[200:203], v151 offset:7168
	s_addc_u32 s92, s25, s47
	s_add_u32 s88, s87, 0x80
	s_addc_u32 s89, s92, 0
	s_add_u32 s93, s71, s46
	s_addc_u32 s94, s72, s47
	s_add_u32 s90, s93, 0x80
	s_mov_b32 m0, s84
	s_nop 0
	global_load_lds_dwordx4 v60, s[88:89]
	s_addc_u32 s91, s94, 0
	s_mov_b32 m0, s85
	s_nop 0
	global_load_lds_dwordx4 v60, s[90:91]
	s_waitcnt vmcnt(8)
	s_waitcnt lgkmcnt(0)
	s_barrier
	s_waitcnt lgkmcnt(7)
	v_mfma_f32_16x16x32_bf16 v[24:27], v[62:65], v[172:175], v[24:27]
	v_mfma_f32_16x16x32_bf16 v[16:19], v[144:147], v[172:175], v[16:19]
	s_waitcnt lgkmcnt(5)
	v_mfma_f32_16x16x32_bf16 v[28:31], v[62:65], v[180:183], v[28:31]
	v_mfma_f32_16x16x32_bf16 v[32:35], v[144:147], v[180:183], v[32:35]
	s_waitcnt lgkmcnt(3)
	v_mfma_f32_16x16x32_bf16 v[88:91], v[62:65], v[188:191], v[88:91]
	v_mfma_f32_16x16x32_bf16 v[80:83], v[144:147], v[188:191], v[80:83]
	s_waitcnt lgkmcnt(1)
	v_mfma_f32_16x16x32_bf16 v[92:95], v[62:65], v[196:199], v[92:95]
	v_mfma_f32_16x16x32_bf16 v[96:99], v[144:147], v[196:199], v[96:99]
	v_mfma_f32_16x16x32_bf16 v[24:27], v[140:143], v[176:179], v[24:27]
	v_mfma_f32_16x16x32_bf16 v[16:19], v[152:155], v[176:179], v[16:19]
	v_mfma_f32_16x16x32_bf16 v[28:31], v[140:143], v[184:187], v[28:31]
	v_mfma_f32_16x16x32_bf16 v[32:35], v[152:155], v[184:187], v[32:35]
	v_mfma_f32_16x16x32_bf16 v[88:91], v[140:143], v[192:195], v[88:91]
	v_mfma_f32_16x16x32_bf16 v[80:83], v[152:155], v[192:195], v[80:83]
	s_waitcnt lgkmcnt(0)
	v_mfma_f32_16x16x32_bf16 v[92:95], v[140:143], v[200:203], v[92:95]
	v_mfma_f32_16x16x32_bf16 v[96:99], v[152:155], v[200:203], v[96:99]
	v_mfma_f32_16x16x32_bf16 v[8:11], v[156:159], v[172:175], v[8:11]
	v_mfma_f32_16x16x32_bf16 v[2:5], v[164:167], v[172:175], v[4:7]
	v_mfma_f32_16x16x32_bf16 v[44:47], v[156:159], v[180:183], v[44:47]
	v_mfma_f32_16x16x32_bf16 v[48:51], v[164:167], v[180:183], v[48:51]
	v_mfma_f32_16x16x32_bf16 v[72:75], v[156:159], v[188:191], v[72:75]
	v_mfma_f32_16x16x32_bf16 v[66:69], v[164:167], v[188:191], v[68:71]
	v_mfma_f32_16x16x32_bf16 v[108:111], v[156:159], v[196:199], v[108:111]
	v_mfma_f32_16x16x32_bf16 v[112:115], v[164:167], v[196:199], v[112:115]
	v_mfma_f32_16x16x32_bf16 v[8:11], v[160:163], v[176:179], v[8:11]
	v_mfma_f32_16x16x32_bf16 v[2:5], v[168:171], v[176:179], v[2:5]
	v_mfma_f32_16x16x32_bf16 v[44:47], v[160:163], v[184:187], v[44:47]
	v_mfma_f32_16x16x32_bf16 v[48:51], v[168:171], v[184:187], v[48:51]
	v_mfma_f32_16x16x32_bf16 v[72:75], v[160:163], v[192:195], v[72:75]
	v_mfma_f32_16x16x32_bf16 v[66:69], v[168:171], v[192:195], v[66:69]
	v_mfma_f32_16x16x32_bf16 v[108:111], v[160:163], v[200:203], v[108:111]
	v_mfma_f32_16x16x32_bf16 v[112:115], v[168:171], v[200:203], v[112:115]
	s_barrier
	s_add_u32 s95, s6, s46
	s_addc_u32 s96, s7, s47
	s_add_u32 s88, s95, 0x100
	s_addc_u32 s89, s96, 0
	s_add_u32 s97, s69, s46
	s_addc_u32 vcc_lo, s70, s47
	s_add_u32 s90, s97, 0x100
	ds_read_b128 v[172:175], v151 offset:16384
	ds_read_b128 v[176:179], v151 offset:17408
	ds_read_b128 v[180:183], v151 offset:18432
	ds_read_b128 v[184:187], v151 offset:19456
	ds_read_b128 v[188:191], v151 offset:20480
	ds_read_b128 v[192:195], v151 offset:21504
	ds_read_b128 v[196:199], v151 offset:22528
	ds_read_b128 v[200:203], v151 offset:23552
	s_addc_u32 s91, vcc_lo, 0
	s_mov_b32 m0, s60
	s_nop 0
	global_load_lds_dwordx4 v61, s[88:89]
	s_add_u32 vcc_hi, s33, s46
	s_mov_b32 m0, s61
	s_nop 0
	global_load_lds_dwordx4 v61, s[90:91]
	s_addc_u32 s59, s50, s47
	s_add_u32 s88, vcc_hi, 0x100
	s_addc_u32 s89, s59, 0
	s_add_u32 s30, s51, s46
	s_addc_u32 s31, s68, s47
	s_add_u32 s90, s30, 0x100
	s_mov_b32 m0, s62
	s_nop 0
	global_load_lds_dwordx4 v61, s[88:89]
	s_addc_u32 s91, s31, 0
	s_mov_b32 m0, s63
	s_nop 0
	global_load_lds_dwordx4 v61, s[90:91]
	s_add_u32 s58, s74, s46
	s_addc_u32 s90, s75, s47
	s_add_u32 s88, s58, 0x100
	s_mov_b32 m0, s57
	s_nop 0
	global_load_lds_dwordx4 v60, s[48:49]
	s_addc_u32 s89, s90, 0
	s_mov_b32 m0, s64
	s_nop 0
	global_load_lds_dwordx4 v60, s[88:89]
	s_waitcnt vmcnt(8)
	s_waitcnt lgkmcnt(0)
	s_barrier
	s_waitcnt lgkmcnt(7)
	v_mfma_f32_16x16x32_bf16 v[136:139], v[62:65], v[172:175], v[136:139]
	v_mfma_f32_16x16x32_bf16 v[132:135], v[144:147], v[172:175], v[132:135]
	s_waitcnt lgkmcnt(5)
	v_mfma_f32_16x16x32_bf16 v[104:107], v[62:65], v[180:183], v[104:107]
	v_mfma_f32_16x16x32_bf16 v[100:103], v[144:147], v[180:183], v[100:103]
	s_waitcnt lgkmcnt(3)
	v_mfma_f32_16x16x32_bf16 v[128:131], v[62:65], v[188:191], v[128:131]
	v_mfma_f32_16x16x32_bf16 v[124:127], v[144:147], v[188:191], v[124:127]
	s_waitcnt lgkmcnt(1)
	v_mfma_f32_16x16x32_bf16 v[40:43], v[62:65], v[196:199], v[40:43]
	v_mfma_f32_16x16x32_bf16 v[36:39], v[144:147], v[196:199], v[36:39]
	v_mfma_f32_16x16x32_bf16 v[136:139], v[140:143], v[176:179], v[136:139]
	v_mfma_f32_16x16x32_bf16 v[132:135], v[152:155], v[176:179], v[132:135]
	v_mfma_f32_16x16x32_bf16 v[104:107], v[140:143], v[184:187], v[104:107]
	v_mfma_f32_16x16x32_bf16 v[100:103], v[152:155], v[184:187], v[100:103]
	v_mfma_f32_16x16x32_bf16 v[128:131], v[140:143], v[192:195], v[128:131]
	v_mfma_f32_16x16x32_bf16 v[124:127], v[152:155], v[192:195], v[124:127]
	s_waitcnt lgkmcnt(0)
	v_mfma_f32_16x16x32_bf16 v[40:43], v[140:143], v[200:203], v[40:43]
	v_mfma_f32_16x16x32_bf16 v[36:39], v[152:155], v[200:203], v[36:39]
	v_mfma_f32_16x16x32_bf16 v[116:119], v[164:167], v[172:175], v[116:119]
	v_mfma_f32_16x16x32_bf16 v[84:87], v[156:159], v[180:183], v[84:87]
	v_mfma_f32_16x16x32_bf16 v[76:79], v[164:167], v[180:183], v[76:79]
	v_mfma_f32_16x16x32_bf16 v[56:59], v[156:159], v[188:191], v[56:59]
	v_mfma_f32_16x16x32_bf16 v[52:55], v[164:167], v[188:191], v[52:55]
	v_mfma_f32_16x16x32_bf16 v[20:23], v[156:159], v[196:199], v[20:23]
	v_mfma_f32_16x16x32_bf16 v[12:15], v[164:167], v[196:199], v[12:15]
	v_mfma_f32_16x16x32_bf16 v[62:65], v[156:159], v[172:175], v[120:123]
	v_mfma_f32_16x16x32_bf16 v[116:119], v[168:171], v[176:179], v[116:119]
	v_mfma_f32_16x16x32_bf16 v[84:87], v[160:163], v[184:187], v[84:87]
	v_mfma_f32_16x16x32_bf16 v[76:79], v[168:171], v[184:187], v[76:79]
	v_mfma_f32_16x16x32_bf16 v[56:59], v[160:163], v[192:195], v[56:59]
	v_mfma_f32_16x16x32_bf16 v[52:55], v[168:171], v[192:195], v[52:55]
	v_mfma_f32_16x16x32_bf16 v[20:23], v[160:163], v[200:203], v[20:23]
	v_mfma_f32_16x16x32_bf16 v[12:15], v[168:171], v[200:203], v[12:15]
	v_mfma_f32_16x16x32_bf16 v[62:65], v[160:163], v[176:179], v[62:65]
	s_barrier
	v_add_u32_e32 v6, 0x18000, v1
	v_add_u32_e32 v1, 0x1c000, v1
	ds_read_b128 v[120:123], v6
	ds_read_b128 v[140:143], v6 offset:1024
	ds_read_b128 v[144:147], v6 offset:2048
	ds_read_b128 v[152:155], v6 offset:3072
	ds_read_b128 v[156:159], v1
	ds_read_b128 v[160:163], v1 offset:1024
	ds_read_b128 v[164:167], v1 offset:2048
	ds_read_b128 v[168:171], v1 offset:3072
	ds_read_b128 v[172:175], v151 offset:32768
	ds_read_b128 v[176:179], v151 offset:33792
	ds_read_b128 v[180:183], v151 offset:34816
	ds_read_b128 v[184:187], v151 offset:35840
	ds_read_b128 v[188:191], v151 offset:36864
	ds_read_b128 v[192:195], v151 offset:37888
	ds_read_b128 v[196:199], v151 offset:38912
	ds_read_b128 v[200:203], v151 offset:39936
	s_add_u32 s48, s87, 0x100
	s_addc_u32 s49, s92, 0
	s_add_u32 s88, s93, 0x100
	s_mov_b32 m0, s65
	s_nop 0
	global_load_lds_dwordx4 v60, s[48:49]
	s_addc_u32 s89, s94, 0
	s_mov_b32 m0, s66
	s_nop 0
	global_load_lds_dwordx4 v60, s[88:89]
	s_waitcnt vmcnt(8)
	s_waitcnt lgkmcnt(0)
	s_barrier
	s_waitcnt lgkmcnt(7)
	v_mfma_f32_16x16x32_bf16 v[24:27], v[120:123], v[172:175], v[24:27]
	v_mfma_f32_16x16x32_bf16 v[16:19], v[144:147], v[172:175], v[16:19]
	s_waitcnt lgkmcnt(5)
	v_mfma_f32_16x16x32_bf16 v[28:31], v[120:123], v[180:183], v[28:31]
	v_mfma_f32_16x16x32_bf16 v[32:35], v[144:147], v[180:183], v[32:35]
	s_waitcnt lgkmcnt(3)
	v_mfma_f32_16x16x32_bf16 v[88:91], v[120:123], v[188:191], v[88:91]
	v_mfma_f32_16x16x32_bf16 v[80:83], v[144:147], v[188:191], v[80:83]
	s_waitcnt lgkmcnt(1)
	v_mfma_f32_16x16x32_bf16 v[92:95], v[120:123], v[196:199], v[92:95]
	v_mfma_f32_16x16x32_bf16 v[96:99], v[144:147], v[196:199], v[96:99]
	v_mfma_f32_16x16x32_bf16 v[24:27], v[140:143], v[176:179], v[24:27]
	v_mfma_f32_16x16x32_bf16 v[16:19], v[152:155], v[176:179], v[16:19]
	v_mfma_f32_16x16x32_bf16 v[28:31], v[140:143], v[184:187], v[28:31]
	v_mfma_f32_16x16x32_bf16 v[32:35], v[152:155], v[184:187], v[32:35]
	v_mfma_f32_16x16x32_bf16 v[88:91], v[140:143], v[192:195], v[88:91]
	v_mfma_f32_16x16x32_bf16 v[80:83], v[152:155], v[192:195], v[80:83]
	s_waitcnt lgkmcnt(0)
	v_mfma_f32_16x16x32_bf16 v[92:95], v[140:143], v[200:203], v[92:95]
	v_mfma_f32_16x16x32_bf16 v[96:99], v[152:155], v[200:203], v[96:99]
	v_mfma_f32_16x16x32_bf16 v[6:9], v[156:159], v[172:175], v[8:11]
	v_mfma_f32_16x16x32_bf16 v[2:5], v[164:167], v[172:175], v[2:5]
	v_mfma_f32_16x16x32_bf16 v[44:47], v[156:159], v[180:183], v[44:47]
	v_mfma_f32_16x16x32_bf16 v[48:51], v[164:167], v[180:183], v[48:51]
	v_mfma_f32_16x16x32_bf16 v[70:73], v[156:159], v[188:191], v[72:75]
	v_mfma_f32_16x16x32_bf16 v[66:69], v[164:167], v[188:191], v[66:69]
	v_mfma_f32_16x16x32_bf16 v[108:111], v[156:159], v[196:199], v[108:111]
	v_mfma_f32_16x16x32_bf16 v[112:115], v[164:167], v[196:199], v[112:115]
	v_mfma_f32_16x16x32_bf16 v[8:11], v[160:163], v[176:179], v[6:9]
	v_mfma_f32_16x16x32_bf16 v[4:7], v[168:171], v[176:179], v[2:5]
	v_mfma_f32_16x16x32_bf16 v[44:47], v[160:163], v[184:187], v[44:47]
	v_mfma_f32_16x16x32_bf16 v[48:51], v[168:171], v[184:187], v[48:51]
	v_mfma_f32_16x16x32_bf16 v[72:75], v[160:163], v[192:195], v[70:73]
	v_mfma_f32_16x16x32_bf16 v[68:71], v[168:171], v[192:195], v[66:69]
	v_mfma_f32_16x16x32_bf16 v[108:111], v[160:163], v[200:203], v[108:111]
	v_mfma_f32_16x16x32_bf16 v[112:115], v[168:171], v[200:203], v[112:115]
	s_barrier
	s_add_u32 s48, s95, 0x180
	s_addc_u32 s49, s96, 0
	ds_read_b128 v[172:175], v151 offset:49152
	ds_read_b128 v[176:179], v151 offset:50176
	ds_read_b128 v[180:183], v151 offset:51200
	ds_read_b128 v[184:187], v151 offset:52224
	ds_read_b128 v[188:191], v151 offset:53248
	ds_read_b128 v[192:195], v151 offset:54272
	ds_read_b128 v[196:199], v151 offset:55296
	ds_read_b128 v[200:203], v151 offset:56320
	s_add_u32 s88, s97, 0x180
	s_mov_b32 m0, s67
	s_nop 0
	global_load_lds_dwordx4 v61, s[48:49]
	s_addc_u32 s89, vcc_lo, 0
	s_mov_b32 m0, s73
	s_nop 0
	global_load_lds_dwordx4 v61, s[88:89]
	s_add_u32 s48, vcc_hi, 0x180
	s_addc_u32 s49, s59, 0
	s_add_u32 s88, s30, 0x180
	s_addc_u32 s89, s31, 0
	s_mov_b32 m0, s82
	s_nop 0
	global_load_lds_dwordx4 v61, s[48:49]
	s_add_u32 s48, s80, 0x180
	s_mov_b32 m0, s83
	s_nop 0
	global_load_lds_dwordx4 v61, s[88:89]
	s_addc_u32 s49, s81, 0
	s_add_u32 s80, s58, 0x180
	s_mov_b32 m0, s78
	s_nop 0
	global_load_lds_dwordx4 v60, s[48:49]
	s_addc_u32 s81, s90, 0
	s_mov_b32 m0, s79
	s_nop 0
	global_load_lds_dwordx4 v60, s[80:81]
	s_waitcnt vmcnt(8)
	s_waitcnt lgkmcnt(0)
	s_barrier
	s_waitcnt lgkmcnt(7)
	v_mfma_f32_16x16x32_bf16 v[136:139], v[120:123], v[172:175], v[136:139]
	v_mfma_f32_16x16x32_bf16 v[132:135], v[144:147], v[172:175], v[132:135]
	s_waitcnt lgkmcnt(5)
	v_mfma_f32_16x16x32_bf16 v[104:107], v[120:123], v[180:183], v[104:107]
	v_mfma_f32_16x16x32_bf16 v[100:103], v[144:147], v[180:183], v[100:103]
	s_waitcnt lgkmcnt(3)
	v_mfma_f32_16x16x32_bf16 v[128:131], v[120:123], v[188:191], v[128:131]
	v_mfma_f32_16x16x32_bf16 v[124:127], v[144:147], v[188:191], v[124:127]
	s_waitcnt lgkmcnt(1)
	v_mfma_f32_16x16x32_bf16 v[40:43], v[120:123], v[196:199], v[40:43]
	v_mfma_f32_16x16x32_bf16 v[36:39], v[144:147], v[196:199], v[36:39]
	v_mfma_f32_16x16x32_bf16 v[136:139], v[140:143], v[176:179], v[136:139]
	v_mfma_f32_16x16x32_bf16 v[132:135], v[152:155], v[176:179], v[132:135]
	v_mfma_f32_16x16x32_bf16 v[104:107], v[140:143], v[184:187], v[104:107]
	v_mfma_f32_16x16x32_bf16 v[100:103], v[152:155], v[184:187], v[100:103]
	v_mfma_f32_16x16x32_bf16 v[128:131], v[140:143], v[192:195], v[128:131]
	v_mfma_f32_16x16x32_bf16 v[124:127], v[152:155], v[192:195], v[124:127]
	s_waitcnt lgkmcnt(0)
	v_mfma_f32_16x16x32_bf16 v[40:43], v[140:143], v[200:203], v[40:43]
	v_mfma_f32_16x16x32_bf16 v[36:39], v[152:155], v[200:203], v[36:39]
	v_mfma_f32_16x16x32_bf16 v[62:65], v[156:159], v[172:175], v[62:65]
	v_mfma_f32_16x16x32_bf16 v[120:123], v[160:163], v[176:179], v[62:65]
	v_mfma_f32_16x16x32_bf16 v[62:65], v[164:167], v[172:175], v[116:119]
	v_mfma_f32_16x16x32_bf16 v[116:119], v[168:171], v[176:179], v[62:65]
	v_mfma_f32_16x16x32_bf16 v[62:65], v[156:159], v[180:183], v[84:87]
	v_mfma_f32_16x16x32_bf16 v[84:87], v[160:163], v[184:187], v[62:65]
	v_mfma_f32_16x16x32_bf16 v[62:65], v[164:167], v[180:183], v[76:79]
	v_mfma_f32_16x16x32_bf16 v[56:59], v[156:159], v[188:191], v[56:59]
	v_mfma_f32_16x16x32_bf16 v[52:55], v[164:167], v[188:191], v[52:55]
	v_mfma_f32_16x16x32_bf16 v[20:23], v[156:159], v[196:199], v[20:23]
	v_mfma_f32_16x16x32_bf16 v[12:15], v[164:167], v[196:199], v[12:15]
	v_mfma_f32_16x16x32_bf16 v[76:79], v[168:171], v[184:187], v[62:65]
	v_mfma_f32_16x16x32_bf16 v[56:59], v[160:163], v[192:195], v[56:59]
	v_mfma_f32_16x16x32_bf16 v[52:55], v[168:171], v[192:195], v[52:55]
	v_mfma_f32_16x16x32_bf16 v[20:23], v[160:163], v[200:203], v[20:23]
	v_mfma_f32_16x16x32_bf16 v[12:15], v[168:171], v[200:203], v[12:15]
	s_barrier
	s_add_u32 s46, s46, 0x100
	s_addc_u32 s47, s47, 0
	s_cmp_ge_i32 s77, s0
	s_cbranch_scc0 .LBB0_702

.LBB0_705:
	v_add_u32_e32 v1, 0, v150
	v_add_u32_e32 v2, 0x10000, v1
	ds_read_b128 v[62:65], v2
	ds_read_b128 v[140:143], v2 offset:1024
	ds_read_b128 v[152:155], v2 offset:2048
	ds_read_b128 v[156:159], v2 offset:3072
	v_add_u32_e32 v2, 0x14000, v1
	ds_read_b128 v[160:163], v2
	ds_read_b128 v[164:167], v2 offset:1024
	ds_read_b128 v[168:171], v2 offset:2048
	ds_read_b128 v[172:175], v2 offset:3072
	s_ashr_i32 s25, s24, 31
	s_lshl_b64 s[24:25], s[24:25], 7
	v_add_u32_e32 v146, 0, v149
	s_add_u32 s0, s4, s24
	ds_read_b128 v[176:179], v146
	ds_read_b128 v[180:183], v146 offset:1024
	ds_read_b128 v[184:187], v146 offset:2048
	ds_read_b128 v[188:191], v146 offset:3072
	ds_read_b128 v[192:195], v146 offset:4096
	ds_read_b128 v[196:199], v146 offset:5120
	ds_read_b128 v[200:203], v146 offset:6144
	ds_read_b128 v[204:207], v146 offset:7168
	s_addc_u32 s4, s5, s25
	s_add_u32 s0, s0, s54
	s_addc_u32 s5, s4, s55
	s_add_u32 s4, s0, 0xffffff80
	s_addc_u32 s5, s5, -1
	s_add_u32 s24, s4, s52
	s_mov_b32 m0, s84
	s_nop 0
	global_load_lds_dwordx4 v60, s[4:5]
	s_addc_u32 s25, s5, s53
	s_mov_b32 m0, s85
	s_nop 0
	global_load_lds_dwordx4 v60, s[24:25]
	s_waitcnt vmcnt(8)
	s_waitcnt lgkmcnt(0)
	s_barrier
	s_waitcnt lgkmcnt(5)
	v_mfma_f32_16x16x32_bf16 v[28:31], v[62:65], v[184:187], v[28:31]
	v_mfma_f32_16x16x32_bf16 v[32:35], v[152:155], v[184:187], v[32:35]
	s_waitcnt lgkmcnt(3)
	v_mfma_f32_16x16x32_bf16 v[88:91], v[62:65], v[192:195], v[88:91]
	v_mfma_f32_16x16x32_bf16 v[80:83], v[152:155], v[192:195], v[80:83]
	s_waitcnt lgkmcnt(1)
	v_mfma_f32_16x16x32_bf16 v[92:95], v[62:65], v[200:203], v[92:95]
	v_mfma_f32_16x16x32_bf16 v[96:99], v[152:155], v[200:203], v[96:99]
	v_mfma_f32_16x16x32_bf16 v[24:27], v[62:65], v[176:179], v[24:27]
	v_mfma_f32_16x16x32_bf16 v[16:19], v[152:155], v[176:179], v[16:19]
	v_mfma_f32_16x16x32_bf16 v[28:31], v[140:143], v[188:191], v[28:31]
	v_mfma_f32_16x16x32_bf16 v[32:35], v[156:159], v[188:191], v[32:35]
	v_mfma_f32_16x16x32_bf16 v[88:91], v[140:143], v[196:199], v[88:91]
	v_mfma_f32_16x16x32_bf16 v[80:83], v[156:159], v[196:199], v[80:83]
	s_waitcnt lgkmcnt(0)
	v_mfma_f32_16x16x32_bf16 v[92:95], v[140:143], v[204:207], v[92:95]
	v_mfma_f32_16x16x32_bf16 v[96:99], v[156:159], v[204:207], v[96:99]
	v_mfma_f32_16x16x32_bf16 v[24:27], v[140:143], v[180:183], v[24:27]
	v_mfma_f32_16x16x32_bf16 v[16:19], v[156:159], v[180:183], v[16:19]
	v_mfma_f32_16x16x32_bf16 v[2:5], v[168:171], v[176:179], v[4:7]
	v_mfma_f32_16x16x32_bf16 v[8:11], v[160:163], v[176:179], v[8:11]
	v_mfma_f32_16x16x32_bf16 v[176:179], v[172:175], v[180:183], v[2:5]
	v_mfma_f32_16x16x32_bf16 v[2:5], v[160:163], v[184:187], v[44:47]
	v_mfma_f32_16x16x32_bf16 v[44:47], v[164:167], v[188:191], v[2:5]
	v_mfma_f32_16x16x32_bf16 v[2:5], v[168:171], v[184:187], v[48:51]
	v_mfma_f32_16x16x32_bf16 v[48:51], v[172:175], v[188:191], v[2:5]
	v_mfma_f32_16x16x32_bf16 v[2:5], v[160:163], v[192:195], v[72:75]
	v_mfma_f32_16x16x32_bf16 v[208:211], v[164:167], v[180:183], v[8:11]
	v_mfma_f32_16x16x32_bf16 v[180:183], v[164:167], v[196:199], v[2:5]
	v_mfma_f32_16x16x32_bf16 v[2:5], v[168:171], v[192:195], v[68:71]
	v_mfma_f32_16x16x32_bf16 v[184:187], v[172:175], v[196:199], v[2:5]
	v_mfma_f32_16x16x32_bf16 v[2:5], v[160:163], v[200:203], v[108:111]
	v_mfma_f32_16x16x32_bf16 v[108:111], v[164:167], v[204:207], v[2:5]
	v_mfma_f32_16x16x32_bf16 v[2:5], v[168:171], v[200:203], v[112:115]
	v_mfma_f32_16x16x32_bf16 v[112:115], v[172:175], v[204:207], v[2:5]
	s_barrier
	s_add_u32 s24, s6, s28
	s_nop 3
	ds_read_b128 v[2:5], v146 offset:16384
	ds_read_b128 v[6:9], v146 offset:17408
	ds_read_b128 v[66:69], v146 offset:18432
	ds_read_b128 v[70:73], v146 offset:19456
	ds_read_b128 v[188:191], v146 offset:20480
	ds_read_b128 v[192:195], v146 offset:21504
	ds_read_b128 v[196:199], v146 offset:22528
	ds_read_b128 v[200:203], v146 offset:23552
	s_addc_u32 s25, s7, s29
	s_mov_b32 m0, s60
	s_nop 0
	global_load_lds_dwordx4 v145, s[6:7]
	s_add_u32 s52, s6, s34
	s_mov_b32 m0, s61
	s_nop 0
	global_load_lds_dwordx4 v145, s[24:25]
	s_addc_u32 s53, s7, s35
	s_add_u32 s54, s52, s28
	s_mov_b32 m0, s62
	s_nop 0
	global_load_lds_dwordx4 v145, s[52:53]
	s_addc_u32 s55, s53, s29
	s_mov_b32 m0, s63
	s_nop 0
	global_load_lds_dwordx4 v145, s[54:55]
	s_add_u32 s4, s50, s48
	s_mov_b32 m0, s57
	s_nop 0
	global_load_lds_dwordx4 v144, s[50:51]
	s_addc_u32 s5, s51, s49
	s_mov_b32 m0, s64
	s_nop 0
	global_load_lds_dwordx4 v144, s[4:5]
	s_waitcnt vmcnt(8)
	s_waitcnt lgkmcnt(0)
	s_barrier
	s_waitcnt lgkmcnt(5)
	v_mfma_f32_16x16x32_bf16 v[104:107], v[62:65], v[66:69], v[104:107]
	v_mfma_f32_16x16x32_bf16 v[100:103], v[152:155], v[66:69], v[100:103]
	s_waitcnt lgkmcnt(3)
	v_mfma_f32_16x16x32_bf16 v[128:131], v[62:65], v[188:191], v[128:131]
	v_mfma_f32_16x16x32_bf16 v[124:127], v[152:155], v[188:191], v[124:127]
	s_waitcnt lgkmcnt(1)
	v_mfma_f32_16x16x32_bf16 v[40:43], v[62:65], v[196:199], v[40:43]
	v_mfma_f32_16x16x32_bf16 v[36:39], v[152:155], v[196:199], v[36:39]
	v_mfma_f32_16x16x32_bf16 v[136:139], v[62:65], v[2:5], v[136:139]
	v_mfma_f32_16x16x32_bf16 v[132:135], v[152:155], v[2:5], v[132:135]
	v_mfma_f32_16x16x32_bf16 v[104:107], v[140:143], v[70:73], v[104:107]
	v_mfma_f32_16x16x32_bf16 v[100:103], v[156:159], v[70:73], v[100:103]
	v_mfma_f32_16x16x32_bf16 v[128:131], v[140:143], v[192:195], v[128:131]
	v_mfma_f32_16x16x32_bf16 v[124:127], v[156:159], v[192:195], v[124:127]
	s_waitcnt lgkmcnt(0)
	v_mfma_f32_16x16x32_bf16 v[40:43], v[140:143], v[200:203], v[40:43]
	v_mfma_f32_16x16x32_bf16 v[36:39], v[156:159], v[200:203], v[36:39]
	v_mfma_f32_16x16x32_bf16 v[204:207], v[140:143], v[6:9], v[136:139]
	v_mfma_f32_16x16x32_bf16 v[212:215], v[156:159], v[6:9], v[132:135]
	v_mfma_f32_16x16x32_bf16 v[60:63], v[160:163], v[2:5], v[120:123]
	v_mfma_f32_16x16x32_bf16 v[2:5], v[168:171], v[2:5], v[116:119]
	v_mfma_f32_16x16x32_bf16 v[140:143], v[172:175], v[6:9], v[2:5]
	v_mfma_f32_16x16x32_bf16 v[2:5], v[160:163], v[66:69], v[84:87]
	v_mfma_f32_16x16x32_bf16 v[84:87], v[164:167], v[70:73], v[2:5]
	v_mfma_f32_16x16x32_bf16 v[2:5], v[168:171], v[66:69], v[76:79]
	v_mfma_f32_16x16x32_bf16 v[64:67], v[172:175], v[70:73], v[2:5]
	v_mfma_f32_16x16x32_bf16 v[2:5], v[160:163], v[188:191], v[56:59]
	v_mfma_f32_16x16x32_bf16 v[152:155], v[164:167], v[192:195], v[2:5]
	v_mfma_f32_16x16x32_bf16 v[2:5], v[168:171], v[188:191], v[52:55]
	v_mfma_f32_16x16x32_bf16 v[156:159], v[172:175], v[192:195], v[2:5]
	v_mfma_f32_16x16x32_bf16 v[2:5], v[160:163], v[196:199], v[20:23]
	v_mfma_f32_16x16x32_bf16 v[20:23], v[164:167], v[200:203], v[2:5]
	v_mfma_f32_16x16x32_bf16 v[2:5], v[168:171], v[196:199], v[12:15]
	v_mfma_f32_16x16x32_bf16 v[60:63], v[164:167], v[6:9], v[60:63]
	v_mfma_f32_16x16x32_bf16 v[10:13], v[172:175], v[200:203], v[2:5]
	s_barrier
	s_nop 3
	v_add_u32_e32 v2, 0x18000, v1
	v_add_u32_e32 v1, 0x1c000, v1
	ds_read_b128 v[76:79], v2
	ds_read_b128 v[160:163], v2 offset:1024
	ds_read_b128 v[164:167], v2 offset:2048
	ds_read_b128 v[168:171], v2 offset:3072
	ds_read_b128 v[172:175], v1
	ds_read_b128 v[188:191], v1 offset:1024
	ds_read_b128 v[192:195], v1 offset:2048
	ds_read_b128 v[196:199], v1 offset:3072
	ds_read_b128 v[52:55], v146 offset:32768
	ds_read_b128 v[56:59], v146 offset:33792
	ds_read_b128 v[116:119], v146 offset:34816
	ds_read_b128 v[120:123], v146 offset:35840
	ds_read_b128 v[136:139], v146 offset:36864
	ds_read_b128 v[200:203], v146 offset:37888
	ds_read_b128 v[216:219], v146 offset:38912
	ds_read_b128 v[220:223], v146 offset:39936
	s_add_u32 s68, s50, s46
	s_addc_u32 s69, s51, s47
	s_add_u32 s70, s68, s48
	s_mov_b32 m0, s65
	s_nop 0
	global_load_lds_dwordx4 v144, s[68:69]
	s_addc_u32 s71, s69, s49
	s_mov_b32 m0, s66
	s_nop 0
	global_load_lds_dwordx4 v144, s[70:71]
	s_waitcnt vmcnt(8)
	s_waitcnt lgkmcnt(0)
	s_barrier
	s_waitcnt lgkmcnt(7)
	v_mfma_f32_16x16x32_bf16 v[6:9], v[164:167], v[52:55], v[16:19]
	s_waitcnt lgkmcnt(5)
	v_mfma_f32_16x16x32_bf16 v[14:17], v[76:79], v[116:119], v[28:31]
	s_waitcnt lgkmcnt(4)
	v_mfma_f32_16x16x32_bf16 v[28:31], v[160:163], v[120:123], v[14:17]
	v_mfma_f32_16x16x32_bf16 v[14:17], v[164:167], v[116:119], v[32:35]
	v_mfma_f32_16x16x32_bf16 v[32:35], v[168:171], v[120:123], v[14:17]
	s_waitcnt lgkmcnt(3)
	v_mfma_f32_16x16x32_bf16 v[14:17], v[76:79], v[136:139], v[88:91]
	s_waitcnt lgkmcnt(2)
	v_mfma_f32_16x16x32_bf16 v[68:71], v[160:163], v[200:203], v[14:17]
	v_mfma_f32_16x16x32_bf16 v[14:17], v[164:167], v[136:139], v[80:83]
	v_mfma_f32_16x16x32_bf16 v[72:75], v[168:171], v[200:203], v[14:17]
	s_waitcnt lgkmcnt(1)
	v_mfma_f32_16x16x32_bf16 v[14:17], v[76:79], v[216:219], v[92:95]
	v_mfma_f32_16x16x32_bf16 v[2:5], v[76:79], v[52:55], v[24:27]
	s_waitcnt lgkmcnt(0)
	v_mfma_f32_16x16x32_bf16 v[92:95], v[160:163], v[220:223], v[14:17]
	v_mfma_f32_16x16x32_bf16 v[14:17], v[164:167], v[216:219], v[96:99]
	v_mfma_f32_16x16x32_bf16 v[2:5], v[160:163], v[56:59], v[2:5]
	v_mfma_f32_16x16x32_bf16 v[6:9], v[168:171], v[56:59], v[6:9]
	v_mfma_f32_16x16x32_bf16 v[96:99], v[168:171], v[220:223], v[14:17]
	v_mfma_f32_16x16x32_bf16 v[14:17], v[172:175], v[52:55], v[208:211]
	v_mfma_f32_16x16x32_bf16 v[80:83], v[188:191], v[56:59], v[14:17]
	v_mfma_f32_16x16x32_bf16 v[14:17], v[192:195], v[52:55], v[176:179]
	v_mfma_f32_16x16x32_bf16 v[88:91], v[196:199], v[56:59], v[14:17]
	v_mfma_f32_16x16x32_bf16 v[14:17], v[172:175], v[116:119], v[44:47]
	v_mfma_f32_16x16x32_bf16 v[44:47], v[188:191], v[120:123], v[14:17]
	v_mfma_f32_16x16x32_bf16 v[14:17], v[192:195], v[116:119], v[48:51]
	v_mfma_f32_16x16x32_bf16 v[48:51], v[196:199], v[120:123], v[14:17]
	v_mfma_f32_16x16x32_bf16 v[14:17], v[172:175], v[136:139], v[180:183]
	v_mfma_f32_16x16x32_bf16 v[132:135], v[188:191], v[200:203], v[14:17]
	v_mfma_f32_16x16x32_bf16 v[14:17], v[192:195], v[136:139], v[184:187]
	v_mfma_f32_16x16x32_bf16 v[136:139], v[196:199], v[200:203], v[14:17]
	v_mfma_f32_16x16x32_bf16 v[14:17], v[172:175], v[216:219], v[108:111]
	v_mfma_f32_16x16x32_bf16 v[108:111], v[188:191], v[220:223], v[14:17]
	v_mfma_f32_16x16x32_bf16 v[14:17], v[192:195], v[216:219], v[112:115]
	v_mfma_f32_16x16x32_bf16 v[112:115], v[196:199], v[220:223], v[14:17]
	s_barrier
	s_add_u32 s68, s6, 0x80
	s_addc_u32 s69, s7, 0
	s_add_u32 s24, s24, 0x80
	s_nop 1
	ds_read_b128 v[14:17], v146 offset:49152
	ds_read_b128 v[24:27], v146 offset:50176
	ds_read_b128 v[176:179], v146 offset:51200
	ds_read_b128 v[180:183], v146 offset:52224
	ds_read_b128 v[184:187], v146 offset:53248
	ds_read_b128 v[200:203], v146 offset:54272
	ds_read_b128 v[208:211], v146 offset:55296
	ds_read_b128 v[216:219], v146 offset:56320
	s_addc_u32 s25, s25, 0
	s_mov_b32 m0, s67
	s_nop 0
	global_load_lds_dwordx4 v145, s[68:69]
	s_nop 0
	s_mov_b32 m0, s73
	s_nop 0
	global_load_lds_dwordx4 v145, s[24:25]
	s_add_u32 s24, s52, 0x80
	s_addc_u32 s25, s53, 0
	s_add_u32 s52, s54, 0x80
	s_addc_u32 s53, s55, 0
	s_mov_b32 m0, s82
	s_nop 0
	global_load_lds_dwordx4 v145, s[24:25]
	s_add_u32 s24, s50, 0x80
	s_mov_b32 m0, s83
	s_nop 0
	global_load_lds_dwordx4 v145, s[52:53]
	s_addc_u32 s25, s51, 0
	s_add_u32 s4, s4, 0x80
	s_mov_b32 m0, s78
	s_nop 0
	global_load_lds_dwordx4 v144, s[24:25]
	s_addc_u32 s5, s5, 0
	s_mov_b32 m0, s79
	s_nop 0
	global_load_lds_dwordx4 v144, s[4:5]
	s_waitcnt vmcnt(8)
	s_waitcnt lgkmcnt(0)
	s_barrier
	s_waitcnt lgkmcnt(7)
	v_mfma_f32_16x16x32_bf16 v[52:55], v[76:79], v[14:17], v[204:207]
	s_waitcnt lgkmcnt(6)
	v_mfma_f32_16x16x32_bf16 v[116:119], v[160:163], v[24:27], v[52:55]
	v_mfma_f32_16x16x32_bf16 v[52:55], v[164:167], v[14:17], v[212:215]
	v_mfma_f32_16x16x32_bf16 v[120:123], v[168:171], v[24:27], v[52:55]
	s_waitcnt lgkmcnt(5)
	v_mfma_f32_16x16x32_bf16 v[52:55], v[76:79], v[176:179], v[104:107]
	s_waitcnt lgkmcnt(4)
	v_mfma_f32_16x16x32_bf16 v[104:107], v[160:163], v[180:183], v[52:55]
	v_mfma_f32_16x16x32_bf16 v[52:55], v[164:167], v[176:179], v[100:103]
	v_mfma_f32_16x16x32_bf16 v[100:103], v[168:171], v[180:183], v[52:55]
	s_waitcnt lgkmcnt(3)
	v_mfma_f32_16x16x32_bf16 v[52:55], v[76:79], v[184:187], v[128:131]
	v_mfma_f32_16x16x32_bf16 v[56:59], v[164:167], v[184:187], v[124:127]
	s_waitcnt lgkmcnt(1)
	v_mfma_f32_16x16x32_bf16 v[40:43], v[76:79], v[208:211], v[40:43]
	v_mfma_f32_16x16x32_bf16 v[36:39], v[164:167], v[208:211], v[36:39]
	v_mfma_f32_16x16x32_bf16 v[52:55], v[160:163], v[200:203], v[52:55]
	v_mfma_f32_16x16x32_bf16 v[56:59], v[168:171], v[200:203], v[56:59]
	s_waitcnt lgkmcnt(0)
	v_mfma_f32_16x16x32_bf16 v[40:43], v[160:163], v[216:219], v[40:43]
	v_mfma_f32_16x16x32_bf16 v[36:39], v[168:171], v[216:219], v[36:39]
	v_mfma_f32_16x16x32_bf16 v[60:63], v[172:175], v[14:17], v[60:63]
	v_mfma_f32_16x16x32_bf16 v[14:17], v[192:195], v[14:17], v[140:143]
	v_mfma_f32_16x16x32_bf16 v[128:131], v[196:199], v[24:27], v[14:17]
	v_mfma_f32_16x16x32_bf16 v[14:17], v[172:175], v[176:179], v[84:87]
	v_mfma_f32_16x16x32_bf16 v[84:87], v[188:191], v[180:183], v[14:17]
	v_mfma_f32_16x16x32_bf16 v[14:17], v[192:195], v[176:179], v[64:67]
	v_mfma_f32_16x16x32_bf16 v[76:79], v[196:199], v[180:183], v[14:17]
	v_mfma_f32_16x16x32_bf16 v[14:17], v[172:175], v[184:187], v[152:155]
	v_mfma_f32_16x16x32_bf16 v[124:127], v[188:191], v[24:27], v[60:63]
	v_mfma_f32_16x16x32_bf16 v[60:63], v[188:191], v[200:203], v[14:17]
	v_mfma_f32_16x16x32_bf16 v[14:17], v[192:195], v[184:187], v[156:159]
	v_mfma_f32_16x16x32_bf16 v[64:67], v[196:199], v[200:203], v[14:17]
	v_mfma_f32_16x16x32_bf16 v[14:17], v[172:175], v[208:211], v[20:23]
	v_mfma_f32_16x16x32_bf16 v[10:13], v[192:195], v[208:211], v[10:13]
	v_mfma_f32_16x16x32_bf16 v[20:23], v[188:191], v[216:219], v[14:17]
	v_mfma_f32_16x16x32_bf16 v[12:15], v[196:199], v[216:219], v[10:13]
	s_barrier
	s_andn2_b64 vcc, exec, s[26:27]
	s_cbranch_vccnz .LBB0_707
	s_barrier

.LBB0_776:
	s_lshl_b32 s65, s2, 6
	v_ashrrev_i32_e32 v1, 6, v2
	s_lshl_b32 s2, s2, 13
	v_and_b32_e32 v3, 48, v2
	v_lshl_add_u32 v4, v1, 10, s2
	v_lshlrev_b32_e32 v5, 6, v2
	s_movk_i32 s2, 0x3c0
	v_and_or_b32 v3, v5, s2, v3
	s_lshl_b32 s2, s76, 5
	s_and_b32 s66, s2, 0x60
	s_lshl_b64 s[48:49], s[16:17], 7
	s_lshl_b64 s[30:31], s[20:21], 7
	s_lshr_b32 s2, s66, 3
	s_add_u32 s16, s6, 0x80
	s_addc_u32 s17, s7, 0
	v_add_lshl_u32 v1, v1, s2, 10
	s_sub_u32 s2, 0, s0
	s_subb_u32 s20, 0, s1
	s_add_u32 s2, s12, s2
	s_addc_u32 s21, s13, s20
	s_add_u32 s20, s2, 0x80
	s_addc_u32 s21, s21, 0
	s_add_i32 s67, s3, 0x18000
	s_add_i32 s73, s3, 0x1a000
	s_mov_b32 s98, 0
	s_cselect_b32 s99, 1, 0
	s_cmp_lt_u32 s76, 4
	s_cbranch_scc0 .Lsprio_9
	s_setprio 1
.Lsprio_9:
	s_cmp_lg_u32 s99, 0
	s_waitcnt vmcnt(2)
	s_barrier
	s_mov_b32 m0, s67
	s_nop 0
	global_load_lds_dwordx4 v0, s[16:17]
	s_add_u32 s16, s4, 0x80
	s_mov_b32 m0, s73
	s_nop 0
	global_load_lds_dwordx4 v0, s[20:21]
	s_addc_u32 s17, s5, 0
	s_sub_u32 s2, 0, s46
	s_subb_u32 s20, 0, s47
	s_add_u32 s2, s18, s2
	s_addc_u32 s19, s19, s20
	s_add_u32 s18, s2, 0x80
	s_addc_u32 s19, s19, 0
	s_add_i32 s78, s3, 0x8000
	s_add_i32 s79, s3, 0xa000
	s_add_u32 s12, s12, 0x80
	s_mov_b32 m0, s78
	s_nop 0
	global_load_lds_dwordx4 v128, s[16:17]
	s_addc_u32 s13, s13, 0
	s_mov_b32 m0, s79
	s_nop 0
	global_load_lds_dwordx4 v128, s[18:19]
	s_add_u32 s14, s14, 0x80
	v_lshlrev_b32_e32 v2, 2, v2
	s_addc_u32 s15, s15, 0
	s_add_i32 s82, s3, 0x1c000
	s_mov_b32 m0, s82
	s_nop 0
	global_load_lds_dwordx4 v0, s[12:13]
	v_and_b32_e32 v2, 32, v2
	s_add_i32 s83, s3, 0x1e000
	s_mov_b32 m0, s83
	s_nop 0
	global_load_lds_dwordx4 v0, s[14:15]
	v_bitop3_b32 v1, v3, v1, v2 bitop3:0xde
	s_waitcnt vmcnt(6)
	s_add_i32 s84, s3, 0xc000
	s_add_i32 s85, s3, 0xe000
	v_readlane_b32 s2, v254, 0
	v_mov_b32_e32 v129, v0
	v_bitop3_b32 v4, v3, v4, v2 bitop3:0xde
	s_cmpk_lt_u32 s2, 0x100
	v_add_u32_e32 v0, 0, v1
	s_mov_b32 s38, s25
	s_mov_b32 s39, s26
	s_mov_b32 s35, 0
	s_cselect_b64 s[36:37], -1, 0
	v_add_u32_e32 v137, 0x10000, v0
	v_add_u32_e32 v138, 0x14000, v0
	v_add_u32_e32 v139, 0, v4
	v_add_u32_e32 v140, 0x18000, v0
	v_add_u32_e32 v141, 0x1c000, v0
	s_mov_b32 s86, 0
	s_mov_b32 s26, s27
	s_barrier
	s_branch .LBB0_779

.LBB0_781:
	s_cmp_lt_i32 s24, 3
	s_cbranch_scc1 .Lhz_783
	s_add_i32 s2, s24, -2
	s_add_u32 s23, s4, s48
	s_addc_u32 s25, s5, s49
	s_add_u32 s27, s6, s30
	s_addc_u32 s33, s7, s31
	s_add_u32 s34, s0, s30
	s_addc_u32 s41, s1, s31
	s_add_u32 s34, s6, s34
	s_addc_u32 s41, s7, s41
	s_add_u32 s54, s6, s0
	s_addc_u32 s55, s7, s1
	s_add_u32 s50, s46, s48
	s_addc_u32 s51, s47, s49
	s_add_u32 s68, s4, s50
	s_addc_u32 s69, s5, s51
	s_add_u32 s70, s4, s46
	s_addc_u32 s71, s5, s47
	s_mov_b32 s72, 0
	s_mov_b64 s[50:51], 0
	s_cmp_eq_u32 s98, 0
	s_cbranch_scc1 .Lhf_783
	ds_read_b128 v[130:133], v137
	ds_read_b128 v[142:145], v137 offset:1024
	ds_read_b128 v[146:149], v137 offset:2048
	ds_read_b128 v[150:153], v137 offset:3072
	ds_read_b128 v[154:157], v138
	ds_read_b128 v[158:161], v138 offset:1024
	ds_read_b128 v[162:165], v138 offset:2048
	ds_read_b128 v[166:169], v138 offset:3072
	s_add_i32 s72, s72, 2
	s_add_u32 s74, s4, s50
	s_addc_u32 s75, s5, s51
	s_add_u32 s52, s74, 0x100
	s_addc_u32 s53, s75, 0
	s_add_u32 s77, s23, s50
	ds_read_b128 v[170:173], v139
	ds_read_b128 v[174:177], v139 offset:1024
	ds_read_b128 v[178:181], v139 offset:2048
	ds_read_b128 v[182:185], v139 offset:3072
	ds_read_b128 v[186:189], v139 offset:4096
	ds_read_b128 v[190:193], v139 offset:5120
	ds_read_b128 v[194:197], v139 offset:6144
	ds_read_b128 v[198:201], v139 offset:7168
	s_addc_u32 s87, s25, s51
	s_add_u32 s80, s77, 0x80
	s_addc_u32 s81, s87, 0
	s_add_u32 s90, s68, s50
	s_addc_u32 s91, s69, s51
	s_add_u32 s88, s90, 0x80
	s_mov_b32 m0, s84
	s_nop 0
	global_load_lds_dwordx4 v128, s[80:81]
	s_addc_u32 s89, s91, 0
	s_mov_b32 m0, s85
	s_nop 0
	global_load_lds_dwordx4 v128, s[88:89]
	s_waitcnt vmcnt(24)
	s_waitcnt lgkmcnt(0)
	s_barrier
	s_waitcnt lgkmcnt(7)
	v_mfma_f32_16x16x32_bf16 v[124:127], v[130:133], v[170:173], 0
	v_mfma_f32_16x16x32_bf16 v[120:123], v[146:149], v[170:173], 0
	s_waitcnt lgkmcnt(5)
	v_mfma_f32_16x16x32_bf16 v[116:119], v[130:133], v[178:181], 0
	v_mfma_f32_16x16x32_bf16 v[112:115], v[146:149], v[178:181], 0
	s_waitcnt lgkmcnt(3)
	v_mfma_f32_16x16x32_bf16 v[108:111], v[130:133], v[186:189], 0
	v_mfma_f32_16x16x32_bf16 v[104:107], v[146:149], v[186:189], 0
	s_waitcnt lgkmcnt(1)
	v_mfma_f32_16x16x32_bf16 v[100:103], v[130:133], v[194:197], 0
	v_mfma_f32_16x16x32_bf16 v[96:99], v[146:149], v[194:197], 0
	v_mfma_f32_16x16x32_bf16 v[124:127], v[142:145], v[174:177], v[124:127]
	v_mfma_f32_16x16x32_bf16 v[120:123], v[150:153], v[174:177], v[120:123]
	v_mfma_f32_16x16x32_bf16 v[116:119], v[142:145], v[182:185], v[116:119]
	v_mfma_f32_16x16x32_bf16 v[112:115], v[150:153], v[182:185], v[112:115]
	v_mfma_f32_16x16x32_bf16 v[108:111], v[142:145], v[190:193], v[108:111]
	v_mfma_f32_16x16x32_bf16 v[104:107], v[150:153], v[190:193], v[104:107]
	s_waitcnt lgkmcnt(0)
	v_mfma_f32_16x16x32_bf16 v[100:103], v[142:145], v[198:201], v[100:103]
	v_mfma_f32_16x16x32_bf16 v[96:99], v[150:153], v[198:201], v[96:99]
	v_mfma_f32_16x16x32_bf16 v[92:95], v[154:157], v[170:173], 0
	v_mfma_f32_16x16x32_bf16 v[88:91], v[162:165], v[170:173], 0
	v_mfma_f32_16x16x32_bf16 v[84:87], v[154:157], v[178:181], 0
	v_mfma_f32_16x16x32_bf16 v[80:83], v[162:165], v[178:181], 0
	v_mfma_f32_16x16x32_bf16 v[76:79], v[154:157], v[186:189], 0
	v_mfma_f32_16x16x32_bf16 v[72:75], v[162:165], v[186:189], 0
	v_mfma_f32_16x16x32_bf16 v[68:71], v[154:157], v[194:197], 0
	v_mfma_f32_16x16x32_bf16 v[64:67], v[162:165], v[194:197], 0
	v_mfma_f32_16x16x32_bf16 v[92:95], v[158:161], v[174:177], v[92:95]
	v_mfma_f32_16x16x32_bf16 v[88:91], v[166:169], v[174:177], v[88:91]
	v_mfma_f32_16x16x32_bf16 v[84:87], v[158:161], v[182:185], v[84:87]
	v_mfma_f32_16x16x32_bf16 v[80:83], v[166:169], v[182:185], v[80:83]
	v_mfma_f32_16x16x32_bf16 v[76:79], v[158:161], v[190:193], v[76:79]
	v_mfma_f32_16x16x32_bf16 v[72:75], v[166:169], v[190:193], v[72:75]
	v_mfma_f32_16x16x32_bf16 v[68:71], v[158:161], v[198:201], v[68:71]
	v_mfma_f32_16x16x32_bf16 v[64:67], v[166:169], v[198:201], v[64:67]
	s_barrier
	s_add_u32 s92, s6, s50
	s_addc_u32 s93, s7, s51
	s_add_u32 s80, s92, 0x100
	s_addc_u32 s81, s93, 0
	s_add_u32 s94, s54, s50
	s_addc_u32 s95, s55, s51
	s_add_u32 s88, s94, 0x100
	ds_read_b128 v[170:173], v139 offset:16384
	ds_read_b128 v[174:177], v139 offset:17408
	ds_read_b128 v[178:181], v139 offset:18432
	ds_read_b128 v[182:185], v139 offset:19456
	ds_read_b128 v[186:189], v139 offset:20480
	ds_read_b128 v[190:193], v139 offset:21504
	ds_read_b128 v[194:197], v139 offset:22528
	ds_read_b128 v[198:201], v139 offset:23552
	s_addc_u32 s89, s95, 0
	s_mov_b32 m0, s58
	s_nop 0
	global_load_lds_dwordx4 v129, s[80:81]
	s_add_u32 s96, s27, s50
	s_mov_b32 m0, s59
	s_nop 0
	global_load_lds_dwordx4 v129, s[88:89]
	s_addc_u32 s97, s33, s51
	s_add_u32 s80, s96, 0x100
	s_addc_u32 s81, s97, 0
	s_add_u32 vcc_lo, s34, s50
	s_addc_u32 vcc_hi, s41, s51
	s_add_u32 s88, vcc_lo, 0x100
	s_mov_b32 m0, s60
	s_nop 0
	global_load_lds_dwordx4 v129, s[80:81]
	s_addc_u32 s89, vcc_hi, 0
	s_mov_b32 m0, s61
	s_nop 0
	global_load_lds_dwordx4 v129, s[88:89]
	s_add_u32 s57, s70, s50
	s_addc_u32 s88, s71, s51
	s_add_u32 s80, s57, 0x100
	s_mov_b32 m0, s3
	s_nop 0
	global_load_lds_dwordx4 v128, s[52:53]
	s_addc_u32 s81, s88, 0
	s_mov_b32 m0, s62
	s_nop 0
	global_load_lds_dwordx4 v128, s[80:81]
	s_waitcnt vmcnt(24)
	s_waitcnt lgkmcnt(0)
	s_barrier
	s_waitcnt lgkmcnt(7)
	v_mfma_f32_16x16x32_bf16 v[60:63], v[130:133], v[170:173], 0
	v_mfma_f32_16x16x32_bf16 v[56:59], v[146:149], v[170:173], 0
	s_waitcnt lgkmcnt(5)
	v_mfma_f32_16x16x32_bf16 v[52:55], v[130:133], v[178:181], 0
	v_mfma_f32_16x16x32_bf16 v[48:51], v[146:149], v[178:181], 0
	s_waitcnt lgkmcnt(3)
	v_mfma_f32_16x16x32_bf16 v[44:47], v[130:133], v[186:189], 0
	v_mfma_f32_16x16x32_bf16 v[40:43], v[146:149], v[186:189], 0
	s_waitcnt lgkmcnt(1)
	v_mfma_f32_16x16x32_bf16 v[36:39], v[130:133], v[194:197], 0
	v_mfma_f32_16x16x32_bf16 v[32:35], v[146:149], v[194:197], 0
	v_mfma_f32_16x16x32_bf16 v[60:63], v[142:145], v[174:177], v[60:63]
	v_mfma_f32_16x16x32_bf16 v[56:59], v[150:153], v[174:177], v[56:59]
	v_mfma_f32_16x16x32_bf16 v[52:55], v[142:145], v[182:185], v[52:55]
	v_mfma_f32_16x16x32_bf16 v[48:51], v[150:153], v[182:185], v[48:51]
	v_mfma_f32_16x16x32_bf16 v[44:47], v[142:145], v[190:193], v[44:47]
	v_mfma_f32_16x16x32_bf16 v[40:43], v[150:153], v[190:193], v[40:43]
	s_waitcnt lgkmcnt(0)
	v_mfma_f32_16x16x32_bf16 v[36:39], v[142:145], v[198:201], v[36:39]
	v_mfma_f32_16x16x32_bf16 v[32:35], v[150:153], v[198:201], v[32:35]
	v_mfma_f32_16x16x32_bf16 v[28:31], v[154:157], v[170:173], 0
	v_mfma_f32_16x16x32_bf16 v[24:27], v[162:165], v[170:173], 0
	v_mfma_f32_16x16x32_bf16 v[20:23], v[154:157], v[178:181], 0
	v_mfma_f32_16x16x32_bf16 v[16:19], v[162:165], v[178:181], 0
	v_mfma_f32_16x16x32_bf16 v[12:15], v[154:157], v[186:189], 0
	v_mfma_f32_16x16x32_bf16 v[8:11], v[162:165], v[186:189], 0
	v_mfma_f32_16x16x32_bf16 v[4:7], v[154:157], v[194:197], 0
	v_mfma_f32_16x16x32_bf16 v[0:3], v[162:165], v[194:197], 0
	v_mfma_f32_16x16x32_bf16 v[28:31], v[158:161], v[174:177], v[28:31]
	v_mfma_f32_16x16x32_bf16 v[24:27], v[166:169], v[174:177], v[24:27]
	v_mfma_f32_16x16x32_bf16 v[20:23], v[158:161], v[182:185], v[20:23]
	v_mfma_f32_16x16x32_bf16 v[16:19], v[166:169], v[182:185], v[16:19]
	v_mfma_f32_16x16x32_bf16 v[12:15], v[158:161], v[190:193], v[12:15]
	v_mfma_f32_16x16x32_bf16 v[8:11], v[166:169], v[190:193], v[8:11]
	v_mfma_f32_16x16x32_bf16 v[4:7], v[158:161], v[198:201], v[4:7]
	v_mfma_f32_16x16x32_bf16 v[0:3], v[166:169], v[198:201], v[0:3]
	s_barrier
	ds_read_b128 v[130:133], v140
	ds_read_b128 v[142:145], v140 offset:1024
	ds_read_b128 v[146:149], v140 offset:2048
	ds_read_b128 v[150:153], v140 offset:3072
	ds_read_b128 v[154:157], v141
	ds_read_b128 v[158:161], v141 offset:1024
	ds_read_b128 v[162:165], v141 offset:2048
	ds_read_b128 v[166:169], v141 offset:3072
	ds_read_b128 v[170:173], v139 offset:32768
	ds_read_b128 v[174:177], v139 offset:33792
	ds_read_b128 v[178:181], v139 offset:34816
	ds_read_b128 v[182:185], v139 offset:35840
	ds_read_b128 v[186:189], v139 offset:36864
	ds_read_b128 v[190:193], v139 offset:37888
	ds_read_b128 v[194:197], v139 offset:38912
	ds_read_b128 v[198:201], v139 offset:39936
	s_add_u32 s52, s77, 0x100
	s_addc_u32 s53, s87, 0
	s_add_u32 s80, s90, 0x100
	s_mov_b32 m0, s63
	s_nop 0
	global_load_lds_dwordx4 v128, s[52:53]
	s_addc_u32 s81, s91, 0
	s_mov_b32 m0, s64
	s_nop 0
	global_load_lds_dwordx4 v128, s[80:81]
	s_waitcnt vmcnt(8)
	s_waitcnt lgkmcnt(0)
	s_barrier
	s_waitcnt lgkmcnt(7)
	v_mfma_f32_16x16x32_bf16 v[124:127], v[130:133], v[170:173], v[124:127]
	v_mfma_f32_16x16x32_bf16 v[120:123], v[146:149], v[170:173], v[120:123]
	s_waitcnt lgkmcnt(5)
	v_mfma_f32_16x16x32_bf16 v[116:119], v[130:133], v[178:181], v[116:119]
	v_mfma_f32_16x16x32_bf16 v[112:115], v[146:149], v[178:181], v[112:115]
	s_waitcnt lgkmcnt(3)
	v_mfma_f32_16x16x32_bf16 v[108:111], v[130:133], v[186:189], v[108:111]
	v_mfma_f32_16x16x32_bf16 v[104:107], v[146:149], v[186:189], v[104:107]
	s_waitcnt lgkmcnt(1)
	v_mfma_f32_16x16x32_bf16 v[100:103], v[130:133], v[194:197], v[100:103]
	v_mfma_f32_16x16x32_bf16 v[96:99], v[146:149], v[194:197], v[96:99]
	v_mfma_f32_16x16x32_bf16 v[124:127], v[142:145], v[174:177], v[124:127]
	v_mfma_f32_16x16x32_bf16 v[120:123], v[150:153], v[174:177], v[120:123]
	v_mfma_f32_16x16x32_bf16 v[116:119], v[142:145], v[182:185], v[116:119]
	v_mfma_f32_16x16x32_bf16 v[112:115], v[150:153], v[182:185], v[112:115]
	v_mfma_f32_16x16x32_bf16 v[108:111], v[142:145], v[190:193], v[108:111]
	v_mfma_f32_16x16x32_bf16 v[104:107], v[150:153], v[190:193], v[104:107]
	s_waitcnt lgkmcnt(0)
	v_mfma_f32_16x16x32_bf16 v[100:103], v[142:145], v[198:201], v[100:103]
	v_mfma_f32_16x16x32_bf16 v[96:99], v[150:153], v[198:201], v[96:99]
	v_mfma_f32_16x16x32_bf16 v[92:95], v[154:157], v[170:173], v[92:95]
	v_mfma_f32_16x16x32_bf16 v[88:91], v[162:165], v[170:173], v[88:91]
	v_mfma_f32_16x16x32_bf16 v[84:87], v[154:157], v[178:181], v[84:87]
	v_mfma_f32_16x16x32_bf16 v[80:83], v[162:165], v[178:181], v[80:83]
	v_mfma_f32_16x16x32_bf16 v[76:79], v[154:157], v[186:189], v[76:79]
	v_mfma_f32_16x16x32_bf16 v[72:75], v[162:165], v[186:189], v[72:75]
	v_mfma_f32_16x16x32_bf16 v[68:71], v[154:157], v[194:197], v[68:71]
	v_mfma_f32_16x16x32_bf16 v[64:67], v[162:165], v[194:197], v[64:67]
	v_mfma_f32_16x16x32_bf16 v[92:95], v[158:161], v[174:177], v[92:95]
	v_mfma_f32_16x16x32_bf16 v[88:91], v[166:169], v[174:177], v[88:91]
	v_mfma_f32_16x16x32_bf16 v[84:87], v[158:161], v[182:185], v[84:87]
	v_mfma_f32_16x16x32_bf16 v[80:83], v[166:169], v[182:185], v[80:83]
	v_mfma_f32_16x16x32_bf16 v[76:79], v[158:161], v[190:193], v[76:79]
	v_mfma_f32_16x16x32_bf16 v[72:75], v[166:169], v[190:193], v[72:75]
	v_mfma_f32_16x16x32_bf16 v[68:71], v[158:161], v[198:201], v[68:71]
	v_mfma_f32_16x16x32_bf16 v[64:67], v[166:169], v[198:201], v[64:67]
	s_barrier
	s_add_u32 s52, s92, 0x180
	s_addc_u32 s53, s93, 0
	ds_read_b128 v[170:173], v139 offset:49152
	ds_read_b128 v[174:177], v139 offset:50176
	ds_read_b128 v[178:181], v139 offset:51200
	ds_read_b128 v[182:185], v139 offset:52224
	ds_read_b128 v[186:189], v139 offset:53248
	ds_read_b128 v[190:193], v139 offset:54272
	ds_read_b128 v[194:197], v139 offset:55296
	ds_read_b128 v[198:201], v139 offset:56320
	s_add_u32 s80, s94, 0x180
	s_mov_b32 m0, s67
	s_nop 0
	global_load_lds_dwordx4 v129, s[52:53]
	s_addc_u32 s81, s95, 0
	s_mov_b32 m0, s73
	s_nop 0
	global_load_lds_dwordx4 v129, s[80:81]
	s_add_u32 s52, s96, 0x180
	s_addc_u32 s53, s97, 0
	s_add_u32 s80, vcc_lo, 0x180
	s_mov_b32 m0, s82
	s_nop 0
	global_load_lds_dwordx4 v129, s[52:53]
	s_addc_u32 s81, vcc_hi, 0
	s_mov_b32 m0, s83
	s_nop 0
	global_load_lds_dwordx4 v129, s[80:81]
	s_add_u32 s52, s74, 0x180
	s_addc_u32 s53, s75, 0
	s_add_u32 s74, s57, 0x180
	s_mov_b32 m0, s78
	s_nop 0
	global_load_lds_dwordx4 v128, s[52:53]
	s_addc_u32 s75, s88, 0
	s_mov_b32 m0, s79
	s_nop 0
	global_load_lds_dwordx4 v128, s[74:75]
	s_waitcnt vmcnt(8)
	s_waitcnt lgkmcnt(0)
	s_barrier
	s_waitcnt lgkmcnt(7)
	v_mfma_f32_16x16x32_bf16 v[60:63], v[130:133], v[170:173], v[60:63]
	v_mfma_f32_16x16x32_bf16 v[56:59], v[146:149], v[170:173], v[56:59]
	s_waitcnt lgkmcnt(5)
	v_mfma_f32_16x16x32_bf16 v[52:55], v[130:133], v[178:181], v[52:55]
	v_mfma_f32_16x16x32_bf16 v[48:51], v[146:149], v[178:181], v[48:51]
	s_waitcnt lgkmcnt(3)
	v_mfma_f32_16x16x32_bf16 v[44:47], v[130:133], v[186:189], v[44:47]
	v_mfma_f32_16x16x32_bf16 v[40:43], v[146:149], v[186:189], v[40:43]
	s_waitcnt lgkmcnt(1)
	v_mfma_f32_16x16x32_bf16 v[36:39], v[130:133], v[194:197], v[36:39]
	v_mfma_f32_16x16x32_bf16 v[32:35], v[146:149], v[194:197], v[32:35]
	v_mfma_f32_16x16x32_bf16 v[60:63], v[142:145], v[174:177], v[60:63]
	v_mfma_f32_16x16x32_bf16 v[56:59], v[150:153], v[174:177], v[56:59]
	v_mfma_f32_16x16x32_bf16 v[52:55], v[142:145], v[182:185], v[52:55]
	v_mfma_f32_16x16x32_bf16 v[48:51], v[150:153], v[182:185], v[48:51]
	v_mfma_f32_16x16x32_bf16 v[44:47], v[142:145], v[190:193], v[44:47]
	v_mfma_f32_16x16x32_bf16 v[40:43], v[150:153], v[190:193], v[40:43]
	s_waitcnt lgkmcnt(0)
	v_mfma_f32_16x16x32_bf16 v[36:39], v[142:145], v[198:201], v[36:39]
	v_mfma_f32_16x16x32_bf16 v[32:35], v[150:153], v[198:201], v[32:35]
	v_mfma_f32_16x16x32_bf16 v[28:31], v[154:157], v[170:173], v[28:31]
	v_mfma_f32_16x16x32_bf16 v[24:27], v[162:165], v[170:173], v[24:27]
	v_mfma_f32_16x16x32_bf16 v[20:23], v[154:157], v[178:181], v[20:23]
	v_mfma_f32_16x16x32_bf16 v[16:19], v[162:165], v[178:181], v[16:19]
	v_mfma_f32_16x16x32_bf16 v[12:15], v[154:157], v[186:189], v[12:15]
	v_mfma_f32_16x16x32_bf16 v[8:11], v[162:165], v[186:189], v[8:11]
	v_mfma_f32_16x16x32_bf16 v[4:7], v[154:157], v[194:197], v[4:7]
	v_mfma_f32_16x16x32_bf16 v[0:3], v[162:165], v[194:197], v[0:3]
	v_mfma_f32_16x16x32_bf16 v[28:31], v[158:161], v[174:177], v[28:31]
	v_mfma_f32_16x16x32_bf16 v[24:27], v[166:169], v[174:177], v[24:27]
	v_mfma_f32_16x16x32_bf16 v[20:23], v[158:161], v[182:185], v[20:23]
	v_mfma_f32_16x16x32_bf16 v[16:19], v[166:169], v[182:185], v[16:19]
	v_mfma_f32_16x16x32_bf16 v[12:15], v[158:161], v[190:193], v[12:15]
	v_mfma_f32_16x16x32_bf16 v[8:11], v[166:169], v[190:193], v[8:11]
	v_mfma_f32_16x16x32_bf16 v[4:7], v[158:161], v[198:201], v[4:7]
	v_mfma_f32_16x16x32_bf16 v[0:3], v[166:169], v[198:201], v[0:3]
	s_barrier
	s_add_u32 s50, s50, 0x100
	s_addc_u32 s51, s51, 0
	s_cmp_ge_i32 s72, s2
	s_cbranch_scc0 .LBB0_783
	s_branch .LBB0_784
.Lhf_783:
	ds_read_b128 v[130:133], v137
	ds_read_b128 v[142:145], v137 offset:1024
	ds_read_b128 v[146:149], v137 offset:2048
	ds_read_b128 v[150:153], v137 offset:3072
	ds_read_b128 v[154:157], v138
	ds_read_b128 v[158:161], v138 offset:1024
	ds_read_b128 v[162:165], v138 offset:2048
	ds_read_b128 v[166:169], v138 offset:3072
	s_add_i32 s72, s72, 2
	s_add_u32 s74, s4, s50
	s_addc_u32 s75, s5, s51
	s_add_u32 s52, s74, 0x100
	s_addc_u32 s53, s75, 0
	s_add_u32 s77, s23, s50
	ds_read_b128 v[170:173], v139
	ds_read_b128 v[174:177], v139 offset:1024
	ds_read_b128 v[178:181], v139 offset:2048
	ds_read_b128 v[182:185], v139 offset:3072
	ds_read_b128 v[186:189], v139 offset:4096
	ds_read_b128 v[190:193], v139 offset:5120
	ds_read_b128 v[194:197], v139 offset:6144
	ds_read_b128 v[198:201], v139 offset:7168
	s_addc_u32 s87, s25, s51
	s_add_u32 s80, s77, 0x80
	s_addc_u32 s81, s87, 0
	s_add_u32 s90, s68, s50
	s_addc_u32 s91, s69, s51
	s_add_u32 s88, s90, 0x80
	s_mov_b32 m0, s84
	s_nop 0
	global_load_lds_dwordx4 v128, s[80:81]
	s_addc_u32 s89, s91, 0
	s_mov_b32 m0, s85
	s_nop 0
	global_load_lds_dwordx4 v128, s[88:89]
	s_waitcnt vmcnt(8)
	s_waitcnt lgkmcnt(0)
	s_barrier
	s_waitcnt lgkmcnt(7)
	v_mfma_f32_16x16x32_bf16 v[124:127], v[130:133], v[170:173], 0
	v_mfma_f32_16x16x32_bf16 v[120:123], v[146:149], v[170:173], 0
	s_waitcnt lgkmcnt(5)
	v_mfma_f32_16x16x32_bf16 v[116:119], v[130:133], v[178:181], 0
	v_mfma_f32_16x16x32_bf16 v[112:115], v[146:149], v[178:181], 0
	s_waitcnt lgkmcnt(3)
	v_mfma_f32_16x16x32_bf16 v[108:111], v[130:133], v[186:189], 0
	v_mfma_f32_16x16x32_bf16 v[104:107], v[146:149], v[186:189], 0
	s_waitcnt lgkmcnt(1)
	v_mfma_f32_16x16x32_bf16 v[100:103], v[130:133], v[194:197], 0
	v_mfma_f32_16x16x32_bf16 v[96:99], v[146:149], v[194:197], 0
	v_mfma_f32_16x16x32_bf16 v[124:127], v[142:145], v[174:177], v[124:127]
	v_mfma_f32_16x16x32_bf16 v[120:123], v[150:153], v[174:177], v[120:123]
	v_mfma_f32_16x16x32_bf16 v[116:119], v[142:145], v[182:185], v[116:119]
	v_mfma_f32_16x16x32_bf16 v[112:115], v[150:153], v[182:185], v[112:115]
	v_mfma_f32_16x16x32_bf16 v[108:111], v[142:145], v[190:193], v[108:111]
	v_mfma_f32_16x16x32_bf16 v[104:107], v[150:153], v[190:193], v[104:107]
	s_waitcnt lgkmcnt(0)
	v_mfma_f32_16x16x32_bf16 v[100:103], v[142:145], v[198:201], v[100:103]
	v_mfma_f32_16x16x32_bf16 v[96:99], v[150:153], v[198:201], v[96:99]
	v_mfma_f32_16x16x32_bf16 v[92:95], v[154:157], v[170:173], 0
	v_mfma_f32_16x16x32_bf16 v[88:91], v[162:165], v[170:173], 0
	v_mfma_f32_16x16x32_bf16 v[84:87], v[154:157], v[178:181], 0
	v_mfma_f32_16x16x32_bf16 v[80:83], v[162:165], v[178:181], 0
	v_mfma_f32_16x16x32_bf16 v[76:79], v[154:157], v[186:189], 0
	v_mfma_f32_16x16x32_bf16 v[72:75], v[162:165], v[186:189], 0
	v_mfma_f32_16x16x32_bf16 v[68:71], v[154:157], v[194:197], 0
	v_mfma_f32_16x16x32_bf16 v[64:67], v[162:165], v[194:197], 0
	v_mfma_f32_16x16x32_bf16 v[92:95], v[158:161], v[174:177], v[92:95]
	v_mfma_f32_16x16x32_bf16 v[88:91], v[166:169], v[174:177], v[88:91]
	v_mfma_f32_16x16x32_bf16 v[84:87], v[158:161], v[182:185], v[84:87]
	v_mfma_f32_16x16x32_bf16 v[80:83], v[166:169], v[182:185], v[80:83]
	v_mfma_f32_16x16x32_bf16 v[76:79], v[158:161], v[190:193], v[76:79]
	v_mfma_f32_16x16x32_bf16 v[72:75], v[166:169], v[190:193], v[72:75]
	v_mfma_f32_16x16x32_bf16 v[68:71], v[158:161], v[198:201], v[68:71]
	v_mfma_f32_16x16x32_bf16 v[64:67], v[166:169], v[198:201], v[64:67]
	s_barrier
	s_add_u32 s92, s6, s50
	s_addc_u32 s93, s7, s51
	s_add_u32 s80, s92, 0x100
	s_addc_u32 s81, s93, 0
	s_add_u32 s94, s54, s50
	s_addc_u32 s95, s55, s51
	s_add_u32 s88, s94, 0x100
	ds_read_b128 v[170:173], v139 offset:16384
	ds_read_b128 v[174:177], v139 offset:17408
	ds_read_b128 v[178:181], v139 offset:18432
	ds_read_b128 v[182:185], v139 offset:19456
	ds_read_b128 v[186:189], v139 offset:20480
	ds_read_b128 v[190:193], v139 offset:21504
	ds_read_b128 v[194:197], v139 offset:22528
	ds_read_b128 v[198:201], v139 offset:23552
	s_addc_u32 s89, s95, 0
	s_mov_b32 m0, s58
	s_nop 0
	global_load_lds_dwordx4 v129, s[80:81]
	s_add_u32 s96, s27, s50
	s_mov_b32 m0, s59
	s_nop 0
	global_load_lds_dwordx4 v129, s[88:89]
	s_addc_u32 s97, s33, s51
	s_add_u32 s80, s96, 0x100
	s_addc_u32 s81, s97, 0
	s_add_u32 vcc_lo, s34, s50
	s_addc_u32 vcc_hi, s41, s51
	s_add_u32 s88, vcc_lo, 0x100
	s_mov_b32 m0, s60
	s_nop 0
	global_load_lds_dwordx4 v129, s[80:81]
	s_addc_u32 s89, vcc_hi, 0
	s_mov_b32 m0, s61
	s_nop 0
	global_load_lds_dwordx4 v129, s[88:89]
	s_add_u32 s57, s70, s50
	s_addc_u32 s88, s71, s51
	s_add_u32 s80, s57, 0x100
	s_mov_b32 m0, s3
	s_nop 0
	global_load_lds_dwordx4 v128, s[52:53]
	s_addc_u32 s81, s88, 0
	s_mov_b32 m0, s62
	s_nop 0
	global_load_lds_dwordx4 v128, s[80:81]
	s_waitcnt vmcnt(8)
	s_waitcnt lgkmcnt(0)
	s_barrier
	s_waitcnt lgkmcnt(7)
	v_mfma_f32_16x16x32_bf16 v[60:63], v[130:133], v[170:173], 0
	v_mfma_f32_16x16x32_bf16 v[56:59], v[146:149], v[170:173], 0
	s_waitcnt lgkmcnt(5)
	v_mfma_f32_16x16x32_bf16 v[52:55], v[130:133], v[178:181], 0
	v_mfma_f32_16x16x32_bf16 v[48:51], v[146:149], v[178:181], 0
	s_waitcnt lgkmcnt(3)
	v_mfma_f32_16x16x32_bf16 v[44:47], v[130:133], v[186:189], 0
	v_mfma_f32_16x16x32_bf16 v[40:43], v[146:149], v[186:189], 0
	s_waitcnt lgkmcnt(1)
	v_mfma_f32_16x16x32_bf16 v[36:39], v[130:133], v[194:197], 0
	v_mfma_f32_16x16x32_bf16 v[32:35], v[146:149], v[194:197], 0
	v_mfma_f32_16x16x32_bf16 v[60:63], v[142:145], v[174:177], v[60:63]
	v_mfma_f32_16x16x32_bf16 v[56:59], v[150:153], v[174:177], v[56:59]
	v_mfma_f32_16x16x32_bf16 v[52:55], v[142:145], v[182:185], v[52:55]
	v_mfma_f32_16x16x32_bf16 v[48:51], v[150:153], v[182:185], v[48:51]
	v_mfma_f32_16x16x32_bf16 v[44:47], v[142:145], v[190:193], v[44:47]
	v_mfma_f32_16x16x32_bf16 v[40:43], v[150:153], v[190:193], v[40:43]
	s_waitcnt lgkmcnt(0)
	v_mfma_f32_16x16x32_bf16 v[36:39], v[142:145], v[198:201], v[36:39]
	v_mfma_f32_16x16x32_bf16 v[32:35], v[150:153], v[198:201], v[32:35]
	v_mfma_f32_16x16x32_bf16 v[28:31], v[154:157], v[170:173], 0
	v_mfma_f32_16x16x32_bf16 v[24:27], v[162:165], v[170:173], 0
	v_mfma_f32_16x16x32_bf16 v[20:23], v[154:157], v[178:181], 0
	v_mfma_f32_16x16x32_bf16 v[16:19], v[162:165], v[178:181], 0
	v_mfma_f32_16x16x32_bf16 v[12:15], v[154:157], v[186:189], 0
	v_mfma_f32_16x16x32_bf16 v[8:11], v[162:165], v[186:189], 0
	v_mfma_f32_16x16x32_bf16 v[4:7], v[154:157], v[194:197], 0
	v_mfma_f32_16x16x32_bf16 v[0:3], v[162:165], v[194:197], 0
	v_mfma_f32_16x16x32_bf16 v[28:31], v[158:161], v[174:177], v[28:31]
	v_mfma_f32_16x16x32_bf16 v[24:27], v[166:169], v[174:177], v[24:27]
	v_mfma_f32_16x16x32_bf16 v[20:23], v[158:161], v[182:185], v[20:23]
	v_mfma_f32_16x16x32_bf16 v[16:19], v[166:169], v[182:185], v[16:19]
	v_mfma_f32_16x16x32_bf16 v[12:15], v[158:161], v[190:193], v[12:15]
	v_mfma_f32_16x16x32_bf16 v[8:11], v[166:169], v[190:193], v[8:11]
	v_mfma_f32_16x16x32_bf16 v[4:7], v[158:161], v[198:201], v[4:7]
	v_mfma_f32_16x16x32_bf16 v[0:3], v[166:169], v[198:201], v[0:3]
	s_barrier
	ds_read_b128 v[130:133], v140
	ds_read_b128 v[142:145], v140 offset:1024
	ds_read_b128 v[146:149], v140 offset:2048
	ds_read_b128 v[150:153], v140 offset:3072
	ds_read_b128 v[154:157], v141
	ds_read_b128 v[158:161], v141 offset:1024
	ds_read_b128 v[162:165], v141 offset:2048
	ds_read_b128 v[166:169], v141 offset:3072
	ds_read_b128 v[170:173], v139 offset:32768
	ds_read_b128 v[174:177], v139 offset:33792
	ds_read_b128 v[178:181], v139 offset:34816
	ds_read_b128 v[182:185], v139 offset:35840
	ds_read_b128 v[186:189], v139 offset:36864
	ds_read_b128 v[190:193], v139 offset:37888
	ds_read_b128 v[194:197], v139 offset:38912
	ds_read_b128 v[198:201], v139 offset:39936
	s_add_u32 s52, s77, 0x100
	s_addc_u32 s53, s87, 0
	s_add_u32 s80, s90, 0x100
	s_mov_b32 m0, s63
	s_nop 0
	global_load_lds_dwordx4 v128, s[52:53]
	s_addc_u32 s81, s91, 0
	s_mov_b32 m0, s64
	s_nop 0
	global_load_lds_dwordx4 v128, s[80:81]
	s_waitcnt vmcnt(8)
	s_waitcnt lgkmcnt(0)
	s_barrier
	s_waitcnt lgkmcnt(7)
	v_mfma_f32_16x16x32_bf16 v[124:127], v[130:133], v[170:173], v[124:127]
	v_mfma_f32_16x16x32_bf16 v[120:123], v[146:149], v[170:173], v[120:123]
	s_waitcnt lgkmcnt(5)
	v_mfma_f32_16x16x32_bf16 v[116:119], v[130:133], v[178:181], v[116:119]
	v_mfma_f32_16x16x32_bf16 v[112:115], v[146:149], v[178:181], v[112:115]
	s_waitcnt lgkmcnt(3)
	v_mfma_f32_16x16x32_bf16 v[108:111], v[130:133], v[186:189], v[108:111]
	v_mfma_f32_16x16x32_bf16 v[104:107], v[146:149], v[186:189], v[104:107]
	s_waitcnt lgkmcnt(1)
	v_mfma_f32_16x16x32_bf16 v[100:103], v[130:133], v[194:197], v[100:103]
	v_mfma_f32_16x16x32_bf16 v[96:99], v[146:149], v[194:197], v[96:99]
	v_mfma_f32_16x16x32_bf16 v[124:127], v[142:145], v[174:177], v[124:127]
	v_mfma_f32_16x16x32_bf16 v[120:123], v[150:153], v[174:177], v[120:123]
	v_mfma_f32_16x16x32_bf16 v[116:119], v[142:145], v[182:185], v[116:119]
	v_mfma_f32_16x16x32_bf16 v[112:115], v[150:153], v[182:185], v[112:115]
	v_mfma_f32_16x16x32_bf16 v[108:111], v[142:145], v[190:193], v[108:111]
	v_mfma_f32_16x16x32_bf16 v[104:107], v[150:153], v[190:193], v[104:107]
	s_waitcnt lgkmcnt(0)
	v_mfma_f32_16x16x32_bf16 v[100:103], v[142:145], v[198:201], v[100:103]
	v_mfma_f32_16x16x32_bf16 v[96:99], v[150:153], v[198:201], v[96:99]
	v_mfma_f32_16x16x32_bf16 v[92:95], v[154:157], v[170:173], v[92:95]
	v_mfma_f32_16x16x32_bf16 v[88:91], v[162:165], v[170:173], v[88:91]
	v_mfma_f32_16x16x32_bf16 v[84:87], v[154:157], v[178:181], v[84:87]
	v_mfma_f32_16x16x32_bf16 v[80:83], v[162:165], v[178:181], v[80:83]
	v_mfma_f32_16x16x32_bf16 v[76:79], v[154:157], v[186:189], v[76:79]
	v_mfma_f32_16x16x32_bf16 v[72:75], v[162:165], v[186:189], v[72:75]
	v_mfma_f32_16x16x32_bf16 v[68:71], v[154:157], v[194:197], v[68:71]
	v_mfma_f32_16x16x32_bf16 v[64:67], v[162:165], v[194:197], v[64:67]
	v_mfma_f32_16x16x32_bf16 v[92:95], v[158:161], v[174:177], v[92:95]
	v_mfma_f32_16x16x32_bf16 v[88:91], v[166:169], v[174:177], v[88:91]
	v_mfma_f32_16x16x32_bf16 v[84:87], v[158:161], v[182:185], v[84:87]
	v_mfma_f32_16x16x32_bf16 v[80:83], v[166:169], v[182:185], v[80:83]
	v_mfma_f32_16x16x32_bf16 v[76:79], v[158:161], v[190:193], v[76:79]
	v_mfma_f32_16x16x32_bf16 v[72:75], v[166:169], v[190:193], v[72:75]
	v_mfma_f32_16x16x32_bf16 v[68:71], v[158:161], v[198:201], v[68:71]
	v_mfma_f32_16x16x32_bf16 v[64:67], v[166:169], v[198:201], v[64:67]
	s_barrier
	s_add_u32 s52, s92, 0x180
	s_addc_u32 s53, s93, 0
	ds_read_b128 v[170:173], v139 offset:49152
	ds_read_b128 v[174:177], v139 offset:50176
	ds_read_b128 v[178:181], v139 offset:51200
	ds_read_b128 v[182:185], v139 offset:52224
	ds_read_b128 v[186:189], v139 offset:53248
	ds_read_b128 v[190:193], v139 offset:54272
	ds_read_b128 v[194:197], v139 offset:55296
	ds_read_b128 v[198:201], v139 offset:56320
	s_add_u32 s80, s94, 0x180
	s_mov_b32 m0, s67
	s_nop 0
	global_load_lds_dwordx4 v129, s[52:53]
	s_addc_u32 s81, s95, 0
	s_mov_b32 m0, s73
	s_nop 0
	global_load_lds_dwordx4 v129, s[80:81]
	s_add_u32 s52, s96, 0x180
	s_addc_u32 s53, s97, 0
	s_add_u32 s80, vcc_lo, 0x180
	s_mov_b32 m0, s82
	s_nop 0
	global_load_lds_dwordx4 v129, s[52:53]
	s_addc_u32 s81, vcc_hi, 0
	s_mov_b32 m0, s83
	s_nop 0
	global_load_lds_dwordx4 v129, s[80:81]
	s_add_u32 s52, s74, 0x180
	s_addc_u32 s53, s75, 0
	s_add_u32 s74, s57, 0x180
	s_mov_b32 m0, s78
	s_nop 0
	global_load_lds_dwordx4 v128, s[52:53]
	s_addc_u32 s75, s88, 0
	s_mov_b32 m0, s79
	s_nop 0
	global_load_lds_dwordx4 v128, s[74:75]
	s_waitcnt vmcnt(8)
	s_waitcnt lgkmcnt(0)
	s_barrier
	s_waitcnt lgkmcnt(7)
	v_mfma_f32_16x16x32_bf16 v[60:63], v[130:133], v[170:173], v[60:63]
	v_mfma_f32_16x16x32_bf16 v[56:59], v[146:149], v[170:173], v[56:59]
	s_waitcnt lgkmcnt(5)
	v_mfma_f32_16x16x32_bf16 v[52:55], v[130:133], v[178:181], v[52:55]
	v_mfma_f32_16x16x32_bf16 v[48:51], v[146:149], v[178:181], v[48:51]
	s_waitcnt lgkmcnt(3)
	v_mfma_f32_16x16x32_bf16 v[44:47], v[130:133], v[186:189], v[44:47]
	v_mfma_f32_16x16x32_bf16 v[40:43], v[146:149], v[186:189], v[40:43]
	s_waitcnt lgkmcnt(1)
	v_mfma_f32_16x16x32_bf16 v[36:39], v[130:133], v[194:197], v[36:39]
	v_mfma_f32_16x16x32_bf16 v[32:35], v[146:149], v[194:197], v[32:35]
	v_mfma_f32_16x16x32_bf16 v[60:63], v[142:145], v[174:177], v[60:63]
	v_mfma_f32_16x16x32_bf16 v[56:59], v[150:153], v[174:177], v[56:59]
	v_mfma_f32_16x16x32_bf16 v[52:55], v[142:145], v[182:185], v[52:55]
	v_mfma_f32_16x16x32_bf16 v[48:51], v[150:153], v[182:185], v[48:51]
	v_mfma_f32_16x16x32_bf16 v[44:47], v[142:145], v[190:193], v[44:47]
	v_mfma_f32_16x16x32_bf16 v[40:43], v[150:153], v[190:193], v[40:43]
	s_waitcnt lgkmcnt(0)
	v_mfma_f32_16x16x32_bf16 v[36:39], v[142:145], v[198:201], v[36:39]
	v_mfma_f32_16x16x32_bf16 v[32:35], v[150:153], v[198:201], v[32:35]
	v_mfma_f32_16x16x32_bf16 v[28:31], v[154:157], v[170:173], v[28:31]
	v_mfma_f32_16x16x32_bf16 v[24:27], v[162:165], v[170:173], v[24:27]
	v_mfma_f32_16x16x32_bf16 v[20:23], v[154:157], v[178:181], v[20:23]
	v_mfma_f32_16x16x32_bf16 v[16:19], v[162:165], v[178:181], v[16:19]
	v_mfma_f32_16x16x32_bf16 v[12:15], v[154:157], v[186:189], v[12:15]
	v_mfma_f32_16x16x32_bf16 v[8:11], v[162:165], v[186:189], v[8:11]
	v_mfma_f32_16x16x32_bf16 v[4:7], v[154:157], v[194:197], v[4:7]
	v_mfma_f32_16x16x32_bf16 v[0:3], v[162:165], v[194:197], v[0:3]
	v_mfma_f32_16x16x32_bf16 v[28:31], v[158:161], v[174:177], v[28:31]
	v_mfma_f32_16x16x32_bf16 v[24:27], v[166:169], v[174:177], v[24:27]
	v_mfma_f32_16x16x32_bf16 v[20:23], v[158:161], v[182:185], v[20:23]
	v_mfma_f32_16x16x32_bf16 v[16:19], v[166:169], v[182:185], v[16:19]
	v_mfma_f32_16x16x32_bf16 v[12:15], v[158:161], v[190:193], v[12:15]
	v_mfma_f32_16x16x32_bf16 v[8:11], v[166:169], v[190:193], v[8:11]
	v_mfma_f32_16x16x32_bf16 v[4:7], v[158:161], v[198:201], v[4:7]
	v_mfma_f32_16x16x32_bf16 v[0:3], v[166:169], v[198:201], v[0:3]
	s_barrier
	s_add_u32 s50, s50, 0x100
	s_addc_u32 s51, s51, 0
	s_cmp_ge_i32 s72, s2
	s_cbranch_scc0 .LBB0_783
	s_branch .LBB0_784

.LBB0_783:
	ds_read_b128 v[130:133], v137
	ds_read_b128 v[142:145], v137 offset:1024
	ds_read_b128 v[146:149], v137 offset:2048
	ds_read_b128 v[150:153], v137 offset:3072
	ds_read_b128 v[154:157], v138
	ds_read_b128 v[158:161], v138 offset:1024
	ds_read_b128 v[162:165], v138 offset:2048
	ds_read_b128 v[166:169], v138 offset:3072
	s_add_i32 s72, s72, 2
	s_add_u32 s74, s4, s50
	s_addc_u32 s75, s5, s51
	s_add_u32 s52, s74, 0x100
	s_addc_u32 s53, s75, 0
	s_add_u32 s77, s23, s50
	ds_read_b128 v[170:173], v139
	ds_read_b128 v[174:177], v139 offset:1024
	ds_read_b128 v[178:181], v139 offset:2048
	ds_read_b128 v[182:185], v139 offset:3072
	ds_read_b128 v[186:189], v139 offset:4096
	ds_read_b128 v[190:193], v139 offset:5120
	ds_read_b128 v[194:197], v139 offset:6144
	ds_read_b128 v[198:201], v139 offset:7168
	s_addc_u32 s87, s25, s51
	s_add_u32 s80, s77, 0x80
	s_addc_u32 s81, s87, 0
	s_add_u32 s90, s68, s50
	s_addc_u32 s91, s69, s51
	s_add_u32 s88, s90, 0x80
	s_mov_b32 m0, s84
	s_nop 0
	global_load_lds_dwordx4 v128, s[80:81]
	s_addc_u32 s89, s91, 0
	s_mov_b32 m0, s85
	s_nop 0
	global_load_lds_dwordx4 v128, s[88:89]
	s_waitcnt vmcnt(8)
	s_waitcnt lgkmcnt(0)
	s_barrier
	s_waitcnt lgkmcnt(7)
	v_mfma_f32_16x16x32_bf16 v[124:127], v[130:133], v[170:173], v[124:127]
	v_mfma_f32_16x16x32_bf16 v[120:123], v[146:149], v[170:173], v[120:123]
	s_waitcnt lgkmcnt(5)
	v_mfma_f32_16x16x32_bf16 v[116:119], v[130:133], v[178:181], v[116:119]
	v_mfma_f32_16x16x32_bf16 v[112:115], v[146:149], v[178:181], v[112:115]
	s_waitcnt lgkmcnt(3)
	v_mfma_f32_16x16x32_bf16 v[108:111], v[130:133], v[186:189], v[108:111]
	v_mfma_f32_16x16x32_bf16 v[104:107], v[146:149], v[186:189], v[104:107]
	s_waitcnt lgkmcnt(1)
	v_mfma_f32_16x16x32_bf16 v[100:103], v[130:133], v[194:197], v[100:103]
	v_mfma_f32_16x16x32_bf16 v[96:99], v[146:149], v[194:197], v[96:99]
	v_mfma_f32_16x16x32_bf16 v[124:127], v[142:145], v[174:177], v[124:127]
	v_mfma_f32_16x16x32_bf16 v[120:123], v[150:153], v[174:177], v[120:123]
	v_mfma_f32_16x16x32_bf16 v[116:119], v[142:145], v[182:185], v[116:119]
	v_mfma_f32_16x16x32_bf16 v[112:115], v[150:153], v[182:185], v[112:115]
	v_mfma_f32_16x16x32_bf16 v[108:111], v[142:145], v[190:193], v[108:111]
	v_mfma_f32_16x16x32_bf16 v[104:107], v[150:153], v[190:193], v[104:107]
	s_waitcnt lgkmcnt(0)
	v_mfma_f32_16x16x32_bf16 v[100:103], v[142:145], v[198:201], v[100:103]
	v_mfma_f32_16x16x32_bf16 v[96:99], v[150:153], v[198:201], v[96:99]
	v_mfma_f32_16x16x32_bf16 v[92:95], v[154:157], v[170:173], v[92:95]
	v_mfma_f32_16x16x32_bf16 v[88:91], v[162:165], v[170:173], v[88:91]
	v_mfma_f32_16x16x32_bf16 v[84:87], v[154:157], v[178:181], v[84:87]
	v_mfma_f32_16x16x32_bf16 v[80:83], v[162:165], v[178:181], v[80:83]
	v_mfma_f32_16x16x32_bf16 v[76:79], v[154:157], v[186:189], v[76:79]
	v_mfma_f32_16x16x32_bf16 v[72:75], v[162:165], v[186:189], v[72:75]
	v_mfma_f32_16x16x32_bf16 v[68:71], v[154:157], v[194:197], v[68:71]
	v_mfma_f32_16x16x32_bf16 v[64:67], v[162:165], v[194:197], v[64:67]
	v_mfma_f32_16x16x32_bf16 v[92:95], v[158:161], v[174:177], v[92:95]
	v_mfma_f32_16x16x32_bf16 v[88:91], v[166:169], v[174:177], v[88:91]
	v_mfma_f32_16x16x32_bf16 v[84:87], v[158:161], v[182:185], v[84:87]
	v_mfma_f32_16x16x32_bf16 v[80:83], v[166:169], v[182:185], v[80:83]
	v_mfma_f32_16x16x32_bf16 v[76:79], v[158:161], v[190:193], v[76:79]
	v_mfma_f32_16x16x32_bf16 v[72:75], v[166:169], v[190:193], v[72:75]
	v_mfma_f32_16x16x32_bf16 v[68:71], v[158:161], v[198:201], v[68:71]
	v_mfma_f32_16x16x32_bf16 v[64:67], v[166:169], v[198:201], v[64:67]
	s_barrier
	s_add_u32 s92, s6, s50
	s_addc_u32 s93, s7, s51
	s_add_u32 s80, s92, 0x100
	s_addc_u32 s81, s93, 0
	s_add_u32 s94, s54, s50
	s_addc_u32 s95, s55, s51
	s_add_u32 s88, s94, 0x100
	ds_read_b128 v[170:173], v139 offset:16384
	ds_read_b128 v[174:177], v139 offset:17408
	ds_read_b128 v[178:181], v139 offset:18432
	ds_read_b128 v[182:185], v139 offset:19456
	ds_read_b128 v[186:189], v139 offset:20480
	ds_read_b128 v[190:193], v139 offset:21504
	ds_read_b128 v[194:197], v139 offset:22528
	ds_read_b128 v[198:201], v139 offset:23552
	s_addc_u32 s89, s95, 0
	s_mov_b32 m0, s58
	s_nop 0
	global_load_lds_dwordx4 v129, s[80:81]
	s_add_u32 s96, s27, s50
	s_mov_b32 m0, s59
	s_nop 0
	global_load_lds_dwordx4 v129, s[88:89]
	s_addc_u32 s97, s33, s51
	s_add_u32 s80, s96, 0x100
	s_addc_u32 s81, s97, 0
	s_add_u32 vcc_lo, s34, s50
	s_addc_u32 vcc_hi, s41, s51
	s_add_u32 s88, vcc_lo, 0x100
	s_mov_b32 m0, s60
	s_nop 0
	global_load_lds_dwordx4 v129, s[80:81]
	s_addc_u32 s89, vcc_hi, 0
	s_mov_b32 m0, s61
	s_nop 0
	global_load_lds_dwordx4 v129, s[88:89]
	s_add_u32 s57, s70, s50
	s_addc_u32 s88, s71, s51
	s_add_u32 s80, s57, 0x100
	s_mov_b32 m0, s3
	s_nop 0
	global_load_lds_dwordx4 v128, s[52:53]
	s_addc_u32 s81, s88, 0
	s_mov_b32 m0, s62
	s_nop 0
	global_load_lds_dwordx4 v128, s[80:81]
	s_waitcnt vmcnt(8)
	s_waitcnt lgkmcnt(0)
	s_barrier
	s_waitcnt lgkmcnt(7)
	v_mfma_f32_16x16x32_bf16 v[60:63], v[130:133], v[170:173], v[60:63]
	v_mfma_f32_16x16x32_bf16 v[56:59], v[146:149], v[170:173], v[56:59]
	s_waitcnt lgkmcnt(5)
	v_mfma_f32_16x16x32_bf16 v[52:55], v[130:133], v[178:181], v[52:55]
	v_mfma_f32_16x16x32_bf16 v[48:51], v[146:149], v[178:181], v[48:51]
	s_waitcnt lgkmcnt(3)
	v_mfma_f32_16x16x32_bf16 v[44:47], v[130:133], v[186:189], v[44:47]
	v_mfma_f32_16x16x32_bf16 v[40:43], v[146:149], v[186:189], v[40:43]
	s_waitcnt lgkmcnt(1)
	v_mfma_f32_16x16x32_bf16 v[36:39], v[130:133], v[194:197], v[36:39]
	v_mfma_f32_16x16x32_bf16 v[32:35], v[146:149], v[194:197], v[32:35]
	v_mfma_f32_16x16x32_bf16 v[60:63], v[142:145], v[174:177], v[60:63]
	v_mfma_f32_16x16x32_bf16 v[56:59], v[150:153], v[174:177], v[56:59]
	v_mfma_f32_16x16x32_bf16 v[52:55], v[142:145], v[182:185], v[52:55]
	v_mfma_f32_16x16x32_bf16 v[48:51], v[150:153], v[182:185], v[48:51]
	v_mfma_f32_16x16x32_bf16 v[44:47], v[142:145], v[190:193], v[44:47]
	v_mfma_f32_16x16x32_bf16 v[40:43], v[150:153], v[190:193], v[40:43]
	s_waitcnt lgkmcnt(0)
	v_mfma_f32_16x16x32_bf16 v[36:39], v[142:145], v[198:201], v[36:39]
	v_mfma_f32_16x16x32_bf16 v[32:35], v[150:153], v[198:201], v[32:35]
	v_mfma_f32_16x16x32_bf16 v[28:31], v[154:157], v[170:173], v[28:31]
	v_mfma_f32_16x16x32_bf16 v[24:27], v[162:165], v[170:173], v[24:27]
	v_mfma_f32_16x16x32_bf16 v[20:23], v[154:157], v[178:181], v[20:23]
	v_mfma_f32_16x16x32_bf16 v[16:19], v[162:165], v[178:181], v[16:19]
	v_mfma_f32_16x16x32_bf16 v[12:15], v[154:157], v[186:189], v[12:15]
	v_mfma_f32_16x16x32_bf16 v[8:11], v[162:165], v[186:189], v[8:11]
	v_mfma_f32_16x16x32_bf16 v[4:7], v[154:157], v[194:197], v[4:7]
	v_mfma_f32_16x16x32_bf16 v[0:3], v[162:165], v[194:197], v[0:3]
	v_mfma_f32_16x16x32_bf16 v[28:31], v[158:161], v[174:177], v[28:31]
	v_mfma_f32_16x16x32_bf16 v[24:27], v[166:169], v[174:177], v[24:27]
	v_mfma_f32_16x16x32_bf16 v[20:23], v[158:161], v[182:185], v[20:23]
	v_mfma_f32_16x16x32_bf16 v[16:19], v[166:169], v[182:185], v[16:19]
	v_mfma_f32_16x16x32_bf16 v[12:15], v[158:161], v[190:193], v[12:15]
	v_mfma_f32_16x16x32_bf16 v[8:11], v[166:169], v[190:193], v[8:11]
	v_mfma_f32_16x16x32_bf16 v[4:7], v[158:161], v[198:201], v[4:7]
	v_mfma_f32_16x16x32_bf16 v[0:3], v[166:169], v[198:201], v[0:3]
	s_barrier
	ds_read_b128 v[130:133], v140
	ds_read_b128 v[142:145], v140 offset:1024
	ds_read_b128 v[146:149], v140 offset:2048
	ds_read_b128 v[150:153], v140 offset:3072
	ds_read_b128 v[154:157], v141
	ds_read_b128 v[158:161], v141 offset:1024
	ds_read_b128 v[162:165], v141 offset:2048
	ds_read_b128 v[166:169], v141 offset:3072
	ds_read_b128 v[170:173], v139 offset:32768
	ds_read_b128 v[174:177], v139 offset:33792
	ds_read_b128 v[178:181], v139 offset:34816
	ds_read_b128 v[182:185], v139 offset:35840
	ds_read_b128 v[186:189], v139 offset:36864
	ds_read_b128 v[190:193], v139 offset:37888
	ds_read_b128 v[194:197], v139 offset:38912
	ds_read_b128 v[198:201], v139 offset:39936
	s_add_u32 s52, s77, 0x100
	s_addc_u32 s53, s87, 0
	s_add_u32 s80, s90, 0x100
	s_mov_b32 m0, s63
	s_nop 0
	global_load_lds_dwordx4 v128, s[52:53]
	s_addc_u32 s81, s91, 0
	s_mov_b32 m0, s64
	s_nop 0
	global_load_lds_dwordx4 v128, s[80:81]
	s_waitcnt vmcnt(8)
	s_waitcnt lgkmcnt(0)
	s_barrier
	s_waitcnt lgkmcnt(7)
	v_mfma_f32_16x16x32_bf16 v[124:127], v[130:133], v[170:173], v[124:127]
	v_mfma_f32_16x16x32_bf16 v[120:123], v[146:149], v[170:173], v[120:123]
	s_waitcnt lgkmcnt(5)
	v_mfma_f32_16x16x32_bf16 v[116:119], v[130:133], v[178:181], v[116:119]
	v_mfma_f32_16x16x32_bf16 v[112:115], v[146:149], v[178:181], v[112:115]
	s_waitcnt lgkmcnt(3)
	v_mfma_f32_16x16x32_bf16 v[108:111], v[130:133], v[186:189], v[108:111]
	v_mfma_f32_16x16x32_bf16 v[104:107], v[146:149], v[186:189], v[104:107]
	s_waitcnt lgkmcnt(1)
	v_mfma_f32_16x16x32_bf16 v[100:103], v[130:133], v[194:197], v[100:103]
	v_mfma_f32_16x16x32_bf16 v[96:99], v[146:149], v[194:197], v[96:99]
	v_mfma_f32_16x16x32_bf16 v[124:127], v[142:145], v[174:177], v[124:127]
	v_mfma_f32_16x16x32_bf16 v[120:123], v[150:153], v[174:177], v[120:123]
	v_mfma_f32_16x16x32_bf16 v[116:119], v[142:145], v[182:185], v[116:119]
	v_mfma_f32_16x16x32_bf16 v[112:115], v[150:153], v[182:185], v[112:115]
	v_mfma_f32_16x16x32_bf16 v[108:111], v[142:145], v[190:193], v[108:111]
	v_mfma_f32_16x16x32_bf16 v[104:107], v[150:153], v[190:193], v[104:107]
	s_waitcnt lgkmcnt(0)
	v_mfma_f32_16x16x32_bf16 v[100:103], v[142:145], v[198:201], v[100:103]
	v_mfma_f32_16x16x32_bf16 v[96:99], v[150:153], v[198:201], v[96:99]
	v_mfma_f32_16x16x32_bf16 v[92:95], v[154:157], v[170:173], v[92:95]
	v_mfma_f32_16x16x32_bf16 v[88:91], v[162:165], v[170:173], v[88:91]
	v_mfma_f32_16x16x32_bf16 v[84:87], v[154:157], v[178:181], v[84:87]
	v_mfma_f32_16x16x32_bf16 v[80:83], v[162:165], v[178:181], v[80:83]
	v_mfma_f32_16x16x32_bf16 v[76:79], v[154:157], v[186:189], v[76:79]
	v_mfma_f32_16x16x32_bf16 v[72:75], v[162:165], v[186:189], v[72:75]
	v_mfma_f32_16x16x32_bf16 v[68:71], v[154:157], v[194:197], v[68:71]
	v_mfma_f32_16x16x32_bf16 v[64:67], v[162:165], v[194:197], v[64:67]
	v_mfma_f32_16x16x32_bf16 v[92:95], v[158:161], v[174:177], v[92:95]
	v_mfma_f32_16x16x32_bf16 v[88:91], v[166:169], v[174:177], v[88:91]
	v_mfma_f32_16x16x32_bf16 v[84:87], v[158:161], v[182:185], v[84:87]
	v_mfma_f32_16x16x32_bf16 v[80:83], v[166:169], v[182:185], v[80:83]
	v_mfma_f32_16x16x32_bf16 v[76:79], v[158:161], v[190:193], v[76:79]
	v_mfma_f32_16x16x32_bf16 v[72:75], v[166:169], v[190:193], v[72:75]
	v_mfma_f32_16x16x32_bf16 v[68:71], v[158:161], v[198:201], v[68:71]
	v_mfma_f32_16x16x32_bf16 v[64:67], v[166:169], v[198:201], v[64:67]
	s_barrier
	s_add_u32 s52, s92, 0x180
	s_addc_u32 s53, s93, 0
	ds_read_b128 v[170:173], v139 offset:49152
	ds_read_b128 v[174:177], v139 offset:50176
	ds_read_b128 v[178:181], v139 offset:51200
	ds_read_b128 v[182:185], v139 offset:52224
	ds_read_b128 v[186:189], v139 offset:53248
	ds_read_b128 v[190:193], v139 offset:54272
	ds_read_b128 v[194:197], v139 offset:55296
	ds_read_b128 v[198:201], v139 offset:56320
	s_add_u32 s80, s94, 0x180
	s_mov_b32 m0, s67
	s_nop 0
	global_load_lds_dwordx4 v129, s[52:53]
	s_addc_u32 s81, s95, 0
	s_mov_b32 m0, s73
	s_nop 0
	global_load_lds_dwordx4 v129, s[80:81]
	s_add_u32 s52, s96, 0x180
	s_addc_u32 s53, s97, 0
	s_add_u32 s80, vcc_lo, 0x180
	s_mov_b32 m0, s82
	s_nop 0
	global_load_lds_dwordx4 v129, s[52:53]
	s_addc_u32 s81, vcc_hi, 0
	s_mov_b32 m0, s83
	s_nop 0
	global_load_lds_dwordx4 v129, s[80:81]
	s_add_u32 s52, s74, 0x180
	s_addc_u32 s53, s75, 0
	s_add_u32 s74, s57, 0x180
	s_mov_b32 m0, s78
	s_nop 0
	global_load_lds_dwordx4 v128, s[52:53]
	s_addc_u32 s75, s88, 0
	s_mov_b32 m0, s79
	s_nop 0
	global_load_lds_dwordx4 v128, s[74:75]
	s_waitcnt vmcnt(8)
	s_waitcnt lgkmcnt(0)
	s_barrier
	s_waitcnt lgkmcnt(7)
	v_mfma_f32_16x16x32_bf16 v[60:63], v[130:133], v[170:173], v[60:63]
	v_mfma_f32_16x16x32_bf16 v[56:59], v[146:149], v[170:173], v[56:59]
	s_waitcnt lgkmcnt(5)
	v_mfma_f32_16x16x32_bf16 v[52:55], v[130:133], v[178:181], v[52:55]
	v_mfma_f32_16x16x32_bf16 v[48:51], v[146:149], v[178:181], v[48:51]
	s_waitcnt lgkmcnt(3)
	v_mfma_f32_16x16x32_bf16 v[44:47], v[130:133], v[186:189], v[44:47]
	v_mfma_f32_16x16x32_bf16 v[40:43], v[146:149], v[186:189], v[40:43]
	s_waitcnt lgkmcnt(1)
	v_mfma_f32_16x16x32_bf16 v[36:39], v[130:133], v[194:197], v[36:39]
	v_mfma_f32_16x16x32_bf16 v[32:35], v[146:149], v[194:197], v[32:35]
	v_mfma_f32_16x16x32_bf16 v[60:63], v[142:145], v[174:177], v[60:63]
	v_mfma_f32_16x16x32_bf16 v[56:59], v[150:153], v[174:177], v[56:59]
	v_mfma_f32_16x16x32_bf16 v[52:55], v[142:145], v[182:185], v[52:55]
	v_mfma_f32_16x16x32_bf16 v[48:51], v[150:153], v[182:185], v[48:51]
	v_mfma_f32_16x16x32_bf16 v[44:47], v[142:145], v[190:193], v[44:47]
	v_mfma_f32_16x16x32_bf16 v[40:43], v[150:153], v[190:193], v[40:43]
	s_waitcnt lgkmcnt(0)
	v_mfma_f32_16x16x32_bf16 v[36:39], v[142:145], v[198:201], v[36:39]
	v_mfma_f32_16x16x32_bf16 v[32:35], v[150:153], v[198:201], v[32:35]
	v_mfma_f32_16x16x32_bf16 v[28:31], v[154:157], v[170:173], v[28:31]
	v_mfma_f32_16x16x32_bf16 v[24:27], v[162:165], v[170:173], v[24:27]
	v_mfma_f32_16x16x32_bf16 v[20:23], v[154:157], v[178:181], v[20:23]
	v_mfma_f32_16x16x32_bf16 v[16:19], v[162:165], v[178:181], v[16:19]
	v_mfma_f32_16x16x32_bf16 v[12:15], v[154:157], v[186:189], v[12:15]
	v_mfma_f32_16x16x32_bf16 v[8:11], v[162:165], v[186:189], v[8:11]
	v_mfma_f32_16x16x32_bf16 v[4:7], v[154:157], v[194:197], v[4:7]
	v_mfma_f32_16x16x32_bf16 v[0:3], v[162:165], v[194:197], v[0:3]
	v_mfma_f32_16x16x32_bf16 v[28:31], v[158:161], v[174:177], v[28:31]
	v_mfma_f32_16x16x32_bf16 v[24:27], v[166:169], v[174:177], v[24:27]
	v_mfma_f32_16x16x32_bf16 v[20:23], v[158:161], v[182:185], v[20:23]
	v_mfma_f32_16x16x32_bf16 v[16:19], v[166:169], v[182:185], v[16:19]
	v_mfma_f32_16x16x32_bf16 v[12:15], v[158:161], v[190:193], v[12:15]
	v_mfma_f32_16x16x32_bf16 v[8:11], v[166:169], v[190:193], v[8:11]
	v_mfma_f32_16x16x32_bf16 v[4:7], v[158:161], v[198:201], v[4:7]
	v_mfma_f32_16x16x32_bf16 v[0:3], v[166:169], v[198:201], v[0:3]
	s_barrier
	s_add_u32 s50, s50, 0x100
	s_addc_u32 s51, s51, 0
	s_cmp_ge_i32 s72, s2
	s_cbranch_scc0 .LBB0_783

.LBB0_786:
	ds_read_b128 v[132:135], v137
	ds_read_b128 v[142:145], v137 offset:1024
	ds_read_b128 v[146:149], v137 offset:2048
	ds_read_b128 v[150:153], v137 offset:3072
	ds_read_b128 v[154:157], v138
	ds_read_b128 v[158:161], v138 offset:1024
	ds_read_b128 v[162:165], v138 offset:2048
	ds_read_b128 v[166:169], v138 offset:3072
	s_ashr_i32 s25, s24, 31
	s_lshl_b64 s[24:25], s[24:25], 7
	s_add_u32 s2, s4, s24
	ds_read_b128 v[170:173], v139
	ds_read_b128 v[174:177], v139 offset:1024
	ds_read_b128 v[178:181], v139 offset:2048
	ds_read_b128 v[182:185], v139 offset:3072
	ds_read_b128 v[186:189], v139 offset:4096
	ds_read_b128 v[190:193], v139 offset:5120
	ds_read_b128 v[194:197], v139 offset:6144
	ds_read_b128 v[198:201], v139 offset:7168
	s_addc_u32 s4, s5, s25
	s_add_u32 s2, s2, s48
	s_addc_u32 s5, s4, s49
	s_add_u32 s4, s2, 0xffffff80
	s_addc_u32 s5, s5, -1
	s_add_u32 s24, s4, s46
	s_mov_b32 m0, s84
	s_nop 0
	global_load_lds_dwordx4 v128, s[4:5]
	s_addc_u32 s25, s5, s47
	s_mov_b32 m0, s85
	s_nop 0
	global_load_lds_dwordx4 v128, s[24:25]
	s_waitcnt vmcnt(8)
	s_waitcnt lgkmcnt(0)
	s_barrier
	s_waitcnt lgkmcnt(7)
	v_mfma_f32_16x16x32_bf16 v[124:127], v[132:135], v[170:173], v[124:127]
	v_mfma_f32_16x16x32_bf16 v[120:123], v[146:149], v[170:173], v[120:123]
	s_waitcnt lgkmcnt(3)
	v_mfma_f32_16x16x32_bf16 v[104:107], v[146:149], v[186:189], v[104:107]
	s_waitcnt lgkmcnt(1)
	v_mfma_f32_16x16x32_bf16 v[96:99], v[146:149], v[194:197], v[96:99]
	v_mfma_f32_16x16x32_bf16 v[124:127], v[142:145], v[174:177], v[124:127]
	v_mfma_f32_16x16x32_bf16 v[120:123], v[150:153], v[174:177], v[120:123]
	v_mfma_f32_16x16x32_bf16 v[116:119], v[132:135], v[178:181], v[116:119]
	v_mfma_f32_16x16x32_bf16 v[112:115], v[146:149], v[178:181], v[112:115]
	v_mfma_f32_16x16x32_bf16 v[108:111], v[132:135], v[186:189], v[108:111]
	v_mfma_f32_16x16x32_bf16 v[104:107], v[150:153], v[190:193], v[104:107]
	v_mfma_f32_16x16x32_bf16 v[100:103], v[132:135], v[194:197], v[100:103]
	s_waitcnt lgkmcnt(0)
	v_mfma_f32_16x16x32_bf16 v[96:99], v[150:153], v[198:201], v[96:99]
	v_mfma_f32_16x16x32_bf16 v[202:205], v[142:145], v[182:185], v[116:119]
	v_mfma_f32_16x16x32_bf16 v[206:209], v[150:153], v[182:185], v[112:115]
	v_mfma_f32_16x16x32_bf16 v[210:213], v[142:145], v[190:193], v[108:111]
	v_mfma_f32_16x16x32_bf16 v[214:217], v[142:145], v[198:201], v[100:103]
	v_mfma_f32_16x16x32_bf16 v[92:95], v[154:157], v[170:173], v[92:95]
	v_mfma_f32_16x16x32_bf16 v[88:91], v[162:165], v[170:173], v[88:91]
	v_mfma_f32_16x16x32_bf16 v[72:75], v[162:165], v[186:189], v[72:75]
	v_mfma_f32_16x16x32_bf16 v[64:67], v[162:165], v[194:197], v[64:67]
	v_mfma_f32_16x16x32_bf16 v[92:95], v[158:161], v[174:177], v[92:95]
	v_mfma_f32_16x16x32_bf16 v[88:91], v[166:169], v[174:177], v[88:91]
	v_mfma_f32_16x16x32_bf16 v[84:87], v[154:157], v[178:181], v[84:87]
	v_mfma_f32_16x16x32_bf16 v[80:83], v[162:165], v[178:181], v[80:83]
	v_mfma_f32_16x16x32_bf16 v[76:79], v[154:157], v[186:189], v[76:79]
	v_mfma_f32_16x16x32_bf16 v[72:75], v[166:169], v[190:193], v[72:75]
	v_mfma_f32_16x16x32_bf16 v[68:71], v[154:157], v[194:197], v[68:71]
	v_mfma_f32_16x16x32_bf16 v[64:67], v[166:169], v[198:201], v[64:67]
	v_mfma_f32_16x16x32_bf16 v[170:173], v[158:161], v[182:185], v[84:87]
	v_mfma_f32_16x16x32_bf16 v[174:177], v[166:169], v[182:185], v[80:83]
	v_mfma_f32_16x16x32_bf16 v[178:181], v[158:161], v[190:193], v[76:79]
	v_mfma_f32_16x16x32_bf16 v[182:185], v[158:161], v[198:201], v[68:71]
	s_barrier
	s_add_u32 s24, s6, s0
	ds_read_b128 v[68:71], v139 offset:16384
	ds_read_b128 v[76:79], v139 offset:17408
	ds_read_b128 v[80:83], v139 offset:18432
	ds_read_b128 v[84:87], v139 offset:19456
	ds_read_b128 v[100:103], v139 offset:20480
	ds_read_b128 v[108:111], v139 offset:21504
	ds_read_b128 v[112:115], v139 offset:22528
	ds_read_b128 v[116:119], v139 offset:23552
	s_addc_u32 s25, s7, s1
	s_mov_b32 m0, s58
	s_nop 0
	global_load_lds_dwordx4 v131, s[6:7]
	s_add_u32 s46, s6, s30
	s_mov_b32 m0, s59
	s_nop 0
	global_load_lds_dwordx4 v131, s[24:25]
	s_addc_u32 s47, s7, s31
	s_add_u32 s48, s46, s0
	s_mov_b32 m0, s60
	s_nop 0
	global_load_lds_dwordx4 v131, s[46:47]
	s_addc_u32 s49, s47, s1
	s_mov_b32 m0, s61
	s_nop 0
	global_load_lds_dwordx4 v131, s[48:49]
	s_add_u32 s4, s54, s52
	s_mov_b32 m0, s3
	s_nop 0
	global_load_lds_dwordx4 v130, s[54:55]
	s_addc_u32 s5, s55, s53
	s_mov_b32 m0, s62
	s_nop 0
	global_load_lds_dwordx4 v130, s[4:5]
	s_waitcnt vmcnt(8)
	s_waitcnt lgkmcnt(0)
	s_barrier
	s_waitcnt lgkmcnt(7)
	v_mfma_f32_16x16x32_bf16 v[60:63], v[132:135], v[68:71], v[60:63]
	v_mfma_f32_16x16x32_bf16 v[56:59], v[146:149], v[68:71], v[56:59]
	s_waitcnt lgkmcnt(3)
	v_mfma_f32_16x16x32_bf16 v[40:43], v[146:149], v[100:103], v[40:43]
	s_waitcnt lgkmcnt(1)
	v_mfma_f32_16x16x32_bf16 v[32:35], v[146:149], v[112:115], v[32:35]
	v_mfma_f32_16x16x32_bf16 v[60:63], v[142:145], v[76:79], v[60:63]
	v_mfma_f32_16x16x32_bf16 v[56:59], v[150:153], v[76:79], v[56:59]
	v_mfma_f32_16x16x32_bf16 v[52:55], v[132:135], v[80:83], v[52:55]
	v_mfma_f32_16x16x32_bf16 v[48:51], v[146:149], v[80:83], v[48:51]
	v_mfma_f32_16x16x32_bf16 v[44:47], v[132:135], v[100:103], v[44:47]
	v_mfma_f32_16x16x32_bf16 v[40:43], v[150:153], v[108:111], v[40:43]
	v_mfma_f32_16x16x32_bf16 v[36:39], v[132:135], v[112:115], v[36:39]
	s_waitcnt lgkmcnt(0)
	v_mfma_f32_16x16x32_bf16 v[32:35], v[150:153], v[116:119], v[32:35]
	v_mfma_f32_16x16x32_bf16 v[186:189], v[142:145], v[84:87], v[52:55]
	v_mfma_f32_16x16x32_bf16 v[190:193], v[150:153], v[84:87], v[48:51]
	v_mfma_f32_16x16x32_bf16 v[194:197], v[142:145], v[108:111], v[44:47]
	v_mfma_f32_16x16x32_bf16 v[132:135], v[142:145], v[116:119], v[36:39]
	v_mfma_f32_16x16x32_bf16 v[28:31], v[154:157], v[68:71], v[28:31]
	v_mfma_f32_16x16x32_bf16 v[24:27], v[162:165], v[68:71], v[24:27]
	v_mfma_f32_16x16x32_bf16 v[20:23], v[154:157], v[80:83], v[20:23]
	v_mfma_f32_16x16x32_bf16 v[16:19], v[162:165], v[80:83], v[16:19]
	v_mfma_f32_16x16x32_bf16 v[28:31], v[158:161], v[76:79], v[28:31]
	v_mfma_f32_16x16x32_bf16 v[24:27], v[166:169], v[76:79], v[24:27]
	v_mfma_f32_16x16x32_bf16 v[20:23], v[158:161], v[84:87], v[20:23]
	v_mfma_f32_16x16x32_bf16 v[16:19], v[166:169], v[84:87], v[16:19]
	v_mfma_f32_16x16x32_bf16 v[12:15], v[154:157], v[100:103], v[12:15]
	v_mfma_f32_16x16x32_bf16 v[8:11], v[162:165], v[100:103], v[8:11]
	v_mfma_f32_16x16x32_bf16 v[4:7], v[154:157], v[112:115], v[4:7]
	v_mfma_f32_16x16x32_bf16 v[0:3], v[162:165], v[112:115], v[0:3]
	v_mfma_f32_16x16x32_bf16 v[142:145], v[158:161], v[108:111], v[12:15]
	v_mfma_f32_16x16x32_bf16 v[146:149], v[166:169], v[108:111], v[8:11]
	v_mfma_f32_16x16x32_bf16 v[150:153], v[158:161], v[116:119], v[4:7]
	v_mfma_f32_16x16x32_bf16 v[154:157], v[166:169], v[116:119], v[0:3]
	s_barrier
	s_nop 1
	ds_read_b128 v[0:3], v140
	ds_read_b128 v[4:7], v140 offset:1024
	ds_read_b128 v[158:161], v140 offset:2048
	ds_read_b128 v[162:165], v140 offset:3072
	ds_read_b128 v[166:169], v141
	ds_read_b128 v[198:201], v141 offset:1024
	ds_read_b128 v[218:221], v141 offset:2048
	ds_read_b128 v[222:225], v141 offset:3072
	ds_read_b128 v[8:11], v139 offset:32768
	ds_read_b128 v[12:15], v139 offset:33792
	ds_read_b128 v[36:39], v139 offset:34816
	ds_read_b128 v[44:47], v139 offset:35840
	ds_read_b128 v[48:51], v139 offset:36864
	ds_read_b128 v[52:55], v139 offset:37888
	ds_read_b128 v[226:229], v139 offset:38912
	ds_read_b128 v[230:233], v139 offset:39936
	s_add_u32 s68, s54, s50
	s_addc_u32 s69, s55, s51
	s_add_u32 s70, s68, s52
	s_mov_b32 m0, s63
	s_nop 0
	global_load_lds_dwordx4 v130, s[68:69]
	s_addc_u32 s71, s69, s53
	s_mov_b32 m0, s64
	s_nop 0
	global_load_lds_dwordx4 v130, s[70:71]
	s_waitcnt vmcnt(8)
	s_waitcnt lgkmcnt(0)
	s_barrier
	s_waitcnt lgkmcnt(7)
	v_mfma_f32_16x16x32_bf16 v[68:71], v[0:3], v[8:11], v[124:127]
	s_waitcnt lgkmcnt(6)
	v_mfma_f32_16x16x32_bf16 v[112:115], v[4:7], v[12:15], v[68:71]
	v_mfma_f32_16x16x32_bf16 v[68:71], v[158:161], v[8:11], v[120:123]
	v_mfma_f32_16x16x32_bf16 v[116:119], v[162:165], v[12:15], v[68:71]
	s_waitcnt lgkmcnt(5)
	v_mfma_f32_16x16x32_bf16 v[68:71], v[0:3], v[36:39], v[202:205]
	s_waitcnt lgkmcnt(4)
	v_mfma_f32_16x16x32_bf16 v[108:111], v[4:7], v[44:47], v[68:71]
	v_mfma_f32_16x16x32_bf16 v[68:71], v[158:161], v[36:39], v[206:209]
	v_mfma_f32_16x16x32_bf16 v[100:103], v[162:165], v[44:47], v[68:71]
	s_waitcnt lgkmcnt(3)
	v_mfma_f32_16x16x32_bf16 v[68:71], v[0:3], v[48:51], v[210:213]
	s_waitcnt lgkmcnt(2)
	v_mfma_f32_16x16x32_bf16 v[80:83], v[4:7], v[52:55], v[68:71]
	v_mfma_f32_16x16x32_bf16 v[68:71], v[158:161], v[48:51], v[104:107]
	v_mfma_f32_16x16x32_bf16 v[84:87], v[162:165], v[52:55], v[68:71]
	s_waitcnt lgkmcnt(1)
	v_mfma_f32_16x16x32_bf16 v[68:71], v[0:3], v[226:229], v[214:217]
	s_waitcnt lgkmcnt(0)
	v_mfma_f32_16x16x32_bf16 v[76:79], v[4:7], v[230:233], v[68:71]
	v_mfma_f32_16x16x32_bf16 v[68:71], v[158:161], v[226:229], v[96:99]
	v_mfma_f32_16x16x32_bf16 v[68:71], v[162:165], v[230:233], v[68:71]
	v_mfma_f32_16x16x32_bf16 v[92:95], v[166:169], v[8:11], v[92:95]
	v_mfma_f32_16x16x32_bf16 v[8:11], v[218:221], v[8:11], v[88:91]
	v_mfma_f32_16x16x32_bf16 v[124:127], v[222:225], v[12:15], v[8:11]
	v_mfma_f32_16x16x32_bf16 v[8:11], v[166:169], v[36:39], v[170:173]
	v_mfma_f32_16x16x32_bf16 v[104:107], v[198:201], v[44:47], v[8:11]
	v_mfma_f32_16x16x32_bf16 v[8:11], v[218:221], v[36:39], v[174:177]
	v_mfma_f32_16x16x32_bf16 v[96:99], v[222:225], v[44:47], v[8:11]
	v_mfma_f32_16x16x32_bf16 v[8:11], v[166:169], v[48:51], v[178:181]
	v_mfma_f32_16x16x32_bf16 v[88:91], v[198:201], v[52:55], v[8:11]
	v_mfma_f32_16x16x32_bf16 v[8:11], v[218:221], v[48:51], v[72:75]
	v_mfma_f32_16x16x32_bf16 v[120:123], v[198:201], v[12:15], v[92:95]
	v_mfma_f32_16x16x32_bf16 v[92:95], v[222:225], v[52:55], v[8:11]
	v_mfma_f32_16x16x32_bf16 v[8:11], v[166:169], v[226:229], v[182:185]
	v_mfma_f32_16x16x32_bf16 v[72:75], v[198:201], v[230:233], v[8:11]
	v_mfma_f32_16x16x32_bf16 v[8:11], v[218:221], v[226:229], v[64:67]
	v_mfma_f32_16x16x32_bf16 v[64:67], v[222:225], v[230:233], v[8:11]
	s_barrier
	s_add_u32 s68, s6, 0x80
	s_addc_u32 s69, s7, 0
	s_add_u32 s24, s24, 0x80
	ds_read_b128 v[170:173], v139 offset:49152
	ds_read_b128 v[174:177], v139 offset:50176
	ds_read_b128 v[178:181], v139 offset:51200
	ds_read_b128 v[182:185], v139 offset:52224
	ds_read_b128 v[202:205], v139 offset:53248
	ds_read_b128 v[206:209], v139 offset:54272
	ds_read_b128 v[210:213], v139 offset:55296
	ds_read_b128 v[214:217], v139 offset:56320
	s_addc_u32 s25, s25, 0
	s_mov_b32 m0, s67
	s_nop 0
	global_load_lds_dwordx4 v131, s[68:69]
	s_nop 0
	s_mov_b32 m0, s73
	s_nop 0
	global_load_lds_dwordx4 v131, s[24:25]
	s_add_u32 s24, s46, 0x80
	s_addc_u32 s25, s47, 0
	s_add_u32 s46, s48, 0x80
	s_addc_u32 s47, s49, 0
	s_mov_b32 m0, s82
	s_nop 0
	global_load_lds_dwordx4 v131, s[24:25]
	s_add_u32 s24, s54, 0x80
	s_mov_b32 m0, s83
	s_nop 0
	global_load_lds_dwordx4 v131, s[46:47]
	s_addc_u32 s25, s55, 0
	s_add_u32 s4, s4, 0x80
	s_mov_b32 m0, s78
	s_nop 0
	global_load_lds_dwordx4 v130, s[24:25]
	s_addc_u32 s5, s5, 0
	s_mov_b32 m0, s79
	s_nop 0
	global_load_lds_dwordx4 v130, s[4:5]
	s_waitcnt vmcnt(8)
	s_waitcnt lgkmcnt(0)
	s_barrier
	s_waitcnt lgkmcnt(7)
	v_mfma_f32_16x16x32_bf16 v[8:11], v[0:3], v[170:173], v[60:63]
	s_waitcnt lgkmcnt(6)
	v_mfma_f32_16x16x32_bf16 v[48:51], v[4:7], v[174:177], v[8:11]
	v_mfma_f32_16x16x32_bf16 v[8:11], v[158:161], v[170:173], v[56:59]
	v_mfma_f32_16x16x32_bf16 v[52:55], v[162:165], v[174:177], v[8:11]
	s_waitcnt lgkmcnt(5)
	v_mfma_f32_16x16x32_bf16 v[8:11], v[0:3], v[178:181], v[186:189]
	s_waitcnt lgkmcnt(4)
	v_mfma_f32_16x16x32_bf16 v[44:47], v[4:7], v[182:185], v[8:11]
	v_mfma_f32_16x16x32_bf16 v[8:11], v[158:161], v[178:181], v[190:193]
	v_mfma_f32_16x16x32_bf16 v[36:39], v[162:165], v[182:185], v[8:11]
	s_waitcnt lgkmcnt(3)
	v_mfma_f32_16x16x32_bf16 v[8:11], v[0:3], v[202:205], v[194:197]
	s_waitcnt lgkmcnt(1)
	v_mfma_f32_16x16x32_bf16 v[0:3], v[0:3], v[210:213], v[132:135]
	v_mfma_f32_16x16x32_bf16 v[8:11], v[4:7], v[206:209], v[8:11]
	v_mfma_f32_16x16x32_bf16 v[12:15], v[158:161], v[202:205], v[40:43]
	s_waitcnt lgkmcnt(0)
	v_mfma_f32_16x16x32_bf16 v[0:3], v[4:7], v[214:217], v[0:3]
	v_mfma_f32_16x16x32_bf16 v[4:7], v[158:161], v[210:213], v[32:35]
	v_mfma_f32_16x16x32_bf16 v[12:15], v[162:165], v[206:209], v[12:15]
	v_mfma_f32_16x16x32_bf16 v[4:7], v[162:165], v[214:217], v[4:7]
	v_mfma_f32_16x16x32_bf16 v[16:19], v[218:221], v[178:181], v[16:19]
	v_mfma_f32_16x16x32_bf16 v[24:27], v[218:221], v[170:173], v[24:27]
	v_mfma_f32_16x16x32_bf16 v[32:35], v[222:225], v[182:185], v[16:19]
	v_mfma_f32_16x16x32_bf16 v[16:19], v[166:169], v[202:205], v[142:145]
	v_mfma_f32_16x16x32_bf16 v[28:31], v[166:169], v[170:173], v[28:31]
	v_mfma_f32_16x16x32_bf16 v[60:63], v[222:225], v[174:177], v[24:27]
	v_mfma_f32_16x16x32_bf16 v[20:23], v[166:169], v[178:181], v[20:23]
	v_mfma_f32_16x16x32_bf16 v[24:27], v[198:201], v[206:209], v[16:19]
	v_mfma_f32_16x16x32_bf16 v[16:19], v[218:221], v[202:205], v[146:149]
	v_mfma_f32_16x16x32_bf16 v[56:59], v[198:201], v[174:177], v[28:31]
	v_mfma_f32_16x16x32_bf16 v[40:43], v[198:201], v[182:185], v[20:23]
	v_mfma_f32_16x16x32_bf16 v[28:31], v[222:225], v[206:209], v[16:19]
	v_mfma_f32_16x16x32_bf16 v[16:19], v[166:169], v[210:213], v[150:153]
	v_mfma_f32_16x16x32_bf16 v[20:23], v[218:221], v[210:213], v[154:157]
	v_mfma_f32_16x16x32_bf16 v[16:19], v[198:201], v[214:217], v[16:19]
	v_mfma_f32_16x16x32_bf16 v[20:23], v[222:225], v[214:217], v[20:23]
	s_barrier
	s_andn2_b64 vcc, exec, s[36:37]
	s_cbranch_vccnz .LBB0_788
	s_barrier

.LBB0_916:
	s_lshl_b64 s[36:37], s[8:9], 7
	s_lshl_b64 s[20:21], s[20:21], 7
	v_and_b32_e32 v1, 15, v2
	v_or_b32_e32 v3, s3, v1
	s_add_u32 s8, s6, 0x80
	v_lshlrev_b32_e32 v5, 6, v3
	v_and_b32_e32 v6, 48, v2
	s_movk_i32 s2, 0x3c0
	s_addc_u32 s9, s7, 0
	v_and_or_b32 v5, v5, s2, v6
	s_sub_u32 s2, 0, s16
	s_subb_u32 s22, 0, s17
	s_add_u32 s2, s10, s2
	s_addc_u32 s23, s11, s22
	s_add_u32 s22, s2, 0x80
	s_addc_u32 s23, s23, 0
	s_add_i32 s60, s55, 0x18000
	s_add_i32 s61, s55, 0x1a000
	s_mov_b32 s98, 0
	s_cselect_b32 s99, 1, 0
	s_cmp_lt_u32 s76, 4
	s_cbranch_scc0 .Lsprio_10
	s_setprio 1
.Lsprio_10:
	s_cmp_lg_u32 s99, 0
	s_waitcnt vmcnt(2)
	s_barrier
	s_mov_b32 m0, s60
	s_nop 0
	global_load_lds_dwordx4 v0, s[8:9]
	s_add_u32 s8, s4, 0x80
	s_mov_b32 m0, s61
	s_nop 0
	global_load_lds_dwordx4 v0, s[22:23]
	s_addc_u32 s9, s5, 0
	s_sub_u32 s2, 0, s34
	s_subb_u32 s22, 0, s35
	s_add_u32 s2, s14, s2
	s_addc_u32 s15, s15, s22
	s_add_u32 s14, s2, 0x80
	s_addc_u32 s15, s15, 0
	s_add_i32 s62, s55, 0x8000
	s_add_i32 s63, s55, 0xa000
	s_mov_b32 m0, s62
	s_nop 0
	global_load_lds_dwordx4 v128, s[8:9]
	s_add_u32 s8, s10, 0x80
	s_addc_u32 s9, s11, 0
	s_mov_b32 m0, s63
	s_nop 0
	global_load_lds_dwordx4 v128, s[14:15]
	s_add_u32 s10, s12, 0x80
	v_ashrrev_i32_e32 v4, 6, v2
	v_lshlrev_b32_e32 v2, 2, v2
	s_addc_u32 s11, s13, 0
	s_add_i32 s64, s55, 0x1c000
	s_mov_b32 m0, s64
	s_nop 0
	global_load_lds_dwordx4 v0, s[8:9]
	v_lshl_add_u32 v7, v4, 10, s46
	v_lshlrev_b32_e32 v3, 2, v3
	v_lshl_or_b32 v1, v1, 6, v6
	v_add_lshl_u32 v4, v4, s47, 10
	v_and_b32_e32 v2, 32, v2
	s_add_i32 s65, s55, 0x1e000
	s_mov_b32 m0, s65
	s_nop 0
	global_load_lds_dwordx4 v0, s[10:11]
	v_and_b32_e32 v3, 32, v3
	v_bitop3_b32 v1, v1, v4, v2 bitop3:0xde
	s_waitcnt vmcnt(6)
	s_add_i32 s66, s55, 0xc000
	s_add_i32 s67, s55, 0xe000
	v_readlane_b32 s2, v254, 0
	v_mov_b32_e32 v129, v0
	v_bitop3_b32 v3, v5, v7, v3 bitop3:0xde
	s_cmpk_lt_u32 s2, 0x100
	v_add_u32_e32 v0, 0, v1
	s_mov_b32 s23, 0
	s_cselect_b64 s[24:25], -1, 0
	v_add_u32_e32 v133, 0x10000, v0
	v_add_u32_e32 v134, 0x14000, v0
	v_add_u32_e32 v135, 0, v3
	v_add_u32_e32 v136, 0x18000, v0
	v_add_u32_e32 v137, 0x1c000, v0
	s_mov_b32 s73, 0
	s_barrier
	s_branch .LBB0_919

.LBB0_921:
	s_cmp_lt_i32 s0, 3
	s_cbranch_scc1 .Lhz_923
	s_add_i32 s2, s0, -2
	s_add_u32 s22, s4, s36
	s_addc_u32 s33, s5, s37
	s_add_u32 s42, s6, s20
	s_addc_u32 s43, s7, s21
	s_add_u32 s38, s16, s20
	s_addc_u32 s39, s17, s21
	s_add_u32 s44, s6, s38
	s_addc_u32 s45, s7, s39
	s_add_u32 s68, s6, s16
	s_addc_u32 s69, s7, s17
	s_add_u32 s38, s34, s36
	s_addc_u32 s39, s35, s37
	s_add_u32 s70, s4, s38
	s_addc_u32 s71, s5, s39
	s_add_u32 s72, s4, s34
	s_addc_u32 s74, s5, s35
	s_mov_b32 s75, 0
	s_mov_b64 s[38:39], 0
	s_cmp_eq_u32 s98, 0
	s_cbranch_scc1 .Lhf_923
	ds_read_b128 v[138:141], v133
	ds_read_b128 v[142:145], v133 offset:1024
	ds_read_b128 v[146:149], v133 offset:2048
	ds_read_b128 v[150:153], v133 offset:3072
	ds_read_b128 v[154:157], v134
	ds_read_b128 v[158:161], v134 offset:1024
	ds_read_b128 v[162:165], v134 offset:2048
	ds_read_b128 v[166:169], v134 offset:3072
	s_add_i32 s75, s75, 2
	s_add_u32 s77, s4, s38
	s_addc_u32 s78, s5, s39
	s_add_u32 s40, s77, 0x100
	s_addc_u32 s41, s78, 0
	s_add_u32 s79, s22, s38
	ds_read_b128 v[170:173], v135
	ds_read_b128 v[174:177], v135 offset:1024
	ds_read_b128 v[178:181], v135 offset:2048
	ds_read_b128 v[182:185], v135 offset:3072
	ds_read_b128 v[186:189], v135 offset:4096
	ds_read_b128 v[190:193], v135 offset:5120
	ds_read_b128 v[194:197], v135 offset:6144
	ds_read_b128 v[198:201], v135 offset:7168
	s_addc_u32 s84, s33, s39
	s_add_u32 s80, s79, 0x80
	s_addc_u32 s81, s84, 0
	s_add_u32 s85, s70, s38
	s_addc_u32 s86, s71, s39
	s_add_u32 s82, s85, 0x80
	s_mov_b32 m0, s66
	s_nop 0
	global_load_lds_dwordx4 v128, s[80:81]
	s_addc_u32 s83, s86, 0
	s_mov_b32 m0, s67
	s_nop 0
	global_load_lds_dwordx4 v128, s[82:83]
	s_waitcnt vmcnt(16)
	s_waitcnt lgkmcnt(0)
	s_barrier
	s_waitcnt lgkmcnt(7)
	v_mfma_f32_16x16x32_bf16 v[124:127], v[138:141], v[170:173], 0
	v_mfma_f32_16x16x32_bf16 v[120:123], v[146:149], v[170:173], 0
	s_waitcnt lgkmcnt(5)
	v_mfma_f32_16x16x32_bf16 v[116:119], v[138:141], v[178:181], 0
	v_mfma_f32_16x16x32_bf16 v[112:115], v[146:149], v[178:181], 0
	s_waitcnt lgkmcnt(3)
	v_mfma_f32_16x16x32_bf16 v[108:111], v[138:141], v[186:189], 0
	v_mfma_f32_16x16x32_bf16 v[104:107], v[146:149], v[186:189], 0
	s_waitcnt lgkmcnt(1)
	v_mfma_f32_16x16x32_bf16 v[100:103], v[138:141], v[194:197], 0
	v_mfma_f32_16x16x32_bf16 v[96:99], v[146:149], v[194:197], 0
	v_mfma_f32_16x16x32_bf16 v[124:127], v[142:145], v[174:177], v[124:127]
	v_mfma_f32_16x16x32_bf16 v[120:123], v[150:153], v[174:177], v[120:123]
	v_mfma_f32_16x16x32_bf16 v[116:119], v[142:145], v[182:185], v[116:119]
	v_mfma_f32_16x16x32_bf16 v[112:115], v[150:153], v[182:185], v[112:115]
	v_mfma_f32_16x16x32_bf16 v[108:111], v[142:145], v[190:193], v[108:111]
	v_mfma_f32_16x16x32_bf16 v[104:107], v[150:153], v[190:193], v[104:107]
	s_waitcnt lgkmcnt(0)
	v_mfma_f32_16x16x32_bf16 v[100:103], v[142:145], v[198:201], v[100:103]
	v_mfma_f32_16x16x32_bf16 v[96:99], v[150:153], v[198:201], v[96:99]
	v_mfma_f32_16x16x32_bf16 v[92:95], v[154:157], v[170:173], 0
	v_mfma_f32_16x16x32_bf16 v[88:91], v[162:165], v[170:173], 0
	v_mfma_f32_16x16x32_bf16 v[84:87], v[154:157], v[178:181], 0
	v_mfma_f32_16x16x32_bf16 v[80:83], v[162:165], v[178:181], 0
	v_mfma_f32_16x16x32_bf16 v[76:79], v[154:157], v[186:189], 0
	v_mfma_f32_16x16x32_bf16 v[72:75], v[162:165], v[186:189], 0
	v_mfma_f32_16x16x32_bf16 v[68:71], v[154:157], v[194:197], 0
	v_mfma_f32_16x16x32_bf16 v[64:67], v[162:165], v[194:197], 0
	v_mfma_f32_16x16x32_bf16 v[92:95], v[158:161], v[174:177], v[92:95]
	v_mfma_f32_16x16x32_bf16 v[88:91], v[166:169], v[174:177], v[88:91]
	v_mfma_f32_16x16x32_bf16 v[84:87], v[158:161], v[182:185], v[84:87]
	v_mfma_f32_16x16x32_bf16 v[80:83], v[166:169], v[182:185], v[80:83]
	v_mfma_f32_16x16x32_bf16 v[76:79], v[158:161], v[190:193], v[76:79]
	v_mfma_f32_16x16x32_bf16 v[72:75], v[166:169], v[190:193], v[72:75]
	v_mfma_f32_16x16x32_bf16 v[68:71], v[158:161], v[198:201], v[68:71]
	v_mfma_f32_16x16x32_bf16 v[64:67], v[166:169], v[198:201], v[64:67]
	s_barrier
	s_add_u32 s87, s6, s38
	s_addc_u32 s88, s7, s39
	s_add_u32 s80, s87, 0x100
	s_addc_u32 s81, s88, 0
	s_add_u32 s89, s68, s38
	s_addc_u32 s90, s69, s39
	s_add_u32 s82, s89, 0x100
	ds_read_b128 v[170:173], v135 offset:16384
	ds_read_b128 v[174:177], v135 offset:17408
	ds_read_b128 v[178:181], v135 offset:18432
	ds_read_b128 v[182:185], v135 offset:19456
	ds_read_b128 v[186:189], v135 offset:20480
	ds_read_b128 v[190:193], v135 offset:21504
	ds_read_b128 v[194:197], v135 offset:22528
	ds_read_b128 v[198:201], v135 offset:23552
	s_addc_u32 s83, s90, 0
	s_mov_b32 m0, s51
	s_nop 0
	global_load_lds_dwordx4 v129, s[80:81]
	s_add_u32 s91, s42, s38
	s_mov_b32 m0, s52
	s_nop 0
	global_load_lds_dwordx4 v129, s[82:83]
	s_addc_u32 s92, s43, s39
	s_add_u32 s80, s91, 0x100
	s_addc_u32 s81, s92, 0
	s_add_u32 s93, s44, s38
	s_addc_u32 s94, s45, s39
	s_add_u32 s82, s93, 0x100
	s_addc_u32 s83, s94, 0
	s_mov_b32 m0, s53
	s_nop 0
	global_load_lds_dwordx4 v129, s[80:81]
	s_mov_b32 m0, s56
	s_nop 0
	global_load_lds_dwordx4 v129, s[82:83]
	s_add_u32 s82, s72, s38
	s_addc_u32 s83, s74, s39
	s_add_u32 s80, s82, 0x100
	s_mov_b32 m0, s55
	s_nop 0
	global_load_lds_dwordx4 v128, s[40:41]
	s_addc_u32 s81, s83, 0
	s_mov_b32 m0, s57
	s_nop 0
	global_load_lds_dwordx4 v128, s[80:81]
	s_waitcnt vmcnt(16)
	s_waitcnt lgkmcnt(0)
	s_barrier
	s_waitcnt lgkmcnt(7)
	v_mfma_f32_16x16x32_bf16 v[60:63], v[138:141], v[170:173], 0
	v_mfma_f32_16x16x32_bf16 v[56:59], v[146:149], v[170:173], 0
	s_waitcnt lgkmcnt(5)
	v_mfma_f32_16x16x32_bf16 v[52:55], v[138:141], v[178:181], 0
	v_mfma_f32_16x16x32_bf16 v[48:51], v[146:149], v[178:181], 0
	s_waitcnt lgkmcnt(3)
	v_mfma_f32_16x16x32_bf16 v[44:47], v[138:141], v[186:189], 0
	v_mfma_f32_16x16x32_bf16 v[40:43], v[146:149], v[186:189], 0
	s_waitcnt lgkmcnt(1)
	v_mfma_f32_16x16x32_bf16 v[36:39], v[138:141], v[194:197], 0
	v_mfma_f32_16x16x32_bf16 v[32:35], v[146:149], v[194:197], 0
	v_mfma_f32_16x16x32_bf16 v[60:63], v[142:145], v[174:177], v[60:63]
	v_mfma_f32_16x16x32_bf16 v[56:59], v[150:153], v[174:177], v[56:59]
	v_mfma_f32_16x16x32_bf16 v[52:55], v[142:145], v[182:185], v[52:55]
	v_mfma_f32_16x16x32_bf16 v[48:51], v[150:153], v[182:185], v[48:51]
	v_mfma_f32_16x16x32_bf16 v[44:47], v[142:145], v[190:193], v[44:47]
	v_mfma_f32_16x16x32_bf16 v[40:43], v[150:153], v[190:193], v[40:43]
	s_waitcnt lgkmcnt(0)
	v_mfma_f32_16x16x32_bf16 v[36:39], v[142:145], v[198:201], v[36:39]
	v_mfma_f32_16x16x32_bf16 v[32:35], v[150:153], v[198:201], v[32:35]
	v_mfma_f32_16x16x32_bf16 v[28:31], v[154:157], v[170:173], 0
	v_mfma_f32_16x16x32_bf16 v[24:27], v[162:165], v[170:173], 0
	v_mfma_f32_16x16x32_bf16 v[20:23], v[154:157], v[178:181], 0
	v_mfma_f32_16x16x32_bf16 v[16:19], v[162:165], v[178:181], 0
	v_mfma_f32_16x16x32_bf16 v[12:15], v[154:157], v[186:189], 0
	v_mfma_f32_16x16x32_bf16 v[8:11], v[162:165], v[186:189], 0
	v_mfma_f32_16x16x32_bf16 v[4:7], v[154:157], v[194:197], 0
	v_mfma_f32_16x16x32_bf16 v[0:3], v[162:165], v[194:197], 0
	v_mfma_f32_16x16x32_bf16 v[28:31], v[158:161], v[174:177], v[28:31]
	v_mfma_f32_16x16x32_bf16 v[24:27], v[166:169], v[174:177], v[24:27]
	v_mfma_f32_16x16x32_bf16 v[20:23], v[158:161], v[182:185], v[20:23]
	v_mfma_f32_16x16x32_bf16 v[16:19], v[166:169], v[182:185], v[16:19]
	v_mfma_f32_16x16x32_bf16 v[12:15], v[158:161], v[190:193], v[12:15]
	v_mfma_f32_16x16x32_bf16 v[8:11], v[166:169], v[190:193], v[8:11]
	v_mfma_f32_16x16x32_bf16 v[4:7], v[158:161], v[198:201], v[4:7]
	v_mfma_f32_16x16x32_bf16 v[0:3], v[166:169], v[198:201], v[0:3]
	s_barrier
	ds_read_b128 v[138:141], v136
	ds_read_b128 v[142:145], v136 offset:1024
	ds_read_b128 v[146:149], v136 offset:2048
	ds_read_b128 v[150:153], v136 offset:3072
	ds_read_b128 v[154:157], v137
	ds_read_b128 v[158:161], v137 offset:1024
	ds_read_b128 v[162:165], v137 offset:2048
	ds_read_b128 v[166:169], v137 offset:3072
	ds_read_b128 v[170:173], v135 offset:32768
	ds_read_b128 v[174:177], v135 offset:33792
	ds_read_b128 v[178:181], v135 offset:34816
	ds_read_b128 v[182:185], v135 offset:35840
	ds_read_b128 v[186:189], v135 offset:36864
	ds_read_b128 v[190:193], v135 offset:37888
	ds_read_b128 v[194:197], v135 offset:38912
	ds_read_b128 v[198:201], v135 offset:39936
	s_add_u32 s40, s79, 0x100
	s_addc_u32 s41, s84, 0
	s_add_u32 s80, s85, 0x100
	s_mov_b32 m0, s58
	s_nop 0
	global_load_lds_dwordx4 v128, s[40:41]
	s_addc_u32 s81, s86, 0
	s_mov_b32 m0, s59
	s_nop 0
	global_load_lds_dwordx4 v128, s[80:81]
	s_waitcnt vmcnt(8)
	s_waitcnt lgkmcnt(0)
	s_barrier
	s_waitcnt lgkmcnt(7)
	v_mfma_f32_16x16x32_bf16 v[124:127], v[138:141], v[170:173], v[124:127]
	v_mfma_f32_16x16x32_bf16 v[120:123], v[146:149], v[170:173], v[120:123]
	s_waitcnt lgkmcnt(5)
	v_mfma_f32_16x16x32_bf16 v[116:119], v[138:141], v[178:181], v[116:119]
	v_mfma_f32_16x16x32_bf16 v[112:115], v[146:149], v[178:181], v[112:115]
	s_waitcnt lgkmcnt(3)
	v_mfma_f32_16x16x32_bf16 v[108:111], v[138:141], v[186:189], v[108:111]
	v_mfma_f32_16x16x32_bf16 v[104:107], v[146:149], v[186:189], v[104:107]
	s_waitcnt lgkmcnt(1)
	v_mfma_f32_16x16x32_bf16 v[100:103], v[138:141], v[194:197], v[100:103]
	v_mfma_f32_16x16x32_bf16 v[96:99], v[146:149], v[194:197], v[96:99]
	v_mfma_f32_16x16x32_bf16 v[124:127], v[142:145], v[174:177], v[124:127]
	v_mfma_f32_16x16x32_bf16 v[120:123], v[150:153], v[174:177], v[120:123]
	v_mfma_f32_16x16x32_bf16 v[116:119], v[142:145], v[182:185], v[116:119]
	v_mfma_f32_16x16x32_bf16 v[112:115], v[150:153], v[182:185], v[112:115]
	v_mfma_f32_16x16x32_bf16 v[108:111], v[142:145], v[190:193], v[108:111]
	v_mfma_f32_16x16x32_bf16 v[104:107], v[150:153], v[190:193], v[104:107]
	s_waitcnt lgkmcnt(0)
	v_mfma_f32_16x16x32_bf16 v[100:103], v[142:145], v[198:201], v[100:103]
	v_mfma_f32_16x16x32_bf16 v[96:99], v[150:153], v[198:201], v[96:99]
	v_mfma_f32_16x16x32_bf16 v[92:95], v[154:157], v[170:173], v[92:95]
	v_mfma_f32_16x16x32_bf16 v[88:91], v[162:165], v[170:173], v[88:91]
	v_mfma_f32_16x16x32_bf16 v[84:87], v[154:157], v[178:181], v[84:87]
	v_mfma_f32_16x16x32_bf16 v[80:83], v[162:165], v[178:181], v[80:83]
	v_mfma_f32_16x16x32_bf16 v[76:79], v[154:157], v[186:189], v[76:79]
	v_mfma_f32_16x16x32_bf16 v[72:75], v[162:165], v[186:189], v[72:75]
	v_mfma_f32_16x16x32_bf16 v[68:71], v[154:157], v[194:197], v[68:71]
	v_mfma_f32_16x16x32_bf16 v[64:67], v[162:165], v[194:197], v[64:67]
	v_mfma_f32_16x16x32_bf16 v[92:95], v[158:161], v[174:177], v[92:95]
	v_mfma_f32_16x16x32_bf16 v[88:91], v[166:169], v[174:177], v[88:91]
	v_mfma_f32_16x16x32_bf16 v[84:87], v[158:161], v[182:185], v[84:87]
	v_mfma_f32_16x16x32_bf16 v[80:83], v[166:169], v[182:185], v[80:83]
	v_mfma_f32_16x16x32_bf16 v[76:79], v[158:161], v[190:193], v[76:79]
	v_mfma_f32_16x16x32_bf16 v[72:75], v[166:169], v[190:193], v[72:75]
	v_mfma_f32_16x16x32_bf16 v[68:71], v[158:161], v[198:201], v[68:71]
	v_mfma_f32_16x16x32_bf16 v[64:67], v[166:169], v[198:201], v[64:67]
	s_barrier
	s_add_u32 s40, s87, 0x180
	s_addc_u32 s41, s88, 0
	ds_read_b128 v[170:173], v135 offset:49152
	ds_read_b128 v[174:177], v135 offset:50176
	ds_read_b128 v[178:181], v135 offset:51200
	ds_read_b128 v[182:185], v135 offset:52224
	ds_read_b128 v[186:189], v135 offset:53248
	ds_read_b128 v[190:193], v135 offset:54272
	ds_read_b128 v[194:197], v135 offset:55296
	ds_read_b128 v[198:201], v135 offset:56320
	s_add_u32 s80, s89, 0x180
	s_mov_b32 m0, s60
	s_nop 0
	global_load_lds_dwordx4 v129, s[40:41]
	s_addc_u32 s81, s90, 0
	s_mov_b32 m0, s61
	s_nop 0
	global_load_lds_dwordx4 v129, s[80:81]
	s_add_u32 s40, s91, 0x180
	s_addc_u32 s41, s92, 0
	s_add_u32 s80, s93, 0x180
	s_mov_b32 m0, s64
	s_nop 0
	global_load_lds_dwordx4 v129, s[40:41]
	s_addc_u32 s81, s94, 0
	s_mov_b32 m0, s65
	s_nop 0
	global_load_lds_dwordx4 v129, s[80:81]
	s_add_u32 s40, s77, 0x180
	s_addc_u32 s41, s78, 0
	s_add_u32 s78, s82, 0x180
	s_mov_b32 m0, s62
	s_nop 0
	global_load_lds_dwordx4 v128, s[40:41]
	s_addc_u32 s79, s83, 0
	s_mov_b32 m0, s63
	s_nop 0
	global_load_lds_dwordx4 v128, s[78:79]
	s_waitcnt vmcnt(8)
	s_waitcnt lgkmcnt(0)
	s_barrier
	s_waitcnt lgkmcnt(7)
	v_mfma_f32_16x16x32_bf16 v[60:63], v[138:141], v[170:173], v[60:63]
	v_mfma_f32_16x16x32_bf16 v[56:59], v[146:149], v[170:173], v[56:59]
	s_waitcnt lgkmcnt(5)
	v_mfma_f32_16x16x32_bf16 v[52:55], v[138:141], v[178:181], v[52:55]
	v_mfma_f32_16x16x32_bf16 v[48:51], v[146:149], v[178:181], v[48:51]
	s_waitcnt lgkmcnt(3)
	v_mfma_f32_16x16x32_bf16 v[44:47], v[138:141], v[186:189], v[44:47]
	v_mfma_f32_16x16x32_bf16 v[40:43], v[146:149], v[186:189], v[40:43]
	s_waitcnt lgkmcnt(1)
	v_mfma_f32_16x16x32_bf16 v[36:39], v[138:141], v[194:197], v[36:39]
	v_mfma_f32_16x16x32_bf16 v[32:35], v[146:149], v[194:197], v[32:35]
	v_mfma_f32_16x16x32_bf16 v[60:63], v[142:145], v[174:177], v[60:63]
	v_mfma_f32_16x16x32_bf16 v[56:59], v[150:153], v[174:177], v[56:59]
	v_mfma_f32_16x16x32_bf16 v[52:55], v[142:145], v[182:185], v[52:55]
	v_mfma_f32_16x16x32_bf16 v[48:51], v[150:153], v[182:185], v[48:51]
	v_mfma_f32_16x16x32_bf16 v[44:47], v[142:145], v[190:193], v[44:47]
	v_mfma_f32_16x16x32_bf16 v[40:43], v[150:153], v[190:193], v[40:43]
	s_waitcnt lgkmcnt(0)
	v_mfma_f32_16x16x32_bf16 v[36:39], v[142:145], v[198:201], v[36:39]
	v_mfma_f32_16x16x32_bf16 v[32:35], v[150:153], v[198:201], v[32:35]
	v_mfma_f32_16x16x32_bf16 v[28:31], v[154:157], v[170:173], v[28:31]
	v_mfma_f32_16x16x32_bf16 v[24:27], v[162:165], v[170:173], v[24:27]
	v_mfma_f32_16x16x32_bf16 v[20:23], v[154:157], v[178:181], v[20:23]
	v_mfma_f32_16x16x32_bf16 v[16:19], v[162:165], v[178:181], v[16:19]
	v_mfma_f32_16x16x32_bf16 v[12:15], v[154:157], v[186:189], v[12:15]
	v_mfma_f32_16x16x32_bf16 v[8:11], v[162:165], v[186:189], v[8:11]
	v_mfma_f32_16x16x32_bf16 v[4:7], v[154:157], v[194:197], v[4:7]
	v_mfma_f32_16x16x32_bf16 v[0:3], v[162:165], v[194:197], v[0:3]
	v_mfma_f32_16x16x32_bf16 v[28:31], v[158:161], v[174:177], v[28:31]
	v_mfma_f32_16x16x32_bf16 v[24:27], v[166:169], v[174:177], v[24:27]
	v_mfma_f32_16x16x32_bf16 v[20:23], v[158:161], v[182:185], v[20:23]
	v_mfma_f32_16x16x32_bf16 v[16:19], v[166:169], v[182:185], v[16:19]
	v_mfma_f32_16x16x32_bf16 v[12:15], v[158:161], v[190:193], v[12:15]
	v_mfma_f32_16x16x32_bf16 v[8:11], v[166:169], v[190:193], v[8:11]
	v_mfma_f32_16x16x32_bf16 v[4:7], v[158:161], v[198:201], v[4:7]
	v_mfma_f32_16x16x32_bf16 v[0:3], v[166:169], v[198:201], v[0:3]
	s_barrier
	s_add_u32 s38, s38, 0x100
	s_addc_u32 s39, s39, 0
	s_cmp_ge_i32 s75, s2
	s_cbranch_scc0 .LBB0_923
	s_branch .LBB0_924
.Lhf_923:
	ds_read_b128 v[138:141], v133
	ds_read_b128 v[142:145], v133 offset:1024
	ds_read_b128 v[146:149], v133 offset:2048
	ds_read_b128 v[150:153], v133 offset:3072
	ds_read_b128 v[154:157], v134
	ds_read_b128 v[158:161], v134 offset:1024
	ds_read_b128 v[162:165], v134 offset:2048
	ds_read_b128 v[166:169], v134 offset:3072
	s_add_i32 s75, s75, 2
	s_add_u32 s77, s4, s38
	s_addc_u32 s78, s5, s39
	s_add_u32 s40, s77, 0x100
	s_addc_u32 s41, s78, 0
	s_add_u32 s79, s22, s38
	ds_read_b128 v[170:173], v135
	ds_read_b128 v[174:177], v135 offset:1024
	ds_read_b128 v[178:181], v135 offset:2048
	ds_read_b128 v[182:185], v135 offset:3072
	ds_read_b128 v[186:189], v135 offset:4096
	ds_read_b128 v[190:193], v135 offset:5120
	ds_read_b128 v[194:197], v135 offset:6144
	ds_read_b128 v[198:201], v135 offset:7168
	s_addc_u32 s84, s33, s39
	s_add_u32 s80, s79, 0x80
	s_addc_u32 s81, s84, 0
	s_add_u32 s85, s70, s38
	s_addc_u32 s86, s71, s39
	s_add_u32 s82, s85, 0x80
	s_mov_b32 m0, s66
	s_nop 0
	global_load_lds_dwordx4 v128, s[80:81]
	s_addc_u32 s83, s86, 0
	s_mov_b32 m0, s67
	s_nop 0
	global_load_lds_dwordx4 v128, s[82:83]
	s_waitcnt vmcnt(8)
	s_waitcnt lgkmcnt(0)
	s_barrier
	s_waitcnt lgkmcnt(7)
	v_mfma_f32_16x16x32_bf16 v[124:127], v[138:141], v[170:173], 0
	v_mfma_f32_16x16x32_bf16 v[120:123], v[146:149], v[170:173], 0
	s_waitcnt lgkmcnt(5)
	v_mfma_f32_16x16x32_bf16 v[116:119], v[138:141], v[178:181], 0
	v_mfma_f32_16x16x32_bf16 v[112:115], v[146:149], v[178:181], 0
	s_waitcnt lgkmcnt(3)
	v_mfma_f32_16x16x32_bf16 v[108:111], v[138:141], v[186:189], 0
	v_mfma_f32_16x16x32_bf16 v[104:107], v[146:149], v[186:189], 0
	s_waitcnt lgkmcnt(1)
	v_mfma_f32_16x16x32_bf16 v[100:103], v[138:141], v[194:197], 0
	v_mfma_f32_16x16x32_bf16 v[96:99], v[146:149], v[194:197], 0
	v_mfma_f32_16x16x32_bf16 v[124:127], v[142:145], v[174:177], v[124:127]
	v_mfma_f32_16x16x32_bf16 v[120:123], v[150:153], v[174:177], v[120:123]
	v_mfma_f32_16x16x32_bf16 v[116:119], v[142:145], v[182:185], v[116:119]
	v_mfma_f32_16x16x32_bf16 v[112:115], v[150:153], v[182:185], v[112:115]
	v_mfma_f32_16x16x32_bf16 v[108:111], v[142:145], v[190:193], v[108:111]
	v_mfma_f32_16x16x32_bf16 v[104:107], v[150:153], v[190:193], v[104:107]
	s_waitcnt lgkmcnt(0)
	v_mfma_f32_16x16x32_bf16 v[100:103], v[142:145], v[198:201], v[100:103]
	v_mfma_f32_16x16x32_bf16 v[96:99], v[150:153], v[198:201], v[96:99]
	v_mfma_f32_16x16x32_bf16 v[92:95], v[154:157], v[170:173], 0
	v_mfma_f32_16x16x32_bf16 v[88:91], v[162:165], v[170:173], 0
	v_mfma_f32_16x16x32_bf16 v[84:87], v[154:157], v[178:181], 0
	v_mfma_f32_16x16x32_bf16 v[80:83], v[162:165], v[178:181], 0
	v_mfma_f32_16x16x32_bf16 v[76:79], v[154:157], v[186:189], 0
	v_mfma_f32_16x16x32_bf16 v[72:75], v[162:165], v[186:189], 0
	v_mfma_f32_16x16x32_bf16 v[68:71], v[154:157], v[194:197], 0
	v_mfma_f32_16x16x32_bf16 v[64:67], v[162:165], v[194:197], 0
	v_mfma_f32_16x16x32_bf16 v[92:95], v[158:161], v[174:177], v[92:95]
	v_mfma_f32_16x16x32_bf16 v[88:91], v[166:169], v[174:177], v[88:91]
	v_mfma_f32_16x16x32_bf16 v[84:87], v[158:161], v[182:185], v[84:87]
	v_mfma_f32_16x16x32_bf16 v[80:83], v[166:169], v[182:185], v[80:83]
	v_mfma_f32_16x16x32_bf16 v[76:79], v[158:161], v[190:193], v[76:79]
	v_mfma_f32_16x16x32_bf16 v[72:75], v[166:169], v[190:193], v[72:75]
	v_mfma_f32_16x16x32_bf16 v[68:71], v[158:161], v[198:201], v[68:71]
	v_mfma_f32_16x16x32_bf16 v[64:67], v[166:169], v[198:201], v[64:67]
	s_barrier
	s_add_u32 s87, s6, s38
	s_addc_u32 s88, s7, s39
	s_add_u32 s80, s87, 0x100
	s_addc_u32 s81, s88, 0
	s_add_u32 s89, s68, s38
	s_addc_u32 s90, s69, s39
	s_add_u32 s82, s89, 0x100
	ds_read_b128 v[170:173], v135 offset:16384
	ds_read_b128 v[174:177], v135 offset:17408
	ds_read_b128 v[178:181], v135 offset:18432
	ds_read_b128 v[182:185], v135 offset:19456
	ds_read_b128 v[186:189], v135 offset:20480
	ds_read_b128 v[190:193], v135 offset:21504
	ds_read_b128 v[194:197], v135 offset:22528
	ds_read_b128 v[198:201], v135 offset:23552
	s_addc_u32 s83, s90, 0
	s_mov_b32 m0, s51
	s_nop 0
	global_load_lds_dwordx4 v129, s[80:81]
	s_add_u32 s91, s42, s38
	s_mov_b32 m0, s52
	s_nop 0
	global_load_lds_dwordx4 v129, s[82:83]
	s_addc_u32 s92, s43, s39
	s_add_u32 s80, s91, 0x100
	s_addc_u32 s81, s92, 0
	s_add_u32 s93, s44, s38
	s_addc_u32 s94, s45, s39
	s_add_u32 s82, s93, 0x100
	s_addc_u32 s83, s94, 0
	s_mov_b32 m0, s53
	s_nop 0
	global_load_lds_dwordx4 v129, s[80:81]
	s_mov_b32 m0, s56
	s_nop 0
	global_load_lds_dwordx4 v129, s[82:83]
	s_add_u32 s82, s72, s38
	s_addc_u32 s83, s74, s39
	s_add_u32 s80, s82, 0x100
	s_mov_b32 m0, s55
	s_nop 0
	global_load_lds_dwordx4 v128, s[40:41]
	s_addc_u32 s81, s83, 0
	s_mov_b32 m0, s57
	s_nop 0
	global_load_lds_dwordx4 v128, s[80:81]
	s_waitcnt vmcnt(8)
	s_waitcnt lgkmcnt(0)
	s_barrier
	s_waitcnt lgkmcnt(7)
	v_mfma_f32_16x16x32_bf16 v[60:63], v[138:141], v[170:173], 0
	v_mfma_f32_16x16x32_bf16 v[56:59], v[146:149], v[170:173], 0
	s_waitcnt lgkmcnt(5)
	v_mfma_f32_16x16x32_bf16 v[52:55], v[138:141], v[178:181], 0
	v_mfma_f32_16x16x32_bf16 v[48:51], v[146:149], v[178:181], 0
	s_waitcnt lgkmcnt(3)
	v_mfma_f32_16x16x32_bf16 v[44:47], v[138:141], v[186:189], 0
	v_mfma_f32_16x16x32_bf16 v[40:43], v[146:149], v[186:189], 0
	s_waitcnt lgkmcnt(1)
	v_mfma_f32_16x16x32_bf16 v[36:39], v[138:141], v[194:197], 0
	v_mfma_f32_16x16x32_bf16 v[32:35], v[146:149], v[194:197], 0
	v_mfma_f32_16x16x32_bf16 v[60:63], v[142:145], v[174:177], v[60:63]
	v_mfma_f32_16x16x32_bf16 v[56:59], v[150:153], v[174:177], v[56:59]
	v_mfma_f32_16x16x32_bf16 v[52:55], v[142:145], v[182:185], v[52:55]
	v_mfma_f32_16x16x32_bf16 v[48:51], v[150:153], v[182:185], v[48:51]
	v_mfma_f32_16x16x32_bf16 v[44:47], v[142:145], v[190:193], v[44:47]
	v_mfma_f32_16x16x32_bf16 v[40:43], v[150:153], v[190:193], v[40:43]
	s_waitcnt lgkmcnt(0)
	v_mfma_f32_16x16x32_bf16 v[36:39], v[142:145], v[198:201], v[36:39]
	v_mfma_f32_16x16x32_bf16 v[32:35], v[150:153], v[198:201], v[32:35]
	v_mfma_f32_16x16x32_bf16 v[28:31], v[154:157], v[170:173], 0
	v_mfma_f32_16x16x32_bf16 v[24:27], v[162:165], v[170:173], 0
	v_mfma_f32_16x16x32_bf16 v[20:23], v[154:157], v[178:181], 0
	v_mfma_f32_16x16x32_bf16 v[16:19], v[162:165], v[178:181], 0
	v_mfma_f32_16x16x32_bf16 v[12:15], v[154:157], v[186:189], 0
	v_mfma_f32_16x16x32_bf16 v[8:11], v[162:165], v[186:189], 0
	v_mfma_f32_16x16x32_bf16 v[4:7], v[154:157], v[194:197], 0
	v_mfma_f32_16x16x32_bf16 v[0:3], v[162:165], v[194:197], 0
	v_mfma_f32_16x16x32_bf16 v[28:31], v[158:161], v[174:177], v[28:31]
	v_mfma_f32_16x16x32_bf16 v[24:27], v[166:169], v[174:177], v[24:27]
	v_mfma_f32_16x16x32_bf16 v[20:23], v[158:161], v[182:185], v[20:23]
	v_mfma_f32_16x16x32_bf16 v[16:19], v[166:169], v[182:185], v[16:19]
	v_mfma_f32_16x16x32_bf16 v[12:15], v[158:161], v[190:193], v[12:15]
	v_mfma_f32_16x16x32_bf16 v[8:11], v[166:169], v[190:193], v[8:11]
	v_mfma_f32_16x16x32_bf16 v[4:7], v[158:161], v[198:201], v[4:7]
	v_mfma_f32_16x16x32_bf16 v[0:3], v[166:169], v[198:201], v[0:3]
	s_barrier
	ds_read_b128 v[138:141], v136
	ds_read_b128 v[142:145], v136 offset:1024
	ds_read_b128 v[146:149], v136 offset:2048
	ds_read_b128 v[150:153], v136 offset:3072
	ds_read_b128 v[154:157], v137
	ds_read_b128 v[158:161], v137 offset:1024
	ds_read_b128 v[162:165], v137 offset:2048
	ds_read_b128 v[166:169], v137 offset:3072
	ds_read_b128 v[170:173], v135 offset:32768
	ds_read_b128 v[174:177], v135 offset:33792
	ds_read_b128 v[178:181], v135 offset:34816
	ds_read_b128 v[182:185], v135 offset:35840
	ds_read_b128 v[186:189], v135 offset:36864
	ds_read_b128 v[190:193], v135 offset:37888
	ds_read_b128 v[194:197], v135 offset:38912
	ds_read_b128 v[198:201], v135 offset:39936
	s_add_u32 s40, s79, 0x100
	s_addc_u32 s41, s84, 0
	s_add_u32 s80, s85, 0x100
	s_mov_b32 m0, s58
	s_nop 0
	global_load_lds_dwordx4 v128, s[40:41]
	s_addc_u32 s81, s86, 0
	s_mov_b32 m0, s59
	s_nop 0
	global_load_lds_dwordx4 v128, s[80:81]
	s_waitcnt vmcnt(8)
	s_waitcnt lgkmcnt(0)
	s_barrier
	s_waitcnt lgkmcnt(7)
	v_mfma_f32_16x16x32_bf16 v[124:127], v[138:141], v[170:173], v[124:127]
	v_mfma_f32_16x16x32_bf16 v[120:123], v[146:149], v[170:173], v[120:123]
	s_waitcnt lgkmcnt(5)
	v_mfma_f32_16x16x32_bf16 v[116:119], v[138:141], v[178:181], v[116:119]
	v_mfma_f32_16x16x32_bf16 v[112:115], v[146:149], v[178:181], v[112:115]
	s_waitcnt lgkmcnt(3)
	v_mfma_f32_16x16x32_bf16 v[108:111], v[138:141], v[186:189], v[108:111]
	v_mfma_f32_16x16x32_bf16 v[104:107], v[146:149], v[186:189], v[104:107]
	s_waitcnt lgkmcnt(1)
	v_mfma_f32_16x16x32_bf16 v[100:103], v[138:141], v[194:197], v[100:103]
	v_mfma_f32_16x16x32_bf16 v[96:99], v[146:149], v[194:197], v[96:99]
	v_mfma_f32_16x16x32_bf16 v[124:127], v[142:145], v[174:177], v[124:127]
	v_mfma_f32_16x16x32_bf16 v[120:123], v[150:153], v[174:177], v[120:123]
	v_mfma_f32_16x16x32_bf16 v[116:119], v[142:145], v[182:185], v[116:119]
	v_mfma_f32_16x16x32_bf16 v[112:115], v[150:153], v[182:185], v[112:115]
	v_mfma_f32_16x16x32_bf16 v[108:111], v[142:145], v[190:193], v[108:111]
	v_mfma_f32_16x16x32_bf16 v[104:107], v[150:153], v[190:193], v[104:107]
	s_waitcnt lgkmcnt(0)
	v_mfma_f32_16x16x32_bf16 v[100:103], v[142:145], v[198:201], v[100:103]
	v_mfma_f32_16x16x32_bf16 v[96:99], v[150:153], v[198:201], v[96:99]
	v_mfma_f32_16x16x32_bf16 v[92:95], v[154:157], v[170:173], v[92:95]
	v_mfma_f32_16x16x32_bf16 v[88:91], v[162:165], v[170:173], v[88:91]
	v_mfma_f32_16x16x32_bf16 v[84:87], v[154:157], v[178:181], v[84:87]
	v_mfma_f32_16x16x32_bf16 v[80:83], v[162:165], v[178:181], v[80:83]
	v_mfma_f32_16x16x32_bf16 v[76:79], v[154:157], v[186:189], v[76:79]
	v_mfma_f32_16x16x32_bf16 v[72:75], v[162:165], v[186:189], v[72:75]
	v_mfma_f32_16x16x32_bf16 v[68:71], v[154:157], v[194:197], v[68:71]
	v_mfma_f32_16x16x32_bf16 v[64:67], v[162:165], v[194:197], v[64:67]
	v_mfma_f32_16x16x32_bf16 v[92:95], v[158:161], v[174:177], v[92:95]
	v_mfma_f32_16x16x32_bf16 v[88:91], v[166:169], v[174:177], v[88:91]
	v_mfma_f32_16x16x32_bf16 v[84:87], v[158:161], v[182:185], v[84:87]
	v_mfma_f32_16x16x32_bf16 v[80:83], v[166:169], v[182:185], v[80:83]
	v_mfma_f32_16x16x32_bf16 v[76:79], v[158:161], v[190:193], v[76:79]
	v_mfma_f32_16x16x32_bf16 v[72:75], v[166:169], v[190:193], v[72:75]
	v_mfma_f32_16x16x32_bf16 v[68:71], v[158:161], v[198:201], v[68:71]
	v_mfma_f32_16x16x32_bf16 v[64:67], v[166:169], v[198:201], v[64:67]
	s_barrier
	s_add_u32 s40, s87, 0x180
	s_addc_u32 s41, s88, 0
	ds_read_b128 v[170:173], v135 offset:49152
	ds_read_b128 v[174:177], v135 offset:50176
	ds_read_b128 v[178:181], v135 offset:51200
	ds_read_b128 v[182:185], v135 offset:52224
	ds_read_b128 v[186:189], v135 offset:53248
	ds_read_b128 v[190:193], v135 offset:54272
	ds_read_b128 v[194:197], v135 offset:55296
	ds_read_b128 v[198:201], v135 offset:56320
	s_add_u32 s80, s89, 0x180
	s_mov_b32 m0, s60
	s_nop 0
	global_load_lds_dwordx4 v129, s[40:41]
	s_addc_u32 s81, s90, 0
	s_mov_b32 m0, s61
	s_nop 0
	global_load_lds_dwordx4 v129, s[80:81]
	s_add_u32 s40, s91, 0x180
	s_addc_u32 s41, s92, 0
	s_add_u32 s80, s93, 0x180
	s_mov_b32 m0, s64
	s_nop 0
	global_load_lds_dwordx4 v129, s[40:41]
	s_addc_u32 s81, s94, 0
	s_mov_b32 m0, s65
	s_nop 0
	global_load_lds_dwordx4 v129, s[80:81]
	s_add_u32 s40, s77, 0x180
	s_addc_u32 s41, s78, 0
	s_add_u32 s78, s82, 0x180
	s_mov_b32 m0, s62
	s_nop 0
	global_load_lds_dwordx4 v128, s[40:41]
	s_addc_u32 s79, s83, 0
	s_mov_b32 m0, s63
	s_nop 0
	global_load_lds_dwordx4 v128, s[78:79]
	s_waitcnt vmcnt(8)
	s_waitcnt lgkmcnt(0)
	s_barrier
	s_waitcnt lgkmcnt(7)
	v_mfma_f32_16x16x32_bf16 v[60:63], v[138:141], v[170:173], v[60:63]
	v_mfma_f32_16x16x32_bf16 v[56:59], v[146:149], v[170:173], v[56:59]
	s_waitcnt lgkmcnt(5)
	v_mfma_f32_16x16x32_bf16 v[52:55], v[138:141], v[178:181], v[52:55]
	v_mfma_f32_16x16x32_bf16 v[48:51], v[146:149], v[178:181], v[48:51]
	s_waitcnt lgkmcnt(3)
	v_mfma_f32_16x16x32_bf16 v[44:47], v[138:141], v[186:189], v[44:47]
	v_mfma_f32_16x16x32_bf16 v[40:43], v[146:149], v[186:189], v[40:43]
	s_waitcnt lgkmcnt(1)
	v_mfma_f32_16x16x32_bf16 v[36:39], v[138:141], v[194:197], v[36:39]
	v_mfma_f32_16x16x32_bf16 v[32:35], v[146:149], v[194:197], v[32:35]
	v_mfma_f32_16x16x32_bf16 v[60:63], v[142:145], v[174:177], v[60:63]
	v_mfma_f32_16x16x32_bf16 v[56:59], v[150:153], v[174:177], v[56:59]
	v_mfma_f32_16x16x32_bf16 v[52:55], v[142:145], v[182:185], v[52:55]
	v_mfma_f32_16x16x32_bf16 v[48:51], v[150:153], v[182:185], v[48:51]
	v_mfma_f32_16x16x32_bf16 v[44:47], v[142:145], v[190:193], v[44:47]
	v_mfma_f32_16x16x32_bf16 v[40:43], v[150:153], v[190:193], v[40:43]
	s_waitcnt lgkmcnt(0)
	v_mfma_f32_16x16x32_bf16 v[36:39], v[142:145], v[198:201], v[36:39]
	v_mfma_f32_16x16x32_bf16 v[32:35], v[150:153], v[198:201], v[32:35]
	v_mfma_f32_16x16x32_bf16 v[28:31], v[154:157], v[170:173], v[28:31]
	v_mfma_f32_16x16x32_bf16 v[24:27], v[162:165], v[170:173], v[24:27]
	v_mfma_f32_16x16x32_bf16 v[20:23], v[154:157], v[178:181], v[20:23]
	v_mfma_f32_16x16x32_bf16 v[16:19], v[162:165], v[178:181], v[16:19]
	v_mfma_f32_16x16x32_bf16 v[12:15], v[154:157], v[186:189], v[12:15]
	v_mfma_f32_16x16x32_bf16 v[8:11], v[162:165], v[186:189], v[8:11]
	v_mfma_f32_16x16x32_bf16 v[4:7], v[154:157], v[194:197], v[4:7]
	v_mfma_f32_16x16x32_bf16 v[0:3], v[162:165], v[194:197], v[0:3]
	v_mfma_f32_16x16x32_bf16 v[28:31], v[158:161], v[174:177], v[28:31]
	v_mfma_f32_16x16x32_bf16 v[24:27], v[166:169], v[174:177], v[24:27]
	v_mfma_f32_16x16x32_bf16 v[20:23], v[158:161], v[182:185], v[20:23]
	v_mfma_f32_16x16x32_bf16 v[16:19], v[166:169], v[182:185], v[16:19]
	v_mfma_f32_16x16x32_bf16 v[12:15], v[158:161], v[190:193], v[12:15]
	v_mfma_f32_16x16x32_bf16 v[8:11], v[166:169], v[190:193], v[8:11]
	v_mfma_f32_16x16x32_bf16 v[4:7], v[158:161], v[198:201], v[4:7]
	v_mfma_f32_16x16x32_bf16 v[0:3], v[166:169], v[198:201], v[0:3]
	s_barrier
	s_add_u32 s38, s38, 0x100
	s_addc_u32 s39, s39, 0
	s_cmp_ge_i32 s75, s2
	s_cbranch_scc0 .LBB0_923
	s_branch .LBB0_924

.LBB0_923:
	ds_read_b128 v[138:141], v133
	ds_read_b128 v[142:145], v133 offset:1024
	ds_read_b128 v[146:149], v133 offset:2048
	ds_read_b128 v[150:153], v133 offset:3072
	ds_read_b128 v[154:157], v134
	ds_read_b128 v[158:161], v134 offset:1024
	ds_read_b128 v[162:165], v134 offset:2048
	ds_read_b128 v[166:169], v134 offset:3072
	s_add_i32 s75, s75, 2
	s_add_u32 s77, s4, s38
	s_addc_u32 s78, s5, s39
	s_add_u32 s40, s77, 0x100
	s_addc_u32 s41, s78, 0
	s_add_u32 s79, s22, s38
	ds_read_b128 v[170:173], v135
	ds_read_b128 v[174:177], v135 offset:1024
	ds_read_b128 v[178:181], v135 offset:2048
	ds_read_b128 v[182:185], v135 offset:3072
	ds_read_b128 v[186:189], v135 offset:4096
	ds_read_b128 v[190:193], v135 offset:5120
	ds_read_b128 v[194:197], v135 offset:6144
	ds_read_b128 v[198:201], v135 offset:7168
	s_addc_u32 s84, s33, s39
	s_add_u32 s80, s79, 0x80
	s_addc_u32 s81, s84, 0
	s_add_u32 s85, s70, s38
	s_addc_u32 s86, s71, s39
	s_add_u32 s82, s85, 0x80
	s_mov_b32 m0, s66
	s_nop 0
	global_load_lds_dwordx4 v128, s[80:81]
	s_addc_u32 s83, s86, 0
	s_mov_b32 m0, s67
	s_nop 0
	global_load_lds_dwordx4 v128, s[82:83]
	s_waitcnt vmcnt(8)
	s_waitcnt lgkmcnt(0)
	s_barrier
	s_waitcnt lgkmcnt(7)
	v_mfma_f32_16x16x32_bf16 v[124:127], v[138:141], v[170:173], v[124:127]
	v_mfma_f32_16x16x32_bf16 v[120:123], v[146:149], v[170:173], v[120:123]
	s_waitcnt lgkmcnt(5)
	v_mfma_f32_16x16x32_bf16 v[116:119], v[138:141], v[178:181], v[116:119]
	v_mfma_f32_16x16x32_bf16 v[112:115], v[146:149], v[178:181], v[112:115]
	s_waitcnt lgkmcnt(3)
	v_mfma_f32_16x16x32_bf16 v[108:111], v[138:141], v[186:189], v[108:111]
	v_mfma_f32_16x16x32_bf16 v[104:107], v[146:149], v[186:189], v[104:107]
	s_waitcnt lgkmcnt(1)
	v_mfma_f32_16x16x32_bf16 v[100:103], v[138:141], v[194:197], v[100:103]
	v_mfma_f32_16x16x32_bf16 v[96:99], v[146:149], v[194:197], v[96:99]
	v_mfma_f32_16x16x32_bf16 v[124:127], v[142:145], v[174:177], v[124:127]
	v_mfma_f32_16x16x32_bf16 v[120:123], v[150:153], v[174:177], v[120:123]
	v_mfma_f32_16x16x32_bf16 v[116:119], v[142:145], v[182:185], v[116:119]
	v_mfma_f32_16x16x32_bf16 v[112:115], v[150:153], v[182:185], v[112:115]
	v_mfma_f32_16x16x32_bf16 v[108:111], v[142:145], v[190:193], v[108:111]
	v_mfma_f32_16x16x32_bf16 v[104:107], v[150:153], v[190:193], v[104:107]
	s_waitcnt lgkmcnt(0)
	v_mfma_f32_16x16x32_bf16 v[100:103], v[142:145], v[198:201], v[100:103]
	v_mfma_f32_16x16x32_bf16 v[96:99], v[150:153], v[198:201], v[96:99]
	v_mfma_f32_16x16x32_bf16 v[92:95], v[154:157], v[170:173], v[92:95]
	v_mfma_f32_16x16x32_bf16 v[88:91], v[162:165], v[170:173], v[88:91]
	v_mfma_f32_16x16x32_bf16 v[84:87], v[154:157], v[178:181], v[84:87]
	v_mfma_f32_16x16x32_bf16 v[80:83], v[162:165], v[178:181], v[80:83]
	v_mfma_f32_16x16x32_bf16 v[76:79], v[154:157], v[186:189], v[76:79]
	v_mfma_f32_16x16x32_bf16 v[72:75], v[162:165], v[186:189], v[72:75]
	v_mfma_f32_16x16x32_bf16 v[68:71], v[154:157], v[194:197], v[68:71]
	v_mfma_f32_16x16x32_bf16 v[64:67], v[162:165], v[194:197], v[64:67]
	v_mfma_f32_16x16x32_bf16 v[92:95], v[158:161], v[174:177], v[92:95]
	v_mfma_f32_16x16x32_bf16 v[88:91], v[166:169], v[174:177], v[88:91]
	v_mfma_f32_16x16x32_bf16 v[84:87], v[158:161], v[182:185], v[84:87]
	v_mfma_f32_16x16x32_bf16 v[80:83], v[166:169], v[182:185], v[80:83]
	v_mfma_f32_16x16x32_bf16 v[76:79], v[158:161], v[190:193], v[76:79]
	v_mfma_f32_16x16x32_bf16 v[72:75], v[166:169], v[190:193], v[72:75]
	v_mfma_f32_16x16x32_bf16 v[68:71], v[158:161], v[198:201], v[68:71]
	v_mfma_f32_16x16x32_bf16 v[64:67], v[166:169], v[198:201], v[64:67]
	s_barrier
	s_add_u32 s87, s6, s38
	s_addc_u32 s88, s7, s39
	s_add_u32 s80, s87, 0x100
	s_addc_u32 s81, s88, 0
	s_add_u32 s89, s68, s38
	s_addc_u32 s90, s69, s39
	s_add_u32 s82, s89, 0x100
	ds_read_b128 v[170:173], v135 offset:16384
	ds_read_b128 v[174:177], v135 offset:17408
	ds_read_b128 v[178:181], v135 offset:18432
	ds_read_b128 v[182:185], v135 offset:19456
	ds_read_b128 v[186:189], v135 offset:20480
	ds_read_b128 v[190:193], v135 offset:21504
	ds_read_b128 v[194:197], v135 offset:22528
	ds_read_b128 v[198:201], v135 offset:23552
	s_addc_u32 s83, s90, 0
	s_mov_b32 m0, s51
	s_nop 0
	global_load_lds_dwordx4 v129, s[80:81]
	s_add_u32 s91, s42, s38
	s_mov_b32 m0, s52
	s_nop 0
	global_load_lds_dwordx4 v129, s[82:83]
	s_addc_u32 s92, s43, s39
	s_add_u32 s80, s91, 0x100
	s_addc_u32 s81, s92, 0
	s_add_u32 s93, s44, s38
	s_addc_u32 s94, s45, s39
	s_add_u32 s82, s93, 0x100
	s_addc_u32 s83, s94, 0
	s_mov_b32 m0, s53
	s_nop 0
	global_load_lds_dwordx4 v129, s[80:81]
	s_mov_b32 m0, s56
	s_nop 0
	global_load_lds_dwordx4 v129, s[82:83]
	s_add_u32 s82, s72, s38
	s_addc_u32 s83, s74, s39
	s_add_u32 s80, s82, 0x100
	s_mov_b32 m0, s55
	s_nop 0
	global_load_lds_dwordx4 v128, s[40:41]
	s_addc_u32 s81, s83, 0
	s_mov_b32 m0, s57
	s_nop 0
	global_load_lds_dwordx4 v128, s[80:81]
	s_waitcnt vmcnt(8)
	s_waitcnt lgkmcnt(0)
	s_barrier
	s_waitcnt lgkmcnt(7)
	v_mfma_f32_16x16x32_bf16 v[60:63], v[138:141], v[170:173], v[60:63]
	v_mfma_f32_16x16x32_bf16 v[56:59], v[146:149], v[170:173], v[56:59]
	s_waitcnt lgkmcnt(5)
	v_mfma_f32_16x16x32_bf16 v[52:55], v[138:141], v[178:181], v[52:55]
	v_mfma_f32_16x16x32_bf16 v[48:51], v[146:149], v[178:181], v[48:51]
	s_waitcnt lgkmcnt(3)
	v_mfma_f32_16x16x32_bf16 v[44:47], v[138:141], v[186:189], v[44:47]
	v_mfma_f32_16x16x32_bf16 v[40:43], v[146:149], v[186:189], v[40:43]
	s_waitcnt lgkmcnt(1)
	v_mfma_f32_16x16x32_bf16 v[36:39], v[138:141], v[194:197], v[36:39]
	v_mfma_f32_16x16x32_bf16 v[32:35], v[146:149], v[194:197], v[32:35]
	v_mfma_f32_16x16x32_bf16 v[60:63], v[142:145], v[174:177], v[60:63]
	v_mfma_f32_16x16x32_bf16 v[56:59], v[150:153], v[174:177], v[56:59]
	v_mfma_f32_16x16x32_bf16 v[52:55], v[142:145], v[182:185], v[52:55]
	v_mfma_f32_16x16x32_bf16 v[48:51], v[150:153], v[182:185], v[48:51]
	v_mfma_f32_16x16x32_bf16 v[44:47], v[142:145], v[190:193], v[44:47]
	v_mfma_f32_16x16x32_bf16 v[40:43], v[150:153], v[190:193], v[40:43]
	s_waitcnt lgkmcnt(0)
	v_mfma_f32_16x16x32_bf16 v[36:39], v[142:145], v[198:201], v[36:39]
	v_mfma_f32_16x16x32_bf16 v[32:35], v[150:153], v[198:201], v[32:35]
	v_mfma_f32_16x16x32_bf16 v[28:31], v[154:157], v[170:173], v[28:31]
	v_mfma_f32_16x16x32_bf16 v[24:27], v[162:165], v[170:173], v[24:27]
	v_mfma_f32_16x16x32_bf16 v[20:23], v[154:157], v[178:181], v[20:23]
	v_mfma_f32_16x16x32_bf16 v[16:19], v[162:165], v[178:181], v[16:19]
	v_mfma_f32_16x16x32_bf16 v[12:15], v[154:157], v[186:189], v[12:15]
	v_mfma_f32_16x16x32_bf16 v[8:11], v[162:165], v[186:189], v[8:11]
	v_mfma_f32_16x16x32_bf16 v[4:7], v[154:157], v[194:197], v[4:7]
	v_mfma_f32_16x16x32_bf16 v[0:3], v[162:165], v[194:197], v[0:3]
	v_mfma_f32_16x16x32_bf16 v[28:31], v[158:161], v[174:177], v[28:31]
	v_mfma_f32_16x16x32_bf16 v[24:27], v[166:169], v[174:177], v[24:27]
	v_mfma_f32_16x16x32_bf16 v[20:23], v[158:161], v[182:185], v[20:23]
	v_mfma_f32_16x16x32_bf16 v[16:19], v[166:169], v[182:185], v[16:19]
	v_mfma_f32_16x16x32_bf16 v[12:15], v[158:161], v[190:193], v[12:15]
	v_mfma_f32_16x16x32_bf16 v[8:11], v[166:169], v[190:193], v[8:11]
	v_mfma_f32_16x16x32_bf16 v[4:7], v[158:161], v[198:201], v[4:7]
	v_mfma_f32_16x16x32_bf16 v[0:3], v[166:169], v[198:201], v[0:3]
	s_barrier
	ds_read_b128 v[138:141], v136
	ds_read_b128 v[142:145], v136 offset:1024
	ds_read_b128 v[146:149], v136 offset:2048
	ds_read_b128 v[150:153], v136 offset:3072
	ds_read_b128 v[154:157], v137
	ds_read_b128 v[158:161], v137 offset:1024
	ds_read_b128 v[162:165], v137 offset:2048
	ds_read_b128 v[166:169], v137 offset:3072
	ds_read_b128 v[170:173], v135 offset:32768
	ds_read_b128 v[174:177], v135 offset:33792
	ds_read_b128 v[178:181], v135 offset:34816
	ds_read_b128 v[182:185], v135 offset:35840
	ds_read_b128 v[186:189], v135 offset:36864
	ds_read_b128 v[190:193], v135 offset:37888
	ds_read_b128 v[194:197], v135 offset:38912
	ds_read_b128 v[198:201], v135 offset:39936
	s_add_u32 s40, s79, 0x100
	s_addc_u32 s41, s84, 0
	s_add_u32 s80, s85, 0x100
	s_mov_b32 m0, s58
	s_nop 0
	global_load_lds_dwordx4 v128, s[40:41]
	s_addc_u32 s81, s86, 0
	s_mov_b32 m0, s59
	s_nop 0
	global_load_lds_dwordx4 v128, s[80:81]
	s_waitcnt vmcnt(8)
	s_waitcnt lgkmcnt(0)
	s_barrier
	s_waitcnt lgkmcnt(7)
	v_mfma_f32_16x16x32_bf16 v[124:127], v[138:141], v[170:173], v[124:127]
	v_mfma_f32_16x16x32_bf16 v[120:123], v[146:149], v[170:173], v[120:123]
	s_waitcnt lgkmcnt(5)
	v_mfma_f32_16x16x32_bf16 v[116:119], v[138:141], v[178:181], v[116:119]
	v_mfma_f32_16x16x32_bf16 v[112:115], v[146:149], v[178:181], v[112:115]
	s_waitcnt lgkmcnt(3)
	v_mfma_f32_16x16x32_bf16 v[108:111], v[138:141], v[186:189], v[108:111]
	v_mfma_f32_16x16x32_bf16 v[104:107], v[146:149], v[186:189], v[104:107]
	s_waitcnt lgkmcnt(1)
	v_mfma_f32_16x16x32_bf16 v[100:103], v[138:141], v[194:197], v[100:103]
	v_mfma_f32_16x16x32_bf16 v[96:99], v[146:149], v[194:197], v[96:99]
	v_mfma_f32_16x16x32_bf16 v[124:127], v[142:145], v[174:177], v[124:127]
	v_mfma_f32_16x16x32_bf16 v[120:123], v[150:153], v[174:177], v[120:123]
	v_mfma_f32_16x16x32_bf16 v[116:119], v[142:145], v[182:185], v[116:119]
	v_mfma_f32_16x16x32_bf16 v[112:115], v[150:153], v[182:185], v[112:115]
	v_mfma_f32_16x16x32_bf16 v[108:111], v[142:145], v[190:193], v[108:111]
	v_mfma_f32_16x16x32_bf16 v[104:107], v[150:153], v[190:193], v[104:107]
	s_waitcnt lgkmcnt(0)
	v_mfma_f32_16x16x32_bf16 v[100:103], v[142:145], v[198:201], v[100:103]
	v_mfma_f32_16x16x32_bf16 v[96:99], v[150:153], v[198:201], v[96:99]
	v_mfma_f32_16x16x32_bf16 v[92:95], v[154:157], v[170:173], v[92:95]
	v_mfma_f32_16x16x32_bf16 v[88:91], v[162:165], v[170:173], v[88:91]
	v_mfma_f32_16x16x32_bf16 v[84:87], v[154:157], v[178:181], v[84:87]
	v_mfma_f32_16x16x32_bf16 v[80:83], v[162:165], v[178:181], v[80:83]
	v_mfma_f32_16x16x32_bf16 v[76:79], v[154:157], v[186:189], v[76:79]
	v_mfma_f32_16x16x32_bf16 v[72:75], v[162:165], v[186:189], v[72:75]
	v_mfma_f32_16x16x32_bf16 v[68:71], v[154:157], v[194:197], v[68:71]
	v_mfma_f32_16x16x32_bf16 v[64:67], v[162:165], v[194:197], v[64:67]
	v_mfma_f32_16x16x32_bf16 v[92:95], v[158:161], v[174:177], v[92:95]
	v_mfma_f32_16x16x32_bf16 v[88:91], v[166:169], v[174:177], v[88:91]
	v_mfma_f32_16x16x32_bf16 v[84:87], v[158:161], v[182:185], v[84:87]
	v_mfma_f32_16x16x32_bf16 v[80:83], v[166:169], v[182:185], v[80:83]
	v_mfma_f32_16x16x32_bf16 v[76:79], v[158:161], v[190:193], v[76:79]
	v_mfma_f32_16x16x32_bf16 v[72:75], v[166:169], v[190:193], v[72:75]
	v_mfma_f32_16x16x32_bf16 v[68:71], v[158:161], v[198:201], v[68:71]
	v_mfma_f32_16x16x32_bf16 v[64:67], v[166:169], v[198:201], v[64:67]
	s_barrier
	s_add_u32 s40, s87, 0x180
	s_addc_u32 s41, s88, 0
	ds_read_b128 v[170:173], v135 offset:49152
	ds_read_b128 v[174:177], v135 offset:50176
	ds_read_b128 v[178:181], v135 offset:51200
	ds_read_b128 v[182:185], v135 offset:52224
	ds_read_b128 v[186:189], v135 offset:53248
	ds_read_b128 v[190:193], v135 offset:54272
	ds_read_b128 v[194:197], v135 offset:55296
	ds_read_b128 v[198:201], v135 offset:56320
	s_add_u32 s80, s89, 0x180
	s_mov_b32 m0, s60
	s_nop 0
	global_load_lds_dwordx4 v129, s[40:41]
	s_addc_u32 s81, s90, 0
	s_mov_b32 m0, s61
	s_nop 0
	global_load_lds_dwordx4 v129, s[80:81]
	s_add_u32 s40, s91, 0x180
	s_addc_u32 s41, s92, 0
	s_add_u32 s80, s93, 0x180
	s_mov_b32 m0, s64
	s_nop 0
	global_load_lds_dwordx4 v129, s[40:41]
	s_addc_u32 s81, s94, 0
	s_mov_b32 m0, s65
	s_nop 0
	global_load_lds_dwordx4 v129, s[80:81]
	s_add_u32 s40, s77, 0x180
	s_addc_u32 s41, s78, 0
	s_add_u32 s78, s82, 0x180
	s_mov_b32 m0, s62
	s_nop 0
	global_load_lds_dwordx4 v128, s[40:41]
	s_addc_u32 s79, s83, 0
	s_mov_b32 m0, s63
	s_nop 0
	global_load_lds_dwordx4 v128, s[78:79]
	s_waitcnt vmcnt(8)
	s_waitcnt lgkmcnt(0)
	s_barrier
	s_waitcnt lgkmcnt(7)
	v_mfma_f32_16x16x32_bf16 v[60:63], v[138:141], v[170:173], v[60:63]
	v_mfma_f32_16x16x32_bf16 v[56:59], v[146:149], v[170:173], v[56:59]
	s_waitcnt lgkmcnt(5)
	v_mfma_f32_16x16x32_bf16 v[52:55], v[138:141], v[178:181], v[52:55]
	v_mfma_f32_16x16x32_bf16 v[48:51], v[146:149], v[178:181], v[48:51]
	s_waitcnt lgkmcnt(3)
	v_mfma_f32_16x16x32_bf16 v[44:47], v[138:141], v[186:189], v[44:47]
	v_mfma_f32_16x16x32_bf16 v[40:43], v[146:149], v[186:189], v[40:43]
	s_waitcnt lgkmcnt(1)
	v_mfma_f32_16x16x32_bf16 v[36:39], v[138:141], v[194:197], v[36:39]
	v_mfma_f32_16x16x32_bf16 v[32:35], v[146:149], v[194:197], v[32:35]
	v_mfma_f32_16x16x32_bf16 v[60:63], v[142:145], v[174:177], v[60:63]
	v_mfma_f32_16x16x32_bf16 v[56:59], v[150:153], v[174:177], v[56:59]
	v_mfma_f32_16x16x32_bf16 v[52:55], v[142:145], v[182:185], v[52:55]
	v_mfma_f32_16x16x32_bf16 v[48:51], v[150:153], v[182:185], v[48:51]
	v_mfma_f32_16x16x32_bf16 v[44:47], v[142:145], v[190:193], v[44:47]
	v_mfma_f32_16x16x32_bf16 v[40:43], v[150:153], v[190:193], v[40:43]
	s_waitcnt lgkmcnt(0)
	v_mfma_f32_16x16x32_bf16 v[36:39], v[142:145], v[198:201], v[36:39]
	v_mfma_f32_16x16x32_bf16 v[32:35], v[150:153], v[198:201], v[32:35]
	v_mfma_f32_16x16x32_bf16 v[28:31], v[154:157], v[170:173], v[28:31]
	v_mfma_f32_16x16x32_bf16 v[24:27], v[162:165], v[170:173], v[24:27]
	v_mfma_f32_16x16x32_bf16 v[20:23], v[154:157], v[178:181], v[20:23]
	v_mfma_f32_16x16x32_bf16 v[16:19], v[162:165], v[178:181], v[16:19]
	v_mfma_f32_16x16x32_bf16 v[12:15], v[154:157], v[186:189], v[12:15]
	v_mfma_f32_16x16x32_bf16 v[8:11], v[162:165], v[186:189], v[8:11]
	v_mfma_f32_16x16x32_bf16 v[4:7], v[154:157], v[194:197], v[4:7]
	v_mfma_f32_16x16x32_bf16 v[0:3], v[162:165], v[194:197], v[0:3]
	v_mfma_f32_16x16x32_bf16 v[28:31], v[158:161], v[174:177], v[28:31]
	v_mfma_f32_16x16x32_bf16 v[24:27], v[166:169], v[174:177], v[24:27]
	v_mfma_f32_16x16x32_bf16 v[20:23], v[158:161], v[182:185], v[20:23]
	v_mfma_f32_16x16x32_bf16 v[16:19], v[166:169], v[182:185], v[16:19]
	v_mfma_f32_16x16x32_bf16 v[12:15], v[158:161], v[190:193], v[12:15]
	v_mfma_f32_16x16x32_bf16 v[8:11], v[166:169], v[190:193], v[8:11]
	v_mfma_f32_16x16x32_bf16 v[4:7], v[158:161], v[198:201], v[4:7]
	v_mfma_f32_16x16x32_bf16 v[0:3], v[166:169], v[198:201], v[0:3]
	s_barrier
	s_add_u32 s38, s38, 0x100
	s_addc_u32 s39, s39, 0
	s_cmp_ge_i32 s75, s2
	s_cbranch_scc0 .LBB0_923

.LBB0_926:
	ds_read_b128 v[138:141], v133
	ds_read_b128 v[142:145], v133 offset:1024
	ds_read_b128 v[146:149], v133 offset:2048
	ds_read_b128 v[150:153], v133 offset:3072
	ds_read_b128 v[154:157], v134
	ds_read_b128 v[158:161], v134 offset:1024
	ds_read_b128 v[162:165], v134 offset:2048
	ds_read_b128 v[166:169], v134 offset:3072
	s_ashr_i32 s45, s0, 31
	s_mov_b32 s44, s0
	s_lshl_b64 s[44:45], s[44:45], 7
	s_add_u32 s0, s4, s44
	ds_read_b128 v[170:173], v135
	ds_read_b128 v[174:177], v135 offset:1024
	ds_read_b128 v[178:181], v135 offset:2048
	ds_read_b128 v[182:185], v135 offset:3072
	ds_read_b128 v[186:189], v135 offset:4096
	ds_read_b128 v[190:193], v135 offset:5120
	ds_read_b128 v[194:197], v135 offset:6144
	ds_read_b128 v[198:201], v135 offset:7168
	s_addc_u32 s2, s5, s45
	s_add_u32 s0, s0, s36
	s_addc_u32 s2, s2, s37
	s_add_u32 s4, s0, 0xffffff80
	s_addc_u32 s5, s2, -1
	s_add_u32 s34, s4, s34
	s_mov_b32 m0, s66
	s_nop 0
	global_load_lds_dwordx4 v128, s[4:5]
	s_addc_u32 s35, s5, s35
	s_mov_b32 m0, s67
	s_nop 0
	global_load_lds_dwordx4 v128, s[34:35]
	s_waitcnt vmcnt(8)
	s_waitcnt lgkmcnt(0)
	s_barrier
	s_waitcnt lgkmcnt(7)
	v_mfma_f32_16x16x32_bf16 v[124:127], v[138:141], v[170:173], v[124:127]
	v_mfma_f32_16x16x32_bf16 v[120:123], v[146:149], v[170:173], v[120:123]
	s_waitcnt lgkmcnt(3)
	v_mfma_f32_16x16x32_bf16 v[108:111], v[138:141], v[186:189], v[108:111]
	v_mfma_f32_16x16x32_bf16 v[104:107], v[146:149], v[186:189], v[104:107]
	v_mfma_f32_16x16x32_bf16 v[124:127], v[142:145], v[174:177], v[124:127]
	v_mfma_f32_16x16x32_bf16 v[120:123], v[150:153], v[174:177], v[120:123]
	v_mfma_f32_16x16x32_bf16 v[116:119], v[138:141], v[178:181], v[116:119]
	v_mfma_f32_16x16x32_bf16 v[112:115], v[146:149], v[178:181], v[112:115]
	s_waitcnt lgkmcnt(2)
	v_mfma_f32_16x16x32_bf16 v[108:111], v[142:145], v[190:193], v[108:111]
	v_mfma_f32_16x16x32_bf16 v[104:107], v[150:153], v[190:193], v[104:107]
	s_waitcnt lgkmcnt(1)
	v_mfma_f32_16x16x32_bf16 v[100:103], v[138:141], v[194:197], v[100:103]
	v_mfma_f32_16x16x32_bf16 v[96:99], v[146:149], v[194:197], v[96:99]
	v_mfma_f32_16x16x32_bf16 v[202:205], v[142:145], v[182:185], v[116:119]
	v_mfma_f32_16x16x32_bf16 v[206:209], v[150:153], v[182:185], v[112:115]
	s_waitcnt lgkmcnt(0)
	v_mfma_f32_16x16x32_bf16 v[210:213], v[142:145], v[198:201], v[100:103]
	v_mfma_f32_16x16x32_bf16 v[214:217], v[150:153], v[198:201], v[96:99]
	v_mfma_f32_16x16x32_bf16 v[92:95], v[154:157], v[170:173], v[92:95]
	v_mfma_f32_16x16x32_bf16 v[88:91], v[162:165], v[170:173], v[88:91]
	v_mfma_f32_16x16x32_bf16 v[76:79], v[154:157], v[186:189], v[76:79]
	v_mfma_f32_16x16x32_bf16 v[72:75], v[162:165], v[186:189], v[72:75]
	v_mfma_f32_16x16x32_bf16 v[68:71], v[154:157], v[194:197], v[68:71]
	v_mfma_f32_16x16x32_bf16 v[64:67], v[162:165], v[194:197], v[64:67]
	v_mfma_f32_16x16x32_bf16 v[92:95], v[158:161], v[174:177], v[92:95]
	v_mfma_f32_16x16x32_bf16 v[88:91], v[166:169], v[174:177], v[88:91]
	v_mfma_f32_16x16x32_bf16 v[84:87], v[154:157], v[178:181], v[84:87]
	v_mfma_f32_16x16x32_bf16 v[80:83], v[162:165], v[178:181], v[80:83]
	v_mfma_f32_16x16x32_bf16 v[76:79], v[158:161], v[190:193], v[76:79]
	v_mfma_f32_16x16x32_bf16 v[72:75], v[166:169], v[190:193], v[72:75]
	v_mfma_f32_16x16x32_bf16 v[68:71], v[158:161], v[198:201], v[68:71]
	v_mfma_f32_16x16x32_bf16 v[64:67], v[166:169], v[198:201], v[64:67]
	v_mfma_f32_16x16x32_bf16 v[170:173], v[158:161], v[182:185], v[84:87]
	v_mfma_f32_16x16x32_bf16 v[174:177], v[166:169], v[182:185], v[80:83]
	s_barrier
	s_add_u32 s34, s6, s16
	ds_read_b128 v[80:83], v135 offset:16384
	ds_read_b128 v[84:87], v135 offset:17408
	ds_read_b128 v[96:99], v135 offset:18432
	ds_read_b128 v[100:103], v135 offset:19456
	ds_read_b128 v[112:115], v135 offset:20480
	ds_read_b128 v[116:119], v135 offset:21504
	ds_read_b128 v[178:181], v135 offset:22528
	ds_read_b128 v[182:185], v135 offset:23552
	s_addc_u32 s35, s7, s17
	s_mov_b32 m0, s51
	s_nop 0
	global_load_lds_dwordx4 v131, s[6:7]
	s_add_u32 s36, s6, s20
	s_mov_b32 m0, s52
	s_nop 0
	global_load_lds_dwordx4 v131, s[34:35]
	s_addc_u32 s37, s7, s21
	s_add_u32 s44, s36, s16
	s_mov_b32 m0, s53
	s_nop 0
	global_load_lds_dwordx4 v131, s[36:37]
	s_addc_u32 s45, s37, s17
	s_mov_b32 m0, s56
	s_nop 0
	global_load_lds_dwordx4 v131, s[44:45]
	s_add_u32 s4, s42, s40
	s_mov_b32 m0, s55
	s_nop 0
	global_load_lds_dwordx4 v130, s[42:43]
	s_addc_u32 s5, s43, s41
	s_mov_b32 m0, s57
	s_nop 0
	global_load_lds_dwordx4 v130, s[4:5]
	s_waitcnt vmcnt(8)
	s_waitcnt lgkmcnt(0)
	s_barrier
	s_waitcnt lgkmcnt(3)
	v_mfma_f32_16x16x32_bf16 v[44:47], v[138:141], v[112:115], v[44:47]
	v_mfma_f32_16x16x32_bf16 v[40:43], v[146:149], v[112:115], v[40:43]
	v_mfma_f32_16x16x32_bf16 v[60:63], v[138:141], v[80:83], v[60:63]
	v_mfma_f32_16x16x32_bf16 v[56:59], v[146:149], v[80:83], v[56:59]
	v_mfma_f32_16x16x32_bf16 v[52:55], v[138:141], v[96:99], v[52:55]
	v_mfma_f32_16x16x32_bf16 v[48:51], v[146:149], v[96:99], v[48:51]
	s_waitcnt lgkmcnt(2)
	v_mfma_f32_16x16x32_bf16 v[44:47], v[142:145], v[116:119], v[44:47]
	v_mfma_f32_16x16x32_bf16 v[40:43], v[150:153], v[116:119], v[40:43]
	s_waitcnt lgkmcnt(1)
	v_mfma_f32_16x16x32_bf16 v[36:39], v[138:141], v[178:181], v[36:39]
	v_mfma_f32_16x16x32_bf16 v[32:35], v[146:149], v[178:181], v[32:35]
	v_mfma_f32_16x16x32_bf16 v[186:189], v[142:145], v[84:87], v[60:63]
	v_mfma_f32_16x16x32_bf16 v[190:193], v[150:153], v[84:87], v[56:59]
	v_mfma_f32_16x16x32_bf16 v[194:197], v[142:145], v[100:103], v[52:55]
	v_mfma_f32_16x16x32_bf16 v[198:201], v[150:153], v[100:103], v[48:51]
	s_waitcnt lgkmcnt(0)
	v_mfma_f32_16x16x32_bf16 v[138:141], v[142:145], v[182:185], v[36:39]
	v_mfma_f32_16x16x32_bf16 v[142:145], v[150:153], v[182:185], v[32:35]
	v_mfma_f32_16x16x32_bf16 v[28:31], v[154:157], v[80:83], v[28:31]
	v_mfma_f32_16x16x32_bf16 v[24:27], v[162:165], v[80:83], v[24:27]
	v_mfma_f32_16x16x32_bf16 v[12:15], v[154:157], v[112:115], v[12:15]
	v_mfma_f32_16x16x32_bf16 v[8:11], v[162:165], v[112:115], v[8:11]
	v_mfma_f32_16x16x32_bf16 v[28:31], v[158:161], v[84:87], v[28:31]
	v_mfma_f32_16x16x32_bf16 v[24:27], v[166:169], v[84:87], v[24:27]
	v_mfma_f32_16x16x32_bf16 v[20:23], v[154:157], v[96:99], v[20:23]
	v_mfma_f32_16x16x32_bf16 v[16:19], v[162:165], v[96:99], v[16:19]
	v_mfma_f32_16x16x32_bf16 v[12:15], v[158:161], v[116:119], v[12:15]
	v_mfma_f32_16x16x32_bf16 v[8:11], v[166:169], v[116:119], v[8:11]
	v_mfma_f32_16x16x32_bf16 v[4:7], v[154:157], v[178:181], v[4:7]
	v_mfma_f32_16x16x32_bf16 v[0:3], v[162:165], v[178:181], v[0:3]
	v_mfma_f32_16x16x32_bf16 v[146:149], v[158:161], v[100:103], v[20:23]
	v_mfma_f32_16x16x32_bf16 v[150:153], v[166:169], v[100:103], v[16:19]
	v_mfma_f32_16x16x32_bf16 v[154:157], v[158:161], v[182:185], v[4:7]
	v_mfma_f32_16x16x32_bf16 v[158:161], v[166:169], v[182:185], v[0:3]
	s_barrier
	s_nop 1
	ds_read_b128 v[0:3], v136
	ds_read_b128 v[4:7], v136 offset:1024
	ds_read_b128 v[162:165], v136 offset:2048
	ds_read_b128 v[166:169], v136 offset:3072
	ds_read_b128 v[178:181], v137
	ds_read_b128 v[182:185], v137 offset:1024
	ds_read_b128 v[218:221], v137 offset:2048
	ds_read_b128 v[222:225], v137 offset:3072
	ds_read_b128 v[16:19], v135 offset:32768
	ds_read_b128 v[20:23], v135 offset:33792
	ds_read_b128 v[32:35], v135 offset:34816
	ds_read_b128 v[36:39], v135 offset:35840
	ds_read_b128 v[48:51], v135 offset:36864
	ds_read_b128 v[56:59], v135 offset:37888
	ds_read_b128 v[226:229], v135 offset:38912
	ds_read_b128 v[230:233], v135 offset:39936
	s_add_u32 s68, s42, s38
	s_addc_u32 s69, s43, s39
	s_add_u32 s70, s68, s40
	s_mov_b32 m0, s58
	s_nop 0
	global_load_lds_dwordx4 v130, s[68:69]
	s_addc_u32 s71, s69, s41
	s_mov_b32 m0, s59
	s_nop 0
	global_load_lds_dwordx4 v130, s[70:71]
	s_waitcnt vmcnt(8)
	s_waitcnt lgkmcnt(0)
	s_barrier
	s_waitcnt lgkmcnt(7)
	v_mfma_f32_16x16x32_bf16 v[52:55], v[0:3], v[16:19], v[124:127]
	s_waitcnt lgkmcnt(6)
	v_mfma_f32_16x16x32_bf16 v[116:119], v[4:7], v[20:23], v[52:55]
	v_mfma_f32_16x16x32_bf16 v[52:55], v[162:165], v[16:19], v[120:123]
	v_mfma_f32_16x16x32_bf16 v[112:115], v[166:169], v[20:23], v[52:55]
	s_waitcnt lgkmcnt(5)
	v_mfma_f32_16x16x32_bf16 v[52:55], v[0:3], v[32:35], v[202:205]
	s_waitcnt lgkmcnt(4)
	v_mfma_f32_16x16x32_bf16 v[100:103], v[4:7], v[36:39], v[52:55]
	v_mfma_f32_16x16x32_bf16 v[52:55], v[162:165], v[32:35], v[206:209]
	v_mfma_f32_16x16x32_bf16 v[96:99], v[166:169], v[36:39], v[52:55]
	s_waitcnt lgkmcnt(3)
	v_mfma_f32_16x16x32_bf16 v[52:55], v[0:3], v[48:51], v[108:111]
	s_waitcnt lgkmcnt(2)
	v_mfma_f32_16x16x32_bf16 v[84:87], v[4:7], v[56:59], v[52:55]
	v_mfma_f32_16x16x32_bf16 v[52:55], v[162:165], v[48:51], v[104:107]
	v_mfma_f32_16x16x32_bf16 v[80:83], v[166:169], v[56:59], v[52:55]
	s_waitcnt lgkmcnt(1)
	v_mfma_f32_16x16x32_bf16 v[52:55], v[0:3], v[226:229], v[210:213]
	s_waitcnt lgkmcnt(0)
	v_mfma_f32_16x16x32_bf16 v[60:63], v[4:7], v[230:233], v[52:55]
	v_mfma_f32_16x16x32_bf16 v[52:55], v[162:165], v[226:229], v[214:217]
	v_mfma_f32_16x16x32_bf16 v[52:55], v[166:169], v[230:233], v[52:55]
	v_mfma_f32_16x16x32_bf16 v[92:95], v[178:181], v[16:19], v[92:95]
	v_mfma_f32_16x16x32_bf16 v[16:19], v[218:221], v[16:19], v[88:91]
	v_mfma_f32_16x16x32_bf16 v[120:123], v[222:225], v[20:23], v[16:19]
	v_mfma_f32_16x16x32_bf16 v[16:19], v[178:181], v[32:35], v[170:173]
	v_mfma_f32_16x16x32_bf16 v[108:111], v[182:185], v[36:39], v[16:19]
	v_mfma_f32_16x16x32_bf16 v[16:19], v[218:221], v[32:35], v[174:177]
	v_mfma_f32_16x16x32_bf16 v[104:107], v[222:225], v[36:39], v[16:19]
	v_mfma_f32_16x16x32_bf16 v[16:19], v[178:181], v[48:51], v[76:79]
	v_mfma_f32_16x16x32_bf16 v[124:127], v[182:185], v[20:23], v[92:95]
	v_mfma_f32_16x16x32_bf16 v[92:95], v[182:185], v[56:59], v[16:19]
	v_mfma_f32_16x16x32_bf16 v[16:19], v[218:221], v[48:51], v[72:75]
	v_mfma_f32_16x16x32_bf16 v[88:91], v[222:225], v[56:59], v[16:19]
	v_mfma_f32_16x16x32_bf16 v[16:19], v[178:181], v[226:229], v[68:71]
	v_mfma_f32_16x16x32_bf16 v[76:79], v[182:185], v[230:233], v[16:19]
	v_mfma_f32_16x16x32_bf16 v[16:19], v[218:221], v[226:229], v[64:67]
	v_mfma_f32_16x16x32_bf16 v[68:71], v[222:225], v[230:233], v[16:19]
	s_barrier
	s_add_u32 s68, s6, 0x80
	s_addc_u32 s69, s7, 0
	s_add_u32 s34, s34, 0x80
	ds_read_b128 v[64:67], v135 offset:49152
	ds_read_b128 v[170:173], v135 offset:50176
	ds_read_b128 v[174:177], v135 offset:51200
	ds_read_b128 v[202:205], v135 offset:52224
	ds_read_b128 v[206:209], v135 offset:53248
	ds_read_b128 v[210:213], v135 offset:54272
	ds_read_b128 v[214:217], v135 offset:55296
	ds_read_b128 v[226:229], v135 offset:56320
	s_addc_u32 s35, s35, 0
	s_mov_b32 m0, s60
	s_nop 0
	global_load_lds_dwordx4 v131, s[68:69]
	s_nop 0
	s_mov_b32 m0, s61
	s_nop 0
	global_load_lds_dwordx4 v131, s[34:35]
	s_add_u32 s34, s36, 0x80
	s_addc_u32 s35, s37, 0
	s_add_u32 s36, s44, 0x80
	s_addc_u32 s37, s45, 0
	s_mov_b32 m0, s64
	s_nop 0
	global_load_lds_dwordx4 v131, s[34:35]
	s_add_u32 s34, s42, 0x80
	s_mov_b32 m0, s65
	s_nop 0
	global_load_lds_dwordx4 v131, s[36:37]
	s_addc_u32 s35, s43, 0
	s_add_u32 s4, s4, 0x80
	s_mov_b32 m0, s62
	s_nop 0
	global_load_lds_dwordx4 v130, s[34:35]
	s_addc_u32 s5, s5, 0
	s_mov_b32 m0, s63
	s_nop 0
	global_load_lds_dwordx4 v130, s[4:5]
	s_waitcnt vmcnt(8)
	s_waitcnt lgkmcnt(0)
	s_barrier
	s_waitcnt lgkmcnt(7)
	v_mfma_f32_16x16x32_bf16 v[16:19], v[0:3], v[64:67], v[186:189]
	s_waitcnt lgkmcnt(6)
	v_mfma_f32_16x16x32_bf16 v[56:59], v[4:7], v[170:173], v[16:19]
	v_mfma_f32_16x16x32_bf16 v[16:19], v[162:165], v[64:67], v[190:193]
	v_mfma_f32_16x16x32_bf16 v[48:51], v[166:169], v[170:173], v[16:19]
	s_waitcnt lgkmcnt(5)
	v_mfma_f32_16x16x32_bf16 v[16:19], v[0:3], v[174:177], v[194:197]
	s_waitcnt lgkmcnt(4)
	v_mfma_f32_16x16x32_bf16 v[36:39], v[4:7], v[202:205], v[16:19]
	v_mfma_f32_16x16x32_bf16 v[16:19], v[162:165], v[174:177], v[198:201]
	v_mfma_f32_16x16x32_bf16 v[32:35], v[166:169], v[202:205], v[16:19]
	s_waitcnt lgkmcnt(3)
	v_mfma_f32_16x16x32_bf16 v[16:19], v[0:3], v[206:209], v[44:47]
	s_waitcnt lgkmcnt(1)
	v_mfma_f32_16x16x32_bf16 v[0:3], v[0:3], v[214:217], v[138:141]
	v_mfma_f32_16x16x32_bf16 v[20:23], v[4:7], v[210:213], v[16:19]
	v_mfma_f32_16x16x32_bf16 v[16:19], v[162:165], v[206:209], v[40:43]
	s_waitcnt lgkmcnt(0)
	v_mfma_f32_16x16x32_bf16 v[4:7], v[4:7], v[226:229], v[0:3]
	v_mfma_f32_16x16x32_bf16 v[0:3], v[162:165], v[214:217], v[142:145]
	v_mfma_f32_16x16x32_bf16 v[16:19], v[166:169], v[210:213], v[16:19]
	v_mfma_f32_16x16x32_bf16 v[0:3], v[166:169], v[226:229], v[0:3]
	v_mfma_f32_16x16x32_bf16 v[24:27], v[218:221], v[64:67], v[24:27]
	v_mfma_f32_16x16x32_bf16 v[28:31], v[178:181], v[64:67], v[28:31]
	v_mfma_f32_16x16x32_bf16 v[64:67], v[222:225], v[170:173], v[24:27]
	v_mfma_f32_16x16x32_bf16 v[24:27], v[178:181], v[174:177], v[146:149]
	v_mfma_f32_16x16x32_bf16 v[44:47], v[182:185], v[202:205], v[24:27]
	v_mfma_f32_16x16x32_bf16 v[24:27], v[218:221], v[174:177], v[150:153]
	v_mfma_f32_16x16x32_bf16 v[8:11], v[218:221], v[206:209], v[8:11]
	v_mfma_f32_16x16x32_bf16 v[40:43], v[222:225], v[202:205], v[24:27]
	v_mfma_f32_16x16x32_bf16 v[12:15], v[178:181], v[206:209], v[12:15]
	v_mfma_f32_16x16x32_bf16 v[24:27], v[222:225], v[210:213], v[8:11]
	v_mfma_f32_16x16x32_bf16 v[8:11], v[178:181], v[214:217], v[154:157]
	v_mfma_f32_16x16x32_bf16 v[72:75], v[182:185], v[170:173], v[28:31]
	v_mfma_f32_16x16x32_bf16 v[28:31], v[182:185], v[210:213], v[12:15]
	v_mfma_f32_16x16x32_bf16 v[12:15], v[182:185], v[226:229], v[8:11]
	v_mfma_f32_16x16x32_bf16 v[8:11], v[218:221], v[214:217], v[158:161]
	v_mfma_f32_16x16x32_bf16 v[8:11], v[222:225], v[226:229], v[8:11]
	s_barrier
	s_andn2_b64 vcc, exec, s[24:25]
	s_cbranch_vccnz .LBB0_928
	s_barrier

.LBB0_935:
	s_lshl_b64 s[52:53], s[28:29], 7
	s_lshl_b64 s[36:37], s[18:19], 7
	v_and_b32_e32 v1, 15, v2
	v_or_b32_e32 v3, s3, v1
	s_add_u32 s18, s6, 0x80
	v_lshlrev_b32_e32 v5, 6, v3
	v_and_b32_e32 v6, 48, v2
	s_movk_i32 s2, 0x3c0
	s_addc_u32 s19, s7, 0
	v_and_or_b32 v5, v5, s2, v6
	s_sub_u32 s2, 0, s30
	s_subb_u32 s20, 0, s31
	s_add_u32 s2, s12, s2
	s_addc_u32 s21, s13, s20
	s_add_u32 s20, s2, 0x80
	s_addc_u32 s21, s21, 0
	s_add_i32 s65, s55, 0x18000
	s_add_i32 s66, s55, 0x1a000
	s_mov_b32 s98, 0
	s_cselect_b32 s99, 1, 0
	s_cmp_lt_u32 s76, 4
	s_cbranch_scc0 .Lsprio_11
	s_setprio 1
.Lsprio_11:
	s_cmp_lg_u32 s99, 0
	s_waitcnt vmcnt(2)
	s_barrier
	s_mov_b32 m0, s65
	s_nop 0
	global_load_lds_dwordx4 v0, s[18:19]
	s_add_u32 s18, s4, 0x80
	s_mov_b32 m0, s66
	s_nop 0
	global_load_lds_dwordx4 v0, s[20:21]
	s_addc_u32 s19, s5, 0
	s_sub_u32 s2, 0, s50
	s_subb_u32 s20, 0, s51
	s_add_u32 s2, s16, s2
	s_addc_u32 s17, s17, s20
	s_add_u32 s16, s2, 0x80
	s_addc_u32 s17, s17, 0
	s_add_i32 s67, s55, 0x8000
	s_add_i32 s73, s55, 0xa000
	s_add_u32 s12, s12, 0x80
	s_mov_b32 m0, s67
	s_nop 0
	global_load_lds_dwordx4 v160, s[18:19]
	s_addc_u32 s13, s13, 0
	s_mov_b32 m0, s73
	s_nop 0
	global_load_lds_dwordx4 v160, s[16:17]
	s_add_u32 s14, s14, 0x80
	v_ashrrev_i32_e32 v4, 6, v2
	v_lshlrev_b32_e32 v2, 2, v2
	s_addc_u32 s15, s15, 0
	s_add_i32 s78, s55, 0x1c000
	s_mov_b32 m0, s78
	s_nop 0
	global_load_lds_dwordx4 v0, s[12:13]
	v_lshl_add_u32 v7, v4, 10, s46
	v_lshlrev_b32_e32 v3, 2, v3
	v_lshl_or_b32 v1, v1, 6, v6
	v_add_lshl_u32 v4, v4, s47, 10
	v_and_b32_e32 v2, 32, v2
	s_add_i32 s79, s55, 0x1e000
	s_mov_b32 m0, s79
	s_nop 0
	global_load_lds_dwordx4 v0, s[14:15]
	v_and_b32_e32 v3, 32, v3
	v_bitop3_b32 v1, v1, v4, v2 bitop3:0xde
	s_waitcnt vmcnt(6)
	s_add_i32 s82, s55, 0xc000
	s_add_i32 s83, s55, 0xe000
	v_readlane_b32 s2, v254, 0
	v_mov_b32_e32 v161, v0
	v_bitop3_b32 v3, v5, v7, v3 bitop3:0xde
	s_cmpk_lt_u32 s2, 0x100
	v_add_u32_e32 v0, 0, v1
	s_mov_b32 s42, s25
	s_mov_b32 s43, s26
	s_cselect_b64 s[26:27], -1, 0
	v_add_u32_e32 v251, 0x10000, v0
	v_add_u32_e32 v252, 0x14000, v0
	v_add_u32_e32 v253, 0, v3
	v_mov_b32_e32 v250, 0x79797979
	v_mov_b32_e32 v248, 0x7f7f7f7f
	v_add_u32_e32 v249, 0x18000, v0
	v_add_u32_e32 v162, 0x1c000, v0
	s_mov_b32 s84, s29
	s_barrier
	s_branch .LBB0_938

.LBB0_940:
	s_cmp_lt_i32 s24, 3
	s_cbranch_scc1 .Lhz_942
	s_add_i32 s2, s24, -2
	s_add_u32 s23, s4, s52
	s_addc_u32 s25, s5, s53
	s_add_u32 s28, s6, s36
	s_addc_u32 s33, s7, s37
	s_add_u32 s34, s30, s36
	s_addc_u32 s35, s31, s37
	s_add_u32 s48, s6, s34
	s_addc_u32 s49, s7, s35
	s_add_u32 s68, s6, s30
	s_addc_u32 s69, s7, s31
	s_add_u32 s34, s50, s52
	s_addc_u32 s35, s51, s53
	s_add_u32 s70, s4, s34
	s_addc_u32 s71, s5, s35
	s_add_u32 s72, s4, s50
	s_addc_u32 s74, s5, s51
	s_mov_b32 s75, 0
	s_mov_b64 s[44:45], 0
	s_cmp_eq_u32 s98, 0
	s_cbranch_scc1 .Lhf_942
	ds_read_b128 v[24:27], v251
	ds_read_b128 v[28:31], v251 offset:1024
	ds_read_b128 v[16:19], v251 offset:2048
	ds_read_b128 v[20:23], v251 offset:3072
	ds_read_b128 v[8:11], v252
	ds_read_b128 v[12:15], v252 offset:1024
	ds_read_b128 v[0:3], v252 offset:2048
	ds_read_b128 v[4:7], v252 offset:3072
	s_add_i32 s75, s75, 2
	s_add_u32 s77, s4, s44
	s_addc_u32 s80, s5, s45
	s_add_u32 s46, s77, 0x100
	s_addc_u32 s47, s80, 0
	s_add_u32 s81, s23, s44
	ds_read_b128 v[164:167], v253
	ds_read_b128 v[168:171], v253 offset:1024
	ds_read_b128 v[172:175], v253 offset:2048
	ds_read_b128 v[176:179], v253 offset:3072
	ds_read_b128 v[180:183], v253 offset:4096
	ds_read_b128 v[184:187], v253 offset:5120
	ds_read_b128 v[188:191], v253 offset:6144
	ds_read_b128 v[192:195], v253 offset:7168
	s_addc_u32 s85, s25, s45
	s_add_u32 s88, s81, 0x80
	s_addc_u32 s89, s85, 0
	s_add_u32 s86, s70, s44
	s_addc_u32 s87, s71, s45
	s_add_u32 s90, s86, 0x80
	s_mov_b32 m0, s82
	s_nop 0
	global_load_lds_dwordx4 v160, s[88:89]
	s_addc_u32 s91, s87, 0
	s_mov_b32 m0, s83
	s_nop 0
	global_load_lds_dwordx4 v160, s[90:91]
	s_waitcnt vmcnt(24)
	s_waitcnt lgkmcnt(0)
	s_barrier
	s_waitcnt lgkmcnt(6)
	v_mfma_scale_f32_16x16x128_f8f6f4 v[156:159], v[24:31], v[164:171], 0, v248, v250 op_sel_hi:[0,0,0]
	v_mfma_scale_f32_16x16x128_f8f6f4 v[152:155], v[16:23], v[164:171], 0, v248, v250 op_sel_hi:[0,0,0]
	s_waitcnt lgkmcnt(4)
	v_mfma_scale_f32_16x16x128_f8f6f4 v[148:151], v[24:31], v[172:179], 0, v248, v250 op_sel_hi:[0,0,0]
	v_mfma_scale_f32_16x16x128_f8f6f4 v[144:147], v[16:23], v[172:179], 0, v248, v250 op_sel_hi:[0,0,0]
	s_waitcnt lgkmcnt(2)
	v_mfma_scale_f32_16x16x128_f8f6f4 v[140:143], v[24:31], v[180:187], 0, v248, v250 op_sel_hi:[0,0,0]
	v_mfma_scale_f32_16x16x128_f8f6f4 v[136:139], v[16:23], v[180:187], 0, v248, v250 op_sel_hi:[0,0,0]
	s_waitcnt lgkmcnt(0)
	v_mfma_scale_f32_16x16x128_f8f6f4 v[132:135], v[24:31], v[188:195], 0, v248, v250 op_sel_hi:[0,0,0]
	v_mfma_scale_f32_16x16x128_f8f6f4 v[128:131], v[16:23], v[188:195], 0, v248, v250 op_sel_hi:[0,0,0]
	v_mfma_scale_f32_16x16x128_f8f6f4 v[124:127], v[8:15], v[164:171], 0, v248, v250 op_sel_hi:[0,0,0]
	v_mfma_scale_f32_16x16x128_f8f6f4 v[120:123], v[0:7], v[164:171], 0, v248, v250 op_sel_hi:[0,0,0]
	v_mfma_scale_f32_16x16x128_f8f6f4 v[116:119], v[8:15], v[172:179], 0, v248, v250 op_sel_hi:[0,0,0]
	v_mfma_scale_f32_16x16x128_f8f6f4 v[112:115], v[0:7], v[172:179], 0, v248, v250 op_sel_hi:[0,0,0]
	v_mfma_scale_f32_16x16x128_f8f6f4 v[108:111], v[8:15], v[180:187], 0, v248, v250 op_sel_hi:[0,0,0]
	v_mfma_scale_f32_16x16x128_f8f6f4 v[104:107], v[0:7], v[180:187], 0, v248, v250 op_sel_hi:[0,0,0]
	v_mfma_scale_f32_16x16x128_f8f6f4 v[100:103], v[8:15], v[188:195], 0, v248, v250 op_sel_hi:[0,0,0]
	v_mfma_scale_f32_16x16x128_f8f6f4 v[96:99], v[0:7], v[188:195], 0, v248, v250 op_sel_hi:[0,0,0]
	s_barrier
	s_add_u32 s88, s6, s44
	s_addc_u32 s89, s7, s45
	s_add_u32 s92, s88, 0x100
	s_addc_u32 s93, s89, 0
	s_add_u32 s90, s68, s44
	s_addc_u32 s91, s69, s45
	s_add_u32 s94, s90, 0x100
	s_addc_u32 s95, s91, 0
	ds_read_b128 v[164:167], v253 offset:16384
	ds_read_b128 v[168:171], v253 offset:17408
	ds_read_b128 v[172:175], v253 offset:18432
	ds_read_b128 v[176:179], v253 offset:19456
	ds_read_b128 v[180:183], v253 offset:20480
	ds_read_b128 v[184:187], v253 offset:21504
	ds_read_b128 v[188:191], v253 offset:22528
	ds_read_b128 v[192:195], v253 offset:23552
	s_mov_b32 m0, s58
	s_nop 0
	global_load_lds_dwordx4 v161, s[92:93]
	s_add_u32 s92, s28, s44
	s_addc_u32 s93, s33, s45
	s_mov_b32 m0, s59
	s_nop 0
	global_load_lds_dwordx4 v161, s[94:95]
	s_add_u32 s94, s92, 0x100
	s_addc_u32 s95, s93, 0
	s_add_u32 s96, s48, s44
	s_addc_u32 s97, s49, s45
	s_add_u32 s34, s96, 0x100
	s_mov_b32 m0, s60
	s_nop 0
	global_load_lds_dwordx4 v161, s[94:95]
	s_addc_u32 s35, s97, 0
	s_mov_b32 m0, s61
	s_nop 0
	global_load_lds_dwordx4 v161, s[34:35]
	s_add_u32 s94, s72, s44
	s_addc_u32 s95, s74, s45
	s_add_u32 s34, s94, 0x100
	s_mov_b32 m0, s55
	s_nop 0
	global_load_lds_dwordx4 v160, s[46:47]
	s_addc_u32 s35, s95, 0
	s_mov_b32 m0, s62
	s_nop 0
	global_load_lds_dwordx4 v160, s[34:35]
	s_waitcnt vmcnt(24)
	s_waitcnt lgkmcnt(0)
	s_barrier
	s_waitcnt lgkmcnt(6)
	v_mfma_scale_f32_16x16x128_f8f6f4 v[92:95], v[24:31], v[164:171], 0, v248, v250 op_sel_hi:[0,0,0]
	v_mfma_scale_f32_16x16x128_f8f6f4 v[88:91], v[16:23], v[164:171], 0, v248, v250 op_sel_hi:[0,0,0]
	s_waitcnt lgkmcnt(4)
	v_mfma_scale_f32_16x16x128_f8f6f4 v[84:87], v[24:31], v[172:179], 0, v248, v250 op_sel_hi:[0,0,0]
	v_mfma_scale_f32_16x16x128_f8f6f4 v[80:83], v[16:23], v[172:179], 0, v248, v250 op_sel_hi:[0,0,0]
	s_waitcnt lgkmcnt(2)
	v_mfma_scale_f32_16x16x128_f8f6f4 v[76:79], v[24:31], v[180:187], 0, v248, v250 op_sel_hi:[0,0,0]
	v_mfma_scale_f32_16x16x128_f8f6f4 v[72:75], v[16:23], v[180:187], 0, v248, v250 op_sel_hi:[0,0,0]
	s_waitcnt lgkmcnt(0)
	v_mfma_scale_f32_16x16x128_f8f6f4 v[68:71], v[24:31], v[188:195], 0, v248, v250 op_sel_hi:[0,0,0]
	v_mfma_scale_f32_16x16x128_f8f6f4 v[64:67], v[16:23], v[188:195], 0, v248, v250 op_sel_hi:[0,0,0]
	v_mfma_scale_f32_16x16x128_f8f6f4 v[60:63], v[8:15], v[164:171], 0, v248, v250 op_sel_hi:[0,0,0]
	v_mfma_scale_f32_16x16x128_f8f6f4 v[56:59], v[0:7], v[164:171], 0, v248, v250 op_sel_hi:[0,0,0]
	v_mfma_scale_f32_16x16x128_f8f6f4 v[52:55], v[8:15], v[172:179], 0, v248, v250 op_sel_hi:[0,0,0]
	v_mfma_scale_f32_16x16x128_f8f6f4 v[48:51], v[0:7], v[172:179], 0, v248, v250 op_sel_hi:[0,0,0]
	v_mfma_scale_f32_16x16x128_f8f6f4 v[44:47], v[8:15], v[180:187], 0, v248, v250 op_sel_hi:[0,0,0]
	v_mfma_scale_f32_16x16x128_f8f6f4 v[40:43], v[0:7], v[180:187], 0, v248, v250 op_sel_hi:[0,0,0]
	v_mfma_scale_f32_16x16x128_f8f6f4 v[36:39], v[8:15], v[188:195], 0, v248, v250 op_sel_hi:[0,0,0]
	v_mfma_scale_f32_16x16x128_f8f6f4 v[32:35], v[0:7], v[188:195], 0, v248, v250 op_sel_hi:[0,0,0]
	s_barrier
	ds_read_b128 v[24:27], v249
	ds_read_b128 v[28:31], v249 offset:1024
	ds_read_b128 v[16:19], v249 offset:2048
	ds_read_b128 v[20:23], v249 offset:3072
	ds_read_b128 v[8:11], v162
	ds_read_b128 v[12:15], v162 offset:1024
	ds_read_b128 v[0:3], v162 offset:2048
	ds_read_b128 v[4:7], v162 offset:3072
	ds_read_b128 v[164:167], v253 offset:32768
	ds_read_b128 v[168:171], v253 offset:33792
	ds_read_b128 v[172:175], v253 offset:34816
	ds_read_b128 v[176:179], v253 offset:35840
	ds_read_b128 v[180:183], v253 offset:36864
	ds_read_b128 v[184:187], v253 offset:37888
	ds_read_b128 v[188:191], v253 offset:38912
	ds_read_b128 v[192:195], v253 offset:39936
	s_add_u32 s34, s81, 0x100
	s_addc_u32 s35, s85, 0
	s_add_u32 s46, s86, 0x100
	s_mov_b32 m0, s63
	s_nop 0
	global_load_lds_dwordx4 v160, s[34:35]
	s_addc_u32 s47, s87, 0
	s_mov_b32 m0, s64
	s_nop 0
	global_load_lds_dwordx4 v160, s[46:47]
	s_waitcnt vmcnt(8)
	s_waitcnt lgkmcnt(0)
	s_barrier
	s_waitcnt lgkmcnt(6)
	v_mfma_scale_f32_16x16x128_f8f6f4 v[156:159], v[24:31], v[164:171], v[156:159], v248, v250 op_sel_hi:[0,0,0]
	v_mfma_scale_f32_16x16x128_f8f6f4 v[152:155], v[16:23], v[164:171], v[152:155], v248, v250 op_sel_hi:[0,0,0]
	s_waitcnt lgkmcnt(4)
	v_mfma_scale_f32_16x16x128_f8f6f4 v[148:151], v[24:31], v[172:179], v[148:151], v248, v250 op_sel_hi:[0,0,0]
	v_mfma_scale_f32_16x16x128_f8f6f4 v[144:147], v[16:23], v[172:179], v[144:147], v248, v250 op_sel_hi:[0,0,0]
	s_waitcnt lgkmcnt(2)
	v_mfma_scale_f32_16x16x128_f8f6f4 v[140:143], v[24:31], v[180:187], v[140:143], v248, v250 op_sel_hi:[0,0,0]
	v_mfma_scale_f32_16x16x128_f8f6f4 v[136:139], v[16:23], v[180:187], v[136:139], v248, v250 op_sel_hi:[0,0,0]
	s_waitcnt lgkmcnt(0)
	v_mfma_scale_f32_16x16x128_f8f6f4 v[132:135], v[24:31], v[188:195], v[132:135], v248, v250 op_sel_hi:[0,0,0]
	v_mfma_scale_f32_16x16x128_f8f6f4 v[128:131], v[16:23], v[188:195], v[128:131], v248, v250 op_sel_hi:[0,0,0]
	v_mfma_scale_f32_16x16x128_f8f6f4 v[124:127], v[8:15], v[164:171], v[124:127], v248, v250 op_sel_hi:[0,0,0]
	v_mfma_scale_f32_16x16x128_f8f6f4 v[120:123], v[0:7], v[164:171], v[120:123], v248, v250 op_sel_hi:[0,0,0]
	v_mfma_scale_f32_16x16x128_f8f6f4 v[116:119], v[8:15], v[172:179], v[116:119], v248, v250 op_sel_hi:[0,0,0]
	v_mfma_scale_f32_16x16x128_f8f6f4 v[112:115], v[0:7], v[172:179], v[112:115], v248, v250 op_sel_hi:[0,0,0]
	v_mfma_scale_f32_16x16x128_f8f6f4 v[108:111], v[8:15], v[180:187], v[108:111], v248, v250 op_sel_hi:[0,0,0]
	v_mfma_scale_f32_16x16x128_f8f6f4 v[104:107], v[0:7], v[180:187], v[104:107], v248, v250 op_sel_hi:[0,0,0]
	v_mfma_scale_f32_16x16x128_f8f6f4 v[100:103], v[8:15], v[188:195], v[100:103], v248, v250 op_sel_hi:[0,0,0]
	v_mfma_scale_f32_16x16x128_f8f6f4 v[96:99], v[0:7], v[188:195], v[96:99], v248, v250 op_sel_hi:[0,0,0]
	s_barrier
	s_add_u32 s34, s88, 0x180
	s_addc_u32 s35, s89, 0
	ds_read_b128 v[164:167], v253 offset:49152
	ds_read_b128 v[168:171], v253 offset:50176
	ds_read_b128 v[172:175], v253 offset:51200
	ds_read_b128 v[176:179], v253 offset:52224
	ds_read_b128 v[180:183], v253 offset:53248
	ds_read_b128 v[184:187], v253 offset:54272
	ds_read_b128 v[188:191], v253 offset:55296
	ds_read_b128 v[192:195], v253 offset:56320
	s_add_u32 s46, s90, 0x180
	s_mov_b32 m0, s65
	s_nop 0
	global_load_lds_dwordx4 v161, s[34:35]
	s_addc_u32 s47, s91, 0
	s_mov_b32 m0, s66
	s_nop 0
	global_load_lds_dwordx4 v161, s[46:47]
	s_add_u32 s34, s92, 0x180
	s_addc_u32 s35, s93, 0
	s_add_u32 s46, s96, 0x180
	s_mov_b32 m0, s78
	s_nop 0
	global_load_lds_dwordx4 v161, s[34:35]
	s_addc_u32 s47, s97, 0
	s_mov_b32 m0, s79
	s_nop 0
	global_load_lds_dwordx4 v161, s[46:47]
	s_add_u32 s34, s77, 0x180
	s_addc_u32 s35, s80, 0
	s_add_u32 s46, s94, 0x180
	s_mov_b32 m0, s67
	s_nop 0
	global_load_lds_dwordx4 v160, s[34:35]
	s_addc_u32 s47, s95, 0
	s_mov_b32 m0, s73
	s_nop 0
	global_load_lds_dwordx4 v160, s[46:47]
	s_waitcnt vmcnt(8)
	s_waitcnt lgkmcnt(0)
	s_barrier
	s_waitcnt lgkmcnt(6)
	v_mfma_scale_f32_16x16x128_f8f6f4 v[92:95], v[24:31], v[164:171], v[92:95], v248, v250 op_sel_hi:[0,0,0]
	v_mfma_scale_f32_16x16x128_f8f6f4 v[88:91], v[16:23], v[164:171], v[88:91], v248, v250 op_sel_hi:[0,0,0]
	s_waitcnt lgkmcnt(4)
	v_mfma_scale_f32_16x16x128_f8f6f4 v[84:87], v[24:31], v[172:179], v[84:87], v248, v250 op_sel_hi:[0,0,0]
	v_mfma_scale_f32_16x16x128_f8f6f4 v[80:83], v[16:23], v[172:179], v[80:83], v248, v250 op_sel_hi:[0,0,0]
	s_waitcnt lgkmcnt(2)
	v_mfma_scale_f32_16x16x128_f8f6f4 v[76:79], v[24:31], v[180:187], v[76:79], v248, v250 op_sel_hi:[0,0,0]
	v_mfma_scale_f32_16x16x128_f8f6f4 v[72:75], v[16:23], v[180:187], v[72:75], v248, v250 op_sel_hi:[0,0,0]
	s_waitcnt lgkmcnt(0)
	v_mfma_scale_f32_16x16x128_f8f6f4 v[68:71], v[24:31], v[188:195], v[68:71], v248, v250 op_sel_hi:[0,0,0]
	v_mfma_scale_f32_16x16x128_f8f6f4 v[64:67], v[16:23], v[188:195], v[64:67], v248, v250 op_sel_hi:[0,0,0]
	v_mfma_scale_f32_16x16x128_f8f6f4 v[60:63], v[8:15], v[164:171], v[60:63], v248, v250 op_sel_hi:[0,0,0]
	v_mfma_scale_f32_16x16x128_f8f6f4 v[56:59], v[0:7], v[164:171], v[56:59], v248, v250 op_sel_hi:[0,0,0]
	v_mfma_scale_f32_16x16x128_f8f6f4 v[52:55], v[8:15], v[172:179], v[52:55], v248, v250 op_sel_hi:[0,0,0]
	v_mfma_scale_f32_16x16x128_f8f6f4 v[48:51], v[0:7], v[172:179], v[48:51], v248, v250 op_sel_hi:[0,0,0]
	v_mfma_scale_f32_16x16x128_f8f6f4 v[44:47], v[8:15], v[180:187], v[44:47], v248, v250 op_sel_hi:[0,0,0]
	v_mfma_scale_f32_16x16x128_f8f6f4 v[40:43], v[0:7], v[180:187], v[40:43], v248, v250 op_sel_hi:[0,0,0]
	v_mfma_scale_f32_16x16x128_f8f6f4 v[36:39], v[8:15], v[188:195], v[36:39], v248, v250 op_sel_hi:[0,0,0]
	v_mfma_scale_f32_16x16x128_f8f6f4 v[32:35], v[0:7], v[188:195], v[32:35], v248, v250 op_sel_hi:[0,0,0]
	s_barrier
	s_add_u32 s44, s44, 0x100
	s_addc_u32 s45, s45, 0
	s_cmp_ge_i32 s75, s2
	s_cbranch_scc0 .LBB0_942
	s_branch .LBB0_943
.Lhf_942:
	ds_read_b128 v[24:27], v251
	ds_read_b128 v[28:31], v251 offset:1024
	ds_read_b128 v[16:19], v251 offset:2048
	ds_read_b128 v[20:23], v251 offset:3072
	ds_read_b128 v[8:11], v252
	ds_read_b128 v[12:15], v252 offset:1024
	ds_read_b128 v[0:3], v252 offset:2048
	ds_read_b128 v[4:7], v252 offset:3072
	s_add_i32 s75, s75, 2
	s_add_u32 s77, s4, s44
	s_addc_u32 s80, s5, s45
	s_add_u32 s46, s77, 0x100
	s_addc_u32 s47, s80, 0
	s_add_u32 s81, s23, s44
	ds_read_b128 v[164:167], v253
	ds_read_b128 v[168:171], v253 offset:1024
	ds_read_b128 v[172:175], v253 offset:2048
	ds_read_b128 v[176:179], v253 offset:3072
	ds_read_b128 v[180:183], v253 offset:4096
	ds_read_b128 v[184:187], v253 offset:5120
	ds_read_b128 v[188:191], v253 offset:6144
	ds_read_b128 v[192:195], v253 offset:7168
	s_addc_u32 s85, s25, s45
	s_add_u32 s88, s81, 0x80
	s_addc_u32 s89, s85, 0
	s_add_u32 s86, s70, s44
	s_addc_u32 s87, s71, s45
	s_add_u32 s90, s86, 0x80
	s_mov_b32 m0, s82
	s_nop 0
	global_load_lds_dwordx4 v160, s[88:89]
	s_addc_u32 s91, s87, 0
	s_mov_b32 m0, s83
	s_nop 0
	global_load_lds_dwordx4 v160, s[90:91]
	s_waitcnt vmcnt(8)
	s_waitcnt lgkmcnt(0)
	s_barrier
	s_waitcnt lgkmcnt(6)
	v_mfma_scale_f32_16x16x128_f8f6f4 v[156:159], v[24:31], v[164:171], 0, v248, v250 op_sel_hi:[0,0,0]
	v_mfma_scale_f32_16x16x128_f8f6f4 v[152:155], v[16:23], v[164:171], 0, v248, v250 op_sel_hi:[0,0,0]
	s_waitcnt lgkmcnt(4)
	v_mfma_scale_f32_16x16x128_f8f6f4 v[148:151], v[24:31], v[172:179], 0, v248, v250 op_sel_hi:[0,0,0]
	v_mfma_scale_f32_16x16x128_f8f6f4 v[144:147], v[16:23], v[172:179], 0, v248, v250 op_sel_hi:[0,0,0]
	s_waitcnt lgkmcnt(2)
	v_mfma_scale_f32_16x16x128_f8f6f4 v[140:143], v[24:31], v[180:187], 0, v248, v250 op_sel_hi:[0,0,0]
	v_mfma_scale_f32_16x16x128_f8f6f4 v[136:139], v[16:23], v[180:187], 0, v248, v250 op_sel_hi:[0,0,0]
	s_waitcnt lgkmcnt(0)
	v_mfma_scale_f32_16x16x128_f8f6f4 v[132:135], v[24:31], v[188:195], 0, v248, v250 op_sel_hi:[0,0,0]
	v_mfma_scale_f32_16x16x128_f8f6f4 v[128:131], v[16:23], v[188:195], 0, v248, v250 op_sel_hi:[0,0,0]
	v_mfma_scale_f32_16x16x128_f8f6f4 v[124:127], v[8:15], v[164:171], 0, v248, v250 op_sel_hi:[0,0,0]
	v_mfma_scale_f32_16x16x128_f8f6f4 v[120:123], v[0:7], v[164:171], 0, v248, v250 op_sel_hi:[0,0,0]
	v_mfma_scale_f32_16x16x128_f8f6f4 v[116:119], v[8:15], v[172:179], 0, v248, v250 op_sel_hi:[0,0,0]
	v_mfma_scale_f32_16x16x128_f8f6f4 v[112:115], v[0:7], v[172:179], 0, v248, v250 op_sel_hi:[0,0,0]
	v_mfma_scale_f32_16x16x128_f8f6f4 v[108:111], v[8:15], v[180:187], 0, v248, v250 op_sel_hi:[0,0,0]
	v_mfma_scale_f32_16x16x128_f8f6f4 v[104:107], v[0:7], v[180:187], 0, v248, v250 op_sel_hi:[0,0,0]
	v_mfma_scale_f32_16x16x128_f8f6f4 v[100:103], v[8:15], v[188:195], 0, v248, v250 op_sel_hi:[0,0,0]
	v_mfma_scale_f32_16x16x128_f8f6f4 v[96:99], v[0:7], v[188:195], 0, v248, v250 op_sel_hi:[0,0,0]
	s_barrier
	s_add_u32 s88, s6, s44
	s_addc_u32 s89, s7, s45
	s_add_u32 s92, s88, 0x100
	s_addc_u32 s93, s89, 0
	s_add_u32 s90, s68, s44
	s_addc_u32 s91, s69, s45
	s_add_u32 s94, s90, 0x100
	s_addc_u32 s95, s91, 0
	ds_read_b128 v[164:167], v253 offset:16384
	ds_read_b128 v[168:171], v253 offset:17408
	ds_read_b128 v[172:175], v253 offset:18432
	ds_read_b128 v[176:179], v253 offset:19456
	ds_read_b128 v[180:183], v253 offset:20480
	ds_read_b128 v[184:187], v253 offset:21504
	ds_read_b128 v[188:191], v253 offset:22528
	ds_read_b128 v[192:195], v253 offset:23552
	s_mov_b32 m0, s58
	s_nop 0
	global_load_lds_dwordx4 v161, s[92:93]
	s_add_u32 s92, s28, s44
	s_addc_u32 s93, s33, s45
	s_mov_b32 m0, s59
	s_nop 0
	global_load_lds_dwordx4 v161, s[94:95]
	s_add_u32 s94, s92, 0x100
	s_addc_u32 s95, s93, 0
	s_add_u32 s96, s48, s44
	s_addc_u32 s97, s49, s45
	s_add_u32 s34, s96, 0x100
	s_mov_b32 m0, s60
	s_nop 0
	global_load_lds_dwordx4 v161, s[94:95]
	s_addc_u32 s35, s97, 0
	s_mov_b32 m0, s61
	s_nop 0
	global_load_lds_dwordx4 v161, s[34:35]
	s_add_u32 s94, s72, s44
	s_addc_u32 s95, s74, s45
	s_add_u32 s34, s94, 0x100
	s_mov_b32 m0, s55
	s_nop 0
	global_load_lds_dwordx4 v160, s[46:47]
	s_addc_u32 s35, s95, 0
	s_mov_b32 m0, s62
	s_nop 0
	global_load_lds_dwordx4 v160, s[34:35]
	s_waitcnt vmcnt(8)
	s_waitcnt lgkmcnt(0)
	s_barrier
	s_waitcnt lgkmcnt(6)
	v_mfma_scale_f32_16x16x128_f8f6f4 v[92:95], v[24:31], v[164:171], 0, v248, v250 op_sel_hi:[0,0,0]
	v_mfma_scale_f32_16x16x128_f8f6f4 v[88:91], v[16:23], v[164:171], 0, v248, v250 op_sel_hi:[0,0,0]
	s_waitcnt lgkmcnt(4)
	v_mfma_scale_f32_16x16x128_f8f6f4 v[84:87], v[24:31], v[172:179], 0, v248, v250 op_sel_hi:[0,0,0]
	v_mfma_scale_f32_16x16x128_f8f6f4 v[80:83], v[16:23], v[172:179], 0, v248, v250 op_sel_hi:[0,0,0]
	s_waitcnt lgkmcnt(2)
	v_mfma_scale_f32_16x16x128_f8f6f4 v[76:79], v[24:31], v[180:187], 0, v248, v250 op_sel_hi:[0,0,0]
	v_mfma_scale_f32_16x16x128_f8f6f4 v[72:75], v[16:23], v[180:187], 0, v248, v250 op_sel_hi:[0,0,0]
	s_waitcnt lgkmcnt(0)
	v_mfma_scale_f32_16x16x128_f8f6f4 v[68:71], v[24:31], v[188:195], 0, v248, v250 op_sel_hi:[0,0,0]
	v_mfma_scale_f32_16x16x128_f8f6f4 v[64:67], v[16:23], v[188:195], 0, v248, v250 op_sel_hi:[0,0,0]
	v_mfma_scale_f32_16x16x128_f8f6f4 v[60:63], v[8:15], v[164:171], 0, v248, v250 op_sel_hi:[0,0,0]
	v_mfma_scale_f32_16x16x128_f8f6f4 v[56:59], v[0:7], v[164:171], 0, v248, v250 op_sel_hi:[0,0,0]
	v_mfma_scale_f32_16x16x128_f8f6f4 v[52:55], v[8:15], v[172:179], 0, v248, v250 op_sel_hi:[0,0,0]
	v_mfma_scale_f32_16x16x128_f8f6f4 v[48:51], v[0:7], v[172:179], 0, v248, v250 op_sel_hi:[0,0,0]
	v_mfma_scale_f32_16x16x128_f8f6f4 v[44:47], v[8:15], v[180:187], 0, v248, v250 op_sel_hi:[0,0,0]
	v_mfma_scale_f32_16x16x128_f8f6f4 v[40:43], v[0:7], v[180:187], 0, v248, v250 op_sel_hi:[0,0,0]
	v_mfma_scale_f32_16x16x128_f8f6f4 v[36:39], v[8:15], v[188:195], 0, v248, v250 op_sel_hi:[0,0,0]
	v_mfma_scale_f32_16x16x128_f8f6f4 v[32:35], v[0:7], v[188:195], 0, v248, v250 op_sel_hi:[0,0,0]
	s_barrier
	ds_read_b128 v[24:27], v249
	ds_read_b128 v[28:31], v249 offset:1024
	ds_read_b128 v[16:19], v249 offset:2048
	ds_read_b128 v[20:23], v249 offset:3072
	ds_read_b128 v[8:11], v162
	ds_read_b128 v[12:15], v162 offset:1024
	ds_read_b128 v[0:3], v162 offset:2048
	ds_read_b128 v[4:7], v162 offset:3072
	ds_read_b128 v[164:167], v253 offset:32768
	ds_read_b128 v[168:171], v253 offset:33792
	ds_read_b128 v[172:175], v253 offset:34816
	ds_read_b128 v[176:179], v253 offset:35840
	ds_read_b128 v[180:183], v253 offset:36864
	ds_read_b128 v[184:187], v253 offset:37888
	ds_read_b128 v[188:191], v253 offset:38912
	ds_read_b128 v[192:195], v253 offset:39936
	s_add_u32 s34, s81, 0x100
	s_addc_u32 s35, s85, 0
	s_add_u32 s46, s86, 0x100
	s_mov_b32 m0, s63
	s_nop 0
	global_load_lds_dwordx4 v160, s[34:35]
	s_addc_u32 s47, s87, 0
	s_mov_b32 m0, s64
	s_nop 0
	global_load_lds_dwordx4 v160, s[46:47]
	s_waitcnt vmcnt(8)
	s_waitcnt lgkmcnt(0)
	s_barrier
	s_waitcnt lgkmcnt(6)
	v_mfma_scale_f32_16x16x128_f8f6f4 v[156:159], v[24:31], v[164:171], v[156:159], v248, v250 op_sel_hi:[0,0,0]
	v_mfma_scale_f32_16x16x128_f8f6f4 v[152:155], v[16:23], v[164:171], v[152:155], v248, v250 op_sel_hi:[0,0,0]
	s_waitcnt lgkmcnt(4)
	v_mfma_scale_f32_16x16x128_f8f6f4 v[148:151], v[24:31], v[172:179], v[148:151], v248, v250 op_sel_hi:[0,0,0]
	v_mfma_scale_f32_16x16x128_f8f6f4 v[144:147], v[16:23], v[172:179], v[144:147], v248, v250 op_sel_hi:[0,0,0]
	s_waitcnt lgkmcnt(2)
	v_mfma_scale_f32_16x16x128_f8f6f4 v[140:143], v[24:31], v[180:187], v[140:143], v248, v250 op_sel_hi:[0,0,0]
	v_mfma_scale_f32_16x16x128_f8f6f4 v[136:139], v[16:23], v[180:187], v[136:139], v248, v250 op_sel_hi:[0,0,0]
	s_waitcnt lgkmcnt(0)
	v_mfma_scale_f32_16x16x128_f8f6f4 v[132:135], v[24:31], v[188:195], v[132:135], v248, v250 op_sel_hi:[0,0,0]
	v_mfma_scale_f32_16x16x128_f8f6f4 v[128:131], v[16:23], v[188:195], v[128:131], v248, v250 op_sel_hi:[0,0,0]
	v_mfma_scale_f32_16x16x128_f8f6f4 v[124:127], v[8:15], v[164:171], v[124:127], v248, v250 op_sel_hi:[0,0,0]
	v_mfma_scale_f32_16x16x128_f8f6f4 v[120:123], v[0:7], v[164:171], v[120:123], v248, v250 op_sel_hi:[0,0,0]
	v_mfma_scale_f32_16x16x128_f8f6f4 v[116:119], v[8:15], v[172:179], v[116:119], v248, v250 op_sel_hi:[0,0,0]
	v_mfma_scale_f32_16x16x128_f8f6f4 v[112:115], v[0:7], v[172:179], v[112:115], v248, v250 op_sel_hi:[0,0,0]
	v_mfma_scale_f32_16x16x128_f8f6f4 v[108:111], v[8:15], v[180:187], v[108:111], v248, v250 op_sel_hi:[0,0,0]
	v_mfma_scale_f32_16x16x128_f8f6f4 v[104:107], v[0:7], v[180:187], v[104:107], v248, v250 op_sel_hi:[0,0,0]
	v_mfma_scale_f32_16x16x128_f8f6f4 v[100:103], v[8:15], v[188:195], v[100:103], v248, v250 op_sel_hi:[0,0,0]
	v_mfma_scale_f32_16x16x128_f8f6f4 v[96:99], v[0:7], v[188:195], v[96:99], v248, v250 op_sel_hi:[0,0,0]
	s_barrier
	s_add_u32 s34, s88, 0x180
	s_addc_u32 s35, s89, 0
	ds_read_b128 v[164:167], v253 offset:49152
	ds_read_b128 v[168:171], v253 offset:50176
	ds_read_b128 v[172:175], v253 offset:51200
	ds_read_b128 v[176:179], v253 offset:52224
	ds_read_b128 v[180:183], v253 offset:53248
	ds_read_b128 v[184:187], v253 offset:54272
	ds_read_b128 v[188:191], v253 offset:55296
	ds_read_b128 v[192:195], v253 offset:56320
	s_add_u32 s46, s90, 0x180
	s_mov_b32 m0, s65
	s_nop 0
	global_load_lds_dwordx4 v161, s[34:35]
	s_addc_u32 s47, s91, 0
	s_mov_b32 m0, s66
	s_nop 0
	global_load_lds_dwordx4 v161, s[46:47]
	s_add_u32 s34, s92, 0x180
	s_addc_u32 s35, s93, 0
	s_add_u32 s46, s96, 0x180
	s_mov_b32 m0, s78
	s_nop 0
	global_load_lds_dwordx4 v161, s[34:35]
	s_addc_u32 s47, s97, 0
	s_mov_b32 m0, s79
	s_nop 0
	global_load_lds_dwordx4 v161, s[46:47]
	s_add_u32 s34, s77, 0x180
	s_addc_u32 s35, s80, 0
	s_add_u32 s46, s94, 0x180
	s_mov_b32 m0, s67
	s_nop 0
	global_load_lds_dwordx4 v160, s[34:35]
	s_addc_u32 s47, s95, 0
	s_mov_b32 m0, s73
	s_nop 0
	global_load_lds_dwordx4 v160, s[46:47]
	s_waitcnt vmcnt(8)
	s_waitcnt lgkmcnt(0)
	s_barrier
	s_waitcnt lgkmcnt(6)
	v_mfma_scale_f32_16x16x128_f8f6f4 v[92:95], v[24:31], v[164:171], v[92:95], v248, v250 op_sel_hi:[0,0,0]
	v_mfma_scale_f32_16x16x128_f8f6f4 v[88:91], v[16:23], v[164:171], v[88:91], v248, v250 op_sel_hi:[0,0,0]
	s_waitcnt lgkmcnt(4)
	v_mfma_scale_f32_16x16x128_f8f6f4 v[84:87], v[24:31], v[172:179], v[84:87], v248, v250 op_sel_hi:[0,0,0]
	v_mfma_scale_f32_16x16x128_f8f6f4 v[80:83], v[16:23], v[172:179], v[80:83], v248, v250 op_sel_hi:[0,0,0]
	s_waitcnt lgkmcnt(2)
	v_mfma_scale_f32_16x16x128_f8f6f4 v[76:79], v[24:31], v[180:187], v[76:79], v248, v250 op_sel_hi:[0,0,0]
	v_mfma_scale_f32_16x16x128_f8f6f4 v[72:75], v[16:23], v[180:187], v[72:75], v248, v250 op_sel_hi:[0,0,0]
	s_waitcnt lgkmcnt(0)
	v_mfma_scale_f32_16x16x128_f8f6f4 v[68:71], v[24:31], v[188:195], v[68:71], v248, v250 op_sel_hi:[0,0,0]
	v_mfma_scale_f32_16x16x128_f8f6f4 v[64:67], v[16:23], v[188:195], v[64:67], v248, v250 op_sel_hi:[0,0,0]
	v_mfma_scale_f32_16x16x128_f8f6f4 v[60:63], v[8:15], v[164:171], v[60:63], v248, v250 op_sel_hi:[0,0,0]
	v_mfma_scale_f32_16x16x128_f8f6f4 v[56:59], v[0:7], v[164:171], v[56:59], v248, v250 op_sel_hi:[0,0,0]
	v_mfma_scale_f32_16x16x128_f8f6f4 v[52:55], v[8:15], v[172:179], v[52:55], v248, v250 op_sel_hi:[0,0,0]
	v_mfma_scale_f32_16x16x128_f8f6f4 v[48:51], v[0:7], v[172:179], v[48:51], v248, v250 op_sel_hi:[0,0,0]
	v_mfma_scale_f32_16x16x128_f8f6f4 v[44:47], v[8:15], v[180:187], v[44:47], v248, v250 op_sel_hi:[0,0,0]
	v_mfma_scale_f32_16x16x128_f8f6f4 v[40:43], v[0:7], v[180:187], v[40:43], v248, v250 op_sel_hi:[0,0,0]
	v_mfma_scale_f32_16x16x128_f8f6f4 v[36:39], v[8:15], v[188:195], v[36:39], v248, v250 op_sel_hi:[0,0,0]
	v_mfma_scale_f32_16x16x128_f8f6f4 v[32:35], v[0:7], v[188:195], v[32:35], v248, v250 op_sel_hi:[0,0,0]
	s_barrier
	s_add_u32 s44, s44, 0x100
	s_addc_u32 s45, s45, 0
	s_cmp_ge_i32 s75, s2
	s_cbranch_scc0 .LBB0_942
	s_branch .LBB0_943

.LBB0_942:
	ds_read_b128 v[24:27], v251
	ds_read_b128 v[28:31], v251 offset:1024
	ds_read_b128 v[16:19], v251 offset:2048
	ds_read_b128 v[20:23], v251 offset:3072
	ds_read_b128 v[8:11], v252
	ds_read_b128 v[12:15], v252 offset:1024
	ds_read_b128 v[0:3], v252 offset:2048
	ds_read_b128 v[4:7], v252 offset:3072
	s_add_i32 s75, s75, 2
	s_add_u32 s77, s4, s44
	s_addc_u32 s80, s5, s45
	s_add_u32 s46, s77, 0x100
	s_addc_u32 s47, s80, 0
	s_add_u32 s81, s23, s44
	ds_read_b128 v[164:167], v253
	ds_read_b128 v[168:171], v253 offset:1024
	ds_read_b128 v[172:175], v253 offset:2048
	ds_read_b128 v[176:179], v253 offset:3072
	ds_read_b128 v[180:183], v253 offset:4096
	ds_read_b128 v[184:187], v253 offset:5120
	ds_read_b128 v[188:191], v253 offset:6144
	ds_read_b128 v[192:195], v253 offset:7168
	s_addc_u32 s85, s25, s45
	s_add_u32 s88, s81, 0x80
	s_addc_u32 s89, s85, 0
	s_add_u32 s86, s70, s44
	s_addc_u32 s87, s71, s45
	s_add_u32 s90, s86, 0x80
	s_mov_b32 m0, s82
	s_nop 0
	global_load_lds_dwordx4 v160, s[88:89]
	s_addc_u32 s91, s87, 0
	s_mov_b32 m0, s83
	s_nop 0
	global_load_lds_dwordx4 v160, s[90:91]
	s_waitcnt vmcnt(8)
	s_waitcnt lgkmcnt(0)
	s_barrier
	s_waitcnt lgkmcnt(6)
	v_mfma_scale_f32_16x16x128_f8f6f4 v[156:159], v[24:31], v[164:171], v[156:159], v248, v250 op_sel_hi:[0,0,0]
	v_mfma_scale_f32_16x16x128_f8f6f4 v[152:155], v[16:23], v[164:171], v[152:155], v248, v250 op_sel_hi:[0,0,0]
	s_waitcnt lgkmcnt(4)
	v_mfma_scale_f32_16x16x128_f8f6f4 v[148:151], v[24:31], v[172:179], v[148:151], v248, v250 op_sel_hi:[0,0,0]
	v_mfma_scale_f32_16x16x128_f8f6f4 v[144:147], v[16:23], v[172:179], v[144:147], v248, v250 op_sel_hi:[0,0,0]
	s_waitcnt lgkmcnt(2)
	v_mfma_scale_f32_16x16x128_f8f6f4 v[140:143], v[24:31], v[180:187], v[140:143], v248, v250 op_sel_hi:[0,0,0]
	v_mfma_scale_f32_16x16x128_f8f6f4 v[136:139], v[16:23], v[180:187], v[136:139], v248, v250 op_sel_hi:[0,0,0]
	s_waitcnt lgkmcnt(0)
	v_mfma_scale_f32_16x16x128_f8f6f4 v[132:135], v[24:31], v[188:195], v[132:135], v248, v250 op_sel_hi:[0,0,0]
	v_mfma_scale_f32_16x16x128_f8f6f4 v[128:131], v[16:23], v[188:195], v[128:131], v248, v250 op_sel_hi:[0,0,0]
	v_mfma_scale_f32_16x16x128_f8f6f4 v[124:127], v[8:15], v[164:171], v[124:127], v248, v250 op_sel_hi:[0,0,0]
	v_mfma_scale_f32_16x16x128_f8f6f4 v[120:123], v[0:7], v[164:171], v[120:123], v248, v250 op_sel_hi:[0,0,0]
	v_mfma_scale_f32_16x16x128_f8f6f4 v[116:119], v[8:15], v[172:179], v[116:119], v248, v250 op_sel_hi:[0,0,0]
	v_mfma_scale_f32_16x16x128_f8f6f4 v[112:115], v[0:7], v[172:179], v[112:115], v248, v250 op_sel_hi:[0,0,0]
	v_mfma_scale_f32_16x16x128_f8f6f4 v[108:111], v[8:15], v[180:187], v[108:111], v248, v250 op_sel_hi:[0,0,0]
	v_mfma_scale_f32_16x16x128_f8f6f4 v[104:107], v[0:7], v[180:187], v[104:107], v248, v250 op_sel_hi:[0,0,0]
	v_mfma_scale_f32_16x16x128_f8f6f4 v[100:103], v[8:15], v[188:195], v[100:103], v248, v250 op_sel_hi:[0,0,0]
	v_mfma_scale_f32_16x16x128_f8f6f4 v[96:99], v[0:7], v[188:195], v[96:99], v248, v250 op_sel_hi:[0,0,0]
	s_barrier
	s_add_u32 s88, s6, s44
	s_addc_u32 s89, s7, s45
	s_add_u32 s92, s88, 0x100
	s_addc_u32 s93, s89, 0
	s_add_u32 s90, s68, s44
	s_addc_u32 s91, s69, s45
	s_add_u32 s94, s90, 0x100
	s_addc_u32 s95, s91, 0
	ds_read_b128 v[164:167], v253 offset:16384
	ds_read_b128 v[168:171], v253 offset:17408
	ds_read_b128 v[172:175], v253 offset:18432
	ds_read_b128 v[176:179], v253 offset:19456
	ds_read_b128 v[180:183], v253 offset:20480
	ds_read_b128 v[184:187], v253 offset:21504
	ds_read_b128 v[188:191], v253 offset:22528
	ds_read_b128 v[192:195], v253 offset:23552
	s_mov_b32 m0, s58
	s_nop 0
	global_load_lds_dwordx4 v161, s[92:93]
	s_add_u32 s92, s28, s44
	s_addc_u32 s93, s33, s45
	s_mov_b32 m0, s59
	s_nop 0
	global_load_lds_dwordx4 v161, s[94:95]
	s_add_u32 s94, s92, 0x100
	s_addc_u32 s95, s93, 0
	s_add_u32 s96, s48, s44
	s_addc_u32 s97, s49, s45
	s_add_u32 s34, s96, 0x100
	s_mov_b32 m0, s60
	s_nop 0
	global_load_lds_dwordx4 v161, s[94:95]
	s_addc_u32 s35, s97, 0
	s_mov_b32 m0, s61
	s_nop 0
	global_load_lds_dwordx4 v161, s[34:35]
	s_add_u32 s94, s72, s44
	s_addc_u32 s95, s74, s45
	s_add_u32 s34, s94, 0x100
	s_mov_b32 m0, s55
	s_nop 0
	global_load_lds_dwordx4 v160, s[46:47]
	s_addc_u32 s35, s95, 0
	s_mov_b32 m0, s62
	s_nop 0
	global_load_lds_dwordx4 v160, s[34:35]
	s_waitcnt vmcnt(8)
	s_waitcnt lgkmcnt(0)
	s_barrier
	s_waitcnt lgkmcnt(6)
	v_mfma_scale_f32_16x16x128_f8f6f4 v[92:95], v[24:31], v[164:171], v[92:95], v248, v250 op_sel_hi:[0,0,0]
	v_mfma_scale_f32_16x16x128_f8f6f4 v[88:91], v[16:23], v[164:171], v[88:91], v248, v250 op_sel_hi:[0,0,0]
	s_waitcnt lgkmcnt(4)
	v_mfma_scale_f32_16x16x128_f8f6f4 v[84:87], v[24:31], v[172:179], v[84:87], v248, v250 op_sel_hi:[0,0,0]
	v_mfma_scale_f32_16x16x128_f8f6f4 v[80:83], v[16:23], v[172:179], v[80:83], v248, v250 op_sel_hi:[0,0,0]
	s_waitcnt lgkmcnt(2)
	v_mfma_scale_f32_16x16x128_f8f6f4 v[76:79], v[24:31], v[180:187], v[76:79], v248, v250 op_sel_hi:[0,0,0]
	v_mfma_scale_f32_16x16x128_f8f6f4 v[72:75], v[16:23], v[180:187], v[72:75], v248, v250 op_sel_hi:[0,0,0]
	s_waitcnt lgkmcnt(0)
	v_mfma_scale_f32_16x16x128_f8f6f4 v[68:71], v[24:31], v[188:195], v[68:71], v248, v250 op_sel_hi:[0,0,0]
	v_mfma_scale_f32_16x16x128_f8f6f4 v[64:67], v[16:23], v[188:195], v[64:67], v248, v250 op_sel_hi:[0,0,0]
	v_mfma_scale_f32_16x16x128_f8f6f4 v[60:63], v[8:15], v[164:171], v[60:63], v248, v250 op_sel_hi:[0,0,0]
	v_mfma_scale_f32_16x16x128_f8f6f4 v[56:59], v[0:7], v[164:171], v[56:59], v248, v250 op_sel_hi:[0,0,0]
	v_mfma_scale_f32_16x16x128_f8f6f4 v[52:55], v[8:15], v[172:179], v[52:55], v248, v250 op_sel_hi:[0,0,0]
	v_mfma_scale_f32_16x16x128_f8f6f4 v[48:51], v[0:7], v[172:179], v[48:51], v248, v250 op_sel_hi:[0,0,0]
	v_mfma_scale_f32_16x16x128_f8f6f4 v[44:47], v[8:15], v[180:187], v[44:47], v248, v250 op_sel_hi:[0,0,0]
	v_mfma_scale_f32_16x16x128_f8f6f4 v[40:43], v[0:7], v[180:187], v[40:43], v248, v250 op_sel_hi:[0,0,0]
	v_mfma_scale_f32_16x16x128_f8f6f4 v[36:39], v[8:15], v[188:195], v[36:39], v248, v250 op_sel_hi:[0,0,0]
	v_mfma_scale_f32_16x16x128_f8f6f4 v[32:35], v[0:7], v[188:195], v[32:35], v248, v250 op_sel_hi:[0,0,0]
	s_barrier
	ds_read_b128 v[24:27], v249
	ds_read_b128 v[28:31], v249 offset:1024
	ds_read_b128 v[16:19], v249 offset:2048
	ds_read_b128 v[20:23], v249 offset:3072
	ds_read_b128 v[8:11], v162
	ds_read_b128 v[12:15], v162 offset:1024
	ds_read_b128 v[0:3], v162 offset:2048
	ds_read_b128 v[4:7], v162 offset:3072
	ds_read_b128 v[164:167], v253 offset:32768
	ds_read_b128 v[168:171], v253 offset:33792
	ds_read_b128 v[172:175], v253 offset:34816
	ds_read_b128 v[176:179], v253 offset:35840
	ds_read_b128 v[180:183], v253 offset:36864
	ds_read_b128 v[184:187], v253 offset:37888
	ds_read_b128 v[188:191], v253 offset:38912
	ds_read_b128 v[192:195], v253 offset:39936
	s_add_u32 s34, s81, 0x100
	s_addc_u32 s35, s85, 0
	s_add_u32 s46, s86, 0x100
	s_mov_b32 m0, s63
	s_nop 0
	global_load_lds_dwordx4 v160, s[34:35]
	s_addc_u32 s47, s87, 0
	s_mov_b32 m0, s64
	s_nop 0
	global_load_lds_dwordx4 v160, s[46:47]
	s_waitcnt vmcnt(8)
	s_waitcnt lgkmcnt(0)
	s_barrier
	s_waitcnt lgkmcnt(6)
	v_mfma_scale_f32_16x16x128_f8f6f4 v[156:159], v[24:31], v[164:171], v[156:159], v248, v250 op_sel_hi:[0,0,0]
	v_mfma_scale_f32_16x16x128_f8f6f4 v[152:155], v[16:23], v[164:171], v[152:155], v248, v250 op_sel_hi:[0,0,0]
	s_waitcnt lgkmcnt(4)
	v_mfma_scale_f32_16x16x128_f8f6f4 v[148:151], v[24:31], v[172:179], v[148:151], v248, v250 op_sel_hi:[0,0,0]
	v_mfma_scale_f32_16x16x128_f8f6f4 v[144:147], v[16:23], v[172:179], v[144:147], v248, v250 op_sel_hi:[0,0,0]
	s_waitcnt lgkmcnt(2)
	v_mfma_scale_f32_16x16x128_f8f6f4 v[140:143], v[24:31], v[180:187], v[140:143], v248, v250 op_sel_hi:[0,0,0]
	v_mfma_scale_f32_16x16x128_f8f6f4 v[136:139], v[16:23], v[180:187], v[136:139], v248, v250 op_sel_hi:[0,0,0]
	s_waitcnt lgkmcnt(0)
	v_mfma_scale_f32_16x16x128_f8f6f4 v[132:135], v[24:31], v[188:195], v[132:135], v248, v250 op_sel_hi:[0,0,0]
	v_mfma_scale_f32_16x16x128_f8f6f4 v[128:131], v[16:23], v[188:195], v[128:131], v248, v250 op_sel_hi:[0,0,0]
	v_mfma_scale_f32_16x16x128_f8f6f4 v[124:127], v[8:15], v[164:171], v[124:127], v248, v250 op_sel_hi:[0,0,0]
	v_mfma_scale_f32_16x16x128_f8f6f4 v[120:123], v[0:7], v[164:171], v[120:123], v248, v250 op_sel_hi:[0,0,0]
	v_mfma_scale_f32_16x16x128_f8f6f4 v[116:119], v[8:15], v[172:179], v[116:119], v248, v250 op_sel_hi:[0,0,0]
	v_mfma_scale_f32_16x16x128_f8f6f4 v[112:115], v[0:7], v[172:179], v[112:115], v248, v250 op_sel_hi:[0,0,0]
	v_mfma_scale_f32_16x16x128_f8f6f4 v[108:111], v[8:15], v[180:187], v[108:111], v248, v250 op_sel_hi:[0,0,0]
	v_mfma_scale_f32_16x16x128_f8f6f4 v[104:107], v[0:7], v[180:187], v[104:107], v248, v250 op_sel_hi:[0,0,0]
	v_mfma_scale_f32_16x16x128_f8f6f4 v[100:103], v[8:15], v[188:195], v[100:103], v248, v250 op_sel_hi:[0,0,0]
	v_mfma_scale_f32_16x16x128_f8f6f4 v[96:99], v[0:7], v[188:195], v[96:99], v248, v250 op_sel_hi:[0,0,0]
	s_barrier
	s_add_u32 s34, s88, 0x180
	s_addc_u32 s35, s89, 0
	ds_read_b128 v[164:167], v253 offset:49152
	ds_read_b128 v[168:171], v253 offset:50176
	ds_read_b128 v[172:175], v253 offset:51200
	ds_read_b128 v[176:179], v253 offset:52224
	ds_read_b128 v[180:183], v253 offset:53248
	ds_read_b128 v[184:187], v253 offset:54272
	ds_read_b128 v[188:191], v253 offset:55296
	ds_read_b128 v[192:195], v253 offset:56320
	s_add_u32 s46, s90, 0x180
	s_mov_b32 m0, s65
	s_nop 0
	global_load_lds_dwordx4 v161, s[34:35]
	s_addc_u32 s47, s91, 0
	s_mov_b32 m0, s66
	s_nop 0
	global_load_lds_dwordx4 v161, s[46:47]
	s_add_u32 s34, s92, 0x180
	s_addc_u32 s35, s93, 0
	s_add_u32 s46, s96, 0x180
	s_mov_b32 m0, s78
	s_nop 0
	global_load_lds_dwordx4 v161, s[34:35]
	s_addc_u32 s47, s97, 0
	s_mov_b32 m0, s79
	s_nop 0
	global_load_lds_dwordx4 v161, s[46:47]
	s_add_u32 s34, s77, 0x180
	s_addc_u32 s35, s80, 0
	s_add_u32 s46, s94, 0x180
	s_mov_b32 m0, s67
	s_nop 0
	global_load_lds_dwordx4 v160, s[34:35]
	s_addc_u32 s47, s95, 0
	s_mov_b32 m0, s73
	s_nop 0
	global_load_lds_dwordx4 v160, s[46:47]
	s_waitcnt vmcnt(8)
	s_waitcnt lgkmcnt(0)
	s_barrier
	s_waitcnt lgkmcnt(6)
	v_mfma_scale_f32_16x16x128_f8f6f4 v[92:95], v[24:31], v[164:171], v[92:95], v248, v250 op_sel_hi:[0,0,0]
	v_mfma_scale_f32_16x16x128_f8f6f4 v[88:91], v[16:23], v[164:171], v[88:91], v248, v250 op_sel_hi:[0,0,0]
	s_waitcnt lgkmcnt(4)
	v_mfma_scale_f32_16x16x128_f8f6f4 v[84:87], v[24:31], v[172:179], v[84:87], v248, v250 op_sel_hi:[0,0,0]
	v_mfma_scale_f32_16x16x128_f8f6f4 v[80:83], v[16:23], v[172:179], v[80:83], v248, v250 op_sel_hi:[0,0,0]
	s_waitcnt lgkmcnt(2)
	v_mfma_scale_f32_16x16x128_f8f6f4 v[76:79], v[24:31], v[180:187], v[76:79], v248, v250 op_sel_hi:[0,0,0]
	v_mfma_scale_f32_16x16x128_f8f6f4 v[72:75], v[16:23], v[180:187], v[72:75], v248, v250 op_sel_hi:[0,0,0]
	s_waitcnt lgkmcnt(0)
	v_mfma_scale_f32_16x16x128_f8f6f4 v[68:71], v[24:31], v[188:195], v[68:71], v248, v250 op_sel_hi:[0,0,0]
	v_mfma_scale_f32_16x16x128_f8f6f4 v[64:67], v[16:23], v[188:195], v[64:67], v248, v250 op_sel_hi:[0,0,0]
	v_mfma_scale_f32_16x16x128_f8f6f4 v[60:63], v[8:15], v[164:171], v[60:63], v248, v250 op_sel_hi:[0,0,0]
	v_mfma_scale_f32_16x16x128_f8f6f4 v[56:59], v[0:7], v[164:171], v[56:59], v248, v250 op_sel_hi:[0,0,0]
	v_mfma_scale_f32_16x16x128_f8f6f4 v[52:55], v[8:15], v[172:179], v[52:55], v248, v250 op_sel_hi:[0,0,0]
	v_mfma_scale_f32_16x16x128_f8f6f4 v[48:51], v[0:7], v[172:179], v[48:51], v248, v250 op_sel_hi:[0,0,0]
	v_mfma_scale_f32_16x16x128_f8f6f4 v[44:47], v[8:15], v[180:187], v[44:47], v248, v250 op_sel_hi:[0,0,0]
	v_mfma_scale_f32_16x16x128_f8f6f4 v[40:43], v[0:7], v[180:187], v[40:43], v248, v250 op_sel_hi:[0,0,0]
	v_mfma_scale_f32_16x16x128_f8f6f4 v[36:39], v[8:15], v[188:195], v[36:39], v248, v250 op_sel_hi:[0,0,0]
	v_mfma_scale_f32_16x16x128_f8f6f4 v[32:35], v[0:7], v[188:195], v[32:35], v248, v250 op_sel_hi:[0,0,0]
	s_barrier
	s_add_u32 s44, s44, 0x100
	s_addc_u32 s45, s45, 0
	s_cmp_ge_i32 s75, s2
	s_cbranch_scc0 .LBB0_942

.LBB0_945:
	ds_read_b128 v[24:27], v251
	ds_read_b128 v[28:31], v251 offset:1024
	ds_read_b128 v[16:19], v251 offset:2048
	ds_read_b128 v[20:23], v251 offset:3072
	ds_read_b128 v[8:11], v252
	ds_read_b128 v[12:15], v252 offset:1024
	ds_read_b128 v[188:191], v252 offset:2048
	ds_read_b128 v[192:195], v252 offset:3072
	s_ashr_i32 s25, s24, 31
	s_lshl_b64 s[24:25], s[24:25], 7
	s_add_u32 s2, s4, s24
	ds_read_b128 v[164:167], v253
	ds_read_b128 v[168:171], v253 offset:1024
	ds_read_b128 v[172:175], v253 offset:2048
	ds_read_b128 v[176:179], v253 offset:3072
	ds_read_b128 v[180:183], v253 offset:4096
	ds_read_b128 v[184:187], v253 offset:5120
	ds_read_b128 v[0:3], v253 offset:6144
	ds_read_b128 v[4:7], v253 offset:7168
	s_addc_u32 s4, s5, s25
	s_add_u32 s2, s2, s52
	s_addc_u32 s5, s4, s53
	s_add_u32 s4, s2, 0xffffff80
	s_addc_u32 s5, s5, -1
	s_add_u32 s24, s4, s50
	s_mov_b32 m0, s82
	s_nop 0
	global_load_lds_dwordx4 v160, s[4:5]
	s_addc_u32 s25, s5, s51
	s_mov_b32 m0, s83
	s_nop 0
	global_load_lds_dwordx4 v160, s[24:25]
	s_waitcnt vmcnt(8)
	s_waitcnt lgkmcnt(0)
	s_barrier
	s_waitcnt lgkmcnt(6)
	v_mfma_scale_f32_16x16x128_f8f6f4 v[156:159], v[24:31], v[164:171], v[156:159], v248, v250 op_sel_hi:[0,0,0]
	v_mfma_scale_f32_16x16x128_f8f6f4 v[196:199], v[16:23], v[164:171], v[152:155], v248, v250 op_sel_hi:[0,0,0]
	s_waitcnt lgkmcnt(4)
	v_mfma_scale_f32_16x16x128_f8f6f4 v[200:203], v[24:31], v[172:179], v[148:151], v248, v250 op_sel_hi:[0,0,0]
	v_mfma_scale_f32_16x16x128_f8f6f4 v[204:207], v[16:23], v[172:179], v[144:147], v248, v250 op_sel_hi:[0,0,0]
	s_waitcnt lgkmcnt(2)
	v_mfma_scale_f32_16x16x128_f8f6f4 v[208:211], v[24:31], v[180:187], v[140:143], v248, v250 op_sel_hi:[0,0,0]
	v_mfma_scale_f32_16x16x128_f8f6f4 v[212:215], v[16:23], v[180:187], v[136:139], v248, v250 op_sel_hi:[0,0,0]
	s_waitcnt lgkmcnt(0)
	v_mfma_scale_f32_16x16x128_f8f6f4 v[132:135], v[24:31], v[0:7], v[132:135], v248, v250 op_sel_hi:[0,0,0]
	v_mfma_scale_f32_16x16x128_f8f6f4 v[216:219], v[16:23], v[0:7], v[128:131], v248, v250 op_sel_hi:[0,0,0]
	v_mfma_scale_f32_16x16x128_f8f6f4 v[124:127], v[8:15], v[164:171], v[124:127], v248, v250 op_sel_hi:[0,0,0]
	v_mov_b64_e32 v[160:161], v[220:221]
	v_mfma_scale_f32_16x16x128_f8f6f4 v[220:223], v[188:195], v[164:171], v[120:123], v248, v250 op_sel_hi:[0,0,0]
	v_mfma_scale_f32_16x16x128_f8f6f4 v[224:227], v[8:15], v[172:179], v[116:119], v248, v250 op_sel_hi:[0,0,0]
	v_mfma_scale_f32_16x16x128_f8f6f4 v[228:231], v[188:195], v[172:179], v[112:115], v248, v250 op_sel_hi:[0,0,0]
	v_mfma_scale_f32_16x16x128_f8f6f4 v[232:235], v[8:15], v[180:187], v[108:111], v248, v250 op_sel_hi:[0,0,0]
	v_mfma_scale_f32_16x16x128_f8f6f4 v[236:239], v[188:195], v[180:187], v[104:107], v248, v250 op_sel_hi:[0,0,0]
	v_mfma_scale_f32_16x16x128_f8f6f4 v[240:243], v[8:15], v[0:7], v[100:103], v248, v250 op_sel_hi:[0,0,0]
	v_mfma_scale_f32_16x16x128_f8f6f4 v[244:247], v[188:195], v[0:7], v[96:99], v248, v250 op_sel_hi:[0,0,0]
	s_barrier
	s_add_u32 s24, s6, s30
	ds_read_b128 v[0:3], v253 offset:16384
	ds_read_b128 v[4:7], v253 offset:17408
	s_nop 1
	ds_read_b128 v[96:99], v253 offset:18432
	ds_read_b128 v[100:103], v253 offset:19456
	ds_read_b128 v[104:107], v253 offset:20480
	ds_read_b128 v[108:111], v253 offset:21504
	ds_read_b128 v[112:115], v253 offset:22528
	ds_read_b128 v[116:119], v253 offset:23552
	s_addc_u32 s25, s7, s31
	s_mov_b32 m0, s58
	s_nop 0
	global_load_lds_dwordx4 v161, s[6:7]
	s_add_u32 s50, s6, s36
	s_mov_b32 m0, s59
	s_nop 0
	global_load_lds_dwordx4 v161, s[24:25]
	s_addc_u32 s51, s7, s37
	s_add_u32 s52, s50, s30
	s_mov_b32 m0, s60
	s_nop 0
	global_load_lds_dwordx4 v161, s[50:51]
	s_addc_u32 s53, s51, s31
	s_mov_b32 m0, s61
	s_nop 0
	global_load_lds_dwordx4 v161, s[52:53]
	s_add_u32 s4, s48, s46
	s_mov_b32 m0, s55
	s_nop 0
	global_load_lds_dwordx4 v160, s[48:49]
	s_addc_u32 s5, s49, s47
	s_mov_b32 m0, s62
	s_nop 0
	global_load_lds_dwordx4 v160, s[4:5]
	s_waitcnt vmcnt(8)
	s_waitcnt lgkmcnt(0)
	s_barrier
	s_waitcnt lgkmcnt(6)
	v_mfma_scale_f32_16x16x128_f8f6f4 v[136:139], v[24:31], v[0:7], v[92:95], v248, v250 op_sel_hi:[0,0,0]
	v_mfma_scale_f32_16x16x128_f8f6f4 v[140:143], v[16:23], v[0:7], v[88:91], v248, v250 op_sel_hi:[0,0,0]
	s_waitcnt lgkmcnt(4)
	v_mfma_scale_f32_16x16x128_f8f6f4 v[144:147], v[24:31], v[96:103], v[84:87], v248, v250 op_sel_hi:[0,0,0]
	v_mfma_scale_f32_16x16x128_f8f6f4 v[148:151], v[16:23], v[96:103], v[80:83], v248, v250 op_sel_hi:[0,0,0]
	s_waitcnt lgkmcnt(2)
	v_mfma_scale_f32_16x16x128_f8f6f4 v[152:155], v[24:31], v[104:111], v[76:79], v248, v250 op_sel_hi:[0,0,0]
	v_mfma_scale_f32_16x16x128_f8f6f4 v[72:75], v[16:23], v[104:111], v[72:75], v248, v250 op_sel_hi:[0,0,0]
	s_waitcnt lgkmcnt(0)
	v_mfma_scale_f32_16x16x128_f8f6f4 v[68:71], v[24:31], v[112:119], v[68:71], v248, v250 op_sel_hi:[0,0,0]
	v_mfma_scale_f32_16x16x128_f8f6f4 v[64:67], v[16:23], v[112:119], v[64:67], v248, v250 op_sel_hi:[0,0,0]
	v_mfma_scale_f32_16x16x128_f8f6f4 v[164:167], v[8:15], v[0:7], v[60:63], v248, v250 op_sel_hi:[0,0,0]
	v_mfma_scale_f32_16x16x128_f8f6f4 v[56:59], v[188:195], v[0:7], v[56:59], v248, v250 op_sel_hi:[0,0,0]
	v_mfma_scale_f32_16x16x128_f8f6f4 v[168:171], v[8:15], v[96:103], v[52:55], v248, v250 op_sel_hi:[0,0,0]
	v_mfma_scale_f32_16x16x128_f8f6f4 v[172:175], v[188:195], v[96:103], v[48:51], v248, v250 op_sel_hi:[0,0,0]
	v_mfma_scale_f32_16x16x128_f8f6f4 v[176:179], v[8:15], v[104:111], v[44:47], v248, v250 op_sel_hi:[0,0,0]
	v_mfma_scale_f32_16x16x128_f8f6f4 v[180:183], v[188:195], v[104:111], v[40:43], v248, v250 op_sel_hi:[0,0,0]
	v_mfma_scale_f32_16x16x128_f8f6f4 v[184:187], v[8:15], v[112:119], v[36:39], v248, v250 op_sel_hi:[0,0,0]
	v_mfma_scale_f32_16x16x128_f8f6f4 v[188:191], v[188:195], v[112:119], v[32:35], v248, v250 op_sel_hi:[0,0,0]
	s_barrier
	ds_read_b128 v[24:27], v249
	ds_read_b128 v[28:31], v249 offset:1024
	ds_read_b128 v[16:19], v249 offset:2048
	ds_read_b128 v[20:23], v249 offset:3072
	ds_read_b128 v[8:11], v162
	ds_read_b128 v[12:15], v162 offset:1024
	ds_read_b128 v[0:3], v162 offset:2048
	ds_read_b128 v[4:7], v162 offset:3072
	ds_read_b128 v[32:35], v253 offset:32768
	ds_read_b128 v[36:39], v253 offset:33792
	ds_read_b128 v[40:43], v253 offset:34816
	ds_read_b128 v[44:47], v253 offset:35840
	ds_read_b128 v[48:51], v253 offset:36864
	ds_read_b128 v[52:55], v253 offset:37888
	ds_read_b128 v[76:79], v253 offset:38912
	ds_read_b128 v[80:83], v253 offset:39936
	s_add_u32 s34, s48, s44
	s_addc_u32 s35, s49, s45
	s_add_u32 s68, s34, s46
	s_mov_b32 m0, s63
	s_nop 0
	global_load_lds_dwordx4 v160, s[34:35]
	s_addc_u32 s69, s35, s47
	s_mov_b32 m0, s64
	s_nop 0
	global_load_lds_dwordx4 v160, s[68:69]
	s_waitcnt vmcnt(8)
	s_waitcnt lgkmcnt(0)
	s_barrier
	s_waitcnt lgkmcnt(6)
	v_mfma_scale_f32_16x16x128_f8f6f4 v[128:131], v[24:31], v[32:39], v[156:159], v248, v250 op_sel_hi:[0,0,0]
	v_mfma_scale_f32_16x16x128_f8f6f4 v[120:123], v[16:23], v[32:39], v[196:199], v248, v250 op_sel_hi:[0,0,0]
	s_waitcnt lgkmcnt(4)
	v_mfma_scale_f32_16x16x128_f8f6f4 v[116:119], v[24:31], v[40:47], v[200:203], v248, v250 op_sel_hi:[0,0,0]
	v_mfma_scale_f32_16x16x128_f8f6f4 v[108:111], v[16:23], v[40:47], v[204:207], v248, v250 op_sel_hi:[0,0,0]
	s_waitcnt lgkmcnt(2)
	v_mfma_scale_f32_16x16x128_f8f6f4 v[100:103], v[24:31], v[48:55], v[208:211], v248, v250 op_sel_hi:[0,0,0]
	v_mfma_scale_f32_16x16x128_f8f6f4 v[92:95], v[16:23], v[48:55], v[212:215], v248, v250 op_sel_hi:[0,0,0]
	s_waitcnt lgkmcnt(0)
	v_mfma_scale_f32_16x16x128_f8f6f4 v[84:87], v[24:31], v[76:83], v[132:135], v248, v250 op_sel_hi:[0,0,0]
	v_mfma_scale_f32_16x16x128_f8f6f4 v[200:203], v[16:23], v[76:83], v[216:219], v248, v250 op_sel_hi:[0,0,0]
	v_mfma_scale_f32_16x16x128_f8f6f4 v[132:135], v[8:15], v[32:39], v[124:127], v248, v250 op_sel_hi:[0,0,0]
	v_mfma_scale_f32_16x16x128_f8f6f4 v[124:127], v[0:7], v[32:39], v[220:223], v248, v250 op_sel_hi:[0,0,0]
	v_mfma_scale_f32_16x16x128_f8f6f4 v[112:115], v[8:15], v[40:47], v[224:227], v248, v250 op_sel_hi:[0,0,0]
	s_nop 5
	v_mov_b64_e32 v[220:221], v[160:161]
	v_mfma_scale_f32_16x16x128_f8f6f4 v[104:107], v[0:7], v[40:47], v[228:231], v248, v250 op_sel_hi:[0,0,0]
	v_mfma_scale_f32_16x16x128_f8f6f4 v[96:99], v[8:15], v[48:55], v[232:235], v248, v250 op_sel_hi:[0,0,0]
	v_mfma_scale_f32_16x16x128_f8f6f4 v[88:91], v[0:7], v[48:55], v[236:239], v248, v250 op_sel_hi:[0,0,0]
	v_mfma_scale_f32_16x16x128_f8f6f4 v[196:199], v[8:15], v[76:83], v[240:243], v248, v250 op_sel_hi:[0,0,0]
	v_mfma_scale_f32_16x16x128_f8f6f4 v[192:195], v[0:7], v[76:83], v[244:247], v248, v250 op_sel_hi:[0,0,0]
	s_barrier
	s_add_u32 s34, s6, 0x80
	s_addc_u32 s35, s7, 0
	s_add_u32 s24, s24, 0x80
	ds_read_b128 v[40:43], v253 offset:49152
	ds_read_b128 v[44:47], v253 offset:50176
	ds_read_b128 v[76:79], v253 offset:51200
	ds_read_b128 v[80:83], v253 offset:52224
	ds_read_b128 v[204:207], v253 offset:53248
	ds_read_b128 v[208:211], v253 offset:54272
	ds_read_b128 v[212:215], v253 offset:55296
	ds_read_b128 v[216:219], v253 offset:56320
	s_addc_u32 s25, s25, 0
	s_mov_b32 m0, s65
	s_nop 0
	global_load_lds_dwordx4 v221, s[34:35]
	s_nop 0
	s_mov_b32 m0, s66
	s_nop 0
	global_load_lds_dwordx4 v221, s[24:25]
	s_add_u32 s24, s50, 0x80
	s_addc_u32 s25, s51, 0
	s_add_u32 s34, s52, 0x80
	s_addc_u32 s35, s53, 0
	s_mov_b32 m0, s78
	s_nop 0
	global_load_lds_dwordx4 v221, s[24:25]
	s_add_u32 s24, s48, 0x80
	s_mov_b32 m0, s79
	s_nop 0
	global_load_lds_dwordx4 v221, s[34:35]
	s_addc_u32 s25, s49, 0
	s_add_u32 s4, s4, 0x80
	s_mov_b32 m0, s67
	s_nop 0
	global_load_lds_dwordx4 v220, s[24:25]
	s_addc_u32 s5, s5, 0
	s_mov_b32 m0, s73
	s_nop 0
	global_load_lds_dwordx4 v220, s[4:5]
	s_waitcnt vmcnt(8)
	s_waitcnt lgkmcnt(0)
	s_barrier
	s_waitcnt lgkmcnt(6)
	v_mfma_scale_f32_16x16x128_f8f6f4 v[156:159], v[24:31], v[40:47], v[136:139], v248, v250 op_sel_hi:[0,0,0]
	v_mfma_scale_f32_16x16x128_f8f6f4 v[60:63], v[16:23], v[40:47], v[140:143], v248, v250 op_sel_hi:[0,0,0]
	s_waitcnt lgkmcnt(4)
	v_mfma_scale_f32_16x16x128_f8f6f4 v[52:55], v[24:31], v[76:83], v[144:147], v248, v250 op_sel_hi:[0,0,0]
	v_mfma_scale_f32_16x16x128_f8f6f4 v[48:51], v[16:23], v[76:83], v[148:151], v248, v250 op_sel_hi:[0,0,0]
	s_waitcnt lgkmcnt(2)
	v_mfma_scale_f32_16x16x128_f8f6f4 v[36:39], v[24:31], v[204:211], v[152:155], v248, v250 op_sel_hi:[0,0,0]
	v_mfma_scale_f32_16x16x128_f8f6f4 v[32:35], v[16:23], v[204:211], v[72:75], v248, v250 op_sel_hi:[0,0,0]
	s_waitcnt lgkmcnt(0)
	v_mfma_scale_f32_16x16x128_f8f6f4 v[24:27], v[24:31], v[212:219], v[68:71], v248, v250 op_sel_hi:[0,0,0]
	v_mfma_scale_f32_16x16x128_f8f6f4 v[16:19], v[16:23], v[212:219], v[64:67], v248, v250 op_sel_hi:[0,0,0]
	v_mfma_scale_f32_16x16x128_f8f6f4 v[64:67], v[8:15], v[40:47], v[164:167], v248, v250 op_sel_hi:[0,0,0]
	v_mfma_scale_f32_16x16x128_f8f6f4 v[56:59], v[0:7], v[40:47], v[56:59], v248, v250 op_sel_hi:[0,0,0]
	v_mfma_scale_f32_16x16x128_f8f6f4 v[44:47], v[8:15], v[76:83], v[168:171], v248, v250 op_sel_hi:[0,0,0]
	v_mfma_scale_f32_16x16x128_f8f6f4 v[40:43], v[0:7], v[76:83], v[172:175], v248, v250 op_sel_hi:[0,0,0]
	v_mfma_scale_f32_16x16x128_f8f6f4 v[28:31], v[8:15], v[204:211], v[176:179], v248, v250 op_sel_hi:[0,0,0]
	v_mfma_scale_f32_16x16x128_f8f6f4 v[20:23], v[0:7], v[204:211], v[180:183], v248, v250 op_sel_hi:[0,0,0]
	v_mfma_scale_f32_16x16x128_f8f6f4 v[8:11], v[8:15], v[212:219], v[184:187], v248, v250 op_sel_hi:[0,0,0]
	v_mfma_scale_f32_16x16x128_f8f6f4 v[0:3], v[0:7], v[212:219], v[188:191], v248, v250 op_sel_hi:[0,0,0]
	s_barrier
	s_andn2_b64 vcc, exec, s[26:27]
	s_cbranch_vccnz .LBB0_947
	s_barrier

.LBB0_1011:
	v_ashrrev_i32_e32 v1, 6, v2
	s_lshl_b32 s11, s18, 13
	v_and_b32_e32 v3, 48, v2
	v_lshl_add_u32 v4, v1, 10, s11
	v_lshlrev_b32_e32 v5, 6, v2
	s_movk_i32 s11, 0x3c0
	v_and_or_b32 v3, v5, s11, v3
	s_lshl_b32 s11, s76, 5
	s_and_b32 s23, s11, 0x60
	s_lshl_b64 s[56:57], s[12:13], 7
	s_lshl_b64 s[38:39], s[16:17], 7
	s_lshl_b32 s20, s18, 6
	s_lshr_b32 s11, s23, 3
	s_add_u32 s12, s6, 0xffffff80
	s_addc_u32 s13, s7, -1
	s_add_u32 s16, s12, s34
	s_mov_b32 s44, s9
	s_addc_u32 s17, s13, s35
	s_add_i32 s9, s3, 0x18000
	s_add_i32 s80, s3, 0x1a000
	s_mov_b32 s45, s10
	s_mov_b32 s98, 0
	s_cselect_b32 s99, 1, 0
	s_cmp_lt_u32 s76, 4
	s_cbranch_scc0 .Lsprio_12
	s_setprio 1
.Lsprio_12:
	s_cmp_lg_u32 s99, 0
	s_waitcnt vmcnt(2)
	s_barrier
	s_mov_b32 m0, s9
	s_nop 0
	global_load_lds_dwordx4 v0, s[12:13]
	s_add_u32 s12, s4, 0xffffff80
	s_addc_u32 s13, s5, -1
	s_mov_b32 m0, s80
	s_nop 0
	global_load_lds_dwordx4 v0, s[16:17]
	s_add_u32 s16, s12, s52
	s_addc_u32 s17, s13, s53
	s_add_i32 s81, s3, 0x8000
	s_add_i32 s82, s3, 0xa000
	s_mov_b32 m0, s81
	s_nop 0
	global_load_lds_dwordx4 v128, s[12:13]
	s_add_u32 s12, s14, 0xffffff80
	s_addc_u32 s13, s15, -1
	s_mov_b32 m0, s82
	s_nop 0
	global_load_lds_dwordx4 v128, s[16:17]
	s_add_u32 s14, s12, s34
	s_addc_u32 s15, s13, s35
	s_add_i32 s83, s3, 0x1c000
	s_mov_b32 m0, s83
	s_nop 0
	global_load_lds_dwordx4 v0, s[12:13]
	v_lshlrev_b32_e32 v2, 2, v2
	s_add_i32 s84, s3, 0x1e000
	s_mov_b32 m0, s84
	s_nop 0
	global_load_lds_dwordx4 v0, s[14:15]
	v_and_b32_e32 v2, 32, v2
	v_add_lshl_u32 v1, v1, s11, 10
	v_readlane_b32 s0, v254, 0
	v_writelane_b32 v254, s12, 55
	v_bitop3_b32 v1, v3, v1, v2 bitop3:0xde
	s_waitcnt vmcnt(6)
	s_add_i32 s85, s3, 0xc000
	s_add_i32 s86, s3, 0xe000
	v_writelane_b32 v254, s13, 56
	v_mov_b32_e32 v129, v0
	v_bitop3_b32 v4, v3, v4, v2 bitop3:0xde
	s_movk_i32 s46, 0xff80
	s_cmpk_lt_u32 s0, 0x100
	v_add_u32_e32 v0, 0, v1
	v_writelane_b32 v254, s14, 57
	s_mov_b32 s47, -1
	s_mov_b32 s11, 0
	s_cselect_b64 s[36:37], -1, 0
	v_add_u32_e32 v173, 0x10000, v0
	v_add_u32_e32 v174, 0x14000, v0
	v_add_u32_e32 v175, 0, v4
	v_add_u32_e32 v176, 0x18000, v0
	v_add_u32_e32 v177, 0x1c000, v0
	v_mov_b32_e32 v161, 0
	v_writelane_b32 v254, s15, 58
	s_mov_b32 s77, 0
	s_mov_b32 s22, s1
	s_barrier
	s_branch .LBB0_1014

.LBB0_1016:
	s_cmp_lt_i32 s2, 3
	s_cbranch_scc1 .Lhz_1018
	s_mul_i32 s13, s47, 3
	s_mul_hi_u32 s19, s46, 3
	s_add_i32 s10, s2, -2
	s_add_i32 s24, s19, s13
	s_mul_i32 s25, s46, 3
	s_add_u32 s13, s38, s25
	s_addc_u32 s19, s39, s24
	s_add_u32 s13, s6, s13
	s_addc_u32 s19, s7, s19
	s_lshl_b64 s[48:49], s[46:47], 1
	s_waitcnt lgkmcnt(0)
	v_writelane_b32 v254, s40, 0
	s_mov_b32 s1, s20
	s_mov_b64 s[20:21], s[26:27]
	s_add_u32 s26, s34, s38
	v_writelane_b32 v254, s41, 1
	s_addc_u32 s27, s35, s39
	v_writelane_b32 v254, s42, 2
	s_add_u32 s33, s26, s25
	v_writelane_b32 v254, s43, 3
	s_mov_b64 s[42:43], s[36:37]
	s_addc_u32 s36, s27, s24
	s_add_u32 s33, s6, s33
	s_addc_u32 s58, s7, s36
	s_add_u32 s59, s6, s25
	s_addc_u32 s68, s7, s24
	s_add_u32 s36, s34, s25
	s_addc_u32 s37, s35, s24
	s_add_u32 s69, s6, s36
	s_addc_u32 s70, s7, s37
	s_add_u32 s36, s38, s48
	s_addc_u32 s37, s39, s49
	s_add_u32 s71, s6, s36
	s_addc_u32 s72, s7, s37
	s_add_u32 s26, s26, s48
	s_addc_u32 s27, s27, s49
	s_add_u32 s74, s6, s26
	s_addc_u32 s75, s7, s27
	s_add_u32 s87, s6, s48
	s_addc_u32 s88, s7, s49
	s_add_u32 s26, s34, s48
	s_addc_u32 s27, s35, s49
	s_add_u32 s89, s6, s26
	s_addc_u32 s90, s7, s27
	s_add_u32 s91, s4, s25
	s_addc_u32 s92, s5, s24
	s_add_u32 s25, s52, s25
	s_addc_u32 s24, s53, s24
	s_add_u32 s93, s4, s25
	s_addc_u32 s94, s5, s24
	s_add_u32 s24, s56, s48
	s_addc_u32 s25, s57, s49
	s_add_u32 s95, s4, s24
	s_addc_u32 s96, s5, s25
	s_add_u32 s24, s52, s56
	s_addc_u32 s25, s53, s57
	s_add_u32 s26, s24, s48
	s_addc_u32 s27, s25, s49
	s_add_u32 s97, s4, s26
	s_addc_u32 vcc_lo, s5, s27
	s_add_u32 vcc_hi, s4, s48
	s_addc_u32 s61, s5, s49
	s_add_u32 s26, s52, s48
	s_addc_u32 s27, s53, s49
	s_add_u32 s36, s4, s26
	s_addc_u32 s37, s5, s27
	s_add_u32 s26, s56, s46
	s_addc_u32 s27, s57, s47
	s_add_u32 s60, s4, s26
	s_addc_u32 s78, s5, s27
	s_add_u32 s24, s24, s46
	s_addc_u32 s25, s25, s47
	s_add_u32 s40, s4, s24
	s_addc_u32 s41, s5, s25
	s_mov_b32 s79, 0
	s_mov_b64 s[50:51], 0
	s_cmp_eq_u32 s98, 0
	s_cbranch_scc1 .Lhf_1018
	ds_read_b128 v[130:133], v173
	ds_read_b128 v[134:137], v173 offset:1024
	ds_read_b128 v[138:141], v173 offset:2048
	ds_read_b128 v[142:145], v173 offset:3072
	ds_read_b128 v[146:149], v174
	ds_read_b128 v[150:153], v174 offset:1024
	ds_read_b128 v[154:157], v174 offset:2048
	ds_read_b128 v[162:165], v174 offset:3072
	s_add_i32 s79, s79, 2
	s_add_u32 s54, vcc_hi, s50
	s_addc_u32 s55, s61, s51
	ds_read_b128 v[166:169], v175
	ds_read_b128 v[178:181], v175 offset:1024
	ds_read_b128 v[182:185], v175 offset:2048
	ds_read_b128 v[186:189], v175 offset:3072
	ds_read_b128 v[190:193], v175 offset:4096
	ds_read_b128 v[194:197], v175 offset:5120
	ds_read_b128 v[198:201], v175 offset:6144
	ds_read_b128 v[202:205], v175 offset:7168
	s_add_u32 s24, s60, s50
	s_addc_u32 s25, s78, s51
	s_add_u32 s26, s40, s50
	s_mov_b32 m0, s85
	s_nop 0
	global_load_lds_dwordx4 v128, s[24:25]
	s_addc_u32 s27, s41, s51
	s_mov_b32 m0, s86
	s_nop 0
	global_load_lds_dwordx4 v128, s[26:27]
	s_waitcnt vmcnt(24)
	s_waitcnt lgkmcnt(0)
	s_barrier
	s_waitcnt lgkmcnt(7)
	v_mfma_f32_16x16x32_bf16 v[124:127], v[130:133], v[166:169], 0
	v_mfma_f32_16x16x32_bf16 v[120:123], v[138:141], v[166:169], 0
	s_waitcnt lgkmcnt(5)
	v_mfma_f32_16x16x32_bf16 v[116:119], v[130:133], v[182:185], 0
	v_mfma_f32_16x16x32_bf16 v[112:115], v[138:141], v[182:185], 0
	s_waitcnt lgkmcnt(3)
	v_mfma_f32_16x16x32_bf16 v[108:111], v[130:133], v[190:193], 0
	v_mfma_f32_16x16x32_bf16 v[104:107], v[138:141], v[190:193], 0
	s_waitcnt lgkmcnt(1)
	v_mfma_f32_16x16x32_bf16 v[100:103], v[130:133], v[198:201], 0
	v_mfma_f32_16x16x32_bf16 v[96:99], v[138:141], v[198:201], 0
	v_mfma_f32_16x16x32_bf16 v[124:127], v[134:137], v[178:181], v[124:127]
	v_mfma_f32_16x16x32_bf16 v[120:123], v[142:145], v[178:181], v[120:123]
	v_mfma_f32_16x16x32_bf16 v[116:119], v[134:137], v[186:189], v[116:119]
	v_mfma_f32_16x16x32_bf16 v[112:115], v[142:145], v[186:189], v[112:115]
	v_mfma_f32_16x16x32_bf16 v[108:111], v[134:137], v[194:197], v[108:111]
	v_mfma_f32_16x16x32_bf16 v[104:107], v[142:145], v[194:197], v[104:107]
	s_waitcnt lgkmcnt(0)
	v_mfma_f32_16x16x32_bf16 v[100:103], v[134:137], v[202:205], v[100:103]
	v_mfma_f32_16x16x32_bf16 v[96:99], v[142:145], v[202:205], v[96:99]
	v_mfma_f32_16x16x32_bf16 v[92:95], v[146:149], v[166:169], 0
	v_mfma_f32_16x16x32_bf16 v[88:91], v[154:157], v[166:169], 0
	v_mfma_f32_16x16x32_bf16 v[84:87], v[146:149], v[182:185], 0
	v_mfma_f32_16x16x32_bf16 v[80:83], v[154:157], v[182:185], 0
	v_mfma_f32_16x16x32_bf16 v[76:79], v[146:149], v[190:193], 0
	v_mfma_f32_16x16x32_bf16 v[72:75], v[154:157], v[190:193], 0
	v_mfma_f32_16x16x32_bf16 v[68:71], v[146:149], v[198:201], 0
	v_mfma_f32_16x16x32_bf16 v[64:67], v[154:157], v[198:201], 0
	v_mfma_f32_16x16x32_bf16 v[92:95], v[150:153], v[178:181], v[92:95]
	v_mfma_f32_16x16x32_bf16 v[88:91], v[162:165], v[178:181], v[88:91]
	v_mfma_f32_16x16x32_bf16 v[84:87], v[150:153], v[186:189], v[84:87]
	v_mfma_f32_16x16x32_bf16 v[80:83], v[162:165], v[186:189], v[80:83]
	v_mfma_f32_16x16x32_bf16 v[76:79], v[150:153], v[194:197], v[76:79]
	v_mfma_f32_16x16x32_bf16 v[72:75], v[162:165], v[194:197], v[72:75]
	v_mfma_f32_16x16x32_bf16 v[68:71], v[150:153], v[202:205], v[68:71]
	v_mfma_f32_16x16x32_bf16 v[64:67], v[162:165], v[202:205], v[64:67]
	s_barrier
	s_add_u32 s24, s87, s50
	s_addc_u32 s25, s88, s51
	s_add_u32 s26, s89, s50
	ds_read_b128 v[166:169], v175 offset:16384
	ds_read_b128 v[178:181], v175 offset:17408
	ds_read_b128 v[182:185], v175 offset:18432
	ds_read_b128 v[186:189], v175 offset:19456
	ds_read_b128 v[190:193], v175 offset:20480
	ds_read_b128 v[194:197], v175 offset:21504
	ds_read_b128 v[198:201], v175 offset:22528
	ds_read_b128 v[202:205], v175 offset:23552
	s_addc_u32 s27, s90, s51
	s_mov_b32 m0, s62
	s_nop 0
	global_load_lds_dwordx4 v129, s[24:25]
	s_add_u32 s24, s71, s50
	s_mov_b32 m0, s63
	s_nop 0
	global_load_lds_dwordx4 v129, s[26:27]
	s_addc_u32 s25, s72, s51
	s_add_u32 s26, s74, s50
	s_mov_b32 m0, s64
	s_nop 0
	global_load_lds_dwordx4 v129, s[24:25]
	s_addc_u32 s27, s75, s51
	s_mov_b32 m0, s65
	s_nop 0
	global_load_lds_dwordx4 v129, s[26:27]
	s_add_u32 s24, s36, s50
	s_mov_b32 m0, s3
	s_nop 0
	global_load_lds_dwordx4 v128, s[54:55]
	s_addc_u32 s25, s37, s51
	s_mov_b32 m0, s66
	s_nop 0
	global_load_lds_dwordx4 v128, s[24:25]
	s_waitcnt vmcnt(24)
	s_waitcnt lgkmcnt(0)
	s_barrier
	s_waitcnt lgkmcnt(7)
	v_mfma_f32_16x16x32_bf16 v[60:63], v[130:133], v[166:169], 0
	v_mfma_f32_16x16x32_bf16 v[56:59], v[138:141], v[166:169], 0
	s_waitcnt lgkmcnt(5)
	v_mfma_f32_16x16x32_bf16 v[52:55], v[130:133], v[182:185], 0
	v_mfma_f32_16x16x32_bf16 v[48:51], v[138:141], v[182:185], 0
	s_waitcnt lgkmcnt(3)
	v_mfma_f32_16x16x32_bf16 v[44:47], v[130:133], v[190:193], 0
	v_mfma_f32_16x16x32_bf16 v[40:43], v[138:141], v[190:193], 0
	s_waitcnt lgkmcnt(1)
	v_mfma_f32_16x16x32_bf16 v[36:39], v[130:133], v[198:201], 0
	v_mfma_f32_16x16x32_bf16 v[32:35], v[138:141], v[198:201], 0
	v_mfma_f32_16x16x32_bf16 v[60:63], v[134:137], v[178:181], v[60:63]
	v_mfma_f32_16x16x32_bf16 v[56:59], v[142:145], v[178:181], v[56:59]
	v_mfma_f32_16x16x32_bf16 v[52:55], v[134:137], v[186:189], v[52:55]
	v_mfma_f32_16x16x32_bf16 v[48:51], v[142:145], v[186:189], v[48:51]
	v_mfma_f32_16x16x32_bf16 v[44:47], v[134:137], v[194:197], v[44:47]
	v_mfma_f32_16x16x32_bf16 v[40:43], v[142:145], v[194:197], v[40:43]
	s_waitcnt lgkmcnt(0)
	v_mfma_f32_16x16x32_bf16 v[36:39], v[134:137], v[202:205], v[36:39]
	v_mfma_f32_16x16x32_bf16 v[32:35], v[142:145], v[202:205], v[32:35]
	v_mfma_f32_16x16x32_bf16 v[28:31], v[146:149], v[166:169], 0
	v_mfma_f32_16x16x32_bf16 v[24:27], v[154:157], v[166:169], 0
	v_mfma_f32_16x16x32_bf16 v[20:23], v[146:149], v[182:185], 0
	v_mfma_f32_16x16x32_bf16 v[16:19], v[154:157], v[182:185], 0
	v_mfma_f32_16x16x32_bf16 v[12:15], v[146:149], v[190:193], 0
	v_mfma_f32_16x16x32_bf16 v[8:11], v[154:157], v[190:193], 0
	v_mfma_f32_16x16x32_bf16 v[4:7], v[146:149], v[198:201], 0
	v_mfma_f32_16x16x32_bf16 v[0:3], v[154:157], v[198:201], 0
	v_mfma_f32_16x16x32_bf16 v[28:31], v[150:153], v[178:181], v[28:31]
	v_mfma_f32_16x16x32_bf16 v[24:27], v[162:165], v[178:181], v[24:27]
	v_mfma_f32_16x16x32_bf16 v[20:23], v[150:153], v[186:189], v[20:23]
	v_mfma_f32_16x16x32_bf16 v[16:19], v[162:165], v[186:189], v[16:19]
	v_mfma_f32_16x16x32_bf16 v[12:15], v[150:153], v[194:197], v[12:15]
	v_mfma_f32_16x16x32_bf16 v[8:11], v[162:165], v[194:197], v[8:11]
	v_mfma_f32_16x16x32_bf16 v[4:7], v[150:153], v[202:205], v[4:7]
	v_mfma_f32_16x16x32_bf16 v[0:3], v[162:165], v[202:205], v[0:3]
	s_barrier
	ds_read_b128 v[130:133], v176
	ds_read_b128 v[134:137], v176 offset:1024
	ds_read_b128 v[138:141], v176 offset:2048
	ds_read_b128 v[142:145], v176 offset:3072
	ds_read_b128 v[146:149], v177
	ds_read_b128 v[150:153], v177 offset:1024
	ds_read_b128 v[154:157], v177 offset:2048
	ds_read_b128 v[162:165], v177 offset:3072
	ds_read_b128 v[166:169], v175 offset:32768
	ds_read_b128 v[178:181], v175 offset:33792
	ds_read_b128 v[182:185], v175 offset:34816
	ds_read_b128 v[186:189], v175 offset:35840
	ds_read_b128 v[190:193], v175 offset:36864
	ds_read_b128 v[194:197], v175 offset:37888
	ds_read_b128 v[198:201], v175 offset:38912
	ds_read_b128 v[202:205], v175 offset:39936
	s_add_u32 s24, s95, s50
	s_addc_u32 s25, s96, s51
	s_add_u32 s26, s97, s50
	s_mov_b32 m0, s67
	s_nop 0
	global_load_lds_dwordx4 v128, s[24:25]
	s_addc_u32 s27, vcc_lo, s51
	s_mov_b32 m0, s73
	s_nop 0
	global_load_lds_dwordx4 v128, s[26:27]
	s_waitcnt vmcnt(8)
	s_waitcnt lgkmcnt(0)
	s_barrier
	s_waitcnt lgkmcnt(7)
	v_mfma_f32_16x16x32_bf16 v[124:127], v[130:133], v[166:169], v[124:127]
	v_mfma_f32_16x16x32_bf16 v[120:123], v[138:141], v[166:169], v[120:123]
	s_waitcnt lgkmcnt(5)
	v_mfma_f32_16x16x32_bf16 v[116:119], v[130:133], v[182:185], v[116:119]
	v_mfma_f32_16x16x32_bf16 v[112:115], v[138:141], v[182:185], v[112:115]
	s_waitcnt lgkmcnt(3)
	v_mfma_f32_16x16x32_bf16 v[108:111], v[130:133], v[190:193], v[108:111]
	v_mfma_f32_16x16x32_bf16 v[104:107], v[138:141], v[190:193], v[104:107]
	s_waitcnt lgkmcnt(1)
	v_mfma_f32_16x16x32_bf16 v[100:103], v[130:133], v[198:201], v[100:103]
	v_mfma_f32_16x16x32_bf16 v[96:99], v[138:141], v[198:201], v[96:99]
	v_mfma_f32_16x16x32_bf16 v[124:127], v[134:137], v[178:181], v[124:127]
	v_mfma_f32_16x16x32_bf16 v[120:123], v[142:145], v[178:181], v[120:123]
	v_mfma_f32_16x16x32_bf16 v[116:119], v[134:137], v[186:189], v[116:119]
	v_mfma_f32_16x16x32_bf16 v[112:115], v[142:145], v[186:189], v[112:115]
	v_mfma_f32_16x16x32_bf16 v[108:111], v[134:137], v[194:197], v[108:111]
	v_mfma_f32_16x16x32_bf16 v[104:107], v[142:145], v[194:197], v[104:107]
	s_waitcnt lgkmcnt(0)
	v_mfma_f32_16x16x32_bf16 v[100:103], v[134:137], v[202:205], v[100:103]
	v_mfma_f32_16x16x32_bf16 v[96:99], v[142:145], v[202:205], v[96:99]
	v_mfma_f32_16x16x32_bf16 v[92:95], v[146:149], v[166:169], v[92:95]
	v_mfma_f32_16x16x32_bf16 v[88:91], v[154:157], v[166:169], v[88:91]
	v_mfma_f32_16x16x32_bf16 v[84:87], v[146:149], v[182:185], v[84:87]
	v_mfma_f32_16x16x32_bf16 v[80:83], v[154:157], v[182:185], v[80:83]
	v_mfma_f32_16x16x32_bf16 v[76:79], v[146:149], v[190:193], v[76:79]
	v_mfma_f32_16x16x32_bf16 v[72:75], v[154:157], v[190:193], v[72:75]
	v_mfma_f32_16x16x32_bf16 v[68:71], v[146:149], v[198:201], v[68:71]
	v_mfma_f32_16x16x32_bf16 v[64:67], v[154:157], v[198:201], v[64:67]
	v_mfma_f32_16x16x32_bf16 v[92:95], v[150:153], v[178:181], v[92:95]
	v_mfma_f32_16x16x32_bf16 v[88:91], v[162:165], v[178:181], v[88:91]
	v_mfma_f32_16x16x32_bf16 v[84:87], v[150:153], v[186:189], v[84:87]
	v_mfma_f32_16x16x32_bf16 v[80:83], v[162:165], v[186:189], v[80:83]
	v_mfma_f32_16x16x32_bf16 v[76:79], v[150:153], v[194:197], v[76:79]
	v_mfma_f32_16x16x32_bf16 v[72:75], v[162:165], v[194:197], v[72:75]
	v_mfma_f32_16x16x32_bf16 v[68:71], v[150:153], v[202:205], v[68:71]
	v_mfma_f32_16x16x32_bf16 v[64:67], v[162:165], v[202:205], v[64:67]
	s_barrier
	s_add_u32 s24, s59, s50
	s_addc_u32 s25, s68, s51
	s_add_u32 s26, s69, s50
	s_addc_u32 s27, s70, s51
	ds_read_b128 v[166:169], v175 offset:49152
	ds_read_b128 v[178:181], v175 offset:50176
	ds_read_b128 v[182:185], v175 offset:51200
	ds_read_b128 v[186:189], v175 offset:52224
	ds_read_b128 v[190:193], v175 offset:53248
	ds_read_b128 v[194:197], v175 offset:54272
	ds_read_b128 v[198:201], v175 offset:55296
	ds_read_b128 v[202:205], v175 offset:56320
	s_mov_b32 m0, s9
	s_nop 0
	global_load_lds_dwordx4 v129, s[24:25]
	s_add_u32 s24, s13, s50
	s_addc_u32 s25, s19, s51
	s_mov_b32 m0, s80
	s_nop 0
	global_load_lds_dwordx4 v129, s[26:27]
	s_add_u32 s26, s33, s50
	s_addc_u32 s27, s58, s51
	s_mov_b32 m0, s83
	s_nop 0
	global_load_lds_dwordx4 v129, s[24:25]
	s_add_u32 s24, s91, s50
	s_mov_b32 m0, s84
	s_nop 0
	global_load_lds_dwordx4 v129, s[26:27]
	s_addc_u32 s25, s92, s51
	s_add_u32 s26, s93, s50
	s_mov_b32 m0, s81
	s_nop 0
	global_load_lds_dwordx4 v128, s[24:25]
	s_addc_u32 s27, s94, s51
	s_mov_b32 m0, s82
	s_nop 0
	global_load_lds_dwordx4 v128, s[26:27]
	s_waitcnt vmcnt(8)
	s_waitcnt lgkmcnt(0)
	s_barrier
	s_waitcnt lgkmcnt(7)
	v_mfma_f32_16x16x32_bf16 v[60:63], v[130:133], v[166:169], v[60:63]
	v_mfma_f32_16x16x32_bf16 v[56:59], v[138:141], v[166:169], v[56:59]
	s_waitcnt lgkmcnt(5)
	v_mfma_f32_16x16x32_bf16 v[52:55], v[130:133], v[182:185], v[52:55]
	v_mfma_f32_16x16x32_bf16 v[48:51], v[138:141], v[182:185], v[48:51]
	s_waitcnt lgkmcnt(3)
	v_mfma_f32_16x16x32_bf16 v[44:47], v[130:133], v[190:193], v[44:47]
	v_mfma_f32_16x16x32_bf16 v[40:43], v[138:141], v[190:193], v[40:43]
	s_waitcnt lgkmcnt(1)
	v_mfma_f32_16x16x32_bf16 v[36:39], v[130:133], v[198:201], v[36:39]
	v_mfma_f32_16x16x32_bf16 v[32:35], v[138:141], v[198:201], v[32:35]
	v_mfma_f32_16x16x32_bf16 v[60:63], v[134:137], v[178:181], v[60:63]
	v_mfma_f32_16x16x32_bf16 v[56:59], v[142:145], v[178:181], v[56:59]
	v_mfma_f32_16x16x32_bf16 v[52:55], v[134:137], v[186:189], v[52:55]
	v_mfma_f32_16x16x32_bf16 v[48:51], v[142:145], v[186:189], v[48:51]
	v_mfma_f32_16x16x32_bf16 v[44:47], v[134:137], v[194:197], v[44:47]
	v_mfma_f32_16x16x32_bf16 v[40:43], v[142:145], v[194:197], v[40:43]
	s_waitcnt lgkmcnt(0)
	v_mfma_f32_16x16x32_bf16 v[36:39], v[134:137], v[202:205], v[36:39]
	v_mfma_f32_16x16x32_bf16 v[32:35], v[142:145], v[202:205], v[32:35]
	v_mfma_f32_16x16x32_bf16 v[28:31], v[146:149], v[166:169], v[28:31]
	v_mfma_f32_16x16x32_bf16 v[24:27], v[154:157], v[166:169], v[24:27]
	v_mfma_f32_16x16x32_bf16 v[20:23], v[146:149], v[182:185], v[20:23]
	v_mfma_f32_16x16x32_bf16 v[16:19], v[154:157], v[182:185], v[16:19]
	v_mfma_f32_16x16x32_bf16 v[12:15], v[146:149], v[190:193], v[12:15]
	v_mfma_f32_16x16x32_bf16 v[8:11], v[154:157], v[190:193], v[8:11]
	v_mfma_f32_16x16x32_bf16 v[4:7], v[146:149], v[198:201], v[4:7]
	v_mfma_f32_16x16x32_bf16 v[0:3], v[154:157], v[198:201], v[0:3]
	v_mfma_f32_16x16x32_bf16 v[28:31], v[150:153], v[178:181], v[28:31]
	v_mfma_f32_16x16x32_bf16 v[24:27], v[162:165], v[178:181], v[24:27]
	v_mfma_f32_16x16x32_bf16 v[20:23], v[150:153], v[186:189], v[20:23]
	v_mfma_f32_16x16x32_bf16 v[16:19], v[162:165], v[186:189], v[16:19]
	v_mfma_f32_16x16x32_bf16 v[12:15], v[150:153], v[194:197], v[12:15]
	v_mfma_f32_16x16x32_bf16 v[8:11], v[162:165], v[194:197], v[8:11]
	v_mfma_f32_16x16x32_bf16 v[4:7], v[150:153], v[202:205], v[4:7]
	v_mfma_f32_16x16x32_bf16 v[0:3], v[162:165], v[202:205], v[0:3]
	s_barrier
	s_add_u32 s50, s50, s48
	s_addc_u32 s51, s51, s49
	s_cmp_ge_i32 s79, s10
	s_cbranch_scc0 .LBB0_1018
	s_branch .Lkloop_exit_1018
.Lhf_1018:
	ds_read_b128 v[130:133], v173
	ds_read_b128 v[134:137], v173 offset:1024
	ds_read_b128 v[138:141], v173 offset:2048
	ds_read_b128 v[142:145], v173 offset:3072
	ds_read_b128 v[146:149], v174
	ds_read_b128 v[150:153], v174 offset:1024
	ds_read_b128 v[154:157], v174 offset:2048
	ds_read_b128 v[162:165], v174 offset:3072
	s_add_i32 s79, s79, 2
	s_add_u32 s54, vcc_hi, s50
	s_addc_u32 s55, s61, s51
	ds_read_b128 v[166:169], v175
	ds_read_b128 v[178:181], v175 offset:1024
	ds_read_b128 v[182:185], v175 offset:2048
	ds_read_b128 v[186:189], v175 offset:3072
	ds_read_b128 v[190:193], v175 offset:4096
	ds_read_b128 v[194:197], v175 offset:5120
	ds_read_b128 v[198:201], v175 offset:6144
	ds_read_b128 v[202:205], v175 offset:7168
	s_add_u32 s24, s60, s50
	s_addc_u32 s25, s78, s51
	s_add_u32 s26, s40, s50
	s_mov_b32 m0, s85
	s_nop 0
	global_load_lds_dwordx4 v128, s[24:25]
	s_addc_u32 s27, s41, s51
	s_mov_b32 m0, s86
	s_nop 0
	global_load_lds_dwordx4 v128, s[26:27]
	s_waitcnt vmcnt(8)
	s_waitcnt lgkmcnt(0)
	s_barrier
	s_waitcnt lgkmcnt(7)
	v_mfma_f32_16x16x32_bf16 v[124:127], v[130:133], v[166:169], 0
	v_mfma_f32_16x16x32_bf16 v[120:123], v[138:141], v[166:169], 0
	s_waitcnt lgkmcnt(5)
	v_mfma_f32_16x16x32_bf16 v[116:119], v[130:133], v[182:185], 0
	v_mfma_f32_16x16x32_bf16 v[112:115], v[138:141], v[182:185], 0
	s_waitcnt lgkmcnt(3)
	v_mfma_f32_16x16x32_bf16 v[108:111], v[130:133], v[190:193], 0
	v_mfma_f32_16x16x32_bf16 v[104:107], v[138:141], v[190:193], 0
	s_waitcnt lgkmcnt(1)
	v_mfma_f32_16x16x32_bf16 v[100:103], v[130:133], v[198:201], 0
	v_mfma_f32_16x16x32_bf16 v[96:99], v[138:141], v[198:201], 0
	v_mfma_f32_16x16x32_bf16 v[124:127], v[134:137], v[178:181], v[124:127]
	v_mfma_f32_16x16x32_bf16 v[120:123], v[142:145], v[178:181], v[120:123]
	v_mfma_f32_16x16x32_bf16 v[116:119], v[134:137], v[186:189], v[116:119]
	v_mfma_f32_16x16x32_bf16 v[112:115], v[142:145], v[186:189], v[112:115]
	v_mfma_f32_16x16x32_bf16 v[108:111], v[134:137], v[194:197], v[108:111]
	v_mfma_f32_16x16x32_bf16 v[104:107], v[142:145], v[194:197], v[104:107]
	s_waitcnt lgkmcnt(0)
	v_mfma_f32_16x16x32_bf16 v[100:103], v[134:137], v[202:205], v[100:103]
	v_mfma_f32_16x16x32_bf16 v[96:99], v[142:145], v[202:205], v[96:99]
	v_mfma_f32_16x16x32_bf16 v[92:95], v[146:149], v[166:169], 0
	v_mfma_f32_16x16x32_bf16 v[88:91], v[154:157], v[166:169], 0
	v_mfma_f32_16x16x32_bf16 v[84:87], v[146:149], v[182:185], 0
	v_mfma_f32_16x16x32_bf16 v[80:83], v[154:157], v[182:185], 0
	v_mfma_f32_16x16x32_bf16 v[76:79], v[146:149], v[190:193], 0
	v_mfma_f32_16x16x32_bf16 v[72:75], v[154:157], v[190:193], 0
	v_mfma_f32_16x16x32_bf16 v[68:71], v[146:149], v[198:201], 0
	v_mfma_f32_16x16x32_bf16 v[64:67], v[154:157], v[198:201], 0
	v_mfma_f32_16x16x32_bf16 v[92:95], v[150:153], v[178:181], v[92:95]
	v_mfma_f32_16x16x32_bf16 v[88:91], v[162:165], v[178:181], v[88:91]
	v_mfma_f32_16x16x32_bf16 v[84:87], v[150:153], v[186:189], v[84:87]
	v_mfma_f32_16x16x32_bf16 v[80:83], v[162:165], v[186:189], v[80:83]
	v_mfma_f32_16x16x32_bf16 v[76:79], v[150:153], v[194:197], v[76:79]
	v_mfma_f32_16x16x32_bf16 v[72:75], v[162:165], v[194:197], v[72:75]
	v_mfma_f32_16x16x32_bf16 v[68:71], v[150:153], v[202:205], v[68:71]
	v_mfma_f32_16x16x32_bf16 v[64:67], v[162:165], v[202:205], v[64:67]
	s_barrier
	s_add_u32 s24, s87, s50
	s_addc_u32 s25, s88, s51
	s_add_u32 s26, s89, s50
	ds_read_b128 v[166:169], v175 offset:16384
	ds_read_b128 v[178:181], v175 offset:17408
	ds_read_b128 v[182:185], v175 offset:18432
	ds_read_b128 v[186:189], v175 offset:19456
	ds_read_b128 v[190:193], v175 offset:20480
	ds_read_b128 v[194:197], v175 offset:21504
	ds_read_b128 v[198:201], v175 offset:22528
	ds_read_b128 v[202:205], v175 offset:23552
	s_addc_u32 s27, s90, s51
	s_mov_b32 m0, s62
	s_nop 0
	global_load_lds_dwordx4 v129, s[24:25]
	s_add_u32 s24, s71, s50
	s_mov_b32 m0, s63
	s_nop 0
	global_load_lds_dwordx4 v129, s[26:27]
	s_addc_u32 s25, s72, s51
	s_add_u32 s26, s74, s50
	s_mov_b32 m0, s64
	s_nop 0
	global_load_lds_dwordx4 v129, s[24:25]
	s_addc_u32 s27, s75, s51
	s_mov_b32 m0, s65
	s_nop 0
	global_load_lds_dwordx4 v129, s[26:27]
	s_add_u32 s24, s36, s50
	s_mov_b32 m0, s3
	s_nop 0
	global_load_lds_dwordx4 v128, s[54:55]
	s_addc_u32 s25, s37, s51
	s_mov_b32 m0, s66
	s_nop 0
	global_load_lds_dwordx4 v128, s[24:25]
	s_waitcnt vmcnt(8)
	s_waitcnt lgkmcnt(0)
	s_barrier
	s_waitcnt lgkmcnt(7)
	v_mfma_f32_16x16x32_bf16 v[60:63], v[130:133], v[166:169], 0
	v_mfma_f32_16x16x32_bf16 v[56:59], v[138:141], v[166:169], 0
	s_waitcnt lgkmcnt(5)
	v_mfma_f32_16x16x32_bf16 v[52:55], v[130:133], v[182:185], 0
	v_mfma_f32_16x16x32_bf16 v[48:51], v[138:141], v[182:185], 0
	s_waitcnt lgkmcnt(3)
	v_mfma_f32_16x16x32_bf16 v[44:47], v[130:133], v[190:193], 0
	v_mfma_f32_16x16x32_bf16 v[40:43], v[138:141], v[190:193], 0
	s_waitcnt lgkmcnt(1)
	v_mfma_f32_16x16x32_bf16 v[36:39], v[130:133], v[198:201], 0
	v_mfma_f32_16x16x32_bf16 v[32:35], v[138:141], v[198:201], 0
	v_mfma_f32_16x16x32_bf16 v[60:63], v[134:137], v[178:181], v[60:63]
	v_mfma_f32_16x16x32_bf16 v[56:59], v[142:145], v[178:181], v[56:59]
	v_mfma_f32_16x16x32_bf16 v[52:55], v[134:137], v[186:189], v[52:55]
	v_mfma_f32_16x16x32_bf16 v[48:51], v[142:145], v[186:189], v[48:51]
	v_mfma_f32_16x16x32_bf16 v[44:47], v[134:137], v[194:197], v[44:47]
	v_mfma_f32_16x16x32_bf16 v[40:43], v[142:145], v[194:197], v[40:43]
	s_waitcnt lgkmcnt(0)
	v_mfma_f32_16x16x32_bf16 v[36:39], v[134:137], v[202:205], v[36:39]
	v_mfma_f32_16x16x32_bf16 v[32:35], v[142:145], v[202:205], v[32:35]
	v_mfma_f32_16x16x32_bf16 v[28:31], v[146:149], v[166:169], 0
	v_mfma_f32_16x16x32_bf16 v[24:27], v[154:157], v[166:169], 0
	v_mfma_f32_16x16x32_bf16 v[20:23], v[146:149], v[182:185], 0
	v_mfma_f32_16x16x32_bf16 v[16:19], v[154:157], v[182:185], 0
	v_mfma_f32_16x16x32_bf16 v[12:15], v[146:149], v[190:193], 0
	v_mfma_f32_16x16x32_bf16 v[8:11], v[154:157], v[190:193], 0
	v_mfma_f32_16x16x32_bf16 v[4:7], v[146:149], v[198:201], 0
	v_mfma_f32_16x16x32_bf16 v[0:3], v[154:157], v[198:201], 0
	v_mfma_f32_16x16x32_bf16 v[28:31], v[150:153], v[178:181], v[28:31]
	v_mfma_f32_16x16x32_bf16 v[24:27], v[162:165], v[178:181], v[24:27]
	v_mfma_f32_16x16x32_bf16 v[20:23], v[150:153], v[186:189], v[20:23]
	v_mfma_f32_16x16x32_bf16 v[16:19], v[162:165], v[186:189], v[16:19]
	v_mfma_f32_16x16x32_bf16 v[12:15], v[150:153], v[194:197], v[12:15]
	v_mfma_f32_16x16x32_bf16 v[8:11], v[162:165], v[194:197], v[8:11]
	v_mfma_f32_16x16x32_bf16 v[4:7], v[150:153], v[202:205], v[4:7]
	v_mfma_f32_16x16x32_bf16 v[0:3], v[162:165], v[202:205], v[0:3]
	s_barrier
	ds_read_b128 v[130:133], v176
	ds_read_b128 v[134:137], v176 offset:1024
	ds_read_b128 v[138:141], v176 offset:2048
	ds_read_b128 v[142:145], v176 offset:3072
	ds_read_b128 v[146:149], v177
	ds_read_b128 v[150:153], v177 offset:1024
	ds_read_b128 v[154:157], v177 offset:2048
	ds_read_b128 v[162:165], v177 offset:3072
	ds_read_b128 v[166:169], v175 offset:32768
	ds_read_b128 v[178:181], v175 offset:33792
	ds_read_b128 v[182:185], v175 offset:34816
	ds_read_b128 v[186:189], v175 offset:35840
	ds_read_b128 v[190:193], v175 offset:36864
	ds_read_b128 v[194:197], v175 offset:37888
	ds_read_b128 v[198:201], v175 offset:38912
	ds_read_b128 v[202:205], v175 offset:39936
	s_add_u32 s24, s95, s50
	s_addc_u32 s25, s96, s51
	s_add_u32 s26, s97, s50
	s_mov_b32 m0, s67
	s_nop 0
	global_load_lds_dwordx4 v128, s[24:25]
	s_addc_u32 s27, vcc_lo, s51
	s_mov_b32 m0, s73
	s_nop 0
	global_load_lds_dwordx4 v128, s[26:27]
	s_waitcnt vmcnt(8)
	s_waitcnt lgkmcnt(0)
	s_barrier
	s_waitcnt lgkmcnt(7)
	v_mfma_f32_16x16x32_bf16 v[124:127], v[130:133], v[166:169], v[124:127]
	v_mfma_f32_16x16x32_bf16 v[120:123], v[138:141], v[166:169], v[120:123]
	s_waitcnt lgkmcnt(5)
	v_mfma_f32_16x16x32_bf16 v[116:119], v[130:133], v[182:185], v[116:119]
	v_mfma_f32_16x16x32_bf16 v[112:115], v[138:141], v[182:185], v[112:115]
	s_waitcnt lgkmcnt(3)
	v_mfma_f32_16x16x32_bf16 v[108:111], v[130:133], v[190:193], v[108:111]
	v_mfma_f32_16x16x32_bf16 v[104:107], v[138:141], v[190:193], v[104:107]
	s_waitcnt lgkmcnt(1)
	v_mfma_f32_16x16x32_bf16 v[100:103], v[130:133], v[198:201], v[100:103]
	v_mfma_f32_16x16x32_bf16 v[96:99], v[138:141], v[198:201], v[96:99]
	v_mfma_f32_16x16x32_bf16 v[124:127], v[134:137], v[178:181], v[124:127]
	v_mfma_f32_16x16x32_bf16 v[120:123], v[142:145], v[178:181], v[120:123]
	v_mfma_f32_16x16x32_bf16 v[116:119], v[134:137], v[186:189], v[116:119]
	v_mfma_f32_16x16x32_bf16 v[112:115], v[142:145], v[186:189], v[112:115]
	v_mfma_f32_16x16x32_bf16 v[108:111], v[134:137], v[194:197], v[108:111]
	v_mfma_f32_16x16x32_bf16 v[104:107], v[142:145], v[194:197], v[104:107]
	s_waitcnt lgkmcnt(0)
	v_mfma_f32_16x16x32_bf16 v[100:103], v[134:137], v[202:205], v[100:103]
	v_mfma_f32_16x16x32_bf16 v[96:99], v[142:145], v[202:205], v[96:99]
	v_mfma_f32_16x16x32_bf16 v[92:95], v[146:149], v[166:169], v[92:95]
	v_mfma_f32_16x16x32_bf16 v[88:91], v[154:157], v[166:169], v[88:91]
	v_mfma_f32_16x16x32_bf16 v[84:87], v[146:149], v[182:185], v[84:87]
	v_mfma_f32_16x16x32_bf16 v[80:83], v[154:157], v[182:185], v[80:83]
	v_mfma_f32_16x16x32_bf16 v[76:79], v[146:149], v[190:193], v[76:79]
	v_mfma_f32_16x16x32_bf16 v[72:75], v[154:157], v[190:193], v[72:75]
	v_mfma_f32_16x16x32_bf16 v[68:71], v[146:149], v[198:201], v[68:71]
	v_mfma_f32_16x16x32_bf16 v[64:67], v[154:157], v[198:201], v[64:67]
	v_mfma_f32_16x16x32_bf16 v[92:95], v[150:153], v[178:181], v[92:95]
	v_mfma_f32_16x16x32_bf16 v[88:91], v[162:165], v[178:181], v[88:91]
	v_mfma_f32_16x16x32_bf16 v[84:87], v[150:153], v[186:189], v[84:87]
	v_mfma_f32_16x16x32_bf16 v[80:83], v[162:165], v[186:189], v[80:83]
	v_mfma_f32_16x16x32_bf16 v[76:79], v[150:153], v[194:197], v[76:79]
	v_mfma_f32_16x16x32_bf16 v[72:75], v[162:165], v[194:197], v[72:75]
	v_mfma_f32_16x16x32_bf16 v[68:71], v[150:153], v[202:205], v[68:71]
	v_mfma_f32_16x16x32_bf16 v[64:67], v[162:165], v[202:205], v[64:67]
	s_barrier
	s_add_u32 s24, s59, s50
	s_addc_u32 s25, s68, s51
	s_add_u32 s26, s69, s50
	s_addc_u32 s27, s70, s51
	ds_read_b128 v[166:169], v175 offset:49152
	ds_read_b128 v[178:181], v175 offset:50176
	ds_read_b128 v[182:185], v175 offset:51200
	ds_read_b128 v[186:189], v175 offset:52224
	ds_read_b128 v[190:193], v175 offset:53248
	ds_read_b128 v[194:197], v175 offset:54272
	ds_read_b128 v[198:201], v175 offset:55296
	ds_read_b128 v[202:205], v175 offset:56320
	s_mov_b32 m0, s9
	s_nop 0
	global_load_lds_dwordx4 v129, s[24:25]
	s_add_u32 s24, s13, s50
	s_addc_u32 s25, s19, s51
	s_mov_b32 m0, s80
	s_nop 0
	global_load_lds_dwordx4 v129, s[26:27]
	s_add_u32 s26, s33, s50
	s_addc_u32 s27, s58, s51
	s_mov_b32 m0, s83
	s_nop 0
	global_load_lds_dwordx4 v129, s[24:25]
	s_add_u32 s24, s91, s50
	s_mov_b32 m0, s84
	s_nop 0
	global_load_lds_dwordx4 v129, s[26:27]
	s_addc_u32 s25, s92, s51
	s_add_u32 s26, s93, s50
	s_mov_b32 m0, s81
	s_nop 0
	global_load_lds_dwordx4 v128, s[24:25]
	s_addc_u32 s27, s94, s51
	s_mov_b32 m0, s82
	s_nop 0
	global_load_lds_dwordx4 v128, s[26:27]
	s_waitcnt vmcnt(8)
	s_waitcnt lgkmcnt(0)
	s_barrier
	s_waitcnt lgkmcnt(7)
	v_mfma_f32_16x16x32_bf16 v[60:63], v[130:133], v[166:169], v[60:63]
	v_mfma_f32_16x16x32_bf16 v[56:59], v[138:141], v[166:169], v[56:59]
	s_waitcnt lgkmcnt(5)
	v_mfma_f32_16x16x32_bf16 v[52:55], v[130:133], v[182:185], v[52:55]
	v_mfma_f32_16x16x32_bf16 v[48:51], v[138:141], v[182:185], v[48:51]
	s_waitcnt lgkmcnt(3)
	v_mfma_f32_16x16x32_bf16 v[44:47], v[130:133], v[190:193], v[44:47]
	v_mfma_f32_16x16x32_bf16 v[40:43], v[138:141], v[190:193], v[40:43]
	s_waitcnt lgkmcnt(1)
	v_mfma_f32_16x16x32_bf16 v[36:39], v[130:133], v[198:201], v[36:39]
	v_mfma_f32_16x16x32_bf16 v[32:35], v[138:141], v[198:201], v[32:35]
	v_mfma_f32_16x16x32_bf16 v[60:63], v[134:137], v[178:181], v[60:63]
	v_mfma_f32_16x16x32_bf16 v[56:59], v[142:145], v[178:181], v[56:59]
	v_mfma_f32_16x16x32_bf16 v[52:55], v[134:137], v[186:189], v[52:55]
	v_mfma_f32_16x16x32_bf16 v[48:51], v[142:145], v[186:189], v[48:51]
	v_mfma_f32_16x16x32_bf16 v[44:47], v[134:137], v[194:197], v[44:47]
	v_mfma_f32_16x16x32_bf16 v[40:43], v[142:145], v[194:197], v[40:43]
	s_waitcnt lgkmcnt(0)
	v_mfma_f32_16x16x32_bf16 v[36:39], v[134:137], v[202:205], v[36:39]
	v_mfma_f32_16x16x32_bf16 v[32:35], v[142:145], v[202:205], v[32:35]
	v_mfma_f32_16x16x32_bf16 v[28:31], v[146:149], v[166:169], v[28:31]
	v_mfma_f32_16x16x32_bf16 v[24:27], v[154:157], v[166:169], v[24:27]
	v_mfma_f32_16x16x32_bf16 v[20:23], v[146:149], v[182:185], v[20:23]
	v_mfma_f32_16x16x32_bf16 v[16:19], v[154:157], v[182:185], v[16:19]
	v_mfma_f32_16x16x32_bf16 v[12:15], v[146:149], v[190:193], v[12:15]
	v_mfma_f32_16x16x32_bf16 v[8:11], v[154:157], v[190:193], v[8:11]
	v_mfma_f32_16x16x32_bf16 v[4:7], v[146:149], v[198:201], v[4:7]
	v_mfma_f32_16x16x32_bf16 v[0:3], v[154:157], v[198:201], v[0:3]
	v_mfma_f32_16x16x32_bf16 v[28:31], v[150:153], v[178:181], v[28:31]
	v_mfma_f32_16x16x32_bf16 v[24:27], v[162:165], v[178:181], v[24:27]
	v_mfma_f32_16x16x32_bf16 v[20:23], v[150:153], v[186:189], v[20:23]
	v_mfma_f32_16x16x32_bf16 v[16:19], v[162:165], v[186:189], v[16:19]
	v_mfma_f32_16x16x32_bf16 v[12:15], v[150:153], v[194:197], v[12:15]
	v_mfma_f32_16x16x32_bf16 v[8:11], v[162:165], v[194:197], v[8:11]
	v_mfma_f32_16x16x32_bf16 v[4:7], v[150:153], v[202:205], v[4:7]
	v_mfma_f32_16x16x32_bf16 v[0:3], v[162:165], v[202:205], v[0:3]
	s_barrier
	s_add_u32 s50, s50, s48
	s_addc_u32 s51, s51, s49
	s_cmp_ge_i32 s79, s10
	s_cbranch_scc0 .LBB0_1018
	s_branch .Lkloop_exit_1018

.LBB0_1018:
	ds_read_b128 v[130:133], v173
	ds_read_b128 v[134:137], v173 offset:1024
	ds_read_b128 v[138:141], v173 offset:2048
	ds_read_b128 v[142:145], v173 offset:3072
	ds_read_b128 v[146:149], v174
	ds_read_b128 v[150:153], v174 offset:1024
	ds_read_b128 v[154:157], v174 offset:2048
	ds_read_b128 v[162:165], v174 offset:3072
	s_add_i32 s79, s79, 2
	s_add_u32 s54, vcc_hi, s50
	s_addc_u32 s55, s61, s51
	ds_read_b128 v[166:169], v175
	ds_read_b128 v[178:181], v175 offset:1024
	ds_read_b128 v[182:185], v175 offset:2048
	ds_read_b128 v[186:189], v175 offset:3072
	ds_read_b128 v[190:193], v175 offset:4096
	ds_read_b128 v[194:197], v175 offset:5120
	ds_read_b128 v[198:201], v175 offset:6144
	ds_read_b128 v[202:205], v175 offset:7168
	s_add_u32 s24, s60, s50
	s_addc_u32 s25, s78, s51
	s_add_u32 s26, s40, s50
	s_mov_b32 m0, s85
	s_nop 0
	global_load_lds_dwordx4 v128, s[24:25]
	s_addc_u32 s27, s41, s51
	s_mov_b32 m0, s86
	s_nop 0
	global_load_lds_dwordx4 v128, s[26:27]
	s_waitcnt vmcnt(8)
	s_waitcnt lgkmcnt(0)
	s_barrier
	s_waitcnt lgkmcnt(7)
	v_mfma_f32_16x16x32_bf16 v[124:127], v[130:133], v[166:169], v[124:127]
	v_mfma_f32_16x16x32_bf16 v[120:123], v[138:141], v[166:169], v[120:123]
	s_waitcnt lgkmcnt(5)
	v_mfma_f32_16x16x32_bf16 v[116:119], v[130:133], v[182:185], v[116:119]
	v_mfma_f32_16x16x32_bf16 v[112:115], v[138:141], v[182:185], v[112:115]
	s_waitcnt lgkmcnt(3)
	v_mfma_f32_16x16x32_bf16 v[108:111], v[130:133], v[190:193], v[108:111]
	v_mfma_f32_16x16x32_bf16 v[104:107], v[138:141], v[190:193], v[104:107]
	s_waitcnt lgkmcnt(1)
	v_mfma_f32_16x16x32_bf16 v[100:103], v[130:133], v[198:201], v[100:103]
	v_mfma_f32_16x16x32_bf16 v[96:99], v[138:141], v[198:201], v[96:99]
	v_mfma_f32_16x16x32_bf16 v[124:127], v[134:137], v[178:181], v[124:127]
	v_mfma_f32_16x16x32_bf16 v[120:123], v[142:145], v[178:181], v[120:123]
	v_mfma_f32_16x16x32_bf16 v[116:119], v[134:137], v[186:189], v[116:119]
	v_mfma_f32_16x16x32_bf16 v[112:115], v[142:145], v[186:189], v[112:115]
	v_mfma_f32_16x16x32_bf16 v[108:111], v[134:137], v[194:197], v[108:111]
	v_mfma_f32_16x16x32_bf16 v[104:107], v[142:145], v[194:197], v[104:107]
	s_waitcnt lgkmcnt(0)
	v_mfma_f32_16x16x32_bf16 v[100:103], v[134:137], v[202:205], v[100:103]
	v_mfma_f32_16x16x32_bf16 v[96:99], v[142:145], v[202:205], v[96:99]
	v_mfma_f32_16x16x32_bf16 v[92:95], v[146:149], v[166:169], v[92:95]
	v_mfma_f32_16x16x32_bf16 v[88:91], v[154:157], v[166:169], v[88:91]
	v_mfma_f32_16x16x32_bf16 v[84:87], v[146:149], v[182:185], v[84:87]
	v_mfma_f32_16x16x32_bf16 v[80:83], v[154:157], v[182:185], v[80:83]
	v_mfma_f32_16x16x32_bf16 v[76:79], v[146:149], v[190:193], v[76:79]
	v_mfma_f32_16x16x32_bf16 v[72:75], v[154:157], v[190:193], v[72:75]
	v_mfma_f32_16x16x32_bf16 v[68:71], v[146:149], v[198:201], v[68:71]
	v_mfma_f32_16x16x32_bf16 v[64:67], v[154:157], v[198:201], v[64:67]
	v_mfma_f32_16x16x32_bf16 v[92:95], v[150:153], v[178:181], v[92:95]
	v_mfma_f32_16x16x32_bf16 v[88:91], v[162:165], v[178:181], v[88:91]
	v_mfma_f32_16x16x32_bf16 v[84:87], v[150:153], v[186:189], v[84:87]
	v_mfma_f32_16x16x32_bf16 v[80:83], v[162:165], v[186:189], v[80:83]
	v_mfma_f32_16x16x32_bf16 v[76:79], v[150:153], v[194:197], v[76:79]
	v_mfma_f32_16x16x32_bf16 v[72:75], v[162:165], v[194:197], v[72:75]
	v_mfma_f32_16x16x32_bf16 v[68:71], v[150:153], v[202:205], v[68:71]
	v_mfma_f32_16x16x32_bf16 v[64:67], v[162:165], v[202:205], v[64:67]
	s_barrier
	s_add_u32 s24, s87, s50
	s_addc_u32 s25, s88, s51
	s_add_u32 s26, s89, s50
	ds_read_b128 v[166:169], v175 offset:16384
	ds_read_b128 v[178:181], v175 offset:17408
	ds_read_b128 v[182:185], v175 offset:18432
	ds_read_b128 v[186:189], v175 offset:19456
	ds_read_b128 v[190:193], v175 offset:20480
	ds_read_b128 v[194:197], v175 offset:21504
	ds_read_b128 v[198:201], v175 offset:22528
	ds_read_b128 v[202:205], v175 offset:23552
	s_addc_u32 s27, s90, s51
	s_mov_b32 m0, s62
	s_nop 0
	global_load_lds_dwordx4 v129, s[24:25]
	s_add_u32 s24, s71, s50
	s_mov_b32 m0, s63
	s_nop 0
	global_load_lds_dwordx4 v129, s[26:27]
	s_addc_u32 s25, s72, s51
	s_add_u32 s26, s74, s50
	s_mov_b32 m0, s64
	s_nop 0
	global_load_lds_dwordx4 v129, s[24:25]
	s_addc_u32 s27, s75, s51
	s_mov_b32 m0, s65
	s_nop 0
	global_load_lds_dwordx4 v129, s[26:27]
	s_add_u32 s24, s36, s50
	s_mov_b32 m0, s3
	s_nop 0
	global_load_lds_dwordx4 v128, s[54:55]
	s_addc_u32 s25, s37, s51
	s_mov_b32 m0, s66
	s_nop 0
	global_load_lds_dwordx4 v128, s[24:25]
	s_waitcnt vmcnt(8)
	s_waitcnt lgkmcnt(0)
	s_barrier
	s_waitcnt lgkmcnt(7)
	v_mfma_f32_16x16x32_bf16 v[60:63], v[130:133], v[166:169], v[60:63]
	v_mfma_f32_16x16x32_bf16 v[56:59], v[138:141], v[166:169], v[56:59]
	s_waitcnt lgkmcnt(5)
	v_mfma_f32_16x16x32_bf16 v[52:55], v[130:133], v[182:185], v[52:55]
	v_mfma_f32_16x16x32_bf16 v[48:51], v[138:141], v[182:185], v[48:51]
	s_waitcnt lgkmcnt(3)
	v_mfma_f32_16x16x32_bf16 v[44:47], v[130:133], v[190:193], v[44:47]
	v_mfma_f32_16x16x32_bf16 v[40:43], v[138:141], v[190:193], v[40:43]
	s_waitcnt lgkmcnt(1)
	v_mfma_f32_16x16x32_bf16 v[36:39], v[130:133], v[198:201], v[36:39]
	v_mfma_f32_16x16x32_bf16 v[32:35], v[138:141], v[198:201], v[32:35]
	v_mfma_f32_16x16x32_bf16 v[60:63], v[134:137], v[178:181], v[60:63]
	v_mfma_f32_16x16x32_bf16 v[56:59], v[142:145], v[178:181], v[56:59]
	v_mfma_f32_16x16x32_bf16 v[52:55], v[134:137], v[186:189], v[52:55]
	v_mfma_f32_16x16x32_bf16 v[48:51], v[142:145], v[186:189], v[48:51]
	v_mfma_f32_16x16x32_bf16 v[44:47], v[134:137], v[194:197], v[44:47]
	v_mfma_f32_16x16x32_bf16 v[40:43], v[142:145], v[194:197], v[40:43]
	s_waitcnt lgkmcnt(0)
	v_mfma_f32_16x16x32_bf16 v[36:39], v[134:137], v[202:205], v[36:39]
	v_mfma_f32_16x16x32_bf16 v[32:35], v[142:145], v[202:205], v[32:35]
	v_mfma_f32_16x16x32_bf16 v[28:31], v[146:149], v[166:169], v[28:31]
	v_mfma_f32_16x16x32_bf16 v[24:27], v[154:157], v[166:169], v[24:27]
	v_mfma_f32_16x16x32_bf16 v[20:23], v[146:149], v[182:185], v[20:23]
	v_mfma_f32_16x16x32_bf16 v[16:19], v[154:157], v[182:185], v[16:19]
	v_mfma_f32_16x16x32_bf16 v[12:15], v[146:149], v[190:193], v[12:15]
	v_mfma_f32_16x16x32_bf16 v[8:11], v[154:157], v[190:193], v[8:11]
	v_mfma_f32_16x16x32_bf16 v[4:7], v[146:149], v[198:201], v[4:7]
	v_mfma_f32_16x16x32_bf16 v[0:3], v[154:157], v[198:201], v[0:3]
	v_mfma_f32_16x16x32_bf16 v[28:31], v[150:153], v[178:181], v[28:31]
	v_mfma_f32_16x16x32_bf16 v[24:27], v[162:165], v[178:181], v[24:27]
	v_mfma_f32_16x16x32_bf16 v[20:23], v[150:153], v[186:189], v[20:23]
	v_mfma_f32_16x16x32_bf16 v[16:19], v[162:165], v[186:189], v[16:19]
	v_mfma_f32_16x16x32_bf16 v[12:15], v[150:153], v[194:197], v[12:15]
	v_mfma_f32_16x16x32_bf16 v[8:11], v[162:165], v[194:197], v[8:11]
	v_mfma_f32_16x16x32_bf16 v[4:7], v[150:153], v[202:205], v[4:7]
	v_mfma_f32_16x16x32_bf16 v[0:3], v[162:165], v[202:205], v[0:3]
	s_barrier
	ds_read_b128 v[130:133], v176
	ds_read_b128 v[134:137], v176 offset:1024
	ds_read_b128 v[138:141], v176 offset:2048
	ds_read_b128 v[142:145], v176 offset:3072
	ds_read_b128 v[146:149], v177
	ds_read_b128 v[150:153], v177 offset:1024
	ds_read_b128 v[154:157], v177 offset:2048
	ds_read_b128 v[162:165], v177 offset:3072
	ds_read_b128 v[166:169], v175 offset:32768
	ds_read_b128 v[178:181], v175 offset:33792
	ds_read_b128 v[182:185], v175 offset:34816
	ds_read_b128 v[186:189], v175 offset:35840
	ds_read_b128 v[190:193], v175 offset:36864
	ds_read_b128 v[194:197], v175 offset:37888
	ds_read_b128 v[198:201], v175 offset:38912
	ds_read_b128 v[202:205], v175 offset:39936
	s_add_u32 s24, s95, s50
	s_addc_u32 s25, s96, s51
	s_add_u32 s26, s97, s50
	s_mov_b32 m0, s67
	s_nop 0
	global_load_lds_dwordx4 v128, s[24:25]
	s_addc_u32 s27, vcc_lo, s51
	s_mov_b32 m0, s73
	s_nop 0
	global_load_lds_dwordx4 v128, s[26:27]
	s_waitcnt vmcnt(8)
	s_waitcnt lgkmcnt(0)
	s_barrier
	s_waitcnt lgkmcnt(7)
	v_mfma_f32_16x16x32_bf16 v[124:127], v[130:133], v[166:169], v[124:127]
	v_mfma_f32_16x16x32_bf16 v[120:123], v[138:141], v[166:169], v[120:123]
	s_waitcnt lgkmcnt(5)
	v_mfma_f32_16x16x32_bf16 v[116:119], v[130:133], v[182:185], v[116:119]
	v_mfma_f32_16x16x32_bf16 v[112:115], v[138:141], v[182:185], v[112:115]
	s_waitcnt lgkmcnt(3)
	v_mfma_f32_16x16x32_bf16 v[108:111], v[130:133], v[190:193], v[108:111]
	v_mfma_f32_16x16x32_bf16 v[104:107], v[138:141], v[190:193], v[104:107]
	s_waitcnt lgkmcnt(1)
	v_mfma_f32_16x16x32_bf16 v[100:103], v[130:133], v[198:201], v[100:103]
	v_mfma_f32_16x16x32_bf16 v[96:99], v[138:141], v[198:201], v[96:99]
	v_mfma_f32_16x16x32_bf16 v[124:127], v[134:137], v[178:181], v[124:127]
	v_mfma_f32_16x16x32_bf16 v[120:123], v[142:145], v[178:181], v[120:123]
	v_mfma_f32_16x16x32_bf16 v[116:119], v[134:137], v[186:189], v[116:119]
	v_mfma_f32_16x16x32_bf16 v[112:115], v[142:145], v[186:189], v[112:115]
	v_mfma_f32_16x16x32_bf16 v[108:111], v[134:137], v[194:197], v[108:111]
	v_mfma_f32_16x16x32_bf16 v[104:107], v[142:145], v[194:197], v[104:107]
	s_waitcnt lgkmcnt(0)
	v_mfma_f32_16x16x32_bf16 v[100:103], v[134:137], v[202:205], v[100:103]
	v_mfma_f32_16x16x32_bf16 v[96:99], v[142:145], v[202:205], v[96:99]
	v_mfma_f32_16x16x32_bf16 v[92:95], v[146:149], v[166:169], v[92:95]
	v_mfma_f32_16x16x32_bf16 v[88:91], v[154:157], v[166:169], v[88:91]
	v_mfma_f32_16x16x32_bf16 v[84:87], v[146:149], v[182:185], v[84:87]
	v_mfma_f32_16x16x32_bf16 v[80:83], v[154:157], v[182:185], v[80:83]
	v_mfma_f32_16x16x32_bf16 v[76:79], v[146:149], v[190:193], v[76:79]
	v_mfma_f32_16x16x32_bf16 v[72:75], v[154:157], v[190:193], v[72:75]
	v_mfma_f32_16x16x32_bf16 v[68:71], v[146:149], v[198:201], v[68:71]
	v_mfma_f32_16x16x32_bf16 v[64:67], v[154:157], v[198:201], v[64:67]
	v_mfma_f32_16x16x32_bf16 v[92:95], v[150:153], v[178:181], v[92:95]
	v_mfma_f32_16x16x32_bf16 v[88:91], v[162:165], v[178:181], v[88:91]
	v_mfma_f32_16x16x32_bf16 v[84:87], v[150:153], v[186:189], v[84:87]
	v_mfma_f32_16x16x32_bf16 v[80:83], v[162:165], v[186:189], v[80:83]
	v_mfma_f32_16x16x32_bf16 v[76:79], v[150:153], v[194:197], v[76:79]
	v_mfma_f32_16x16x32_bf16 v[72:75], v[162:165], v[194:197], v[72:75]
	v_mfma_f32_16x16x32_bf16 v[68:71], v[150:153], v[202:205], v[68:71]
	v_mfma_f32_16x16x32_bf16 v[64:67], v[162:165], v[202:205], v[64:67]
	s_barrier
	s_add_u32 s24, s59, s50
	s_addc_u32 s25, s68, s51
	s_add_u32 s26, s69, s50
	s_addc_u32 s27, s70, s51
	ds_read_b128 v[166:169], v175 offset:49152
	ds_read_b128 v[178:181], v175 offset:50176
	ds_read_b128 v[182:185], v175 offset:51200
	ds_read_b128 v[186:189], v175 offset:52224
	ds_read_b128 v[190:193], v175 offset:53248
	ds_read_b128 v[194:197], v175 offset:54272
	ds_read_b128 v[198:201], v175 offset:55296
	ds_read_b128 v[202:205], v175 offset:56320
	s_mov_b32 m0, s9
	s_nop 0
	global_load_lds_dwordx4 v129, s[24:25]
	s_add_u32 s24, s13, s50
	s_addc_u32 s25, s19, s51
	s_mov_b32 m0, s80
	s_nop 0
	global_load_lds_dwordx4 v129, s[26:27]
	s_add_u32 s26, s33, s50
	s_addc_u32 s27, s58, s51
	s_mov_b32 m0, s83
	s_nop 0
	global_load_lds_dwordx4 v129, s[24:25]
	s_add_u32 s24, s91, s50
	s_mov_b32 m0, s84
	s_nop 0
	global_load_lds_dwordx4 v129, s[26:27]
	s_addc_u32 s25, s92, s51
	s_add_u32 s26, s93, s50
	s_mov_b32 m0, s81
	s_nop 0
	global_load_lds_dwordx4 v128, s[24:25]
	s_addc_u32 s27, s94, s51
	s_mov_b32 m0, s82
	s_nop 0
	global_load_lds_dwordx4 v128, s[26:27]
	s_waitcnt vmcnt(8)
	s_waitcnt lgkmcnt(0)
	s_barrier
	s_waitcnt lgkmcnt(7)
	v_mfma_f32_16x16x32_bf16 v[60:63], v[130:133], v[166:169], v[60:63]
	v_mfma_f32_16x16x32_bf16 v[56:59], v[138:141], v[166:169], v[56:59]
	s_waitcnt lgkmcnt(5)
	v_mfma_f32_16x16x32_bf16 v[52:55], v[130:133], v[182:185], v[52:55]
	v_mfma_f32_16x16x32_bf16 v[48:51], v[138:141], v[182:185], v[48:51]
	s_waitcnt lgkmcnt(3)
	v_mfma_f32_16x16x32_bf16 v[44:47], v[130:133], v[190:193], v[44:47]
	v_mfma_f32_16x16x32_bf16 v[40:43], v[138:141], v[190:193], v[40:43]
	s_waitcnt lgkmcnt(1)
	v_mfma_f32_16x16x32_bf16 v[36:39], v[130:133], v[198:201], v[36:39]
	v_mfma_f32_16x16x32_bf16 v[32:35], v[138:141], v[198:201], v[32:35]
	v_mfma_f32_16x16x32_bf16 v[60:63], v[134:137], v[178:181], v[60:63]
	v_mfma_f32_16x16x32_bf16 v[56:59], v[142:145], v[178:181], v[56:59]
	v_mfma_f32_16x16x32_bf16 v[52:55], v[134:137], v[186:189], v[52:55]
	v_mfma_f32_16x16x32_bf16 v[48:51], v[142:145], v[186:189], v[48:51]
	v_mfma_f32_16x16x32_bf16 v[44:47], v[134:137], v[194:197], v[44:47]
	v_mfma_f32_16x16x32_bf16 v[40:43], v[142:145], v[194:197], v[40:43]
	s_waitcnt lgkmcnt(0)
	v_mfma_f32_16x16x32_bf16 v[36:39], v[134:137], v[202:205], v[36:39]
	v_mfma_f32_16x16x32_bf16 v[32:35], v[142:145], v[202:205], v[32:35]
	v_mfma_f32_16x16x32_bf16 v[28:31], v[146:149], v[166:169], v[28:31]
	v_mfma_f32_16x16x32_bf16 v[24:27], v[154:157], v[166:169], v[24:27]
	v_mfma_f32_16x16x32_bf16 v[20:23], v[146:149], v[182:185], v[20:23]
	v_mfma_f32_16x16x32_bf16 v[16:19], v[154:157], v[182:185], v[16:19]
	v_mfma_f32_16x16x32_bf16 v[12:15], v[146:149], v[190:193], v[12:15]
	v_mfma_f32_16x16x32_bf16 v[8:11], v[154:157], v[190:193], v[8:11]
	v_mfma_f32_16x16x32_bf16 v[4:7], v[146:149], v[198:201], v[4:7]
	v_mfma_f32_16x16x32_bf16 v[0:3], v[154:157], v[198:201], v[0:3]
	v_mfma_f32_16x16x32_bf16 v[28:31], v[150:153], v[178:181], v[28:31]
	v_mfma_f32_16x16x32_bf16 v[24:27], v[162:165], v[178:181], v[24:27]
	v_mfma_f32_16x16x32_bf16 v[20:23], v[150:153], v[186:189], v[20:23]
	v_mfma_f32_16x16x32_bf16 v[16:19], v[162:165], v[186:189], v[16:19]
	v_mfma_f32_16x16x32_bf16 v[12:15], v[150:153], v[194:197], v[12:15]
	v_mfma_f32_16x16x32_bf16 v[8:11], v[162:165], v[194:197], v[8:11]
	v_mfma_f32_16x16x32_bf16 v[4:7], v[150:153], v[202:205], v[4:7]
	v_mfma_f32_16x16x32_bf16 v[0:3], v[162:165], v[202:205], v[0:3]
	s_barrier
	s_add_u32 s50, s50, s48
	s_addc_u32 s51, s51, s49
	s_cmp_ge_i32 s79, s10
	s_cbranch_scc0 .LBB0_1018

.LBB0_1022:
	ds_read_b128 v[130:133], v173
	ds_read_b128 v[134:137], v173 offset:1024
	ds_read_b128 v[138:141], v173 offset:2048
	ds_read_b128 v[142:145], v173 offset:3072
	ds_read_b128 v[146:149], v174
	ds_read_b128 v[150:153], v174 offset:1024
	ds_read_b128 v[154:157], v174 offset:2048
	ds_read_b128 v[164:167], v174 offset:3072
	s_add_i32 s0, s2, -1
	s_ashr_i32 s1, s0, 31
	s_mul_i32 s1, s46, s1
	s_mul_hi_u32 s2, s46, s0
	s_add_i32 s1, s2, s1
	s_mul_i32 s2, s47, s0
	s_add_i32 s1, s1, s2
	s_sub_u32 s58, 0, s46
	s_mul_i32 s0, s46, s0
	s_subb_u32 s59, 0, s47
	s_add_u32 s0, s4, s0
	s_addc_u32 s1, s5, s1
	ds_read_b128 v[168:171], v175
	ds_read_b128 v[178:181], v175 offset:1024
	ds_read_b128 v[182:185], v175 offset:2048
	ds_read_b128 v[186:189], v175 offset:3072
	ds_read_b128 v[190:193], v175 offset:4096
	ds_read_b128 v[194:197], v175 offset:5120
	ds_read_b128 v[198:201], v175 offset:6144
	ds_read_b128 v[202:205], v175 offset:7168
	s_add_u32 s4, s0, s56
	s_addc_u32 s5, s1, s57
	s_add_u32 s24, s4, s52
	s_mov_b32 m0, s85
	s_nop 0
	global_load_lds_dwordx4 v128, s[4:5]
	s_addc_u32 s25, s5, s53
	s_mov_b32 m0, s86
	s_nop 0
	global_load_lds_dwordx4 v128, s[24:25]
	s_waitcnt vmcnt(8)
	s_waitcnt lgkmcnt(0)
	s_barrier
	s_waitcnt lgkmcnt(0)
	v_mfma_f32_16x16x32_bf16 v[124:127], v[130:133], v[168:171], v[124:127]
	v_mfma_f32_16x16x32_bf16 v[120:123], v[138:141], v[168:171], v[120:123]
	v_mfma_f32_16x16x32_bf16 v[116:119], v[130:133], v[182:185], v[116:119]
	v_mfma_f32_16x16x32_bf16 v[112:115], v[138:141], v[182:185], v[112:115]
	v_mfma_f32_16x16x32_bf16 v[108:111], v[130:133], v[190:193], v[108:111]
	v_mfma_f32_16x16x32_bf16 v[104:107], v[138:141], v[190:193], v[104:107]
	v_mfma_f32_16x16x32_bf16 v[100:103], v[130:133], v[198:201], v[100:103]
	v_mfma_f32_16x16x32_bf16 v[96:99], v[138:141], v[198:201], v[96:99]
	v_mfma_f32_16x16x32_bf16 v[124:127], v[134:137], v[178:181], v[124:127]
	v_mfma_f32_16x16x32_bf16 v[120:123], v[142:145], v[178:181], v[120:123]
	v_mfma_f32_16x16x32_bf16 v[116:119], v[134:137], v[186:189], v[116:119]
	v_mfma_f32_16x16x32_bf16 v[112:115], v[142:145], v[186:189], v[112:115]
	v_mfma_f32_16x16x32_bf16 v[108:111], v[134:137], v[194:197], v[108:111]
	v_mfma_f32_16x16x32_bf16 v[104:107], v[142:145], v[194:197], v[104:107]
	v_mfma_f32_16x16x32_bf16 v[100:103], v[134:137], v[202:205], v[100:103]
	v_mfma_f32_16x16x32_bf16 v[96:99], v[142:145], v[202:205], v[96:99]
	v_mfma_f32_16x16x32_bf16 v[92:95], v[146:149], v[168:171], v[92:95]
	v_mfma_f32_16x16x32_bf16 v[88:91], v[154:157], v[168:171], v[88:91]
	v_mfma_f32_16x16x32_bf16 v[84:87], v[146:149], v[182:185], v[84:87]
	v_mfma_f32_16x16x32_bf16 v[80:83], v[154:157], v[182:185], v[80:83]
	v_mfma_f32_16x16x32_bf16 v[76:79], v[146:149], v[190:193], v[76:79]
	v_mfma_f32_16x16x32_bf16 v[72:75], v[154:157], v[190:193], v[72:75]
	v_mfma_f32_16x16x32_bf16 v[68:71], v[146:149], v[198:201], v[68:71]
	v_mfma_f32_16x16x32_bf16 v[64:67], v[154:157], v[198:201], v[64:67]
	v_mfma_f32_16x16x32_bf16 v[92:95], v[150:153], v[178:181], v[92:95]
	v_mfma_f32_16x16x32_bf16 v[88:91], v[164:167], v[178:181], v[88:91]
	v_mfma_f32_16x16x32_bf16 v[84:87], v[150:153], v[186:189], v[84:87]
	v_mfma_f32_16x16x32_bf16 v[80:83], v[164:167], v[186:189], v[80:83]
	v_mfma_f32_16x16x32_bf16 v[76:79], v[150:153], v[194:197], v[76:79]
	v_mfma_f32_16x16x32_bf16 v[72:75], v[164:167], v[194:197], v[72:75]
	v_mfma_f32_16x16x32_bf16 v[68:71], v[150:153], v[202:205], v[68:71]
	v_mfma_f32_16x16x32_bf16 v[64:67], v[164:167], v[202:205], v[64:67]
	s_barrier
	s_add_u32 s4, s6, s34
	ds_read_b128 v[168:171], v175 offset:16384
	ds_read_b128 v[178:181], v175 offset:17408
	ds_read_b128 v[182:185], v175 offset:18432
	ds_read_b128 v[186:189], v175 offset:19456
	ds_read_b128 v[190:193], v175 offset:20480
	ds_read_b128 v[194:197], v175 offset:21504
	ds_read_b128 v[198:201], v175 offset:22528
	ds_read_b128 v[202:205], v175 offset:23552
	s_addc_u32 s5, s7, s35
	s_mov_b32 m0, s62
	s_nop 0
	global_load_lds_dwordx4 v163, s[6:7]
	s_nop 0
	s_mov_b32 m0, s63
	s_nop 0
	global_load_lds_dwordx4 v163, s[4:5]
	s_add_u32 s4, s6, s38
	s_addc_u32 s5, s7, s39
	s_add_u32 s24, s4, s34
	s_mov_b32 m0, s64
	s_nop 0
	global_load_lds_dwordx4 v163, s[4:5]
	s_addc_u32 s25, s5, s35
	s_mov_b32 m0, s65
	s_nop 0
	global_load_lds_dwordx4 v163, s[24:25]
	s_add_u32 s4, s54, s50
	s_mov_b32 m0, s3
	s_nop 0
	global_load_lds_dwordx4 v162, s[54:55]
	s_addc_u32 s5, s55, s51
	s_mov_b32 m0, s66
	s_nop 0
	global_load_lds_dwordx4 v162, s[4:5]
	s_waitcnt vmcnt(8)
	s_waitcnt lgkmcnt(0)
	s_barrier
	s_waitcnt lgkmcnt(7)
	v_mfma_f32_16x16x32_bf16 v[56:59], v[138:141], v[168:171], v[56:59]
	s_waitcnt lgkmcnt(5)
	v_mfma_f32_16x16x32_bf16 v[48:51], v[138:141], v[182:185], v[48:51]
	s_waitcnt lgkmcnt(3)
	v_mfma_f32_16x16x32_bf16 v[44:47], v[130:133], v[190:193], v[44:47]
	s_waitcnt lgkmcnt(1)
	v_mfma_f32_16x16x32_bf16 v[36:39], v[130:133], v[198:201], v[36:39]
	v_mfma_f32_16x16x32_bf16 v[60:63], v[130:133], v[168:171], v[60:63]
	v_mfma_f32_16x16x32_bf16 v[56:59], v[142:145], v[178:181], v[56:59]
	v_mfma_f32_16x16x32_bf16 v[52:55], v[130:133], v[182:185], v[52:55]
	v_mfma_f32_16x16x32_bf16 v[48:51], v[142:145], v[186:189], v[48:51]
	v_mfma_f32_16x16x32_bf16 v[44:47], v[134:137], v[194:197], v[44:47]
	v_mfma_f32_16x16x32_bf16 v[40:43], v[138:141], v[190:193], v[40:43]
	s_waitcnt lgkmcnt(0)
	v_mfma_f32_16x16x32_bf16 v[36:39], v[134:137], v[202:205], v[36:39]
	v_mfma_f32_16x16x32_bf16 v[32:35], v[138:141], v[198:201], v[32:35]
	v_mfma_f32_16x16x32_bf16 v[60:63], v[134:137], v[178:181], v[60:63]
	v_mfma_f32_16x16x32_bf16 v[52:55], v[134:137], v[186:189], v[52:55]
	v_mfma_f32_16x16x32_bf16 v[40:43], v[142:145], v[194:197], v[40:43]
	v_mfma_f32_16x16x32_bf16 v[32:35], v[142:145], v[202:205], v[32:35]
	v_mfma_f32_16x16x32_bf16 v[4:7], v[146:149], v[198:201], v[4:7]
	v_mfma_f32_16x16x32_bf16 v[0:3], v[154:157], v[198:201], v[0:3]
	v_mfma_f32_16x16x32_bf16 v[28:31], v[146:149], v[168:171], v[28:31]
	v_mfma_f32_16x16x32_bf16 v[24:27], v[154:157], v[168:171], v[24:27]
	v_mfma_f32_16x16x32_bf16 v[20:23], v[146:149], v[182:185], v[20:23]
	v_mfma_f32_16x16x32_bf16 v[16:19], v[154:157], v[182:185], v[16:19]
	v_mfma_f32_16x16x32_bf16 v[12:15], v[146:149], v[190:193], v[12:15]
	v_mfma_f32_16x16x32_bf16 v[8:11], v[154:157], v[190:193], v[8:11]
	v_mfma_f32_16x16x32_bf16 v[4:7], v[150:153], v[202:205], v[4:7]
	v_mfma_f32_16x16x32_bf16 v[0:3], v[164:167], v[202:205], v[0:3]
	v_mfma_f32_16x16x32_bf16 v[28:31], v[150:153], v[178:181], v[28:31]
	v_mfma_f32_16x16x32_bf16 v[24:27], v[164:167], v[178:181], v[24:27]
	v_mfma_f32_16x16x32_bf16 v[168:171], v[150:153], v[186:189], v[20:23]
	v_mfma_f32_16x16x32_bf16 v[16:19], v[164:167], v[186:189], v[16:19]
	v_mfma_f32_16x16x32_bf16 v[12:15], v[150:153], v[194:197], v[12:15]
	v_mfma_f32_16x16x32_bf16 v[178:181], v[164:167], v[194:197], v[8:11]
	s_barrier
	s_nop 0
	ds_read_b128 v[8:11], v176
	ds_read_b128 v[20:23], v176 offset:1024
	ds_read_b128 v[164:167], v176 offset:2048
	ds_read_b128 v[182:185], v176 offset:3072
	ds_read_b128 v[186:189], v177
	ds_read_b128 v[190:193], v177 offset:1024
	ds_read_b128 v[194:197], v177 offset:2048
	ds_read_b128 v[198:201], v177 offset:3072
	ds_read_b128 v[128:131], v175 offset:32768
	ds_read_b128 v[132:135], v175 offset:33792
	ds_read_b128 v[202:205], v175 offset:34816
	ds_read_b128 v[206:209], v175 offset:35840
	ds_read_b128 v[210:213], v175 offset:36864
	ds_read_b128 v[214:217], v175 offset:37888
	ds_read_b128 v[218:221], v175 offset:38912
	ds_read_b128 v[222:225], v175 offset:39936
	s_add_u32 s4, s54, s48
	s_addc_u32 s5, s55, s49
	s_add_u32 s24, s4, s50
	s_mov_b32 m0, s67
	s_nop 0
	global_load_lds_dwordx4 v162, s[4:5]
	s_addc_u32 s25, s5, s51
	s_mov_b32 m0, s73
	s_nop 0
	global_load_lds_dwordx4 v162, s[24:25]
	s_waitcnt vmcnt(8)
	s_waitcnt lgkmcnt(0)
	s_barrier
	s_waitcnt lgkmcnt(7)
	v_mfma_f32_16x16x32_bf16 v[124:127], v[8:11], v[128:131], v[124:127]
	v_mfma_f32_16x16x32_bf16 v[120:123], v[164:167], v[128:131], v[120:123]
	s_waitcnt lgkmcnt(5)
	v_mfma_f32_16x16x32_bf16 v[116:119], v[8:11], v[202:205], v[116:119]
	v_mfma_f32_16x16x32_bf16 v[112:115], v[164:167], v[202:205], v[112:115]
	s_waitcnt lgkmcnt(3)
	v_mfma_f32_16x16x32_bf16 v[108:111], v[8:11], v[210:213], v[108:111]
	v_mfma_f32_16x16x32_bf16 v[104:107], v[164:167], v[210:213], v[104:107]
	s_waitcnt lgkmcnt(1)
	v_mfma_f32_16x16x32_bf16 v[100:103], v[8:11], v[218:221], v[100:103]
	v_mfma_f32_16x16x32_bf16 v[96:99], v[164:167], v[218:221], v[96:99]
	v_mfma_f32_16x16x32_bf16 v[152:155], v[20:23], v[132:135], v[124:127]
	v_mfma_f32_16x16x32_bf16 v[156:159], v[182:185], v[132:135], v[120:123]
	v_mfma_f32_16x16x32_bf16 v[140:143], v[20:23], v[206:209], v[116:119]
	v_mfma_f32_16x16x32_bf16 v[136:139], v[182:185], v[206:209], v[112:115]
	v_mfma_f32_16x16x32_bf16 v[116:119], v[20:23], v[214:217], v[108:111]
	v_mfma_f32_16x16x32_bf16 v[120:123], v[182:185], v[214:217], v[104:107]
	s_waitcnt lgkmcnt(0)
	v_mfma_f32_16x16x32_bf16 v[108:111], v[20:23], v[222:225], v[100:103]
	v_mfma_f32_16x16x32_bf16 v[104:107], v[182:185], v[222:225], v[96:99]
	v_mfma_f32_16x16x32_bf16 v[92:95], v[186:189], v[128:131], v[92:95]
	v_mfma_f32_16x16x32_bf16 v[88:91], v[194:197], v[128:131], v[88:91]
	v_mfma_f32_16x16x32_bf16 v[84:87], v[186:189], v[202:205], v[84:87]
	v_mfma_f32_16x16x32_bf16 v[80:83], v[194:197], v[202:205], v[80:83]
	v_mfma_f32_16x16x32_bf16 v[76:79], v[186:189], v[210:213], v[76:79]
	v_mfma_f32_16x16x32_bf16 v[72:75], v[194:197], v[210:213], v[72:75]
	v_mfma_f32_16x16x32_bf16 v[68:71], v[186:189], v[218:221], v[68:71]
	v_mfma_f32_16x16x32_bf16 v[64:67], v[194:197], v[218:221], v[64:67]
	v_mfma_f32_16x16x32_bf16 v[148:151], v[190:193], v[132:135], v[92:95]
	v_mfma_f32_16x16x32_bf16 v[144:147], v[198:201], v[132:135], v[88:91]
	v_mfma_f32_16x16x32_bf16 v[132:135], v[190:193], v[206:209], v[84:87]
	v_mfma_f32_16x16x32_bf16 v[128:131], v[198:201], v[206:209], v[80:83]
	v_mfma_f32_16x16x32_bf16 v[124:127], v[190:193], v[214:217], v[76:79]
	v_mfma_f32_16x16x32_bf16 v[112:115], v[198:201], v[214:217], v[72:75]
	v_mfma_f32_16x16x32_bf16 v[100:103], v[190:193], v[222:225], v[68:71]
	v_mfma_f32_16x16x32_bf16 v[96:99], v[198:201], v[222:225], v[64:67]
	s_barrier
	s_and_b64 s[4:5], exec, s[14:15]
	s_cselect_b32 s1, s58, s46
	s_cselect_b32 s0, s59, s47
	s_add_u32 s4, s6, s1
	s_addc_u32 s5, s7, s0
	s_add_u32 s24, s4, s34
	s_addc_u32 s25, s5, s35
	ds_read_b128 v[64:67], v175 offset:49152
	ds_read_b128 v[68:71], v175 offset:50176
	ds_read_b128 v[202:205], v175 offset:51200
	ds_read_b128 v[206:209], v175 offset:52224
	ds_read_b128 v[210:213], v175 offset:53248
	ds_read_b128 v[214:217], v175 offset:54272
	ds_read_b128 v[218:221], v175 offset:55296
	ds_read_b128 v[222:225], v175 offset:56320
	s_mov_b32 m0, s9
	s_nop 0
	global_load_lds_dwordx4 v163, s[4:5]
	s_add_u32 s4, s4, s38
	s_addc_u32 s5, s5, s39
	s_mov_b32 m0, s80
	s_nop 0
	global_load_lds_dwordx4 v163, s[24:25]
	s_add_u32 s24, s4, s34
	s_addc_u32 s25, s5, s35
	s_mov_b32 m0, s83
	s_nop 0
	global_load_lds_dwordx4 v163, s[4:5]
	s_add_u32 s4, s54, s1
	s_mov_b32 m0, s84
	s_nop 0
	global_load_lds_dwordx4 v163, s[24:25]
	s_addc_u32 s5, s55, s0
	s_add_u32 s24, s4, s50
	s_mov_b32 m0, s81
	s_nop 0
	global_load_lds_dwordx4 v162, s[4:5]
	s_addc_u32 s25, s5, s51
	s_mov_b32 m0, s82
	s_nop 0
	global_load_lds_dwordx4 v162, s[24:25]
	s_waitcnt vmcnt(8)
	s_waitcnt lgkmcnt(0)
	s_barrier
	s_waitcnt lgkmcnt(7)
	v_mfma_f32_16x16x32_bf16 v[60:63], v[8:11], v[64:67], v[60:63]
	s_waitcnt lgkmcnt(5)
	v_mfma_f32_16x16x32_bf16 v[52:55], v[8:11], v[202:205], v[52:55]
	s_waitcnt lgkmcnt(3)
	v_mfma_f32_16x16x32_bf16 v[44:47], v[8:11], v[210:213], v[44:47]
	s_waitcnt lgkmcnt(1)
	v_mfma_f32_16x16x32_bf16 v[8:11], v[8:11], v[218:221], v[36:39]
	v_mfma_f32_16x16x32_bf16 v[84:87], v[20:23], v[68:71], v[60:63]
	v_mfma_f32_16x16x32_bf16 v[56:59], v[164:167], v[64:67], v[56:59]
	v_mfma_f32_16x16x32_bf16 v[76:79], v[20:23], v[206:209], v[52:55]
	v_mfma_f32_16x16x32_bf16 v[48:51], v[164:167], v[202:205], v[48:51]
	v_mfma_f32_16x16x32_bf16 v[44:47], v[20:23], v[214:217], v[44:47]
	v_mfma_f32_16x16x32_bf16 v[40:43], v[164:167], v[210:213], v[40:43]
	s_waitcnt lgkmcnt(0)
	v_mfma_f32_16x16x32_bf16 v[20:23], v[20:23], v[222:225], v[8:11]
	v_mfma_f32_16x16x32_bf16 v[8:11], v[164:167], v[218:221], v[32:35]
	v_mfma_f32_16x16x32_bf16 v[88:91], v[182:185], v[68:71], v[56:59]
	v_mfma_f32_16x16x32_bf16 v[72:75], v[182:185], v[206:209], v[48:51]
	v_mfma_f32_16x16x32_bf16 v[48:51], v[182:185], v[214:217], v[40:43]
	v_mfma_f32_16x16x32_bf16 v[8:11], v[182:185], v[222:225], v[8:11]
	v_mfma_f32_16x16x32_bf16 v[24:27], v[194:197], v[64:67], v[24:27]
	v_mfma_f32_16x16x32_bf16 v[12:15], v[186:189], v[210:213], v[12:15]
	v_mfma_f32_16x16x32_bf16 v[28:31], v[186:189], v[64:67], v[28:31]
	v_mfma_f32_16x16x32_bf16 v[80:83], v[198:201], v[68:71], v[24:27]
	v_mfma_f32_16x16x32_bf16 v[24:27], v[186:189], v[202:205], v[168:171]
	v_mfma_f32_16x16x32_bf16 v[16:19], v[194:197], v[202:205], v[16:19]
	v_mfma_f32_16x16x32_bf16 v[56:59], v[190:193], v[214:217], v[12:15]
	v_mfma_f32_16x16x32_bf16 v[12:15], v[194:197], v[210:213], v[178:181]
	v_mfma_f32_16x16x32_bf16 v[4:7], v[186:189], v[218:221], v[4:7]
	v_mfma_f32_16x16x32_bf16 v[0:3], v[194:197], v[218:221], v[0:3]
	v_mfma_f32_16x16x32_bf16 v[92:95], v[190:193], v[68:71], v[28:31]
	v_mfma_f32_16x16x32_bf16 v[68:71], v[190:193], v[206:209], v[24:27]
	v_mfma_f32_16x16x32_bf16 v[64:67], v[198:201], v[206:209], v[16:19]
	v_mfma_f32_16x16x32_bf16 v[36:39], v[198:201], v[214:217], v[12:15]
	v_mfma_f32_16x16x32_bf16 v[4:7], v[190:193], v[222:225], v[4:7]
	v_mfma_f32_16x16x32_bf16 v[0:3], v[198:201], v[222:225], v[0:3]
	s_barrier
	s_andn2_b64 vcc, exec, s[36:37]
	s_cbranch_vccnz .LBB0_1024
	s_barrier

	.amdhsa_kernel _Z6mk_fwd4Args
		.amdhsa_group_segment_fixed_size 0
		.amdhsa_private_segment_fixed_size 0
		.amdhsa_kernarg_size 408
		.amdhsa_user_sgpr_count 2
		.amdhsa_user_sgpr_dispatch_ptr 0
		.amdhsa_user_sgpr_queue_ptr 0
		.amdhsa_user_sgpr_kernarg_segment_ptr 1
		.amdhsa_user_sgpr_dispatch_id 0
		.amdhsa_user_sgpr_kernarg_preload_length 0
		.amdhsa_user_sgpr_kernarg_preload_offset 0
		.amdhsa_user_sgpr_private_segment_size 0
		.amdhsa_uses_dynamic_stack 0
		.amdhsa_enable_private_segment 0
		.amdhsa_system_sgpr_workgroup_id_x 1
		.amdhsa_system_sgpr_workgroup_id_y 0
		.amdhsa_system_sgpr_workgroup_id_z 0
		.amdhsa_system_sgpr_workgroup_info 0
		.amdhsa_system_vgpr_workitem_id 0
		.amdhsa_next_free_vgpr 256
		.amdhsa_next_free_sgpr 100
		.amdhsa_accum_offset 256
		.amdhsa_reserve_vcc 1
		.amdhsa_float_round_mode_32 0
		.amdhsa_float_round_mode_16_64 0
		.amdhsa_float_denorm_mode_32 3
		.amdhsa_float_denorm_mode_16_64 3
		.amdhsa_dx10_clamp 1
		.amdhsa_ieee_mode 1
		.amdhsa_fp16_overflow 0
		.amdhsa_tg_split 0
		.amdhsa_exception_fp_ieee_invalid_op 0
		.amdhsa_exception_fp_denorm_src 0
		.amdhsa_exception_fp_ieee_div_zero 0
		.amdhsa_exception_fp_ieee_overflow 0
		.amdhsa_exception_fp_ieee_underflow 0
		.amdhsa_exception_fp_ieee_inexact 0
		.amdhsa_exception_int_div_zero 0
	.end_amdhsa_kernel

amdhsa.kernels:
  - .agpr_count:     0
    .args:
      - .offset:         0
        .size:           152
        .value_kind:     by_value
      - .offset:         152
        .size:           4
        .value_kind:     hidden_block_count_x
      - .offset:         156
        .size:           4
        .value_kind:     hidden_block_count_y
      - .offset:         160
        .size:           4
        .value_kind:     hidden_block_count_z
      - .offset:         164
        .size:           2
        .value_kind:     hidden_group_size_x
      - .offset:         166
        .size:           2
        .value_kind:     hidden_group_size_y
      - .offset:         168
        .size:           2
        .value_kind:     hidden_group_size_z
      - .offset:         170
        .size:           2
        .value_kind:     hidden_remainder_x
      - .offset:         172
        .size:           2
        .value_kind:     hidden_remainder_y
      - .offset:         174
        .size:           2
        .value_kind:     hidden_remainder_z
      - .offset:         192
        .size:           8
        .value_kind:     hidden_global_offset_x
      - .offset:         200
        .size:           8
        .value_kind:     hidden_global_offset_y
      - .offset:         208
        .size:           8
        .value_kind:     hidden_global_offset_z
      - .offset:         216
        .size:           2
        .value_kind:     hidden_grid_dims
      - .offset:         272
        .size:           4
        .value_kind:     hidden_dynamic_lds_size
    .group_segment_fixed_size: 0
    .kernarg_segment_align: 8
    .kernarg_segment_size: 408
    .language:       OpenCL C
    .language_version:
      - 2
      - 0
    .max_flat_workgroup_size: 512
    .name:           _Z6mk_fwd4Args
    .private_segment_fixed_size: 0
    .sgpr_count:     106
    .sgpr_spill_count: 99
    .symbol:         _Z6mk_fwd4Args.kd
    .uniform_work_group_size: 1
    .uses_dynamic_stack: false
    .vgpr_count:     256
    .vgpr_spill_count: 0
    .wavefront_size: 64
